# speedup vs baseline: 1.0730x; 1.0730x over previous
; DEV u16 f2bf(float f) { return (u16)(pack2(f, 0.f) & 0xffffu); }
; DEV float bf2f(u16 b) { return __uint_as_float(((unsigned)b) << 16); }
; DEV size_t tixw(long row, int col, int W) { return (size_t)(row >> 8) * (256 * (size_t)W) + (size_t)(col >> 5) * 8192 + (size_t)(row & 255) * 32 + (col & 31); }
; DEV float sigmoidf_(float x) { return 1.f / (1.f + __expf(-x)); }
;     ...
; #pragma unroll
;     for (int ms = 0; ms < 8; ++ms) {
;       asm volatile("" ::: "memory");
; #pragma unroll
;       for (int ns = 0; ns < 4; ++ns)
; #pragma unroll
;         for (int j = 0; j < 4; ++j) {
;           int row = m0 + wm * 128 + ms * 16 + quad * 4 + j;
;           int col = n0 + wn * 64 + ns * 16 + l15;
;           size_t idx = (size_t)row * D + col;
;           float gate = sigmoidf_(acc[ms][ns][j] + bg[col]);
;           float v = P.out[idx] + psc * gate * bf2f(Pp[idx]);
;           P.out[idx] = v;
;           xbn[tixw(row, col, D)] = f2bf(v);
;         }
.LBB0_66:
	v_or_b32_e32 v0, s14, v183
	v_or_b32_e32 v134, v0, v178
	v_add_u32_e32 v136, s12, v184
	v_lshlrev_b32_e32 v172, 2, v134
	global_load_dword v138, v172, s[8:9]
	global_load_dword v139, v172, s[8:9] offset:64
	global_load_dword v214, v172, s[8:9] offset:128
	global_load_dword v215, v172, s[8:9] offset:192
	v_lshrrev_b32_e32 v137, 5, v134
	v_lshlrev_b32_e32 v137, 14, v137
	v_and_b32_e32 v173, 31, v134
	v_lshl_add_u32 v137, v173, 1, v137
	v_lshrrev_b32_e32 v173, 8, v136
	v_lshl_add_u32 v137, v173, 19, v137
	v_and_b32_e32 v173, 0xff, v136
	v_lshl_add_u32 v137, v173, 6, v137
	v_lshlrev_b32_e32 v136, 12, v136
	v_lshl_add_u32 v136, v134, 2, v136
	v_add_u32_e32 v136, 0x1000, v136
	v_mov_b32_e32 v130, v136
	v_add_u32_e32 v131, 0x2000, v130
	v_lshrrev_b32_e32 v132, 1, v130
	v_lshrrev_b32_e32 v133, 1, v131
	v_mov_b32_e32 v134, v137
	v_add_u32_e32 v135, 0x4000, v134
	global_load_dword v140, v130, s[86:87] offset:-4096
	global_load_dword v141, v130, s[86:87]
	global_load_dword v142, v131, s[86:87] offset:-4096
	global_load_dword v143, v131, s[86:87]
	global_load_dword v144, v130, s[86:87] offset:-4032
	global_load_dword v145, v130, s[86:87] offset:64
	global_load_dword v146, v131, s[86:87] offset:-4032
	global_load_dword v147, v131, s[86:87] offset:64
	global_load_dword v148, v130, s[86:87] offset:-3968
	global_load_dword v149, v130, s[86:87] offset:128
	global_load_dword v150, v131, s[86:87] offset:-3968
	global_load_dword v151, v131, s[86:87] offset:128
	global_load_dword v152, v130, s[86:87] offset:-3904
	global_load_dword v153, v130, s[86:87] offset:192
	global_load_dword v154, v131, s[86:87] offset:-3904
	global_load_dword v155, v131, s[86:87] offset:192
	global_load_ushort v156, v132, s[96:97] offset:-2048
	global_load_ushort v157, v132, s[96:97]
	global_load_ushort v158, v133, s[96:97] offset:-2048
	global_load_ushort v159, v133, s[96:97]
	global_load_ushort v160, v132, s[96:97] offset:-2016
	global_load_ushort v161, v132, s[96:97] offset:32
	global_load_ushort v162, v133, s[96:97] offset:-2016
	global_load_ushort v163, v133, s[96:97] offset:32
	global_load_ushort v164, v132, s[96:97] offset:-1984
	global_load_ushort v165, v132, s[96:97] offset:64
	global_load_ushort v166, v133, s[96:97] offset:-1984
	global_load_ushort v167, v133, s[96:97] offset:64
	global_load_ushort v168, v132, s[96:97] offset:-1952
	global_load_ushort v169, v132, s[96:97] offset:96
	global_load_ushort v170, v133, s[96:97] offset:-1952
	global_load_ushort v171, v133, s[96:97] offset:96
	s_waitcnt vmcnt(0)
	v_add_f32_e32 v126, v126, v138
	v_mul_f32_e32 v126, 0xbfb8aa3b, v126
	v_exp_f32_e32 v126, v126
	v_lshlrev_b32_e32 v156, 16, v156
	v_add_f32_e32 v126, 1.0, v126
	v_div_scale_f32 v172, s[4:5], v126, v126, 1.0
	v_rcp_f32_e32 v173, v172
	s_nop 0
	v_fma_f32 v174, -v172, v173, 1.0
	v_fmac_f32_e32 v173, v174, v173
	v_div_scale_f32 v174, vcc, 1.0, v126, 1.0
	v_mul_f32_e32 v175, v174, v173
	v_fma_f32 v176, -v172, v175, v174
	v_fmac_f32_e32 v175, v176, v173
	v_fma_f32 v172, -v172, v175, v174
	v_div_fmas_f32 v172, v172, v173, v175
	v_div_fixup_f32 v126, v172, v126, 1.0
	v_mul_f32_e32 v126, v181, v126
	v_fmac_f32_e32 v140, v126, v156
	global_store_dword v130, v140, s[86:87] offset:-4096
	v_cvt_pk_bf16_f32 v126, v140, s0
	global_store_short v134, v126, s[88:89]
	v_add_f32_e32 v127, v127, v138
	v_mul_f32_e32 v127, 0xbfb8aa3b, v127
	v_exp_f32_e32 v127, v127
	v_lshlrev_b32_e32 v157, 16, v157
	v_add_f32_e32 v127, 1.0, v127
	v_div_scale_f32 v172, s[4:5], v127, v127, 1.0
	v_rcp_f32_e32 v173, v172
	s_nop 0
	v_fma_f32 v174, -v172, v173, 1.0
	v_fmac_f32_e32 v173, v174, v173
	v_div_scale_f32 v174, vcc, 1.0, v127, 1.0
	v_mul_f32_e32 v175, v174, v173
	v_fma_f32 v176, -v172, v175, v174
	v_fmac_f32_e32 v175, v176, v173
	v_fma_f32 v172, -v172, v175, v174
	v_div_fmas_f32 v172, v172, v173, v175
	v_div_fixup_f32 v127, v172, v127, 1.0
	v_mul_f32_e32 v127, v181, v127
	v_fmac_f32_e32 v141, v127, v157
	global_store_dword v130, v141, s[86:87]
	v_cvt_pk_bf16_f32 v127, v141, s0
	global_store_short v134, v127, s[88:89] offset:64
	v_add_f32_e32 v128, v128, v138
	v_mul_f32_e32 v128, 0xbfb8aa3b, v128
	v_exp_f32_e32 v128, v128
	v_lshlrev_b32_e32 v158, 16, v158
	v_add_f32_e32 v128, 1.0, v128
	v_div_scale_f32 v172, s[4:5], v128, v128, 1.0
	v_rcp_f32_e32 v173, v172
	s_nop 0
	v_fma_f32 v174, -v172, v173, 1.0
	v_fmac_f32_e32 v173, v174, v173
	v_div_scale_f32 v174, vcc, 1.0, v128, 1.0
	v_mul_f32_e32 v175, v174, v173
	v_fma_f32 v176, -v172, v175, v174
	v_fmac_f32_e32 v175, v176, v173
	v_fma_f32 v172, -v172, v175, v174
	v_div_fmas_f32 v172, v172, v173, v175
	v_div_fixup_f32 v128, v172, v128, 1.0
	v_mul_f32_e32 v128, v181, v128
	v_fmac_f32_e32 v142, v128, v158
	global_store_dword v131, v142, s[86:87] offset:-4096
	v_cvt_pk_bf16_f32 v128, v142, s0
	global_store_short v134, v128, s[88:89] offset:128
	v_add_f32_e32 v129, v129, v138
	v_mul_f32_e32 v129, 0xbfb8aa3b, v129
	v_exp_f32_e32 v129, v129
	v_lshlrev_b32_e32 v159, 16, v159
	v_add_f32_e32 v129, 1.0, v129
	v_div_scale_f32 v172, s[4:5], v129, v129, 1.0
	v_rcp_f32_e32 v173, v172
	s_nop 0
	v_fma_f32 v174, -v172, v173, 1.0
	v_fmac_f32_e32 v173, v174, v173
	v_div_scale_f32 v174, vcc, 1.0, v129, 1.0
	v_mul_f32_e32 v175, v174, v173
	v_fma_f32 v176, -v172, v175, v174
	v_fmac_f32_e32 v175, v176, v173
	v_fma_f32 v172, -v172, v175, v174
	v_div_fmas_f32 v172, v172, v173, v175
	v_div_fixup_f32 v129, v172, v129, 1.0
	v_mul_f32_e32 v129, v181, v129
	v_fmac_f32_e32 v143, v129, v159
	global_store_dword v131, v143, s[86:87]
	v_cvt_pk_bf16_f32 v129, v143, s0
	global_store_short v134, v129, s[88:89] offset:192
	v_add_f32_e32 v122, v122, v139
	v_mul_f32_e32 v122, 0xbfb8aa3b, v122
; DEV u16 f2bf(float f) { return (u16)(pack2(f, 0.f) & 0xffffu); }
; DEV float bf2f(u16 b) { return __uint_as_float(((unsigned)b) << 16); }
; DEV size_t tixw(long row, int col, int W) { return (size_t)(row >> 8) * (256 * (size_t)W) + (size_t)(col >> 5) * 8192 + (size_t)(row & 255) * 32 + (col & 31); }
; DEV float sigmoidf_(float x) { return 1.f / (1.f + __expf(-x)); }
;     ...
;         for (int j = 0; j < 4; ++j) {
;           int row = m0 + wm * 128 + ms * 16 + quad * 4 + j;
;           int col = n0 + wn * 64 + ns * 16 + l15;
;           size_t idx = (size_t)row * D + col;
;           float gate = sigmoidf_(acc[ms][ns][j] + bg[col]);
;           float v = P.out[idx] + psc * gate * bf2f(Pp[idx]);
;           P.out[idx] = v;
;           xbn[tixw(row, col, D)] = f2bf(v);
	v_exp_f32_e32 v122, v122
	v_lshlrev_b32_e32 v160, 16, v160
	v_add_f32_e32 v122, 1.0, v122
	v_div_scale_f32 v172, s[4:5], v122, v122, 1.0
	v_rcp_f32_e32 v173, v172
	s_nop 0
	v_fma_f32 v174, -v172, v173, 1.0
	v_fmac_f32_e32 v173, v174, v173
	v_div_scale_f32 v174, vcc, 1.0, v122, 1.0
	v_mul_f32_e32 v175, v174, v173
	v_fma_f32 v176, -v172, v175, v174
	v_fmac_f32_e32 v175, v176, v173
	v_fma_f32 v172, -v172, v175, v174
	v_div_fmas_f32 v172, v172, v173, v175
	v_div_fixup_f32 v122, v172, v122, 1.0
	v_mul_f32_e32 v122, v181, v122
	v_fmac_f32_e32 v144, v122, v160
	global_store_dword v130, v144, s[86:87] offset:-4032
	v_cvt_pk_bf16_f32 v122, v144, s0
	global_store_short v134, v122, s[88:89] offset:32
	v_add_f32_e32 v123, v123, v139
	v_mul_f32_e32 v123, 0xbfb8aa3b, v123
	v_exp_f32_e32 v123, v123
	v_lshlrev_b32_e32 v161, 16, v161
	v_add_f32_e32 v123, 1.0, v123
	v_div_scale_f32 v172, s[4:5], v123, v123, 1.0
	v_rcp_f32_e32 v173, v172
	s_nop 0
	v_fma_f32 v174, -v172, v173, 1.0
	v_fmac_f32_e32 v173, v174, v173
	v_div_scale_f32 v174, vcc, 1.0, v123, 1.0
	v_mul_f32_e32 v175, v174, v173
	v_fma_f32 v176, -v172, v175, v174
	v_fmac_f32_e32 v175, v176, v173
	v_fma_f32 v172, -v172, v175, v174
	v_div_fmas_f32 v172, v172, v173, v175
	v_div_fixup_f32 v123, v172, v123, 1.0
	v_mul_f32_e32 v123, v181, v123
	v_fmac_f32_e32 v145, v123, v161
	global_store_dword v130, v145, s[86:87] offset:64
	v_cvt_pk_bf16_f32 v123, v145, s0
	global_store_short v134, v123, s[88:89] offset:96
	v_add_f32_e32 v124, v124, v139
	v_mul_f32_e32 v124, 0xbfb8aa3b, v124
	v_exp_f32_e32 v124, v124
	v_lshlrev_b32_e32 v162, 16, v162
	v_add_f32_e32 v124, 1.0, v124
	v_div_scale_f32 v172, s[4:5], v124, v124, 1.0
	v_rcp_f32_e32 v173, v172
	s_nop 0
	v_fma_f32 v174, -v172, v173, 1.0
	v_fmac_f32_e32 v173, v174, v173
	v_div_scale_f32 v174, vcc, 1.0, v124, 1.0
	v_mul_f32_e32 v175, v174, v173
	v_fma_f32 v176, -v172, v175, v174
	v_fmac_f32_e32 v175, v176, v173
	v_fma_f32 v172, -v172, v175, v174
	v_div_fmas_f32 v172, v172, v173, v175
	v_div_fixup_f32 v124, v172, v124, 1.0
	v_mul_f32_e32 v124, v181, v124
	v_fmac_f32_e32 v146, v124, v162
	global_store_dword v131, v146, s[86:87] offset:-4032
	v_cvt_pk_bf16_f32 v124, v146, s0
	global_store_short v134, v124, s[88:89] offset:160
	v_add_f32_e32 v125, v125, v139
	v_mul_f32_e32 v125, 0xbfb8aa3b, v125
	v_exp_f32_e32 v125, v125
	v_lshlrev_b32_e32 v163, 16, v163
	v_add_f32_e32 v125, 1.0, v125
	v_div_scale_f32 v172, s[4:5], v125, v125, 1.0
	v_rcp_f32_e32 v173, v172
	s_nop 0
	v_fma_f32 v174, -v172, v173, 1.0
	v_fmac_f32_e32 v173, v174, v173
	v_div_scale_f32 v174, vcc, 1.0, v125, 1.0
	v_mul_f32_e32 v175, v174, v173
	v_fma_f32 v176, -v172, v175, v174
	v_fmac_f32_e32 v175, v176, v173
	v_fma_f32 v172, -v172, v175, v174
	v_div_fmas_f32 v172, v172, v173, v175
	v_div_fixup_f32 v125, v172, v125, 1.0
	v_mul_f32_e32 v125, v181, v125
	v_fmac_f32_e32 v147, v125, v163
	global_store_dword v131, v147, s[86:87] offset:64
	v_cvt_pk_bf16_f32 v125, v147, s0
	global_store_short v134, v125, s[88:89] offset:224
	v_add_f32_e32 v118, v118, v214
	v_mul_f32_e32 v118, 0xbfb8aa3b, v118
	v_exp_f32_e32 v118, v118
	v_lshlrev_b32_e32 v164, 16, v164
	v_add_f32_e32 v118, 1.0, v118
	v_div_scale_f32 v172, s[4:5], v118, v118, 1.0
	v_rcp_f32_e32 v173, v172
	s_nop 0
	v_fma_f32 v174, -v172, v173, 1.0
	v_fmac_f32_e32 v173, v174, v173
	v_div_scale_f32 v174, vcc, 1.0, v118, 1.0
	v_mul_f32_e32 v175, v174, v173
	v_fma_f32 v176, -v172, v175, v174
	v_fmac_f32_e32 v175, v176, v173
	v_fma_f32 v172, -v172, v175, v174
	v_div_fmas_f32 v172, v172, v173, v175
	v_div_fixup_f32 v118, v172, v118, 1.0
	v_mul_f32_e32 v118, v181, v118
	v_fmac_f32_e32 v148, v118, v164
	global_store_dword v130, v148, s[86:87] offset:-3968
	v_cvt_pk_bf16_f32 v118, v148, s0
	global_store_short v135, v118, s[88:89]
	v_add_f32_e32 v119, v119, v214
	v_mul_f32_e32 v119, 0xbfb8aa3b, v119
	v_exp_f32_e32 v119, v119
	v_lshlrev_b32_e32 v165, 16, v165
	v_add_f32_e32 v119, 1.0, v119
	v_div_scale_f32 v172, s[4:5], v119, v119, 1.0
	v_rcp_f32_e32 v173, v172
	s_nop 0
	v_fma_f32 v174, -v172, v173, 1.0
	v_fmac_f32_e32 v173, v174, v173
	v_div_scale_f32 v174, vcc, 1.0, v119, 1.0
	v_mul_f32_e32 v175, v174, v173
	v_fma_f32 v176, -v172, v175, v174
	v_fmac_f32_e32 v175, v176, v173
	v_fma_f32 v172, -v172, v175, v174
	v_div_fmas_f32 v172, v172, v173, v175
	v_div_fixup_f32 v119, v172, v119, 1.0
	v_mul_f32_e32 v119, v181, v119
	v_fmac_f32_e32 v149, v119, v165
	global_store_dword v130, v149, s[86:87] offset:128
	v_cvt_pk_bf16_f32 v119, v149, s0
	global_store_short v135, v119, s[88:89] offset:64
	v_add_f32_e32 v120, v120, v214
	v_mul_f32_e32 v120, 0xbfb8aa3b, v120
	v_exp_f32_e32 v120, v120
	v_lshlrev_b32_e32 v166, 16, v166
	v_add_f32_e32 v120, 1.0, v120
	v_div_scale_f32 v172, s[4:5], v120, v120, 1.0
	v_rcp_f32_e32 v173, v172
	s_nop 0
	v_fma_f32 v174, -v172, v173, 1.0
	v_fmac_f32_e32 v173, v174, v173
	v_div_scale_f32 v174, vcc, 1.0, v120, 1.0
	v_mul_f32_e32 v175, v174, v173
	v_fma_f32 v176, -v172, v175, v174
	v_fmac_f32_e32 v175, v176, v173
	v_fma_f32 v172, -v172, v175, v174
	v_div_fmas_f32 v172, v172, v173, v175
	v_div_fixup_f32 v120, v172, v120, 1.0
	v_mul_f32_e32 v120, v181, v120
	v_fmac_f32_e32 v150, v120, v166
	global_store_dword v131, v150, s[86:87] offset:-3968
	v_cvt_pk_bf16_f32 v120, v150, s0
	global_store_short v135, v120, s[88:89] offset:128
	v_add_f32_e32 v121, v121, v214
	v_mul_f32_e32 v121, 0xbfb8aa3b, v121
	v_exp_f32_e32 v121, v121
	v_lshlrev_b32_e32 v167, 16, v167
	v_add_f32_e32 v121, 1.0, v121
	v_div_scale_f32 v172, s[4:5], v121, v121, 1.0
	v_rcp_f32_e32 v173, v172
	s_nop 0
	v_fma_f32 v174, -v172, v173, 1.0
	v_fmac_f32_e32 v173, v174, v173
	v_div_scale_f32 v174, vcc, 1.0, v121, 1.0
; DEV u16 f2bf(float f) { return (u16)(pack2(f, 0.f) & 0xffffu); }
; DEV float bf2f(u16 b) { return __uint_as_float(((unsigned)b) << 16); }
; DEV size_t tixw(long row, int col, int W) { return (size_t)(row >> 8) * (256 * (size_t)W) + (size_t)(col >> 5) * 8192 + (size_t)(row & 255) * 32 + (col & 31); }
; DEV float sigmoidf_(float x) { return 1.f / (1.f + __expf(-x)); }
;     ...
;   for_tiles_pf(128, 8, [&](int mt, int nt, int mtn, int ntn, bool hn, bool first) {
;     f32x4 acc[8][4];
;     zero_acc<8>(acc);
;     int m0 = mt * 256, n0 = nt * 128;
;     gemm_mainloop<8>(acc, RowLin{xb + (size_t)m0 * D, 32}, 16384, Wg + (size_t)n0 * D, D, 0, 16, smem, 8192, 32, 4096,
;                      !first, hn, xb + (size_t)mtn * 256 * D, Wg + (size_t)ntn * 128 * D);
;     ...
;         for (int j = 0; j < 4; ++j) {
;           int row = m0 + wm * 128 + ms * 16 + quad * 4 + j;
;           int col = n0 + wn * 64 + ns * 16 + l15;
;           size_t idx = (size_t)row * D + col;
;           float gate = sigmoidf_(acc[ms][ns][j] + bg[col]);
;           float v = P.out[idx] + psc * gate * bf2f(Pp[idx]);
;           P.out[idx] = v;
;           xbn[tixw(row, col, D)] = f2bf(v);
	v_mul_f32_e32 v175, v174, v173
	v_fma_f32 v176, -v172, v175, v174
	v_fmac_f32_e32 v175, v176, v173
	v_fma_f32 v172, -v172, v175, v174
	v_div_fmas_f32 v172, v172, v173, v175
	v_div_fixup_f32 v121, v172, v121, 1.0
	v_mul_f32_e32 v121, v181, v121
	v_fmac_f32_e32 v151, v121, v167
	global_store_dword v131, v151, s[86:87] offset:128
	v_cvt_pk_bf16_f32 v121, v151, s0
	global_store_short v135, v121, s[88:89] offset:192
	v_add_f32_e32 v114, v114, v215
	v_mul_f32_e32 v114, 0xbfb8aa3b, v114
	v_exp_f32_e32 v114, v114
	v_lshlrev_b32_e32 v168, 16, v168
	v_add_f32_e32 v114, 1.0, v114
	v_div_scale_f32 v172, s[4:5], v114, v114, 1.0
	v_rcp_f32_e32 v173, v172
	s_nop 0
	v_fma_f32 v174, -v172, v173, 1.0
	v_fmac_f32_e32 v173, v174, v173
	v_div_scale_f32 v174, vcc, 1.0, v114, 1.0
	v_mul_f32_e32 v175, v174, v173
	v_fma_f32 v176, -v172, v175, v174
	v_fmac_f32_e32 v175, v176, v173
	v_fma_f32 v172, -v172, v175, v174
	v_div_fmas_f32 v172, v172, v173, v175
	v_div_fixup_f32 v114, v172, v114, 1.0
	v_mul_f32_e32 v114, v181, v114
	v_fmac_f32_e32 v152, v114, v168
	global_store_dword v130, v152, s[86:87] offset:-3904
	v_cvt_pk_bf16_f32 v114, v152, s0
	global_store_short v135, v114, s[88:89] offset:32
	v_add_f32_e32 v115, v115, v215
	v_mul_f32_e32 v115, 0xbfb8aa3b, v115
	v_exp_f32_e32 v115, v115
	v_lshlrev_b32_e32 v169, 16, v169
	v_add_f32_e32 v115, 1.0, v115
	v_div_scale_f32 v172, s[4:5], v115, v115, 1.0
	v_rcp_f32_e32 v173, v172
	s_nop 0
	v_fma_f32 v174, -v172, v173, 1.0
	v_fmac_f32_e32 v173, v174, v173
	v_div_scale_f32 v174, vcc, 1.0, v115, 1.0
	v_mul_f32_e32 v175, v174, v173
	v_fma_f32 v176, -v172, v175, v174
	v_fmac_f32_e32 v175, v176, v173
	v_fma_f32 v172, -v172, v175, v174
	v_div_fmas_f32 v172, v172, v173, v175
	v_div_fixup_f32 v115, v172, v115, 1.0
	v_mul_f32_e32 v115, v181, v115
	v_fmac_f32_e32 v153, v115, v169
	global_store_dword v130, v153, s[86:87] offset:192
	v_cvt_pk_bf16_f32 v115, v153, s0
	global_store_short v135, v115, s[88:89] offset:96
	v_add_f32_e32 v116, v116, v215
	v_mul_f32_e32 v116, 0xbfb8aa3b, v116
	v_exp_f32_e32 v116, v116
	v_lshlrev_b32_e32 v170, 16, v170
	v_add_f32_e32 v116, 1.0, v116
	v_div_scale_f32 v172, s[4:5], v116, v116, 1.0
	v_rcp_f32_e32 v173, v172
	s_nop 0
	v_fma_f32 v174, -v172, v173, 1.0
	v_fmac_f32_e32 v173, v174, v173
	v_div_scale_f32 v174, vcc, 1.0, v116, 1.0
	v_mul_f32_e32 v175, v174, v173
	v_fma_f32 v176, -v172, v175, v174
	v_fmac_f32_e32 v175, v176, v173
	v_fma_f32 v172, -v172, v175, v174
	v_div_fmas_f32 v172, v172, v173, v175
	v_div_fixup_f32 v116, v172, v116, 1.0
	v_mul_f32_e32 v116, v181, v116
	v_fmac_f32_e32 v154, v116, v170
	global_store_dword v131, v154, s[86:87] offset:-3904
	v_cvt_pk_bf16_f32 v116, v154, s0
	global_store_short v135, v116, s[88:89] offset:160
	v_add_f32_e32 v117, v117, v215
	v_mul_f32_e32 v117, 0xbfb8aa3b, v117
	v_exp_f32_e32 v117, v117
	v_lshlrev_b32_e32 v171, 16, v171
	v_add_f32_e32 v117, 1.0, v117
	v_div_scale_f32 v172, s[4:5], v117, v117, 1.0
	v_rcp_f32_e32 v173, v172
	s_nop 0
	v_fma_f32 v174, -v172, v173, 1.0
	v_fmac_f32_e32 v173, v174, v173
	v_div_scale_f32 v174, vcc, 1.0, v117, 1.0
	v_mul_f32_e32 v175, v174, v173
	v_fma_f32 v176, -v172, v175, v174
	v_fmac_f32_e32 v175, v176, v173
	v_fma_f32 v172, -v172, v175, v174
	v_div_fmas_f32 v172, v172, v173, v175
	v_div_fixup_f32 v117, v172, v117, 1.0
	v_mul_f32_e32 v117, v181, v117
	v_fmac_f32_e32 v155, v117, v171
	global_store_dword v131, v155, s[86:87] offset:192
	v_cvt_pk_bf16_f32 v117, v155, s0
	global_store_short v135, v117, s[88:89] offset:224
	v_add_u32_e32 v130, 0x10000, v136
	v_add_u32_e32 v131, 0x2000, v130
	v_lshrrev_b32_e32 v132, 1, v130
	v_lshrrev_b32_e32 v133, 1, v131
	global_load_dword v140, v130, s[86:87] offset:-4096
	global_load_dword v141, v130, s[86:87]
	global_load_dword v142, v131, s[86:87] offset:-4096
	global_load_dword v143, v131, s[86:87]
	global_load_dword v144, v130, s[86:87] offset:-4032
	global_load_dword v145, v130, s[86:87] offset:64
	global_load_dword v146, v131, s[86:87] offset:-4032
	global_load_dword v147, v131, s[86:87] offset:64
	global_load_dword v148, v130, s[86:87] offset:-3968
	global_load_dword v149, v130, s[86:87] offset:128
	global_load_dword v150, v131, s[86:87] offset:-3968
	global_load_dword v151, v131, s[86:87] offset:128
	global_load_dword v152, v130, s[86:87] offset:-3904
	global_load_dword v153, v130, s[86:87] offset:192
	global_load_dword v154, v131, s[86:87] offset:-3904
	global_load_dword v155, v131, s[86:87] offset:192
	global_load_ushort v156, v132, s[96:97] offset:-2048
	global_load_ushort v157, v132, s[96:97]
	global_load_ushort v158, v133, s[96:97] offset:-2048
	global_load_ushort v159, v133, s[96:97]
	global_load_ushort v160, v132, s[96:97] offset:-2016
	global_load_ushort v161, v132, s[96:97] offset:32
	global_load_ushort v162, v133, s[96:97] offset:-2016
	global_load_ushort v163, v133, s[96:97] offset:32
	global_load_ushort v164, v132, s[96:97] offset:-1984
	global_load_ushort v165, v132, s[96:97] offset:64
	global_load_ushort v166, v133, s[96:97] offset:-1984
	global_load_ushort v167, v133, s[96:97] offset:64
	global_load_ushort v168, v132, s[96:97] offset:-1952
	global_load_ushort v169, v132, s[96:97] offset:96
	global_load_ushort v170, v133, s[96:97] offset:-1952
	global_load_ushort v171, v133, s[96:97] offset:96
	s_waitcnt vmcnt(0)
; DEV u16 f2bf(float f) { return (u16)(pack2(f, 0.f) & 0xffffu); }
; DEV float bf2f(u16 b) { return __uint_as_float(((unsigned)b) << 16); }
; DEV size_t tixw(long row, int col, int W) { return (size_t)(row >> 8) * (256 * (size_t)W) + (size_t)(col >> 5) * 8192 + (size_t)(row & 255) * 32 + (col & 31); }
; DEV float sigmoidf_(float x) { return 1.f / (1.f + __expf(-x)); }
;     ...
;         for (int j = 0; j < 4; ++j) {
;           int row = m0 + wm * 128 + ms * 16 + quad * 4 + j;
;           int col = n0 + wn * 64 + ns * 16 + l15;
;           size_t idx = (size_t)row * D + col;
;           float gate = sigmoidf_(acc[ms][ns][j] + bg[col]);
;           float v = P.out[idx] + psc * gate * bf2f(Pp[idx]);
;           P.out[idx] = v;
;           xbn[tixw(row, col, D)] = f2bf(v);
	v_add_f32_e32 v110, v110, v138
	v_mul_f32_e32 v110, 0xbfb8aa3b, v110
	v_exp_f32_e32 v110, v110
	v_lshlrev_b32_e32 v156, 16, v156
	v_add_f32_e32 v110, 1.0, v110
	v_div_scale_f32 v172, s[4:5], v110, v110, 1.0
	v_rcp_f32_e32 v173, v172
	s_nop 0
	v_fma_f32 v174, -v172, v173, 1.0
	v_fmac_f32_e32 v173, v174, v173
	v_div_scale_f32 v174, vcc, 1.0, v110, 1.0
	v_mul_f32_e32 v175, v174, v173
	v_fma_f32 v176, -v172, v175, v174
	v_fmac_f32_e32 v175, v176, v173
	v_fma_f32 v172, -v172, v175, v174
	v_div_fmas_f32 v172, v172, v173, v175
	v_div_fixup_f32 v110, v172, v110, 1.0
	v_mul_f32_e32 v110, v181, v110
	v_fmac_f32_e32 v140, v110, v156
	global_store_dword v130, v140, s[86:87] offset:-4096
	v_cvt_pk_bf16_f32 v110, v140, s0
	global_store_short v134, v110, s[88:89] offset:1024
	v_add_f32_e32 v111, v111, v138
	v_mul_f32_e32 v111, 0xbfb8aa3b, v111
	v_exp_f32_e32 v111, v111
	v_lshlrev_b32_e32 v157, 16, v157
	v_add_f32_e32 v111, 1.0, v111
	v_div_scale_f32 v172, s[4:5], v111, v111, 1.0
	v_rcp_f32_e32 v173, v172
	s_nop 0
	v_fma_f32 v174, -v172, v173, 1.0
	v_fmac_f32_e32 v173, v174, v173
	v_div_scale_f32 v174, vcc, 1.0, v111, 1.0
	v_mul_f32_e32 v175, v174, v173
	v_fma_f32 v176, -v172, v175, v174
	v_fmac_f32_e32 v175, v176, v173
	v_fma_f32 v172, -v172, v175, v174
	v_div_fmas_f32 v172, v172, v173, v175
	v_div_fixup_f32 v111, v172, v111, 1.0
	v_mul_f32_e32 v111, v181, v111
	v_fmac_f32_e32 v141, v111, v157
	global_store_dword v130, v141, s[86:87]
	v_cvt_pk_bf16_f32 v111, v141, s0
	global_store_short v134, v111, s[88:89] offset:1088
	v_add_f32_e32 v112, v112, v138
	v_mul_f32_e32 v112, 0xbfb8aa3b, v112
	v_exp_f32_e32 v112, v112
	v_lshlrev_b32_e32 v158, 16, v158
	v_add_f32_e32 v112, 1.0, v112
	v_div_scale_f32 v172, s[4:5], v112, v112, 1.0
	v_rcp_f32_e32 v173, v172
	s_nop 0
	v_fma_f32 v174, -v172, v173, 1.0
	v_fmac_f32_e32 v173, v174, v173
	v_div_scale_f32 v174, vcc, 1.0, v112, 1.0
	v_mul_f32_e32 v175, v174, v173
	v_fma_f32 v176, -v172, v175, v174
	v_fmac_f32_e32 v175, v176, v173
	v_fma_f32 v172, -v172, v175, v174
	v_div_fmas_f32 v172, v172, v173, v175
	v_div_fixup_f32 v112, v172, v112, 1.0
	v_mul_f32_e32 v112, v181, v112
	v_fmac_f32_e32 v142, v112, v158
	global_store_dword v131, v142, s[86:87] offset:-4096
	v_cvt_pk_bf16_f32 v112, v142, s0
	global_store_short v134, v112, s[88:89] offset:1152
	v_add_f32_e32 v113, v113, v138
	v_mul_f32_e32 v113, 0xbfb8aa3b, v113
	v_exp_f32_e32 v113, v113
	v_lshlrev_b32_e32 v159, 16, v159
	v_add_f32_e32 v113, 1.0, v113
	v_div_scale_f32 v172, s[4:5], v113, v113, 1.0
	v_rcp_f32_e32 v173, v172
	s_nop 0
	v_fma_f32 v174, -v172, v173, 1.0
	v_fmac_f32_e32 v173, v174, v173
	v_div_scale_f32 v174, vcc, 1.0, v113, 1.0
	v_mul_f32_e32 v175, v174, v173
	v_fma_f32 v176, -v172, v175, v174
	v_fmac_f32_e32 v175, v176, v173
	v_fma_f32 v172, -v172, v175, v174
	v_div_fmas_f32 v172, v172, v173, v175
	v_div_fixup_f32 v113, v172, v113, 1.0
	v_mul_f32_e32 v113, v181, v113
	v_fmac_f32_e32 v143, v113, v159
	global_store_dword v131, v143, s[86:87]
	v_cvt_pk_bf16_f32 v113, v143, s0
	global_store_short v134, v113, s[88:89] offset:1216
	v_add_f32_e32 v106, v106, v139
	v_mul_f32_e32 v106, 0xbfb8aa3b, v106
	v_exp_f32_e32 v106, v106
	v_lshlrev_b32_e32 v160, 16, v160
	v_add_f32_e32 v106, 1.0, v106
	v_div_scale_f32 v172, s[4:5], v106, v106, 1.0
	v_rcp_f32_e32 v173, v172
	s_nop 0
	v_fma_f32 v174, -v172, v173, 1.0
	v_fmac_f32_e32 v173, v174, v173
	v_div_scale_f32 v174, vcc, 1.0, v106, 1.0
	v_mul_f32_e32 v175, v174, v173
	v_fma_f32 v176, -v172, v175, v174
	v_fmac_f32_e32 v175, v176, v173
	v_fma_f32 v172, -v172, v175, v174
	v_div_fmas_f32 v172, v172, v173, v175
	v_div_fixup_f32 v106, v172, v106, 1.0
	v_mul_f32_e32 v106, v181, v106
	v_fmac_f32_e32 v144, v106, v160
	global_store_dword v130, v144, s[86:87] offset:-4032
	v_cvt_pk_bf16_f32 v106, v144, s0
	global_store_short v134, v106, s[88:89] offset:1056
	v_add_f32_e32 v107, v107, v139
	v_mul_f32_e32 v107, 0xbfb8aa3b, v107
	v_exp_f32_e32 v107, v107
	v_lshlrev_b32_e32 v161, 16, v161
	v_add_f32_e32 v107, 1.0, v107
	v_div_scale_f32 v172, s[4:5], v107, v107, 1.0
	v_rcp_f32_e32 v173, v172
	s_nop 0
	v_fma_f32 v174, -v172, v173, 1.0
	v_fmac_f32_e32 v173, v174, v173
	v_div_scale_f32 v174, vcc, 1.0, v107, 1.0
	v_mul_f32_e32 v175, v174, v173
	v_fma_f32 v176, -v172, v175, v174
	v_fmac_f32_e32 v175, v176, v173
	v_fma_f32 v172, -v172, v175, v174
	v_div_fmas_f32 v172, v172, v173, v175
	v_div_fixup_f32 v107, v172, v107, 1.0
	v_mul_f32_e32 v107, v181, v107
	v_fmac_f32_e32 v145, v107, v161
	global_store_dword v130, v145, s[86:87] offset:64
	v_cvt_pk_bf16_f32 v107, v145, s0
	global_store_short v134, v107, s[88:89] offset:1120
	v_add_f32_e32 v108, v108, v139
	v_mul_f32_e32 v108, 0xbfb8aa3b, v108
	v_exp_f32_e32 v108, v108
	v_lshlrev_b32_e32 v162, 16, v162
	v_add_f32_e32 v108, 1.0, v108
	v_div_scale_f32 v172, s[4:5], v108, v108, 1.0
	v_rcp_f32_e32 v173, v172
	s_nop 0
	v_fma_f32 v174, -v172, v173, 1.0
	v_fmac_f32_e32 v173, v174, v173
	v_div_scale_f32 v174, vcc, 1.0, v108, 1.0
	v_mul_f32_e32 v175, v174, v173
	v_fma_f32 v176, -v172, v175, v174
	v_fmac_f32_e32 v175, v176, v173
	v_fma_f32 v172, -v172, v175, v174
	v_div_fmas_f32 v172, v172, v173, v175
	v_div_fixup_f32 v108, v172, v108, 1.0
	v_mul_f32_e32 v108, v181, v108
	v_fmac_f32_e32 v146, v108, v162
	global_store_dword v131, v146, s[86:87] offset:-4032
	v_cvt_pk_bf16_f32 v108, v146, s0
	global_store_short v134, v108, s[88:89] offset:1184
	v_add_f32_e32 v109, v109, v139
	v_mul_f32_e32 v109, 0xbfb8aa3b, v109
	v_exp_f32_e32 v109, v109
	v_lshlrev_b32_e32 v163, 16, v163
	v_add_f32_e32 v109, 1.0, v109
	v_div_scale_f32 v172, s[4:5], v109, v109, 1.0
	v_rcp_f32_e32 v173, v172
	s_nop 0
	v_fma_f32 v174, -v172, v173, 1.0
; DEV u16 f2bf(float f) { return (u16)(pack2(f, 0.f) & 0xffffu); }
; DEV float bf2f(u16 b) { return __uint_as_float(((unsigned)b) << 16); }
; DEV size_t tixw(long row, int col, int W) { return (size_t)(row >> 8) * (256 * (size_t)W) + (size_t)(col >> 5) * 8192 + (size_t)(row & 255) * 32 + (col & 31); }
; DEV float sigmoidf_(float x) { return 1.f / (1.f + __expf(-x)); }
;     ...
;         for (int j = 0; j < 4; ++j) {
;           int row = m0 + wm * 128 + ms * 16 + quad * 4 + j;
;           int col = n0 + wn * 64 + ns * 16 + l15;
;           size_t idx = (size_t)row * D + col;
;           float gate = sigmoidf_(acc[ms][ns][j] + bg[col]);
;           float v = P.out[idx] + psc * gate * bf2f(Pp[idx]);
;           P.out[idx] = v;
;           xbn[tixw(row, col, D)] = f2bf(v);
	v_fmac_f32_e32 v173, v174, v173
	v_div_scale_f32 v174, vcc, 1.0, v109, 1.0
	v_mul_f32_e32 v175, v174, v173
	v_fma_f32 v176, -v172, v175, v174
	v_fmac_f32_e32 v175, v176, v173
	v_fma_f32 v172, -v172, v175, v174
	v_div_fmas_f32 v172, v172, v173, v175
	v_div_fixup_f32 v109, v172, v109, 1.0
	v_mul_f32_e32 v109, v181, v109
	v_fmac_f32_e32 v147, v109, v163
	global_store_dword v131, v147, s[86:87] offset:64
	v_cvt_pk_bf16_f32 v109, v147, s0
	global_store_short v134, v109, s[88:89] offset:1248
	v_add_f32_e32 v102, v102, v214
	v_mul_f32_e32 v102, 0xbfb8aa3b, v102
	v_exp_f32_e32 v102, v102
	v_lshlrev_b32_e32 v164, 16, v164
	v_add_f32_e32 v102, 1.0, v102
	v_div_scale_f32 v172, s[4:5], v102, v102, 1.0
	v_rcp_f32_e32 v173, v172
	s_nop 0
	v_fma_f32 v174, -v172, v173, 1.0
	v_fmac_f32_e32 v173, v174, v173
	v_div_scale_f32 v174, vcc, 1.0, v102, 1.0
	v_mul_f32_e32 v175, v174, v173
	v_fma_f32 v176, -v172, v175, v174
	v_fmac_f32_e32 v175, v176, v173
	v_fma_f32 v172, -v172, v175, v174
	v_div_fmas_f32 v172, v172, v173, v175
	v_div_fixup_f32 v102, v172, v102, 1.0
	v_mul_f32_e32 v102, v181, v102
	v_fmac_f32_e32 v148, v102, v164
	global_store_dword v130, v148, s[86:87] offset:-3968
	v_cvt_pk_bf16_f32 v102, v148, s0
	global_store_short v135, v102, s[88:89] offset:1024
	v_add_f32_e32 v103, v103, v214
	v_mul_f32_e32 v103, 0xbfb8aa3b, v103
	v_exp_f32_e32 v103, v103
	v_lshlrev_b32_e32 v165, 16, v165
	v_add_f32_e32 v103, 1.0, v103
	v_div_scale_f32 v172, s[4:5], v103, v103, 1.0
	v_rcp_f32_e32 v173, v172
	s_nop 0
	v_fma_f32 v174, -v172, v173, 1.0
	v_fmac_f32_e32 v173, v174, v173
	v_div_scale_f32 v174, vcc, 1.0, v103, 1.0
	v_mul_f32_e32 v175, v174, v173
	v_fma_f32 v176, -v172, v175, v174
	v_fmac_f32_e32 v175, v176, v173
	v_fma_f32 v172, -v172, v175, v174
	v_div_fmas_f32 v172, v172, v173, v175
	v_div_fixup_f32 v103, v172, v103, 1.0
	v_mul_f32_e32 v103, v181, v103
	v_fmac_f32_e32 v149, v103, v165
	global_store_dword v130, v149, s[86:87] offset:128
	v_cvt_pk_bf16_f32 v103, v149, s0
	global_store_short v135, v103, s[88:89] offset:1088
	v_add_f32_e32 v104, v104, v214
	v_mul_f32_e32 v104, 0xbfb8aa3b, v104
	v_exp_f32_e32 v104, v104
	v_lshlrev_b32_e32 v166, 16, v166
	v_add_f32_e32 v104, 1.0, v104
	v_div_scale_f32 v172, s[4:5], v104, v104, 1.0
	v_rcp_f32_e32 v173, v172
	s_nop 0
	v_fma_f32 v174, -v172, v173, 1.0
	v_fmac_f32_e32 v173, v174, v173
	v_div_scale_f32 v174, vcc, 1.0, v104, 1.0
	v_mul_f32_e32 v175, v174, v173
	v_fma_f32 v176, -v172, v175, v174
	v_fmac_f32_e32 v175, v176, v173
	v_fma_f32 v172, -v172, v175, v174
	v_div_fmas_f32 v172, v172, v173, v175
	v_div_fixup_f32 v104, v172, v104, 1.0
	v_mul_f32_e32 v104, v181, v104
	v_fmac_f32_e32 v150, v104, v166
	global_store_dword v131, v150, s[86:87] offset:-3968
	v_cvt_pk_bf16_f32 v104, v150, s0
	global_store_short v135, v104, s[88:89] offset:1152
	v_add_f32_e32 v105, v105, v214
	v_mul_f32_e32 v105, 0xbfb8aa3b, v105
	v_exp_f32_e32 v105, v105
	v_lshlrev_b32_e32 v167, 16, v167
	v_add_f32_e32 v105, 1.0, v105
	v_div_scale_f32 v172, s[4:5], v105, v105, 1.0
	v_rcp_f32_e32 v173, v172
	s_nop 0
	v_fma_f32 v174, -v172, v173, 1.0
	v_fmac_f32_e32 v173, v174, v173
	v_div_scale_f32 v174, vcc, 1.0, v105, 1.0
	v_mul_f32_e32 v175, v174, v173
	v_fma_f32 v176, -v172, v175, v174
	v_fmac_f32_e32 v175, v176, v173
	v_fma_f32 v172, -v172, v175, v174
	v_div_fmas_f32 v172, v172, v173, v175
	v_div_fixup_f32 v105, v172, v105, 1.0
	v_mul_f32_e32 v105, v181, v105
	v_fmac_f32_e32 v151, v105, v167
	global_store_dword v131, v151, s[86:87] offset:128
	v_cvt_pk_bf16_f32 v105, v151, s0
	global_store_short v135, v105, s[88:89] offset:1216
	v_add_f32_e32 v98, v98, v215
	v_mul_f32_e32 v98, 0xbfb8aa3b, v98
	v_exp_f32_e32 v98, v98
	v_lshlrev_b32_e32 v168, 16, v168
	v_add_f32_e32 v98, 1.0, v98
	v_div_scale_f32 v172, s[4:5], v98, v98, 1.0
	v_rcp_f32_e32 v173, v172
	s_nop 0
	v_fma_f32 v174, -v172, v173, 1.0
	v_fmac_f32_e32 v173, v174, v173
	v_div_scale_f32 v174, vcc, 1.0, v98, 1.0
	v_mul_f32_e32 v175, v174, v173
	v_fma_f32 v176, -v172, v175, v174
	v_fmac_f32_e32 v175, v176, v173
	v_fma_f32 v172, -v172, v175, v174
	v_div_fmas_f32 v172, v172, v173, v175
	v_div_fixup_f32 v98, v172, v98, 1.0
	v_mul_f32_e32 v98, v181, v98
	v_fmac_f32_e32 v152, v98, v168
	global_store_dword v130, v152, s[86:87] offset:-3904
	v_cvt_pk_bf16_f32 v98, v152, s0
	global_store_short v135, v98, s[88:89] offset:1056
	v_add_f32_e32 v99, v99, v215
	v_mul_f32_e32 v99, 0xbfb8aa3b, v99
	v_exp_f32_e32 v99, v99
	v_lshlrev_b32_e32 v169, 16, v169
	v_add_f32_e32 v99, 1.0, v99
	v_div_scale_f32 v172, s[4:5], v99, v99, 1.0
	v_rcp_f32_e32 v173, v172
	s_nop 0
	v_fma_f32 v174, -v172, v173, 1.0
	v_fmac_f32_e32 v173, v174, v173
	v_div_scale_f32 v174, vcc, 1.0, v99, 1.0
	v_mul_f32_e32 v175, v174, v173
	v_fma_f32 v176, -v172, v175, v174
	v_fmac_f32_e32 v175, v176, v173
	v_fma_f32 v172, -v172, v175, v174
	v_div_fmas_f32 v172, v172, v173, v175
	v_div_fixup_f32 v99, v172, v99, 1.0
	v_mul_f32_e32 v99, v181, v99
	v_fmac_f32_e32 v153, v99, v169
	global_store_dword v130, v153, s[86:87] offset:192
	v_cvt_pk_bf16_f32 v99, v153, s0
	global_store_short v135, v99, s[88:89] offset:1120
	v_add_f32_e32 v100, v100, v215
	v_mul_f32_e32 v100, 0xbfb8aa3b, v100
	v_exp_f32_e32 v100, v100
	v_lshlrev_b32_e32 v170, 16, v170
	v_add_f32_e32 v100, 1.0, v100
	v_div_scale_f32 v172, s[4:5], v100, v100, 1.0
	v_rcp_f32_e32 v173, v172
	s_nop 0
	v_fma_f32 v174, -v172, v173, 1.0
	v_fmac_f32_e32 v173, v174, v173
	v_div_scale_f32 v174, vcc, 1.0, v100, 1.0
	v_mul_f32_e32 v175, v174, v173
	v_fma_f32 v176, -v172, v175, v174
	v_fmac_f32_e32 v175, v176, v173
	v_fma_f32 v172, -v172, v175, v174
	v_div_fmas_f32 v172, v172, v173, v175
	v_div_fixup_f32 v100, v172, v100, 1.0
; DEV u16 f2bf(float f) { return (u16)(pack2(f, 0.f) & 0xffffu); }
; DEV float bf2f(u16 b) { return __uint_as_float(((unsigned)b) << 16); }
; DEV size_t tixw(long row, int col, int W) { return (size_t)(row >> 8) * (256 * (size_t)W) + (size_t)(col >> 5) * 8192 + (size_t)(row & 255) * 32 + (col & 31); }
; DEV float sigmoidf_(float x) { return 1.f / (1.f + __expf(-x)); }
;     ...
;   for_tiles_pf(128, 8, [&](int mt, int nt, int mtn, int ntn, bool hn, bool first) {
;     f32x4 acc[8][4];
;     zero_acc<8>(acc);
;     int m0 = mt * 256, n0 = nt * 128;
;     gemm_mainloop<8>(acc, RowLin{xb + (size_t)m0 * D, 32}, 16384, Wg + (size_t)n0 * D, D, 0, 16, smem, 8192, 32, 4096,
;                      !first, hn, xb + (size_t)mtn * 256 * D, Wg + (size_t)ntn * 128 * D);
;     ...
;         for (int j = 0; j < 4; ++j) {
;           int row = m0 + wm * 128 + ms * 16 + quad * 4 + j;
;           int col = n0 + wn * 64 + ns * 16 + l15;
;           size_t idx = (size_t)row * D + col;
;           float gate = sigmoidf_(acc[ms][ns][j] + bg[col]);
;           float v = P.out[idx] + psc * gate * bf2f(Pp[idx]);
;           P.out[idx] = v;
;           xbn[tixw(row, col, D)] = f2bf(v);
	v_mul_f32_e32 v100, v181, v100
	v_fmac_f32_e32 v154, v100, v170
	global_store_dword v131, v154, s[86:87] offset:-3904
	v_cvt_pk_bf16_f32 v100, v154, s0
	global_store_short v135, v100, s[88:89] offset:1184
	v_add_f32_e32 v101, v101, v215
	v_mul_f32_e32 v101, 0xbfb8aa3b, v101
	v_exp_f32_e32 v101, v101
	v_lshlrev_b32_e32 v171, 16, v171
	v_add_f32_e32 v101, 1.0, v101
	v_div_scale_f32 v172, s[4:5], v101, v101, 1.0
	v_rcp_f32_e32 v173, v172
	s_nop 0
	v_fma_f32 v174, -v172, v173, 1.0
	v_fmac_f32_e32 v173, v174, v173
	v_div_scale_f32 v174, vcc, 1.0, v101, 1.0
	v_mul_f32_e32 v175, v174, v173
	v_fma_f32 v176, -v172, v175, v174
	v_fmac_f32_e32 v175, v176, v173
	v_fma_f32 v172, -v172, v175, v174
	v_div_fmas_f32 v172, v172, v173, v175
	v_div_fixup_f32 v101, v172, v101, 1.0
	v_mul_f32_e32 v101, v181, v101
	v_fmac_f32_e32 v155, v101, v171
	global_store_dword v131, v155, s[86:87] offset:192
	v_cvt_pk_bf16_f32 v101, v155, s0
	global_store_short v135, v101, s[88:89] offset:1248
	v_add_u32_e32 v130, 0x20000, v136
	v_add_u32_e32 v131, 0x2000, v130
	v_lshrrev_b32_e32 v132, 1, v130
	v_lshrrev_b32_e32 v133, 1, v131
	global_load_dword v140, v130, s[86:87] offset:-4096
	global_load_dword v141, v130, s[86:87]
	global_load_dword v142, v131, s[86:87] offset:-4096
	global_load_dword v143, v131, s[86:87]
	global_load_dword v144, v130, s[86:87] offset:-4032
	global_load_dword v145, v130, s[86:87] offset:64
	global_load_dword v146, v131, s[86:87] offset:-4032
	global_load_dword v147, v131, s[86:87] offset:64
	global_load_dword v148, v130, s[86:87] offset:-3968
	global_load_dword v149, v130, s[86:87] offset:128
	global_load_dword v150, v131, s[86:87] offset:-3968
	global_load_dword v151, v131, s[86:87] offset:128
	global_load_dword v152, v130, s[86:87] offset:-3904
	global_load_dword v153, v130, s[86:87] offset:192
	global_load_dword v154, v131, s[86:87] offset:-3904
	global_load_dword v155, v131, s[86:87] offset:192
	global_load_ushort v156, v132, s[96:97] offset:-2048
	global_load_ushort v157, v132, s[96:97]
	global_load_ushort v158, v133, s[96:97] offset:-2048
	global_load_ushort v159, v133, s[96:97]
	global_load_ushort v160, v132, s[96:97] offset:-2016
	global_load_ushort v161, v132, s[96:97] offset:32
	global_load_ushort v162, v133, s[96:97] offset:-2016
	global_load_ushort v163, v133, s[96:97] offset:32
	global_load_ushort v164, v132, s[96:97] offset:-1984
	global_load_ushort v165, v132, s[96:97] offset:64
	global_load_ushort v166, v133, s[96:97] offset:-1984
	global_load_ushort v167, v133, s[96:97] offset:64
	global_load_ushort v168, v132, s[96:97] offset:-1952
	global_load_ushort v169, v132, s[96:97] offset:96
	global_load_ushort v170, v133, s[96:97] offset:-1952
	global_load_ushort v171, v133, s[96:97] offset:96
	s_waitcnt vmcnt(0)
	v_add_f32_e32 v94, v94, v138
	v_mul_f32_e32 v94, 0xbfb8aa3b, v94
	v_exp_f32_e32 v94, v94
	v_lshlrev_b32_e32 v156, 16, v156
	v_add_f32_e32 v94, 1.0, v94
	v_div_scale_f32 v172, s[4:5], v94, v94, 1.0
	v_rcp_f32_e32 v173, v172
	s_nop 0
	v_fma_f32 v174, -v172, v173, 1.0
	v_fmac_f32_e32 v173, v174, v173
	v_div_scale_f32 v174, vcc, 1.0, v94, 1.0
	v_mul_f32_e32 v175, v174, v173
	v_fma_f32 v176, -v172, v175, v174
	v_fmac_f32_e32 v175, v176, v173
	v_fma_f32 v172, -v172, v175, v174
	v_div_fmas_f32 v172, v172, v173, v175
	v_div_fixup_f32 v94, v172, v94, 1.0
	v_mul_f32_e32 v94, v181, v94
	v_fmac_f32_e32 v140, v94, v156
	global_store_dword v130, v140, s[86:87] offset:-4096
	v_cvt_pk_bf16_f32 v94, v140, s0
	global_store_short v134, v94, s[88:89] offset:2048
	v_add_f32_e32 v95, v95, v138
	v_mul_f32_e32 v95, 0xbfb8aa3b, v95
	v_exp_f32_e32 v95, v95
	v_lshlrev_b32_e32 v157, 16, v157
	v_add_f32_e32 v95, 1.0, v95
	v_div_scale_f32 v172, s[4:5], v95, v95, 1.0
	v_rcp_f32_e32 v173, v172
	s_nop 0
	v_fma_f32 v174, -v172, v173, 1.0
	v_fmac_f32_e32 v173, v174, v173
	v_div_scale_f32 v174, vcc, 1.0, v95, 1.0
	v_mul_f32_e32 v175, v174, v173
	v_fma_f32 v176, -v172, v175, v174
	v_fmac_f32_e32 v175, v176, v173
	v_fma_f32 v172, -v172, v175, v174
	v_div_fmas_f32 v172, v172, v173, v175
	v_div_fixup_f32 v95, v172, v95, 1.0
	v_mul_f32_e32 v95, v181, v95
	v_fmac_f32_e32 v141, v95, v157
	global_store_dword v130, v141, s[86:87]
	v_cvt_pk_bf16_f32 v95, v141, s0
	global_store_short v134, v95, s[88:89] offset:2112
	v_add_f32_e32 v96, v96, v138
	v_mul_f32_e32 v96, 0xbfb8aa3b, v96
	v_exp_f32_e32 v96, v96
	v_lshlrev_b32_e32 v158, 16, v158
	v_add_f32_e32 v96, 1.0, v96
	v_div_scale_f32 v172, s[4:5], v96, v96, 1.0
	v_rcp_f32_e32 v173, v172
	s_nop 0
	v_fma_f32 v174, -v172, v173, 1.0
	v_fmac_f32_e32 v173, v174, v173
	v_div_scale_f32 v174, vcc, 1.0, v96, 1.0
	v_mul_f32_e32 v175, v174, v173
	v_fma_f32 v176, -v172, v175, v174
	v_fmac_f32_e32 v175, v176, v173
	v_fma_f32 v172, -v172, v175, v174
	v_div_fmas_f32 v172, v172, v173, v175
	v_div_fixup_f32 v96, v172, v96, 1.0
	v_mul_f32_e32 v96, v181, v96
	v_fmac_f32_e32 v142, v96, v158
	global_store_dword v131, v142, s[86:87] offset:-4096
	v_cvt_pk_bf16_f32 v96, v142, s0
	global_store_short v134, v96, s[88:89] offset:2176
	v_add_f32_e32 v97, v97, v138
	v_mul_f32_e32 v97, 0xbfb8aa3b, v97
	v_exp_f32_e32 v97, v97
	v_lshlrev_b32_e32 v159, 16, v159
	v_add_f32_e32 v97, 1.0, v97
	v_div_scale_f32 v172, s[4:5], v97, v97, 1.0
	v_rcp_f32_e32 v173, v172
	s_nop 0
	v_fma_f32 v174, -v172, v173, 1.0
	v_fmac_f32_e32 v173, v174, v173
	v_div_scale_f32 v174, vcc, 1.0, v97, 1.0
	v_mul_f32_e32 v175, v174, v173
	v_fma_f32 v176, -v172, v175, v174
	v_fmac_f32_e32 v175, v176, v173
	v_fma_f32 v172, -v172, v175, v174
	v_div_fmas_f32 v172, v172, v173, v175
	v_div_fixup_f32 v97, v172, v97, 1.0
	v_mul_f32_e32 v97, v181, v97
	v_fmac_f32_e32 v143, v97, v159
; DEV u16 f2bf(float f) { return (u16)(pack2(f, 0.f) & 0xffffu); }
; DEV float bf2f(u16 b) { return __uint_as_float(((unsigned)b) << 16); }
; DEV size_t tixw(long row, int col, int W) { return (size_t)(row >> 8) * (256 * (size_t)W) + (size_t)(col >> 5) * 8192 + (size_t)(row & 255) * 32 + (col & 31); }
; DEV float sigmoidf_(float x) { return 1.f / (1.f + __expf(-x)); }
;     ...
;         for (int j = 0; j < 4; ++j) {
;           int row = m0 + wm * 128 + ms * 16 + quad * 4 + j;
;           int col = n0 + wn * 64 + ns * 16 + l15;
;           size_t idx = (size_t)row * D + col;
;           float gate = sigmoidf_(acc[ms][ns][j] + bg[col]);
;           float v = P.out[idx] + psc * gate * bf2f(Pp[idx]);
;           P.out[idx] = v;
;           xbn[tixw(row, col, D)] = f2bf(v);
	global_store_dword v131, v143, s[86:87]
	v_cvt_pk_bf16_f32 v97, v143, s0
	global_store_short v134, v97, s[88:89] offset:2240
	v_add_f32_e32 v90, v90, v139
	v_mul_f32_e32 v90, 0xbfb8aa3b, v90
	v_exp_f32_e32 v90, v90
	v_lshlrev_b32_e32 v160, 16, v160
	v_add_f32_e32 v90, 1.0, v90
	v_div_scale_f32 v172, s[4:5], v90, v90, 1.0
	v_rcp_f32_e32 v173, v172
	s_nop 0
	v_fma_f32 v174, -v172, v173, 1.0
	v_fmac_f32_e32 v173, v174, v173
	v_div_scale_f32 v174, vcc, 1.0, v90, 1.0
	v_mul_f32_e32 v175, v174, v173
	v_fma_f32 v176, -v172, v175, v174
	v_fmac_f32_e32 v175, v176, v173
	v_fma_f32 v172, -v172, v175, v174
	v_div_fmas_f32 v172, v172, v173, v175
	v_div_fixup_f32 v90, v172, v90, 1.0
	v_mul_f32_e32 v90, v181, v90
	v_fmac_f32_e32 v144, v90, v160
	global_store_dword v130, v144, s[86:87] offset:-4032
	v_cvt_pk_bf16_f32 v90, v144, s0
	global_store_short v134, v90, s[88:89] offset:2080
	v_add_f32_e32 v91, v91, v139
	v_mul_f32_e32 v91, 0xbfb8aa3b, v91
	v_exp_f32_e32 v91, v91
	v_lshlrev_b32_e32 v161, 16, v161
	v_add_f32_e32 v91, 1.0, v91
	v_div_scale_f32 v172, s[4:5], v91, v91, 1.0
	v_rcp_f32_e32 v173, v172
	s_nop 0
	v_fma_f32 v174, -v172, v173, 1.0
	v_fmac_f32_e32 v173, v174, v173
	v_div_scale_f32 v174, vcc, 1.0, v91, 1.0
	v_mul_f32_e32 v175, v174, v173
	v_fma_f32 v176, -v172, v175, v174
	v_fmac_f32_e32 v175, v176, v173
	v_fma_f32 v172, -v172, v175, v174
	v_div_fmas_f32 v172, v172, v173, v175
	v_div_fixup_f32 v91, v172, v91, 1.0
	v_mul_f32_e32 v91, v181, v91
	v_fmac_f32_e32 v145, v91, v161
	global_store_dword v130, v145, s[86:87] offset:64
	v_cvt_pk_bf16_f32 v91, v145, s0
	global_store_short v134, v91, s[88:89] offset:2144
	v_add_f32_e32 v92, v92, v139
	v_mul_f32_e32 v92, 0xbfb8aa3b, v92
	v_exp_f32_e32 v92, v92
	v_lshlrev_b32_e32 v162, 16, v162
	v_add_f32_e32 v92, 1.0, v92
	v_div_scale_f32 v172, s[4:5], v92, v92, 1.0
	v_rcp_f32_e32 v173, v172
	s_nop 0
	v_fma_f32 v174, -v172, v173, 1.0
	v_fmac_f32_e32 v173, v174, v173
	v_div_scale_f32 v174, vcc, 1.0, v92, 1.0
	v_mul_f32_e32 v175, v174, v173
	v_fma_f32 v176, -v172, v175, v174
	v_fmac_f32_e32 v175, v176, v173
	v_fma_f32 v172, -v172, v175, v174
	v_div_fmas_f32 v172, v172, v173, v175
	v_div_fixup_f32 v92, v172, v92, 1.0
	v_mul_f32_e32 v92, v181, v92
	v_fmac_f32_e32 v146, v92, v162
	global_store_dword v131, v146, s[86:87] offset:-4032
	v_cvt_pk_bf16_f32 v92, v146, s0
	global_store_short v134, v92, s[88:89] offset:2208
	v_add_f32_e32 v93, v93, v139
	v_mul_f32_e32 v93, 0xbfb8aa3b, v93
	v_exp_f32_e32 v93, v93
	v_lshlrev_b32_e32 v163, 16, v163
	v_add_f32_e32 v93, 1.0, v93
	v_div_scale_f32 v172, s[4:5], v93, v93, 1.0
	v_rcp_f32_e32 v173, v172
	s_nop 0
	v_fma_f32 v174, -v172, v173, 1.0
	v_fmac_f32_e32 v173, v174, v173
	v_div_scale_f32 v174, vcc, 1.0, v93, 1.0
	v_mul_f32_e32 v175, v174, v173
	v_fma_f32 v176, -v172, v175, v174
	v_fmac_f32_e32 v175, v176, v173
	v_fma_f32 v172, -v172, v175, v174
	v_div_fmas_f32 v172, v172, v173, v175
	v_div_fixup_f32 v93, v172, v93, 1.0
	v_mul_f32_e32 v93, v181, v93
	v_fmac_f32_e32 v147, v93, v163
	global_store_dword v131, v147, s[86:87] offset:64
	v_cvt_pk_bf16_f32 v93, v147, s0
	global_store_short v134, v93, s[88:89] offset:2272
	v_add_f32_e32 v86, v86, v214
	v_mul_f32_e32 v86, 0xbfb8aa3b, v86
	v_exp_f32_e32 v86, v86
	v_lshlrev_b32_e32 v164, 16, v164
	v_add_f32_e32 v86, 1.0, v86
	v_div_scale_f32 v172, s[4:5], v86, v86, 1.0
	v_rcp_f32_e32 v173, v172
	s_nop 0
	v_fma_f32 v174, -v172, v173, 1.0
	v_fmac_f32_e32 v173, v174, v173
	v_div_scale_f32 v174, vcc, 1.0, v86, 1.0
	v_mul_f32_e32 v175, v174, v173
	v_fma_f32 v176, -v172, v175, v174
	v_fmac_f32_e32 v175, v176, v173
	v_fma_f32 v172, -v172, v175, v174
	v_div_fmas_f32 v172, v172, v173, v175
	v_div_fixup_f32 v86, v172, v86, 1.0
	v_mul_f32_e32 v86, v181, v86
	v_fmac_f32_e32 v148, v86, v164
	global_store_dword v130, v148, s[86:87] offset:-3968
	v_cvt_pk_bf16_f32 v86, v148, s0
	global_store_short v135, v86, s[88:89] offset:2048
	v_add_f32_e32 v87, v87, v214
	v_mul_f32_e32 v87, 0xbfb8aa3b, v87
	v_exp_f32_e32 v87, v87
	v_lshlrev_b32_e32 v165, 16, v165
	v_add_f32_e32 v87, 1.0, v87
	v_div_scale_f32 v172, s[4:5], v87, v87, 1.0
	v_rcp_f32_e32 v173, v172
	s_nop 0
	v_fma_f32 v174, -v172, v173, 1.0
	v_fmac_f32_e32 v173, v174, v173
	v_div_scale_f32 v174, vcc, 1.0, v87, 1.0
	v_mul_f32_e32 v175, v174, v173
	v_fma_f32 v176, -v172, v175, v174
	v_fmac_f32_e32 v175, v176, v173
	v_fma_f32 v172, -v172, v175, v174
	v_div_fmas_f32 v172, v172, v173, v175
	v_div_fixup_f32 v87, v172, v87, 1.0
	v_mul_f32_e32 v87, v181, v87
	v_fmac_f32_e32 v149, v87, v165
	global_store_dword v130, v149, s[86:87] offset:128
	v_cvt_pk_bf16_f32 v87, v149, s0
	global_store_short v135, v87, s[88:89] offset:2112
	v_add_f32_e32 v88, v88, v214
	v_mul_f32_e32 v88, 0xbfb8aa3b, v88
	v_exp_f32_e32 v88, v88
	v_lshlrev_b32_e32 v166, 16, v166
	v_add_f32_e32 v88, 1.0, v88
	v_div_scale_f32 v172, s[4:5], v88, v88, 1.0
	v_rcp_f32_e32 v173, v172
	s_nop 0
	v_fma_f32 v174, -v172, v173, 1.0
	v_fmac_f32_e32 v173, v174, v173
	v_div_scale_f32 v174, vcc, 1.0, v88, 1.0
	v_mul_f32_e32 v175, v174, v173
	v_fma_f32 v176, -v172, v175, v174
	v_fmac_f32_e32 v175, v176, v173
	v_fma_f32 v172, -v172, v175, v174
	v_div_fmas_f32 v172, v172, v173, v175
	v_div_fixup_f32 v88, v172, v88, 1.0
	v_mul_f32_e32 v88, v181, v88
	v_fmac_f32_e32 v150, v88, v166
	global_store_dword v131, v150, s[86:87] offset:-3968
	v_cvt_pk_bf16_f32 v88, v150, s0
	global_store_short v135, v88, s[88:89] offset:2176
	v_add_f32_e32 v89, v89, v214
	v_mul_f32_e32 v89, 0xbfb8aa3b, v89
	v_exp_f32_e32 v89, v89
	v_lshlrev_b32_e32 v167, 16, v167
	v_add_f32_e32 v89, 1.0, v89
	v_div_scale_f32 v172, s[4:5], v89, v89, 1.0
	v_rcp_f32_e32 v173, v172
	s_nop 0
; DEV u16 f2bf(float f) { return (u16)(pack2(f, 0.f) & 0xffffu); }
; DEV float bf2f(u16 b) { return __uint_as_float(((unsigned)b) << 16); }
; DEV size_t tixw(long row, int col, int W) { return (size_t)(row >> 8) * (256 * (size_t)W) + (size_t)(col >> 5) * 8192 + (size_t)(row & 255) * 32 + (col & 31); }
; DEV float sigmoidf_(float x) { return 1.f / (1.f + __expf(-x)); }
;     ...
;   for_tiles_pf(128, 8, [&](int mt, int nt, int mtn, int ntn, bool hn, bool first) {
;     f32x4 acc[8][4];
;     zero_acc<8>(acc);
;     int m0 = mt * 256, n0 = nt * 128;
;     gemm_mainloop<8>(acc, RowLin{xb + (size_t)m0 * D, 32}, 16384, Wg + (size_t)n0 * D, D, 0, 16, smem, 8192, 32, 4096,
;                      !first, hn, xb + (size_t)mtn * 256 * D, Wg + (size_t)ntn * 128 * D);
;     ...
;         for (int j = 0; j < 4; ++j) {
;           int row = m0 + wm * 128 + ms * 16 + quad * 4 + j;
;           int col = n0 + wn * 64 + ns * 16 + l15;
;           size_t idx = (size_t)row * D + col;
;           float gate = sigmoidf_(acc[ms][ns][j] + bg[col]);
;           float v = P.out[idx] + psc * gate * bf2f(Pp[idx]);
;           P.out[idx] = v;
;           xbn[tixw(row, col, D)] = f2bf(v);
	v_fma_f32 v174, -v172, v173, 1.0
	v_fmac_f32_e32 v173, v174, v173
	v_div_scale_f32 v174, vcc, 1.0, v89, 1.0
	v_mul_f32_e32 v175, v174, v173
	v_fma_f32 v176, -v172, v175, v174
	v_fmac_f32_e32 v175, v176, v173
	v_fma_f32 v172, -v172, v175, v174
	v_div_fmas_f32 v172, v172, v173, v175
	v_div_fixup_f32 v89, v172, v89, 1.0
	v_mul_f32_e32 v89, v181, v89
	v_fmac_f32_e32 v151, v89, v167
	global_store_dword v131, v151, s[86:87] offset:128
	v_cvt_pk_bf16_f32 v89, v151, s0
	global_store_short v135, v89, s[88:89] offset:2240
	v_add_f32_e32 v82, v82, v215
	v_mul_f32_e32 v82, 0xbfb8aa3b, v82
	v_exp_f32_e32 v82, v82
	v_lshlrev_b32_e32 v168, 16, v168
	v_add_f32_e32 v82, 1.0, v82
	v_div_scale_f32 v172, s[4:5], v82, v82, 1.0
	v_rcp_f32_e32 v173, v172
	s_nop 0
	v_fma_f32 v174, -v172, v173, 1.0
	v_fmac_f32_e32 v173, v174, v173
	v_div_scale_f32 v174, vcc, 1.0, v82, 1.0
	v_mul_f32_e32 v175, v174, v173
	v_fma_f32 v176, -v172, v175, v174
	v_fmac_f32_e32 v175, v176, v173
	v_fma_f32 v172, -v172, v175, v174
	v_div_fmas_f32 v172, v172, v173, v175
	v_div_fixup_f32 v82, v172, v82, 1.0
	v_mul_f32_e32 v82, v181, v82
	v_fmac_f32_e32 v152, v82, v168
	global_store_dword v130, v152, s[86:87] offset:-3904
	v_cvt_pk_bf16_f32 v82, v152, s0
	global_store_short v135, v82, s[88:89] offset:2080
	v_add_f32_e32 v83, v83, v215
	v_mul_f32_e32 v83, 0xbfb8aa3b, v83
	v_exp_f32_e32 v83, v83
	v_lshlrev_b32_e32 v169, 16, v169
	v_add_f32_e32 v83, 1.0, v83
	v_div_scale_f32 v172, s[4:5], v83, v83, 1.0
	v_rcp_f32_e32 v173, v172
	s_nop 0
	v_fma_f32 v174, -v172, v173, 1.0
	v_fmac_f32_e32 v173, v174, v173
	v_div_scale_f32 v174, vcc, 1.0, v83, 1.0
	v_mul_f32_e32 v175, v174, v173
	v_fma_f32 v176, -v172, v175, v174
	v_fmac_f32_e32 v175, v176, v173
	v_fma_f32 v172, -v172, v175, v174
	v_div_fmas_f32 v172, v172, v173, v175
	v_div_fixup_f32 v83, v172, v83, 1.0
	v_mul_f32_e32 v83, v181, v83
	v_fmac_f32_e32 v153, v83, v169
	global_store_dword v130, v153, s[86:87] offset:192
	v_cvt_pk_bf16_f32 v83, v153, s0
	global_store_short v135, v83, s[88:89] offset:2144
	v_add_f32_e32 v84, v84, v215
	v_mul_f32_e32 v84, 0xbfb8aa3b, v84
	v_exp_f32_e32 v84, v84
	v_lshlrev_b32_e32 v170, 16, v170
	v_add_f32_e32 v84, 1.0, v84
	v_div_scale_f32 v172, s[4:5], v84, v84, 1.0
	v_rcp_f32_e32 v173, v172
	s_nop 0
	v_fma_f32 v174, -v172, v173, 1.0
	v_fmac_f32_e32 v173, v174, v173
	v_div_scale_f32 v174, vcc, 1.0, v84, 1.0
	v_mul_f32_e32 v175, v174, v173
	v_fma_f32 v176, -v172, v175, v174
	v_fmac_f32_e32 v175, v176, v173
	v_fma_f32 v172, -v172, v175, v174
	v_div_fmas_f32 v172, v172, v173, v175
	v_div_fixup_f32 v84, v172, v84, 1.0
	v_mul_f32_e32 v84, v181, v84
	v_fmac_f32_e32 v154, v84, v170
	global_store_dword v131, v154, s[86:87] offset:-3904
	v_cvt_pk_bf16_f32 v84, v154, s0
	global_store_short v135, v84, s[88:89] offset:2208
	v_add_f32_e32 v85, v85, v215
	v_mul_f32_e32 v85, 0xbfb8aa3b, v85
	v_exp_f32_e32 v85, v85
	v_lshlrev_b32_e32 v171, 16, v171
	v_add_f32_e32 v85, 1.0, v85
	v_div_scale_f32 v172, s[4:5], v85, v85, 1.0
	v_rcp_f32_e32 v173, v172
	s_nop 0
	v_fma_f32 v174, -v172, v173, 1.0
	v_fmac_f32_e32 v173, v174, v173
	v_div_scale_f32 v174, vcc, 1.0, v85, 1.0
	v_mul_f32_e32 v175, v174, v173
	v_fma_f32 v176, -v172, v175, v174
	v_fmac_f32_e32 v175, v176, v173
	v_fma_f32 v172, -v172, v175, v174
	v_div_fmas_f32 v172, v172, v173, v175
	v_div_fixup_f32 v85, v172, v85, 1.0
	v_mul_f32_e32 v85, v181, v85
	v_fmac_f32_e32 v155, v85, v171
	global_store_dword v131, v155, s[86:87] offset:192
	v_cvt_pk_bf16_f32 v85, v155, s0
	global_store_short v135, v85, s[88:89] offset:2272
	v_add_u32_e32 v130, 0x30000, v136
	v_add_u32_e32 v131, 0x2000, v130
	v_lshrrev_b32_e32 v132, 1, v130
	v_lshrrev_b32_e32 v133, 1, v131
	global_load_dword v140, v130, s[86:87] offset:-4096
	global_load_dword v141, v130, s[86:87]
	global_load_dword v142, v131, s[86:87] offset:-4096
	global_load_dword v143, v131, s[86:87]
	global_load_dword v144, v130, s[86:87] offset:-4032
	global_load_dword v145, v130, s[86:87] offset:64
	global_load_dword v146, v131, s[86:87] offset:-4032
	global_load_dword v147, v131, s[86:87] offset:64
	global_load_dword v148, v130, s[86:87] offset:-3968
	global_load_dword v149, v130, s[86:87] offset:128
	global_load_dword v150, v131, s[86:87] offset:-3968
	global_load_dword v151, v131, s[86:87] offset:128
	global_load_dword v152, v130, s[86:87] offset:-3904
	global_load_dword v153, v130, s[86:87] offset:192
	global_load_dword v154, v131, s[86:87] offset:-3904
	global_load_dword v155, v131, s[86:87] offset:192
	global_load_ushort v156, v132, s[96:97] offset:-2048
	global_load_ushort v157, v132, s[96:97]
	global_load_ushort v158, v133, s[96:97] offset:-2048
	global_load_ushort v159, v133, s[96:97]
	global_load_ushort v160, v132, s[96:97] offset:-2016
	global_load_ushort v161, v132, s[96:97] offset:32
	global_load_ushort v162, v133, s[96:97] offset:-2016
	global_load_ushort v163, v133, s[96:97] offset:32
	global_load_ushort v164, v132, s[96:97] offset:-1984
	global_load_ushort v165, v132, s[96:97] offset:64
	global_load_ushort v166, v133, s[96:97] offset:-1984
	global_load_ushort v167, v133, s[96:97] offset:64
	global_load_ushort v168, v132, s[96:97] offset:-1952
	global_load_ushort v169, v132, s[96:97] offset:96
	global_load_ushort v170, v133, s[96:97] offset:-1952
	global_load_ushort v171, v133, s[96:97] offset:96
	s_waitcnt vmcnt(0)
; DEV u16 f2bf(float f) { return (u16)(pack2(f, 0.f) & 0xffffu); }
; DEV float bf2f(u16 b) { return __uint_as_float(((unsigned)b) << 16); }
; DEV size_t tixw(long row, int col, int W) { return (size_t)(row >> 8) * (256 * (size_t)W) + (size_t)(col >> 5) * 8192 + (size_t)(row & 255) * 32 + (col & 31); }
; DEV float sigmoidf_(float x) { return 1.f / (1.f + __expf(-x)); }
;     ...
;         for (int j = 0; j < 4; ++j) {
;           int row = m0 + wm * 128 + ms * 16 + quad * 4 + j;
;           int col = n0 + wn * 64 + ns * 16 + l15;
;           size_t idx = (size_t)row * D + col;
;           float gate = sigmoidf_(acc[ms][ns][j] + bg[col]);
;           float v = P.out[idx] + psc * gate * bf2f(Pp[idx]);
;           P.out[idx] = v;
;           xbn[tixw(row, col, D)] = f2bf(v);
	v_add_f32_e32 v78, v78, v138
	v_mul_f32_e32 v78, 0xbfb8aa3b, v78
	v_exp_f32_e32 v78, v78
	v_lshlrev_b32_e32 v156, 16, v156
	v_add_f32_e32 v78, 1.0, v78
	v_div_scale_f32 v172, s[4:5], v78, v78, 1.0
	v_rcp_f32_e32 v173, v172
	s_nop 0
	v_fma_f32 v174, -v172, v173, 1.0
	v_fmac_f32_e32 v173, v174, v173
	v_div_scale_f32 v174, vcc, 1.0, v78, 1.0
	v_mul_f32_e32 v175, v174, v173
	v_fma_f32 v176, -v172, v175, v174
	v_fmac_f32_e32 v175, v176, v173
	v_fma_f32 v172, -v172, v175, v174
	v_div_fmas_f32 v172, v172, v173, v175
	v_div_fixup_f32 v78, v172, v78, 1.0
	v_mul_f32_e32 v78, v181, v78
	v_fmac_f32_e32 v140, v78, v156
	global_store_dword v130, v140, s[86:87] offset:-4096
	v_cvt_pk_bf16_f32 v78, v140, s0
	global_store_short v134, v78, s[88:89] offset:3072
	v_add_f32_e32 v79, v79, v138
	v_mul_f32_e32 v79, 0xbfb8aa3b, v79
	v_exp_f32_e32 v79, v79
	v_lshlrev_b32_e32 v157, 16, v157
	v_add_f32_e32 v79, 1.0, v79
	v_div_scale_f32 v172, s[4:5], v79, v79, 1.0
	v_rcp_f32_e32 v173, v172
	s_nop 0
	v_fma_f32 v174, -v172, v173, 1.0
	v_fmac_f32_e32 v173, v174, v173
	v_div_scale_f32 v174, vcc, 1.0, v79, 1.0
	v_mul_f32_e32 v175, v174, v173
	v_fma_f32 v176, -v172, v175, v174
	v_fmac_f32_e32 v175, v176, v173
	v_fma_f32 v172, -v172, v175, v174
	v_div_fmas_f32 v172, v172, v173, v175
	v_div_fixup_f32 v79, v172, v79, 1.0
	v_mul_f32_e32 v79, v181, v79
	v_fmac_f32_e32 v141, v79, v157
	global_store_dword v130, v141, s[86:87]
	v_cvt_pk_bf16_f32 v79, v141, s0
	global_store_short v134, v79, s[88:89] offset:3136
	v_add_f32_e32 v80, v80, v138
	v_mul_f32_e32 v80, 0xbfb8aa3b, v80
	v_exp_f32_e32 v80, v80
	v_lshlrev_b32_e32 v158, 16, v158
	v_add_f32_e32 v80, 1.0, v80
	v_div_scale_f32 v172, s[4:5], v80, v80, 1.0
	v_rcp_f32_e32 v173, v172
	s_nop 0
	v_fma_f32 v174, -v172, v173, 1.0
	v_fmac_f32_e32 v173, v174, v173
	v_div_scale_f32 v174, vcc, 1.0, v80, 1.0
	v_mul_f32_e32 v175, v174, v173
	v_fma_f32 v176, -v172, v175, v174
	v_fmac_f32_e32 v175, v176, v173
	v_fma_f32 v172, -v172, v175, v174
	v_div_fmas_f32 v172, v172, v173, v175
	v_div_fixup_f32 v80, v172, v80, 1.0
	v_mul_f32_e32 v80, v181, v80
	v_fmac_f32_e32 v142, v80, v158
	global_store_dword v131, v142, s[86:87] offset:-4096
	v_cvt_pk_bf16_f32 v80, v142, s0
	global_store_short v134, v80, s[88:89] offset:3200
	v_add_f32_e32 v81, v81, v138
	v_mul_f32_e32 v81, 0xbfb8aa3b, v81
	v_exp_f32_e32 v81, v81
	v_lshlrev_b32_e32 v159, 16, v159
	v_add_f32_e32 v81, 1.0, v81
	v_div_scale_f32 v172, s[4:5], v81, v81, 1.0
	v_rcp_f32_e32 v173, v172
	s_nop 0
	v_fma_f32 v174, -v172, v173, 1.0
	v_fmac_f32_e32 v173, v174, v173
	v_div_scale_f32 v174, vcc, 1.0, v81, 1.0
	v_mul_f32_e32 v175, v174, v173
	v_fma_f32 v176, -v172, v175, v174
	v_fmac_f32_e32 v175, v176, v173
	v_fma_f32 v172, -v172, v175, v174
	v_div_fmas_f32 v172, v172, v173, v175
	v_div_fixup_f32 v81, v172, v81, 1.0
	v_mul_f32_e32 v81, v181, v81
	v_fmac_f32_e32 v143, v81, v159
	global_store_dword v131, v143, s[86:87]
	v_cvt_pk_bf16_f32 v81, v143, s0
	global_store_short v134, v81, s[88:89] offset:3264
	v_add_f32_e32 v74, v74, v139
	v_mul_f32_e32 v74, 0xbfb8aa3b, v74
	v_exp_f32_e32 v74, v74
	v_lshlrev_b32_e32 v160, 16, v160
	v_add_f32_e32 v74, 1.0, v74
	v_div_scale_f32 v172, s[4:5], v74, v74, 1.0
	v_rcp_f32_e32 v173, v172
	s_nop 0
	v_fma_f32 v174, -v172, v173, 1.0
	v_fmac_f32_e32 v173, v174, v173
	v_div_scale_f32 v174, vcc, 1.0, v74, 1.0
	v_mul_f32_e32 v175, v174, v173
	v_fma_f32 v176, -v172, v175, v174
	v_fmac_f32_e32 v175, v176, v173
	v_fma_f32 v172, -v172, v175, v174
	v_div_fmas_f32 v172, v172, v173, v175
	v_div_fixup_f32 v74, v172, v74, 1.0
	v_mul_f32_e32 v74, v181, v74
	v_fmac_f32_e32 v144, v74, v160
	global_store_dword v130, v144, s[86:87] offset:-4032
	v_cvt_pk_bf16_f32 v74, v144, s0
	global_store_short v134, v74, s[88:89] offset:3104
	v_add_f32_e32 v75, v75, v139
	v_mul_f32_e32 v75, 0xbfb8aa3b, v75
	v_exp_f32_e32 v75, v75
	v_lshlrev_b32_e32 v161, 16, v161
	v_add_f32_e32 v75, 1.0, v75
	v_div_scale_f32 v172, s[4:5], v75, v75, 1.0
	v_rcp_f32_e32 v173, v172
	s_nop 0
	v_fma_f32 v174, -v172, v173, 1.0
	v_fmac_f32_e32 v173, v174, v173
	v_div_scale_f32 v174, vcc, 1.0, v75, 1.0
	v_mul_f32_e32 v175, v174, v173
	v_fma_f32 v176, -v172, v175, v174
	v_fmac_f32_e32 v175, v176, v173
	v_fma_f32 v172, -v172, v175, v174
	v_div_fmas_f32 v172, v172, v173, v175
	v_div_fixup_f32 v75, v172, v75, 1.0
	v_mul_f32_e32 v75, v181, v75
	v_fmac_f32_e32 v145, v75, v161
	global_store_dword v130, v145, s[86:87] offset:64
	v_cvt_pk_bf16_f32 v75, v145, s0
	global_store_short v134, v75, s[88:89] offset:3168
	v_add_f32_e32 v76, v76, v139
	v_mul_f32_e32 v76, 0xbfb8aa3b, v76
	v_exp_f32_e32 v76, v76
	v_lshlrev_b32_e32 v162, 16, v162
	v_add_f32_e32 v76, 1.0, v76
	v_div_scale_f32 v172, s[4:5], v76, v76, 1.0
	v_rcp_f32_e32 v173, v172
	s_nop 0
	v_fma_f32 v174, -v172, v173, 1.0
	v_fmac_f32_e32 v173, v174, v173
	v_div_scale_f32 v174, vcc, 1.0, v76, 1.0
	v_mul_f32_e32 v175, v174, v173
	v_fma_f32 v176, -v172, v175, v174
	v_fmac_f32_e32 v175, v176, v173
	v_fma_f32 v172, -v172, v175, v174
	v_div_fmas_f32 v172, v172, v173, v175
	v_div_fixup_f32 v76, v172, v76, 1.0
	v_mul_f32_e32 v76, v181, v76
	v_fmac_f32_e32 v146, v76, v162
	global_store_dword v131, v146, s[86:87] offset:-4032
	v_cvt_pk_bf16_f32 v76, v146, s0
	global_store_short v134, v76, s[88:89] offset:3232
	v_add_f32_e32 v77, v77, v139
	v_mul_f32_e32 v77, 0xbfb8aa3b, v77
	v_exp_f32_e32 v77, v77
	v_lshlrev_b32_e32 v163, 16, v163
	v_add_f32_e32 v77, 1.0, v77
	v_div_scale_f32 v172, s[4:5], v77, v77, 1.0
	v_rcp_f32_e32 v173, v172
	s_nop 0
	v_fma_f32 v174, -v172, v173, 1.0
	v_fmac_f32_e32 v173, v174, v173
	v_div_scale_f32 v174, vcc, 1.0, v77, 1.0
	v_mul_f32_e32 v175, v174, v173
; DEV u16 f2bf(float f) { return (u16)(pack2(f, 0.f) & 0xffffu); }
; DEV float bf2f(u16 b) { return __uint_as_float(((unsigned)b) << 16); }
; DEV size_t tixw(long row, int col, int W) { return (size_t)(row >> 8) * (256 * (size_t)W) + (size_t)(col >> 5) * 8192 + (size_t)(row & 255) * 32 + (col & 31); }
; DEV float sigmoidf_(float x) { return 1.f / (1.f + __expf(-x)); }
;     ...
;         for (int j = 0; j < 4; ++j) {
;           int row = m0 + wm * 128 + ms * 16 + quad * 4 + j;
;           int col = n0 + wn * 64 + ns * 16 + l15;
;           size_t idx = (size_t)row * D + col;
;           float gate = sigmoidf_(acc[ms][ns][j] + bg[col]);
;           float v = P.out[idx] + psc * gate * bf2f(Pp[idx]);
;           P.out[idx] = v;
;           xbn[tixw(row, col, D)] = f2bf(v);
	v_fma_f32 v176, -v172, v175, v174
	v_fmac_f32_e32 v175, v176, v173
	v_fma_f32 v172, -v172, v175, v174
	v_div_fmas_f32 v172, v172, v173, v175
	v_div_fixup_f32 v77, v172, v77, 1.0
	v_mul_f32_e32 v77, v181, v77
	v_fmac_f32_e32 v147, v77, v163
	global_store_dword v131, v147, s[86:87] offset:64
	v_cvt_pk_bf16_f32 v77, v147, s0
	global_store_short v134, v77, s[88:89] offset:3296
	v_add_f32_e32 v70, v70, v214
	v_mul_f32_e32 v70, 0xbfb8aa3b, v70
	v_exp_f32_e32 v70, v70
	v_lshlrev_b32_e32 v164, 16, v164
	v_add_f32_e32 v70, 1.0, v70
	v_div_scale_f32 v172, s[4:5], v70, v70, 1.0
	v_rcp_f32_e32 v173, v172
	s_nop 0
	v_fma_f32 v174, -v172, v173, 1.0
	v_fmac_f32_e32 v173, v174, v173
	v_div_scale_f32 v174, vcc, 1.0, v70, 1.0
	v_mul_f32_e32 v175, v174, v173
	v_fma_f32 v176, -v172, v175, v174
	v_fmac_f32_e32 v175, v176, v173
	v_fma_f32 v172, -v172, v175, v174
	v_div_fmas_f32 v172, v172, v173, v175
	v_div_fixup_f32 v70, v172, v70, 1.0
	v_mul_f32_e32 v70, v181, v70
	v_fmac_f32_e32 v148, v70, v164
	global_store_dword v130, v148, s[86:87] offset:-3968
	v_cvt_pk_bf16_f32 v70, v148, s0
	global_store_short v135, v70, s[88:89] offset:3072
	v_add_f32_e32 v71, v71, v214
	v_mul_f32_e32 v71, 0xbfb8aa3b, v71
	v_exp_f32_e32 v71, v71
	v_lshlrev_b32_e32 v165, 16, v165
	v_add_f32_e32 v71, 1.0, v71
	v_div_scale_f32 v172, s[4:5], v71, v71, 1.0
	v_rcp_f32_e32 v173, v172
	s_nop 0
	v_fma_f32 v174, -v172, v173, 1.0
	v_fmac_f32_e32 v173, v174, v173
	v_div_scale_f32 v174, vcc, 1.0, v71, 1.0
	v_mul_f32_e32 v175, v174, v173
	v_fma_f32 v176, -v172, v175, v174
	v_fmac_f32_e32 v175, v176, v173
	v_fma_f32 v172, -v172, v175, v174
	v_div_fmas_f32 v172, v172, v173, v175
	v_div_fixup_f32 v71, v172, v71, 1.0
	v_mul_f32_e32 v71, v181, v71
	v_fmac_f32_e32 v149, v71, v165
	global_store_dword v130, v149, s[86:87] offset:128
	v_cvt_pk_bf16_f32 v71, v149, s0
	global_store_short v135, v71, s[88:89] offset:3136
	v_add_f32_e32 v72, v72, v214
	v_mul_f32_e32 v72, 0xbfb8aa3b, v72
	v_exp_f32_e32 v72, v72
	v_lshlrev_b32_e32 v166, 16, v166
	v_add_f32_e32 v72, 1.0, v72
	v_div_scale_f32 v172, s[4:5], v72, v72, 1.0
	v_rcp_f32_e32 v173, v172
	s_nop 0
	v_fma_f32 v174, -v172, v173, 1.0
	v_fmac_f32_e32 v173, v174, v173
	v_div_scale_f32 v174, vcc, 1.0, v72, 1.0
	v_mul_f32_e32 v175, v174, v173
	v_fma_f32 v176, -v172, v175, v174
	v_fmac_f32_e32 v175, v176, v173
	v_fma_f32 v172, -v172, v175, v174
	v_div_fmas_f32 v172, v172, v173, v175
	v_div_fixup_f32 v72, v172, v72, 1.0
	v_mul_f32_e32 v72, v181, v72
	v_fmac_f32_e32 v150, v72, v166
	global_store_dword v131, v150, s[86:87] offset:-3968
	v_cvt_pk_bf16_f32 v72, v150, s0
	global_store_short v135, v72, s[88:89] offset:3200
	v_add_f32_e32 v73, v73, v214
	v_mul_f32_e32 v73, 0xbfb8aa3b, v73
	v_exp_f32_e32 v73, v73
	v_lshlrev_b32_e32 v167, 16, v167
	v_add_f32_e32 v73, 1.0, v73
	v_div_scale_f32 v172, s[4:5], v73, v73, 1.0
	v_rcp_f32_e32 v173, v172
	s_nop 0
	v_fma_f32 v174, -v172, v173, 1.0
	v_fmac_f32_e32 v173, v174, v173
	v_div_scale_f32 v174, vcc, 1.0, v73, 1.0
	v_mul_f32_e32 v175, v174, v173
	v_fma_f32 v176, -v172, v175, v174
	v_fmac_f32_e32 v175, v176, v173
	v_fma_f32 v172, -v172, v175, v174
	v_div_fmas_f32 v172, v172, v173, v175
	v_div_fixup_f32 v73, v172, v73, 1.0
	v_mul_f32_e32 v73, v181, v73
	v_fmac_f32_e32 v151, v73, v167
	global_store_dword v131, v151, s[86:87] offset:128
	v_cvt_pk_bf16_f32 v73, v151, s0
	global_store_short v135, v73, s[88:89] offset:3264
	v_add_f32_e32 v66, v66, v215
	v_mul_f32_e32 v66, 0xbfb8aa3b, v66
	v_exp_f32_e32 v66, v66
	v_lshlrev_b32_e32 v168, 16, v168
	v_add_f32_e32 v66, 1.0, v66
	v_div_scale_f32 v172, s[4:5], v66, v66, 1.0
	v_rcp_f32_e32 v173, v172
	s_nop 0
	v_fma_f32 v174, -v172, v173, 1.0
	v_fmac_f32_e32 v173, v174, v173
	v_div_scale_f32 v174, vcc, 1.0, v66, 1.0
	v_mul_f32_e32 v175, v174, v173
	v_fma_f32 v176, -v172, v175, v174
	v_fmac_f32_e32 v175, v176, v173
	v_fma_f32 v172, -v172, v175, v174
	v_div_fmas_f32 v172, v172, v173, v175
	v_div_fixup_f32 v66, v172, v66, 1.0
	v_mul_f32_e32 v66, v181, v66
	v_fmac_f32_e32 v152, v66, v168
	global_store_dword v130, v152, s[86:87] offset:-3904
	v_cvt_pk_bf16_f32 v66, v152, s0
	global_store_short v135, v66, s[88:89] offset:3104
	v_add_f32_e32 v67, v67, v215
	v_mul_f32_e32 v67, 0xbfb8aa3b, v67
	v_exp_f32_e32 v67, v67
	v_lshlrev_b32_e32 v169, 16, v169
	v_add_f32_e32 v67, 1.0, v67
	v_div_scale_f32 v172, s[4:5], v67, v67, 1.0
	v_rcp_f32_e32 v173, v172
	s_nop 0
	v_fma_f32 v174, -v172, v173, 1.0
	v_fmac_f32_e32 v173, v174, v173
	v_div_scale_f32 v174, vcc, 1.0, v67, 1.0
	v_mul_f32_e32 v175, v174, v173
	v_fma_f32 v176, -v172, v175, v174
	v_fmac_f32_e32 v175, v176, v173
	v_fma_f32 v172, -v172, v175, v174
	v_div_fmas_f32 v172, v172, v173, v175
	v_div_fixup_f32 v67, v172, v67, 1.0
	v_mul_f32_e32 v67, v181, v67
	v_fmac_f32_e32 v153, v67, v169
	global_store_dword v130, v153, s[86:87] offset:192
	v_cvt_pk_bf16_f32 v67, v153, s0
	global_store_short v135, v67, s[88:89] offset:3168
	v_add_f32_e32 v68, v68, v215
	v_mul_f32_e32 v68, 0xbfb8aa3b, v68
	v_exp_f32_e32 v68, v68
	v_lshlrev_b32_e32 v170, 16, v170
	v_add_f32_e32 v68, 1.0, v68
	v_div_scale_f32 v172, s[4:5], v68, v68, 1.0
	v_rcp_f32_e32 v173, v172
	s_nop 0
	v_fma_f32 v174, -v172, v173, 1.0
	v_fmac_f32_e32 v173, v174, v173
	v_div_scale_f32 v174, vcc, 1.0, v68, 1.0
	v_mul_f32_e32 v175, v174, v173
	v_fma_f32 v176, -v172, v175, v174
	v_fmac_f32_e32 v175, v176, v173
	v_fma_f32 v172, -v172, v175, v174
	v_div_fmas_f32 v172, v172, v173, v175
	v_div_fixup_f32 v68, v172, v68, 1.0
	v_mul_f32_e32 v68, v181, v68
	v_fmac_f32_e32 v154, v68, v170
	global_store_dword v131, v154, s[86:87] offset:-3904
	v_cvt_pk_bf16_f32 v68, v154, s0
	global_store_short v135, v68, s[88:89] offset:3232
; DEV u16 f2bf(float f) { return (u16)(pack2(f, 0.f) & 0xffffu); }
; DEV float bf2f(u16 b) { return __uint_as_float(((unsigned)b) << 16); }
; DEV size_t tixw(long row, int col, int W) { return (size_t)(row >> 8) * (256 * (size_t)W) + (size_t)(col >> 5) * 8192 + (size_t)(row & 255) * 32 + (col & 31); }
; DEV float sigmoidf_(float x) { return 1.f / (1.f + __expf(-x)); }
;     ...
;   for_tiles_pf(128, 8, [&](int mt, int nt, int mtn, int ntn, bool hn, bool first) {
;     f32x4 acc[8][4];
;     zero_acc<8>(acc);
;     int m0 = mt * 256, n0 = nt * 128;
;     gemm_mainloop<8>(acc, RowLin{xb + (size_t)m0 * D, 32}, 16384, Wg + (size_t)n0 * D, D, 0, 16, smem, 8192, 32, 4096,
;                      !first, hn, xb + (size_t)mtn * 256 * D, Wg + (size_t)ntn * 128 * D);
;     ...
;         for (int j = 0; j < 4; ++j) {
;           int row = m0 + wm * 128 + ms * 16 + quad * 4 + j;
;           int col = n0 + wn * 64 + ns * 16 + l15;
;           size_t idx = (size_t)row * D + col;
;           float gate = sigmoidf_(acc[ms][ns][j] + bg[col]);
;           float v = P.out[idx] + psc * gate * bf2f(Pp[idx]);
;           P.out[idx] = v;
;           xbn[tixw(row, col, D)] = f2bf(v);
	v_add_f32_e32 v69, v69, v215
	v_mul_f32_e32 v69, 0xbfb8aa3b, v69
	v_exp_f32_e32 v69, v69
	v_lshlrev_b32_e32 v171, 16, v171
	v_add_f32_e32 v69, 1.0, v69
	v_div_scale_f32 v172, s[4:5], v69, v69, 1.0
	v_rcp_f32_e32 v173, v172
	s_nop 0
	v_fma_f32 v174, -v172, v173, 1.0
	v_fmac_f32_e32 v173, v174, v173
	v_div_scale_f32 v174, vcc, 1.0, v69, 1.0
	v_mul_f32_e32 v175, v174, v173
	v_fma_f32 v176, -v172, v175, v174
	v_fmac_f32_e32 v175, v176, v173
	v_fma_f32 v172, -v172, v175, v174
	v_div_fmas_f32 v172, v172, v173, v175
	v_div_fixup_f32 v69, v172, v69, 1.0
	v_mul_f32_e32 v69, v181, v69
	v_fmac_f32_e32 v155, v69, v171
	global_store_dword v131, v155, s[86:87] offset:192
	v_cvt_pk_bf16_f32 v69, v155, s0
	global_store_short v135, v69, s[88:89] offset:3296
	v_add_u32_e32 v130, 0x40000, v136
	v_add_u32_e32 v131, 0x2000, v130
	v_lshrrev_b32_e32 v132, 1, v130
	v_lshrrev_b32_e32 v133, 1, v131
	v_add_u32_e32 v134, 0x1000, v137
	v_add_u32_e32 v135, 0x4000, v134
	global_load_dword v140, v130, s[86:87] offset:-4096
	global_load_dword v141, v130, s[86:87]
	global_load_dword v142, v131, s[86:87] offset:-4096
	global_load_dword v143, v131, s[86:87]
	global_load_dword v144, v130, s[86:87] offset:-4032
	global_load_dword v145, v130, s[86:87] offset:64
	global_load_dword v146, v131, s[86:87] offset:-4032
	global_load_dword v147, v131, s[86:87] offset:64
	global_load_dword v148, v130, s[86:87] offset:-3968
	global_load_dword v149, v130, s[86:87] offset:128
	global_load_dword v150, v131, s[86:87] offset:-3968
	global_load_dword v151, v131, s[86:87] offset:128
	global_load_dword v152, v130, s[86:87] offset:-3904
	global_load_dword v153, v130, s[86:87] offset:192
	global_load_dword v154, v131, s[86:87] offset:-3904
	global_load_dword v155, v131, s[86:87] offset:192
	global_load_ushort v156, v132, s[96:97] offset:-2048
	global_load_ushort v157, v132, s[96:97]
	global_load_ushort v158, v133, s[96:97] offset:-2048
	global_load_ushort v159, v133, s[96:97]
	global_load_ushort v160, v132, s[96:97] offset:-2016
	global_load_ushort v161, v132, s[96:97] offset:32
	global_load_ushort v162, v133, s[96:97] offset:-2016
	global_load_ushort v163, v133, s[96:97] offset:32
	global_load_ushort v164, v132, s[96:97] offset:-1984
	global_load_ushort v165, v132, s[96:97] offset:64
	global_load_ushort v166, v133, s[96:97] offset:-1984
	global_load_ushort v167, v133, s[96:97] offset:64
	global_load_ushort v168, v132, s[96:97] offset:-1952
	global_load_ushort v169, v132, s[96:97] offset:96
	global_load_ushort v170, v133, s[96:97] offset:-1952
	global_load_ushort v171, v133, s[96:97] offset:96
	s_waitcnt vmcnt(0)
	v_add_f32_e32 v62, v62, v138
	v_mul_f32_e32 v62, 0xbfb8aa3b, v62
	v_exp_f32_e32 v62, v62
	v_lshlrev_b32_e32 v156, 16, v156
	v_add_f32_e32 v62, 1.0, v62
	v_div_scale_f32 v172, s[4:5], v62, v62, 1.0
	v_rcp_f32_e32 v173, v172
	s_nop 0
	v_fma_f32 v174, -v172, v173, 1.0
	v_fmac_f32_e32 v173, v174, v173
	v_div_scale_f32 v174, vcc, 1.0, v62, 1.0
	v_mul_f32_e32 v175, v174, v173
	v_fma_f32 v176, -v172, v175, v174
	v_fmac_f32_e32 v175, v176, v173
	v_fma_f32 v172, -v172, v175, v174
	v_div_fmas_f32 v172, v172, v173, v175
	v_div_fixup_f32 v62, v172, v62, 1.0
	v_mul_f32_e32 v62, v181, v62
	v_fmac_f32_e32 v140, v62, v156
	global_store_dword v130, v140, s[86:87] offset:-4096
	v_cvt_pk_bf16_f32 v62, v140, s0
	global_store_short v134, v62, s[88:89]
	v_add_f32_e32 v63, v63, v138
	v_mul_f32_e32 v63, 0xbfb8aa3b, v63
	v_exp_f32_e32 v63, v63
	v_lshlrev_b32_e32 v157, 16, v157
	v_add_f32_e32 v63, 1.0, v63
	v_div_scale_f32 v172, s[4:5], v63, v63, 1.0
	v_rcp_f32_e32 v173, v172
	s_nop 0
	v_fma_f32 v174, -v172, v173, 1.0
	v_fmac_f32_e32 v173, v174, v173
	v_div_scale_f32 v174, vcc, 1.0, v63, 1.0
	v_mul_f32_e32 v175, v174, v173
	v_fma_f32 v176, -v172, v175, v174
	v_fmac_f32_e32 v175, v176, v173
	v_fma_f32 v172, -v172, v175, v174
	v_div_fmas_f32 v172, v172, v173, v175
	v_div_fixup_f32 v63, v172, v63, 1.0
	v_mul_f32_e32 v63, v181, v63
	v_fmac_f32_e32 v141, v63, v157
	global_store_dword v130, v141, s[86:87]
	v_cvt_pk_bf16_f32 v63, v141, s0
	global_store_short v134, v63, s[88:89] offset:64
	v_add_f32_e32 v64, v64, v138
	v_mul_f32_e32 v64, 0xbfb8aa3b, v64
	v_exp_f32_e32 v64, v64
	v_lshlrev_b32_e32 v158, 16, v158
	v_add_f32_e32 v64, 1.0, v64
	v_div_scale_f32 v172, s[4:5], v64, v64, 1.0
	v_rcp_f32_e32 v173, v172
	s_nop 0
	v_fma_f32 v174, -v172, v173, 1.0
	v_fmac_f32_e32 v173, v174, v173
	v_div_scale_f32 v174, vcc, 1.0, v64, 1.0
	v_mul_f32_e32 v175, v174, v173
	v_fma_f32 v176, -v172, v175, v174
	v_fmac_f32_e32 v175, v176, v173
	v_fma_f32 v172, -v172, v175, v174
	v_div_fmas_f32 v172, v172, v173, v175
	v_div_fixup_f32 v64, v172, v64, 1.0
	v_mul_f32_e32 v64, v181, v64
	v_fmac_f32_e32 v142, v64, v158
	global_store_dword v131, v142, s[86:87] offset:-4096
	v_cvt_pk_bf16_f32 v64, v142, s0
	global_store_short v134, v64, s[88:89] offset:128
	v_add_f32_e32 v65, v65, v138
	v_mul_f32_e32 v65, 0xbfb8aa3b, v65
	v_exp_f32_e32 v65, v65
	v_lshlrev_b32_e32 v159, 16, v159
	v_add_f32_e32 v65, 1.0, v65
	v_div_scale_f32 v172, s[4:5], v65, v65, 1.0
	v_rcp_f32_e32 v173, v172
	s_nop 0
	v_fma_f32 v174, -v172, v173, 1.0
	v_fmac_f32_e32 v173, v174, v173
	v_div_scale_f32 v174, vcc, 1.0, v65, 1.0
	v_mul_f32_e32 v175, v174, v173
	v_fma_f32 v176, -v172, v175, v174
	v_fmac_f32_e32 v175, v176, v173
	v_fma_f32 v172, -v172, v175, v174
	v_div_fmas_f32 v172, v172, v173, v175
	v_div_fixup_f32 v65, v172, v65, 1.0
	v_mul_f32_e32 v65, v181, v65
	v_fmac_f32_e32 v143, v65, v159
	global_store_dword v131, v143, s[86:87]
	v_cvt_pk_bf16_f32 v65, v143, s0
	global_store_short v134, v65, s[88:89] offset:192
	v_add_f32_e32 v58, v58, v139
	v_mul_f32_e32 v58, 0xbfb8aa3b, v58
; DEV u16 f2bf(float f) { return (u16)(pack2(f, 0.f) & 0xffffu); }
; DEV float bf2f(u16 b) { return __uint_as_float(((unsigned)b) << 16); }
; DEV size_t tixw(long row, int col, int W) { return (size_t)(row >> 8) * (256 * (size_t)W) + (size_t)(col >> 5) * 8192 + (size_t)(row & 255) * 32 + (col & 31); }
; DEV float sigmoidf_(float x) { return 1.f / (1.f + __expf(-x)); }
;     ...
;       for (int ns = 0; ns < 4; ++ns)
; #pragma unroll
;         for (int j = 0; j < 4; ++j) {
;           int row = m0 + wm * 128 + ms * 16 + quad * 4 + j;
;           int col = n0 + wn * 64 + ns * 16 + l15;
;           size_t idx = (size_t)row * D + col;
;           float gate = sigmoidf_(acc[ms][ns][j] + bg[col]);
;           float v = P.out[idx] + psc * gate * bf2f(Pp[idx]);
;           P.out[idx] = v;
;           xbn[tixw(row, col, D)] = f2bf(v);
;         }
	v_exp_f32_e32 v58, v58
	v_lshlrev_b32_e32 v160, 16, v160
	v_add_f32_e32 v58, 1.0, v58
	v_div_scale_f32 v172, s[4:5], v58, v58, 1.0
	v_rcp_f32_e32 v173, v172
	s_nop 0
	v_fma_f32 v174, -v172, v173, 1.0
	v_fmac_f32_e32 v173, v174, v173
	v_div_scale_f32 v174, vcc, 1.0, v58, 1.0
	v_mul_f32_e32 v175, v174, v173
	v_fma_f32 v176, -v172, v175, v174
	v_fmac_f32_e32 v175, v176, v173
	v_fma_f32 v172, -v172, v175, v174
	v_div_fmas_f32 v172, v172, v173, v175
	v_div_fixup_f32 v58, v172, v58, 1.0
	v_mul_f32_e32 v58, v181, v58
	v_fmac_f32_e32 v144, v58, v160
	global_store_dword v130, v144, s[86:87] offset:-4032
	v_cvt_pk_bf16_f32 v58, v144, s0
	global_store_short v134, v58, s[88:89] offset:32
	v_add_f32_e32 v59, v59, v139
	v_mul_f32_e32 v59, 0xbfb8aa3b, v59
	v_exp_f32_e32 v59, v59
	v_lshlrev_b32_e32 v161, 16, v161
	v_add_f32_e32 v59, 1.0, v59
	v_div_scale_f32 v172, s[4:5], v59, v59, 1.0
	v_rcp_f32_e32 v173, v172
	s_nop 0
	v_fma_f32 v174, -v172, v173, 1.0
	v_fmac_f32_e32 v173, v174, v173
	v_div_scale_f32 v174, vcc, 1.0, v59, 1.0
	v_mul_f32_e32 v175, v174, v173
	v_fma_f32 v176, -v172, v175, v174
	v_fmac_f32_e32 v175, v176, v173
	v_fma_f32 v172, -v172, v175, v174
	v_div_fmas_f32 v172, v172, v173, v175
	v_div_fixup_f32 v59, v172, v59, 1.0
	v_mul_f32_e32 v59, v181, v59
	v_fmac_f32_e32 v145, v59, v161
	global_store_dword v130, v145, s[86:87] offset:64
	v_cvt_pk_bf16_f32 v59, v145, s0
	global_store_short v134, v59, s[88:89] offset:96
	v_add_f32_e32 v60, v60, v139
	v_mul_f32_e32 v60, 0xbfb8aa3b, v60
	v_exp_f32_e32 v60, v60
	v_lshlrev_b32_e32 v162, 16, v162
	v_add_f32_e32 v60, 1.0, v60
	v_div_scale_f32 v172, s[4:5], v60, v60, 1.0
	v_rcp_f32_e32 v173, v172
	s_nop 0
	v_fma_f32 v174, -v172, v173, 1.0
	v_fmac_f32_e32 v173, v174, v173
	v_div_scale_f32 v174, vcc, 1.0, v60, 1.0
	v_mul_f32_e32 v175, v174, v173
	v_fma_f32 v176, -v172, v175, v174
	v_fmac_f32_e32 v175, v176, v173
	v_fma_f32 v172, -v172, v175, v174
	v_div_fmas_f32 v172, v172, v173, v175
	v_div_fixup_f32 v60, v172, v60, 1.0
	v_mul_f32_e32 v60, v181, v60
	v_fmac_f32_e32 v146, v60, v162
	global_store_dword v131, v146, s[86:87] offset:-4032
	v_cvt_pk_bf16_f32 v60, v146, s0
	global_store_short v134, v60, s[88:89] offset:160
	v_add_f32_e32 v61, v61, v139
	v_mul_f32_e32 v61, 0xbfb8aa3b, v61
	v_exp_f32_e32 v61, v61
	v_lshlrev_b32_e32 v163, 16, v163
	v_add_f32_e32 v61, 1.0, v61
	v_div_scale_f32 v172, s[4:5], v61, v61, 1.0
	v_rcp_f32_e32 v173, v172
	s_nop 0
	v_fma_f32 v174, -v172, v173, 1.0
	v_fmac_f32_e32 v173, v174, v173
	v_div_scale_f32 v174, vcc, 1.0, v61, 1.0
	v_mul_f32_e32 v175, v174, v173
	v_fma_f32 v176, -v172, v175, v174
	v_fmac_f32_e32 v175, v176, v173
	v_fma_f32 v172, -v172, v175, v174
	v_div_fmas_f32 v172, v172, v173, v175
	v_div_fixup_f32 v61, v172, v61, 1.0
	v_mul_f32_e32 v61, v181, v61
	v_fmac_f32_e32 v147, v61, v163
	global_store_dword v131, v147, s[86:87] offset:64
	v_cvt_pk_bf16_f32 v61, v147, s0
	global_store_short v134, v61, s[88:89] offset:224
	v_add_f32_e32 v54, v54, v214
	v_mul_f32_e32 v54, 0xbfb8aa3b, v54
	v_exp_f32_e32 v54, v54
	v_lshlrev_b32_e32 v164, 16, v164
	v_add_f32_e32 v54, 1.0, v54
	v_div_scale_f32 v172, s[4:5], v54, v54, 1.0
	v_rcp_f32_e32 v173, v172
	s_nop 0
	v_fma_f32 v174, -v172, v173, 1.0
	v_fmac_f32_e32 v173, v174, v173
	v_div_scale_f32 v174, vcc, 1.0, v54, 1.0
	v_mul_f32_e32 v175, v174, v173
	v_fma_f32 v176, -v172, v175, v174
	v_fmac_f32_e32 v175, v176, v173
	v_fma_f32 v172, -v172, v175, v174
	v_div_fmas_f32 v172, v172, v173, v175
	v_div_fixup_f32 v54, v172, v54, 1.0
	v_mul_f32_e32 v54, v181, v54
	v_fmac_f32_e32 v148, v54, v164
	global_store_dword v130, v148, s[86:87] offset:-3968
	v_cvt_pk_bf16_f32 v54, v148, s0
	global_store_short v135, v54, s[88:89]
	v_add_f32_e32 v55, v55, v214
	v_mul_f32_e32 v55, 0xbfb8aa3b, v55
	v_exp_f32_e32 v55, v55
	v_lshlrev_b32_e32 v165, 16, v165
	v_add_f32_e32 v55, 1.0, v55
	v_div_scale_f32 v172, s[4:5], v55, v55, 1.0
	v_rcp_f32_e32 v173, v172
	s_nop 0
	v_fma_f32 v174, -v172, v173, 1.0
	v_fmac_f32_e32 v173, v174, v173
	v_div_scale_f32 v174, vcc, 1.0, v55, 1.0
	v_mul_f32_e32 v175, v174, v173
	v_fma_f32 v176, -v172, v175, v174
	v_fmac_f32_e32 v175, v176, v173
	v_fma_f32 v172, -v172, v175, v174
	v_div_fmas_f32 v172, v172, v173, v175
	v_div_fixup_f32 v55, v172, v55, 1.0
	v_mul_f32_e32 v55, v181, v55
	v_fmac_f32_e32 v149, v55, v165
	global_store_dword v130, v149, s[86:87] offset:128
	v_cvt_pk_bf16_f32 v55, v149, s0
	global_store_short v135, v55, s[88:89] offset:64
	v_add_f32_e32 v56, v56, v214
	v_mul_f32_e32 v56, 0xbfb8aa3b, v56
	v_exp_f32_e32 v56, v56
	v_lshlrev_b32_e32 v166, 16, v166
	v_add_f32_e32 v56, 1.0, v56
	v_div_scale_f32 v172, s[4:5], v56, v56, 1.0
	v_rcp_f32_e32 v173, v172
	s_nop 0
	v_fma_f32 v174, -v172, v173, 1.0
	v_fmac_f32_e32 v173, v174, v173
	v_div_scale_f32 v174, vcc, 1.0, v56, 1.0
	v_mul_f32_e32 v175, v174, v173
	v_fma_f32 v176, -v172, v175, v174
	v_fmac_f32_e32 v175, v176, v173
	v_fma_f32 v172, -v172, v175, v174
	v_div_fmas_f32 v172, v172, v173, v175
	v_div_fixup_f32 v56, v172, v56, 1.0
	v_mul_f32_e32 v56, v181, v56
	v_fmac_f32_e32 v150, v56, v166
	global_store_dword v131, v150, s[86:87] offset:-3968
	v_cvt_pk_bf16_f32 v56, v150, s0
	global_store_short v135, v56, s[88:89] offset:128
	v_add_f32_e32 v57, v57, v214
	v_mul_f32_e32 v57, 0xbfb8aa3b, v57
	v_exp_f32_e32 v57, v57
	v_lshlrev_b32_e32 v167, 16, v167
	v_add_f32_e32 v57, 1.0, v57
	v_div_scale_f32 v172, s[4:5], v57, v57, 1.0
	v_rcp_f32_e32 v173, v172
	s_nop 0
	v_fma_f32 v174, -v172, v173, 1.0
	v_fmac_f32_e32 v173, v174, v173
	v_div_scale_f32 v174, vcc, 1.0, v57, 1.0
	v_mul_f32_e32 v175, v174, v173
	v_fma_f32 v176, -v172, v175, v174
	v_fmac_f32_e32 v175, v176, v173
; DEV u16 f2bf(float f) { return (u16)(pack2(f, 0.f) & 0xffffu); }
; DEV float bf2f(u16 b) { return __uint_as_float(((unsigned)b) << 16); }
; DEV size_t tixw(long row, int col, int W) { return (size_t)(row >> 8) * (256 * (size_t)W) + (size_t)(col >> 5) * 8192 + (size_t)(row & 255) * 32 + (col & 31); }
; DEV float sigmoidf_(float x) { return 1.f / (1.f + __expf(-x)); }
;     ...
;       for (int ns = 0; ns < 4; ++ns)
; #pragma unroll
;         for (int j = 0; j < 4; ++j) {
;           int row = m0 + wm * 128 + ms * 16 + quad * 4 + j;
;           int col = n0 + wn * 64 + ns * 16 + l15;
;           size_t idx = (size_t)row * D + col;
;           float gate = sigmoidf_(acc[ms][ns][j] + bg[col]);
;           float v = P.out[idx] + psc * gate * bf2f(Pp[idx]);
;           P.out[idx] = v;
;           xbn[tixw(row, col, D)] = f2bf(v);
;         }
	v_fma_f32 v172, -v172, v175, v174
	v_div_fmas_f32 v172, v172, v173, v175
	v_div_fixup_f32 v57, v172, v57, 1.0
	v_mul_f32_e32 v57, v181, v57
	v_fmac_f32_e32 v151, v57, v167
	global_store_dword v131, v151, s[86:87] offset:128
	v_cvt_pk_bf16_f32 v57, v151, s0
	global_store_short v135, v57, s[88:89] offset:192
	v_add_f32_e32 v50, v50, v215
	v_mul_f32_e32 v50, 0xbfb8aa3b, v50
	v_exp_f32_e32 v50, v50
	v_lshlrev_b32_e32 v168, 16, v168
	v_add_f32_e32 v50, 1.0, v50
	v_div_scale_f32 v172, s[4:5], v50, v50, 1.0
	v_rcp_f32_e32 v173, v172
	s_nop 0
	v_fma_f32 v174, -v172, v173, 1.0
	v_fmac_f32_e32 v173, v174, v173
	v_div_scale_f32 v174, vcc, 1.0, v50, 1.0
	v_mul_f32_e32 v175, v174, v173
	v_fma_f32 v176, -v172, v175, v174
	v_fmac_f32_e32 v175, v176, v173
	v_fma_f32 v172, -v172, v175, v174
	v_div_fmas_f32 v172, v172, v173, v175
	v_div_fixup_f32 v50, v172, v50, 1.0
	v_mul_f32_e32 v50, v181, v50
	v_fmac_f32_e32 v152, v50, v168
	global_store_dword v130, v152, s[86:87] offset:-3904
	v_cvt_pk_bf16_f32 v50, v152, s0
	global_store_short v135, v50, s[88:89] offset:32
	v_add_f32_e32 v51, v51, v215
	v_mul_f32_e32 v51, 0xbfb8aa3b, v51
	v_exp_f32_e32 v51, v51
	v_lshlrev_b32_e32 v169, 16, v169
	v_add_f32_e32 v51, 1.0, v51
	v_div_scale_f32 v172, s[4:5], v51, v51, 1.0
	v_rcp_f32_e32 v173, v172
	s_nop 0
	v_fma_f32 v174, -v172, v173, 1.0
	v_fmac_f32_e32 v173, v174, v173
	v_div_scale_f32 v174, vcc, 1.0, v51, 1.0
	v_mul_f32_e32 v175, v174, v173
	v_fma_f32 v176, -v172, v175, v174
	v_fmac_f32_e32 v175, v176, v173
	v_fma_f32 v172, -v172, v175, v174
	v_div_fmas_f32 v172, v172, v173, v175
	v_div_fixup_f32 v51, v172, v51, 1.0
	v_mul_f32_e32 v51, v181, v51
	v_fmac_f32_e32 v153, v51, v169
	global_store_dword v130, v153, s[86:87] offset:192
	v_cvt_pk_bf16_f32 v51, v153, s0
	global_store_short v135, v51, s[88:89] offset:96
	v_add_f32_e32 v52, v52, v215
	v_mul_f32_e32 v52, 0xbfb8aa3b, v52
	v_exp_f32_e32 v52, v52
	v_lshlrev_b32_e32 v170, 16, v170
	v_add_f32_e32 v52, 1.0, v52
	v_div_scale_f32 v172, s[4:5], v52, v52, 1.0
	v_rcp_f32_e32 v173, v172
	s_nop 0
	v_fma_f32 v174, -v172, v173, 1.0
	v_fmac_f32_e32 v173, v174, v173
	v_div_scale_f32 v174, vcc, 1.0, v52, 1.0
	v_mul_f32_e32 v175, v174, v173
	v_fma_f32 v176, -v172, v175, v174
	v_fmac_f32_e32 v175, v176, v173
	v_fma_f32 v172, -v172, v175, v174
	v_div_fmas_f32 v172, v172, v173, v175
	v_div_fixup_f32 v52, v172, v52, 1.0
	v_mul_f32_e32 v52, v181, v52
	v_fmac_f32_e32 v154, v52, v170
	global_store_dword v131, v154, s[86:87] offset:-3904
	v_cvt_pk_bf16_f32 v52, v154, s0
	global_store_short v135, v52, s[88:89] offset:160
	v_add_f32_e32 v53, v53, v215
	v_mul_f32_e32 v53, 0xbfb8aa3b, v53
	v_exp_f32_e32 v53, v53
	v_lshlrev_b32_e32 v171, 16, v171
	v_add_f32_e32 v53, 1.0, v53
	v_div_scale_f32 v172, s[4:5], v53, v53, 1.0
	v_rcp_f32_e32 v173, v172
	s_nop 0
	v_fma_f32 v174, -v172, v173, 1.0
	v_fmac_f32_e32 v173, v174, v173
	v_div_scale_f32 v174, vcc, 1.0, v53, 1.0
	v_mul_f32_e32 v175, v174, v173
	v_fma_f32 v176, -v172, v175, v174
	v_fmac_f32_e32 v175, v176, v173
	v_fma_f32 v172, -v172, v175, v174
	v_div_fmas_f32 v172, v172, v173, v175
	v_div_fixup_f32 v53, v172, v53, 1.0
	v_mul_f32_e32 v53, v181, v53
	v_fmac_f32_e32 v155, v53, v171
	global_store_dword v131, v155, s[86:87] offset:192
	v_cvt_pk_bf16_f32 v53, v155, s0
	global_store_short v135, v53, s[88:89] offset:224
	v_add_u32_e32 v130, 0x50000, v136
	v_add_u32_e32 v131, 0x2000, v130
	v_lshrrev_b32_e32 v132, 1, v130
	v_lshrrev_b32_e32 v133, 1, v131
	global_load_dword v140, v130, s[86:87] offset:-4096
	global_load_dword v141, v130, s[86:87]
	global_load_dword v142, v131, s[86:87] offset:-4096
	global_load_dword v143, v131, s[86:87]
	global_load_dword v144, v130, s[86:87] offset:-4032
	global_load_dword v145, v130, s[86:87] offset:64
	global_load_dword v146, v131, s[86:87] offset:-4032
	global_load_dword v147, v131, s[86:87] offset:64
	global_load_dword v148, v130, s[86:87] offset:-3968
	global_load_dword v149, v130, s[86:87] offset:128
	global_load_dword v150, v131, s[86:87] offset:-3968
	global_load_dword v151, v131, s[86:87] offset:128
	global_load_dword v152, v130, s[86:87] offset:-3904
	global_load_dword v153, v130, s[86:87] offset:192
	global_load_dword v154, v131, s[86:87] offset:-3904
	global_load_dword v155, v131, s[86:87] offset:192
	global_load_ushort v156, v132, s[96:97] offset:-2048
	global_load_ushort v157, v132, s[96:97]
	global_load_ushort v158, v133, s[96:97] offset:-2048
	global_load_ushort v159, v133, s[96:97]
	global_load_ushort v160, v132, s[96:97] offset:-2016
	global_load_ushort v161, v132, s[96:97] offset:32
	global_load_ushort v162, v133, s[96:97] offset:-2016
	global_load_ushort v163, v133, s[96:97] offset:32
	global_load_ushort v164, v132, s[96:97] offset:-1984
	global_load_ushort v165, v132, s[96:97] offset:64
	global_load_ushort v166, v133, s[96:97] offset:-1984
	global_load_ushort v167, v133, s[96:97] offset:64
	global_load_ushort v168, v132, s[96:97] offset:-1952
	global_load_ushort v169, v132, s[96:97] offset:96
	global_load_ushort v170, v133, s[96:97] offset:-1952
	global_load_ushort v171, v133, s[96:97] offset:96
	s_waitcnt vmcnt(0)
; DEV u16 f2bf(float f) { return (u16)(pack2(f, 0.f) & 0xffffu); }
; DEV float bf2f(u16 b) { return __uint_as_float(((unsigned)b) << 16); }
; DEV size_t tixw(long row, int col, int W) { return (size_t)(row >> 8) * (256 * (size_t)W) + (size_t)(col >> 5) * 8192 + (size_t)(row & 255) * 32 + (col & 31); }
; DEV float sigmoidf_(float x) { return 1.f / (1.f + __expf(-x)); }
;     ...
;       for (int ns = 0; ns < 4; ++ns)
; #pragma unroll
;         for (int j = 0; j < 4; ++j) {
;           int row = m0 + wm * 128 + ms * 16 + quad * 4 + j;
;           int col = n0 + wn * 64 + ns * 16 + l15;
;           size_t idx = (size_t)row * D + col;
;           float gate = sigmoidf_(acc[ms][ns][j] + bg[col]);
;           float v = P.out[idx] + psc * gate * bf2f(Pp[idx]);
;           P.out[idx] = v;
;           xbn[tixw(row, col, D)] = f2bf(v);
;         }
	v_add_f32_e32 v46, v46, v138
	v_mul_f32_e32 v46, 0xbfb8aa3b, v46
	v_exp_f32_e32 v46, v46
	v_lshlrev_b32_e32 v156, 16, v156
	v_add_f32_e32 v46, 1.0, v46
	v_div_scale_f32 v172, s[4:5], v46, v46, 1.0
	v_rcp_f32_e32 v173, v172
	s_nop 0
	v_fma_f32 v174, -v172, v173, 1.0
	v_fmac_f32_e32 v173, v174, v173
	v_div_scale_f32 v174, vcc, 1.0, v46, 1.0
	v_mul_f32_e32 v175, v174, v173
	v_fma_f32 v176, -v172, v175, v174
	v_fmac_f32_e32 v175, v176, v173
	v_fma_f32 v172, -v172, v175, v174
	v_div_fmas_f32 v172, v172, v173, v175
	v_div_fixup_f32 v46, v172, v46, 1.0
	v_mul_f32_e32 v46, v181, v46
	v_fmac_f32_e32 v140, v46, v156
	global_store_dword v130, v140, s[86:87] offset:-4096
	v_cvt_pk_bf16_f32 v46, v140, s0
	global_store_short v134, v46, s[88:89] offset:1024
	v_add_f32_e32 v47, v47, v138
	v_mul_f32_e32 v47, 0xbfb8aa3b, v47
	v_exp_f32_e32 v47, v47
	v_lshlrev_b32_e32 v157, 16, v157
	v_add_f32_e32 v47, 1.0, v47
	v_div_scale_f32 v172, s[4:5], v47, v47, 1.0
	v_rcp_f32_e32 v173, v172
	s_nop 0
	v_fma_f32 v174, -v172, v173, 1.0
	v_fmac_f32_e32 v173, v174, v173
	v_div_scale_f32 v174, vcc, 1.0, v47, 1.0
	v_mul_f32_e32 v175, v174, v173
	v_fma_f32 v176, -v172, v175, v174
	v_fmac_f32_e32 v175, v176, v173
	v_fma_f32 v172, -v172, v175, v174
	v_div_fmas_f32 v172, v172, v173, v175
	v_div_fixup_f32 v47, v172, v47, 1.0
	v_mul_f32_e32 v47, v181, v47
	v_fmac_f32_e32 v141, v47, v157
	global_store_dword v130, v141, s[86:87]
	v_cvt_pk_bf16_f32 v47, v141, s0
	global_store_short v134, v47, s[88:89] offset:1088
	v_add_f32_e32 v48, v48, v138
	v_mul_f32_e32 v48, 0xbfb8aa3b, v48
	v_exp_f32_e32 v48, v48
	v_lshlrev_b32_e32 v158, 16, v158
	v_add_f32_e32 v48, 1.0, v48
	v_div_scale_f32 v172, s[4:5], v48, v48, 1.0
	v_rcp_f32_e32 v173, v172
	s_nop 0
	v_fma_f32 v174, -v172, v173, 1.0
	v_fmac_f32_e32 v173, v174, v173
	v_div_scale_f32 v174, vcc, 1.0, v48, 1.0
	v_mul_f32_e32 v175, v174, v173
	v_fma_f32 v176, -v172, v175, v174
	v_fmac_f32_e32 v175, v176, v173
	v_fma_f32 v172, -v172, v175, v174
	v_div_fmas_f32 v172, v172, v173, v175
	v_div_fixup_f32 v48, v172, v48, 1.0
	v_mul_f32_e32 v48, v181, v48
	v_fmac_f32_e32 v142, v48, v158
	global_store_dword v131, v142, s[86:87] offset:-4096
	v_cvt_pk_bf16_f32 v48, v142, s0
	global_store_short v134, v48, s[88:89] offset:1152
	v_add_f32_e32 v49, v49, v138
	v_mul_f32_e32 v49, 0xbfb8aa3b, v49
	v_exp_f32_e32 v49, v49
	v_lshlrev_b32_e32 v159, 16, v159
	v_add_f32_e32 v49, 1.0, v49
	v_div_scale_f32 v172, s[4:5], v49, v49, 1.0
	v_rcp_f32_e32 v173, v172
	s_nop 0
	v_fma_f32 v174, -v172, v173, 1.0
	v_fmac_f32_e32 v173, v174, v173
	v_div_scale_f32 v174, vcc, 1.0, v49, 1.0
	v_mul_f32_e32 v175, v174, v173
	v_fma_f32 v176, -v172, v175, v174
	v_fmac_f32_e32 v175, v176, v173
	v_fma_f32 v172, -v172, v175, v174
	v_div_fmas_f32 v172, v172, v173, v175
	v_div_fixup_f32 v49, v172, v49, 1.0
	v_mul_f32_e32 v49, v181, v49
	v_fmac_f32_e32 v143, v49, v159
	global_store_dword v131, v143, s[86:87]
	v_cvt_pk_bf16_f32 v49, v143, s0
	global_store_short v134, v49, s[88:89] offset:1216
	v_add_f32_e32 v42, v42, v139
	v_mul_f32_e32 v42, 0xbfb8aa3b, v42
	v_exp_f32_e32 v42, v42
	v_lshlrev_b32_e32 v160, 16, v160
	v_add_f32_e32 v42, 1.0, v42
	v_div_scale_f32 v172, s[4:5], v42, v42, 1.0
	v_rcp_f32_e32 v173, v172
	s_nop 0
	v_fma_f32 v174, -v172, v173, 1.0
	v_fmac_f32_e32 v173, v174, v173
	v_div_scale_f32 v174, vcc, 1.0, v42, 1.0
	v_mul_f32_e32 v175, v174, v173
	v_fma_f32 v176, -v172, v175, v174
	v_fmac_f32_e32 v175, v176, v173
	v_fma_f32 v172, -v172, v175, v174
	v_div_fmas_f32 v172, v172, v173, v175
	v_div_fixup_f32 v42, v172, v42, 1.0
	v_mul_f32_e32 v42, v181, v42
	v_fmac_f32_e32 v144, v42, v160
	global_store_dword v130, v144, s[86:87] offset:-4032
	v_cvt_pk_bf16_f32 v42, v144, s0
	global_store_short v134, v42, s[88:89] offset:1056
	v_add_f32_e32 v43, v43, v139
	v_mul_f32_e32 v43, 0xbfb8aa3b, v43
	v_exp_f32_e32 v43, v43
	v_lshlrev_b32_e32 v161, 16, v161
	v_add_f32_e32 v43, 1.0, v43
	v_div_scale_f32 v172, s[4:5], v43, v43, 1.0
	v_rcp_f32_e32 v173, v172
	s_nop 0
	v_fma_f32 v174, -v172, v173, 1.0
	v_fmac_f32_e32 v173, v174, v173
	v_div_scale_f32 v174, vcc, 1.0, v43, 1.0
	v_mul_f32_e32 v175, v174, v173
	v_fma_f32 v176, -v172, v175, v174
	v_fmac_f32_e32 v175, v176, v173
	v_fma_f32 v172, -v172, v175, v174
	v_div_fmas_f32 v172, v172, v173, v175
	v_div_fixup_f32 v43, v172, v43, 1.0
	v_mul_f32_e32 v43, v181, v43
	v_fmac_f32_e32 v145, v43, v161
	global_store_dword v130, v145, s[86:87] offset:64
	v_cvt_pk_bf16_f32 v43, v145, s0
	global_store_short v134, v43, s[88:89] offset:1120
	v_add_f32_e32 v44, v44, v139
	v_mul_f32_e32 v44, 0xbfb8aa3b, v44
	v_exp_f32_e32 v44, v44
	v_lshlrev_b32_e32 v162, 16, v162
	v_add_f32_e32 v44, 1.0, v44
	v_div_scale_f32 v172, s[4:5], v44, v44, 1.0
	v_rcp_f32_e32 v173, v172
	s_nop 0
	v_fma_f32 v174, -v172, v173, 1.0
	v_fmac_f32_e32 v173, v174, v173
	v_div_scale_f32 v174, vcc, 1.0, v44, 1.0
	v_mul_f32_e32 v175, v174, v173
	v_fma_f32 v176, -v172, v175, v174
	v_fmac_f32_e32 v175, v176, v173
	v_fma_f32 v172, -v172, v175, v174
	v_div_fmas_f32 v172, v172, v173, v175
	v_div_fixup_f32 v44, v172, v44, 1.0
	v_mul_f32_e32 v44, v181, v44
	v_fmac_f32_e32 v146, v44, v162
	global_store_dword v131, v146, s[86:87] offset:-4032
	v_cvt_pk_bf16_f32 v44, v146, s0
	global_store_short v134, v44, s[88:89] offset:1184
	v_add_f32_e32 v45, v45, v139
	v_mul_f32_e32 v45, 0xbfb8aa3b, v45
	v_exp_f32_e32 v45, v45
	v_lshlrev_b32_e32 v163, 16, v163
	v_add_f32_e32 v45, 1.0, v45
	v_div_scale_f32 v172, s[4:5], v45, v45, 1.0
	v_rcp_f32_e32 v173, v172
	s_nop 0
	v_fma_f32 v174, -v172, v173, 1.0
	v_fmac_f32_e32 v173, v174, v173
	v_div_scale_f32 v174, vcc, 1.0, v45, 1.0
	v_mul_f32_e32 v175, v174, v173
; DEV u16 f2bf(float f) { return (u16)(pack2(f, 0.f) & 0xffffu); }
; DEV float bf2f(u16 b) { return __uint_as_float(((unsigned)b) << 16); }
; DEV size_t tixw(long row, int col, int W) { return (size_t)(row >> 8) * (256 * (size_t)W) + (size_t)(col >> 5) * 8192 + (size_t)(row & 255) * 32 + (col & 31); }
; DEV float sigmoidf_(float x) { return 1.f / (1.f + __expf(-x)); }
;     ...
;       for (int ns = 0; ns < 4; ++ns)
; #pragma unroll
;         for (int j = 0; j < 4; ++j) {
;           int row = m0 + wm * 128 + ms * 16 + quad * 4 + j;
;           int col = n0 + wn * 64 + ns * 16 + l15;
;           size_t idx = (size_t)row * D + col;
;           float gate = sigmoidf_(acc[ms][ns][j] + bg[col]);
;           float v = P.out[idx] + psc * gate * bf2f(Pp[idx]);
;           P.out[idx] = v;
;           xbn[tixw(row, col, D)] = f2bf(v);
;         }
	v_fma_f32 v176, -v172, v175, v174
	v_fmac_f32_e32 v175, v176, v173
	v_fma_f32 v172, -v172, v175, v174
	v_div_fmas_f32 v172, v172, v173, v175
	v_div_fixup_f32 v45, v172, v45, 1.0
	v_mul_f32_e32 v45, v181, v45
	v_fmac_f32_e32 v147, v45, v163
	global_store_dword v131, v147, s[86:87] offset:64
	v_cvt_pk_bf16_f32 v45, v147, s0
	global_store_short v134, v45, s[88:89] offset:1248
	v_add_f32_e32 v38, v38, v214
	v_mul_f32_e32 v38, 0xbfb8aa3b, v38
	v_exp_f32_e32 v38, v38
	v_lshlrev_b32_e32 v164, 16, v164
	v_add_f32_e32 v38, 1.0, v38
	v_div_scale_f32 v172, s[4:5], v38, v38, 1.0
	v_rcp_f32_e32 v173, v172
	s_nop 0
	v_fma_f32 v174, -v172, v173, 1.0
	v_fmac_f32_e32 v173, v174, v173
	v_div_scale_f32 v174, vcc, 1.0, v38, 1.0
	v_mul_f32_e32 v175, v174, v173
	v_fma_f32 v176, -v172, v175, v174
	v_fmac_f32_e32 v175, v176, v173
	v_fma_f32 v172, -v172, v175, v174
	v_div_fmas_f32 v172, v172, v173, v175
	v_div_fixup_f32 v38, v172, v38, 1.0
	v_mul_f32_e32 v38, v181, v38
	v_fmac_f32_e32 v148, v38, v164
	global_store_dword v130, v148, s[86:87] offset:-3968
	v_cvt_pk_bf16_f32 v38, v148, s0
	global_store_short v135, v38, s[88:89] offset:1024
	v_add_f32_e32 v39, v39, v214
	v_mul_f32_e32 v39, 0xbfb8aa3b, v39
	v_exp_f32_e32 v39, v39
	v_lshlrev_b32_e32 v165, 16, v165
	v_add_f32_e32 v39, 1.0, v39
	v_div_scale_f32 v172, s[4:5], v39, v39, 1.0
	v_rcp_f32_e32 v173, v172
	s_nop 0
	v_fma_f32 v174, -v172, v173, 1.0
	v_fmac_f32_e32 v173, v174, v173
	v_div_scale_f32 v174, vcc, 1.0, v39, 1.0
	v_mul_f32_e32 v175, v174, v173
	v_fma_f32 v176, -v172, v175, v174
	v_fmac_f32_e32 v175, v176, v173
	v_fma_f32 v172, -v172, v175, v174
	v_div_fmas_f32 v172, v172, v173, v175
	v_div_fixup_f32 v39, v172, v39, 1.0
	v_mul_f32_e32 v39, v181, v39
	v_fmac_f32_e32 v149, v39, v165
	global_store_dword v130, v149, s[86:87] offset:128
	v_cvt_pk_bf16_f32 v39, v149, s0
	global_store_short v135, v39, s[88:89] offset:1088
	v_add_f32_e32 v40, v40, v214
	v_mul_f32_e32 v40, 0xbfb8aa3b, v40
	v_exp_f32_e32 v40, v40
	v_lshlrev_b32_e32 v166, 16, v166
	v_add_f32_e32 v40, 1.0, v40
	v_div_scale_f32 v172, s[4:5], v40, v40, 1.0
	v_rcp_f32_e32 v173, v172
	s_nop 0
	v_fma_f32 v174, -v172, v173, 1.0
	v_fmac_f32_e32 v173, v174, v173
	v_div_scale_f32 v174, vcc, 1.0, v40, 1.0
	v_mul_f32_e32 v175, v174, v173
	v_fma_f32 v176, -v172, v175, v174
	v_fmac_f32_e32 v175, v176, v173
	v_fma_f32 v172, -v172, v175, v174
	v_div_fmas_f32 v172, v172, v173, v175
	v_div_fixup_f32 v40, v172, v40, 1.0
	v_mul_f32_e32 v40, v181, v40
	v_fmac_f32_e32 v150, v40, v166
	global_store_dword v131, v150, s[86:87] offset:-3968
	v_cvt_pk_bf16_f32 v40, v150, s0
	global_store_short v135, v40, s[88:89] offset:1152
	v_add_f32_e32 v41, v41, v214
	v_mul_f32_e32 v41, 0xbfb8aa3b, v41
	v_exp_f32_e32 v41, v41
	v_lshlrev_b32_e32 v167, 16, v167
	v_add_f32_e32 v41, 1.0, v41
	v_div_scale_f32 v172, s[4:5], v41, v41, 1.0
	v_rcp_f32_e32 v173, v172
	s_nop 0
	v_fma_f32 v174, -v172, v173, 1.0
	v_fmac_f32_e32 v173, v174, v173
	v_div_scale_f32 v174, vcc, 1.0, v41, 1.0
	v_mul_f32_e32 v175, v174, v173
	v_fma_f32 v176, -v172, v175, v174
	v_fmac_f32_e32 v175, v176, v173
	v_fma_f32 v172, -v172, v175, v174
	v_div_fmas_f32 v172, v172, v173, v175
	v_div_fixup_f32 v41, v172, v41, 1.0
	v_mul_f32_e32 v41, v181, v41
	v_fmac_f32_e32 v151, v41, v167
	global_store_dword v131, v151, s[86:87] offset:128
	v_cvt_pk_bf16_f32 v41, v151, s0
	global_store_short v135, v41, s[88:89] offset:1216
	v_add_f32_e32 v34, v34, v215
	v_mul_f32_e32 v34, 0xbfb8aa3b, v34
	v_exp_f32_e32 v34, v34
	v_lshlrev_b32_e32 v168, 16, v168
	v_add_f32_e32 v34, 1.0, v34
	v_div_scale_f32 v172, s[4:5], v34, v34, 1.0
	v_rcp_f32_e32 v173, v172
	s_nop 0
	v_fma_f32 v174, -v172, v173, 1.0
	v_fmac_f32_e32 v173, v174, v173
	v_div_scale_f32 v174, vcc, 1.0, v34, 1.0
	v_mul_f32_e32 v175, v174, v173
	v_fma_f32 v176, -v172, v175, v174
	v_fmac_f32_e32 v175, v176, v173
	v_fma_f32 v172, -v172, v175, v174
	v_div_fmas_f32 v172, v172, v173, v175
	v_div_fixup_f32 v34, v172, v34, 1.0
	v_mul_f32_e32 v34, v181, v34
	v_fmac_f32_e32 v152, v34, v168
	global_store_dword v130, v152, s[86:87] offset:-3904
	v_cvt_pk_bf16_f32 v34, v152, s0
	global_store_short v135, v34, s[88:89] offset:1056
	v_add_f32_e32 v35, v35, v215
	v_mul_f32_e32 v35, 0xbfb8aa3b, v35
	v_exp_f32_e32 v35, v35
	v_lshlrev_b32_e32 v169, 16, v169
	v_add_f32_e32 v35, 1.0, v35
	v_div_scale_f32 v172, s[4:5], v35, v35, 1.0
	v_rcp_f32_e32 v173, v172
	s_nop 0
	v_fma_f32 v174, -v172, v173, 1.0
	v_fmac_f32_e32 v173, v174, v173
	v_div_scale_f32 v174, vcc, 1.0, v35, 1.0
	v_mul_f32_e32 v175, v174, v173
	v_fma_f32 v176, -v172, v175, v174
	v_fmac_f32_e32 v175, v176, v173
	v_fma_f32 v172, -v172, v175, v174
	v_div_fmas_f32 v172, v172, v173, v175
	v_div_fixup_f32 v35, v172, v35, 1.0
	v_mul_f32_e32 v35, v181, v35
	v_fmac_f32_e32 v153, v35, v169
	global_store_dword v130, v153, s[86:87] offset:192
	v_cvt_pk_bf16_f32 v35, v153, s0
	global_store_short v135, v35, s[88:89] offset:1120
	v_add_f32_e32 v36, v36, v215
	v_mul_f32_e32 v36, 0xbfb8aa3b, v36
	v_exp_f32_e32 v36, v36
	v_lshlrev_b32_e32 v170, 16, v170
	v_add_f32_e32 v36, 1.0, v36
	v_div_scale_f32 v172, s[4:5], v36, v36, 1.0
	v_rcp_f32_e32 v173, v172
	s_nop 0
	v_fma_f32 v174, -v172, v173, 1.0
	v_fmac_f32_e32 v173, v174, v173
	v_div_scale_f32 v174, vcc, 1.0, v36, 1.0
	v_mul_f32_e32 v175, v174, v173
	v_fma_f32 v176, -v172, v175, v174
	v_fmac_f32_e32 v175, v176, v173
	v_fma_f32 v172, -v172, v175, v174
	v_div_fmas_f32 v172, v172, v173, v175
	v_div_fixup_f32 v36, v172, v36, 1.0
	v_mul_f32_e32 v36, v181, v36
	v_fmac_f32_e32 v154, v36, v170
	global_store_dword v131, v154, s[86:87] offset:-3904
	v_cvt_pk_bf16_f32 v36, v154, s0
	global_store_short v135, v36, s[88:89] offset:1184
; DEV u16 f2bf(float f) { return (u16)(pack2(f, 0.f) & 0xffffu); }
; DEV float bf2f(u16 b) { return __uint_as_float(((unsigned)b) << 16); }
; DEV size_t tixw(long row, int col, int W) { return (size_t)(row >> 8) * (256 * (size_t)W) + (size_t)(col >> 5) * 8192 + (size_t)(row & 255) * 32 + (col & 31); }
; DEV float sigmoidf_(float x) { return 1.f / (1.f + __expf(-x)); }
;     ...
;       for (int ns = 0; ns < 4; ++ns)
; #pragma unroll
;         for (int j = 0; j < 4; ++j) {
;           int row = m0 + wm * 128 + ms * 16 + quad * 4 + j;
;           int col = n0 + wn * 64 + ns * 16 + l15;
;           size_t idx = (size_t)row * D + col;
;           float gate = sigmoidf_(acc[ms][ns][j] + bg[col]);
;           float v = P.out[idx] + psc * gate * bf2f(Pp[idx]);
;           P.out[idx] = v;
;           xbn[tixw(row, col, D)] = f2bf(v);
;         }
	v_add_f32_e32 v37, v37, v215
	v_mul_f32_e32 v37, 0xbfb8aa3b, v37
	v_exp_f32_e32 v37, v37
	v_lshlrev_b32_e32 v171, 16, v171
	v_add_f32_e32 v37, 1.0, v37
	v_div_scale_f32 v172, s[4:5], v37, v37, 1.0
	v_rcp_f32_e32 v173, v172
	s_nop 0
	v_fma_f32 v174, -v172, v173, 1.0
	v_fmac_f32_e32 v173, v174, v173
	v_div_scale_f32 v174, vcc, 1.0, v37, 1.0
	v_mul_f32_e32 v175, v174, v173
	v_fma_f32 v176, -v172, v175, v174
	v_fmac_f32_e32 v175, v176, v173
	v_fma_f32 v172, -v172, v175, v174
	v_div_fmas_f32 v172, v172, v173, v175
	v_div_fixup_f32 v37, v172, v37, 1.0
	v_mul_f32_e32 v37, v181, v37
	v_fmac_f32_e32 v155, v37, v171
	global_store_dword v131, v155, s[86:87] offset:192
	v_cvt_pk_bf16_f32 v37, v155, s0
	global_store_short v135, v37, s[88:89] offset:1248
	v_add_u32_e32 v130, 0x60000, v136
	v_add_u32_e32 v131, 0x2000, v130
	v_lshrrev_b32_e32 v132, 1, v130
	v_lshrrev_b32_e32 v133, 1, v131
	global_load_dword v140, v130, s[86:87] offset:-4096
	global_load_dword v141, v130, s[86:87]
	global_load_dword v142, v131, s[86:87] offset:-4096
	global_load_dword v143, v131, s[86:87]
	global_load_dword v144, v130, s[86:87] offset:-4032
	global_load_dword v145, v130, s[86:87] offset:64
	global_load_dword v146, v131, s[86:87] offset:-4032
	global_load_dword v147, v131, s[86:87] offset:64
	global_load_dword v148, v130, s[86:87] offset:-3968
	global_load_dword v149, v130, s[86:87] offset:128
	global_load_dword v150, v131, s[86:87] offset:-3968
	global_load_dword v151, v131, s[86:87] offset:128
	global_load_dword v152, v130, s[86:87] offset:-3904
	global_load_dword v153, v130, s[86:87] offset:192
	global_load_dword v154, v131, s[86:87] offset:-3904
	global_load_dword v155, v131, s[86:87] offset:192
	global_load_ushort v156, v132, s[96:97] offset:-2048
	global_load_ushort v157, v132, s[96:97]
	global_load_ushort v158, v133, s[96:97] offset:-2048
	global_load_ushort v159, v133, s[96:97]
	global_load_ushort v160, v132, s[96:97] offset:-2016
	global_load_ushort v161, v132, s[96:97] offset:32
	global_load_ushort v162, v133, s[96:97] offset:-2016
	global_load_ushort v163, v133, s[96:97] offset:32
	global_load_ushort v164, v132, s[96:97] offset:-1984
	global_load_ushort v165, v132, s[96:97] offset:64
	global_load_ushort v166, v133, s[96:97] offset:-1984
	global_load_ushort v167, v133, s[96:97] offset:64
	global_load_ushort v168, v132, s[96:97] offset:-1952
	global_load_ushort v169, v132, s[96:97] offset:96
	global_load_ushort v170, v133, s[96:97] offset:-1952
	global_load_ushort v171, v133, s[96:97] offset:96
	s_waitcnt vmcnt(0)
	v_add_f32_e32 v30, v30, v138
	v_mul_f32_e32 v30, 0xbfb8aa3b, v30
	v_exp_f32_e32 v30, v30
	v_lshlrev_b32_e32 v156, 16, v156
	v_add_f32_e32 v30, 1.0, v30
	v_div_scale_f32 v172, s[4:5], v30, v30, 1.0
	v_rcp_f32_e32 v173, v172
	s_nop 0
	v_fma_f32 v174, -v172, v173, 1.0
	v_fmac_f32_e32 v173, v174, v173
	v_div_scale_f32 v174, vcc, 1.0, v30, 1.0
	v_mul_f32_e32 v175, v174, v173
	v_fma_f32 v176, -v172, v175, v174
	v_fmac_f32_e32 v175, v176, v173
	v_fma_f32 v172, -v172, v175, v174
	v_div_fmas_f32 v172, v172, v173, v175
	v_div_fixup_f32 v30, v172, v30, 1.0
	v_mul_f32_e32 v30, v181, v30
	v_fmac_f32_e32 v140, v30, v156
	global_store_dword v130, v140, s[86:87] offset:-4096
	v_cvt_pk_bf16_f32 v30, v140, s0
	global_store_short v134, v30, s[88:89] offset:2048
	v_add_f32_e32 v31, v31, v138
	v_mul_f32_e32 v31, 0xbfb8aa3b, v31
	v_exp_f32_e32 v31, v31
	v_lshlrev_b32_e32 v157, 16, v157
	v_add_f32_e32 v31, 1.0, v31
	v_div_scale_f32 v172, s[4:5], v31, v31, 1.0
	v_rcp_f32_e32 v173, v172
	s_nop 0
	v_fma_f32 v174, -v172, v173, 1.0
	v_fmac_f32_e32 v173, v174, v173
	v_div_scale_f32 v174, vcc, 1.0, v31, 1.0
	v_mul_f32_e32 v175, v174, v173
	v_fma_f32 v176, -v172, v175, v174
	v_fmac_f32_e32 v175, v176, v173
	v_fma_f32 v172, -v172, v175, v174
	v_div_fmas_f32 v172, v172, v173, v175
	v_div_fixup_f32 v31, v172, v31, 1.0
	v_mul_f32_e32 v31, v181, v31
	v_fmac_f32_e32 v141, v31, v157
	global_store_dword v130, v141, s[86:87]
	v_cvt_pk_bf16_f32 v31, v141, s0
	global_store_short v134, v31, s[88:89] offset:2112
	v_add_f32_e32 v32, v32, v138
	v_mul_f32_e32 v32, 0xbfb8aa3b, v32
	v_exp_f32_e32 v32, v32
	v_lshlrev_b32_e32 v158, 16, v158
	v_add_f32_e32 v32, 1.0, v32
	v_div_scale_f32 v172, s[4:5], v32, v32, 1.0
	v_rcp_f32_e32 v173, v172
	s_nop 0
	v_fma_f32 v174, -v172, v173, 1.0
	v_fmac_f32_e32 v173, v174, v173
	v_div_scale_f32 v174, vcc, 1.0, v32, 1.0
	v_mul_f32_e32 v175, v174, v173
	v_fma_f32 v176, -v172, v175, v174
	v_fmac_f32_e32 v175, v176, v173
	v_fma_f32 v172, -v172, v175, v174
	v_div_fmas_f32 v172, v172, v173, v175
	v_div_fixup_f32 v32, v172, v32, 1.0
	v_mul_f32_e32 v32, v181, v32
	v_fmac_f32_e32 v142, v32, v158
	global_store_dword v131, v142, s[86:87] offset:-4096
	v_cvt_pk_bf16_f32 v32, v142, s0
	global_store_short v134, v32, s[88:89] offset:2176
	v_add_f32_e32 v33, v33, v138
	v_mul_f32_e32 v33, 0xbfb8aa3b, v33
	v_exp_f32_e32 v33, v33
	v_lshlrev_b32_e32 v159, 16, v159
	v_add_f32_e32 v33, 1.0, v33
	v_div_scale_f32 v172, s[4:5], v33, v33, 1.0
	v_rcp_f32_e32 v173, v172
	s_nop 0
	v_fma_f32 v174, -v172, v173, 1.0
	v_fmac_f32_e32 v173, v174, v173
	v_div_scale_f32 v174, vcc, 1.0, v33, 1.0
	v_mul_f32_e32 v175, v174, v173
	v_fma_f32 v176, -v172, v175, v174
	v_fmac_f32_e32 v175, v176, v173
	v_fma_f32 v172, -v172, v175, v174
	v_div_fmas_f32 v172, v172, v173, v175
	v_div_fixup_f32 v33, v172, v33, 1.0
	v_mul_f32_e32 v33, v181, v33
	v_fmac_f32_e32 v143, v33, v159
	global_store_dword v131, v143, s[86:87]
	v_cvt_pk_bf16_f32 v33, v143, s0
	global_store_short v134, v33, s[88:89] offset:2240
	v_add_f32_e32 v26, v26, v139
	v_mul_f32_e32 v26, 0xbfb8aa3b, v26
	v_exp_f32_e32 v26, v26
	v_lshlrev_b32_e32 v160, 16, v160
; DEV u16 f2bf(float f) { return (u16)(pack2(f, 0.f) & 0xffffu); }
; DEV float bf2f(u16 b) { return __uint_as_float(((unsigned)b) << 16); }
; DEV size_t tixw(long row, int col, int W) { return (size_t)(row >> 8) * (256 * (size_t)W) + (size_t)(col >> 5) * 8192 + (size_t)(row & 255) * 32 + (col & 31); }
; DEV float sigmoidf_(float x) { return 1.f / (1.f + __expf(-x)); }
;     ...
;       for (int ns = 0; ns < 4; ++ns)
; #pragma unroll
;         for (int j = 0; j < 4; ++j) {
;           int row = m0 + wm * 128 + ms * 16 + quad * 4 + j;
;           int col = n0 + wn * 64 + ns * 16 + l15;
;           size_t idx = (size_t)row * D + col;
;           float gate = sigmoidf_(acc[ms][ns][j] + bg[col]);
;           float v = P.out[idx] + psc * gate * bf2f(Pp[idx]);
;           P.out[idx] = v;
;           xbn[tixw(row, col, D)] = f2bf(v);
;         }
	v_add_f32_e32 v26, 1.0, v26
	v_div_scale_f32 v172, s[4:5], v26, v26, 1.0
	v_rcp_f32_e32 v173, v172
	s_nop 0
	v_fma_f32 v174, -v172, v173, 1.0
	v_fmac_f32_e32 v173, v174, v173
	v_div_scale_f32 v174, vcc, 1.0, v26, 1.0
	v_mul_f32_e32 v175, v174, v173
	v_fma_f32 v176, -v172, v175, v174
	v_fmac_f32_e32 v175, v176, v173
	v_fma_f32 v172, -v172, v175, v174
	v_div_fmas_f32 v172, v172, v173, v175
	v_div_fixup_f32 v26, v172, v26, 1.0
	v_mul_f32_e32 v26, v181, v26
	v_fmac_f32_e32 v144, v26, v160
	global_store_dword v130, v144, s[86:87] offset:-4032
	v_cvt_pk_bf16_f32 v26, v144, s0
	global_store_short v134, v26, s[88:89] offset:2080
	v_add_f32_e32 v27, v27, v139
	v_mul_f32_e32 v27, 0xbfb8aa3b, v27
	v_exp_f32_e32 v27, v27
	v_lshlrev_b32_e32 v161, 16, v161
	v_add_f32_e32 v27, 1.0, v27
	v_div_scale_f32 v172, s[4:5], v27, v27, 1.0
	v_rcp_f32_e32 v173, v172
	s_nop 0
	v_fma_f32 v174, -v172, v173, 1.0
	v_fmac_f32_e32 v173, v174, v173
	v_div_scale_f32 v174, vcc, 1.0, v27, 1.0
	v_mul_f32_e32 v175, v174, v173
	v_fma_f32 v176, -v172, v175, v174
	v_fmac_f32_e32 v175, v176, v173
	v_fma_f32 v172, -v172, v175, v174
	v_div_fmas_f32 v172, v172, v173, v175
	v_div_fixup_f32 v27, v172, v27, 1.0
	v_mul_f32_e32 v27, v181, v27
	v_fmac_f32_e32 v145, v27, v161
	global_store_dword v130, v145, s[86:87] offset:64
	v_cvt_pk_bf16_f32 v27, v145, s0
	global_store_short v134, v27, s[88:89] offset:2144
	v_add_f32_e32 v28, v28, v139
	v_mul_f32_e32 v28, 0xbfb8aa3b, v28
	v_exp_f32_e32 v28, v28
	v_lshlrev_b32_e32 v162, 16, v162
	v_add_f32_e32 v28, 1.0, v28
	v_div_scale_f32 v172, s[4:5], v28, v28, 1.0
	v_rcp_f32_e32 v173, v172
	s_nop 0
	v_fma_f32 v174, -v172, v173, 1.0
	v_fmac_f32_e32 v173, v174, v173
	v_div_scale_f32 v174, vcc, 1.0, v28, 1.0
	v_mul_f32_e32 v175, v174, v173
	v_fma_f32 v176, -v172, v175, v174
	v_fmac_f32_e32 v175, v176, v173
	v_fma_f32 v172, -v172, v175, v174
	v_div_fmas_f32 v172, v172, v173, v175
	v_div_fixup_f32 v28, v172, v28, 1.0
	v_mul_f32_e32 v28, v181, v28
	v_fmac_f32_e32 v146, v28, v162
	global_store_dword v131, v146, s[86:87] offset:-4032
	v_cvt_pk_bf16_f32 v28, v146, s0
	global_store_short v134, v28, s[88:89] offset:2208
	v_add_f32_e32 v29, v29, v139
	v_mul_f32_e32 v29, 0xbfb8aa3b, v29
	v_exp_f32_e32 v29, v29
	v_lshlrev_b32_e32 v163, 16, v163
	v_add_f32_e32 v29, 1.0, v29
	v_div_scale_f32 v172, s[4:5], v29, v29, 1.0
	v_rcp_f32_e32 v173, v172
	s_nop 0
	v_fma_f32 v174, -v172, v173, 1.0
	v_fmac_f32_e32 v173, v174, v173
	v_div_scale_f32 v174, vcc, 1.0, v29, 1.0
	v_mul_f32_e32 v175, v174, v173
	v_fma_f32 v176, -v172, v175, v174
	v_fmac_f32_e32 v175, v176, v173
	v_fma_f32 v172, -v172, v175, v174
	v_div_fmas_f32 v172, v172, v173, v175
	v_div_fixup_f32 v29, v172, v29, 1.0
	v_mul_f32_e32 v29, v181, v29
	v_fmac_f32_e32 v147, v29, v163
	global_store_dword v131, v147, s[86:87] offset:64
	v_cvt_pk_bf16_f32 v29, v147, s0
	global_store_short v134, v29, s[88:89] offset:2272
	v_add_f32_e32 v22, v22, v214
	v_mul_f32_e32 v22, 0xbfb8aa3b, v22
	v_exp_f32_e32 v22, v22
	v_lshlrev_b32_e32 v164, 16, v164
	v_add_f32_e32 v22, 1.0, v22
	v_div_scale_f32 v172, s[4:5], v22, v22, 1.0
	v_rcp_f32_e32 v173, v172
	s_nop 0
	v_fma_f32 v174, -v172, v173, 1.0
	v_fmac_f32_e32 v173, v174, v173
	v_div_scale_f32 v174, vcc, 1.0, v22, 1.0
	v_mul_f32_e32 v175, v174, v173
	v_fma_f32 v176, -v172, v175, v174
	v_fmac_f32_e32 v175, v176, v173
	v_fma_f32 v172, -v172, v175, v174
	v_div_fmas_f32 v172, v172, v173, v175
	v_div_fixup_f32 v22, v172, v22, 1.0
	v_mul_f32_e32 v22, v181, v22
	v_fmac_f32_e32 v148, v22, v164
	global_store_dword v130, v148, s[86:87] offset:-3968
	v_cvt_pk_bf16_f32 v22, v148, s0
	global_store_short v135, v22, s[88:89] offset:2048
	v_add_f32_e32 v23, v23, v214
	v_mul_f32_e32 v23, 0xbfb8aa3b, v23
	v_exp_f32_e32 v23, v23
	v_lshlrev_b32_e32 v165, 16, v165
	v_add_f32_e32 v23, 1.0, v23
	v_div_scale_f32 v172, s[4:5], v23, v23, 1.0
	v_rcp_f32_e32 v173, v172
	s_nop 0
	v_fma_f32 v174, -v172, v173, 1.0
	v_fmac_f32_e32 v173, v174, v173
	v_div_scale_f32 v174, vcc, 1.0, v23, 1.0
	v_mul_f32_e32 v175, v174, v173
	v_fma_f32 v176, -v172, v175, v174
	v_fmac_f32_e32 v175, v176, v173
	v_fma_f32 v172, -v172, v175, v174
	v_div_fmas_f32 v172, v172, v173, v175
	v_div_fixup_f32 v23, v172, v23, 1.0
	v_mul_f32_e32 v23, v181, v23
	v_fmac_f32_e32 v149, v23, v165
	global_store_dword v130, v149, s[86:87] offset:128
	v_cvt_pk_bf16_f32 v23, v149, s0
	global_store_short v135, v23, s[88:89] offset:2112
	v_add_f32_e32 v24, v24, v214
	v_mul_f32_e32 v24, 0xbfb8aa3b, v24
	v_exp_f32_e32 v24, v24
	v_lshlrev_b32_e32 v166, 16, v166
	v_add_f32_e32 v24, 1.0, v24
	v_div_scale_f32 v172, s[4:5], v24, v24, 1.0
	v_rcp_f32_e32 v173, v172
	s_nop 0
	v_fma_f32 v174, -v172, v173, 1.0
	v_fmac_f32_e32 v173, v174, v173
	v_div_scale_f32 v174, vcc, 1.0, v24, 1.0
	v_mul_f32_e32 v175, v174, v173
	v_fma_f32 v176, -v172, v175, v174
	v_fmac_f32_e32 v175, v176, v173
	v_fma_f32 v172, -v172, v175, v174
	v_div_fmas_f32 v172, v172, v173, v175
	v_div_fixup_f32 v24, v172, v24, 1.0
	v_mul_f32_e32 v24, v181, v24
	v_fmac_f32_e32 v150, v24, v166
	global_store_dword v131, v150, s[86:87] offset:-3968
	v_cvt_pk_bf16_f32 v24, v150, s0
	global_store_short v135, v24, s[88:89] offset:2176
	v_add_f32_e32 v25, v25, v214
	v_mul_f32_e32 v25, 0xbfb8aa3b, v25
	v_exp_f32_e32 v25, v25
	v_lshlrev_b32_e32 v167, 16, v167
	v_add_f32_e32 v25, 1.0, v25
	v_div_scale_f32 v172, s[4:5], v25, v25, 1.0
	v_rcp_f32_e32 v173, v172
	s_nop 0
	v_fma_f32 v174, -v172, v173, 1.0
	v_fmac_f32_e32 v173, v174, v173
	v_div_scale_f32 v174, vcc, 1.0, v25, 1.0
	v_mul_f32_e32 v175, v174, v173
	v_fma_f32 v176, -v172, v175, v174
	v_fmac_f32_e32 v175, v176, v173
	v_fma_f32 v172, -v172, v175, v174
; DEV u16 f2bf(float f) { return (u16)(pack2(f, 0.f) & 0xffffu); }
; DEV float bf2f(u16 b) { return __uint_as_float(((unsigned)b) << 16); }
; DEV size_t tixw(long row, int col, int W) { return (size_t)(row >> 8) * (256 * (size_t)W) + (size_t)(col >> 5) * 8192 + (size_t)(row & 255) * 32 + (col & 31); }
; DEV float sigmoidf_(float x) { return 1.f / (1.f + __expf(-x)); }
;     ...
;       for (int ns = 0; ns < 4; ++ns)
; #pragma unroll
;         for (int j = 0; j < 4; ++j) {
;           int row = m0 + wm * 128 + ms * 16 + quad * 4 + j;
;           int col = n0 + wn * 64 + ns * 16 + l15;
;           size_t idx = (size_t)row * D + col;
;           float gate = sigmoidf_(acc[ms][ns][j] + bg[col]);
;           float v = P.out[idx] + psc * gate * bf2f(Pp[idx]);
;           P.out[idx] = v;
;           xbn[tixw(row, col, D)] = f2bf(v);
;         }
	v_div_fmas_f32 v172, v172, v173, v175
	v_div_fixup_f32 v25, v172, v25, 1.0
	v_mul_f32_e32 v25, v181, v25
	v_fmac_f32_e32 v151, v25, v167
	global_store_dword v131, v151, s[86:87] offset:128
	v_cvt_pk_bf16_f32 v25, v151, s0
	global_store_short v135, v25, s[88:89] offset:2240
	v_add_f32_e32 v18, v18, v215
	v_mul_f32_e32 v18, 0xbfb8aa3b, v18
	v_exp_f32_e32 v18, v18
	v_lshlrev_b32_e32 v168, 16, v168
	v_add_f32_e32 v18, 1.0, v18
	v_div_scale_f32 v172, s[4:5], v18, v18, 1.0
	v_rcp_f32_e32 v173, v172
	s_nop 0
	v_fma_f32 v174, -v172, v173, 1.0
	v_fmac_f32_e32 v173, v174, v173
	v_div_scale_f32 v174, vcc, 1.0, v18, 1.0
	v_mul_f32_e32 v175, v174, v173
	v_fma_f32 v176, -v172, v175, v174
	v_fmac_f32_e32 v175, v176, v173
	v_fma_f32 v172, -v172, v175, v174
	v_div_fmas_f32 v172, v172, v173, v175
	v_div_fixup_f32 v18, v172, v18, 1.0
	v_mul_f32_e32 v18, v181, v18
	v_fmac_f32_e32 v152, v18, v168
	global_store_dword v130, v152, s[86:87] offset:-3904
	v_cvt_pk_bf16_f32 v18, v152, s0
	global_store_short v135, v18, s[88:89] offset:2080
	v_add_f32_e32 v19, v19, v215
	v_mul_f32_e32 v19, 0xbfb8aa3b, v19
	v_exp_f32_e32 v19, v19
	v_lshlrev_b32_e32 v169, 16, v169
	v_add_f32_e32 v19, 1.0, v19
	v_div_scale_f32 v172, s[4:5], v19, v19, 1.0
	v_rcp_f32_e32 v173, v172
	s_nop 0
	v_fma_f32 v174, -v172, v173, 1.0
	v_fmac_f32_e32 v173, v174, v173
	v_div_scale_f32 v174, vcc, 1.0, v19, 1.0
	v_mul_f32_e32 v175, v174, v173
	v_fma_f32 v176, -v172, v175, v174
	v_fmac_f32_e32 v175, v176, v173
	v_fma_f32 v172, -v172, v175, v174
	v_div_fmas_f32 v172, v172, v173, v175
	v_div_fixup_f32 v19, v172, v19, 1.0
	v_mul_f32_e32 v19, v181, v19
	v_fmac_f32_e32 v153, v19, v169
	global_store_dword v130, v153, s[86:87] offset:192
	v_cvt_pk_bf16_f32 v19, v153, s0
	global_store_short v135, v19, s[88:89] offset:2144
	v_add_f32_e32 v20, v20, v215
	v_mul_f32_e32 v20, 0xbfb8aa3b, v20
	v_exp_f32_e32 v20, v20
	v_lshlrev_b32_e32 v170, 16, v170
	v_add_f32_e32 v20, 1.0, v20
	v_div_scale_f32 v172, s[4:5], v20, v20, 1.0
	v_rcp_f32_e32 v173, v172
	s_nop 0
	v_fma_f32 v174, -v172, v173, 1.0
	v_fmac_f32_e32 v173, v174, v173
	v_div_scale_f32 v174, vcc, 1.0, v20, 1.0
	v_mul_f32_e32 v175, v174, v173
	v_fma_f32 v176, -v172, v175, v174
	v_fmac_f32_e32 v175, v176, v173
	v_fma_f32 v172, -v172, v175, v174
	v_div_fmas_f32 v172, v172, v173, v175
	v_div_fixup_f32 v20, v172, v20, 1.0
	v_mul_f32_e32 v20, v181, v20
	v_fmac_f32_e32 v154, v20, v170
	global_store_dword v131, v154, s[86:87] offset:-3904
	v_cvt_pk_bf16_f32 v20, v154, s0
	global_store_short v135, v20, s[88:89] offset:2208
	v_add_f32_e32 v21, v21, v215
	v_mul_f32_e32 v21, 0xbfb8aa3b, v21
	v_exp_f32_e32 v21, v21
	v_lshlrev_b32_e32 v171, 16, v171
	v_add_f32_e32 v21, 1.0, v21
	v_div_scale_f32 v172, s[4:5], v21, v21, 1.0
	v_rcp_f32_e32 v173, v172
	s_nop 0
	v_fma_f32 v174, -v172, v173, 1.0
	v_fmac_f32_e32 v173, v174, v173
	v_div_scale_f32 v174, vcc, 1.0, v21, 1.0
	v_mul_f32_e32 v175, v174, v173
	v_fma_f32 v176, -v172, v175, v174
	v_fmac_f32_e32 v175, v176, v173
	v_fma_f32 v172, -v172, v175, v174
	v_div_fmas_f32 v172, v172, v173, v175
	v_div_fixup_f32 v21, v172, v21, 1.0
	v_mul_f32_e32 v21, v181, v21
	v_fmac_f32_e32 v155, v21, v171
	global_store_dword v131, v155, s[86:87] offset:192
	v_cvt_pk_bf16_f32 v21, v155, s0
	global_store_short v135, v21, s[88:89] offset:2272
	v_add_u32_e32 v130, 0x70000, v136
	v_add_u32_e32 v131, 0x2000, v130
	v_lshrrev_b32_e32 v132, 1, v130
	v_lshrrev_b32_e32 v133, 1, v131
	global_load_dword v140, v130, s[86:87] offset:-4096
	global_load_dword v141, v130, s[86:87]
	global_load_dword v142, v131, s[86:87] offset:-4096
	global_load_dword v143, v131, s[86:87]
	global_load_dword v144, v130, s[86:87] offset:-4032
	global_load_dword v145, v130, s[86:87] offset:64
	global_load_dword v146, v131, s[86:87] offset:-4032
	global_load_dword v147, v131, s[86:87] offset:64
	global_load_dword v148, v130, s[86:87] offset:-3968
	global_load_dword v149, v130, s[86:87] offset:128
	global_load_dword v150, v131, s[86:87] offset:-3968
	global_load_dword v151, v131, s[86:87] offset:128
	global_load_dword v152, v130, s[86:87] offset:-3904
	global_load_dword v153, v130, s[86:87] offset:192
	global_load_dword v154, v131, s[86:87] offset:-3904
	global_load_dword v155, v131, s[86:87] offset:192
	global_load_ushort v156, v132, s[96:97] offset:-2048
	global_load_ushort v157, v132, s[96:97]
	global_load_ushort v158, v133, s[96:97] offset:-2048
	global_load_ushort v159, v133, s[96:97]
	global_load_ushort v160, v132, s[96:97] offset:-2016
	global_load_ushort v161, v132, s[96:97] offset:32
	global_load_ushort v162, v133, s[96:97] offset:-2016
	global_load_ushort v163, v133, s[96:97] offset:32
	global_load_ushort v164, v132, s[96:97] offset:-1984
	global_load_ushort v165, v132, s[96:97] offset:64
	global_load_ushort v166, v133, s[96:97] offset:-1984
	global_load_ushort v167, v133, s[96:97] offset:64
	global_load_ushort v168, v132, s[96:97] offset:-1952
	global_load_ushort v169, v132, s[96:97] offset:96
	global_load_ushort v170, v133, s[96:97] offset:-1952
	global_load_ushort v171, v133, s[96:97] offset:96
	s_waitcnt vmcnt(0)
; DEV u16 f2bf(float f) { return (u16)(pack2(f, 0.f) & 0xffffu); }
; DEV float bf2f(u16 b) { return __uint_as_float(((unsigned)b) << 16); }
; DEV size_t tixw(long row, int col, int W) { return (size_t)(row >> 8) * (256 * (size_t)W) + (size_t)(col >> 5) * 8192 + (size_t)(row & 255) * 32 + (col & 31); }
; DEV float sigmoidf_(float x) { return 1.f / (1.f + __expf(-x)); }
;     ...
;       for (int ns = 0; ns < 4; ++ns)
; #pragma unroll
;         for (int j = 0; j < 4; ++j) {
;           int row = m0 + wm * 128 + ms * 16 + quad * 4 + j;
;           int col = n0 + wn * 64 + ns * 16 + l15;
;           size_t idx = (size_t)row * D + col;
;           float gate = sigmoidf_(acc[ms][ns][j] + bg[col]);
;           float v = P.out[idx] + psc * gate * bf2f(Pp[idx]);
;           P.out[idx] = v;
;           xbn[tixw(row, col, D)] = f2bf(v);
;         }
	v_add_f32_e32 v14, v14, v138
	v_mul_f32_e32 v14, 0xbfb8aa3b, v14
	v_exp_f32_e32 v14, v14
	v_lshlrev_b32_e32 v156, 16, v156
	v_add_f32_e32 v14, 1.0, v14
	v_div_scale_f32 v172, s[4:5], v14, v14, 1.0
	v_rcp_f32_e32 v173, v172
	s_nop 0
	v_fma_f32 v174, -v172, v173, 1.0
	v_fmac_f32_e32 v173, v174, v173
	v_div_scale_f32 v174, vcc, 1.0, v14, 1.0
	v_mul_f32_e32 v175, v174, v173
	v_fma_f32 v176, -v172, v175, v174
	v_fmac_f32_e32 v175, v176, v173
	v_fma_f32 v172, -v172, v175, v174
	v_div_fmas_f32 v172, v172, v173, v175
	v_div_fixup_f32 v14, v172, v14, 1.0
	v_mul_f32_e32 v14, v181, v14
	v_fmac_f32_e32 v140, v14, v156
	global_store_dword v130, v140, s[86:87] offset:-4096
	v_cvt_pk_bf16_f32 v14, v140, s0
	global_store_short v134, v14, s[88:89] offset:3072
	v_add_f32_e32 v15, v15, v138
	v_mul_f32_e32 v15, 0xbfb8aa3b, v15
	v_exp_f32_e32 v15, v15
	v_lshlrev_b32_e32 v157, 16, v157
	v_add_f32_e32 v15, 1.0, v15
	v_div_scale_f32 v172, s[4:5], v15, v15, 1.0
	v_rcp_f32_e32 v173, v172
	s_nop 0
	v_fma_f32 v174, -v172, v173, 1.0
	v_fmac_f32_e32 v173, v174, v173
	v_div_scale_f32 v174, vcc, 1.0, v15, 1.0
	v_mul_f32_e32 v175, v174, v173
	v_fma_f32 v176, -v172, v175, v174
	v_fmac_f32_e32 v175, v176, v173
	v_fma_f32 v172, -v172, v175, v174
	v_div_fmas_f32 v172, v172, v173, v175
	v_div_fixup_f32 v15, v172, v15, 1.0
	v_mul_f32_e32 v15, v181, v15
	v_fmac_f32_e32 v141, v15, v157
	global_store_dword v130, v141, s[86:87]
	v_cvt_pk_bf16_f32 v15, v141, s0
	global_store_short v134, v15, s[88:89] offset:3136
	v_add_f32_e32 v16, v16, v138
	v_mul_f32_e32 v16, 0xbfb8aa3b, v16
	v_exp_f32_e32 v16, v16
	v_lshlrev_b32_e32 v158, 16, v158
	v_add_f32_e32 v16, 1.0, v16
	v_div_scale_f32 v172, s[4:5], v16, v16, 1.0
	v_rcp_f32_e32 v173, v172
	s_nop 0
	v_fma_f32 v174, -v172, v173, 1.0
	v_fmac_f32_e32 v173, v174, v173
	v_div_scale_f32 v174, vcc, 1.0, v16, 1.0
	v_mul_f32_e32 v175, v174, v173
	v_fma_f32 v176, -v172, v175, v174
	v_fmac_f32_e32 v175, v176, v173
	v_fma_f32 v172, -v172, v175, v174
	v_div_fmas_f32 v172, v172, v173, v175
	v_div_fixup_f32 v16, v172, v16, 1.0
	v_mul_f32_e32 v16, v181, v16
	v_fmac_f32_e32 v142, v16, v158
	global_store_dword v131, v142, s[86:87] offset:-4096
	v_cvt_pk_bf16_f32 v16, v142, s0
	global_store_short v134, v16, s[88:89] offset:3200
	v_add_f32_e32 v17, v17, v138
	v_mul_f32_e32 v17, 0xbfb8aa3b, v17
	v_exp_f32_e32 v17, v17
	v_lshlrev_b32_e32 v159, 16, v159
	v_add_f32_e32 v17, 1.0, v17
	v_div_scale_f32 v172, s[4:5], v17, v17, 1.0
	v_rcp_f32_e32 v173, v172
	s_nop 0
	v_fma_f32 v174, -v172, v173, 1.0
	v_fmac_f32_e32 v173, v174, v173
	v_div_scale_f32 v174, vcc, 1.0, v17, 1.0
	v_mul_f32_e32 v175, v174, v173
	v_fma_f32 v176, -v172, v175, v174
	v_fmac_f32_e32 v175, v176, v173
	v_fma_f32 v172, -v172, v175, v174
	v_div_fmas_f32 v172, v172, v173, v175
	v_div_fixup_f32 v17, v172, v17, 1.0
	v_mul_f32_e32 v17, v181, v17
	v_fmac_f32_e32 v143, v17, v159
	global_store_dword v131, v143, s[86:87]
	v_cvt_pk_bf16_f32 v17, v143, s0
	global_store_short v134, v17, s[88:89] offset:3264
	v_add_f32_e32 v10, v10, v139
	v_mul_f32_e32 v10, 0xbfb8aa3b, v10
	v_exp_f32_e32 v10, v10
	v_lshlrev_b32_e32 v160, 16, v160
	v_add_f32_e32 v10, 1.0, v10
	v_div_scale_f32 v172, s[4:5], v10, v10, 1.0
	v_rcp_f32_e32 v173, v172
	s_nop 0
	v_fma_f32 v174, -v172, v173, 1.0
	v_fmac_f32_e32 v173, v174, v173
	v_div_scale_f32 v174, vcc, 1.0, v10, 1.0
	v_mul_f32_e32 v175, v174, v173
	v_fma_f32 v176, -v172, v175, v174
	v_fmac_f32_e32 v175, v176, v173
	v_fma_f32 v172, -v172, v175, v174
	v_div_fmas_f32 v172, v172, v173, v175
	v_div_fixup_f32 v10, v172, v10, 1.0
	v_mul_f32_e32 v10, v181, v10
	v_fmac_f32_e32 v144, v10, v160
	global_store_dword v130, v144, s[86:87] offset:-4032
	v_cvt_pk_bf16_f32 v10, v144, s0
	global_store_short v134, v10, s[88:89] offset:3104
	v_add_f32_e32 v11, v11, v139
	v_mul_f32_e32 v11, 0xbfb8aa3b, v11
	v_exp_f32_e32 v11, v11
	v_lshlrev_b32_e32 v161, 16, v161
	v_add_f32_e32 v11, 1.0, v11
	v_div_scale_f32 v172, s[4:5], v11, v11, 1.0
	v_rcp_f32_e32 v173, v172
	s_nop 0
	v_fma_f32 v174, -v172, v173, 1.0
	v_fmac_f32_e32 v173, v174, v173
	v_div_scale_f32 v174, vcc, 1.0, v11, 1.0
	v_mul_f32_e32 v175, v174, v173
	v_fma_f32 v176, -v172, v175, v174
	v_fmac_f32_e32 v175, v176, v173
	v_fma_f32 v172, -v172, v175, v174
	v_div_fmas_f32 v172, v172, v173, v175
	v_div_fixup_f32 v11, v172, v11, 1.0
	v_mul_f32_e32 v11, v181, v11
	v_fmac_f32_e32 v145, v11, v161
	global_store_dword v130, v145, s[86:87] offset:64
	v_cvt_pk_bf16_f32 v11, v145, s0
	global_store_short v134, v11, s[88:89] offset:3168
	v_add_f32_e32 v12, v12, v139
	v_mul_f32_e32 v12, 0xbfb8aa3b, v12
	v_exp_f32_e32 v12, v12
	v_lshlrev_b32_e32 v162, 16, v162
	v_add_f32_e32 v12, 1.0, v12
	v_div_scale_f32 v172, s[4:5], v12, v12, 1.0
	v_rcp_f32_e32 v173, v172
	s_nop 0
	v_fma_f32 v174, -v172, v173, 1.0
	v_fmac_f32_e32 v173, v174, v173
	v_div_scale_f32 v174, vcc, 1.0, v12, 1.0
	v_mul_f32_e32 v175, v174, v173
	v_fma_f32 v176, -v172, v175, v174
	v_fmac_f32_e32 v175, v176, v173
	v_fma_f32 v172, -v172, v175, v174
	v_div_fmas_f32 v172, v172, v173, v175
	v_div_fixup_f32 v12, v172, v12, 1.0
	v_mul_f32_e32 v12, v181, v12
	v_fmac_f32_e32 v146, v12, v162
	global_store_dword v131, v146, s[86:87] offset:-4032
	v_cvt_pk_bf16_f32 v12, v146, s0
	global_store_short v134, v12, s[88:89] offset:3232
	v_add_f32_e32 v13, v13, v139
	v_mul_f32_e32 v13, 0xbfb8aa3b, v13
	v_exp_f32_e32 v13, v13
	v_lshlrev_b32_e32 v163, 16, v163
	v_add_f32_e32 v13, 1.0, v13
	v_div_scale_f32 v172, s[4:5], v13, v13, 1.0
	v_rcp_f32_e32 v173, v172
	s_nop 0
	v_fma_f32 v174, -v172, v173, 1.0
	v_fmac_f32_e32 v173, v174, v173
	v_div_scale_f32 v174, vcc, 1.0, v13, 1.0
	v_mul_f32_e32 v175, v174, v173
; DEV u16 f2bf(float f) { return (u16)(pack2(f, 0.f) & 0xffffu); }
; DEV float bf2f(u16 b) { return __uint_as_float(((unsigned)b) << 16); }
; DEV size_t tixw(long row, int col, int W) { return (size_t)(row >> 8) * (256 * (size_t)W) + (size_t)(col >> 5) * 8192 + (size_t)(row & 255) * 32 + (col & 31); }
; DEV float sigmoidf_(float x) { return 1.f / (1.f + __expf(-x)); }
;     ...
;       for (int ns = 0; ns < 4; ++ns)
; #pragma unroll
;         for (int j = 0; j < 4; ++j) {
;           int row = m0 + wm * 128 + ms * 16 + quad * 4 + j;
;           int col = n0 + wn * 64 + ns * 16 + l15;
;           size_t idx = (size_t)row * D + col;
;           float gate = sigmoidf_(acc[ms][ns][j] + bg[col]);
;           float v = P.out[idx] + psc * gate * bf2f(Pp[idx]);
;           P.out[idx] = v;
;           xbn[tixw(row, col, D)] = f2bf(v);
;         }
	v_fma_f32 v176, -v172, v175, v174
	v_fmac_f32_e32 v175, v176, v173
	v_fma_f32 v172, -v172, v175, v174
	v_div_fmas_f32 v172, v172, v173, v175
	v_div_fixup_f32 v13, v172, v13, 1.0
	v_mul_f32_e32 v13, v181, v13
	v_fmac_f32_e32 v147, v13, v163
	global_store_dword v131, v147, s[86:87] offset:64
	v_cvt_pk_bf16_f32 v13, v147, s0
	global_store_short v134, v13, s[88:89] offset:3296
	v_add_f32_e32 v6, v6, v214
	v_mul_f32_e32 v6, 0xbfb8aa3b, v6
	v_exp_f32_e32 v6, v6
	v_lshlrev_b32_e32 v164, 16, v164
	v_add_f32_e32 v6, 1.0, v6
	v_div_scale_f32 v172, s[4:5], v6, v6, 1.0
	v_rcp_f32_e32 v173, v172
	s_nop 0
	v_fma_f32 v174, -v172, v173, 1.0
	v_fmac_f32_e32 v173, v174, v173
	v_div_scale_f32 v174, vcc, 1.0, v6, 1.0
	v_mul_f32_e32 v175, v174, v173
	v_fma_f32 v176, -v172, v175, v174
	v_fmac_f32_e32 v175, v176, v173
	v_fma_f32 v172, -v172, v175, v174
	v_div_fmas_f32 v172, v172, v173, v175
	v_div_fixup_f32 v6, v172, v6, 1.0
	v_mul_f32_e32 v6, v181, v6
	v_fmac_f32_e32 v148, v6, v164
	global_store_dword v130, v148, s[86:87] offset:-3968
	v_cvt_pk_bf16_f32 v6, v148, s0
	global_store_short v135, v6, s[88:89] offset:3072
	v_add_f32_e32 v7, v7, v214
	v_mul_f32_e32 v7, 0xbfb8aa3b, v7
	v_exp_f32_e32 v7, v7
	v_lshlrev_b32_e32 v165, 16, v165
	v_add_f32_e32 v7, 1.0, v7
	v_div_scale_f32 v172, s[4:5], v7, v7, 1.0
	v_rcp_f32_e32 v173, v172
	s_nop 0
	v_fma_f32 v174, -v172, v173, 1.0
	v_fmac_f32_e32 v173, v174, v173
	v_div_scale_f32 v174, vcc, 1.0, v7, 1.0
	v_mul_f32_e32 v175, v174, v173
	v_fma_f32 v176, -v172, v175, v174
	v_fmac_f32_e32 v175, v176, v173
	v_fma_f32 v172, -v172, v175, v174
	v_div_fmas_f32 v172, v172, v173, v175
	v_div_fixup_f32 v7, v172, v7, 1.0
	v_mul_f32_e32 v7, v181, v7
	v_fmac_f32_e32 v149, v7, v165
	global_store_dword v130, v149, s[86:87] offset:128
	v_cvt_pk_bf16_f32 v7, v149, s0
	global_store_short v135, v7, s[88:89] offset:3136
	v_add_f32_e32 v8, v8, v214
	v_mul_f32_e32 v8, 0xbfb8aa3b, v8
	v_exp_f32_e32 v8, v8
	v_lshlrev_b32_e32 v166, 16, v166
	v_add_f32_e32 v8, 1.0, v8
	v_div_scale_f32 v172, s[4:5], v8, v8, 1.0
	v_rcp_f32_e32 v173, v172
	s_nop 0
	v_fma_f32 v174, -v172, v173, 1.0
	v_fmac_f32_e32 v173, v174, v173
	v_div_scale_f32 v174, vcc, 1.0, v8, 1.0
	v_mul_f32_e32 v175, v174, v173
	v_fma_f32 v176, -v172, v175, v174
	v_fmac_f32_e32 v175, v176, v173
	v_fma_f32 v172, -v172, v175, v174
	v_div_fmas_f32 v172, v172, v173, v175
	v_div_fixup_f32 v8, v172, v8, 1.0
	v_mul_f32_e32 v8, v181, v8
	v_fmac_f32_e32 v150, v8, v166
	global_store_dword v131, v150, s[86:87] offset:-3968
	v_cvt_pk_bf16_f32 v8, v150, s0
	global_store_short v135, v8, s[88:89] offset:3200
	v_add_f32_e32 v9, v9, v214
	v_mul_f32_e32 v9, 0xbfb8aa3b, v9
	v_exp_f32_e32 v9, v9
	v_lshlrev_b32_e32 v167, 16, v167
	v_add_f32_e32 v9, 1.0, v9
	v_div_scale_f32 v172, s[4:5], v9, v9, 1.0
	v_rcp_f32_e32 v173, v172
	s_nop 0
	v_fma_f32 v174, -v172, v173, 1.0
	v_fmac_f32_e32 v173, v174, v173
	v_div_scale_f32 v174, vcc, 1.0, v9, 1.0
	v_mul_f32_e32 v175, v174, v173
	v_fma_f32 v176, -v172, v175, v174
	v_fmac_f32_e32 v175, v176, v173
	v_fma_f32 v172, -v172, v175, v174
	v_div_fmas_f32 v172, v172, v173, v175
	v_div_fixup_f32 v9, v172, v9, 1.0
	v_mul_f32_e32 v9, v181, v9
	v_fmac_f32_e32 v151, v9, v167
	global_store_dword v131, v151, s[86:87] offset:128
	v_cvt_pk_bf16_f32 v9, v151, s0
	global_store_short v135, v9, s[88:89] offset:3264
	v_add_f32_e32 v2, v2, v215
	v_mul_f32_e32 v2, 0xbfb8aa3b, v2
	v_exp_f32_e32 v2, v2
	v_lshlrev_b32_e32 v168, 16, v168
	v_add_f32_e32 v2, 1.0, v2
	v_div_scale_f32 v172, s[4:5], v2, v2, 1.0
	v_rcp_f32_e32 v173, v172
	s_nop 0
	v_fma_f32 v174, -v172, v173, 1.0
	v_fmac_f32_e32 v173, v174, v173
	v_div_scale_f32 v174, vcc, 1.0, v2, 1.0
	v_mul_f32_e32 v175, v174, v173
	v_fma_f32 v176, -v172, v175, v174
	v_fmac_f32_e32 v175, v176, v173
	v_fma_f32 v172, -v172, v175, v174
	v_div_fmas_f32 v172, v172, v173, v175
	v_div_fixup_f32 v2, v172, v2, 1.0
	v_mul_f32_e32 v2, v181, v2
	v_fmac_f32_e32 v152, v2, v168
	global_store_dword v130, v152, s[86:87] offset:-3904
	v_cvt_pk_bf16_f32 v2, v152, s0
	global_store_short v135, v2, s[88:89] offset:3104
	v_add_f32_e32 v3, v3, v215
	v_mul_f32_e32 v3, 0xbfb8aa3b, v3
	v_exp_f32_e32 v3, v3
	v_lshlrev_b32_e32 v169, 16, v169
	v_add_f32_e32 v3, 1.0, v3
	v_div_scale_f32 v172, s[4:5], v3, v3, 1.0
	v_rcp_f32_e32 v173, v172
	s_nop 0
	v_fma_f32 v174, -v172, v173, 1.0
	v_fmac_f32_e32 v173, v174, v173
	v_div_scale_f32 v174, vcc, 1.0, v3, 1.0
	v_mul_f32_e32 v175, v174, v173
	v_fma_f32 v176, -v172, v175, v174
	v_fmac_f32_e32 v175, v176, v173
	v_fma_f32 v172, -v172, v175, v174
	v_div_fmas_f32 v172, v172, v173, v175
	v_div_fixup_f32 v3, v172, v3, 1.0
	v_mul_f32_e32 v3, v181, v3
	v_fmac_f32_e32 v153, v3, v169
	global_store_dword v130, v153, s[86:87] offset:192
	v_cvt_pk_bf16_f32 v3, v153, s0
	global_store_short v135, v3, s[88:89] offset:3168
	v_add_f32_e32 v4, v4, v215
	v_mul_f32_e32 v4, 0xbfb8aa3b, v4
	v_exp_f32_e32 v4, v4
	v_lshlrev_b32_e32 v170, 16, v170
	v_add_f32_e32 v4, 1.0, v4
	v_div_scale_f32 v172, s[4:5], v4, v4, 1.0
	v_rcp_f32_e32 v173, v172
	s_nop 0
	v_fma_f32 v174, -v172, v173, 1.0
	v_fmac_f32_e32 v173, v174, v173
	v_div_scale_f32 v174, vcc, 1.0, v4, 1.0
	v_mul_f32_e32 v175, v174, v173
	v_fma_f32 v176, -v172, v175, v174
	v_fmac_f32_e32 v175, v176, v173
	v_fma_f32 v172, -v172, v175, v174
	v_div_fmas_f32 v172, v172, v173, v175
	v_div_fixup_f32 v4, v172, v4, 1.0
	v_mul_f32_e32 v4, v181, v4
	v_fmac_f32_e32 v154, v4, v170
	global_store_dword v131, v154, s[86:87] offset:-3904
	v_cvt_pk_bf16_f32 v4, v154, s0
	global_store_short v135, v4, s[88:89] offset:3232
	v_add_f32_e32 v5, v5, v215
	v_mul_f32_e32 v5, 0xbfb8aa3b, v5
	v_exp_f32_e32 v5, v5
	v_lshlrev_b32_e32 v171, 16, v171
	v_add_f32_e32 v5, 1.0, v5
	v_div_scale_f32 v172, s[4:5], v5, v5, 1.0
	v_rcp_f32_e32 v173, v172
	s_nop 0
	v_fma_f32 v174, -v172, v173, 1.0
	v_fmac_f32_e32 v173, v174, v173
	v_div_scale_f32 v174, vcc, 1.0, v5, 1.0
	v_mul_f32_e32 v175, v174, v173
	v_fma_f32 v176, -v172, v175, v174
	v_fmac_f32_e32 v175, v176, v173
	v_fma_f32 v172, -v172, v175, v174
	v_div_fmas_f32 v172, v172, v173, v175
	v_div_fixup_f32 v5, v172, v5, 1.0
	v_mul_f32_e32 v5, v181, v5
	v_fmac_f32_e32 v155, v5, v171
	global_store_dword v131, v155, s[86:87] offset:192
	v_cvt_pk_bf16_f32 v5, v155, s0
	global_store_short v135, v5, s[88:89] offset:3296
	s_and_b64 vcc, exec, s[10:11]
	s_cbranch_vccnz .LBB0_91

; DEV void phase_ln(const Params& P, const float* __restrict__ g, const float* __restrict__ bta, u16* __restrict__ xb, bool zero_kc) {
;     ...
;   for (int row = gw; row < T; row += 2 * nw) {
;     const bool hasB = (row + nw) < T;
;     const int rows[2] = {row, hasB ? row + nw : row};
;     float4 v[2][4];
; #pragma unroll
;     for (int r = 0; r < 2; ++r) {
;       const float* xr = P.out + (size_t)rows[r] * D + lane * 4;
; #pragma unroll
;       for (int i = 0; i < 4; ++i) v[r][i] = *(const float4*)(xr + i * 256);
;     }
;     float s[2] = {0.f, 0.f};
; #pragma unroll
;     for (int r = 0; r < 2; ++r)
; #pragma unroll
;       for (int i = 0; i < 4; ++i) s[r] += v[r][i].x + v[r][i].y + v[r][i].z + v[r][i].w;
; #pragma unroll
;     for (int o = 32; o >= 1; o >>= 1) {
;       s[0] += __shfl_xor(s[0], o);
;       s[1] += __shfl_xor(s[1], o);
;     }
.LBB0_95:
.LBB0_96:
	v_readfirstlane_b32 s4, v34
	v_readlane_b32 s5, v254, 3
	s_mul_i32 s4, s4, 4
	s_mul_i32 s5, s5, 4
	v_and_b32_e32 v35, 63, v210
	v_lshlrev_b32_e32 v35, 4, v35
	v_add_u32_e32 v36, v52, v0
	v_add_u32_e32 v37, 0x20000, v36
	v_add_u32_e32 v38, 0x40000, v36
	v_add_u32_e32 v39, 0x60000, v36
.Lln_loop_1:
	s_add_i32 s8, s4, 0
	s_min_i32 s8, s8, 0x7fff
	s_lshl_b32 s8, s8, 12
	v_add_u32_e32 v72, s8, v35
	global_load_dwordx4 v[108:111], v72, s[86:87]
	global_load_dwordx4 v[112:115], v72, s[86:87] offset:1024
	global_load_dwordx4 v[116:119], v72, s[86:87] offset:2048
	global_load_dwordx4 v[120:123], v72, s[86:87] offset:3072
	s_add_i32 s8, s4, 1
	s_min_i32 s8, s8, 0x7fff
	s_lshl_b32 s8, s8, 12
	v_add_u32_e32 v73, s8, v35
	global_load_dwordx4 v[124:127], v73, s[86:87]
	global_load_dwordx4 v[128:131], v73, s[86:87] offset:1024
	global_load_dwordx4 v[132:135], v73, s[86:87] offset:2048
	global_load_dwordx4 v[136:139], v73, s[86:87] offset:3072
	s_add_i32 s8, s4, 2
	s_min_i32 s8, s8, 0x7fff
	s_lshl_b32 s8, s8, 12
	v_add_u32_e32 v74, s8, v35
	global_load_dwordx4 v[140:143], v74, s[86:87]
	global_load_dwordx4 v[144:147], v74, s[86:87] offset:1024
	global_load_dwordx4 v[148:151], v74, s[86:87] offset:2048
	global_load_dwordx4 v[152:155], v74, s[86:87] offset:3072
	s_add_i32 s8, s4, 3
	s_min_i32 s8, s8, 0x7fff
	s_lshl_b32 s8, s8, 12
	v_add_u32_e32 v75, s8, v35
	global_load_dwordx4 v[156:159], v75, s[86:87]
	global_load_dwordx4 v[160:163], v75, s[86:87] offset:1024
	global_load_dwordx4 v[164:167], v75, s[86:87] offset:2048
	global_load_dwordx4 v[168:171], v75, s[86:87] offset:3072
	s_waitcnt vmcnt(0)
	v_add_f32_e32 v42, v108, v109
	v_add_f32_e32 v42, v42, v110
	v_add_f32_e32 v42, v42, v111
	v_add_f32_e32 v60, v112, v113
	v_add_f32_e32 v60, v60, v114
	v_add_f32_e32 v60, v60, v115
	v_add_f32_e32 v42, v42, v60
	v_add_f32_e32 v60, v116, v117
	v_add_f32_e32 v60, v60, v118
	v_add_f32_e32 v60, v60, v119
	v_add_f32_e32 v42, v42, v60
	v_add_f32_e32 v60, v120, v121
	v_add_f32_e32 v60, v60, v122
	v_add_f32_e32 v60, v60, v123
	v_add_f32_e32 v42, v42, v60
	v_add_f32_e32 v43, v124, v125
	v_add_f32_e32 v43, v43, v126
	v_add_f32_e32 v43, v43, v127
	v_add_f32_e32 v61, v128, v129
	v_add_f32_e32 v61, v61, v130
	v_add_f32_e32 v61, v61, v131
	v_add_f32_e32 v43, v43, v61
	v_add_f32_e32 v61, v132, v133
	v_add_f32_e32 v61, v61, v134
	v_add_f32_e32 v61, v61, v135
	v_add_f32_e32 v43, v43, v61
	v_add_f32_e32 v61, v136, v137
	v_add_f32_e32 v61, v61, v138
	v_add_f32_e32 v61, v61, v139
	v_add_f32_e32 v43, v43, v61
	v_add_f32_e32 v44, v140, v141
	v_add_f32_e32 v44, v44, v142
	v_add_f32_e32 v44, v44, v143
	v_add_f32_e32 v62, v144, v145
	v_add_f32_e32 v62, v62, v146
	v_add_f32_e32 v62, v62, v147
	v_add_f32_e32 v44, v44, v62
	v_add_f32_e32 v62, v148, v149
	v_add_f32_e32 v62, v62, v150
	v_add_f32_e32 v62, v62, v151
	v_add_f32_e32 v44, v44, v62
	v_add_f32_e32 v62, v152, v153
	v_add_f32_e32 v62, v62, v154
	v_add_f32_e32 v62, v62, v155
	v_add_f32_e32 v44, v44, v62
	v_add_f32_e32 v45, v156, v157
	v_add_f32_e32 v45, v45, v158
	v_add_f32_e32 v45, v45, v159
	v_add_f32_e32 v63, v160, v161
	v_add_f32_e32 v63, v63, v162
	v_add_f32_e32 v63, v63, v163
	v_add_f32_e32 v45, v45, v63
	v_add_f32_e32 v63, v164, v165
	v_add_f32_e32 v63, v63, v166
	v_add_f32_e32 v63, v63, v167
	v_add_f32_e32 v45, v45, v63
	v_add_f32_e32 v63, v168, v169
	v_add_f32_e32 v63, v63, v170
	v_add_f32_e32 v63, v63, v171
	v_add_f32_e32 v45, v45, v63
	ds_bpermute_b32 v60, v96, v42
	ds_bpermute_b32 v61, v96, v43
	ds_bpermute_b32 v62, v96, v44
	ds_bpermute_b32 v63, v96, v45
	s_waitcnt lgkmcnt(3)
	v_add_f32_e32 v42, v42, v60
	s_waitcnt lgkmcnt(2)
	v_add_f32_e32 v43, v43, v61
	s_waitcnt lgkmcnt(1)
	v_add_f32_e32 v44, v44, v62
	s_waitcnt lgkmcnt(0)
	v_add_f32_e32 v45, v45, v63
	ds_bpermute_b32 v60, v97, v42
	ds_bpermute_b32 v61, v97, v43
	ds_bpermute_b32 v62, v97, v44
	ds_bpermute_b32 v63, v97, v45
	s_waitcnt lgkmcnt(3)
	v_add_f32_e32 v42, v42, v60
	s_waitcnt lgkmcnt(2)
	v_add_f32_e32 v43, v43, v61
	s_waitcnt lgkmcnt(1)
	v_add_f32_e32 v44, v44, v62
	s_waitcnt lgkmcnt(0)
	v_add_f32_e32 v45, v45, v63
	ds_bpermute_b32 v60, v98, v42
	ds_bpermute_b32 v61, v98, v43
	ds_bpermute_b32 v62, v98, v44
	ds_bpermute_b32 v63, v98, v45
	s_waitcnt lgkmcnt(3)
	v_add_f32_e32 v42, v42, v60
	s_waitcnt lgkmcnt(2)
	v_add_f32_e32 v43, v43, v61
	s_waitcnt lgkmcnt(1)
	v_add_f32_e32 v44, v44, v62
	s_waitcnt lgkmcnt(0)
	v_add_f32_e32 v45, v45, v63
	ds_bpermute_b32 v60, v99, v42
	ds_bpermute_b32 v61, v99, v43
	ds_bpermute_b32 v62, v99, v44
	ds_bpermute_b32 v63, v99, v45
	s_waitcnt lgkmcnt(3)
	v_add_f32_e32 v42, v42, v60
	s_waitcnt lgkmcnt(2)
	v_add_f32_e32 v43, v43, v61
	s_waitcnt lgkmcnt(1)
	v_add_f32_e32 v44, v44, v62
	s_waitcnt lgkmcnt(0)
	v_add_f32_e32 v45, v45, v63
	ds_bpermute_b32 v60, v100, v42
	ds_bpermute_b32 v61, v100, v43
	ds_bpermute_b32 v62, v100, v44
	ds_bpermute_b32 v63, v100, v45
	s_waitcnt lgkmcnt(3)
	v_add_f32_e32 v42, v42, v60
	s_waitcnt lgkmcnt(2)
	v_add_f32_e32 v43, v43, v61
	s_waitcnt lgkmcnt(1)
	v_add_f32_e32 v44, v44, v62
	s_waitcnt lgkmcnt(0)
	v_add_f32_e32 v45, v45, v63
	ds_bpermute_b32 v60, v101, v42
	ds_bpermute_b32 v61, v101, v43
	ds_bpermute_b32 v62, v101, v44
	ds_bpermute_b32 v63, v101, v45
	s_waitcnt lgkmcnt(3)
	v_add_f32_e32 v42, v42, v60
	s_waitcnt lgkmcnt(2)
	v_add_f32_e32 v43, v43, v61
	s_waitcnt lgkmcnt(1)
	v_add_f32_e32 v44, v44, v62
	s_waitcnt lgkmcnt(0)
; DEV void phase_ln(const Params& P, const float* __restrict__ g, const float* __restrict__ bta, u16* __restrict__ xb, bool zero_kc) {
;     ...
;     float q[2] = {0.f, 0.f};
; #pragma unroll
;     for (int r = 0; r < 2; ++r) {
;       const float mu = s[r] * (1.f / 1024.f);
; #pragma unroll
;       for (int i = 0; i < 4; ++i) {
;         v[r][i].x -= mu; v[r][i].y -= mu; v[r][i].z -= mu; v[r][i].w -= mu;
;         q[r] += v[r][i].x * v[r][i].x + v[r][i].y * v[r][i].y + v[r][i].z * v[r][i].z + v[r][i].w * v[r][i].w;
;       }
;     }
; #pragma unroll
;     for (int o = 32; o >= 1; o >>= 1) {
;       q[0] += __shfl_xor(q[0], o);
;       q[1] += __shfl_xor(q[1], o);
;     }
	v_add_f32_e32 v45, v45, v63
	v_mul_f32_e32 v42, 0x3a800000, v42
	v_mul_f32_e32 v43, 0x3a800000, v43
	v_mul_f32_e32 v44, 0x3a800000, v44
	v_mul_f32_e32 v45, 0x3a800000, v45
	v_sub_f32_e32 v108, v108, v42
	v_sub_f32_e32 v109, v109, v42
	v_sub_f32_e32 v110, v110, v42
	v_sub_f32_e32 v111, v111, v42
	v_mul_f32_e32 v46, v108, v108
	v_fmac_f32_e32 v46, v109, v109
	v_fmac_f32_e32 v46, v110, v110
	v_fmac_f32_e32 v46, v111, v111
	v_sub_f32_e32 v112, v112, v42
	v_sub_f32_e32 v113, v113, v42
	v_sub_f32_e32 v114, v114, v42
	v_sub_f32_e32 v115, v115, v42
	v_mul_f32_e32 v60, v112, v112
	v_fmac_f32_e32 v60, v113, v113
	v_fmac_f32_e32 v60, v114, v114
	v_fmac_f32_e32 v60, v115, v115
	v_add_f32_e32 v46, v46, v60
	v_sub_f32_e32 v116, v116, v42
	v_sub_f32_e32 v117, v117, v42
	v_sub_f32_e32 v118, v118, v42
	v_sub_f32_e32 v119, v119, v42
	v_mul_f32_e32 v60, v116, v116
	v_fmac_f32_e32 v60, v117, v117
	v_fmac_f32_e32 v60, v118, v118
	v_fmac_f32_e32 v60, v119, v119
	v_add_f32_e32 v46, v46, v60
	v_sub_f32_e32 v120, v120, v42
	v_sub_f32_e32 v121, v121, v42
	v_sub_f32_e32 v122, v122, v42
	v_sub_f32_e32 v123, v123, v42
	v_mul_f32_e32 v60, v120, v120
	v_fmac_f32_e32 v60, v121, v121
	v_fmac_f32_e32 v60, v122, v122
	v_fmac_f32_e32 v60, v123, v123
	v_add_f32_e32 v46, v46, v60
	v_sub_f32_e32 v124, v124, v43
	v_sub_f32_e32 v125, v125, v43
	v_sub_f32_e32 v126, v126, v43
	v_sub_f32_e32 v127, v127, v43
	v_mul_f32_e32 v48, v124, v124
	v_fmac_f32_e32 v48, v125, v125
	v_fmac_f32_e32 v48, v126, v126
	v_fmac_f32_e32 v48, v127, v127
	v_sub_f32_e32 v128, v128, v43
	v_sub_f32_e32 v129, v129, v43
	v_sub_f32_e32 v130, v130, v43
	v_sub_f32_e32 v131, v131, v43
	v_mul_f32_e32 v61, v128, v128
	v_fmac_f32_e32 v61, v129, v129
	v_fmac_f32_e32 v61, v130, v130
	v_fmac_f32_e32 v61, v131, v131
	v_add_f32_e32 v48, v48, v61
	v_sub_f32_e32 v132, v132, v43
	v_sub_f32_e32 v133, v133, v43
	v_sub_f32_e32 v134, v134, v43
	v_sub_f32_e32 v135, v135, v43
	v_mul_f32_e32 v61, v132, v132
	v_fmac_f32_e32 v61, v133, v133
	v_fmac_f32_e32 v61, v134, v134
	v_fmac_f32_e32 v61, v135, v135
	v_add_f32_e32 v48, v48, v61
	v_sub_f32_e32 v136, v136, v43
	v_sub_f32_e32 v137, v137, v43
	v_sub_f32_e32 v138, v138, v43
	v_sub_f32_e32 v139, v139, v43
	v_mul_f32_e32 v61, v136, v136
	v_fmac_f32_e32 v61, v137, v137
	v_fmac_f32_e32 v61, v138, v138
	v_fmac_f32_e32 v61, v139, v139
	v_add_f32_e32 v48, v48, v61
	v_sub_f32_e32 v140, v140, v44
	v_sub_f32_e32 v141, v141, v44
	v_sub_f32_e32 v142, v142, v44
	v_sub_f32_e32 v143, v143, v44
	v_mul_f32_e32 v50, v140, v140
	v_fmac_f32_e32 v50, v141, v141
	v_fmac_f32_e32 v50, v142, v142
	v_fmac_f32_e32 v50, v143, v143
	v_sub_f32_e32 v144, v144, v44
	v_sub_f32_e32 v145, v145, v44
	v_sub_f32_e32 v146, v146, v44
	v_sub_f32_e32 v147, v147, v44
	v_mul_f32_e32 v62, v144, v144
	v_fmac_f32_e32 v62, v145, v145
	v_fmac_f32_e32 v62, v146, v146
	v_fmac_f32_e32 v62, v147, v147
	v_add_f32_e32 v50, v50, v62
	v_sub_f32_e32 v148, v148, v44
	v_sub_f32_e32 v149, v149, v44
	v_sub_f32_e32 v150, v150, v44
	v_sub_f32_e32 v151, v151, v44
	v_mul_f32_e32 v62, v148, v148
	v_fmac_f32_e32 v62, v149, v149
	v_fmac_f32_e32 v62, v150, v150
	v_fmac_f32_e32 v62, v151, v151
	v_add_f32_e32 v50, v50, v62
	v_sub_f32_e32 v152, v152, v44
	v_sub_f32_e32 v153, v153, v44
	v_sub_f32_e32 v154, v154, v44
	v_sub_f32_e32 v155, v155, v44
	v_mul_f32_e32 v62, v152, v152
	v_fmac_f32_e32 v62, v153, v153
	v_fmac_f32_e32 v62, v154, v154
	v_fmac_f32_e32 v62, v155, v155
	v_add_f32_e32 v50, v50, v62
	v_sub_f32_e32 v156, v156, v45
	v_sub_f32_e32 v157, v157, v45
	v_sub_f32_e32 v158, v158, v45
	v_sub_f32_e32 v159, v159, v45
	v_mul_f32_e32 v52, v156, v156
	v_fmac_f32_e32 v52, v157, v157
	v_fmac_f32_e32 v52, v158, v158
	v_fmac_f32_e32 v52, v159, v159
	v_sub_f32_e32 v160, v160, v45
	v_sub_f32_e32 v161, v161, v45
	v_sub_f32_e32 v162, v162, v45
	v_sub_f32_e32 v163, v163, v45
	v_mul_f32_e32 v63, v160, v160
	v_fmac_f32_e32 v63, v161, v161
	v_fmac_f32_e32 v63, v162, v162
	v_fmac_f32_e32 v63, v163, v163
	v_add_f32_e32 v52, v52, v63
	v_sub_f32_e32 v164, v164, v45
	v_sub_f32_e32 v165, v165, v45
	v_sub_f32_e32 v166, v166, v45
	v_sub_f32_e32 v167, v167, v45
	v_mul_f32_e32 v63, v164, v164
	v_fmac_f32_e32 v63, v165, v165
	v_fmac_f32_e32 v63, v166, v166
	v_fmac_f32_e32 v63, v167, v167
	v_add_f32_e32 v52, v52, v63
	v_sub_f32_e32 v168, v168, v45
	v_sub_f32_e32 v169, v169, v45
	v_sub_f32_e32 v170, v170, v45
	v_sub_f32_e32 v171, v171, v45
	v_mul_f32_e32 v63, v168, v168
	v_fmac_f32_e32 v63, v169, v169
	v_fmac_f32_e32 v63, v170, v170
	v_fmac_f32_e32 v63, v171, v171
	v_add_f32_e32 v52, v52, v63
	ds_bpermute_b32 v60, v96, v46
	ds_bpermute_b32 v61, v96, v48
	ds_bpermute_b32 v62, v96, v50
	ds_bpermute_b32 v63, v96, v52
	s_waitcnt lgkmcnt(3)
	v_add_f32_e32 v46, v46, v60
	s_waitcnt lgkmcnt(2)
	v_add_f32_e32 v48, v48, v61
	s_waitcnt lgkmcnt(1)
	v_add_f32_e32 v50, v50, v62
	s_waitcnt lgkmcnt(0)
	v_add_f32_e32 v52, v52, v63
	ds_bpermute_b32 v60, v97, v46
	ds_bpermute_b32 v61, v97, v48
	ds_bpermute_b32 v62, v97, v50
	ds_bpermute_b32 v63, v97, v52
	s_waitcnt lgkmcnt(3)
	v_add_f32_e32 v46, v46, v60
	s_waitcnt lgkmcnt(2)
	v_add_f32_e32 v48, v48, v61
	s_waitcnt lgkmcnt(1)
	v_add_f32_e32 v50, v50, v62
	s_waitcnt lgkmcnt(0)
	v_add_f32_e32 v52, v52, v63
	ds_bpermute_b32 v60, v98, v46
	ds_bpermute_b32 v61, v98, v48
	ds_bpermute_b32 v62, v98, v50
	ds_bpermute_b32 v63, v98, v52
	s_waitcnt lgkmcnt(3)
	v_add_f32_e32 v46, v46, v60
	s_waitcnt lgkmcnt(2)
	v_add_f32_e32 v48, v48, v61
	s_waitcnt lgkmcnt(1)
	v_add_f32_e32 v50, v50, v62
	s_waitcnt lgkmcnt(0)
	v_add_f32_e32 v52, v52, v63
	ds_bpermute_b32 v60, v99, v46
	ds_bpermute_b32 v61, v99, v48
	ds_bpermute_b32 v62, v99, v50
	ds_bpermute_b32 v63, v99, v52
	s_waitcnt lgkmcnt(3)
; DEV void phase_ln(const Params& P, const float* __restrict__ g, const float* __restrict__ bta, u16* __restrict__ xb, bool zero_kc) {
;     ...
; #pragma unroll
;     for (int o = 32; o >= 1; o >>= 1) {
;       q[0] += __shfl_xor(q[0], o);
;       q[1] += __shfl_xor(q[1], o);
;     }
; #pragma unroll
;     for (int r = 0; r < 2; ++r) {
;       if (r == 1 && !hasB) break;
;       const float rs = rsqrtf(q[r] * (1.f / 1024.f) + 1e-5f);
;       const int rw = rows[r];
;       float* xr = P.out + (size_t)rw * D;
; #pragma unroll
;       for (int i = 0; i < 4; ++i) {
;         float4 y;
;         y.x = v[r][i].x * rs * gv[i].x + bv[i].x;
;         y.y = v[r][i].y * rs * gv[i].y + bv[i].y;
;         y.z = v[r][i].z * rs * gv[i].z + bv[i].z;
;         y.w = v[r][i].w * rs * gv[i].w + bv[i].w;
;         *(float4*)(xr + i * 256 + lane * 4) = y;
;         const int col = i * 256 + lane * 4;
;         *(uint2*)(xb + (size_t)(rw >> 8) * (256 * D) + (size_t)(col >> 5) * 8192 + (rw & 255) * 32 + (col & 31)) = make_uint2(pack2(y.x, y.y), pack2(y.z, y.w));
;       }
;     }
	v_add_f32_e32 v46, v46, v60
	s_waitcnt lgkmcnt(2)
	v_add_f32_e32 v48, v48, v61
	s_waitcnt lgkmcnt(1)
	v_add_f32_e32 v50, v50, v62
	s_waitcnt lgkmcnt(0)
	v_add_f32_e32 v52, v52, v63
	ds_bpermute_b32 v60, v100, v46
	ds_bpermute_b32 v61, v100, v48
	ds_bpermute_b32 v62, v100, v50
	ds_bpermute_b32 v63, v100, v52
	s_waitcnt lgkmcnt(3)
	v_add_f32_e32 v46, v46, v60
	s_waitcnt lgkmcnt(2)
	v_add_f32_e32 v48, v48, v61
	s_waitcnt lgkmcnt(1)
	v_add_f32_e32 v50, v50, v62
	s_waitcnt lgkmcnt(0)
	v_add_f32_e32 v52, v52, v63
	ds_bpermute_b32 v60, v101, v46
	ds_bpermute_b32 v61, v101, v48
	ds_bpermute_b32 v62, v101, v50
	ds_bpermute_b32 v63, v101, v52
	s_waitcnt lgkmcnt(3)
	v_add_f32_e32 v46, v46, v60
	s_waitcnt lgkmcnt(2)
	v_add_f32_e32 v48, v48, v61
	s_waitcnt lgkmcnt(1)
	v_add_f32_e32 v50, v50, v62
	s_waitcnt lgkmcnt(0)
	v_add_f32_e32 v52, v52, v63
	s_mov_b32 s2, 0x800000
	v_fmamk_f32 v46, v46, 0x3a800000, v216
	v_cmp_gt_f32_e32 vcc, s2, v46
	v_mul_f32_e32 v60, 0x4b800000, v46
	s_nop 1
	v_cndmask_b32_e32 v46, v46, v60, vcc
	v_rsq_f32_e32 v46, v46
	s_nop 0
	v_mul_f32_e32 v60, 0x45800000, v46
	s_nop 0
	v_cndmask_b32_e32 v46, v46, v60, vcc
	v_fmamk_f32 v48, v48, 0x3a800000, v216
	v_cmp_gt_f32_e32 vcc, s2, v48
	v_mul_f32_e32 v61, 0x4b800000, v48
	s_nop 1
	v_cndmask_b32_e32 v48, v48, v61, vcc
	v_rsq_f32_e32 v48, v48
	s_nop 0
	v_mul_f32_e32 v61, 0x45800000, v48
	s_nop 0
	v_cndmask_b32_e32 v48, v48, v61, vcc
	v_fmamk_f32 v50, v50, 0x3a800000, v216
	v_cmp_gt_f32_e32 vcc, s2, v50
	v_mul_f32_e32 v62, 0x4b800000, v50
	s_nop 1
	v_cndmask_b32_e32 v50, v50, v62, vcc
	v_rsq_f32_e32 v50, v50
	s_nop 0
	v_mul_f32_e32 v62, 0x45800000, v50
	s_nop 0
	v_cndmask_b32_e32 v50, v50, v62, vcc
	v_fmamk_f32 v52, v52, 0x3a800000, v216
	v_cmp_gt_f32_e32 vcc, s2, v52
	v_mul_f32_e32 v63, 0x4b800000, v52
	s_nop 1
	v_cndmask_b32_e32 v52, v52, v63, vcc
	v_rsq_f32_e32 v52, v52
	s_nop 0
	v_mul_f32_e32 v63, 0x45800000, v52
	s_nop 0
	v_cndmask_b32_e32 v52, v52, v63, vcc
	s_add_i32 s9, s4, 0
	s_cmp_lt_i32 s9, 0x8000
	s_cbranch_scc0 .Lln_skip_1_0
	s_lshr_b32 s8, s9, 8
	s_lshl_b32 s8, s8, 19
	s_and_b32 s2, s9, 0xff
	s_lshl_b32 s2, s2, 6
	s_add_i32 s8, s8, s2
	v_pk_mul_f32 v[64:65], v[108:109], v[46:47] op_sel_hi:[1,0]
	v_pk_mul_f32 v[66:67], v[110:111], v[46:47] op_sel_hi:[1,0]
	v_pk_fma_f32 v[64:65], v[2:3], v[64:65], v[6:7]
	v_pk_fma_f32 v[66:67], v[4:5], v[66:67], v[8:9]
	global_store_dwordx4 v72, v[64:67], s[86:87]
	v_add_u32_e32 v70, s8, v36
	v_cvt_pk_bf16_f32 v68, v64, v65
	v_cvt_pk_bf16_f32 v69, v66, v67
	global_store_dwordx2 v70, v[68:69], s[42:43]
	v_pk_mul_f32 v[64:65], v[112:113], v[46:47] op_sel_hi:[1,0]
	v_pk_mul_f32 v[66:67], v[114:115], v[46:47] op_sel_hi:[1,0]
	v_pk_fma_f32 v[64:65], v[10:11], v[64:65], v[18:19]
	v_pk_fma_f32 v[66:67], v[12:13], v[66:67], v[20:21]
	global_store_dwordx4 v72, v[64:67], s[86:87] offset:1024
	v_add_u32_e32 v70, s8, v37
	v_cvt_pk_bf16_f32 v68, v64, v65
	v_cvt_pk_bf16_f32 v69, v66, v67
	global_store_dwordx2 v70, v[68:69], s[42:43]
	v_pk_mul_f32 v[64:65], v[116:117], v[46:47] op_sel_hi:[1,0]
	v_pk_mul_f32 v[66:67], v[118:119], v[46:47] op_sel_hi:[1,0]
	v_pk_fma_f32 v[64:65], v[14:15], v[64:65], v[22:23]
	v_pk_fma_f32 v[66:67], v[16:17], v[66:67], v[24:25]
	global_store_dwordx4 v72, v[64:67], s[86:87] offset:2048
	v_add_u32_e32 v70, s8, v38
	v_cvt_pk_bf16_f32 v68, v64, v65
	v_cvt_pk_bf16_f32 v69, v66, v67
	global_store_dwordx2 v70, v[68:69], s[42:43]
	v_pk_mul_f32 v[64:65], v[120:121], v[46:47] op_sel_hi:[1,0]
	v_pk_mul_f32 v[66:67], v[122:123], v[46:47] op_sel_hi:[1,0]
	v_pk_fma_f32 v[64:65], v[26:27], v[64:65], v[30:31]
	v_pk_fma_f32 v[66:67], v[28:29], v[66:67], v[32:33]
	global_store_dwordx4 v72, v[64:67], s[86:87] offset:3072
	v_add_u32_e32 v70, s8, v39
	v_cvt_pk_bf16_f32 v68, v64, v65
	v_cvt_pk_bf16_f32 v69, v66, v67
	global_store_dwordx2 v70, v[68:69], s[42:43]
.Lln_skip_1_0:
	s_add_i32 s9, s4, 1
	s_cmp_lt_i32 s9, 0x8000
	s_cbranch_scc0 .Lln_skip_1_1
	s_lshr_b32 s8, s9, 8
	s_lshl_b32 s8, s8, 19
	s_and_b32 s2, s9, 0xff
	s_lshl_b32 s2, s2, 6
	s_add_i32 s8, s8, s2
	v_pk_mul_f32 v[64:65], v[124:125], v[48:49] op_sel_hi:[1,0]
	v_pk_mul_f32 v[66:67], v[126:127], v[48:49] op_sel_hi:[1,0]
	v_pk_fma_f32 v[64:65], v[2:3], v[64:65], v[6:7]
	v_pk_fma_f32 v[66:67], v[4:5], v[66:67], v[8:9]
	global_store_dwordx4 v73, v[64:67], s[86:87]
	v_add_u32_e32 v70, s8, v36
	v_cvt_pk_bf16_f32 v68, v64, v65
	v_cvt_pk_bf16_f32 v69, v66, v67
	global_store_dwordx2 v70, v[68:69], s[42:43]
	v_pk_mul_f32 v[64:65], v[128:129], v[48:49] op_sel_hi:[1,0]
	v_pk_mul_f32 v[66:67], v[130:131], v[48:49] op_sel_hi:[1,0]
	v_pk_fma_f32 v[64:65], v[10:11], v[64:65], v[18:19]
	v_pk_fma_f32 v[66:67], v[12:13], v[66:67], v[20:21]
	global_store_dwordx4 v73, v[64:67], s[86:87] offset:1024
	v_add_u32_e32 v70, s8, v37
	v_cvt_pk_bf16_f32 v68, v64, v65
	v_cvt_pk_bf16_f32 v69, v66, v67
	global_store_dwordx2 v70, v[68:69], s[42:43]
	v_pk_mul_f32 v[64:65], v[132:133], v[48:49] op_sel_hi:[1,0]
	v_pk_mul_f32 v[66:67], v[134:135], v[48:49] op_sel_hi:[1,0]
	v_pk_fma_f32 v[64:65], v[14:15], v[64:65], v[22:23]
	v_pk_fma_f32 v[66:67], v[16:17], v[66:67], v[24:25]
	global_store_dwordx4 v73, v[64:67], s[86:87] offset:2048
	v_add_u32_e32 v70, s8, v38
	v_cvt_pk_bf16_f32 v68, v64, v65
	v_cvt_pk_bf16_f32 v69, v66, v67
	global_store_dwordx2 v70, v[68:69], s[42:43]
	v_pk_mul_f32 v[64:65], v[136:137], v[48:49] op_sel_hi:[1,0]
	v_pk_mul_f32 v[66:67], v[138:139], v[48:49] op_sel_hi:[1,0]
	v_pk_fma_f32 v[64:65], v[26:27], v[64:65], v[30:31]
	v_pk_fma_f32 v[66:67], v[28:29], v[66:67], v[32:33]
	global_store_dwordx4 v73, v[64:67], s[86:87] offset:3072
	v_add_u32_e32 v70, s8, v39
	v_cvt_pk_bf16_f32 v68, v64, v65
	v_cvt_pk_bf16_f32 v69, v66, v67
	global_store_dwordx2 v70, v[68:69], s[42:43]
; DEV void phase_ln(const Params& P, const float* __restrict__ g, const float* __restrict__ bta, u16* __restrict__ xb, bool zero_kc) {
;     ...
; #pragma unroll
;     for (int r = 0; r < 2; ++r) {
;       if (r == 1 && !hasB) break;
;       const float rs = rsqrtf(q[r] * (1.f / 1024.f) + 1e-5f);
;       const int rw = rows[r];
;       float* xr = P.out + (size_t)rw * D;
; #pragma unroll
;       for (int i = 0; i < 4; ++i) {
;         float4 y;
;         y.x = v[r][i].x * rs * gv[i].x + bv[i].x;
;         y.y = v[r][i].y * rs * gv[i].y + bv[i].y;
;         y.z = v[r][i].z * rs * gv[i].z + bv[i].z;
;         y.w = v[r][i].w * rs * gv[i].w + bv[i].w;
;         *(float4*)(xr + i * 256 + lane * 4) = y;
;         const int col = i * 256 + lane * 4;
;         *(uint2*)(xb + (size_t)(rw >> 8) * (256 * D) + (size_t)(col >> 5) * 8192 + (rw & 255) * 32 + (col & 31)) = make_uint2(pack2(y.x, y.y), pack2(y.z, y.w));
;       }
;     }
.Lln_skip_1_1:
	s_add_i32 s9, s4, 2
	s_cmp_lt_i32 s9, 0x8000
	s_cbranch_scc0 .Lln_skip_1_2
	s_lshr_b32 s8, s9, 8
	s_lshl_b32 s8, s8, 19
	s_and_b32 s2, s9, 0xff
	s_lshl_b32 s2, s2, 6
	s_add_i32 s8, s8, s2
	v_pk_mul_f32 v[64:65], v[140:141], v[50:51] op_sel_hi:[1,0]
	v_pk_mul_f32 v[66:67], v[142:143], v[50:51] op_sel_hi:[1,0]
	v_pk_fma_f32 v[64:65], v[2:3], v[64:65], v[6:7]
	v_pk_fma_f32 v[66:67], v[4:5], v[66:67], v[8:9]
	global_store_dwordx4 v74, v[64:67], s[86:87]
	v_add_u32_e32 v70, s8, v36
	v_cvt_pk_bf16_f32 v68, v64, v65
	v_cvt_pk_bf16_f32 v69, v66, v67
	global_store_dwordx2 v70, v[68:69], s[42:43]
	v_pk_mul_f32 v[64:65], v[144:145], v[50:51] op_sel_hi:[1,0]
	v_pk_mul_f32 v[66:67], v[146:147], v[50:51] op_sel_hi:[1,0]
	v_pk_fma_f32 v[64:65], v[10:11], v[64:65], v[18:19]
	v_pk_fma_f32 v[66:67], v[12:13], v[66:67], v[20:21]
	global_store_dwordx4 v74, v[64:67], s[86:87] offset:1024
	v_add_u32_e32 v70, s8, v37
	v_cvt_pk_bf16_f32 v68, v64, v65
	v_cvt_pk_bf16_f32 v69, v66, v67
	global_store_dwordx2 v70, v[68:69], s[42:43]
	v_pk_mul_f32 v[64:65], v[148:149], v[50:51] op_sel_hi:[1,0]
	v_pk_mul_f32 v[66:67], v[150:151], v[50:51] op_sel_hi:[1,0]
	v_pk_fma_f32 v[64:65], v[14:15], v[64:65], v[22:23]
	v_pk_fma_f32 v[66:67], v[16:17], v[66:67], v[24:25]
	global_store_dwordx4 v74, v[64:67], s[86:87] offset:2048
	v_add_u32_e32 v70, s8, v38
	v_cvt_pk_bf16_f32 v68, v64, v65
	v_cvt_pk_bf16_f32 v69, v66, v67
	global_store_dwordx2 v70, v[68:69], s[42:43]
	v_pk_mul_f32 v[64:65], v[152:153], v[50:51] op_sel_hi:[1,0]
	v_pk_mul_f32 v[66:67], v[154:155], v[50:51] op_sel_hi:[1,0]
	v_pk_fma_f32 v[64:65], v[26:27], v[64:65], v[30:31]
	v_pk_fma_f32 v[66:67], v[28:29], v[66:67], v[32:33]
	global_store_dwordx4 v74, v[64:67], s[86:87] offset:3072
	v_add_u32_e32 v70, s8, v39
	v_cvt_pk_bf16_f32 v68, v64, v65
	v_cvt_pk_bf16_f32 v69, v66, v67
	global_store_dwordx2 v70, v[68:69], s[42:43]
.Lln_skip_1_2:
	s_add_i32 s9, s4, 3
	s_cmp_lt_i32 s9, 0x8000
	s_cbranch_scc0 .Lln_skip_1_3
	s_lshr_b32 s8, s9, 8
	s_lshl_b32 s8, s8, 19
	s_and_b32 s2, s9, 0xff
	s_lshl_b32 s2, s2, 6
	s_add_i32 s8, s8, s2
	v_pk_mul_f32 v[64:65], v[156:157], v[52:53] op_sel_hi:[1,0]
	v_pk_mul_f32 v[66:67], v[158:159], v[52:53] op_sel_hi:[1,0]
	v_pk_fma_f32 v[64:65], v[2:3], v[64:65], v[6:7]
	v_pk_fma_f32 v[66:67], v[4:5], v[66:67], v[8:9]
	global_store_dwordx4 v75, v[64:67], s[86:87]
	v_add_u32_e32 v70, s8, v36
	v_cvt_pk_bf16_f32 v68, v64, v65
	v_cvt_pk_bf16_f32 v69, v66, v67
	global_store_dwordx2 v70, v[68:69], s[42:43]
	v_pk_mul_f32 v[64:65], v[160:161], v[52:53] op_sel_hi:[1,0]
	v_pk_mul_f32 v[66:67], v[162:163], v[52:53] op_sel_hi:[1,0]
	v_pk_fma_f32 v[64:65], v[10:11], v[64:65], v[18:19]
	v_pk_fma_f32 v[66:67], v[12:13], v[66:67], v[20:21]
	global_store_dwordx4 v75, v[64:67], s[86:87] offset:1024
	v_add_u32_e32 v70, s8, v37
	v_cvt_pk_bf16_f32 v68, v64, v65
	v_cvt_pk_bf16_f32 v69, v66, v67
	global_store_dwordx2 v70, v[68:69], s[42:43]
	v_pk_mul_f32 v[64:65], v[164:165], v[52:53] op_sel_hi:[1,0]
	v_pk_mul_f32 v[66:67], v[166:167], v[52:53] op_sel_hi:[1,0]
	v_pk_fma_f32 v[64:65], v[14:15], v[64:65], v[22:23]
	v_pk_fma_f32 v[66:67], v[16:17], v[66:67], v[24:25]
	global_store_dwordx4 v75, v[64:67], s[86:87] offset:2048
	v_add_u32_e32 v70, s8, v38
	v_cvt_pk_bf16_f32 v68, v64, v65
	v_cvt_pk_bf16_f32 v69, v66, v67
	global_store_dwordx2 v70, v[68:69], s[42:43]
	v_pk_mul_f32 v[64:65], v[168:169], v[52:53] op_sel_hi:[1,0]
	v_pk_mul_f32 v[66:67], v[170:171], v[52:53] op_sel_hi:[1,0]
	v_pk_fma_f32 v[64:65], v[26:27], v[64:65], v[30:31]
	v_pk_fma_f32 v[66:67], v[28:29], v[66:67], v[32:33]
	global_store_dwordx4 v75, v[64:67], s[86:87] offset:3072
	v_add_u32_e32 v70, s8, v39
	v_cvt_pk_bf16_f32 v68, v64, v65
	v_cvt_pk_bf16_f32 v69, v66, v67
	global_store_dwordx2 v70, v[68:69], s[42:43]
.Lln_skip_1_3:
	s_add_i32 s4, s4, s5
	s_cmp_lt_i32 s4, 0x8000
	s_cbranch_scc1 .Lln_loop_1
	s_branch .LBB0_98

; DEV int otid() { int t = threadIdx.x; asm volatile("" : "+v"(t)); return t; }
; template <class MaskFn>
; DEV void attn_tile64(AttnAcc& st, const bf16x8 (&qf)[2], const char* smem, MaskFn mask) {
;   const int lane = otid() & 63, l15 = lane & 15, quad = lane >> 4;
;   f32x4 s[4];
; #pragma unroll
;   for (int sub = 0; sub < 4; ++sub) {
;     f32x4 a = {0.f, 0.f, 0.f, 0.f};
; #pragma unroll
;     for (int ks2 = 0; ks2 < 2; ++ks2) {
;       bf16x8 kf = *(const bf16x8*)(smem + K64_SK + (sub * 16 + l15) * KSTR + (ks2 * 4 + quad) * 16);
;       a = __builtin_amdgcn_mfma_f32_16x16x32_bf16(kf, qf[ks2], a, 0, 0, 0);
;     }
;     s[sub] = a * 0.125f;
;   }
;   float lmx = -1e30f;
; #pragma unroll
;   for (int sub = 0; sub < 4; ++sub)
; #pragma unroll
;     for (int j = 0; j < 4; ++j) {
;       bool ok = mask(sub * 16 + quad * 4 + j);
;       float v = ok ? s[sub][j] : -1e30f;
;       s[sub][j] = v;
;       lmx = fmaxf(lmx, v);
;     }
;   if (__any(lmx > st.m + 8.0f)) {
;     float mx = fmaxf(st.m, lmx);
;     mx = fmaxf(mx, __shfl_xor(mx, 16));
;     mx = fmaxf(mx, __shfl_xor(mx, 32));
;     const float alpha = __expf(st.m - mx);
;     st.l *= alpha;
;     st.m = mx;
; #pragma unroll
;     for (int dt = 0; dt < 4; ++dt) st.o[dt] = st.o[dt] * alpha;
;   }
.LBB0_399:
	s_lshl_b64 s[4:5], 1, s8
	v_and_b32_e32 v3, s5, v87
	v_and_b32_e32 v2, s4, v86
	v_cmp_ne_u64_e32 vcc, 0, v[2:3]
	s_waitcnt lgkmcnt(0)
	s_barrier
	s_cbranch_vccz .LBB0_403
	v_mov_b32_e32 v2, v210
	s_lshl_b32 s4, s8, 6
	v_and_b32_e32 v0, 15, v2
	v_bfe_u32 v2, v2, 4, 2
	v_mul_u32_u24_e32 v3, 0x90, v0
	v_lshl_add_u32 v3, v2, 4, v3
	ds_read_b128 v[122:125], v3
	ds_read_b128 v[126:129], v3 offset:2304
	ds_read_b128 v[130:133], v3 offset:4608
	ds_read_b128 v[134:137], v3 offset:6912
	ds_read_b128 v[138:141], v3 offset:64
	ds_read_b128 v[142:145], v3 offset:2368
	ds_read_b128 v[146:149], v3 offset:4672
	ds_read_b128 v[150:153], v3 offset:6976
	v_mul_u32_u24_e32 v166, 0x88, v0
	v_lshl_add_u32 v166, v2, 3, v166
	v_add_u32_e32 v167, 0x2800, v166
	v_add_u32_e32 v168, 0x3000, v166
	v_add_u32_e32 v169, 0x3800, v166
	v_add_u32_e32 v166, 0x2000, v166
	s_waitcnt lgkmcnt(7)
	v_mfma_f32_16x16x32_bf16 v[154:157], v[122:125], v[20:23], 0
	s_waitcnt lgkmcnt(6)
	v_mfma_f32_16x16x32_bf16 v[158:161], v[126:129], v[20:23], 0
	s_waitcnt lgkmcnt(5)
	v_mfma_f32_16x16x32_bf16 v[162:165], v[130:133], v[20:23], 0
	s_waitcnt lgkmcnt(4)
	v_mfma_f32_16x16x32_bf16 v[28:31], v[134:137], v[20:23], 0
	s_waitcnt lgkmcnt(3)
	v_mfma_f32_16x16x32_bf16 v[154:157], v[138:141], v[24:27], v[154:157]
	s_waitcnt lgkmcnt(2)
	v_mfma_f32_16x16x32_bf16 v[158:161], v[142:145], v[24:27], v[158:161]
	s_waitcnt lgkmcnt(1)
	v_mfma_f32_16x16x32_bf16 v[162:165], v[146:149], v[24:27], v[162:165]
	s_waitcnt lgkmcnt(0)
	v_mfma_f32_16x16x32_bf16 v[28:31], v[150:153], v[24:27], v[28:31]
	ds_read2_b64 v[122:125], v166 offset0:128 offset1:132
	ds_read2_b64 v[126:129], v166 offset0:136 offset1:140
	ds_read2_b64 v[130:133], v167 offset0:144 offset1:148
	ds_read2_b64 v[134:137], v167 offset0:152 offset1:156
	ds_read2_b64 v[138:141], v168 offset0:160 offset1:164
	ds_read2_b64 v[142:145], v168 offset0:168 offset1:172
	ds_read2_b64 v[146:149], v169 offset0:176 offset1:180
	ds_read2_b64 v[150:153], v169 offset0:184 offset1:188
	v_pk_mul_f32 v[36:37], v[156:157], s[90:91] op_sel_hi:[1,0]
	v_pk_mul_f32 v[38:39], v[154:155], s[90:91] op_sel_hi:[1,0]
	v_pk_mul_f32 v[94:95], v[160:161], s[90:91] op_sel_hi:[1,0]
	v_pk_mul_f32 v[96:97], v[158:159], s[90:91] op_sel_hi:[1,0]
	v_pk_mul_f32 v[98:99], v[164:165], s[90:91] op_sel_hi:[1,0]
	v_pk_mul_f32 v[100:101], v[162:163], s[90:91] op_sel_hi:[1,0]
	v_pk_mul_f32 v[102:103], v[30:31], s[90:91] op_sel_hi:[1,0]
	v_lshl_or_b32 v3, v2, 2, s4
	v_cmp_le_i32_e64 s[8:9], v3, v76
	s_and_b64 s[8:9], vcc, s[8:9]
	v_cndmask_b32_e64 v42, v221, v38, s[8:9]
	v_cmp_lt_i32_e64 s[8:9], v3, v76
	s_and_b64 s[8:9], vcc, s[8:9]
	s_mov_b32 s4, 0xf149f2ca
	v_cndmask_b32_e64 v41, v221, v39, s[8:9]
	v_or_b32_e32 v31, 2, v3
	v_cmp_le_i32_e64 s[8:9], v31, v76
	s_and_b64 s[8:9], vcc, s[8:9]
	v_or_b32_e32 v31, 3, v3
	v_cndmask_b32_e64 v40, v221, v36, s[8:9]
	v_cmp_le_i32_e64 s[8:9], v31, v76
	s_and_b64 s[8:9], vcc, s[8:9]
	v_or_b32_e32 v31, 16, v3
	v_cndmask_b32_e64 v39, v221, v37, s[8:9]
	v_cmp_le_i32_e64 s[8:9], v31, v76
	s_and_b64 s[8:9], vcc, s[8:9]
	v_or_b32_e32 v31, 17, v3
	v_cndmask_b32_e64 v38, v221, v96, s[8:9]
	v_cmp_le_i32_e64 s[8:9], v31, v76
	s_and_b64 s[8:9], vcc, s[8:9]
	v_or_b32_e32 v31, 18, v3
	v_cndmask_b32_e64 v37, v221, v97, s[8:9]
	v_cmp_le_i32_e64 s[8:9], v31, v76
	s_and_b64 s[8:9], vcc, s[8:9]
	v_or_b32_e32 v31, 19, v3
	v_cndmask_b32_e64 v36, v221, v94, s[8:9]
	v_cmp_le_i32_e64 s[8:9], v31, v76
	s_and_b64 s[8:9], vcc, s[8:9]
	v_or_b32_e32 v31, 32, v3
	v_cndmask_b32_e64 v35, v221, v95, s[8:9]
	v_cmp_le_i32_e64 s[8:9], v31, v76
	s_and_b64 s[8:9], vcc, s[8:9]
	v_or_b32_e32 v31, 33, v3
	v_cndmask_b32_e64 v34, v221, v100, s[8:9]
	v_cmp_le_i32_e64 s[8:9], v31, v76
	s_and_b64 s[8:9], vcc, s[8:9]
	v_or_b32_e32 v31, 34, v3
	v_max3_f32 v30, v42, s4, v41
	v_cndmask_b32_e64 v33, v221, v101, s[8:9]
	v_cmp_le_i32_e64 s[8:9], v31, v76
	v_max3_f32 v30, v30, v40, v39
	s_and_b64 s[8:9], vcc, s[8:9]
	v_or_b32_e32 v31, 35, v3
	v_max3_f32 v30, v30, v38, v37
	v_cndmask_b32_e64 v32, v221, v98, s[8:9]
	v_cmp_le_i32_e64 s[8:9], v31, v76
	v_max3_f32 v30, v30, v36, v35
	s_and_b64 s[8:9], vcc, s[8:9]
	v_max3_f32 v30, v30, v34, v33
	v_cndmask_b32_e64 v31, v221, v99, s[8:9]
	v_max3_f32 v43, v30, v32, v31
	v_or_b32_e32 v30, 48, v3
	v_cmp_le_i32_e64 s[8:9], v30, v76
	v_pk_mul_f32 v[28:29], v[28:29], s[90:91] op_sel_hi:[1,0]
	s_and_b64 s[8:9], vcc, s[8:9]
	v_cndmask_b32_e64 v30, v221, v28, s[8:9]
	v_or_b32_e32 v28, 49, v3
	v_cmp_le_i32_e64 s[8:9], v28, v76
	s_and_b64 s[8:9], vcc, s[8:9]
	v_or_b32_e32 v28, 50, v3
	v_cndmask_b32_e64 v29, v221, v29, s[8:9]
	v_cmp_le_i32_e64 s[8:9], v28, v76
	s_and_b64 s[8:9], vcc, s[8:9]
	v_or_b32_e32 v3, 51, v3
	v_cndmask_b32_e64 v28, v221, v102, s[8:9]
	v_cmp_le_i32_e64 s[8:9], v3, v76
	s_and_b64 vcc, vcc, s[8:9]
	v_max3_f32 v43, v43, v30, v29
	v_cndmask_b32_e32 v3, v221, v103, vcc
	v_max3_f32 v43, v43, v28, v3
	v_add_f32_e32 v94, 0x41000000, v93
	v_cmp_gt_f32_e32 vcc, v43, v94
	s_cbranch_vccz .LBB0_402
	v_max_f32_e32 v43, v43, v43
	v_max_f32_e32 v94, v93, v93
	v_max_f32_e32 v43, v94, v43
	ds_bpermute_b32 v94, v77, v43
	s_waitcnt lgkmcnt(0)
	v_max_f32_e32 v94, v94, v94
	v_max_f32_e32 v43, v43, v94
	ds_bpermute_b32 v94, v89, v43
	s_waitcnt lgkmcnt(0)
	v_max_f32_e32 v94, v94, v94
	v_max_f32_e32 v43, v43, v94
	v_sub_f32_e32 v93, v93, v43
	v_mul_f32_e32 v93, 0x3fb8aa3b, v93
	v_exp_f32_e32 v94, v93
	v_mov_b32_e32 v93, v43
	v_mul_f32_e32 v92, v92, v94
	v_pk_mul_f32 v[74:75], v[74:75], v[94:95] op_sel_hi:[1,0]
	v_pk_mul_f32 v[72:73], v[72:73], v[94:95] op_sel_hi:[1,0]
	v_pk_mul_f32 v[70:71], v[70:71], v[94:95] op_sel_hi:[1,0]
	v_pk_mul_f32 v[68:69], v[68:69], v[94:95] op_sel_hi:[1,0]
	v_pk_mul_f32 v[66:67], v[66:67], v[94:95] op_sel_hi:[1,0]
	v_pk_mul_f32 v[64:65], v[64:65], v[94:95] op_sel_hi:[1,0]
	v_pk_mul_f32 v[62:63], v[62:63], v[94:95] op_sel_hi:[1,0]
	v_pk_mul_f32 v[60:61], v[60:61], v[94:95] op_sel_hi:[1,0]
; template <class MaskFn>
; DEV void attn_tile64(AttnAcc& st, const bf16x8 (&qf)[2], const char* smem, MaskFn mask) {
;     ...
;   const float mref = st.m;
;   float ps = 0.f;
; #pragma unroll
;   for (int sub = 0; sub < 4; ++sub)
; #pragma unroll
;     for (int j = 0; j < 4; ++j) {
;       float pv = (s[sub][j] > -1e29f) ? __expf(s[sub][j] - mref) : 0.f;
;       s[sub][j] = pv;
;       ps += pv;
;     }
;   st.l += ps;
;   union { bf16x8 v; unsigned u[4]; } pf0, pf1;
;   pf0.u[0] = pack2(s[0][0], s[0][1]); pf0.u[1] = pack2(s[0][2], s[0][3]);
;   pf0.u[2] = pack2(s[1][0], s[1][1]); pf0.u[3] = pack2(s[1][2], s[1][3]);
;   pf1.u[0] = pack2(s[2][0], s[2][1]); pf1.u[1] = pack2(s[2][2], s[2][3]);
;   pf1.u[2] = pack2(s[3][0], s[3][1]); pf1.u[3] = pack2(s[3][2], s[3][3]);
; #pragma unroll
;   for (int dt = 0; dt < 4; ++dt) {
;     const char* vrow = smem + K64_VT + (dt * 16 + l15) * 136;
;     uint2 lo = *(const uint2*)(vrow + quad * 8);
;     uint2 hi = *(const uint2*)(vrow + 32 + quad * 8);
;     union { bf16x8 v; unsigned u[4]; } vf;
;     vf.u[0] = lo.x; vf.u[1] = lo.y; vf.u[2] = hi.x; vf.u[3] = hi.y;
;     st.o[dt] = __builtin_amdgcn_mfma_f32_16x16x32_bf16(vf.v, pf0.v, st.o[dt], 0, 0, 0);
;     lo = *(const uint2*)(vrow + 64 + quad * 8);
;     hi = *(const uint2*)(vrow + 96 + quad * 8);
;     vf.u[0] = lo.x; vf.u[1] = lo.y; vf.u[2] = hi.x; vf.u[3] = hi.y;
;     st.o[dt] = __builtin_amdgcn_mfma_f32_16x16x32_bf16(vf.v, pf1.v, st.o[dt], 0, 0, 0);
;   }
.LBB0_402:
	v_cmp_lt_f32_e32 vcc, s6, v42
	v_sub_f32_e32 v42, v42, v93
	v_mul_f32_e32 v42, 0x3fb8aa3b, v42
	v_exp_f32_e32 v42, v42
	v_lshlrev_b32_e32 v2, 3, v2
	s_movk_i32 s4, 0x88
	v_mad_u32_u24 v0, v0, s4, v2
	v_cndmask_b32_e32 v42, 0, v42, vcc
	v_cmp_lt_f32_e32 vcc, s6, v41
	v_sub_f32_e32 v41, v41, v93
	v_mul_f32_e32 v41, 0x3fb8aa3b, v41
	v_exp_f32_e32 v41, v41
	v_add_f32_e32 v43, 0, v42
	v_add_u32_e32 v2, 0x2000, v0
	v_cndmask_b32_e32 v41, 0, v41, vcc
	v_cmp_lt_f32_e32 vcc, s6, v40
	v_sub_f32_e32 v40, v40, v93
	v_mul_f32_e32 v40, 0x3fb8aa3b, v40
	v_exp_f32_e32 v40, v40
	v_add_f32_e32 v43, v41, v43
	v_cndmask_b32_e32 v94, 0, v40, vcc
	v_cmp_lt_f32_e32 vcc, s6, v39
	v_sub_f32_e32 v39, v39, v93
	v_mul_f32_e32 v39, 0x3fb8aa3b, v39
	v_exp_f32_e32 v39, v39
	v_add_f32_e32 v40, v94, v43
	v_cndmask_b32_e32 v39, 0, v39, vcc
	v_cmp_lt_f32_e32 vcc, s6, v38
	v_sub_f32_e32 v38, v38, v93
	v_mul_f32_e32 v38, 0x3fb8aa3b, v38
	v_exp_f32_e32 v38, v38
	v_add_f32_e32 v40, v39, v40
	v_cndmask_b32_e32 v38, 0, v38, vcc
	v_cmp_lt_f32_e32 vcc, s6, v37
	v_sub_f32_e32 v37, v37, v93
	v_mul_f32_e32 v37, 0x3fb8aa3b, v37
	v_exp_f32_e32 v37, v37
	v_add_f32_e32 v40, v38, v40
	v_cndmask_b32_e32 v37, 0, v37, vcc
	v_cmp_lt_f32_e32 vcc, s6, v36
	v_sub_f32_e32 v36, v36, v93
	v_mul_f32_e32 v36, 0x3fb8aa3b, v36
	v_exp_f32_e32 v36, v36
	v_add_f32_e32 v40, v37, v40
	v_cndmask_b32_e32 v36, 0, v36, vcc
	v_cmp_lt_f32_e32 vcc, s6, v35
	v_sub_f32_e32 v35, v35, v93
	v_mul_f32_e32 v35, 0x3fb8aa3b, v35
	v_exp_f32_e32 v35, v35
	v_add_f32_e32 v40, v36, v40
	v_cndmask_b32_e32 v35, 0, v35, vcc
	v_cmp_lt_f32_e32 vcc, s6, v34
	v_sub_f32_e32 v34, v34, v93
	v_mul_f32_e32 v34, 0x3fb8aa3b, v34
	v_exp_f32_e32 v34, v34
	v_add_f32_e32 v40, v35, v40
	v_cvt_pk_bf16_f32 v43, v36, v35
	v_cndmask_b32_e32 v34, 0, v34, vcc
	v_cmp_lt_f32_e32 vcc, s6, v33
	v_sub_f32_e32 v33, v33, v93
	v_mul_f32_e32 v33, 0x3fb8aa3b, v33
	v_exp_f32_e32 v33, v33
	v_add_f32_e32 v40, v34, v40
	v_cndmask_b32_e32 v33, 0, v33, vcc
	v_cmp_lt_f32_e32 vcc, s6, v32
	v_sub_f32_e32 v32, v32, v93
	v_mul_f32_e32 v32, 0x3fb8aa3b, v32
	v_exp_f32_e32 v32, v32
	v_add_f32_e32 v40, v33, v40
	v_cndmask_b32_e32 v32, 0, v32, vcc
	v_cmp_lt_f32_e32 vcc, s6, v31
	v_sub_f32_e32 v31, v31, v93
	v_mul_f32_e32 v31, 0x3fb8aa3b, v31
	v_exp_f32_e32 v31, v31
	v_add_f32_e32 v40, v32, v40
	v_cndmask_b32_e32 v31, 0, v31, vcc
	v_cmp_lt_f32_e32 vcc, s6, v30
	v_sub_f32_e32 v30, v30, v93
	v_mul_f32_e32 v30, 0x3fb8aa3b, v30
	v_exp_f32_e32 v30, v30
	v_add_f32_e32 v40, v31, v40
	v_cvt_pk_bf16_f32 v95, v32, v31
	v_cndmask_b32_e32 v30, 0, v30, vcc
	v_cmp_lt_f32_e32 vcc, s6, v29
	v_sub_f32_e32 v29, v29, v93
	v_mul_f32_e32 v29, 0x3fb8aa3b, v29
	v_exp_f32_e32 v29, v29
	v_add_f32_e32 v40, v30, v40
	v_cndmask_b32_e32 v29, 0, v29, vcc
	v_cmp_lt_f32_e32 vcc, s6, v28
	v_sub_f32_e32 v28, v28, v93
	v_mul_f32_e32 v28, 0x3fb8aa3b, v28
	v_exp_f32_e32 v28, v28
	v_add_f32_e32 v40, v29, v40
	v_cvt_pk_bf16_f32 v96, v30, v29
	v_cndmask_b32_e32 v28, 0, v28, vcc
	v_cmp_lt_f32_e32 vcc, s6, v3
	v_sub_f32_e32 v3, v3, v93
	v_mul_f32_e32 v3, 0x3fb8aa3b, v3
	v_exp_f32_e32 v3, v3
	v_add_f32_e32 v40, v28, v40
	v_cndmask_b32_e32 v3, 0, v3, vcc
	v_cvt_pk_bf16_f32 v97, v28, v3
	v_add_f32_e32 v40, v3, v40
	v_add_f32_e32 v92, v92, v40
	v_cvt_pk_bf16_f32 v40, v42, v41
	v_cvt_pk_bf16_f32 v41, v94, v39
	v_cvt_pk_bf16_f32 v94, v34, v33
	v_cvt_pk_bf16_f32 v42, v38, v37
	v_add_u32_e32 v2, 0x2800, v0
	s_waitcnt lgkmcnt(2)
	v_mfma_f32_16x16x32_bf16 v[28:31], v[122:125], v[40:43], v[72:75]
	s_waitcnt lgkmcnt(1)
	v_mfma_f32_16x16x32_bf16 v[28:31], v[126:129], v[94:97], v[28:31]
	v_add_u32_e32 v2, 0x3000, v0
	v_add_u32_e32 v0, 0x3800, v0
	s_waitcnt lgkmcnt(0)
	v_mfma_f32_16x16x32_bf16 v[32:35], v[130:133], v[40:43], v[68:71]
	s_nop 2
	v_mov_b64_e32 v[74:75], v[30:31]
	v_mov_b64_e32 v[72:73], v[28:29]
	v_mfma_f32_16x16x32_bf16 v[32:35], v[134:137], v[94:97], v[32:35]
	s_waitcnt lgkmcnt(0)
	v_mfma_f32_16x16x32_bf16 v[36:39], v[138:141], v[40:43], v[64:67]
	s_nop 2
	s_nop 0
	v_mov_b64_e32 v[70:71], v[34:35]
	v_mov_b64_e32 v[68:69], v[32:33]
	s_waitcnt lgkmcnt(0)
	v_mfma_f32_16x16x32_bf16 v[36:39], v[142:145], v[94:97], v[36:39]
	s_waitcnt lgkmcnt(0)
	v_mfma_f32_16x16x32_bf16 v[40:43], v[146:149], v[40:43], v[60:63]
	s_nop 2
	s_nop 0
	v_mov_b64_e32 v[66:67], v[38:39]
	v_mov_b64_e32 v[64:65], v[36:37]
	s_waitcnt lgkmcnt(0)
	v_mfma_f32_16x16x32_bf16 v[40:43], v[150:153], v[94:97], v[40:43]
	s_nop 7
	v_mov_b64_e32 v[62:63], v[42:43]
	v_mov_b64_e32 v[60:61], v[40:41]

; template <class MaskFn>
; DEV void attn_tile64(AttnAcc& st, const bf16x8 (&qf)[2], const char* smem, MaskFn mask) {
;     ...
;   const float mref = st.m;
;   float ps = 0.f;
; #pragma unroll
;   for (int sub = 0; sub < 4; ++sub)
; #pragma unroll
;     for (int j = 0; j < 4; ++j) {
;       float pv = (s[sub][j] > -1e29f) ? __expf(s[sub][j] - mref) : 0.f;
;       s[sub][j] = pv;
;       ps += pv;
;     }
;   st.l += ps;
;   union { bf16x8 v; unsigned u[4]; } pf0, pf1;
;   pf0.u[0] = pack2(s[0][0], s[0][1]); pf0.u[1] = pack2(s[0][2], s[0][3]);
;   pf0.u[2] = pack2(s[1][0], s[1][1]); pf0.u[3] = pack2(s[1][2], s[1][3]);
;   pf1.u[0] = pack2(s[2][0], s[2][1]); pf1.u[1] = pack2(s[2][2], s[2][3]);
;   pf1.u[2] = pack2(s[3][0], s[3][1]); pf1.u[3] = pack2(s[3][2], s[3][3]);
; #pragma unroll
;   for (int dt = 0; dt < 4; ++dt) {
;     const char* vrow = smem + K64_VT + (dt * 16 + l15) * 136;
;     uint2 lo = *(const uint2*)(vrow + quad * 8);
;     uint2 hi = *(const uint2*)(vrow + 32 + quad * 8);
;     union { bf16x8 v; unsigned u[4]; } vf;
;     vf.u[0] = lo.x; vf.u[1] = lo.y; vf.u[2] = hi.x; vf.u[3] = hi.y;
;     st.o[dt] = __builtin_amdgcn_mfma_f32_16x16x32_bf16(vf.v, pf0.v, st.o[dt], 0, 0, 0);
;     lo = *(const uint2*)(vrow + 64 + quad * 8);
;     hi = *(const uint2*)(vrow + 96 + quad * 8);
;     vf.u[0] = lo.x; vf.u[1] = lo.y; vf.u[2] = hi.x; vf.u[3] = hi.y;
;     st.o[dt] = __builtin_amdgcn_mfma_f32_16x16x32_bf16(vf.v, pf1.v, st.o[dt], 0, 0, 0);
;   }
.LBB0_442:
	v_cmp_lt_f32_e32 vcc, s6, v110
	v_sub_f32_e32 v110, v110, v94
	v_mul_f32_e32 v110, 0x3fb8aa3b, v110
	v_exp_f32_e32 v110, v110
	v_lshlrev_b32_e32 v3, 3, v3
	s_movk_i32 s2, 0x88
	v_mad_u32_u24 v0, v0, s2, v3
	v_cndmask_b32_e32 v110, 0, v110, vcc
	v_cmp_lt_f32_e32 vcc, s6, v109
	v_sub_f32_e32 v109, v109, v94
	v_mul_f32_e32 v109, 0x3fb8aa3b, v109
	v_exp_f32_e32 v109, v109
	v_add_f32_e32 v111, 0, v110
	v_add_u32_e32 v3, 0x2000, v0
	v_add_u32_e32 v93, 64, v93
	v_cndmask_b32_e32 v109, 0, v109, vcc
	v_cmp_lt_f32_e32 vcc, s6, v108
	v_sub_f32_e32 v108, v108, v94
	v_mul_f32_e32 v108, 0x3fb8aa3b, v108
	v_exp_f32_e32 v108, v108
	v_add_f32_e32 v111, v109, v111
	v_cndmask_b32_e32 v108, 0, v108, vcc
	v_cmp_lt_f32_e32 vcc, s6, v107
	v_sub_f32_e32 v107, v107, v94
	v_mul_f32_e32 v107, 0x3fb8aa3b, v107
	v_exp_f32_e32 v107, v107
	v_add_f32_e32 v111, v108, v111
	v_cndmask_b32_e32 v107, 0, v107, vcc
	v_cmp_lt_f32_e32 vcc, s6, v106
	v_sub_f32_e32 v106, v106, v94
	v_mul_f32_e32 v106, 0x3fb8aa3b, v106
	v_exp_f32_e32 v106, v106
	v_add_f32_e32 v111, v107, v111
	v_cndmask_b32_e32 v106, 0, v106, vcc
	v_cmp_lt_f32_e32 vcc, s6, v105
	v_sub_f32_e32 v105, v105, v94
	v_mul_f32_e32 v105, 0x3fb8aa3b, v105
	v_exp_f32_e32 v105, v105
	v_add_f32_e32 v111, v106, v111
	v_cndmask_b32_e32 v105, 0, v105, vcc
	v_cmp_lt_f32_e32 vcc, s6, v104
	v_sub_f32_e32 v104, v104, v94
	v_mul_f32_e32 v104, 0x3fb8aa3b, v104
	v_exp_f32_e32 v104, v104
	v_add_f32_e32 v111, v105, v111
	v_cndmask_b32_e32 v104, 0, v104, vcc
	v_cmp_lt_f32_e32 vcc, s6, v103
	v_sub_f32_e32 v103, v103, v94
	v_mul_f32_e32 v103, 0x3fb8aa3b, v103
	v_exp_f32_e32 v103, v103
	v_add_f32_e32 v111, v104, v111
	v_cndmask_b32_e32 v103, 0, v103, vcc
	v_cmp_lt_f32_e32 vcc, s6, v102
	v_sub_f32_e32 v102, v102, v94
	v_mul_f32_e32 v102, 0x3fb8aa3b, v102
	v_exp_f32_e32 v102, v102
	v_add_f32_e32 v111, v103, v111
	v_cndmask_b32_e32 v102, 0, v102, vcc
	v_cmp_lt_f32_e32 vcc, s6, v101
	v_sub_f32_e32 v101, v101, v94
	v_mul_f32_e32 v101, 0x3fb8aa3b, v101
	v_exp_f32_e32 v101, v101
	v_add_f32_e32 v111, v102, v111
	v_cndmask_b32_e32 v101, 0, v101, vcc
	v_cmp_lt_f32_e32 vcc, s6, v100
	v_sub_f32_e32 v100, v100, v94
	v_mul_f32_e32 v100, 0x3fb8aa3b, v100
	v_exp_f32_e32 v100, v100
	v_add_f32_e32 v111, v101, v111
	v_cndmask_b32_e32 v112, 0, v100, vcc
	v_cmp_lt_f32_e32 vcc, s6, v99
	v_sub_f32_e32 v99, v99, v94
	v_mul_f32_e32 v99, 0x3fb8aa3b, v99
	v_exp_f32_e32 v99, v99
	v_add_f32_e32 v100, v112, v111
	v_cndmask_b32_e32 v111, 0, v99, vcc
	v_cmp_lt_f32_e32 vcc, s6, v98
	v_sub_f32_e32 v98, v98, v94
	v_mul_f32_e32 v98, 0x3fb8aa3b, v98
	v_exp_f32_e32 v98, v98
	v_add_f32_e32 v99, v111, v100
	v_cvt_pk_bf16_f32 v100, v102, v101
	v_cvt_pk_bf16_f32 v101, v112, v111
	v_cndmask_b32_e32 v113, 0, v98, vcc
	v_cmp_lt_f32_e32 vcc, s6, v97
	v_sub_f32_e32 v97, v97, v94
	v_mul_f32_e32 v97, 0x3fb8aa3b, v97
	v_exp_f32_e32 v97, v97
	v_add_f32_e32 v98, v113, v99
	v_cvt_pk_bf16_f32 v99, v104, v103
	v_cndmask_b32_e32 v114, 0, v97, vcc
	v_cmp_lt_f32_e32 vcc, s6, v96
	v_sub_f32_e32 v96, v96, v94
	v_mul_f32_e32 v96, 0x3fb8aa3b, v96
	v_exp_f32_e32 v96, v96
	v_add_f32_e32 v97, v114, v98
	v_cvt_pk_bf16_f32 v98, v106, v105
	v_cvt_pk_bf16_f32 v102, v113, v114
	v_cndmask_b32_e32 v115, 0, v96, vcc
	v_add_f32_e32 v96, v115, v97
	v_cmp_lt_f32_e32 vcc, s6, v95
	v_sub_f32_e32 v95, v95, v94
	v_cvt_pk_bf16_f32 v97, v108, v107
	v_mul_f32_e32 v95, 0x3fb8aa3b, v95
	v_exp_f32_e32 v95, v95
	s_nop 0
	v_cndmask_b32_e32 v95, 0, v95, vcc
	v_add_f32_e32 v96, v95, v96
	v_add_f32_e32 v91, v91, v96
	v_cvt_pk_bf16_f32 v96, v110, v109
	v_cvt_pk_bf16_f32 v103, v115, v95
	v_cmp_gt_i32_e32 vcc, v2, v87
	s_waitcnt lgkmcnt(0)
	v_mfma_f32_16x16x32_bf16 v[44:47], v[122:125], v[96:99], v[44:47]
	v_add_u32_e32 v3, 0x2800, v0
	s_or_b64 s[12:13], vcc, s[12:13]
	s_waitcnt lgkmcnt(0)
	v_mfma_f32_16x16x32_bf16 v[44:47], v[126:129], v[100:103], v[44:47]
	s_waitcnt lgkmcnt(0)
	v_mfma_f32_16x16x32_bf16 v[52:55], v[130:133], v[96:99], v[52:55]
	v_add_u32_e32 v3, 0x3000, v0
	v_add_u32_e32 v0, 0x3800, v0
	s_waitcnt lgkmcnt(0)
	v_mfma_f32_16x16x32_bf16 v[52:55], v[134:137], v[100:103], v[52:55]
	s_waitcnt lgkmcnt(0)
	v_mfma_f32_16x16x32_bf16 v[48:51], v[138:141], v[96:99], v[48:51]
	s_waitcnt lgkmcnt(0)
	v_mfma_f32_16x16x32_bf16 v[48:51], v[142:145], v[100:103], v[48:51]
	s_waitcnt lgkmcnt(0)
	v_mfma_f32_16x16x32_bf16 v[56:59], v[146:149], v[96:99], v[56:59]
	s_waitcnt lgkmcnt(0)
	v_mfma_f32_16x16x32_bf16 v[56:59], v[150:153], v[100:103], v[56:59]
	s_andn2_b64 exec, exec, s[12:13]
	s_cbranch_execz .LBB0_447

; DEV int otid() { int t = threadIdx.x; asm volatile("" : "+v"(t)); return t; }
; template <class MaskFn>
; DEV void attn_tile64(AttnAcc& st, const bf16x8 (&qf)[2], const char* smem, MaskFn mask) {
;   const int lane = otid() & 63, l15 = lane & 15, quad = lane >> 4;
;   f32x4 s[4];
; #pragma unroll
;   for (int sub = 0; sub < 4; ++sub) {
;     f32x4 a = {0.f, 0.f, 0.f, 0.f};
; #pragma unroll
;     for (int ks2 = 0; ks2 < 2; ++ks2) {
;       bf16x8 kf = *(const bf16x8*)(smem + K64_SK + (sub * 16 + l15) * KSTR + (ks2 * 4 + quad) * 16);
;       a = __builtin_amdgcn_mfma_f32_16x16x32_bf16(kf, qf[ks2], a, 0, 0, 0);
;     }
;     s[sub] = a * 0.125f;
;   }
;   float lmx = -1e30f;
; #pragma unroll
;   for (int sub = 0; sub < 4; ++sub)
; #pragma unroll
;     for (int j = 0; j < 4; ++j) {
;       bool ok = mask(sub * 16 + quad * 4 + j);
;       float v = ok ? s[sub][j] : -1e30f;
;       s[sub][j] = v;
;       lmx = fmaxf(lmx, v);
;     }
;   if (__any(lmx > st.m + 8.0f)) {
;     float mx = fmaxf(st.m, lmx);
;     mx = fmaxf(mx, __shfl_xor(mx, 16));
;     mx = fmaxf(mx, __shfl_xor(mx, 32));
;     const float alpha = __expf(st.m - mx);
;     st.l *= alpha;
;     st.m = mx;
; #pragma unroll
;     for (int dt = 0; dt < 4; ++dt) st.o[dt] = st.o[dt] * alpha;
;   }
.LBB0_445:
	s_or_b64 exec, exec, s[4:5]
	v_mov_b32_e32 v3, v210
	s_waitcnt lgkmcnt(0)
	s_barrier
	s_mov_b32 s2, 0xf149f2ca
	v_and_b32_e32 v0, 15, v3
	v_bfe_u32 v3, v3, 4, 2
	v_mul_u32_u24_e32 v95, 0x90, v0
	v_lshl_add_u32 v95, v3, 4, v95
	ds_read_b128 v[122:125], v95
	ds_read_b128 v[126:129], v95 offset:2304
	ds_read_b128 v[130:133], v95 offset:4608
	ds_read_b128 v[134:137], v95 offset:6912
	ds_read_b128 v[138:141], v95 offset:64
	ds_read_b128 v[142:145], v95 offset:2368
	ds_read_b128 v[146:149], v95 offset:4672
	ds_read_b128 v[150:153], v95 offset:6976
	v_mul_u32_u24_e32 v166, 0x88, v0
	v_lshl_add_u32 v166, v3, 3, v166
	v_add_u32_e32 v167, 0x2800, v166
	v_add_u32_e32 v168, 0x3000, v166
	v_add_u32_e32 v169, 0x3800, v166
	v_add_u32_e32 v166, 0x2000, v166
	s_waitcnt lgkmcnt(7)
	v_mfma_f32_16x16x32_bf16 v[154:157], v[122:125], v[20:23], 0
	s_waitcnt lgkmcnt(6)
	v_mfma_f32_16x16x32_bf16 v[158:161], v[126:129], v[20:23], 0
	s_waitcnt lgkmcnt(5)
	v_mfma_f32_16x16x32_bf16 v[162:165], v[130:133], v[20:23], 0
	s_waitcnt lgkmcnt(4)
	v_mfma_f32_16x16x32_bf16 v[96:99], v[134:137], v[20:23], 0
	s_waitcnt lgkmcnt(3)
	v_mfma_f32_16x16x32_bf16 v[154:157], v[138:141], v[24:27], v[154:157]
	s_waitcnt lgkmcnt(2)
	v_mfma_f32_16x16x32_bf16 v[158:161], v[142:145], v[24:27], v[158:161]
	s_waitcnt lgkmcnt(1)
	v_mfma_f32_16x16x32_bf16 v[162:165], v[146:149], v[24:27], v[162:165]
	s_waitcnt lgkmcnt(0)
	v_mfma_f32_16x16x32_bf16 v[96:99], v[150:153], v[24:27], v[96:99]
	ds_read2_b64 v[122:125], v166 offset0:128 offset1:132
	ds_read2_b64 v[126:129], v166 offset0:136 offset1:140
	ds_read2_b64 v[130:133], v167 offset0:144 offset1:148
	ds_read2_b64 v[134:137], v167 offset0:152 offset1:156
	ds_read2_b64 v[138:141], v168 offset0:160 offset1:164
	ds_read2_b64 v[142:145], v168 offset0:168 offset1:172
	ds_read2_b64 v[146:149], v169 offset0:176 offset1:180
	ds_read2_b64 v[150:153], v169 offset0:184 offset1:188
	v_pk_mul_f32 v[104:105], v[156:157], s[90:91] op_sel_hi:[1,0]
	v_pk_mul_f32 v[106:107], v[154:155], s[90:91] op_sel_hi:[1,0]
	v_pk_mul_f32 v[112:113], v[160:161], s[90:91] op_sel_hi:[1,0]
	v_pk_mul_f32 v[114:115], v[158:159], s[90:91] op_sel_hi:[1,0]
	v_pk_mul_f32 v[116:117], v[164:165], s[90:91] op_sel_hi:[1,0]
	v_pk_mul_f32 v[118:119], v[162:163], s[90:91] op_sel_hi:[1,0]
	v_pk_mul_f32 v[120:121], v[98:99], s[90:91] op_sel_hi:[1,0]
	v_lshl_add_u32 v95, v3, 2, v93
	v_subrev_u32_e32 v98, 48, v95
	v_cmp_le_i32_e32 vcc, v98, v76
	v_cmp_ge_i32_e64 s[8:9], v98, v92
	s_and_b64 vcc, vcc, s[8:9]
	v_subrev_u32_e32 v99, 47, v95
	v_cndmask_b32_e32 v110, v221, v106, vcc
	v_cmp_lt_i32_e32 vcc, v98, v76
	v_cmp_ge_i32_e64 s[8:9], v99, v92
	s_and_b64 vcc, vcc, s[8:9]
	v_subrev_u32_e32 v99, 46, v95
	v_cndmask_b32_e32 v109, v221, v107, vcc
	v_cmp_le_i32_e32 vcc, v99, v76
	v_cmp_ge_i32_e64 s[8:9], v99, v92
	s_and_b64 vcc, vcc, s[8:9]
	v_subrev_u32_e32 v99, 45, v95
	v_cndmask_b32_e32 v108, v221, v104, vcc
	v_cmp_le_i32_e32 vcc, v99, v76
	v_cmp_ge_i32_e64 s[8:9], v99, v92
	s_and_b64 vcc, vcc, s[8:9]
	v_subrev_u32_e32 v99, 32, v95
	v_cndmask_b32_e32 v107, v221, v105, vcc
	v_cmp_le_i32_e32 vcc, v99, v76
	v_cmp_ge_i32_e64 s[8:9], v99, v92
	s_and_b64 vcc, vcc, s[8:9]
	v_subrev_u32_e32 v99, 31, v95
	v_cndmask_b32_e32 v106, v221, v114, vcc
	v_cmp_le_i32_e32 vcc, v99, v76
	v_cmp_ge_i32_e64 s[8:9], v99, v92
	s_and_b64 vcc, vcc, s[8:9]
	v_subrev_u32_e32 v99, 30, v95
	v_cndmask_b32_e32 v105, v221, v115, vcc
	v_cmp_le_i32_e32 vcc, v99, v76
	v_cmp_ge_i32_e64 s[8:9], v99, v92
	s_and_b64 vcc, vcc, s[8:9]
	v_subrev_u32_e32 v99, 29, v95
	v_cndmask_b32_e32 v104, v221, v112, vcc
	v_cmp_le_i32_e32 vcc, v99, v76
	v_cmp_ge_i32_e64 s[8:9], v99, v92
	s_and_b64 vcc, vcc, s[8:9]
	v_add_u32_e32 v99, -16, v95
	v_cndmask_b32_e32 v103, v221, v113, vcc
	v_cmp_le_i32_e32 vcc, v99, v76
	v_cmp_ge_i32_e64 s[8:9], v99, v92
	s_and_b64 vcc, vcc, s[8:9]
	v_add_u32_e32 v99, -15, v95
	v_cndmask_b32_e32 v102, v221, v118, vcc
	v_cmp_le_i32_e32 vcc, v99, v76
	v_cmp_ge_i32_e64 s[8:9], v99, v92
	s_and_b64 vcc, vcc, s[8:9]
	v_add_u32_e32 v99, -14, v95
	v_cndmask_b32_e32 v101, v221, v119, vcc
	v_cmp_le_i32_e32 vcc, v99, v76
	v_cmp_ge_i32_e64 s[8:9], v99, v92
	v_max3_f32 v98, v110, s2, v109
	s_and_b64 vcc, vcc, s[8:9]
	v_add_u32_e32 v99, -13, v95
	v_max3_f32 v98, v98, v108, v107
	v_cndmask_b32_e32 v100, v221, v116, vcc
	v_cmp_le_i32_e32 vcc, v99, v76
	v_cmp_ge_i32_e64 s[8:9], v99, v92
	v_max3_f32 v98, v98, v106, v105
	s_and_b64 vcc, vcc, s[8:9]
	v_max3_f32 v98, v98, v104, v103
	v_cndmask_b32_e32 v99, v221, v117, vcc
	v_cmp_le_i32_e32 vcc, v95, v76
	v_cmp_ge_i32_e64 s[8:9], v95, v92
	v_pk_mul_f32 v[96:97], v[96:97], s[90:91] op_sel_hi:[1,0]
	v_max3_f32 v98, v98, v102, v101
	s_and_b64 vcc, vcc, s[8:9]
	v_max3_f32 v111, v98, v100, v99
	v_cndmask_b32_e32 v98, v221, v96, vcc
	v_add_u32_e32 v96, 1, v95
	v_cmp_le_i32_e32 vcc, v96, v76
	v_cmp_ge_i32_e64 s[8:9], v96, v92
	s_and_b64 vcc, vcc, s[8:9]
	v_add_u32_e32 v96, 2, v95
	v_cndmask_b32_e32 v97, v221, v97, vcc
	v_cmp_le_i32_e32 vcc, v96, v76
	v_cmp_ge_i32_e64 s[8:9], v96, v92
	s_and_b64 vcc, vcc, s[8:9]
	v_add_u32_e32 v95, 3, v95
	v_cndmask_b32_e32 v96, v221, v120, vcc
	v_cmp_le_i32_e32 vcc, v95, v76
	v_cmp_ge_i32_e64 s[8:9], v95, v92
	s_and_b64 vcc, vcc, s[8:9]
	v_max3_f32 v111, v111, v98, v97
	v_cndmask_b32_e32 v95, v221, v121, vcc
	v_max3_f32 v111, v111, v96, v95
	v_add_f32_e32 v112, 0x41000000, v94
	v_cmp_gt_f32_e32 vcc, v111, v112
	s_cbranch_vccz .LBB0_442
	v_max_f32_e32 v111, v111, v111
	v_max_f32_e32 v112, v94, v94
	v_max_f32_e32 v111, v112, v111
	ds_bpermute_b32 v112, v77, v111
	s_waitcnt lgkmcnt(0)
	v_max_f32_e32 v112, v112, v112
	v_max_f32_e32 v111, v111, v112
	ds_bpermute_b32 v112, v89, v111
	s_waitcnt lgkmcnt(0)
	v_max_f32_e32 v112, v112, v112
	v_max_f32_e32 v111, v111, v112
	v_sub_f32_e32 v94, v94, v111
	v_mul_f32_e32 v94, 0x3fb8aa3b, v94
	v_exp_f32_e32 v94, v94
	s_nop 0
	v_mul_f32_e32 v91, v91, v94
	v_pk_mul_f32 v[46:47], v[46:47], v[94:95] op_sel_hi:[1,0]
	v_pk_mul_f32 v[44:45], v[44:45], v[94:95] op_sel_hi:[1,0]
	v_pk_mul_f32 v[54:55], v[54:55], v[94:95] op_sel_hi:[1,0]
	v_pk_mul_f32 v[52:53], v[52:53], v[94:95] op_sel_hi:[1,0]
	v_pk_mul_f32 v[50:51], v[50:51], v[94:95] op_sel_hi:[1,0]
	v_pk_mul_f32 v[48:49], v[48:49], v[94:95] op_sel_hi:[1,0]
	v_pk_mul_f32 v[58:59], v[58:59], v[94:95] op_sel_hi:[1,0]
	v_pk_mul_f32 v[56:57], v[56:57], v[94:95] op_sel_hi:[1,0]
	v_mov_b32_e32 v94, v111
	s_branch .LBB0_442

; template <class MaskFn>
; DEV void attn_tile64(AttnAcc& st, const bf16x8 (&qf)[2], const char* smem, MaskFn mask) {
;     ...
;   const float mref = st.m;
;   float ps = 0.f;
; #pragma unroll
;   for (int sub = 0; sub < 4; ++sub)
; #pragma unroll
;     for (int j = 0; j < 4; ++j) {
;       float pv = (s[sub][j] > -1e29f) ? __expf(s[sub][j] - mref) : 0.f;
;       s[sub][j] = pv;
;       ps += pv;
;     }
;   st.l += ps;
;   union { bf16x8 v; unsigned u[4]; } pf0, pf1;
;   pf0.u[0] = pack2(s[0][0], s[0][1]); pf0.u[1] = pack2(s[0][2], s[0][3]);
;   pf0.u[2] = pack2(s[1][0], s[1][1]); pf0.u[3] = pack2(s[1][2], s[1][3]);
;   pf1.u[0] = pack2(s[2][0], s[2][1]); pf1.u[1] = pack2(s[2][2], s[2][3]);
;   pf1.u[2] = pack2(s[3][0], s[3][1]); pf1.u[3] = pack2(s[3][2], s[3][3]);
; #pragma unroll
;   for (int dt = 0; dt < 4; ++dt) {
;     const char* vrow = smem + K64_VT + (dt * 16 + l15) * 136;
;     uint2 lo = *(const uint2*)(vrow + quad * 8);
;     uint2 hi = *(const uint2*)(vrow + 32 + quad * 8);
;     union { bf16x8 v; unsigned u[4]; } vf;
;     vf.u[0] = lo.x; vf.u[1] = lo.y; vf.u[2] = hi.x; vf.u[3] = hi.y;
;     st.o[dt] = __builtin_amdgcn_mfma_f32_16x16x32_bf16(vf.v, pf0.v, st.o[dt], 0, 0, 0);
;     lo = *(const uint2*)(vrow + 64 + quad * 8);
;     hi = *(const uint2*)(vrow + 96 + quad * 8);
;     vf.u[0] = lo.x; vf.u[1] = lo.y; vf.u[2] = hi.x; vf.u[3] = hi.y;
;     st.o[dt] = __builtin_amdgcn_mfma_f32_16x16x32_bf16(vf.v, pf1.v, st.o[dt], 0, 0, 0);
;   }
.LBB0_459:
	v_cmp_lt_f32_e32 vcc, s6, v65
	v_sub_f32_e32 v65, v65, v47
	v_mul_f32_e32 v65, 0x3fb8aa3b, v65
	v_exp_f32_e32 v65, v65
	v_lshlrev_b32_e32 v49, 3, v49
	s_movk_i32 s8, 0x88
	v_mad_u32_u24 v0, v0, s8, v49
	v_cndmask_b32_e32 v65, 0, v65, vcc
	v_cmp_lt_f32_e32 vcc, s6, v64
	v_sub_f32_e32 v64, v64, v47
	v_mul_f32_e32 v64, 0x3fb8aa3b, v64
	v_exp_f32_e32 v64, v64
	v_add_f32_e32 v66, 0, v65
	v_add_u32_e32 v49, 0x2000, v0
	s_add_i32 s14, s14, 64
	v_cndmask_b32_e32 v64, 0, v64, vcc
	v_cmp_lt_f32_e32 vcc, s6, v63
	v_sub_f32_e32 v63, v63, v47
	v_mul_f32_e32 v63, 0x3fb8aa3b, v63
	v_exp_f32_e32 v63, v63
	v_add_f32_e32 v66, v64, v66
	s_cmp_le_i32 s15, s13
	v_cndmask_b32_e32 v63, 0, v63, vcc
	v_cmp_lt_f32_e32 vcc, s6, v62
	v_sub_f32_e32 v62, v62, v47
	v_mul_f32_e32 v62, 0x3fb8aa3b, v62
	v_exp_f32_e32 v62, v62
	v_add_f32_e32 v66, v63, v66
	v_cndmask_b32_e32 v62, 0, v62, vcc
	v_cmp_lt_f32_e32 vcc, s6, v61
	v_sub_f32_e32 v61, v61, v47
	v_mul_f32_e32 v61, 0x3fb8aa3b, v61
	v_exp_f32_e32 v61, v61
	v_add_f32_e32 v66, v62, v66
	v_cndmask_b32_e32 v61, 0, v61, vcc
	v_cmp_lt_f32_e32 vcc, s6, v60
	v_sub_f32_e32 v60, v60, v47
	v_mul_f32_e32 v60, 0x3fb8aa3b, v60
	v_exp_f32_e32 v60, v60
	v_add_f32_e32 v66, v61, v66
	v_cndmask_b32_e32 v60, 0, v60, vcc
	v_cmp_lt_f32_e32 vcc, s6, v59
	v_sub_f32_e32 v59, v59, v47
	v_mul_f32_e32 v59, 0x3fb8aa3b, v59
	v_exp_f32_e32 v59, v59
	v_add_f32_e32 v66, v60, v66
	v_cndmask_b32_e32 v59, 0, v59, vcc
	v_cmp_lt_f32_e32 vcc, s6, v58
	v_sub_f32_e32 v58, v58, v47
	v_mul_f32_e32 v58, 0x3fb8aa3b, v58
	v_exp_f32_e32 v58, v58
	v_add_f32_e32 v66, v59, v66
	v_cndmask_b32_e32 v58, 0, v58, vcc
	v_cmp_lt_f32_e32 vcc, s6, v57
	v_sub_f32_e32 v57, v57, v47
	v_mul_f32_e32 v57, 0x3fb8aa3b, v57
	v_exp_f32_e32 v57, v57
	v_add_f32_e32 v66, v58, v66
	v_cndmask_b32_e32 v57, 0, v57, vcc
	v_cmp_lt_f32_e32 vcc, s6, v56
	v_sub_f32_e32 v56, v56, v47
	v_mul_f32_e32 v56, 0x3fb8aa3b, v56
	v_exp_f32_e32 v56, v56
	v_add_f32_e32 v66, v57, v66
	v_cndmask_b32_e32 v56, 0, v56, vcc
	v_cmp_lt_f32_e32 vcc, s6, v55
	v_sub_f32_e32 v55, v55, v47
	v_mul_f32_e32 v55, 0x3fb8aa3b, v55
	v_exp_f32_e32 v55, v55
	v_add_f32_e32 v66, v56, v66
	v_cndmask_b32_e32 v55, 0, v55, vcc
	v_cmp_lt_f32_e32 vcc, s6, v54
	v_sub_f32_e32 v54, v54, v47
	v_mul_f32_e32 v54, 0x3fb8aa3b, v54
	v_exp_f32_e32 v54, v54
	v_add_f32_e32 v66, v55, v66
	v_cndmask_b32_e32 v67, 0, v54, vcc
	v_cmp_lt_f32_e32 vcc, s6, v53
	v_sub_f32_e32 v53, v53, v47
	v_mul_f32_e32 v53, 0x3fb8aa3b, v53
	v_exp_f32_e32 v53, v53
	v_add_f32_e32 v54, v67, v66
	v_cvt_pk_bf16_f32 v55, v55, v67
	v_cndmask_b32_e32 v66, 0, v53, vcc
	v_cmp_lt_f32_e32 vcc, s6, v52
	v_sub_f32_e32 v52, v52, v47
	v_mul_f32_e32 v52, 0x3fb8aa3b, v52
	v_exp_f32_e32 v52, v52
	v_add_f32_e32 v53, v66, v54
	v_cvt_pk_bf16_f32 v54, v57, v56
	v_cndmask_b32_e32 v68, 0, v52, vcc
	v_cmp_lt_f32_e32 vcc, s6, v51
	v_sub_f32_e32 v51, v51, v47
	v_mul_f32_e32 v51, 0x3fb8aa3b, v51
	v_exp_f32_e32 v51, v51
	v_add_f32_e32 v52, v68, v53
	v_cvt_pk_bf16_f32 v53, v59, v58
	v_cvt_pk_bf16_f32 v56, v66, v68
	v_cndmask_b32_e32 v69, 0, v51, vcc
	v_add_f32_e32 v51, v69, v52
	v_cmp_lt_f32_e32 vcc, s6, v50
	v_sub_f32_e32 v50, v50, v47
	v_cvt_pk_bf16_f32 v52, v61, v60
	v_mul_f32_e32 v50, 0x3fb8aa3b, v50
	v_exp_f32_e32 v50, v50
	s_nop 0
	v_cndmask_b32_e32 v70, 0, v50, vcc
	v_add_f32_e32 v50, v70, v51
	v_add_f32_e32 v46, v46, v50
	v_cvt_pk_bf16_f32 v50, v65, v64
	v_cvt_pk_bf16_f32 v51, v63, v62
	v_cvt_pk_bf16_f32 v57, v69, v70
	s_waitcnt lgkmcnt(0)
	v_mfma_f32_16x16x32_bf16 v[14:17], v[122:125], v[50:53], v[14:17]
	v_add_u32_e32 v49, 0x2800, v0
	s_waitcnt lgkmcnt(0)
	v_mfma_f32_16x16x32_bf16 v[14:17], v[126:129], v[54:57], v[14:17]
	s_waitcnt lgkmcnt(0)
	v_mfma_f32_16x16x32_bf16 v[10:13], v[130:133], v[50:53], v[10:13]
	v_add_u32_e32 v49, 0x3000, v0
	v_add_u32_e32 v0, 0x3800, v0
	s_waitcnt lgkmcnt(0)
	v_mfma_f32_16x16x32_bf16 v[10:13], v[134:137], v[54:57], v[10:13]
	s_waitcnt lgkmcnt(0)
	v_mfma_f32_16x16x32_bf16 v[6:9], v[138:141], v[50:53], v[6:9]
	s_waitcnt lgkmcnt(0)
	v_mfma_f32_16x16x32_bf16 v[6:9], v[142:145], v[54:57], v[6:9]
	s_waitcnt lgkmcnt(0)
	v_mfma_f32_16x16x32_bf16 v[2:5], v[146:149], v[50:53], v[2:5]
	s_waitcnt lgkmcnt(0)
	v_mfma_f32_16x16x32_bf16 v[2:5], v[150:153], v[54:57], v[2:5]
	s_cbranch_scc0 .LBB0_456

; DEV int otid() { int t = threadIdx.x; asm volatile("" : "+v"(t)); return t; }
; template <class MaskFn>
; DEV void attn_tile64(AttnAcc& st, const bf16x8 (&qf)[2], const char* smem, MaskFn mask) {
;   const int lane = otid() & 63, l15 = lane & 15, quad = lane >> 4;
;   f32x4 s[4];
; #pragma unroll
;   for (int sub = 0; sub < 4; ++sub) {
;     f32x4 a = {0.f, 0.f, 0.f, 0.f};
; #pragma unroll
;     for (int ks2 = 0; ks2 < 2; ++ks2) {
;       bf16x8 kf = *(const bf16x8*)(smem + K64_SK + (sub * 16 + l15) * KSTR + (ks2 * 4 + quad) * 16);
;       a = __builtin_amdgcn_mfma_f32_16x16x32_bf16(kf, qf[ks2], a, 0, 0, 0);
;     }
;     s[sub] = a * 0.125f;
;   }
;   float lmx = -1e30f;
; #pragma unroll
;   for (int sub = 0; sub < 4; ++sub)
; #pragma unroll
;     for (int j = 0; j < 4; ++j) {
;       bool ok = mask(sub * 16 + quad * 4 + j);
;       float v = ok ? s[sub][j] : -1e30f;
;       s[sub][j] = v;
;       lmx = fmaxf(lmx, v);
;     }
;   if (__any(lmx > st.m + 8.0f)) {
;     float mx = fmaxf(st.m, lmx);
;     mx = fmaxf(mx, __shfl_xor(mx, 16));
;     mx = fmaxf(mx, __shfl_xor(mx, 32));
;     const float alpha = __expf(st.m - mx);
;     st.l *= alpha;
;     st.m = mx;
; #pragma unroll
;     for (int dt = 0; dt < 4; ++dt) st.o[dt] = st.o[dt] * alpha;
;   }
.LBB0_462:
	v_mov_b32_e32 v49, v210
	s_waitcnt lgkmcnt(0)
	s_barrier
	s_nop 0
	v_and_b32_e32 v0, 15, v49
	v_bfe_u32 v49, v49, 4, 2
	v_mul_u32_u24_e32 v50, 0x90, v0
	v_lshl_add_u32 v62, v49, 4, v50
	ds_read_b128 v[122:125], v62
	ds_read_b128 v[126:129], v62 offset:2304
	ds_read_b128 v[130:133], v62 offset:4608
	ds_read_b128 v[134:137], v62 offset:6912
	ds_read_b128 v[138:141], v62 offset:64
	ds_read_b128 v[142:145], v62 offset:2368
	ds_read_b128 v[146:149], v62 offset:4672
	ds_read_b128 v[150:153], v62 offset:6976
	v_mul_u32_u24_e32 v166, 0x88, v0
	v_lshl_add_u32 v166, v49, 3, v166
	v_add_u32_e32 v167, 0x2800, v166
	v_add_u32_e32 v168, 0x3000, v166
	v_add_u32_e32 v169, 0x3800, v166
	v_add_u32_e32 v166, 0x2000, v166
	s_waitcnt lgkmcnt(7)
	v_mfma_f32_16x16x32_bf16 v[154:157], v[122:125], v[18:21], 0
	s_waitcnt lgkmcnt(6)
	v_mfma_f32_16x16x32_bf16 v[158:161], v[126:129], v[18:21], 0
	s_waitcnt lgkmcnt(5)
	v_mfma_f32_16x16x32_bf16 v[162:165], v[130:133], v[18:21], 0
	s_waitcnt lgkmcnt(4)
	v_mfma_f32_16x16x32_bf16 v[50:53], v[134:137], v[18:21], 0
	s_waitcnt lgkmcnt(3)
	v_mfma_f32_16x16x32_bf16 v[154:157], v[138:141], v[22:25], v[154:157]
	s_waitcnt lgkmcnt(2)
	v_mfma_f32_16x16x32_bf16 v[158:161], v[142:145], v[22:25], v[158:161]
	s_waitcnt lgkmcnt(1)
	v_mfma_f32_16x16x32_bf16 v[162:165], v[146:149], v[22:25], v[162:165]
	s_waitcnt lgkmcnt(0)
	v_mfma_f32_16x16x32_bf16 v[50:53], v[150:153], v[22:25], v[50:53]
	ds_read2_b64 v[122:125], v166 offset0:128 offset1:132
	ds_read2_b64 v[126:129], v166 offset0:136 offset1:140
	ds_read2_b64 v[130:133], v167 offset0:144 offset1:148
	ds_read2_b64 v[134:137], v167 offset0:152 offset1:156
	ds_read2_b64 v[138:141], v168 offset0:160 offset1:164
	ds_read2_b64 v[142:145], v168 offset0:168 offset1:172
	ds_read2_b64 v[146:149], v169 offset0:176 offset1:180
	ds_read2_b64 v[150:153], v169 offset0:184 offset1:188
	v_pk_mul_f32 v[58:59], v[156:157], s[90:91] op_sel_hi:[1,0]
	v_pk_mul_f32 v[60:61], v[154:155], s[90:91] op_sel_hi:[1,0]
	v_pk_mul_f32 v[66:67], v[160:161], s[90:91] op_sel_hi:[1,0]
	v_pk_mul_f32 v[68:69], v[158:159], s[90:91] op_sel_hi:[1,0]
	v_pk_mul_f32 v[70:71], v[164:165], s[90:91] op_sel_hi:[1,0]
	v_pk_mul_f32 v[72:73], v[162:163], s[90:91] op_sel_hi:[1,0]
	v_pk_mul_f32 v[74:75], v[52:53], s[90:91] op_sel_hi:[1,0]
	v_lshl_add_u32 v76, v49, 2, s14
	v_subrev_u32_e32 v52, 48, v76
	v_cmp_le_i32_e32 vcc, v52, v42
	v_cmp_ge_i32_e64 s[8:9], v52, v48
	s_and_b64 vcc, vcc, s[8:9]
	v_subrev_u32_e32 v53, 47, v76
	v_cndmask_b32_e32 v65, v221, v60, vcc
	v_cmp_lt_i32_e32 vcc, v52, v42
	v_cmp_ge_i32_e64 s[8:9], v53, v48
	s_and_b64 vcc, vcc, s[8:9]
	v_cndmask_b32_e32 v64, v221, v61, vcc
	s_mov_b32 s8, 0xf149f2ca
	v_subrev_u32_e32 v53, 46, v76
	v_max3_f32 v52, v65, s8, v64
	v_cmp_le_i32_e32 vcc, v53, v42
	v_cmp_ge_i32_e64 s[8:9], v53, v48
	s_and_b64 vcc, vcc, s[8:9]
	v_subrev_u32_e32 v53, 45, v76
	v_cndmask_b32_e32 v63, v221, v58, vcc
	v_cmp_le_i32_e32 vcc, v53, v42
	v_cmp_ge_i32_e64 s[8:9], v53, v48
	s_and_b64 vcc, vcc, s[8:9]
	v_subrev_u32_e32 v53, 32, v76
	v_cndmask_b32_e32 v62, v221, v59, vcc
	v_cmp_le_i32_e32 vcc, v53, v42
	v_cmp_ge_i32_e64 s[8:9], v53, v48
	s_and_b64 vcc, vcc, s[8:9]
	v_subrev_u32_e32 v53, 31, v76
	v_cndmask_b32_e32 v61, v221, v68, vcc
	v_cmp_le_i32_e32 vcc, v53, v42
	v_cmp_ge_i32_e64 s[8:9], v53, v48
	s_and_b64 vcc, vcc, s[8:9]
	v_subrev_u32_e32 v53, 30, v76
	v_cndmask_b32_e32 v60, v221, v69, vcc
	v_cmp_le_i32_e32 vcc, v53, v42
	v_cmp_ge_i32_e64 s[8:9], v53, v48
	s_and_b64 vcc, vcc, s[8:9]
	v_subrev_u32_e32 v53, 29, v76
	v_cndmask_b32_e32 v59, v221, v66, vcc
	v_cmp_le_i32_e32 vcc, v53, v42
	v_cmp_ge_i32_e64 s[8:9], v53, v48
	s_and_b64 vcc, vcc, s[8:9]
	v_add_u32_e32 v53, -16, v76
	v_cndmask_b32_e32 v58, v221, v67, vcc
	v_cmp_le_i32_e32 vcc, v53, v42
	v_cmp_ge_i32_e64 s[8:9], v53, v48
	s_and_b64 vcc, vcc, s[8:9]
	v_add_u32_e32 v53, -15, v76
	v_cndmask_b32_e32 v57, v221, v72, vcc
	v_cmp_le_i32_e32 vcc, v53, v42
	v_cmp_ge_i32_e64 s[8:9], v53, v48
	s_and_b64 vcc, vcc, s[8:9]
	v_add_u32_e32 v53, -14, v76
	v_cndmask_b32_e32 v56, v221, v73, vcc
	v_cmp_le_i32_e32 vcc, v53, v42
	v_cmp_ge_i32_e64 s[8:9], v53, v48
	s_and_b64 vcc, vcc, s[8:9]
	v_add_u32_e32 v53, -13, v76
	v_cndmask_b32_e32 v55, v221, v70, vcc
	v_cmp_le_i32_e32 vcc, v53, v42
	v_cmp_ge_i32_e64 s[8:9], v53, v48
	s_and_b64 vcc, vcc, s[8:9]
	v_cndmask_b32_e32 v54, v221, v71, vcc
	v_cmp_le_i32_e32 vcc, v76, v42
	v_cmp_ge_i32_e64 s[8:9], v76, v48
	v_pk_mul_f32 v[50:51], v[50:51], s[90:91] op_sel_hi:[1,0]
	v_max3_f32 v52, v52, v63, v62
	s_and_b64 vcc, vcc, s[8:9]
	v_max3_f32 v52, v52, v61, v60
	v_cndmask_b32_e32 v53, v221, v50, vcc
	v_add_u32_e32 v50, 1, v76
	v_max3_f32 v52, v52, v59, v58
	v_cmp_le_i32_e32 vcc, v50, v42
	v_cmp_ge_i32_e64 s[8:9], v50, v48
	v_max3_f32 v52, v52, v57, v56
	s_and_b64 vcc, vcc, s[8:9]
	v_add_u32_e32 v50, 2, v76
	v_max3_f32 v66, v52, v55, v54
	v_cndmask_b32_e32 v52, v221, v51, vcc
	v_cmp_le_i32_e32 vcc, v50, v42
	v_cmp_ge_i32_e64 s[8:9], v50, v48
	s_and_b64 vcc, vcc, s[8:9]
	v_add_u32_e32 v50, 3, v76
	v_cndmask_b32_e32 v51, v221, v74, vcc
	v_cmp_le_i32_e32 vcc, v50, v42
	v_cmp_ge_i32_e64 s[8:9], v50, v48
	s_and_b64 vcc, vcc, s[8:9]
	v_max3_f32 v66, v66, v53, v52
	v_cndmask_b32_e32 v50, v221, v75, vcc
	v_max3_f32 v66, v66, v51, v50
	v_add_f32_e32 v67, 0x41000000, v47
	v_cmp_gt_f32_e32 vcc, v66, v67
	s_cbranch_vccz .LBB0_459
	v_max_f32_e32 v66, v66, v66
	v_max_f32_e32 v67, v47, v47
	v_and_b32_e32 v68, 64, v219
	v_max_f32_e32 v66, v67, v66
	v_xor_b32_e32 v67, 16, v219
	v_add_u32_e32 v68, 64, v68
	v_cmp_lt_i32_e32 vcc, v67, v68
	s_nop 1
	v_cndmask_b32_e32 v67, v219, v67, vcc
	v_lshlrev_b32_e32 v67, 2, v67
	ds_bpermute_b32 v67, v67, v66
	s_waitcnt lgkmcnt(0)
	v_max_f32_e32 v67, v67, v67
	v_max_f32_e32 v66, v66, v67
	v_xor_b32_e32 v67, 32, v219
	v_cmp_lt_i32_e32 vcc, v67, v68
	s_nop 1
	v_cndmask_b32_e32 v67, v219, v67, vcc
	v_lshlrev_b32_e32 v67, 2, v67
	ds_bpermute_b32 v67, v67, v66
	s_waitcnt lgkmcnt(0)
	v_max_f32_e32 v67, v67, v67
	v_max_f32_e32 v67, v66, v67
	v_sub_f32_e32 v47, v47, v67
	v_mul_f32_e32 v47, 0x3fb8aa3b, v47
	v_exp_f32_e32 v66, v47
	v_mov_b32_e32 v47, v67
	v_mul_f32_e32 v46, v46, v66
	v_pk_mul_f32 v[16:17], v[16:17], v[66:67] op_sel_hi:[1,0]
	v_pk_mul_f32 v[14:15], v[14:15], v[66:67] op_sel_hi:[1,0]
	v_pk_mul_f32 v[12:13], v[12:13], v[66:67] op_sel_hi:[1,0]
	v_pk_mul_f32 v[10:11], v[10:11], v[66:67] op_sel_hi:[1,0]
	v_pk_mul_f32 v[8:9], v[8:9], v[66:67] op_sel_hi:[1,0]
	v_pk_mul_f32 v[6:7], v[6:7], v[66:67] op_sel_hi:[1,0]
	v_pk_mul_f32 v[4:5], v[4:5], v[66:67] op_sel_hi:[1,0]
	v_pk_mul_f32 v[2:3], v[2:3], v[66:67] op_sel_hi:[1,0]
	s_branch .LBB0_459

; DEV u16 f2bf(float f) { return (u16)(pack2(f, 0.f) & 0xffffu); }
; DEV void phase_win(const Params& P, int l, const u16* __restrict__ xb, const u16* __restrict__ Wt, u16* __restrict__ h, char* smem) {
;     ...
;     const int mode = (cb >= C_HF && cb < C_HI) ? 1 : ((cb >= C_HG) ? 2 : 0);
; #pragma unroll
;     for (int ms = 0; ms < 8; ++ms) {
;       asm volatile("" ::: "memory");
; #pragma unroll
;       for (int ns = 0; ns < 4; ++ns)
; #pragma unroll
;         for (int j = 0; j < 4; ++j) {
;           int row = m0 + wm * 128 + ms * 16 + quad * 4 + j;
;           int col = cb + ns * 16 + l15;
;           float v = acc[ms][ns][j];
;           if (mode == 1) { float lbv = lbp[col - C_HF]; v = __logf(lbv + (1.f - lbv) / (1.f + __expf(-v))); }
;           else if (mode == 2) v = v / (1.f + __expf(-v));
;           h[(size_t)row * HS + col] = f2bf(v);
.LBB0_1433:
	s_add_i32 s4, s30, 0xfffffd80
	s_cmpk_lt_u32 s4, 0x180
	s_cselect_b64 s[28:29], -1, 0
	s_cmpk_gt_u32 s4, 0x17f
	s_cbranch_scc0 .LBB0_2075
	s_add_i32 s4, s30, 0xfffff980
	s_cmpk_gt_u32 s30, 0xa7f
	s_cselect_b32 s5, 2, 0
	s_cmpk_gt_u32 s4, 0x1ff
	s_cselect_b32 s17, s5, 1
	s_cmp_lg_u32 s17, 1
	s_cbranch_scc1 .Lwin_nolbp
	v_or_b32_e32 v164, v130, v186
	v_add_u32_e32 v164, 0xfffff980, v164
	v_lshlrev_b32_e32 v164, 2, v164
	v_ashrrev_i32_e32 v165, 31, v164
	v_lshl_add_u64 v[164:165], v[164:165], 0, s[14:15]
	global_load_dword v160, v[164:165], off
	global_load_dword v161, v[164:165], off offset:64
	global_load_dword v162, v[164:165], off offset:128
	global_load_dword v163, v[164:165], off offset:192
	s_waitcnt vmcnt(0)
.Lwin_nolbp:
	s_cmp_gt_i32 s17, 1
	s_mov_b64 s[4:5], -1
	s_cbranch_scc0 .LBB0_1436
	v_mul_f32_e32 v0, 0xbfb8aa3b, v38
	v_exp_f32_e32 v0, v0
	s_nop 0
	v_add_f32_e32 v0, 1.0, v0
	v_div_scale_f32 v131, s[4:5], v0, v0, v38
	v_rcp_f32_e32 v132, v131
	v_div_scale_f32 v133, vcc, v38, v0, v38
	s_mov_b64 s[4:5], 0
	v_fma_f32 v134, -v131, v132, 1.0
	v_fmac_f32_e32 v132, v134, v132
	v_mul_f32_e32 v134, v133, v132
	v_fma_f32 v135, -v131, v134, v133
	v_fmac_f32_e32 v134, v135, v132
	v_fma_f32 v131, -v131, v134, v133
	v_div_fmas_f32 v131, v131, v132, v134
	v_div_fixup_f32 v134, v131, v0, v38
.LBB0_1436:
	s_andn2_b64 vcc, exec, s[4:5]
	v_or_b32_e32 v0, v130, v186
	s_cbranch_vccnz .LBB0_1439
	s_cmp_lg_u32 s17, 1
	v_mov_b32_e32 v134, v38
	s_cbranch_scc1 .LBB0_1439
	v_lshl_add_u64 v[132:133], v[0:1], 2, s[14:15]
	v_add_co_u32_e32 v132, vcc, 0xfffff000, v132
	s_nop 1
	v_addc_co_u32_e32 v133, vcc, -1, v133, vcc
	v_mov_b32_e32 v131, v160
	v_mul_f32_e32 v132, 0xbfb8aa3b, v38
	v_exp_f32_e32 v132, v132
	v_sub_f32_e32 v133, 1.0, v131
	v_add_f32_e32 v132, 1.0, v132
	v_div_scale_f32 v134, s[4:5], v132, v132, v133
	v_rcp_f32_e32 v135, v134
	v_div_scale_f32 v136, vcc, v133, v132, v133
	s_mov_b32 s4, 0x800000
	v_fma_f32 v137, -v134, v135, 1.0
	v_fmac_f32_e32 v135, v137, v135
	v_mul_f32_e32 v137, v136, v135
	v_fma_f32 v138, -v134, v137, v136
	v_fmac_f32_e32 v137, v138, v135
	v_fma_f32 v134, -v134, v137, v136
	v_div_fmas_f32 v134, v134, v135, v137
	v_div_fixup_f32 v132, v134, v132, v133
	v_add_f32_e32 v131, v131, v132
	v_cmp_gt_f32_e32 vcc, s4, v131
	s_mov_b32 s4, 0x3f317217
	s_nop 0
	v_cndmask_b32_e64 v132, 0, 32, vcc
	v_ldexp_f32 v131, v131, v132
	v_log_f32_e32 v131, v131
	s_nop 0
	v_mul_f32_e32 v132, 0x3f317217, v131
	v_fma_f32 v132, v131, s4, -v132
	v_fmac_f32_e32 v132, 0x3377d1cf, v131
	s_mov_b32 s4, 0x7f800000
	v_fmac_f32_e32 v132, 0x3f317217, v131
	v_cmp_lt_f32_e64 s[12:13], |v131|, s4
	s_nop 1
	v_cndmask_b32_e64 v131, v131, v132, s[12:13]
	v_cndmask_b32_e32 v132, 0, v227, vcc
	v_sub_f32_e32 v134, v131, v132

; DEV u16 f2bf(float f) { return (u16)(pack2(f, 0.f) & 0xffffu); }
; DEV void phase_win(const Params& P, int l, const u16* __restrict__ xb, const u16* __restrict__ Wt, u16* __restrict__ h, char* smem) {
;     ...
;         for (int j = 0; j < 4; ++j) {
;           int row = m0 + wm * 128 + ms * 16 + quad * 4 + j;
;           int col = cb + ns * 16 + l15;
;           float v = acc[ms][ns][j];
;           if (mode == 1) { float lbv = lbp[col - C_HF]; v = __logf(lbv + (1.f - lbv) / (1.f + __expf(-v))); }
;           else if (mode == 2) v = v / (1.f + __expf(-v));
;           h[(size_t)row * HS + col] = f2bf(v);
.LBB0_1441:
	s_andn2_b64 vcc, exec, s[4:5]
	s_cbranch_vccnz .LBB0_1444
	s_cmp_eq_u32 s17, 1
	v_mov_b32_e32 v134, v39
	s_cbranch_scc0 .LBB0_1444
	v_lshl_add_u64 v[134:135], v[0:1], 2, s[14:15]
	v_add_co_u32_e32 v134, vcc, 0xfffff000, v134
	s_nop 1
	v_addc_co_u32_e32 v135, vcc, -1, v135, vcc
	v_mov_b32_e32 v134, v160
	v_mul_f32_e32 v135, 0xbfb8aa3b, v39
	v_exp_f32_e32 v135, v135
	v_sub_f32_e32 v138, 1.0, v134
	v_add_f32_e32 v135, 1.0, v135
	v_div_scale_f32 v139, s[4:5], v135, v135, v138
	v_rcp_f32_e32 v140, v139
	v_div_scale_f32 v141, vcc, v138, v135, v138
	s_mov_b32 s4, 0x800000
	v_fma_f32 v142, -v139, v140, 1.0
	v_fmac_f32_e32 v140, v142, v140
	v_mul_f32_e32 v142, v141, v140
	v_fma_f32 v143, -v139, v142, v141
	v_fmac_f32_e32 v142, v143, v140
	v_fma_f32 v139, -v139, v142, v141
	v_div_fmas_f32 v139, v139, v140, v142
	v_div_fixup_f32 v135, v139, v135, v138
	v_add_f32_e32 v134, v134, v135
	v_cmp_gt_f32_e32 vcc, s4, v134
	s_mov_b32 s4, 0x3f317217
	s_nop 0
	v_cndmask_b32_e64 v135, 0, 32, vcc
	v_ldexp_f32 v134, v134, v135
	v_log_f32_e32 v134, v134
	s_nop 0
	v_mul_f32_e32 v135, 0x3f317217, v134
	v_fma_f32 v135, v134, s4, -v135
	v_fmac_f32_e32 v135, 0x3377d1cf, v134
	s_mov_b32 s4, 0x7f800000
	v_fmac_f32_e32 v135, 0x3f317217, v134
	v_cmp_lt_f32_e64 s[12:13], |v134|, s4
	s_nop 1
	v_cndmask_b32_e64 v134, v134, v135, s[12:13]
	v_cndmask_b32_e32 v135, 0, v227, vcc
	v_sub_f32_e32 v134, v134, v135

; DEV u16 f2bf(float f) { return (u16)(pack2(f, 0.f) & 0xffffu); }
; DEV void phase_win(const Params& P, int l, const u16* __restrict__ xb, const u16* __restrict__ Wt, u16* __restrict__ h, char* smem) {
;     ...
;         for (int j = 0; j < 4; ++j) {
;           int row = m0 + wm * 128 + ms * 16 + quad * 4 + j;
;           int col = cb + ns * 16 + l15;
;           float v = acc[ms][ns][j];
;           if (mode == 1) { float lbv = lbp[col - C_HF]; v = __logf(lbv + (1.f - lbv) / (1.f + __expf(-v))); }
;           else if (mode == 2) v = v / (1.f + __expf(-v));
;           h[(size_t)row * HS + col] = f2bf(v);
.LBB0_1446:
	s_andn2_b64 vcc, exec, s[4:5]
	s_cbranch_vccnz .LBB0_1449
	s_cmp_eq_u32 s17, 1
	v_mov_b32_e32 v134, v40
	s_cbranch_scc0 .LBB0_1449
	v_lshl_add_u64 v[134:135], v[0:1], 2, s[14:15]
	v_add_co_u32_e32 v134, vcc, 0xfffff000, v134
	s_nop 1
	v_addc_co_u32_e32 v135, vcc, -1, v135, vcc
	v_mov_b32_e32 v134, v160
	v_mul_f32_e32 v135, 0xbfb8aa3b, v40
	v_exp_f32_e32 v135, v135
	v_sub_f32_e32 v140, 1.0, v134
	v_add_f32_e32 v135, 1.0, v135
	v_div_scale_f32 v141, s[4:5], v135, v135, v140
	v_rcp_f32_e32 v142, v141
	v_div_scale_f32 v143, vcc, v140, v135, v140
	s_mov_b32 s4, 0x800000
	v_fma_f32 v144, -v141, v142, 1.0
	v_fmac_f32_e32 v142, v144, v142
	v_mul_f32_e32 v144, v143, v142
	v_fma_f32 v145, -v141, v144, v143
	v_fmac_f32_e32 v144, v145, v142
	v_fma_f32 v141, -v141, v144, v143
	v_div_fmas_f32 v141, v141, v142, v144
	v_div_fixup_f32 v135, v141, v135, v140
	v_add_f32_e32 v134, v134, v135
	v_cmp_gt_f32_e32 vcc, s4, v134
	s_mov_b32 s4, 0x3f317217
	s_nop 0
	v_cndmask_b32_e64 v135, 0, 32, vcc
	v_ldexp_f32 v134, v134, v135
	v_log_f32_e32 v134, v134
	s_nop 0
	v_mul_f32_e32 v135, 0x3f317217, v134
	v_fma_f32 v135, v134, s4, -v135
	v_fmac_f32_e32 v135, 0x3377d1cf, v134
	s_mov_b32 s4, 0x7f800000
	v_fmac_f32_e32 v135, 0x3f317217, v134
	v_cmp_lt_f32_e64 s[12:13], |v134|, s4
	s_nop 1
	v_cndmask_b32_e64 v134, v134, v135, s[12:13]
	v_cndmask_b32_e32 v135, 0, v227, vcc
	v_sub_f32_e32 v134, v134, v135

; DEV u16 f2bf(float f) { return (u16)(pack2(f, 0.f) & 0xffffu); }
; DEV void phase_win(const Params& P, int l, const u16* __restrict__ xb, const u16* __restrict__ Wt, u16* __restrict__ h, char* smem) {
;     ...
;         for (int j = 0; j < 4; ++j) {
;           int row = m0 + wm * 128 + ms * 16 + quad * 4 + j;
;           int col = cb + ns * 16 + l15;
;           float v = acc[ms][ns][j];
;           if (mode == 1) { float lbv = lbp[col - C_HF]; v = __logf(lbv + (1.f - lbv) / (1.f + __expf(-v))); }
;           else if (mode == 2) v = v / (1.f + __expf(-v));
;           h[(size_t)row * HS + col] = f2bf(v);
.LBB0_1451:
	s_andn2_b64 vcc, exec, s[4:5]
	s_cbranch_vccnz .LBB0_1454
	s_cmp_eq_u32 s17, 1
	v_mov_b32_e32 v134, v41
	s_cbranch_scc0 .LBB0_1454
	v_lshl_add_u64 v[134:135], v[0:1], 2, s[14:15]
	v_add_co_u32_e32 v134, vcc, 0xfffff000, v134
	s_nop 1
	v_addc_co_u32_e32 v135, vcc, -1, v135, vcc
	v_mov_b32_e32 v134, v160
	v_mul_f32_e32 v135, 0xbfb8aa3b, v41
	v_exp_f32_e32 v135, v135
	v_sub_f32_e32 v140, 1.0, v134
	v_add_f32_e32 v135, 1.0, v135
	v_div_scale_f32 v141, s[4:5], v135, v135, v140
	v_rcp_f32_e32 v142, v141
	v_div_scale_f32 v143, vcc, v140, v135, v140
	s_mov_b32 s4, 0x800000
	v_fma_f32 v146, -v141, v142, 1.0
	v_fmac_f32_e32 v142, v146, v142
	v_mul_f32_e32 v146, v143, v142
	v_fma_f32 v147, -v141, v146, v143
	v_fmac_f32_e32 v146, v147, v142
	v_fma_f32 v141, -v141, v146, v143
	v_div_fmas_f32 v141, v141, v142, v146
	v_div_fixup_f32 v135, v141, v135, v140
	v_add_f32_e32 v134, v134, v135
	v_cmp_gt_f32_e32 vcc, s4, v134
	s_mov_b32 s4, 0x3f317217
	s_nop 0
	v_cndmask_b32_e64 v135, 0, 32, vcc
	v_ldexp_f32 v134, v134, v135
	v_log_f32_e32 v134, v134
	s_nop 0
	v_mul_f32_e32 v135, 0x3f317217, v134
	v_fma_f32 v135, v134, s4, -v135
	v_fmac_f32_e32 v135, 0x3377d1cf, v134
	s_mov_b32 s4, 0x7f800000
	v_fmac_f32_e32 v135, 0x3f317217, v134
	v_cmp_lt_f32_e64 s[12:13], |v134|, s4
	s_nop 1
	v_cndmask_b32_e64 v134, v134, v135, s[12:13]
	v_cndmask_b32_e32 v135, 0, v227, vcc
	v_sub_f32_e32 v134, v134, v135

; DEV u16 f2bf(float f) { return (u16)(pack2(f, 0.f) & 0xffffu); }
; DEV void phase_win(const Params& P, int l, const u16* __restrict__ xb, const u16* __restrict__ Wt, u16* __restrict__ h, char* smem) {
;     ...
;         for (int j = 0; j < 4; ++j) {
;           int row = m0 + wm * 128 + ms * 16 + quad * 4 + j;
;           int col = cb + ns * 16 + l15;
;           float v = acc[ms][ns][j];
;           if (mode == 1) { float lbv = lbp[col - C_HF]; v = __logf(lbv + (1.f - lbv) / (1.f + __expf(-v))); }
;           else if (mode == 2) v = v / (1.f + __expf(-v));
;           h[(size_t)row * HS + col] = f2bf(v);
.LBB0_1456:
	s_andn2_b64 vcc, exec, s[4:5]
	s_cbranch_vccnz .LBB0_1459
	s_cmp_eq_u32 s17, 1
	v_mov_b32_e32 v131, v122
	s_cbranch_scc0 .LBB0_1459
	v_lshl_add_u64 v[134:135], v[0:1], 2, s[14:15]
	v_add_co_u32_e32 v134, vcc, 0xfffff000, v134
	s_nop 1
	v_addc_co_u32_e32 v135, vcc, -1, v135, vcc
	v_mov_b32_e32 v131, v161
	v_mul_f32_e32 v134, 0xbfb8aa3b, v122
	v_exp_f32_e32 v134, v134
	v_sub_f32_e32 v135, 1.0, v131
	v_add_f32_e32 v134, 1.0, v134
	v_div_scale_f32 v140, s[4:5], v134, v134, v135
	v_rcp_f32_e32 v141, v140
	v_div_scale_f32 v142, vcc, v135, v134, v135
	s_mov_b32 s4, 0x800000
	v_fma_f32 v143, -v140, v141, 1.0
	v_fmac_f32_e32 v141, v143, v141
	v_mul_f32_e32 v143, v142, v141
	v_fma_f32 v148, -v140, v143, v142
	v_fmac_f32_e32 v143, v148, v141
	v_fma_f32 v140, -v140, v143, v142
	v_div_fmas_f32 v140, v140, v141, v143
	v_div_fixup_f32 v134, v140, v134, v135
	v_add_f32_e32 v131, v131, v134
	v_cmp_gt_f32_e32 vcc, s4, v131
	s_mov_b32 s4, 0x3f317217
	s_nop 0
	v_cndmask_b32_e64 v134, 0, 32, vcc
	v_ldexp_f32 v131, v131, v134
	v_log_f32_e32 v131, v131
	s_nop 0
	v_mul_f32_e32 v134, 0x3f317217, v131
	v_fma_f32 v134, v131, s4, -v134
	v_fmac_f32_e32 v134, 0x3377d1cf, v131
	s_mov_b32 s4, 0x7f800000
	v_fmac_f32_e32 v134, 0x3f317217, v131
	v_cmp_lt_f32_e64 s[12:13], |v131|, s4
	s_nop 1
	v_cndmask_b32_e64 v131, v131, v134, s[12:13]
	v_cndmask_b32_e32 v134, 0, v227, vcc
	v_sub_f32_e32 v131, v131, v134

; DEV u16 f2bf(float f) { return (u16)(pack2(f, 0.f) & 0xffffu); }
; DEV void phase_win(const Params& P, int l, const u16* __restrict__ xb, const u16* __restrict__ Wt, u16* __restrict__ h, char* smem) {
;     ...
;         for (int j = 0; j < 4; ++j) {
;           int row = m0 + wm * 128 + ms * 16 + quad * 4 + j;
;           int col = cb + ns * 16 + l15;
;           float v = acc[ms][ns][j];
;           if (mode == 1) { float lbv = lbp[col - C_HF]; v = __logf(lbv + (1.f - lbv) / (1.f + __expf(-v))); }
;           else if (mode == 2) v = v / (1.f + __expf(-v));
;           h[(size_t)row * HS + col] = f2bf(v);
.LBB0_1461:
	s_andn2_b64 vcc, exec, s[4:5]
	s_cbranch_vccnz .LBB0_1464
	s_cmp_eq_u32 s17, 1
	v_mov_b32_e32 v131, v123
	s_cbranch_scc0 .LBB0_1464
	v_lshl_add_u64 v[136:137], v[0:1], 2, s[14:15]
	v_add_co_u32_e32 v136, vcc, 0xfffff000, v136
	s_nop 1
	v_addc_co_u32_e32 v137, vcc, -1, v137, vcc
	v_mov_b32_e32 v131, v161
	v_mul_f32_e32 v136, 0xbfb8aa3b, v123
	v_exp_f32_e32 v136, v136
	v_sub_f32_e32 v137, 1.0, v131
	v_add_f32_e32 v136, 1.0, v136
	v_div_scale_f32 v142, s[4:5], v136, v136, v137
	v_rcp_f32_e32 v143, v142
	v_div_scale_f32 v148, vcc, v137, v136, v137
	s_mov_b32 s4, 0x800000
	v_fma_f32 v149, -v142, v143, 1.0
	v_fmac_f32_e32 v143, v149, v143
	v_mul_f32_e32 v149, v148, v143
	v_fma_f32 v150, -v142, v149, v148
	v_fmac_f32_e32 v149, v150, v143
	v_fma_f32 v142, -v142, v149, v148
	v_div_fmas_f32 v142, v142, v143, v149
	v_div_fixup_f32 v136, v142, v136, v137
	v_add_f32_e32 v131, v131, v136
	v_cmp_gt_f32_e32 vcc, s4, v131
	s_mov_b32 s4, 0x3f317217
	s_nop 0
	v_cndmask_b32_e64 v136, 0, 32, vcc
	v_ldexp_f32 v131, v131, v136
	v_log_f32_e32 v131, v131
	s_nop 0
	v_mul_f32_e32 v136, 0x3f317217, v131
	v_fma_f32 v136, v131, s4, -v136
	v_fmac_f32_e32 v136, 0x3377d1cf, v131
	s_mov_b32 s4, 0x7f800000
	v_fmac_f32_e32 v136, 0x3f317217, v131
	v_cmp_lt_f32_e64 s[12:13], |v131|, s4
	s_nop 1
	v_cndmask_b32_e64 v131, v131, v136, s[12:13]
	v_cndmask_b32_e32 v136, 0, v227, vcc
	v_sub_f32_e32 v131, v131, v136

; DEV u16 f2bf(float f) { return (u16)(pack2(f, 0.f) & 0xffffu); }
; DEV void phase_win(const Params& P, int l, const u16* __restrict__ xb, const u16* __restrict__ Wt, u16* __restrict__ h, char* smem) {
;     ...
;         for (int j = 0; j < 4; ++j) {
;           int row = m0 + wm * 128 + ms * 16 + quad * 4 + j;
;           int col = cb + ns * 16 + l15;
;           float v = acc[ms][ns][j];
;           if (mode == 1) { float lbv = lbp[col - C_HF]; v = __logf(lbv + (1.f - lbv) / (1.f + __expf(-v))); }
;           else if (mode == 2) v = v / (1.f + __expf(-v));
;           h[(size_t)row * HS + col] = f2bf(v);
.LBB0_1466:
	s_andn2_b64 vcc, exec, s[4:5]
	s_cbranch_vccnz .LBB0_1469
	s_cmp_eq_u32 s17, 1
	v_mov_b32_e32 v131, v124
	s_cbranch_scc0 .LBB0_1469
	v_lshl_add_u64 v[136:137], v[0:1], 2, s[14:15]
	v_add_co_u32_e32 v136, vcc, 0xfffff000, v136
	s_nop 1
	v_addc_co_u32_e32 v137, vcc, -1, v137, vcc
	v_mov_b32_e32 v131, v161
	v_mul_f32_e32 v136, 0xbfb8aa3b, v124
	v_exp_f32_e32 v136, v136
	v_sub_f32_e32 v137, 1.0, v131
	v_add_f32_e32 v136, 1.0, v136
	v_div_scale_f32 v138, s[4:5], v136, v136, v137
	v_rcp_f32_e32 v139, v138
	v_div_scale_f32 v148, vcc, v137, v136, v137
	s_mov_b32 s4, 0x800000
	v_fma_f32 v149, -v138, v139, 1.0
	v_fmac_f32_e32 v139, v149, v139
	v_mul_f32_e32 v149, v148, v139
	v_fma_f32 v150, -v138, v149, v148
	v_fmac_f32_e32 v149, v150, v139
	v_fma_f32 v138, -v138, v149, v148
	v_div_fmas_f32 v138, v138, v139, v149
	v_div_fixup_f32 v136, v138, v136, v137
	v_add_f32_e32 v131, v131, v136
	v_cmp_gt_f32_e32 vcc, s4, v131
	s_mov_b32 s4, 0x3f317217
	s_nop 0
	v_cndmask_b32_e64 v136, 0, 32, vcc
	v_ldexp_f32 v131, v131, v136
	v_log_f32_e32 v131, v131
	s_nop 0
	v_mul_f32_e32 v136, 0x3f317217, v131
	v_fma_f32 v136, v131, s4, -v136
	v_fmac_f32_e32 v136, 0x3377d1cf, v131
	s_mov_b32 s4, 0x7f800000
	v_fmac_f32_e32 v136, 0x3f317217, v131
	v_cmp_lt_f32_e64 s[12:13], |v131|, s4
	s_nop 1
	v_cndmask_b32_e64 v131, v131, v136, s[12:13]
	v_cndmask_b32_e32 v136, 0, v227, vcc
	v_sub_f32_e32 v131, v131, v136

; DEV u16 f2bf(float f) { return (u16)(pack2(f, 0.f) & 0xffffu); }
; DEV void phase_win(const Params& P, int l, const u16* __restrict__ xb, const u16* __restrict__ Wt, u16* __restrict__ h, char* smem) {
;     ...
;         for (int j = 0; j < 4; ++j) {
;           int row = m0 + wm * 128 + ms * 16 + quad * 4 + j;
;           int col = cb + ns * 16 + l15;
;           float v = acc[ms][ns][j];
;           if (mode == 1) { float lbv = lbp[col - C_HF]; v = __logf(lbv + (1.f - lbv) / (1.f + __expf(-v))); }
;           else if (mode == 2) v = v / (1.f + __expf(-v));
;           h[(size_t)row * HS + col] = f2bf(v);
.LBB0_1471:
	s_andn2_b64 vcc, exec, s[4:5]
	s_cbranch_vccnz .LBB0_1474
	s_cmp_eq_u32 s17, 1
	v_mov_b32_e32 v131, v125
	s_cbranch_scc0 .LBB0_1474
	v_lshl_add_u64 v[136:137], v[0:1], 2, s[14:15]
	v_add_co_u32_e32 v136, vcc, 0xfffff000, v136
	s_nop 1
	v_addc_co_u32_e32 v137, vcc, -1, v137, vcc
	v_mov_b32_e32 v131, v161
	v_mul_f32_e32 v136, 0xbfb8aa3b, v125
	v_exp_f32_e32 v136, v136
	v_sub_f32_e32 v137, 1.0, v131
	v_add_f32_e32 v136, 1.0, v136
	v_div_scale_f32 v138, s[4:5], v136, v136, v137
	v_rcp_f32_e32 v139, v138
	v_div_scale_f32 v148, vcc, v137, v136, v137
	s_mov_b32 s4, 0x800000
	v_fma_f32 v149, -v138, v139, 1.0
	v_fmac_f32_e32 v139, v149, v139
	v_mul_f32_e32 v149, v148, v139
	v_fma_f32 v150, -v138, v149, v148
	v_fmac_f32_e32 v149, v150, v139
	v_fma_f32 v138, -v138, v149, v148
	v_div_fmas_f32 v138, v138, v139, v149
	v_div_fixup_f32 v136, v138, v136, v137
	v_add_f32_e32 v131, v131, v136
	v_cmp_gt_f32_e32 vcc, s4, v131
	s_mov_b32 s4, 0x3f317217
	s_nop 0
	v_cndmask_b32_e64 v136, 0, 32, vcc
	v_ldexp_f32 v131, v131, v136
	v_log_f32_e32 v131, v131
	s_nop 0
	v_mul_f32_e32 v136, 0x3f317217, v131
	v_fma_f32 v136, v131, s4, -v136
	v_fmac_f32_e32 v136, 0x3377d1cf, v131
	s_mov_b32 s4, 0x7f800000
	v_fmac_f32_e32 v136, 0x3f317217, v131
	v_cmp_lt_f32_e64 s[12:13], |v131|, s4
	s_nop 1
	v_cndmask_b32_e64 v131, v131, v136, s[12:13]
	v_cndmask_b32_e32 v136, 0, v227, vcc
	v_sub_f32_e32 v131, v131, v136

; DEV u16 f2bf(float f) { return (u16)(pack2(f, 0.f) & 0xffffu); }
; DEV void phase_win(const Params& P, int l, const u16* __restrict__ xb, const u16* __restrict__ Wt, u16* __restrict__ h, char* smem) {
;     ...
;         for (int j = 0; j < 4; ++j) {
;           int row = m0 + wm * 128 + ms * 16 + quad * 4 + j;
;           int col = cb + ns * 16 + l15;
;           float v = acc[ms][ns][j];
;           if (mode == 1) { float lbv = lbp[col - C_HF]; v = __logf(lbv + (1.f - lbv) / (1.f + __expf(-v))); }
;           else if (mode == 2) v = v / (1.f + __expf(-v));
;           h[(size_t)row * HS + col] = f2bf(v);
.LBB0_1476:
	s_andn2_b64 vcc, exec, s[4:5]
	s_cbranch_vccnz .LBB0_1479
	s_cmp_eq_u32 s17, 1
	v_mov_b32_e32 v131, v126
	s_cbranch_scc0 .LBB0_1479
	v_lshl_add_u64 v[136:137], v[0:1], 2, s[14:15]
	v_add_co_u32_e32 v136, vcc, 0xfffff000, v136
	s_nop 1
	v_addc_co_u32_e32 v137, vcc, -1, v137, vcc
	v_mov_b32_e32 v131, v162
	v_mul_f32_e32 v136, 0xbfb8aa3b, v126
	v_exp_f32_e32 v136, v136
	v_sub_f32_e32 v137, 1.0, v131
	v_add_f32_e32 v136, 1.0, v136
	v_div_scale_f32 v138, s[4:5], v136, v136, v137
	v_rcp_f32_e32 v139, v138
	v_div_scale_f32 v148, vcc, v137, v136, v137
	s_mov_b32 s4, 0x800000
	v_fma_f32 v149, -v138, v139, 1.0
	v_fmac_f32_e32 v139, v149, v139
	v_mul_f32_e32 v149, v148, v139
	v_fma_f32 v150, -v138, v149, v148
	v_fmac_f32_e32 v149, v150, v139
	v_fma_f32 v138, -v138, v149, v148
	v_div_fmas_f32 v138, v138, v139, v149
	v_div_fixup_f32 v136, v138, v136, v137
	v_add_f32_e32 v131, v131, v136
	v_cmp_gt_f32_e32 vcc, s4, v131
	s_mov_b32 s4, 0x3f317217
	s_nop 0
	v_cndmask_b32_e64 v136, 0, 32, vcc
	v_ldexp_f32 v131, v131, v136
	v_log_f32_e32 v131, v131
	s_nop 0
	v_mul_f32_e32 v136, 0x3f317217, v131
	v_fma_f32 v136, v131, s4, -v136
	v_fmac_f32_e32 v136, 0x3377d1cf, v131
	s_mov_b32 s4, 0x7f800000
	v_fmac_f32_e32 v136, 0x3f317217, v131
	v_cmp_lt_f32_e64 s[12:13], |v131|, s4
	s_nop 1
	v_cndmask_b32_e64 v131, v131, v136, s[12:13]
	v_cndmask_b32_e32 v136, 0, v227, vcc
	v_sub_f32_e32 v131, v131, v136

; DEV u16 f2bf(float f) { return (u16)(pack2(f, 0.f) & 0xffffu); }
; DEV void phase_win(const Params& P, int l, const u16* __restrict__ xb, const u16* __restrict__ Wt, u16* __restrict__ h, char* smem) {
;     ...
;         for (int j = 0; j < 4; ++j) {
;           int row = m0 + wm * 128 + ms * 16 + quad * 4 + j;
;           int col = cb + ns * 16 + l15;
;           float v = acc[ms][ns][j];
;           if (mode == 1) { float lbv = lbp[col - C_HF]; v = __logf(lbv + (1.f - lbv) / (1.f + __expf(-v))); }
;           else if (mode == 2) v = v / (1.f + __expf(-v));
;           h[(size_t)row * HS + col] = f2bf(v);
.LBB0_1481:
	s_andn2_b64 vcc, exec, s[4:5]
	s_cbranch_vccnz .LBB0_1484
	s_cmp_eq_u32 s17, 1
	v_mov_b32_e32 v131, v127
	s_cbranch_scc0 .LBB0_1484
	v_lshl_add_u64 v[138:139], v[0:1], 2, s[14:15]
	v_add_co_u32_e32 v138, vcc, 0xfffff000, v138
	s_nop 1
	v_addc_co_u32_e32 v139, vcc, -1, v139, vcc
	v_mov_b32_e32 v131, v162
	v_mul_f32_e32 v138, 0xbfb8aa3b, v127
	v_exp_f32_e32 v138, v138
	v_sub_f32_e32 v139, 1.0, v131
	v_add_f32_e32 v138, 1.0, v138
	v_div_scale_f32 v148, s[4:5], v138, v138, v139
	v_rcp_f32_e32 v149, v148
	v_div_scale_f32 v150, vcc, v139, v138, v139
	s_mov_b32 s4, 0x800000
	v_fma_f32 v151, -v148, v149, 1.0
	v_fmac_f32_e32 v149, v151, v149
	v_mul_f32_e32 v151, v150, v149
	v_fma_f32 v152, -v148, v151, v150
	v_fmac_f32_e32 v151, v152, v149
	v_fma_f32 v148, -v148, v151, v150
	v_div_fmas_f32 v148, v148, v149, v151
	v_div_fixup_f32 v138, v148, v138, v139
	v_add_f32_e32 v131, v131, v138
	v_cmp_gt_f32_e32 vcc, s4, v131
	s_mov_b32 s4, 0x3f317217
	s_nop 0
	v_cndmask_b32_e64 v138, 0, 32, vcc
	v_ldexp_f32 v131, v131, v138
	v_log_f32_e32 v131, v131
	s_nop 0
	v_mul_f32_e32 v138, 0x3f317217, v131
	v_fma_f32 v138, v131, s4, -v138
	v_fmac_f32_e32 v138, 0x3377d1cf, v131
	s_mov_b32 s4, 0x7f800000
	v_fmac_f32_e32 v138, 0x3f317217, v131
	v_cmp_lt_f32_e64 s[12:13], |v131|, s4
	s_nop 1
	v_cndmask_b32_e64 v131, v131, v138, s[12:13]
	v_cndmask_b32_e32 v138, 0, v227, vcc
	v_sub_f32_e32 v131, v131, v138

; DEV u16 f2bf(float f) { return (u16)(pack2(f, 0.f) & 0xffffu); }
; DEV void phase_win(const Params& P, int l, const u16* __restrict__ xb, const u16* __restrict__ Wt, u16* __restrict__ h, char* smem) {
;     ...
;         for (int j = 0; j < 4; ++j) {
;           int row = m0 + wm * 128 + ms * 16 + quad * 4 + j;
;           int col = cb + ns * 16 + l15;
;           float v = acc[ms][ns][j];
;           if (mode == 1) { float lbv = lbp[col - C_HF]; v = __logf(lbv + (1.f - lbv) / (1.f + __expf(-v))); }
;           else if (mode == 2) v = v / (1.f + __expf(-v));
;           h[(size_t)row * HS + col] = f2bf(v);
.LBB0_1486:
	s_andn2_b64 vcc, exec, s[4:5]
	s_cbranch_vccnz .LBB0_1489
	s_cmp_eq_u32 s17, 1
	v_mov_b32_e32 v131, v128
	s_cbranch_scc0 .LBB0_1489
	v_lshl_add_u64 v[138:139], v[0:1], 2, s[14:15]
	v_add_co_u32_e32 v138, vcc, 0xfffff000, v138
	s_nop 1
	v_addc_co_u32_e32 v139, vcc, -1, v139, vcc
	v_mov_b32_e32 v131, v162
	v_mul_f32_e32 v138, 0xbfb8aa3b, v128
	v_exp_f32_e32 v138, v138
	v_sub_f32_e32 v139, 1.0, v131
	v_add_f32_e32 v138, 1.0, v138
	v_div_scale_f32 v148, s[4:5], v138, v138, v139
	v_rcp_f32_e32 v149, v148
	v_div_scale_f32 v150, vcc, v139, v138, v139
	s_mov_b32 s4, 0x800000
	v_fma_f32 v151, -v148, v149, 1.0
	v_fmac_f32_e32 v149, v151, v149
	v_mul_f32_e32 v151, v150, v149
	v_fma_f32 v152, -v148, v151, v150
	v_fmac_f32_e32 v151, v152, v149
	v_fma_f32 v148, -v148, v151, v150
	v_div_fmas_f32 v148, v148, v149, v151
	v_div_fixup_f32 v138, v148, v138, v139
	v_add_f32_e32 v131, v131, v138
	v_cmp_gt_f32_e32 vcc, s4, v131
	s_mov_b32 s4, 0x3f317217
	s_nop 0
	v_cndmask_b32_e64 v138, 0, 32, vcc
	v_ldexp_f32 v131, v131, v138
	v_log_f32_e32 v131, v131
	s_nop 0
	v_mul_f32_e32 v138, 0x3f317217, v131
	v_fma_f32 v138, v131, s4, -v138
	v_fmac_f32_e32 v138, 0x3377d1cf, v131
	s_mov_b32 s4, 0x7f800000
	v_fmac_f32_e32 v138, 0x3f317217, v131
	v_cmp_lt_f32_e64 s[12:13], |v131|, s4
	s_nop 1
	v_cndmask_b32_e64 v131, v131, v138, s[12:13]
	v_cndmask_b32_e32 v138, 0, v227, vcc
	v_sub_f32_e32 v131, v131, v138

; DEV u16 f2bf(float f) { return (u16)(pack2(f, 0.f) & 0xffffu); }
; DEV void phase_win(const Params& P, int l, const u16* __restrict__ xb, const u16* __restrict__ Wt, u16* __restrict__ h, char* smem) {
;     ...
;         for (int j = 0; j < 4; ++j) {
;           int row = m0 + wm * 128 + ms * 16 + quad * 4 + j;
;           int col = cb + ns * 16 + l15;
;           float v = acc[ms][ns][j];
;           if (mode == 1) { float lbv = lbp[col - C_HF]; v = __logf(lbv + (1.f - lbv) / (1.f + __expf(-v))); }
;           else if (mode == 2) v = v / (1.f + __expf(-v));
;           h[(size_t)row * HS + col] = f2bf(v);
.LBB0_1491:
	s_andn2_b64 vcc, exec, s[4:5]
	s_cbranch_vccnz .LBB0_1494
	s_cmp_eq_u32 s17, 1
	v_mov_b32_e32 v131, v129
	s_cbranch_scc0 .LBB0_1494
	v_lshl_add_u64 v[138:139], v[0:1], 2, s[14:15]
	v_add_co_u32_e32 v138, vcc, 0xfffff000, v138
	s_nop 1
	v_addc_co_u32_e32 v139, vcc, -1, v139, vcc
	v_mov_b32_e32 v131, v162
	v_mul_f32_e32 v138, 0xbfb8aa3b, v129
	v_exp_f32_e32 v138, v138
	v_sub_f32_e32 v139, 1.0, v131
	v_add_f32_e32 v138, 1.0, v138
	v_div_scale_f32 v148, s[4:5], v138, v138, v139
	v_rcp_f32_e32 v149, v148
	v_div_scale_f32 v150, vcc, v139, v138, v139
	s_mov_b32 s4, 0x800000
	v_fma_f32 v151, -v148, v149, 1.0
	v_fmac_f32_e32 v149, v151, v149
	v_mul_f32_e32 v151, v150, v149
	v_fma_f32 v152, -v148, v151, v150
	v_fmac_f32_e32 v151, v152, v149
	v_fma_f32 v148, -v148, v151, v150
	v_div_fmas_f32 v148, v148, v149, v151
	v_div_fixup_f32 v138, v148, v138, v139
	v_add_f32_e32 v131, v131, v138
	v_cmp_gt_f32_e32 vcc, s4, v131
	s_mov_b32 s4, 0x3f317217
	s_nop 0
	v_cndmask_b32_e64 v138, 0, 32, vcc
	v_ldexp_f32 v131, v131, v138
	v_log_f32_e32 v131, v131
	s_nop 0
	v_mul_f32_e32 v138, 0x3f317217, v131
	v_fma_f32 v138, v131, s4, -v138
	v_fmac_f32_e32 v138, 0x3377d1cf, v131
	s_mov_b32 s4, 0x7f800000
	v_fmac_f32_e32 v138, 0x3f317217, v131
	v_cmp_lt_f32_e64 s[12:13], |v131|, s4
	s_nop 1
	v_cndmask_b32_e64 v131, v131, v138, s[12:13]
	v_cndmask_b32_e32 v138, 0, v227, vcc
	v_sub_f32_e32 v131, v131, v138

; DEV u16 f2bf(float f) { return (u16)(pack2(f, 0.f) & 0xffffu); }
; DEV void phase_win(const Params& P, int l, const u16* __restrict__ xb, const u16* __restrict__ Wt, u16* __restrict__ h, char* smem) {
;     ...
;         for (int j = 0; j < 4; ++j) {
;           int row = m0 + wm * 128 + ms * 16 + quad * 4 + j;
;           int col = cb + ns * 16 + l15;
;           float v = acc[ms][ns][j];
;           if (mode == 1) { float lbv = lbp[col - C_HF]; v = __logf(lbv + (1.f - lbv) / (1.f + __expf(-v))); }
;           else if (mode == 2) v = v / (1.f + __expf(-v));
;           h[(size_t)row * HS + col] = f2bf(v);
.LBB0_1496:
	s_andn2_b64 vcc, exec, s[4:5]
	s_cbranch_vccnz .LBB0_1499
	s_cmp_eq_u32 s17, 1
	v_mov_b32_e32 v131, v118
	s_cbranch_scc0 .LBB0_1499
	v_lshl_add_u64 v[138:139], v[0:1], 2, s[14:15]
	v_add_co_u32_e32 v138, vcc, 0xfffff000, v138
	s_nop 1
	v_addc_co_u32_e32 v139, vcc, -1, v139, vcc
	v_mov_b32_e32 v131, v163
	v_mul_f32_e32 v138, 0xbfb8aa3b, v118
	v_exp_f32_e32 v138, v138
	v_sub_f32_e32 v139, 1.0, v131
	v_add_f32_e32 v138, 1.0, v138
	v_div_scale_f32 v148, s[4:5], v138, v138, v139
	v_rcp_f32_e32 v149, v148
	v_div_scale_f32 v150, vcc, v139, v138, v139
	s_mov_b32 s4, 0x800000
	v_fma_f32 v151, -v148, v149, 1.0
	v_fmac_f32_e32 v149, v151, v149
	v_mul_f32_e32 v151, v150, v149
	v_fma_f32 v152, -v148, v151, v150
	v_fmac_f32_e32 v151, v152, v149
	v_fma_f32 v148, -v148, v151, v150
	v_div_fmas_f32 v148, v148, v149, v151
	v_div_fixup_f32 v138, v148, v138, v139
	v_add_f32_e32 v131, v131, v138
	v_cmp_gt_f32_e32 vcc, s4, v131
	s_mov_b32 s4, 0x3f317217
	s_nop 0
	v_cndmask_b32_e64 v138, 0, 32, vcc
	v_ldexp_f32 v131, v131, v138
	v_log_f32_e32 v131, v131
	s_nop 0
	v_mul_f32_e32 v138, 0x3f317217, v131
	v_fma_f32 v138, v131, s4, -v138
	v_fmac_f32_e32 v138, 0x3377d1cf, v131
	s_mov_b32 s4, 0x7f800000
	v_fmac_f32_e32 v138, 0x3f317217, v131
	v_cmp_lt_f32_e64 s[12:13], |v131|, s4
	s_nop 1
	v_cndmask_b32_e64 v131, v131, v138, s[12:13]
	v_cndmask_b32_e32 v138, 0, v227, vcc
	v_sub_f32_e32 v131, v131, v138

; DEV u16 f2bf(float f) { return (u16)(pack2(f, 0.f) & 0xffffu); }
; DEV void phase_win(const Params& P, int l, const u16* __restrict__ xb, const u16* __restrict__ Wt, u16* __restrict__ h, char* smem) {
;     ...
;         for (int j = 0; j < 4; ++j) {
;           int row = m0 + wm * 128 + ms * 16 + quad * 4 + j;
;           int col = cb + ns * 16 + l15;
;           float v = acc[ms][ns][j];
;           if (mode == 1) { float lbv = lbp[col - C_HF]; v = __logf(lbv + (1.f - lbv) / (1.f + __expf(-v))); }
;           else if (mode == 2) v = v / (1.f + __expf(-v));
;           h[(size_t)row * HS + col] = f2bf(v);
.LBB0_1501:
	s_andn2_b64 vcc, exec, s[4:5]
	s_cbranch_vccnz .LBB0_1504
	s_cmp_eq_u32 s17, 1
	v_mov_b32_e32 v131, v119
	s_cbranch_scc0 .LBB0_1504
	v_lshl_add_u64 v[140:141], v[0:1], 2, s[14:15]
	v_add_co_u32_e32 v140, vcc, 0xfffff000, v140
	s_nop 1
	v_addc_co_u32_e32 v141, vcc, -1, v141, vcc
	v_mov_b32_e32 v131, v163
	v_mul_f32_e32 v140, 0xbfb8aa3b, v119
	v_exp_f32_e32 v140, v140
	v_sub_f32_e32 v141, 1.0, v131
	v_add_f32_e32 v140, 1.0, v140
	v_div_scale_f32 v148, s[4:5], v140, v140, v141
	v_rcp_f32_e32 v149, v148
	v_div_scale_f32 v150, vcc, v141, v140, v141
	s_mov_b32 s4, 0x800000
	v_fma_f32 v151, -v148, v149, 1.0
	v_fmac_f32_e32 v149, v151, v149
	v_mul_f32_e32 v151, v150, v149
	v_fma_f32 v152, -v148, v151, v150
	v_fmac_f32_e32 v151, v152, v149
	v_fma_f32 v148, -v148, v151, v150
	v_div_fmas_f32 v148, v148, v149, v151
	v_div_fixup_f32 v140, v148, v140, v141
	v_add_f32_e32 v131, v131, v140
	v_cmp_gt_f32_e32 vcc, s4, v131
	s_mov_b32 s4, 0x3f317217
	s_nop 0
	v_cndmask_b32_e64 v140, 0, 32, vcc
	v_ldexp_f32 v131, v131, v140
	v_log_f32_e32 v131, v131
	s_nop 0
	v_mul_f32_e32 v140, 0x3f317217, v131
	v_fma_f32 v140, v131, s4, -v140
	v_fmac_f32_e32 v140, 0x3377d1cf, v131
	s_mov_b32 s4, 0x7f800000
	v_fmac_f32_e32 v140, 0x3f317217, v131
	v_cmp_lt_f32_e64 s[12:13], |v131|, s4
	s_nop 1
	v_cndmask_b32_e64 v131, v131, v140, s[12:13]
	v_cndmask_b32_e32 v140, 0, v227, vcc
	v_sub_f32_e32 v131, v131, v140

; DEV u16 f2bf(float f) { return (u16)(pack2(f, 0.f) & 0xffffu); }
; DEV void phase_win(const Params& P, int l, const u16* __restrict__ xb, const u16* __restrict__ Wt, u16* __restrict__ h, char* smem) {
;     ...
;         for (int j = 0; j < 4; ++j) {
;           int row = m0 + wm * 128 + ms * 16 + quad * 4 + j;
;           int col = cb + ns * 16 + l15;
;           float v = acc[ms][ns][j];
;           if (mode == 1) { float lbv = lbp[col - C_HF]; v = __logf(lbv + (1.f - lbv) / (1.f + __expf(-v))); }
;           else if (mode == 2) v = v / (1.f + __expf(-v));
;           h[(size_t)row * HS + col] = f2bf(v);
.LBB0_1506:
	s_andn2_b64 vcc, exec, s[4:5]
	s_cbranch_vccnz .LBB0_1509
	s_cmp_eq_u32 s17, 1
	v_mov_b32_e32 v131, v120
	s_cbranch_scc0 .LBB0_1509
	v_lshl_add_u64 v[140:141], v[0:1], 2, s[14:15]
	v_add_co_u32_e32 v140, vcc, 0xfffff000, v140
	s_nop 1
	v_addc_co_u32_e32 v141, vcc, -1, v141, vcc
	v_mov_b32_e32 v131, v163
	v_mul_f32_e32 v140, 0xbfb8aa3b, v120
	v_exp_f32_e32 v140, v140
	v_sub_f32_e32 v141, 1.0, v131
	v_add_f32_e32 v140, 1.0, v140
	v_div_scale_f32 v142, s[4:5], v140, v140, v141
	v_rcp_f32_e32 v143, v142
	v_div_scale_f32 v148, vcc, v141, v140, v141
	s_mov_b32 s4, 0x800000
	v_fma_f32 v149, -v142, v143, 1.0
	v_fmac_f32_e32 v143, v149, v143
	v_mul_f32_e32 v149, v148, v143
	v_fma_f32 v150, -v142, v149, v148
	v_fmac_f32_e32 v149, v150, v143
	v_fma_f32 v142, -v142, v149, v148
	v_div_fmas_f32 v142, v142, v143, v149
	v_div_fixup_f32 v140, v142, v140, v141
	v_add_f32_e32 v131, v131, v140
	v_cmp_gt_f32_e32 vcc, s4, v131
	s_mov_b32 s4, 0x3f317217
	s_nop 0
	v_cndmask_b32_e64 v140, 0, 32, vcc
	v_ldexp_f32 v131, v131, v140
	v_log_f32_e32 v131, v131
	s_nop 0
	v_mul_f32_e32 v140, 0x3f317217, v131
	v_fma_f32 v140, v131, s4, -v140
	v_fmac_f32_e32 v140, 0x3377d1cf, v131
	s_mov_b32 s4, 0x7f800000
	v_fmac_f32_e32 v140, 0x3f317217, v131
	v_cmp_lt_f32_e64 s[12:13], |v131|, s4
	s_nop 1
	v_cndmask_b32_e64 v131, v131, v140, s[12:13]
	v_cndmask_b32_e32 v140, 0, v227, vcc
	v_sub_f32_e32 v131, v131, v140

; DEV u16 f2bf(float f) { return (u16)(pack2(f, 0.f) & 0xffffu); }
; DEV void phase_win(const Params& P, int l, const u16* __restrict__ xb, const u16* __restrict__ Wt, u16* __restrict__ h, char* smem) {
;     ...
;         for (int j = 0; j < 4; ++j) {
;           int row = m0 + wm * 128 + ms * 16 + quad * 4 + j;
;           int col = cb + ns * 16 + l15;
;           float v = acc[ms][ns][j];
;           if (mode == 1) { float lbv = lbp[col - C_HF]; v = __logf(lbv + (1.f - lbv) / (1.f + __expf(-v))); }
;           else if (mode == 2) v = v / (1.f + __expf(-v));
;           h[(size_t)row * HS + col] = f2bf(v);
.LBB0_1511:
	s_andn2_b64 vcc, exec, s[4:5]
	s_cbranch_vccnz .LBB0_1514
	s_cmp_eq_u32 s17, 1
	v_mov_b32_e32 v131, v121
	s_cbranch_scc0 .LBB0_1514
	v_lshl_add_u64 v[140:141], v[0:1], 2, s[14:15]
	v_add_co_u32_e32 v140, vcc, 0xfffff000, v140
	s_nop 1
	v_addc_co_u32_e32 v141, vcc, -1, v141, vcc
	v_mov_b32_e32 v131, v163
	v_mul_f32_e32 v140, 0xbfb8aa3b, v121
	v_exp_f32_e32 v140, v140
	v_sub_f32_e32 v141, 1.0, v131
	v_add_f32_e32 v140, 1.0, v140
	v_div_scale_f32 v142, s[4:5], v140, v140, v141
	v_rcp_f32_e32 v143, v142
	v_div_scale_f32 v144, vcc, v141, v140, v141
	s_mov_b32 s4, 0x800000
	v_fma_f32 v145, -v142, v143, 1.0
	v_fmac_f32_e32 v143, v145, v143
	v_mul_f32_e32 v145, v144, v143
	v_fma_f32 v148, -v142, v145, v144
	v_fmac_f32_e32 v145, v148, v143
	v_fma_f32 v142, -v142, v145, v144
	v_div_fmas_f32 v142, v142, v143, v145
	v_div_fixup_f32 v140, v142, v140, v141
	v_add_f32_e32 v131, v131, v140
	v_cmp_gt_f32_e32 vcc, s4, v131
	s_mov_b32 s4, 0x3f317217
	s_nop 0
	v_cndmask_b32_e64 v140, 0, 32, vcc
	v_ldexp_f32 v131, v131, v140
	v_log_f32_e32 v131, v131
	s_nop 0
	v_mul_f32_e32 v140, 0x3f317217, v131
	v_fma_f32 v140, v131, s4, -v140
	v_fmac_f32_e32 v140, 0x3377d1cf, v131
	s_mov_b32 s4, 0x7f800000
	v_fmac_f32_e32 v140, 0x3f317217, v131
	v_cmp_lt_f32_e64 s[12:13], |v131|, s4
	s_nop 1
	v_cndmask_b32_e64 v131, v131, v140, s[12:13]
	v_cndmask_b32_e32 v140, 0, v227, vcc
	v_sub_f32_e32 v131, v131, v140

; DEV u16 f2bf(float f) { return (u16)(pack2(f, 0.f) & 0xffffu); }
; DEV void phase_win(const Params& P, int l, const u16* __restrict__ xb, const u16* __restrict__ Wt, u16* __restrict__ h, char* smem) {
;     ...
;         for (int j = 0; j < 4; ++j) {
;           int row = m0 + wm * 128 + ms * 16 + quad * 4 + j;
;           int col = cb + ns * 16 + l15;
;           float v = acc[ms][ns][j];
;           if (mode == 1) { float lbv = lbp[col - C_HF]; v = __logf(lbv + (1.f - lbv) / (1.f + __expf(-v))); }
;           else if (mode == 2) v = v / (1.f + __expf(-v));
;           h[(size_t)row * HS + col] = f2bf(v);
.LBB0_1516:
	s_andn2_b64 vcc, exec, s[4:5]
	s_cbranch_vccnz .LBB0_1519
	s_cmp_eq_u32 s17, 1
	v_mov_b32_e32 v140, v26
	s_cbranch_scc0 .LBB0_1519
	v_lshl_add_u64 v[140:141], v[0:1], 2, s[14:15]
	v_add_co_u32_e32 v140, vcc, 0xfffff000, v140
	s_nop 1
	v_addc_co_u32_e32 v141, vcc, -1, v141, vcc
	v_mov_b32_e32 v131, v160
	v_mul_f32_e32 v140, 0xbfb8aa3b, v26
	v_exp_f32_e32 v140, v140
	v_sub_f32_e32 v141, 1.0, v131
	v_add_f32_e32 v140, 1.0, v140
	v_div_scale_f32 v142, s[4:5], v140, v140, v141
	v_rcp_f32_e32 v143, v142
	v_div_scale_f32 v144, vcc, v141, v140, v141
	s_mov_b32 s4, 0x800000
	v_fma_f32 v145, -v142, v143, 1.0
	v_fmac_f32_e32 v143, v145, v143
	v_mul_f32_e32 v145, v144, v143
	v_fma_f32 v146, -v142, v145, v144
	v_fmac_f32_e32 v145, v146, v143
	v_fma_f32 v142, -v142, v145, v144
	v_div_fmas_f32 v142, v142, v143, v145
	v_div_fixup_f32 v140, v142, v140, v141
	v_add_f32_e32 v131, v131, v140
	v_cmp_gt_f32_e32 vcc, s4, v131
	s_mov_b32 s4, 0x3f317217
	s_nop 0
	v_cndmask_b32_e64 v140, 0, 32, vcc
	v_ldexp_f32 v131, v131, v140
	v_log_f32_e32 v131, v131
	s_nop 0
	v_mul_f32_e32 v140, 0x3f317217, v131
	v_fma_f32 v140, v131, s4, -v140
	v_fmac_f32_e32 v140, 0x3377d1cf, v131
	s_mov_b32 s4, 0x7f800000
	v_fmac_f32_e32 v140, 0x3f317217, v131
	v_cmp_lt_f32_e64 s[12:13], |v131|, s4
	s_nop 1
	v_cndmask_b32_e64 v131, v131, v140, s[12:13]
	v_cndmask_b32_e32 v140, 0, v227, vcc
	v_sub_f32_e32 v140, v131, v140

; DEV u16 f2bf(float f) { return (u16)(pack2(f, 0.f) & 0xffffu); }
; DEV void phase_win(const Params& P, int l, const u16* __restrict__ xb, const u16* __restrict__ Wt, u16* __restrict__ h, char* smem) {
;     ...
;         for (int j = 0; j < 4; ++j) {
;           int row = m0 + wm * 128 + ms * 16 + quad * 4 + j;
;           int col = cb + ns * 16 + l15;
;           float v = acc[ms][ns][j];
;           if (mode == 1) { float lbv = lbp[col - C_HF]; v = __logf(lbv + (1.f - lbv) / (1.f + __expf(-v))); }
;           else if (mode == 2) v = v / (1.f + __expf(-v));
;           h[(size_t)row * HS + col] = f2bf(v);
.LBB0_1521:
	s_andn2_b64 vcc, exec, s[4:5]
	s_cbranch_vccnz .LBB0_1524
	s_cmp_eq_u32 s17, 1
	v_mov_b32_e32 v142, v27
	s_cbranch_scc0 .LBB0_1524
	v_lshl_add_u64 v[142:143], v[0:1], 2, s[14:15]
	v_add_co_u32_e32 v142, vcc, 0xfffff000, v142
	s_nop 1
	v_addc_co_u32_e32 v143, vcc, -1, v143, vcc
	v_mov_b32_e32 v142, v160
	v_mul_f32_e32 v143, 0xbfb8aa3b, v27
	v_exp_f32_e32 v143, v143
	v_sub_f32_e32 v144, 1.0, v142
	v_add_f32_e32 v143, 1.0, v143
	v_div_scale_f32 v145, s[4:5], v143, v143, v144
	v_rcp_f32_e32 v146, v145
	v_div_scale_f32 v147, vcc, v144, v143, v144
	s_mov_b32 s4, 0x800000
	v_fma_f32 v148, -v145, v146, 1.0
	v_fmac_f32_e32 v146, v148, v146
	v_mul_f32_e32 v148, v147, v146
	v_fma_f32 v149, -v145, v148, v147
	v_fmac_f32_e32 v148, v149, v146
	v_fma_f32 v145, -v145, v148, v147
	v_div_fmas_f32 v145, v145, v146, v148
	v_div_fixup_f32 v143, v145, v143, v144
	v_add_f32_e32 v142, v142, v143
	v_cmp_gt_f32_e32 vcc, s4, v142
	s_mov_b32 s4, 0x3f317217
	s_nop 0
	v_cndmask_b32_e64 v143, 0, 32, vcc
	v_ldexp_f32 v142, v142, v143
	v_log_f32_e32 v142, v142
	s_nop 0
	v_mul_f32_e32 v143, 0x3f317217, v142
	v_fma_f32 v143, v142, s4, -v143
	v_fmac_f32_e32 v143, 0x3377d1cf, v142
	s_mov_b32 s4, 0x7f800000
	v_fmac_f32_e32 v143, 0x3f317217, v142
	v_cmp_lt_f32_e64 s[12:13], |v142|, s4
	s_nop 1
	v_cndmask_b32_e64 v142, v142, v143, s[12:13]
	v_cndmask_b32_e32 v143, 0, v227, vcc
	v_sub_f32_e32 v142, v142, v143

; DEV u16 f2bf(float f) { return (u16)(pack2(f, 0.f) & 0xffffu); }
; DEV void phase_win(const Params& P, int l, const u16* __restrict__ xb, const u16* __restrict__ Wt, u16* __restrict__ h, char* smem) {
;     ...
;         for (int j = 0; j < 4; ++j) {
;           int row = m0 + wm * 128 + ms * 16 + quad * 4 + j;
;           int col = cb + ns * 16 + l15;
;           float v = acc[ms][ns][j];
;           if (mode == 1) { float lbv = lbp[col - C_HF]; v = __logf(lbv + (1.f - lbv) / (1.f + __expf(-v))); }
;           else if (mode == 2) v = v / (1.f + __expf(-v));
;           h[(size_t)row * HS + col] = f2bf(v);
.LBB0_1526:
	s_andn2_b64 vcc, exec, s[4:5]
	s_cbranch_vccnz .LBB0_1529
	s_cmp_eq_u32 s17, 1
	v_mov_b32_e32 v144, v28
	s_cbranch_scc0 .LBB0_1529
	v_lshl_add_u64 v[144:145], v[0:1], 2, s[14:15]
	v_add_co_u32_e32 v144, vcc, 0xfffff000, v144
	s_nop 1
	v_addc_co_u32_e32 v145, vcc, -1, v145, vcc
	v_mov_b32_e32 v144, v160
	v_mul_f32_e32 v145, 0xbfb8aa3b, v28
	v_exp_f32_e32 v145, v145
	v_sub_f32_e32 v146, 1.0, v144
	v_add_f32_e32 v145, 1.0, v145
	v_div_scale_f32 v147, s[4:5], v145, v145, v146
	v_rcp_f32_e32 v148, v147
	v_div_scale_f32 v149, vcc, v146, v145, v146
	s_mov_b32 s4, 0x800000
	v_fma_f32 v150, -v147, v148, 1.0
	v_fmac_f32_e32 v148, v150, v148
	v_mul_f32_e32 v150, v149, v148
	v_fma_f32 v151, -v147, v150, v149
	v_fmac_f32_e32 v150, v151, v148
	v_fma_f32 v147, -v147, v150, v149
	v_div_fmas_f32 v147, v147, v148, v150
	v_div_fixup_f32 v145, v147, v145, v146
	v_add_f32_e32 v144, v144, v145
	v_cmp_gt_f32_e32 vcc, s4, v144
	s_mov_b32 s4, 0x3f317217
	s_nop 0
	v_cndmask_b32_e64 v145, 0, 32, vcc
	v_ldexp_f32 v144, v144, v145
	v_log_f32_e32 v144, v144
	s_nop 0
	v_mul_f32_e32 v145, 0x3f317217, v144
	v_fma_f32 v145, v144, s4, -v145
	v_fmac_f32_e32 v145, 0x3377d1cf, v144
	s_mov_b32 s4, 0x7f800000
	v_fmac_f32_e32 v145, 0x3f317217, v144
	v_cmp_lt_f32_e64 s[12:13], |v144|, s4
	s_nop 1
	v_cndmask_b32_e64 v144, v144, v145, s[12:13]
	v_cndmask_b32_e32 v145, 0, v227, vcc
	v_sub_f32_e32 v144, v144, v145

; DEV u16 f2bf(float f) { return (u16)(pack2(f, 0.f) & 0xffffu); }
; DEV void phase_win(const Params& P, int l, const u16* __restrict__ xb, const u16* __restrict__ Wt, u16* __restrict__ h, char* smem) {
;     ...
;         for (int j = 0; j < 4; ++j) {
;           int row = m0 + wm * 128 + ms * 16 + quad * 4 + j;
;           int col = cb + ns * 16 + l15;
;           float v = acc[ms][ns][j];
;           if (mode == 1) { float lbv = lbp[col - C_HF]; v = __logf(lbv + (1.f - lbv) / (1.f + __expf(-v))); }
;           else if (mode == 2) v = v / (1.f + __expf(-v));
;           h[(size_t)row * HS + col] = f2bf(v);
.LBB0_1531:
	s_andn2_b64 vcc, exec, s[4:5]
	s_cbranch_vccnz .LBB0_1534
	s_cmp_eq_u32 s17, 1
	v_mov_b32_e32 v146, v29
	s_cbranch_scc0 .LBB0_1534
	v_lshl_add_u64 v[146:147], v[0:1], 2, s[14:15]
	v_add_co_u32_e32 v146, vcc, 0xfffff000, v146
	s_nop 1
	v_addc_co_u32_e32 v147, vcc, -1, v147, vcc
	v_mov_b32_e32 v146, v160
	v_mul_f32_e32 v147, 0xbfb8aa3b, v29
	v_exp_f32_e32 v147, v147
	v_sub_f32_e32 v148, 1.0, v146
	v_add_f32_e32 v147, 1.0, v147
	v_div_scale_f32 v149, s[4:5], v147, v147, v148
	v_rcp_f32_e32 v150, v149
	v_div_scale_f32 v151, vcc, v148, v147, v148
	s_mov_b32 s4, 0x800000
	v_fma_f32 v152, -v149, v150, 1.0
	v_fmac_f32_e32 v150, v152, v150
	v_mul_f32_e32 v152, v151, v150
	v_fma_f32 v153, -v149, v152, v151
	v_fmac_f32_e32 v152, v153, v150
	v_fma_f32 v149, -v149, v152, v151
	v_div_fmas_f32 v149, v149, v150, v152
	v_div_fixup_f32 v147, v149, v147, v148
	v_add_f32_e32 v146, v146, v147
	v_cmp_gt_f32_e32 vcc, s4, v146
	s_mov_b32 s4, 0x3f317217
	s_nop 0
	v_cndmask_b32_e64 v147, 0, 32, vcc
	v_ldexp_f32 v146, v146, v147
	v_log_f32_e32 v146, v146
	s_nop 0
	v_mul_f32_e32 v147, 0x3f317217, v146
	v_fma_f32 v147, v146, s4, -v147
	v_fmac_f32_e32 v147, 0x3377d1cf, v146
	s_mov_b32 s4, 0x7f800000
	v_fmac_f32_e32 v147, 0x3f317217, v146
	v_cmp_lt_f32_e64 s[12:13], |v146|, s4
	s_nop 1
	v_cndmask_b32_e64 v146, v146, v147, s[12:13]
	v_cndmask_b32_e32 v147, 0, v227, vcc
	v_sub_f32_e32 v146, v146, v147

; DEV u16 f2bf(float f) { return (u16)(pack2(f, 0.f) & 0xffffu); }
; DEV void phase_win(const Params& P, int l, const u16* __restrict__ xb, const u16* __restrict__ Wt, u16* __restrict__ h, char* smem) {
;     ...
;         for (int j = 0; j < 4; ++j) {
;           int row = m0 + wm * 128 + ms * 16 + quad * 4 + j;
;           int col = cb + ns * 16 + l15;
;           float v = acc[ms][ns][j];
;           if (mode == 1) { float lbv = lbp[col - C_HF]; v = __logf(lbv + (1.f - lbv) / (1.f + __expf(-v))); }
;           else if (mode == 2) v = v / (1.f + __expf(-v));
;           h[(size_t)row * HS + col] = f2bf(v);
.LBB0_1536:
	s_andn2_b64 vcc, exec, s[4:5]
	s_cbranch_vccnz .LBB0_1539
	s_cmp_eq_u32 s17, 1
	v_mov_b32_e32 v131, v110
	s_cbranch_scc0 .LBB0_1539
	v_lshl_add_u64 v[148:149], v[0:1], 2, s[14:15]
	v_add_co_u32_e32 v148, vcc, 0xfffff000, v148
	s_nop 1
	v_addc_co_u32_e32 v149, vcc, -1, v149, vcc
	v_mov_b32_e32 v131, v161
	v_mul_f32_e32 v148, 0xbfb8aa3b, v110
	v_exp_f32_e32 v148, v148
	v_sub_f32_e32 v149, 1.0, v131
	v_add_f32_e32 v148, 1.0, v148
	v_div_scale_f32 v150, s[4:5], v148, v148, v149
	v_rcp_f32_e32 v151, v150
	v_div_scale_f32 v152, vcc, v149, v148, v149
	s_mov_b32 s4, 0x800000
	v_fma_f32 v153, -v150, v151, 1.0
	v_fmac_f32_e32 v151, v153, v151
	v_mul_f32_e32 v153, v152, v151
	v_fma_f32 v154, -v150, v153, v152
	v_fmac_f32_e32 v153, v154, v151
	v_fma_f32 v150, -v150, v153, v152
	v_div_fmas_f32 v150, v150, v151, v153
	v_div_fixup_f32 v148, v150, v148, v149
	v_add_f32_e32 v131, v131, v148
	v_cmp_gt_f32_e32 vcc, s4, v131
	s_mov_b32 s4, 0x3f317217
	s_nop 0
	v_cndmask_b32_e64 v148, 0, 32, vcc
	v_ldexp_f32 v131, v131, v148
	v_log_f32_e32 v131, v131
	s_nop 0
	v_mul_f32_e32 v148, 0x3f317217, v131
	v_fma_f32 v148, v131, s4, -v148
	v_fmac_f32_e32 v148, 0x3377d1cf, v131
	s_mov_b32 s4, 0x7f800000
	v_fmac_f32_e32 v148, 0x3f317217, v131
	v_cmp_lt_f32_e64 s[12:13], |v131|, s4
	s_nop 1
	v_cndmask_b32_e64 v131, v131, v148, s[12:13]
	v_cndmask_b32_e32 v148, 0, v227, vcc
	v_sub_f32_e32 v131, v131, v148

; DEV u16 f2bf(float f) { return (u16)(pack2(f, 0.f) & 0xffffu); }
; DEV void phase_win(const Params& P, int l, const u16* __restrict__ xb, const u16* __restrict__ Wt, u16* __restrict__ h, char* smem) {
;     ...
;         for (int j = 0; j < 4; ++j) {
;           int row = m0 + wm * 128 + ms * 16 + quad * 4 + j;
;           int col = cb + ns * 16 + l15;
;           float v = acc[ms][ns][j];
;           if (mode == 1) { float lbv = lbp[col - C_HF]; v = __logf(lbv + (1.f - lbv) / (1.f + __expf(-v))); }
;           else if (mode == 2) v = v / (1.f + __expf(-v));
;           h[(size_t)row * HS + col] = f2bf(v);
.LBB0_1541:
	s_andn2_b64 vcc, exec, s[4:5]
	s_cbranch_vccnz .LBB0_1544
	s_cmp_eq_u32 s17, 1
	v_mov_b32_e32 v131, v111
	s_cbranch_scc0 .LBB0_1544
	v_lshl_add_u64 v[148:149], v[0:1], 2, s[14:15]
	v_add_co_u32_e32 v148, vcc, 0xfffff000, v148
	s_nop 1
	v_addc_co_u32_e32 v149, vcc, -1, v149, vcc
	v_mov_b32_e32 v131, v161
	v_mul_f32_e32 v148, 0xbfb8aa3b, v111
	v_exp_f32_e32 v148, v148
	v_sub_f32_e32 v149, 1.0, v131
	v_add_f32_e32 v148, 1.0, v148
	v_div_scale_f32 v150, s[4:5], v148, v148, v149
	v_rcp_f32_e32 v151, v150
	v_div_scale_f32 v152, vcc, v149, v148, v149
	s_mov_b32 s4, 0x800000
	v_fma_f32 v153, -v150, v151, 1.0
	v_fmac_f32_e32 v151, v153, v151
	v_mul_f32_e32 v153, v152, v151
	v_fma_f32 v154, -v150, v153, v152
	v_fmac_f32_e32 v153, v154, v151
	v_fma_f32 v150, -v150, v153, v152
	v_div_fmas_f32 v150, v150, v151, v153
	v_div_fixup_f32 v148, v150, v148, v149
	v_add_f32_e32 v131, v131, v148
	v_cmp_gt_f32_e32 vcc, s4, v131
	s_mov_b32 s4, 0x3f317217
	s_nop 0
	v_cndmask_b32_e64 v148, 0, 32, vcc
	v_ldexp_f32 v131, v131, v148
	v_log_f32_e32 v131, v131
	s_nop 0
	v_mul_f32_e32 v148, 0x3f317217, v131
	v_fma_f32 v148, v131, s4, -v148
	v_fmac_f32_e32 v148, 0x3377d1cf, v131
	s_mov_b32 s4, 0x7f800000
	v_fmac_f32_e32 v148, 0x3f317217, v131
	v_cmp_lt_f32_e64 s[12:13], |v131|, s4
	s_nop 1
	v_cndmask_b32_e64 v131, v131, v148, s[12:13]
	v_cndmask_b32_e32 v148, 0, v227, vcc
	v_sub_f32_e32 v131, v131, v148

; DEV u16 f2bf(float f) { return (u16)(pack2(f, 0.f) & 0xffffu); }
; DEV void phase_win(const Params& P, int l, const u16* __restrict__ xb, const u16* __restrict__ Wt, u16* __restrict__ h, char* smem) {
;     ...
;         for (int j = 0; j < 4; ++j) {
;           int row = m0 + wm * 128 + ms * 16 + quad * 4 + j;
;           int col = cb + ns * 16 + l15;
;           float v = acc[ms][ns][j];
;           if (mode == 1) { float lbv = lbp[col - C_HF]; v = __logf(lbv + (1.f - lbv) / (1.f + __expf(-v))); }
;           else if (mode == 2) v = v / (1.f + __expf(-v));
;           h[(size_t)row * HS + col] = f2bf(v);
.LBB0_1546:
	s_andn2_b64 vcc, exec, s[4:5]
	s_cbranch_vccnz .LBB0_1549
	s_cmp_eq_u32 s17, 1
	v_mov_b32_e32 v131, v112
	s_cbranch_scc0 .LBB0_1549
	v_lshl_add_u64 v[148:149], v[0:1], 2, s[14:15]
	v_add_co_u32_e32 v148, vcc, 0xfffff000, v148
	s_nop 1
	v_addc_co_u32_e32 v149, vcc, -1, v149, vcc
	v_mov_b32_e32 v131, v161
	v_mul_f32_e32 v148, 0xbfb8aa3b, v112
	v_exp_f32_e32 v148, v148
	v_sub_f32_e32 v149, 1.0, v131
	v_add_f32_e32 v148, 1.0, v148
	v_div_scale_f32 v150, s[4:5], v148, v148, v149
	v_rcp_f32_e32 v151, v150
	v_div_scale_f32 v152, vcc, v149, v148, v149
	s_mov_b32 s4, 0x800000
	v_fma_f32 v153, -v150, v151, 1.0
	v_fmac_f32_e32 v151, v153, v151
	v_mul_f32_e32 v153, v152, v151
	v_fma_f32 v154, -v150, v153, v152
	v_fmac_f32_e32 v153, v154, v151
	v_fma_f32 v150, -v150, v153, v152
	v_div_fmas_f32 v150, v150, v151, v153
	v_div_fixup_f32 v148, v150, v148, v149
	v_add_f32_e32 v131, v131, v148
	v_cmp_gt_f32_e32 vcc, s4, v131
	s_mov_b32 s4, 0x3f317217
	s_nop 0
	v_cndmask_b32_e64 v148, 0, 32, vcc
	v_ldexp_f32 v131, v131, v148
	v_log_f32_e32 v131, v131
	s_nop 0
	v_mul_f32_e32 v148, 0x3f317217, v131
	v_fma_f32 v148, v131, s4, -v148
	v_fmac_f32_e32 v148, 0x3377d1cf, v131
	s_mov_b32 s4, 0x7f800000
	v_fmac_f32_e32 v148, 0x3f317217, v131
	v_cmp_lt_f32_e64 s[12:13], |v131|, s4
	s_nop 1
	v_cndmask_b32_e64 v131, v131, v148, s[12:13]
	v_cndmask_b32_e32 v148, 0, v227, vcc
	v_sub_f32_e32 v131, v131, v148

; DEV u16 f2bf(float f) { return (u16)(pack2(f, 0.f) & 0xffffu); }
; DEV void phase_win(const Params& P, int l, const u16* __restrict__ xb, const u16* __restrict__ Wt, u16* __restrict__ h, char* smem) {
;     ...
;         for (int j = 0; j < 4; ++j) {
;           int row = m0 + wm * 128 + ms * 16 + quad * 4 + j;
;           int col = cb + ns * 16 + l15;
;           float v = acc[ms][ns][j];
;           if (mode == 1) { float lbv = lbp[col - C_HF]; v = __logf(lbv + (1.f - lbv) / (1.f + __expf(-v))); }
;           else if (mode == 2) v = v / (1.f + __expf(-v));
;           h[(size_t)row * HS + col] = f2bf(v);
.LBB0_1551:
	s_andn2_b64 vcc, exec, s[4:5]
	s_cbranch_vccnz .LBB0_1554
	s_cmp_eq_u32 s17, 1
	v_mov_b32_e32 v131, v113
	s_cbranch_scc0 .LBB0_1554
	v_lshl_add_u64 v[148:149], v[0:1], 2, s[14:15]
	v_add_co_u32_e32 v148, vcc, 0xfffff000, v148
	s_nop 1
	v_addc_co_u32_e32 v149, vcc, -1, v149, vcc
	v_mov_b32_e32 v131, v161
	v_mul_f32_e32 v148, 0xbfb8aa3b, v113
	v_exp_f32_e32 v148, v148
	v_sub_f32_e32 v149, 1.0, v131
	v_add_f32_e32 v148, 1.0, v148
	v_div_scale_f32 v150, s[4:5], v148, v148, v149
	v_rcp_f32_e32 v151, v150
	v_div_scale_f32 v152, vcc, v149, v148, v149
	s_mov_b32 s4, 0x800000
	v_fma_f32 v153, -v150, v151, 1.0
	v_fmac_f32_e32 v151, v153, v151
	v_mul_f32_e32 v153, v152, v151
	v_fma_f32 v154, -v150, v153, v152
	v_fmac_f32_e32 v153, v154, v151
	v_fma_f32 v150, -v150, v153, v152
	v_div_fmas_f32 v150, v150, v151, v153
	v_div_fixup_f32 v148, v150, v148, v149
	v_add_f32_e32 v131, v131, v148
	v_cmp_gt_f32_e32 vcc, s4, v131
	s_mov_b32 s4, 0x3f317217
	s_nop 0
	v_cndmask_b32_e64 v148, 0, 32, vcc
	v_ldexp_f32 v131, v131, v148
	v_log_f32_e32 v131, v131
	s_nop 0
	v_mul_f32_e32 v148, 0x3f317217, v131
	v_fma_f32 v148, v131, s4, -v148
	v_fmac_f32_e32 v148, 0x3377d1cf, v131
	s_mov_b32 s4, 0x7f800000
	v_fmac_f32_e32 v148, 0x3f317217, v131
	v_cmp_lt_f32_e64 s[12:13], |v131|, s4
	s_nop 1
	v_cndmask_b32_e64 v131, v131, v148, s[12:13]
	v_cndmask_b32_e32 v148, 0, v227, vcc
	v_sub_f32_e32 v131, v131, v148

; DEV u16 f2bf(float f) { return (u16)(pack2(f, 0.f) & 0xffffu); }
; DEV void phase_win(const Params& P, int l, const u16* __restrict__ xb, const u16* __restrict__ Wt, u16* __restrict__ h, char* smem) {
;     ...
;         for (int j = 0; j < 4; ++j) {
;           int row = m0 + wm * 128 + ms * 16 + quad * 4 + j;
;           int col = cb + ns * 16 + l15;
;           float v = acc[ms][ns][j];
;           if (mode == 1) { float lbv = lbp[col - C_HF]; v = __logf(lbv + (1.f - lbv) / (1.f + __expf(-v))); }
;           else if (mode == 2) v = v / (1.f + __expf(-v));
;           h[(size_t)row * HS + col] = f2bf(v);
.LBB0_1556:
	s_andn2_b64 vcc, exec, s[4:5]
	s_cbranch_vccnz .LBB0_1559
	s_cmp_eq_u32 s17, 1
	v_mov_b32_e32 v131, v114
	s_cbranch_scc0 .LBB0_1559
	v_lshl_add_u64 v[148:149], v[0:1], 2, s[14:15]
	v_add_co_u32_e32 v148, vcc, 0xfffff000, v148
	s_nop 1
	v_addc_co_u32_e32 v149, vcc, -1, v149, vcc
	v_mov_b32_e32 v131, v162
	v_mul_f32_e32 v148, 0xbfb8aa3b, v114
	v_exp_f32_e32 v148, v148
	v_sub_f32_e32 v149, 1.0, v131
	v_add_f32_e32 v148, 1.0, v148
	v_div_scale_f32 v150, s[4:5], v148, v148, v149
	v_rcp_f32_e32 v151, v150
	v_div_scale_f32 v152, vcc, v149, v148, v149
	s_mov_b32 s4, 0x800000
	v_fma_f32 v153, -v150, v151, 1.0
	v_fmac_f32_e32 v151, v153, v151
	v_mul_f32_e32 v153, v152, v151
	v_fma_f32 v154, -v150, v153, v152
	v_fmac_f32_e32 v153, v154, v151
	v_fma_f32 v150, -v150, v153, v152
	v_div_fmas_f32 v150, v150, v151, v153
	v_div_fixup_f32 v148, v150, v148, v149
	v_add_f32_e32 v131, v131, v148
	v_cmp_gt_f32_e32 vcc, s4, v131
	s_mov_b32 s4, 0x3f317217
	s_nop 0
	v_cndmask_b32_e64 v148, 0, 32, vcc
	v_ldexp_f32 v131, v131, v148
	v_log_f32_e32 v131, v131
	s_nop 0
	v_mul_f32_e32 v148, 0x3f317217, v131
	v_fma_f32 v148, v131, s4, -v148
	v_fmac_f32_e32 v148, 0x3377d1cf, v131
	s_mov_b32 s4, 0x7f800000
	v_fmac_f32_e32 v148, 0x3f317217, v131
	v_cmp_lt_f32_e64 s[12:13], |v131|, s4
	s_nop 1
	v_cndmask_b32_e64 v131, v131, v148, s[12:13]
	v_cndmask_b32_e32 v148, 0, v227, vcc
	v_sub_f32_e32 v131, v131, v148

; DEV u16 f2bf(float f) { return (u16)(pack2(f, 0.f) & 0xffffu); }
; DEV void phase_win(const Params& P, int l, const u16* __restrict__ xb, const u16* __restrict__ Wt, u16* __restrict__ h, char* smem) {
;     ...
;         for (int j = 0; j < 4; ++j) {
;           int row = m0 + wm * 128 + ms * 16 + quad * 4 + j;
;           int col = cb + ns * 16 + l15;
;           float v = acc[ms][ns][j];
;           if (mode == 1) { float lbv = lbp[col - C_HF]; v = __logf(lbv + (1.f - lbv) / (1.f + __expf(-v))); }
;           else if (mode == 2) v = v / (1.f + __expf(-v));
;           h[(size_t)row * HS + col] = f2bf(v);
.LBB0_1561:
	s_andn2_b64 vcc, exec, s[4:5]
	s_cbranch_vccnz .LBB0_1564
	s_cmp_eq_u32 s17, 1
	v_mov_b32_e32 v131, v115
	s_cbranch_scc0 .LBB0_1564
	v_lshl_add_u64 v[148:149], v[0:1], 2, s[14:15]
	v_add_co_u32_e32 v148, vcc, 0xfffff000, v148
	s_nop 1
	v_addc_co_u32_e32 v149, vcc, -1, v149, vcc
	v_mov_b32_e32 v131, v162
	v_mul_f32_e32 v148, 0xbfb8aa3b, v115
	v_exp_f32_e32 v148, v148
	v_sub_f32_e32 v149, 1.0, v131
	v_add_f32_e32 v148, 1.0, v148
	v_div_scale_f32 v150, s[4:5], v148, v148, v149
	v_rcp_f32_e32 v151, v150
	v_div_scale_f32 v152, vcc, v149, v148, v149
	s_mov_b32 s4, 0x800000
	v_fma_f32 v153, -v150, v151, 1.0
	v_fmac_f32_e32 v151, v153, v151
	v_mul_f32_e32 v153, v152, v151
	v_fma_f32 v154, -v150, v153, v152
	v_fmac_f32_e32 v153, v154, v151
	v_fma_f32 v150, -v150, v153, v152
	v_div_fmas_f32 v150, v150, v151, v153
	v_div_fixup_f32 v148, v150, v148, v149
	v_add_f32_e32 v131, v131, v148
	v_cmp_gt_f32_e32 vcc, s4, v131
	s_mov_b32 s4, 0x3f317217
	s_nop 0
	v_cndmask_b32_e64 v148, 0, 32, vcc
	v_ldexp_f32 v131, v131, v148
	v_log_f32_e32 v131, v131
	s_nop 0
	v_mul_f32_e32 v148, 0x3f317217, v131
	v_fma_f32 v148, v131, s4, -v148
	v_fmac_f32_e32 v148, 0x3377d1cf, v131
	s_mov_b32 s4, 0x7f800000
	v_fmac_f32_e32 v148, 0x3f317217, v131
	v_cmp_lt_f32_e64 s[12:13], |v131|, s4
	s_nop 1
	v_cndmask_b32_e64 v131, v131, v148, s[12:13]
	v_cndmask_b32_e32 v148, 0, v227, vcc
	v_sub_f32_e32 v131, v131, v148

; DEV u16 f2bf(float f) { return (u16)(pack2(f, 0.f) & 0xffffu); }
; DEV void phase_win(const Params& P, int l, const u16* __restrict__ xb, const u16* __restrict__ Wt, u16* __restrict__ h, char* smem) {
;     ...
;         for (int j = 0; j < 4; ++j) {
;           int row = m0 + wm * 128 + ms * 16 + quad * 4 + j;
;           int col = cb + ns * 16 + l15;
;           float v = acc[ms][ns][j];
;           if (mode == 1) { float lbv = lbp[col - C_HF]; v = __logf(lbv + (1.f - lbv) / (1.f + __expf(-v))); }
;           else if (mode == 2) v = v / (1.f + __expf(-v));
;           h[(size_t)row * HS + col] = f2bf(v);
.LBB0_1566:
	s_andn2_b64 vcc, exec, s[4:5]
	s_cbranch_vccnz .LBB0_1569
	s_cmp_eq_u32 s17, 1
	v_mov_b32_e32 v131, v116
	s_cbranch_scc0 .LBB0_1569
	v_lshl_add_u64 v[148:149], v[0:1], 2, s[14:15]
	v_add_co_u32_e32 v148, vcc, 0xfffff000, v148
	s_nop 1
	v_addc_co_u32_e32 v149, vcc, -1, v149, vcc
	v_mov_b32_e32 v131, v162
	v_mul_f32_e32 v148, 0xbfb8aa3b, v116
	v_exp_f32_e32 v148, v148
	v_sub_f32_e32 v149, 1.0, v131
	v_add_f32_e32 v148, 1.0, v148
	v_div_scale_f32 v150, s[4:5], v148, v148, v149
	v_rcp_f32_e32 v151, v150
	v_div_scale_f32 v152, vcc, v149, v148, v149
	s_mov_b32 s4, 0x800000
	v_fma_f32 v153, -v150, v151, 1.0
	v_fmac_f32_e32 v151, v153, v151
	v_mul_f32_e32 v153, v152, v151
	v_fma_f32 v154, -v150, v153, v152
	v_fmac_f32_e32 v153, v154, v151
	v_fma_f32 v150, -v150, v153, v152
	v_div_fmas_f32 v150, v150, v151, v153
	v_div_fixup_f32 v148, v150, v148, v149
	v_add_f32_e32 v131, v131, v148
	v_cmp_gt_f32_e32 vcc, s4, v131
	s_mov_b32 s4, 0x3f317217
	s_nop 0
	v_cndmask_b32_e64 v148, 0, 32, vcc
	v_ldexp_f32 v131, v131, v148
	v_log_f32_e32 v131, v131
	s_nop 0
	v_mul_f32_e32 v148, 0x3f317217, v131
	v_fma_f32 v148, v131, s4, -v148
	v_fmac_f32_e32 v148, 0x3377d1cf, v131
	s_mov_b32 s4, 0x7f800000
	v_fmac_f32_e32 v148, 0x3f317217, v131
	v_cmp_lt_f32_e64 s[12:13], |v131|, s4
	s_nop 1
	v_cndmask_b32_e64 v131, v131, v148, s[12:13]
	v_cndmask_b32_e32 v148, 0, v227, vcc
	v_sub_f32_e32 v131, v131, v148

; DEV u16 f2bf(float f) { return (u16)(pack2(f, 0.f) & 0xffffu); }
; DEV void phase_win(const Params& P, int l, const u16* __restrict__ xb, const u16* __restrict__ Wt, u16* __restrict__ h, char* smem) {
;     ...
;         for (int j = 0; j < 4; ++j) {
;           int row = m0 + wm * 128 + ms * 16 + quad * 4 + j;
;           int col = cb + ns * 16 + l15;
;           float v = acc[ms][ns][j];
;           if (mode == 1) { float lbv = lbp[col - C_HF]; v = __logf(lbv + (1.f - lbv) / (1.f + __expf(-v))); }
;           else if (mode == 2) v = v / (1.f + __expf(-v));
;           h[(size_t)row * HS + col] = f2bf(v);
.LBB0_1571:
	s_andn2_b64 vcc, exec, s[4:5]
	s_cbranch_vccnz .LBB0_1574
	s_cmp_eq_u32 s17, 1
	v_mov_b32_e32 v131, v117
	s_cbranch_scc0 .LBB0_1574
	v_lshl_add_u64 v[148:149], v[0:1], 2, s[14:15]
	v_add_co_u32_e32 v148, vcc, 0xfffff000, v148
	s_nop 1
	v_addc_co_u32_e32 v149, vcc, -1, v149, vcc
	v_mov_b32_e32 v131, v162
	v_mul_f32_e32 v148, 0xbfb8aa3b, v117
	v_exp_f32_e32 v148, v148
	v_sub_f32_e32 v149, 1.0, v131
	v_add_f32_e32 v148, 1.0, v148
	v_div_scale_f32 v150, s[4:5], v148, v148, v149
	v_rcp_f32_e32 v151, v150
	v_div_scale_f32 v152, vcc, v149, v148, v149
	s_mov_b32 s4, 0x800000
	v_fma_f32 v153, -v150, v151, 1.0
	v_fmac_f32_e32 v151, v153, v151
	v_mul_f32_e32 v153, v152, v151
	v_fma_f32 v154, -v150, v153, v152
	v_fmac_f32_e32 v153, v154, v151
	v_fma_f32 v150, -v150, v153, v152
	v_div_fmas_f32 v150, v150, v151, v153
	v_div_fixup_f32 v148, v150, v148, v149
	v_add_f32_e32 v131, v131, v148
	v_cmp_gt_f32_e32 vcc, s4, v131
	s_mov_b32 s4, 0x3f317217
	s_nop 0
	v_cndmask_b32_e64 v148, 0, 32, vcc
	v_ldexp_f32 v131, v131, v148
	v_log_f32_e32 v131, v131
	s_nop 0
	v_mul_f32_e32 v148, 0x3f317217, v131
	v_fma_f32 v148, v131, s4, -v148
	v_fmac_f32_e32 v148, 0x3377d1cf, v131
	s_mov_b32 s4, 0x7f800000
	v_fmac_f32_e32 v148, 0x3f317217, v131
	v_cmp_lt_f32_e64 s[12:13], |v131|, s4
	s_nop 1
	v_cndmask_b32_e64 v131, v131, v148, s[12:13]
	v_cndmask_b32_e32 v148, 0, v227, vcc
	v_sub_f32_e32 v131, v131, v148

; DEV u16 f2bf(float f) { return (u16)(pack2(f, 0.f) & 0xffffu); }
; DEV void phase_win(const Params& P, int l, const u16* __restrict__ xb, const u16* __restrict__ Wt, u16* __restrict__ h, char* smem) {
;     ...
;         for (int j = 0; j < 4; ++j) {
;           int row = m0 + wm * 128 + ms * 16 + quad * 4 + j;
;           int col = cb + ns * 16 + l15;
;           float v = acc[ms][ns][j];
;           if (mode == 1) { float lbv = lbp[col - C_HF]; v = __logf(lbv + (1.f - lbv) / (1.f + __expf(-v))); }
;           else if (mode == 2) v = v / (1.f + __expf(-v));
;           h[(size_t)row * HS + col] = f2bf(v);
.LBB0_1576:
	s_andn2_b64 vcc, exec, s[4:5]
	s_cbranch_vccnz .LBB0_1579
	s_cmp_eq_u32 s17, 1
	v_mov_b32_e32 v131, v106
	s_cbranch_scc0 .LBB0_1579
	v_lshl_add_u64 v[148:149], v[0:1], 2, s[14:15]
	v_add_co_u32_e32 v148, vcc, 0xfffff000, v148
	s_nop 1
	v_addc_co_u32_e32 v149, vcc, -1, v149, vcc
	v_mov_b32_e32 v131, v163
	v_mul_f32_e32 v148, 0xbfb8aa3b, v106
	v_exp_f32_e32 v148, v148
	v_sub_f32_e32 v149, 1.0, v131
	v_add_f32_e32 v148, 1.0, v148
	v_div_scale_f32 v150, s[4:5], v148, v148, v149
	v_rcp_f32_e32 v151, v150
	v_div_scale_f32 v152, vcc, v149, v148, v149
	s_mov_b32 s4, 0x800000
	v_fma_f32 v153, -v150, v151, 1.0
	v_fmac_f32_e32 v151, v153, v151
	v_mul_f32_e32 v153, v152, v151
	v_fma_f32 v154, -v150, v153, v152
	v_fmac_f32_e32 v153, v154, v151
	v_fma_f32 v150, -v150, v153, v152
	v_div_fmas_f32 v150, v150, v151, v153
	v_div_fixup_f32 v148, v150, v148, v149
	v_add_f32_e32 v131, v131, v148
	v_cmp_gt_f32_e32 vcc, s4, v131
	s_mov_b32 s4, 0x3f317217
	s_nop 0
	v_cndmask_b32_e64 v148, 0, 32, vcc
	v_ldexp_f32 v131, v131, v148
	v_log_f32_e32 v131, v131
	s_nop 0
	v_mul_f32_e32 v148, 0x3f317217, v131
	v_fma_f32 v148, v131, s4, -v148
	v_fmac_f32_e32 v148, 0x3377d1cf, v131
	s_mov_b32 s4, 0x7f800000
	v_fmac_f32_e32 v148, 0x3f317217, v131
	v_cmp_lt_f32_e64 s[12:13], |v131|, s4
	s_nop 1
	v_cndmask_b32_e64 v131, v131, v148, s[12:13]
	v_cndmask_b32_e32 v148, 0, v227, vcc
	v_sub_f32_e32 v131, v131, v148

; DEV u16 f2bf(float f) { return (u16)(pack2(f, 0.f) & 0xffffu); }
; DEV void phase_win(const Params& P, int l, const u16* __restrict__ xb, const u16* __restrict__ Wt, u16* __restrict__ h, char* smem) {
;     ...
;         for (int j = 0; j < 4; ++j) {
;           int row = m0 + wm * 128 + ms * 16 + quad * 4 + j;
;           int col = cb + ns * 16 + l15;
;           float v = acc[ms][ns][j];
;           if (mode == 1) { float lbv = lbp[col - C_HF]; v = __logf(lbv + (1.f - lbv) / (1.f + __expf(-v))); }
;           else if (mode == 2) v = v / (1.f + __expf(-v));
;           h[(size_t)row * HS + col] = f2bf(v);
.LBB0_1581:
	s_andn2_b64 vcc, exec, s[4:5]
	s_cbranch_vccnz .LBB0_1584
	s_cmp_eq_u32 s17, 1
	v_mov_b32_e32 v131, v107
	s_cbranch_scc0 .LBB0_1584
	v_lshl_add_u64 v[140:141], v[0:1], 2, s[14:15]
	v_add_co_u32_e32 v140, vcc, 0xfffff000, v140
	s_nop 1
	v_addc_co_u32_e32 v141, vcc, -1, v141, vcc
	v_mov_b32_e32 v131, v163
	v_mul_f32_e32 v140, 0xbfb8aa3b, v107
	v_exp_f32_e32 v140, v140
	v_sub_f32_e32 v141, 1.0, v131
	v_add_f32_e32 v140, 1.0, v140
	v_div_scale_f32 v148, s[4:5], v140, v140, v141
	v_rcp_f32_e32 v149, v148
	v_div_scale_f32 v150, vcc, v141, v140, v141
	s_mov_b32 s4, 0x800000
	v_fma_f32 v151, -v148, v149, 1.0
	v_fmac_f32_e32 v149, v151, v149
	v_mul_f32_e32 v151, v150, v149
	v_fma_f32 v152, -v148, v151, v150
	v_fmac_f32_e32 v151, v152, v149
	v_fma_f32 v148, -v148, v151, v150
	v_div_fmas_f32 v148, v148, v149, v151
	v_div_fixup_f32 v140, v148, v140, v141
	v_add_f32_e32 v131, v131, v140
	v_cmp_gt_f32_e32 vcc, s4, v131
	s_mov_b32 s4, 0x3f317217
	s_nop 0
	v_cndmask_b32_e64 v140, 0, 32, vcc
	v_ldexp_f32 v131, v131, v140
	v_log_f32_e32 v131, v131
	s_nop 0
	v_mul_f32_e32 v140, 0x3f317217, v131
	v_fma_f32 v140, v131, s4, -v140
	v_fmac_f32_e32 v140, 0x3377d1cf, v131
	s_mov_b32 s4, 0x7f800000
	v_fmac_f32_e32 v140, 0x3f317217, v131
	v_cmp_lt_f32_e64 s[12:13], |v131|, s4
	s_nop 1
	v_cndmask_b32_e64 v131, v131, v140, s[12:13]
	v_cndmask_b32_e32 v140, 0, v227, vcc
	v_sub_f32_e32 v131, v131, v140

; DEV u16 f2bf(float f) { return (u16)(pack2(f, 0.f) & 0xffffu); }
; DEV void phase_win(const Params& P, int l, const u16* __restrict__ xb, const u16* __restrict__ Wt, u16* __restrict__ h, char* smem) {
;     ...
;         for (int j = 0; j < 4; ++j) {
;           int row = m0 + wm * 128 + ms * 16 + quad * 4 + j;
;           int col = cb + ns * 16 + l15;
;           float v = acc[ms][ns][j];
;           if (mode == 1) { float lbv = lbp[col - C_HF]; v = __logf(lbv + (1.f - lbv) / (1.f + __expf(-v))); }
;           else if (mode == 2) v = v / (1.f + __expf(-v));
;           h[(size_t)row * HS + col] = f2bf(v);
.LBB0_1586:
	s_andn2_b64 vcc, exec, s[4:5]
	s_cbranch_vccnz .LBB0_1589
	s_cmp_eq_u32 s17, 1
	v_mov_b32_e32 v131, v108
	s_cbranch_scc0 .LBB0_1589
	v_lshl_add_u64 v[140:141], v[0:1], 2, s[14:15]
	v_add_co_u32_e32 v140, vcc, 0xfffff000, v140
	s_nop 1
	v_addc_co_u32_e32 v141, vcc, -1, v141, vcc
	v_mov_b32_e32 v131, v163
	v_mul_f32_e32 v140, 0xbfb8aa3b, v108
	v_exp_f32_e32 v140, v140
	v_sub_f32_e32 v141, 1.0, v131
	v_add_f32_e32 v140, 1.0, v140
	v_div_scale_f32 v142, s[4:5], v140, v140, v141
	v_rcp_f32_e32 v143, v142
	v_div_scale_f32 v148, vcc, v141, v140, v141
	s_mov_b32 s4, 0x800000
	v_fma_f32 v149, -v142, v143, 1.0
	v_fmac_f32_e32 v143, v149, v143
	v_mul_f32_e32 v149, v148, v143
	v_fma_f32 v150, -v142, v149, v148
	v_fmac_f32_e32 v149, v150, v143
	v_fma_f32 v142, -v142, v149, v148
	v_div_fmas_f32 v142, v142, v143, v149
	v_div_fixup_f32 v140, v142, v140, v141
	v_add_f32_e32 v131, v131, v140
	v_cmp_gt_f32_e32 vcc, s4, v131
	s_mov_b32 s4, 0x3f317217
	s_nop 0
	v_cndmask_b32_e64 v140, 0, 32, vcc
	v_ldexp_f32 v131, v131, v140
	v_log_f32_e32 v131, v131
	s_nop 0
	v_mul_f32_e32 v140, 0x3f317217, v131
	v_fma_f32 v140, v131, s4, -v140
	v_fmac_f32_e32 v140, 0x3377d1cf, v131
	s_mov_b32 s4, 0x7f800000
	v_fmac_f32_e32 v140, 0x3f317217, v131
	v_cmp_lt_f32_e64 s[12:13], |v131|, s4
	s_nop 1
	v_cndmask_b32_e64 v131, v131, v140, s[12:13]
	v_cndmask_b32_e32 v140, 0, v227, vcc
	v_sub_f32_e32 v131, v131, v140

; DEV u16 f2bf(float f) { return (u16)(pack2(f, 0.f) & 0xffffu); }
; DEV void phase_win(const Params& P, int l, const u16* __restrict__ xb, const u16* __restrict__ Wt, u16* __restrict__ h, char* smem) {
;     ...
;         for (int j = 0; j < 4; ++j) {
;           int row = m0 + wm * 128 + ms * 16 + quad * 4 + j;
;           int col = cb + ns * 16 + l15;
;           float v = acc[ms][ns][j];
;           if (mode == 1) { float lbv = lbp[col - C_HF]; v = __logf(lbv + (1.f - lbv) / (1.f + __expf(-v))); }
;           else if (mode == 2) v = v / (1.f + __expf(-v));
;           h[(size_t)row * HS + col] = f2bf(v);
.LBB0_1591:
	s_andn2_b64 vcc, exec, s[4:5]
	s_cbranch_vccnz .LBB0_1594
	s_cmp_eq_u32 s17, 1
	v_mov_b32_e32 v131, v109
	s_cbranch_scc0 .LBB0_1594
	v_lshl_add_u64 v[140:141], v[0:1], 2, s[14:15]
	v_add_co_u32_e32 v140, vcc, 0xfffff000, v140
	s_nop 1
	v_addc_co_u32_e32 v141, vcc, -1, v141, vcc
	v_mov_b32_e32 v131, v163
	v_mul_f32_e32 v140, 0xbfb8aa3b, v109
	v_exp_f32_e32 v140, v140
	v_sub_f32_e32 v141, 1.0, v131
	v_add_f32_e32 v140, 1.0, v140
	v_div_scale_f32 v142, s[4:5], v140, v140, v141
	v_rcp_f32_e32 v143, v142
	v_div_scale_f32 v144, vcc, v141, v140, v141
	s_mov_b32 s4, 0x800000
	v_fma_f32 v145, -v142, v143, 1.0
	v_fmac_f32_e32 v143, v145, v143
	v_mul_f32_e32 v145, v144, v143
	v_fma_f32 v148, -v142, v145, v144
	v_fmac_f32_e32 v145, v148, v143
	v_fma_f32 v142, -v142, v145, v144
	v_div_fmas_f32 v142, v142, v143, v145
	v_div_fixup_f32 v140, v142, v140, v141
	v_add_f32_e32 v131, v131, v140
	v_cmp_gt_f32_e32 vcc, s4, v131
	s_mov_b32 s4, 0x3f317217
	s_nop 0
	v_cndmask_b32_e64 v140, 0, 32, vcc
	v_ldexp_f32 v131, v131, v140
	v_log_f32_e32 v131, v131
	s_nop 0
	v_mul_f32_e32 v140, 0x3f317217, v131
	v_fma_f32 v140, v131, s4, -v140
	v_fmac_f32_e32 v140, 0x3377d1cf, v131
	s_mov_b32 s4, 0x7f800000
	v_fmac_f32_e32 v140, 0x3f317217, v131
	v_cmp_lt_f32_e64 s[12:13], |v131|, s4
	s_nop 1
	v_cndmask_b32_e64 v131, v131, v140, s[12:13]
	v_cndmask_b32_e32 v140, 0, v227, vcc
	v_sub_f32_e32 v131, v131, v140

; DEV u16 f2bf(float f) { return (u16)(pack2(f, 0.f) & 0xffffu); }
; DEV void phase_win(const Params& P, int l, const u16* __restrict__ xb, const u16* __restrict__ Wt, u16* __restrict__ h, char* smem) {
;     ...
;         for (int j = 0; j < 4; ++j) {
;           int row = m0 + wm * 128 + ms * 16 + quad * 4 + j;
;           int col = cb + ns * 16 + l15;
;           float v = acc[ms][ns][j];
;           if (mode == 1) { float lbv = lbp[col - C_HF]; v = __logf(lbv + (1.f - lbv) / (1.f + __expf(-v))); }
;           else if (mode == 2) v = v / (1.f + __expf(-v));
;           h[(size_t)row * HS + col] = f2bf(v);
.LBB0_1596:
	s_andn2_b64 vcc, exec, s[4:5]
	s_cbranch_vccnz .LBB0_1599
	s_cmp_eq_u32 s17, 1
	v_mov_b32_e32 v140, v22
	s_cbranch_scc0 .LBB0_1599
	v_lshl_add_u64 v[140:141], v[0:1], 2, s[14:15]
	v_add_co_u32_e32 v140, vcc, 0xfffff000, v140
	s_nop 1
	v_addc_co_u32_e32 v141, vcc, -1, v141, vcc
	v_mov_b32_e32 v131, v160
	v_mul_f32_e32 v140, 0xbfb8aa3b, v22
	v_exp_f32_e32 v140, v140
	v_sub_f32_e32 v141, 1.0, v131
	v_add_f32_e32 v140, 1.0, v140
	v_div_scale_f32 v142, s[4:5], v140, v140, v141
	v_rcp_f32_e32 v143, v142
	v_div_scale_f32 v144, vcc, v141, v140, v141
	s_mov_b32 s4, 0x800000
	v_fma_f32 v145, -v142, v143, 1.0
	v_fmac_f32_e32 v143, v145, v143
	v_mul_f32_e32 v145, v144, v143
	v_fma_f32 v146, -v142, v145, v144
	v_fmac_f32_e32 v145, v146, v143
	v_fma_f32 v142, -v142, v145, v144
	v_div_fmas_f32 v142, v142, v143, v145
	v_div_fixup_f32 v140, v142, v140, v141
	v_add_f32_e32 v131, v131, v140
	v_cmp_gt_f32_e32 vcc, s4, v131
	s_mov_b32 s4, 0x3f317217
	s_nop 0
	v_cndmask_b32_e64 v140, 0, 32, vcc
	v_ldexp_f32 v131, v131, v140
	v_log_f32_e32 v131, v131
	s_nop 0
	v_mul_f32_e32 v140, 0x3f317217, v131
	v_fma_f32 v140, v131, s4, -v140
	v_fmac_f32_e32 v140, 0x3377d1cf, v131
	s_mov_b32 s4, 0x7f800000
	v_fmac_f32_e32 v140, 0x3f317217, v131
	v_cmp_lt_f32_e64 s[12:13], |v131|, s4
	s_nop 1
	v_cndmask_b32_e64 v131, v131, v140, s[12:13]
	v_cndmask_b32_e32 v140, 0, v227, vcc
	v_sub_f32_e32 v140, v131, v140

; DEV u16 f2bf(float f) { return (u16)(pack2(f, 0.f) & 0xffffu); }
; DEV void phase_win(const Params& P, int l, const u16* __restrict__ xb, const u16* __restrict__ Wt, u16* __restrict__ h, char* smem) {
;     ...
;         for (int j = 0; j < 4; ++j) {
;           int row = m0 + wm * 128 + ms * 16 + quad * 4 + j;
;           int col = cb + ns * 16 + l15;
;           float v = acc[ms][ns][j];
;           if (mode == 1) { float lbv = lbp[col - C_HF]; v = __logf(lbv + (1.f - lbv) / (1.f + __expf(-v))); }
;           else if (mode == 2) v = v / (1.f + __expf(-v));
;           h[(size_t)row * HS + col] = f2bf(v);
.LBB0_1601:
	s_andn2_b64 vcc, exec, s[4:5]
	s_cbranch_vccnz .LBB0_1604
	s_cmp_eq_u32 s17, 1
	v_mov_b32_e32 v142, v23
	s_cbranch_scc0 .LBB0_1604
	v_lshl_add_u64 v[142:143], v[0:1], 2, s[14:15]
	v_add_co_u32_e32 v142, vcc, 0xfffff000, v142
	s_nop 1
	v_addc_co_u32_e32 v143, vcc, -1, v143, vcc
	v_mov_b32_e32 v142, v160
	v_mul_f32_e32 v143, 0xbfb8aa3b, v23
	v_exp_f32_e32 v143, v143
	v_sub_f32_e32 v144, 1.0, v142
	v_add_f32_e32 v143, 1.0, v143
	v_div_scale_f32 v145, s[4:5], v143, v143, v144
	v_rcp_f32_e32 v146, v145
	v_div_scale_f32 v147, vcc, v144, v143, v144
	s_mov_b32 s4, 0x800000
	v_fma_f32 v148, -v145, v146, 1.0
	v_fmac_f32_e32 v146, v148, v146
	v_mul_f32_e32 v148, v147, v146
	v_fma_f32 v149, -v145, v148, v147
	v_fmac_f32_e32 v148, v149, v146
	v_fma_f32 v145, -v145, v148, v147
	v_div_fmas_f32 v145, v145, v146, v148
	v_div_fixup_f32 v143, v145, v143, v144
	v_add_f32_e32 v142, v142, v143
	v_cmp_gt_f32_e32 vcc, s4, v142
	s_mov_b32 s4, 0x3f317217
	s_nop 0
	v_cndmask_b32_e64 v143, 0, 32, vcc
	v_ldexp_f32 v142, v142, v143
	v_log_f32_e32 v142, v142
	s_nop 0
	v_mul_f32_e32 v143, 0x3f317217, v142
	v_fma_f32 v143, v142, s4, -v143
	v_fmac_f32_e32 v143, 0x3377d1cf, v142
	s_mov_b32 s4, 0x7f800000
	v_fmac_f32_e32 v143, 0x3f317217, v142
	v_cmp_lt_f32_e64 s[12:13], |v142|, s4
	s_nop 1
	v_cndmask_b32_e64 v142, v142, v143, s[12:13]
	v_cndmask_b32_e32 v143, 0, v227, vcc
	v_sub_f32_e32 v142, v142, v143

; DEV u16 f2bf(float f) { return (u16)(pack2(f, 0.f) & 0xffffu); }
; DEV void phase_win(const Params& P, int l, const u16* __restrict__ xb, const u16* __restrict__ Wt, u16* __restrict__ h, char* smem) {
;     ...
;         for (int j = 0; j < 4; ++j) {
;           int row = m0 + wm * 128 + ms * 16 + quad * 4 + j;
;           int col = cb + ns * 16 + l15;
;           float v = acc[ms][ns][j];
;           if (mode == 1) { float lbv = lbp[col - C_HF]; v = __logf(lbv + (1.f - lbv) / (1.f + __expf(-v))); }
;           else if (mode == 2) v = v / (1.f + __expf(-v));
;           h[(size_t)row * HS + col] = f2bf(v);
.LBB0_1606:
	s_andn2_b64 vcc, exec, s[4:5]
	s_cbranch_vccnz .LBB0_1609
	s_cmp_eq_u32 s17, 1
	v_mov_b32_e32 v144, v24
	s_cbranch_scc0 .LBB0_1609
	v_lshl_add_u64 v[144:145], v[0:1], 2, s[14:15]
	v_add_co_u32_e32 v144, vcc, 0xfffff000, v144
	s_nop 1
	v_addc_co_u32_e32 v145, vcc, -1, v145, vcc
	v_mov_b32_e32 v144, v160
	v_mul_f32_e32 v145, 0xbfb8aa3b, v24
	v_exp_f32_e32 v145, v145
	v_sub_f32_e32 v146, 1.0, v144
	v_add_f32_e32 v145, 1.0, v145
	v_div_scale_f32 v147, s[4:5], v145, v145, v146
	v_rcp_f32_e32 v148, v147
	v_div_scale_f32 v149, vcc, v146, v145, v146
	s_mov_b32 s4, 0x800000
	v_fma_f32 v150, -v147, v148, 1.0
	v_fmac_f32_e32 v148, v150, v148
	v_mul_f32_e32 v150, v149, v148
	v_fma_f32 v151, -v147, v150, v149
	v_fmac_f32_e32 v150, v151, v148
	v_fma_f32 v147, -v147, v150, v149
	v_div_fmas_f32 v147, v147, v148, v150
	v_div_fixup_f32 v145, v147, v145, v146
	v_add_f32_e32 v144, v144, v145
	v_cmp_gt_f32_e32 vcc, s4, v144
	s_mov_b32 s4, 0x3f317217
	s_nop 0
	v_cndmask_b32_e64 v145, 0, 32, vcc
	v_ldexp_f32 v144, v144, v145
	v_log_f32_e32 v144, v144
	s_nop 0
	v_mul_f32_e32 v145, 0x3f317217, v144
	v_fma_f32 v145, v144, s4, -v145
	v_fmac_f32_e32 v145, 0x3377d1cf, v144
	s_mov_b32 s4, 0x7f800000
	v_fmac_f32_e32 v145, 0x3f317217, v144
	v_cmp_lt_f32_e64 s[12:13], |v144|, s4
	s_nop 1
	v_cndmask_b32_e64 v144, v144, v145, s[12:13]
	v_cndmask_b32_e32 v145, 0, v227, vcc
	v_sub_f32_e32 v144, v144, v145

; DEV u16 f2bf(float f) { return (u16)(pack2(f, 0.f) & 0xffffu); }
; DEV void phase_win(const Params& P, int l, const u16* __restrict__ xb, const u16* __restrict__ Wt, u16* __restrict__ h, char* smem) {
;     ...
;         for (int j = 0; j < 4; ++j) {
;           int row = m0 + wm * 128 + ms * 16 + quad * 4 + j;
;           int col = cb + ns * 16 + l15;
;           float v = acc[ms][ns][j];
;           if (mode == 1) { float lbv = lbp[col - C_HF]; v = __logf(lbv + (1.f - lbv) / (1.f + __expf(-v))); }
;           else if (mode == 2) v = v / (1.f + __expf(-v));
;           h[(size_t)row * HS + col] = f2bf(v);
.LBB0_1611:
	s_andn2_b64 vcc, exec, s[4:5]
	s_cbranch_vccnz .LBB0_1614
	s_cmp_eq_u32 s17, 1
	v_mov_b32_e32 v146, v25
	s_cbranch_scc0 .LBB0_1614
	v_lshl_add_u64 v[146:147], v[0:1], 2, s[14:15]
	v_add_co_u32_e32 v146, vcc, 0xfffff000, v146
	s_nop 1
	v_addc_co_u32_e32 v147, vcc, -1, v147, vcc
	v_mov_b32_e32 v146, v160
	v_mul_f32_e32 v147, 0xbfb8aa3b, v25
	v_exp_f32_e32 v147, v147
	v_sub_f32_e32 v148, 1.0, v146
	v_add_f32_e32 v147, 1.0, v147
	v_div_scale_f32 v149, s[4:5], v147, v147, v148
	v_rcp_f32_e32 v150, v149
	v_div_scale_f32 v151, vcc, v148, v147, v148
	s_mov_b32 s4, 0x800000
	v_fma_f32 v152, -v149, v150, 1.0
	v_fmac_f32_e32 v150, v152, v150
	v_mul_f32_e32 v152, v151, v150
	v_fma_f32 v153, -v149, v152, v151
	v_fmac_f32_e32 v152, v153, v150
	v_fma_f32 v149, -v149, v152, v151
	v_div_fmas_f32 v149, v149, v150, v152
	v_div_fixup_f32 v147, v149, v147, v148
	v_add_f32_e32 v146, v146, v147
	v_cmp_gt_f32_e32 vcc, s4, v146
	s_mov_b32 s4, 0x3f317217
	s_nop 0
	v_cndmask_b32_e64 v147, 0, 32, vcc
	v_ldexp_f32 v146, v146, v147
	v_log_f32_e32 v146, v146
	s_nop 0
	v_mul_f32_e32 v147, 0x3f317217, v146
	v_fma_f32 v147, v146, s4, -v147
	v_fmac_f32_e32 v147, 0x3377d1cf, v146
	s_mov_b32 s4, 0x7f800000
	v_fmac_f32_e32 v147, 0x3f317217, v146
	v_cmp_lt_f32_e64 s[12:13], |v146|, s4
	s_nop 1
	v_cndmask_b32_e64 v146, v146, v147, s[12:13]
	v_cndmask_b32_e32 v147, 0, v227, vcc
	v_sub_f32_e32 v146, v146, v147

; DEV u16 f2bf(float f) { return (u16)(pack2(f, 0.f) & 0xffffu); }
; DEV void phase_win(const Params& P, int l, const u16* __restrict__ xb, const u16* __restrict__ Wt, u16* __restrict__ h, char* smem) {
;     ...
;         for (int j = 0; j < 4; ++j) {
;           int row = m0 + wm * 128 + ms * 16 + quad * 4 + j;
;           int col = cb + ns * 16 + l15;
;           float v = acc[ms][ns][j];
;           if (mode == 1) { float lbv = lbp[col - C_HF]; v = __logf(lbv + (1.f - lbv) / (1.f + __expf(-v))); }
;           else if (mode == 2) v = v / (1.f + __expf(-v));
;           h[(size_t)row * HS + col] = f2bf(v);
.LBB0_1616:
	s_andn2_b64 vcc, exec, s[4:5]
	s_cbranch_vccnz .LBB0_1619
	s_cmp_eq_u32 s17, 1
	v_mov_b32_e32 v131, v98
	s_cbranch_scc0 .LBB0_1619
	v_lshl_add_u64 v[148:149], v[0:1], 2, s[14:15]
	v_add_co_u32_e32 v148, vcc, 0xfffff000, v148
	s_nop 1
	v_addc_co_u32_e32 v149, vcc, -1, v149, vcc
	v_mov_b32_e32 v131, v161
	v_mul_f32_e32 v148, 0xbfb8aa3b, v98
	v_exp_f32_e32 v148, v148
	v_sub_f32_e32 v149, 1.0, v131
	v_add_f32_e32 v148, 1.0, v148
	v_div_scale_f32 v150, s[4:5], v148, v148, v149
	v_rcp_f32_e32 v151, v150
	v_div_scale_f32 v152, vcc, v149, v148, v149
	s_mov_b32 s4, 0x800000
	v_fma_f32 v153, -v150, v151, 1.0
	v_fmac_f32_e32 v151, v153, v151
	v_mul_f32_e32 v153, v152, v151
	v_fma_f32 v154, -v150, v153, v152
	v_fmac_f32_e32 v153, v154, v151
	v_fma_f32 v150, -v150, v153, v152
	v_div_fmas_f32 v150, v150, v151, v153
	v_div_fixup_f32 v148, v150, v148, v149
	v_add_f32_e32 v131, v131, v148
	v_cmp_gt_f32_e32 vcc, s4, v131
	s_mov_b32 s4, 0x3f317217
	s_nop 0
	v_cndmask_b32_e64 v148, 0, 32, vcc
	v_ldexp_f32 v131, v131, v148
	v_log_f32_e32 v131, v131
	s_nop 0
	v_mul_f32_e32 v148, 0x3f317217, v131
	v_fma_f32 v148, v131, s4, -v148
	v_fmac_f32_e32 v148, 0x3377d1cf, v131
	s_mov_b32 s4, 0x7f800000
	v_fmac_f32_e32 v148, 0x3f317217, v131
	v_cmp_lt_f32_e64 s[12:13], |v131|, s4
	s_nop 1
	v_cndmask_b32_e64 v131, v131, v148, s[12:13]
	v_cndmask_b32_e32 v148, 0, v227, vcc
	v_sub_f32_e32 v131, v131, v148

; DEV u16 f2bf(float f) { return (u16)(pack2(f, 0.f) & 0xffffu); }
; DEV void phase_win(const Params& P, int l, const u16* __restrict__ xb, const u16* __restrict__ Wt, u16* __restrict__ h, char* smem) {
;     ...
;         for (int j = 0; j < 4; ++j) {
;           int row = m0 + wm * 128 + ms * 16 + quad * 4 + j;
;           int col = cb + ns * 16 + l15;
;           float v = acc[ms][ns][j];
;           if (mode == 1) { float lbv = lbp[col - C_HF]; v = __logf(lbv + (1.f - lbv) / (1.f + __expf(-v))); }
;           else if (mode == 2) v = v / (1.f + __expf(-v));
;           h[(size_t)row * HS + col] = f2bf(v);
.LBB0_1621:
	s_andn2_b64 vcc, exec, s[4:5]
	s_cbranch_vccnz .LBB0_1624
	s_cmp_eq_u32 s17, 1
	v_mov_b32_e32 v131, v99
	s_cbranch_scc0 .LBB0_1624
	v_lshl_add_u64 v[148:149], v[0:1], 2, s[14:15]
	v_add_co_u32_e32 v148, vcc, 0xfffff000, v148
	s_nop 1
	v_addc_co_u32_e32 v149, vcc, -1, v149, vcc
	v_mov_b32_e32 v131, v161
	v_mul_f32_e32 v148, 0xbfb8aa3b, v99
	v_exp_f32_e32 v148, v148
	v_sub_f32_e32 v149, 1.0, v131
	v_add_f32_e32 v148, 1.0, v148
	v_div_scale_f32 v150, s[4:5], v148, v148, v149
	v_rcp_f32_e32 v151, v150
	v_div_scale_f32 v152, vcc, v149, v148, v149
	s_mov_b32 s4, 0x800000
	v_fma_f32 v153, -v150, v151, 1.0
	v_fmac_f32_e32 v151, v153, v151
	v_mul_f32_e32 v153, v152, v151
	v_fma_f32 v154, -v150, v153, v152
	v_fmac_f32_e32 v153, v154, v151
	v_fma_f32 v150, -v150, v153, v152
	v_div_fmas_f32 v150, v150, v151, v153
	v_div_fixup_f32 v148, v150, v148, v149
	v_add_f32_e32 v131, v131, v148
	v_cmp_gt_f32_e32 vcc, s4, v131
	s_mov_b32 s4, 0x3f317217
	s_nop 0
	v_cndmask_b32_e64 v148, 0, 32, vcc
	v_ldexp_f32 v131, v131, v148
	v_log_f32_e32 v131, v131
	s_nop 0
	v_mul_f32_e32 v148, 0x3f317217, v131
	v_fma_f32 v148, v131, s4, -v148
	v_fmac_f32_e32 v148, 0x3377d1cf, v131
	s_mov_b32 s4, 0x7f800000
	v_fmac_f32_e32 v148, 0x3f317217, v131
	v_cmp_lt_f32_e64 s[12:13], |v131|, s4
	s_nop 1
	v_cndmask_b32_e64 v131, v131, v148, s[12:13]
	v_cndmask_b32_e32 v148, 0, v227, vcc
	v_sub_f32_e32 v131, v131, v148

; DEV u16 f2bf(float f) { return (u16)(pack2(f, 0.f) & 0xffffu); }
; DEV void phase_win(const Params& P, int l, const u16* __restrict__ xb, const u16* __restrict__ Wt, u16* __restrict__ h, char* smem) {
;     ...
;         for (int j = 0; j < 4; ++j) {
;           int row = m0 + wm * 128 + ms * 16 + quad * 4 + j;
;           int col = cb + ns * 16 + l15;
;           float v = acc[ms][ns][j];
;           if (mode == 1) { float lbv = lbp[col - C_HF]; v = __logf(lbv + (1.f - lbv) / (1.f + __expf(-v))); }
;           else if (mode == 2) v = v / (1.f + __expf(-v));
;           h[(size_t)row * HS + col] = f2bf(v);
.LBB0_1626:
	s_andn2_b64 vcc, exec, s[4:5]
	s_cbranch_vccnz .LBB0_1629
	s_cmp_eq_u32 s17, 1
	v_mov_b32_e32 v131, v100
	s_cbranch_scc0 .LBB0_1629
	v_lshl_add_u64 v[148:149], v[0:1], 2, s[14:15]
	v_add_co_u32_e32 v148, vcc, 0xfffff000, v148
	s_nop 1
	v_addc_co_u32_e32 v149, vcc, -1, v149, vcc
	v_mov_b32_e32 v131, v161
	v_mul_f32_e32 v148, 0xbfb8aa3b, v100
	v_exp_f32_e32 v148, v148
	v_sub_f32_e32 v149, 1.0, v131
	v_add_f32_e32 v148, 1.0, v148
	v_div_scale_f32 v150, s[4:5], v148, v148, v149
	v_rcp_f32_e32 v151, v150
	v_div_scale_f32 v152, vcc, v149, v148, v149
	s_mov_b32 s4, 0x800000
	v_fma_f32 v153, -v150, v151, 1.0
	v_fmac_f32_e32 v151, v153, v151
	v_mul_f32_e32 v153, v152, v151
	v_fma_f32 v154, -v150, v153, v152
	v_fmac_f32_e32 v153, v154, v151
	v_fma_f32 v150, -v150, v153, v152
	v_div_fmas_f32 v150, v150, v151, v153
	v_div_fixup_f32 v148, v150, v148, v149
	v_add_f32_e32 v131, v131, v148
	v_cmp_gt_f32_e32 vcc, s4, v131
	s_mov_b32 s4, 0x3f317217
	s_nop 0
	v_cndmask_b32_e64 v148, 0, 32, vcc
	v_ldexp_f32 v131, v131, v148
	v_log_f32_e32 v131, v131
	s_nop 0
	v_mul_f32_e32 v148, 0x3f317217, v131
	v_fma_f32 v148, v131, s4, -v148
	v_fmac_f32_e32 v148, 0x3377d1cf, v131
	s_mov_b32 s4, 0x7f800000
	v_fmac_f32_e32 v148, 0x3f317217, v131
	v_cmp_lt_f32_e64 s[12:13], |v131|, s4
	s_nop 1
	v_cndmask_b32_e64 v131, v131, v148, s[12:13]
	v_cndmask_b32_e32 v148, 0, v227, vcc
	v_sub_f32_e32 v131, v131, v148

; DEV u16 f2bf(float f) { return (u16)(pack2(f, 0.f) & 0xffffu); }
; DEV void phase_win(const Params& P, int l, const u16* __restrict__ xb, const u16* __restrict__ Wt, u16* __restrict__ h, char* smem) {
;     ...
;         for (int j = 0; j < 4; ++j) {
;           int row = m0 + wm * 128 + ms * 16 + quad * 4 + j;
;           int col = cb + ns * 16 + l15;
;           float v = acc[ms][ns][j];
;           if (mode == 1) { float lbv = lbp[col - C_HF]; v = __logf(lbv + (1.f - lbv) / (1.f + __expf(-v))); }
;           else if (mode == 2) v = v / (1.f + __expf(-v));
;           h[(size_t)row * HS + col] = f2bf(v);
.LBB0_1631:
	s_andn2_b64 vcc, exec, s[4:5]
	s_cbranch_vccnz .LBB0_1634
	s_cmp_eq_u32 s17, 1
	v_mov_b32_e32 v131, v101
	s_cbranch_scc0 .LBB0_1634
	v_lshl_add_u64 v[148:149], v[0:1], 2, s[14:15]
	v_add_co_u32_e32 v148, vcc, 0xfffff000, v148
	s_nop 1
	v_addc_co_u32_e32 v149, vcc, -1, v149, vcc
	v_mov_b32_e32 v131, v161
	v_mul_f32_e32 v148, 0xbfb8aa3b, v101
	v_exp_f32_e32 v148, v148
	v_sub_f32_e32 v149, 1.0, v131
	v_add_f32_e32 v148, 1.0, v148
	v_div_scale_f32 v150, s[4:5], v148, v148, v149
	v_rcp_f32_e32 v151, v150
	v_div_scale_f32 v152, vcc, v149, v148, v149
	s_mov_b32 s4, 0x800000
	v_fma_f32 v153, -v150, v151, 1.0
	v_fmac_f32_e32 v151, v153, v151
	v_mul_f32_e32 v153, v152, v151
	v_fma_f32 v154, -v150, v153, v152
	v_fmac_f32_e32 v153, v154, v151
	v_fma_f32 v150, -v150, v153, v152
	v_div_fmas_f32 v150, v150, v151, v153
	v_div_fixup_f32 v148, v150, v148, v149
	v_add_f32_e32 v131, v131, v148
	v_cmp_gt_f32_e32 vcc, s4, v131
	s_mov_b32 s4, 0x3f317217
	s_nop 0
	v_cndmask_b32_e64 v148, 0, 32, vcc
	v_ldexp_f32 v131, v131, v148
	v_log_f32_e32 v131, v131
	s_nop 0
	v_mul_f32_e32 v148, 0x3f317217, v131
	v_fma_f32 v148, v131, s4, -v148
	v_fmac_f32_e32 v148, 0x3377d1cf, v131
	s_mov_b32 s4, 0x7f800000
	v_fmac_f32_e32 v148, 0x3f317217, v131
	v_cmp_lt_f32_e64 s[12:13], |v131|, s4
	s_nop 1
	v_cndmask_b32_e64 v131, v131, v148, s[12:13]
	v_cndmask_b32_e32 v148, 0, v227, vcc
	v_sub_f32_e32 v131, v131, v148

; DEV u16 f2bf(float f) { return (u16)(pack2(f, 0.f) & 0xffffu); }
; DEV void phase_win(const Params& P, int l, const u16* __restrict__ xb, const u16* __restrict__ Wt, u16* __restrict__ h, char* smem) {
;     ...
;         for (int j = 0; j < 4; ++j) {
;           int row = m0 + wm * 128 + ms * 16 + quad * 4 + j;
;           int col = cb + ns * 16 + l15;
;           float v = acc[ms][ns][j];
;           if (mode == 1) { float lbv = lbp[col - C_HF]; v = __logf(lbv + (1.f - lbv) / (1.f + __expf(-v))); }
;           else if (mode == 2) v = v / (1.f + __expf(-v));
;           h[(size_t)row * HS + col] = f2bf(v);
.LBB0_1636:
	s_andn2_b64 vcc, exec, s[4:5]
	s_cbranch_vccnz .LBB0_1639
	s_cmp_eq_u32 s17, 1
	v_mov_b32_e32 v131, v102
	s_cbranch_scc0 .LBB0_1639
	v_lshl_add_u64 v[148:149], v[0:1], 2, s[14:15]
	v_add_co_u32_e32 v148, vcc, 0xfffff000, v148
	s_nop 1
	v_addc_co_u32_e32 v149, vcc, -1, v149, vcc
	v_mov_b32_e32 v131, v162
	v_mul_f32_e32 v148, 0xbfb8aa3b, v102
	v_exp_f32_e32 v148, v148
	v_sub_f32_e32 v149, 1.0, v131
	v_add_f32_e32 v148, 1.0, v148
	v_div_scale_f32 v150, s[4:5], v148, v148, v149
	v_rcp_f32_e32 v151, v150
	v_div_scale_f32 v152, vcc, v149, v148, v149
	s_mov_b32 s4, 0x800000
	v_fma_f32 v153, -v150, v151, 1.0
	v_fmac_f32_e32 v151, v153, v151
	v_mul_f32_e32 v153, v152, v151
	v_fma_f32 v154, -v150, v153, v152
	v_fmac_f32_e32 v153, v154, v151
	v_fma_f32 v150, -v150, v153, v152
	v_div_fmas_f32 v150, v150, v151, v153
	v_div_fixup_f32 v148, v150, v148, v149
	v_add_f32_e32 v131, v131, v148
	v_cmp_gt_f32_e32 vcc, s4, v131
	s_mov_b32 s4, 0x3f317217
	s_nop 0
	v_cndmask_b32_e64 v148, 0, 32, vcc
	v_ldexp_f32 v131, v131, v148
	v_log_f32_e32 v131, v131
	s_nop 0
	v_mul_f32_e32 v148, 0x3f317217, v131
	v_fma_f32 v148, v131, s4, -v148
	v_fmac_f32_e32 v148, 0x3377d1cf, v131
	s_mov_b32 s4, 0x7f800000
	v_fmac_f32_e32 v148, 0x3f317217, v131
	v_cmp_lt_f32_e64 s[12:13], |v131|, s4
	s_nop 1
	v_cndmask_b32_e64 v131, v131, v148, s[12:13]
	v_cndmask_b32_e32 v148, 0, v227, vcc
	v_sub_f32_e32 v131, v131, v148

; DEV u16 f2bf(float f) { return (u16)(pack2(f, 0.f) & 0xffffu); }
; DEV void phase_win(const Params& P, int l, const u16* __restrict__ xb, const u16* __restrict__ Wt, u16* __restrict__ h, char* smem) {
;     ...
;         for (int j = 0; j < 4; ++j) {
;           int row = m0 + wm * 128 + ms * 16 + quad * 4 + j;
;           int col = cb + ns * 16 + l15;
;           float v = acc[ms][ns][j];
;           if (mode == 1) { float lbv = lbp[col - C_HF]; v = __logf(lbv + (1.f - lbv) / (1.f + __expf(-v))); }
;           else if (mode == 2) v = v / (1.f + __expf(-v));
;           h[(size_t)row * HS + col] = f2bf(v);
.LBB0_1641:
	s_andn2_b64 vcc, exec, s[4:5]
	s_cbranch_vccnz .LBB0_1644
	s_cmp_eq_u32 s17, 1
	v_mov_b32_e32 v131, v103
	s_cbranch_scc0 .LBB0_1644
	v_lshl_add_u64 v[148:149], v[0:1], 2, s[14:15]
	v_add_co_u32_e32 v148, vcc, 0xfffff000, v148
	s_nop 1
	v_addc_co_u32_e32 v149, vcc, -1, v149, vcc
	v_mov_b32_e32 v131, v162
	v_mul_f32_e32 v148, 0xbfb8aa3b, v103
	v_exp_f32_e32 v148, v148
	v_sub_f32_e32 v149, 1.0, v131
	v_add_f32_e32 v148, 1.0, v148
	v_div_scale_f32 v150, s[4:5], v148, v148, v149
	v_rcp_f32_e32 v151, v150
	v_div_scale_f32 v152, vcc, v149, v148, v149
	s_mov_b32 s4, 0x800000
	v_fma_f32 v153, -v150, v151, 1.0
	v_fmac_f32_e32 v151, v153, v151
	v_mul_f32_e32 v153, v152, v151
	v_fma_f32 v154, -v150, v153, v152
	v_fmac_f32_e32 v153, v154, v151
	v_fma_f32 v150, -v150, v153, v152
	v_div_fmas_f32 v150, v150, v151, v153
	v_div_fixup_f32 v148, v150, v148, v149
	v_add_f32_e32 v131, v131, v148
	v_cmp_gt_f32_e32 vcc, s4, v131
	s_mov_b32 s4, 0x3f317217
	s_nop 0
	v_cndmask_b32_e64 v148, 0, 32, vcc
	v_ldexp_f32 v131, v131, v148
	v_log_f32_e32 v131, v131
	s_nop 0
	v_mul_f32_e32 v148, 0x3f317217, v131
	v_fma_f32 v148, v131, s4, -v148
	v_fmac_f32_e32 v148, 0x3377d1cf, v131
	s_mov_b32 s4, 0x7f800000
	v_fmac_f32_e32 v148, 0x3f317217, v131
	v_cmp_lt_f32_e64 s[12:13], |v131|, s4
	s_nop 1
	v_cndmask_b32_e64 v131, v131, v148, s[12:13]
	v_cndmask_b32_e32 v148, 0, v227, vcc
	v_sub_f32_e32 v131, v131, v148

; DEV u16 f2bf(float f) { return (u16)(pack2(f, 0.f) & 0xffffu); }
; DEV void phase_win(const Params& P, int l, const u16* __restrict__ xb, const u16* __restrict__ Wt, u16* __restrict__ h, char* smem) {
;     ...
;         for (int j = 0; j < 4; ++j) {
;           int row = m0 + wm * 128 + ms * 16 + quad * 4 + j;
;           int col = cb + ns * 16 + l15;
;           float v = acc[ms][ns][j];
;           if (mode == 1) { float lbv = lbp[col - C_HF]; v = __logf(lbv + (1.f - lbv) / (1.f + __expf(-v))); }
;           else if (mode == 2) v = v / (1.f + __expf(-v));
;           h[(size_t)row * HS + col] = f2bf(v);
.LBB0_1646:
	s_andn2_b64 vcc, exec, s[4:5]
	s_cbranch_vccnz .LBB0_1649
	s_cmp_eq_u32 s17, 1
	v_mov_b32_e32 v131, v104
	s_cbranch_scc0 .LBB0_1649
	v_lshl_add_u64 v[148:149], v[0:1], 2, s[14:15]
	v_add_co_u32_e32 v148, vcc, 0xfffff000, v148
	s_nop 1
	v_addc_co_u32_e32 v149, vcc, -1, v149, vcc
	v_mov_b32_e32 v131, v162
	v_mul_f32_e32 v148, 0xbfb8aa3b, v104
	v_exp_f32_e32 v148, v148
	v_sub_f32_e32 v149, 1.0, v131
	v_add_f32_e32 v148, 1.0, v148
	v_div_scale_f32 v150, s[4:5], v148, v148, v149
	v_rcp_f32_e32 v151, v150
	v_div_scale_f32 v152, vcc, v149, v148, v149
	s_mov_b32 s4, 0x800000
	v_fma_f32 v153, -v150, v151, 1.0
	v_fmac_f32_e32 v151, v153, v151
	v_mul_f32_e32 v153, v152, v151
	v_fma_f32 v154, -v150, v153, v152
	v_fmac_f32_e32 v153, v154, v151
	v_fma_f32 v150, -v150, v153, v152
	v_div_fmas_f32 v150, v150, v151, v153
	v_div_fixup_f32 v148, v150, v148, v149
	v_add_f32_e32 v131, v131, v148
	v_cmp_gt_f32_e32 vcc, s4, v131
	s_mov_b32 s4, 0x3f317217
	s_nop 0
	v_cndmask_b32_e64 v148, 0, 32, vcc
	v_ldexp_f32 v131, v131, v148
	v_log_f32_e32 v131, v131
	s_nop 0
	v_mul_f32_e32 v148, 0x3f317217, v131
	v_fma_f32 v148, v131, s4, -v148
	v_fmac_f32_e32 v148, 0x3377d1cf, v131
	s_mov_b32 s4, 0x7f800000
	v_fmac_f32_e32 v148, 0x3f317217, v131
	v_cmp_lt_f32_e64 s[12:13], |v131|, s4
	s_nop 1
	v_cndmask_b32_e64 v131, v131, v148, s[12:13]
	v_cndmask_b32_e32 v148, 0, v227, vcc
	v_sub_f32_e32 v131, v131, v148

; DEV u16 f2bf(float f) { return (u16)(pack2(f, 0.f) & 0xffffu); }
; DEV void phase_win(const Params& P, int l, const u16* __restrict__ xb, const u16* __restrict__ Wt, u16* __restrict__ h, char* smem) {
;     ...
;         for (int j = 0; j < 4; ++j) {
;           int row = m0 + wm * 128 + ms * 16 + quad * 4 + j;
;           int col = cb + ns * 16 + l15;
;           float v = acc[ms][ns][j];
;           if (mode == 1) { float lbv = lbp[col - C_HF]; v = __logf(lbv + (1.f - lbv) / (1.f + __expf(-v))); }
;           else if (mode == 2) v = v / (1.f + __expf(-v));
;           h[(size_t)row * HS + col] = f2bf(v);
.LBB0_1651:
	s_andn2_b64 vcc, exec, s[4:5]
	s_cbranch_vccnz .LBB0_1654
	s_cmp_eq_u32 s17, 1
	v_mov_b32_e32 v131, v105
	s_cbranch_scc0 .LBB0_1654
	v_lshl_add_u64 v[148:149], v[0:1], 2, s[14:15]
	v_add_co_u32_e32 v148, vcc, 0xfffff000, v148
	s_nop 1
	v_addc_co_u32_e32 v149, vcc, -1, v149, vcc
	v_mov_b32_e32 v131, v162
	v_mul_f32_e32 v148, 0xbfb8aa3b, v105
	v_exp_f32_e32 v148, v148
	v_sub_f32_e32 v149, 1.0, v131
	v_add_f32_e32 v148, 1.0, v148
	v_div_scale_f32 v150, s[4:5], v148, v148, v149
	v_rcp_f32_e32 v151, v150
	v_div_scale_f32 v152, vcc, v149, v148, v149
	s_mov_b32 s4, 0x800000
	v_fma_f32 v153, -v150, v151, 1.0
	v_fmac_f32_e32 v151, v153, v151
	v_mul_f32_e32 v153, v152, v151
	v_fma_f32 v154, -v150, v153, v152
	v_fmac_f32_e32 v153, v154, v151
	v_fma_f32 v150, -v150, v153, v152
	v_div_fmas_f32 v150, v150, v151, v153
	v_div_fixup_f32 v148, v150, v148, v149
	v_add_f32_e32 v131, v131, v148
	v_cmp_gt_f32_e32 vcc, s4, v131
	s_mov_b32 s4, 0x3f317217
	s_nop 0
	v_cndmask_b32_e64 v148, 0, 32, vcc
	v_ldexp_f32 v131, v131, v148
	v_log_f32_e32 v131, v131
	s_nop 0
	v_mul_f32_e32 v148, 0x3f317217, v131
	v_fma_f32 v148, v131, s4, -v148
	v_fmac_f32_e32 v148, 0x3377d1cf, v131
	s_mov_b32 s4, 0x7f800000
	v_fmac_f32_e32 v148, 0x3f317217, v131
	v_cmp_lt_f32_e64 s[12:13], |v131|, s4
	s_nop 1
	v_cndmask_b32_e64 v131, v131, v148, s[12:13]
	v_cndmask_b32_e32 v148, 0, v227, vcc
	v_sub_f32_e32 v131, v131, v148

; DEV u16 f2bf(float f) { return (u16)(pack2(f, 0.f) & 0xffffu); }
; DEV void phase_win(const Params& P, int l, const u16* __restrict__ xb, const u16* __restrict__ Wt, u16* __restrict__ h, char* smem) {
;     ...
;         for (int j = 0; j < 4; ++j) {
;           int row = m0 + wm * 128 + ms * 16 + quad * 4 + j;
;           int col = cb + ns * 16 + l15;
;           float v = acc[ms][ns][j];
;           if (mode == 1) { float lbv = lbp[col - C_HF]; v = __logf(lbv + (1.f - lbv) / (1.f + __expf(-v))); }
;           else if (mode == 2) v = v / (1.f + __expf(-v));
;           h[(size_t)row * HS + col] = f2bf(v);
.LBB0_1656:
	s_andn2_b64 vcc, exec, s[4:5]
	s_cbranch_vccnz .LBB0_1659
	s_cmp_eq_u32 s17, 1
	v_mov_b32_e32 v131, v94
	s_cbranch_scc0 .LBB0_1659
	v_lshl_add_u64 v[148:149], v[0:1], 2, s[14:15]
	v_add_co_u32_e32 v148, vcc, 0xfffff000, v148
	s_nop 1
	v_addc_co_u32_e32 v149, vcc, -1, v149, vcc
	v_mov_b32_e32 v131, v163
	v_mul_f32_e32 v148, 0xbfb8aa3b, v94
	v_exp_f32_e32 v148, v148
	v_sub_f32_e32 v149, 1.0, v131
	v_add_f32_e32 v148, 1.0, v148
	v_div_scale_f32 v150, s[4:5], v148, v148, v149
	v_rcp_f32_e32 v151, v150
	v_div_scale_f32 v152, vcc, v149, v148, v149
	s_mov_b32 s4, 0x800000
	v_fma_f32 v153, -v150, v151, 1.0
	v_fmac_f32_e32 v151, v153, v151
	v_mul_f32_e32 v153, v152, v151
	v_fma_f32 v154, -v150, v153, v152
	v_fmac_f32_e32 v153, v154, v151
	v_fma_f32 v150, -v150, v153, v152
	v_div_fmas_f32 v150, v150, v151, v153
	v_div_fixup_f32 v148, v150, v148, v149
	v_add_f32_e32 v131, v131, v148
	v_cmp_gt_f32_e32 vcc, s4, v131
	s_mov_b32 s4, 0x3f317217
	s_nop 0
	v_cndmask_b32_e64 v148, 0, 32, vcc
	v_ldexp_f32 v131, v131, v148
	v_log_f32_e32 v131, v131
	s_nop 0
	v_mul_f32_e32 v148, 0x3f317217, v131
	v_fma_f32 v148, v131, s4, -v148
	v_fmac_f32_e32 v148, 0x3377d1cf, v131
	s_mov_b32 s4, 0x7f800000
	v_fmac_f32_e32 v148, 0x3f317217, v131
	v_cmp_lt_f32_e64 s[12:13], |v131|, s4
	s_nop 1
	v_cndmask_b32_e64 v131, v131, v148, s[12:13]
	v_cndmask_b32_e32 v148, 0, v227, vcc
	v_sub_f32_e32 v131, v131, v148

; DEV u16 f2bf(float f) { return (u16)(pack2(f, 0.f) & 0xffffu); }
; DEV void phase_win(const Params& P, int l, const u16* __restrict__ xb, const u16* __restrict__ Wt, u16* __restrict__ h, char* smem) {
;     ...
;         for (int j = 0; j < 4; ++j) {
;           int row = m0 + wm * 128 + ms * 16 + quad * 4 + j;
;           int col = cb + ns * 16 + l15;
;           float v = acc[ms][ns][j];
;           if (mode == 1) { float lbv = lbp[col - C_HF]; v = __logf(lbv + (1.f - lbv) / (1.f + __expf(-v))); }
;           else if (mode == 2) v = v / (1.f + __expf(-v));
;           h[(size_t)row * HS + col] = f2bf(v);
.LBB0_1661:
	s_andn2_b64 vcc, exec, s[4:5]
	s_cbranch_vccnz .LBB0_1664
	s_cmp_eq_u32 s17, 1
	v_mov_b32_e32 v131, v95
	s_cbranch_scc0 .LBB0_1664
	v_lshl_add_u64 v[140:141], v[0:1], 2, s[14:15]
	v_add_co_u32_e32 v140, vcc, 0xfffff000, v140
	s_nop 1
	v_addc_co_u32_e32 v141, vcc, -1, v141, vcc
	v_mov_b32_e32 v131, v163
	v_mul_f32_e32 v140, 0xbfb8aa3b, v95
	v_exp_f32_e32 v140, v140
	v_sub_f32_e32 v141, 1.0, v131
	v_add_f32_e32 v140, 1.0, v140
	v_div_scale_f32 v148, s[4:5], v140, v140, v141
	v_rcp_f32_e32 v149, v148
	v_div_scale_f32 v150, vcc, v141, v140, v141
	s_mov_b32 s4, 0x800000
	v_fma_f32 v151, -v148, v149, 1.0
	v_fmac_f32_e32 v149, v151, v149
	v_mul_f32_e32 v151, v150, v149
	v_fma_f32 v152, -v148, v151, v150
	v_fmac_f32_e32 v151, v152, v149
	v_fma_f32 v148, -v148, v151, v150
	v_div_fmas_f32 v148, v148, v149, v151
	v_div_fixup_f32 v140, v148, v140, v141
	v_add_f32_e32 v131, v131, v140
	v_cmp_gt_f32_e32 vcc, s4, v131
	s_mov_b32 s4, 0x3f317217
	s_nop 0
	v_cndmask_b32_e64 v140, 0, 32, vcc
	v_ldexp_f32 v131, v131, v140
	v_log_f32_e32 v131, v131
	s_nop 0
	v_mul_f32_e32 v140, 0x3f317217, v131
	v_fma_f32 v140, v131, s4, -v140
	v_fmac_f32_e32 v140, 0x3377d1cf, v131
	s_mov_b32 s4, 0x7f800000
	v_fmac_f32_e32 v140, 0x3f317217, v131
	v_cmp_lt_f32_e64 s[12:13], |v131|, s4
	s_nop 1
	v_cndmask_b32_e64 v131, v131, v140, s[12:13]
	v_cndmask_b32_e32 v140, 0, v227, vcc
	v_sub_f32_e32 v131, v131, v140

; DEV u16 f2bf(float f) { return (u16)(pack2(f, 0.f) & 0xffffu); }
; DEV void phase_win(const Params& P, int l, const u16* __restrict__ xb, const u16* __restrict__ Wt, u16* __restrict__ h, char* smem) {
;     ...
;         for (int j = 0; j < 4; ++j) {
;           int row = m0 + wm * 128 + ms * 16 + quad * 4 + j;
;           int col = cb + ns * 16 + l15;
;           float v = acc[ms][ns][j];
;           if (mode == 1) { float lbv = lbp[col - C_HF]; v = __logf(lbv + (1.f - lbv) / (1.f + __expf(-v))); }
;           else if (mode == 2) v = v / (1.f + __expf(-v));
;           h[(size_t)row * HS + col] = f2bf(v);
.LBB0_1666:
	s_andn2_b64 vcc, exec, s[4:5]
	s_cbranch_vccnz .LBB0_1669
	s_cmp_eq_u32 s17, 1
	v_mov_b32_e32 v131, v96
	s_cbranch_scc0 .LBB0_1669
	v_lshl_add_u64 v[140:141], v[0:1], 2, s[14:15]
	v_add_co_u32_e32 v140, vcc, 0xfffff000, v140
	s_nop 1
	v_addc_co_u32_e32 v141, vcc, -1, v141, vcc
	v_mov_b32_e32 v131, v163
	v_mul_f32_e32 v140, 0xbfb8aa3b, v96
	v_exp_f32_e32 v140, v140
	v_sub_f32_e32 v141, 1.0, v131
	v_add_f32_e32 v140, 1.0, v140
	v_div_scale_f32 v142, s[4:5], v140, v140, v141
	v_rcp_f32_e32 v143, v142
	v_div_scale_f32 v148, vcc, v141, v140, v141
	s_mov_b32 s4, 0x800000
	v_fma_f32 v149, -v142, v143, 1.0
	v_fmac_f32_e32 v143, v149, v143
	v_mul_f32_e32 v149, v148, v143
	v_fma_f32 v150, -v142, v149, v148
	v_fmac_f32_e32 v149, v150, v143
	v_fma_f32 v142, -v142, v149, v148
	v_div_fmas_f32 v142, v142, v143, v149
	v_div_fixup_f32 v140, v142, v140, v141
	v_add_f32_e32 v131, v131, v140
	v_cmp_gt_f32_e32 vcc, s4, v131
	s_mov_b32 s4, 0x3f317217
	s_nop 0
	v_cndmask_b32_e64 v140, 0, 32, vcc
	v_ldexp_f32 v131, v131, v140
	v_log_f32_e32 v131, v131
	s_nop 0
	v_mul_f32_e32 v140, 0x3f317217, v131
	v_fma_f32 v140, v131, s4, -v140
	v_fmac_f32_e32 v140, 0x3377d1cf, v131
	s_mov_b32 s4, 0x7f800000
	v_fmac_f32_e32 v140, 0x3f317217, v131
	v_cmp_lt_f32_e64 s[12:13], |v131|, s4
	s_nop 1
	v_cndmask_b32_e64 v131, v131, v140, s[12:13]
	v_cndmask_b32_e32 v140, 0, v227, vcc
	v_sub_f32_e32 v131, v131, v140

; DEV u16 f2bf(float f) { return (u16)(pack2(f, 0.f) & 0xffffu); }
; DEV void phase_win(const Params& P, int l, const u16* __restrict__ xb, const u16* __restrict__ Wt, u16* __restrict__ h, char* smem) {
;     ...
;         for (int j = 0; j < 4; ++j) {
;           int row = m0 + wm * 128 + ms * 16 + quad * 4 + j;
;           int col = cb + ns * 16 + l15;
;           float v = acc[ms][ns][j];
;           if (mode == 1) { float lbv = lbp[col - C_HF]; v = __logf(lbv + (1.f - lbv) / (1.f + __expf(-v))); }
;           else if (mode == 2) v = v / (1.f + __expf(-v));
;           h[(size_t)row * HS + col] = f2bf(v);
.LBB0_1671:
	s_andn2_b64 vcc, exec, s[4:5]
	s_cbranch_vccnz .LBB0_1674
	s_cmp_eq_u32 s17, 1
	v_mov_b32_e32 v131, v97
	s_cbranch_scc0 .LBB0_1674
	v_lshl_add_u64 v[140:141], v[0:1], 2, s[14:15]
	v_add_co_u32_e32 v140, vcc, 0xfffff000, v140
	s_nop 1
	v_addc_co_u32_e32 v141, vcc, -1, v141, vcc
	v_mov_b32_e32 v131, v163
	v_mul_f32_e32 v140, 0xbfb8aa3b, v97
	v_exp_f32_e32 v140, v140
	v_sub_f32_e32 v141, 1.0, v131
	v_add_f32_e32 v140, 1.0, v140
	v_div_scale_f32 v142, s[4:5], v140, v140, v141
	v_rcp_f32_e32 v143, v142
	v_div_scale_f32 v144, vcc, v141, v140, v141
	s_mov_b32 s4, 0x800000
	v_fma_f32 v145, -v142, v143, 1.0
	v_fmac_f32_e32 v143, v145, v143
	v_mul_f32_e32 v145, v144, v143
	v_fma_f32 v148, -v142, v145, v144
	v_fmac_f32_e32 v145, v148, v143
	v_fma_f32 v142, -v142, v145, v144
	v_div_fmas_f32 v142, v142, v143, v145
	v_div_fixup_f32 v140, v142, v140, v141
	v_add_f32_e32 v131, v131, v140
	v_cmp_gt_f32_e32 vcc, s4, v131
	s_mov_b32 s4, 0x3f317217
	s_nop 0
	v_cndmask_b32_e64 v140, 0, 32, vcc
	v_ldexp_f32 v131, v131, v140
	v_log_f32_e32 v131, v131
	s_nop 0
	v_mul_f32_e32 v140, 0x3f317217, v131
	v_fma_f32 v140, v131, s4, -v140
	v_fmac_f32_e32 v140, 0x3377d1cf, v131
	s_mov_b32 s4, 0x7f800000
	v_fmac_f32_e32 v140, 0x3f317217, v131
	v_cmp_lt_f32_e64 s[12:13], |v131|, s4
	s_nop 1
	v_cndmask_b32_e64 v131, v131, v140, s[12:13]
	v_cndmask_b32_e32 v140, 0, v227, vcc
	v_sub_f32_e32 v131, v131, v140

; DEV u16 f2bf(float f) { return (u16)(pack2(f, 0.f) & 0xffffu); }
; DEV void phase_win(const Params& P, int l, const u16* __restrict__ xb, const u16* __restrict__ Wt, u16* __restrict__ h, char* smem) {
;     ...
;         for (int j = 0; j < 4; ++j) {
;           int row = m0 + wm * 128 + ms * 16 + quad * 4 + j;
;           int col = cb + ns * 16 + l15;
;           float v = acc[ms][ns][j];
;           if (mode == 1) { float lbv = lbp[col - C_HF]; v = __logf(lbv + (1.f - lbv) / (1.f + __expf(-v))); }
;           else if (mode == 2) v = v / (1.f + __expf(-v));
;           h[(size_t)row * HS + col] = f2bf(v);
.LBB0_1676:
	s_andn2_b64 vcc, exec, s[4:5]
	s_cbranch_vccnz .LBB0_1679
	s_cmp_eq_u32 s17, 1
	v_mov_b32_e32 v140, v18
	s_cbranch_scc0 .LBB0_1679
	v_lshl_add_u64 v[140:141], v[0:1], 2, s[14:15]
	v_add_co_u32_e32 v140, vcc, 0xfffff000, v140
	s_nop 1
	v_addc_co_u32_e32 v141, vcc, -1, v141, vcc
	v_mov_b32_e32 v131, v160
	v_mul_f32_e32 v140, 0xbfb8aa3b, v18
	v_exp_f32_e32 v140, v140
	v_sub_f32_e32 v141, 1.0, v131
	v_add_f32_e32 v140, 1.0, v140
	v_div_scale_f32 v142, s[4:5], v140, v140, v141
	v_rcp_f32_e32 v143, v142
	v_div_scale_f32 v144, vcc, v141, v140, v141
	s_mov_b32 s4, 0x800000
	v_fma_f32 v145, -v142, v143, 1.0
	v_fmac_f32_e32 v143, v145, v143
	v_mul_f32_e32 v145, v144, v143
	v_fma_f32 v146, -v142, v145, v144
	v_fmac_f32_e32 v145, v146, v143
	v_fma_f32 v142, -v142, v145, v144
	v_div_fmas_f32 v142, v142, v143, v145
	v_div_fixup_f32 v140, v142, v140, v141
	v_add_f32_e32 v131, v131, v140
	v_cmp_gt_f32_e32 vcc, s4, v131
	s_mov_b32 s4, 0x3f317217
	s_nop 0
	v_cndmask_b32_e64 v140, 0, 32, vcc
	v_ldexp_f32 v131, v131, v140
	v_log_f32_e32 v131, v131
	s_nop 0
	v_mul_f32_e32 v140, 0x3f317217, v131
	v_fma_f32 v140, v131, s4, -v140
	v_fmac_f32_e32 v140, 0x3377d1cf, v131
	s_mov_b32 s4, 0x7f800000
	v_fmac_f32_e32 v140, 0x3f317217, v131
	v_cmp_lt_f32_e64 s[12:13], |v131|, s4
	s_nop 1
	v_cndmask_b32_e64 v131, v131, v140, s[12:13]
	v_cndmask_b32_e32 v140, 0, v227, vcc
	v_sub_f32_e32 v140, v131, v140

; DEV u16 f2bf(float f) { return (u16)(pack2(f, 0.f) & 0xffffu); }
; DEV void phase_win(const Params& P, int l, const u16* __restrict__ xb, const u16* __restrict__ Wt, u16* __restrict__ h, char* smem) {
;     ...
;         for (int j = 0; j < 4; ++j) {
;           int row = m0 + wm * 128 + ms * 16 + quad * 4 + j;
;           int col = cb + ns * 16 + l15;
;           float v = acc[ms][ns][j];
;           if (mode == 1) { float lbv = lbp[col - C_HF]; v = __logf(lbv + (1.f - lbv) / (1.f + __expf(-v))); }
;           else if (mode == 2) v = v / (1.f + __expf(-v));
;           h[(size_t)row * HS + col] = f2bf(v);
.LBB0_1681:
	s_andn2_b64 vcc, exec, s[4:5]
	s_cbranch_vccnz .LBB0_1684
	s_cmp_eq_u32 s17, 1
	v_mov_b32_e32 v142, v19
	s_cbranch_scc0 .LBB0_1684
	v_lshl_add_u64 v[142:143], v[0:1], 2, s[14:15]
	v_add_co_u32_e32 v142, vcc, 0xfffff000, v142
	s_nop 1
	v_addc_co_u32_e32 v143, vcc, -1, v143, vcc
	v_mov_b32_e32 v142, v160
	v_mul_f32_e32 v143, 0xbfb8aa3b, v19
	v_exp_f32_e32 v143, v143
	v_sub_f32_e32 v144, 1.0, v142
	v_add_f32_e32 v143, 1.0, v143
	v_div_scale_f32 v145, s[4:5], v143, v143, v144
	v_rcp_f32_e32 v146, v145
	v_div_scale_f32 v147, vcc, v144, v143, v144
	s_mov_b32 s4, 0x800000
	v_fma_f32 v148, -v145, v146, 1.0
	v_fmac_f32_e32 v146, v148, v146
	v_mul_f32_e32 v148, v147, v146
	v_fma_f32 v149, -v145, v148, v147
	v_fmac_f32_e32 v148, v149, v146
	v_fma_f32 v145, -v145, v148, v147
	v_div_fmas_f32 v145, v145, v146, v148
	v_div_fixup_f32 v143, v145, v143, v144
	v_add_f32_e32 v142, v142, v143
	v_cmp_gt_f32_e32 vcc, s4, v142
	s_mov_b32 s4, 0x3f317217
	s_nop 0
	v_cndmask_b32_e64 v143, 0, 32, vcc
	v_ldexp_f32 v142, v142, v143
	v_log_f32_e32 v142, v142
	s_nop 0
	v_mul_f32_e32 v143, 0x3f317217, v142
	v_fma_f32 v143, v142, s4, -v143
	v_fmac_f32_e32 v143, 0x3377d1cf, v142
	s_mov_b32 s4, 0x7f800000
	v_fmac_f32_e32 v143, 0x3f317217, v142
	v_cmp_lt_f32_e64 s[12:13], |v142|, s4
	s_nop 1
	v_cndmask_b32_e64 v142, v142, v143, s[12:13]
	v_cndmask_b32_e32 v143, 0, v227, vcc
	v_sub_f32_e32 v142, v142, v143

; DEV u16 f2bf(float f) { return (u16)(pack2(f, 0.f) & 0xffffu); }
; DEV void phase_win(const Params& P, int l, const u16* __restrict__ xb, const u16* __restrict__ Wt, u16* __restrict__ h, char* smem) {
;     ...
;         for (int j = 0; j < 4; ++j) {
;           int row = m0 + wm * 128 + ms * 16 + quad * 4 + j;
;           int col = cb + ns * 16 + l15;
;           float v = acc[ms][ns][j];
;           if (mode == 1) { float lbv = lbp[col - C_HF]; v = __logf(lbv + (1.f - lbv) / (1.f + __expf(-v))); }
;           else if (mode == 2) v = v / (1.f + __expf(-v));
;           h[(size_t)row * HS + col] = f2bf(v);
.LBB0_1686:
	s_andn2_b64 vcc, exec, s[4:5]
	s_cbranch_vccnz .LBB0_1689
	s_cmp_eq_u32 s17, 1
	v_mov_b32_e32 v144, v20
	s_cbranch_scc0 .LBB0_1689
	v_lshl_add_u64 v[144:145], v[0:1], 2, s[14:15]
	v_add_co_u32_e32 v144, vcc, 0xfffff000, v144
	s_nop 1
	v_addc_co_u32_e32 v145, vcc, -1, v145, vcc
	v_mov_b32_e32 v144, v160
	v_mul_f32_e32 v145, 0xbfb8aa3b, v20
	v_exp_f32_e32 v145, v145
	v_sub_f32_e32 v146, 1.0, v144
	v_add_f32_e32 v145, 1.0, v145
	v_div_scale_f32 v147, s[4:5], v145, v145, v146
	v_rcp_f32_e32 v148, v147
	v_div_scale_f32 v149, vcc, v146, v145, v146
	s_mov_b32 s4, 0x800000
	v_fma_f32 v150, -v147, v148, 1.0
	v_fmac_f32_e32 v148, v150, v148
	v_mul_f32_e32 v150, v149, v148
	v_fma_f32 v151, -v147, v150, v149
	v_fmac_f32_e32 v150, v151, v148
	v_fma_f32 v147, -v147, v150, v149
	v_div_fmas_f32 v147, v147, v148, v150
	v_div_fixup_f32 v145, v147, v145, v146
	v_add_f32_e32 v144, v144, v145
	v_cmp_gt_f32_e32 vcc, s4, v144
	s_mov_b32 s4, 0x3f317217
	s_nop 0
	v_cndmask_b32_e64 v145, 0, 32, vcc
	v_ldexp_f32 v144, v144, v145
	v_log_f32_e32 v144, v144
	s_nop 0
	v_mul_f32_e32 v145, 0x3f317217, v144
	v_fma_f32 v145, v144, s4, -v145
	v_fmac_f32_e32 v145, 0x3377d1cf, v144
	s_mov_b32 s4, 0x7f800000
	v_fmac_f32_e32 v145, 0x3f317217, v144
	v_cmp_lt_f32_e64 s[12:13], |v144|, s4
	s_nop 1
	v_cndmask_b32_e64 v144, v144, v145, s[12:13]
	v_cndmask_b32_e32 v145, 0, v227, vcc
	v_sub_f32_e32 v144, v144, v145

; DEV u16 f2bf(float f) { return (u16)(pack2(f, 0.f) & 0xffffu); }
; DEV void phase_win(const Params& P, int l, const u16* __restrict__ xb, const u16* __restrict__ Wt, u16* __restrict__ h, char* smem) {
;     ...
;         for (int j = 0; j < 4; ++j) {
;           int row = m0 + wm * 128 + ms * 16 + quad * 4 + j;
;           int col = cb + ns * 16 + l15;
;           float v = acc[ms][ns][j];
;           if (mode == 1) { float lbv = lbp[col - C_HF]; v = __logf(lbv + (1.f - lbv) / (1.f + __expf(-v))); }
;           else if (mode == 2) v = v / (1.f + __expf(-v));
;           h[(size_t)row * HS + col] = f2bf(v);
.LBB0_1691:
	s_andn2_b64 vcc, exec, s[4:5]
	s_cbranch_vccnz .LBB0_1694
	s_cmp_eq_u32 s17, 1
	v_mov_b32_e32 v146, v21
	s_cbranch_scc0 .LBB0_1694
	v_lshl_add_u64 v[146:147], v[0:1], 2, s[14:15]
	v_add_co_u32_e32 v146, vcc, 0xfffff000, v146
	s_nop 1
	v_addc_co_u32_e32 v147, vcc, -1, v147, vcc
	v_mov_b32_e32 v146, v160
	v_mul_f32_e32 v147, 0xbfb8aa3b, v21
	v_exp_f32_e32 v147, v147
	v_sub_f32_e32 v148, 1.0, v146
	v_add_f32_e32 v147, 1.0, v147
	v_div_scale_f32 v149, s[4:5], v147, v147, v148
	v_rcp_f32_e32 v150, v149
	v_div_scale_f32 v151, vcc, v148, v147, v148
	s_mov_b32 s4, 0x800000
	v_fma_f32 v152, -v149, v150, 1.0
	v_fmac_f32_e32 v150, v152, v150
	v_mul_f32_e32 v152, v151, v150
	v_fma_f32 v153, -v149, v152, v151
	v_fmac_f32_e32 v152, v153, v150
	v_fma_f32 v149, -v149, v152, v151
	v_div_fmas_f32 v149, v149, v150, v152
	v_div_fixup_f32 v147, v149, v147, v148
	v_add_f32_e32 v146, v146, v147
	v_cmp_gt_f32_e32 vcc, s4, v146
	s_mov_b32 s4, 0x3f317217
	s_nop 0
	v_cndmask_b32_e64 v147, 0, 32, vcc
	v_ldexp_f32 v146, v146, v147
	v_log_f32_e32 v146, v146
	s_nop 0
	v_mul_f32_e32 v147, 0x3f317217, v146
	v_fma_f32 v147, v146, s4, -v147
	v_fmac_f32_e32 v147, 0x3377d1cf, v146
	s_mov_b32 s4, 0x7f800000
	v_fmac_f32_e32 v147, 0x3f317217, v146
	v_cmp_lt_f32_e64 s[12:13], |v146|, s4
	s_nop 1
	v_cndmask_b32_e64 v146, v146, v147, s[12:13]
	v_cndmask_b32_e32 v147, 0, v227, vcc
	v_sub_f32_e32 v146, v146, v147

; DEV u16 f2bf(float f) { return (u16)(pack2(f, 0.f) & 0xffffu); }
; DEV void phase_win(const Params& P, int l, const u16* __restrict__ xb, const u16* __restrict__ Wt, u16* __restrict__ h, char* smem) {
;     ...
;         for (int j = 0; j < 4; ++j) {
;           int row = m0 + wm * 128 + ms * 16 + quad * 4 + j;
;           int col = cb + ns * 16 + l15;
;           float v = acc[ms][ns][j];
;           if (mode == 1) { float lbv = lbp[col - C_HF]; v = __logf(lbv + (1.f - lbv) / (1.f + __expf(-v))); }
;           else if (mode == 2) v = v / (1.f + __expf(-v));
;           h[(size_t)row * HS + col] = f2bf(v);
.LBB0_1696:
	s_andn2_b64 vcc, exec, s[4:5]
	s_cbranch_vccnz .LBB0_1699
	s_cmp_eq_u32 s17, 1
	v_mov_b32_e32 v131, v86
	s_cbranch_scc0 .LBB0_1699
	v_lshl_add_u64 v[148:149], v[0:1], 2, s[14:15]
	v_add_co_u32_e32 v148, vcc, 0xfffff000, v148
	s_nop 1
	v_addc_co_u32_e32 v149, vcc, -1, v149, vcc
	v_mov_b32_e32 v131, v161
	v_mul_f32_e32 v148, 0xbfb8aa3b, v86
	v_exp_f32_e32 v148, v148
	v_sub_f32_e32 v149, 1.0, v131
	v_add_f32_e32 v148, 1.0, v148
	v_div_scale_f32 v150, s[4:5], v148, v148, v149
	v_rcp_f32_e32 v151, v150
	v_div_scale_f32 v152, vcc, v149, v148, v149
	s_mov_b32 s4, 0x800000
	v_fma_f32 v153, -v150, v151, 1.0
	v_fmac_f32_e32 v151, v153, v151
	v_mul_f32_e32 v153, v152, v151
	v_fma_f32 v154, -v150, v153, v152
	v_fmac_f32_e32 v153, v154, v151
	v_fma_f32 v150, -v150, v153, v152
	v_div_fmas_f32 v150, v150, v151, v153
	v_div_fixup_f32 v148, v150, v148, v149
	v_add_f32_e32 v131, v131, v148
	v_cmp_gt_f32_e32 vcc, s4, v131
	s_mov_b32 s4, 0x3f317217
	s_nop 0
	v_cndmask_b32_e64 v148, 0, 32, vcc
	v_ldexp_f32 v131, v131, v148
	v_log_f32_e32 v131, v131
	s_nop 0
	v_mul_f32_e32 v148, 0x3f317217, v131
	v_fma_f32 v148, v131, s4, -v148
	v_fmac_f32_e32 v148, 0x3377d1cf, v131
	s_mov_b32 s4, 0x7f800000
	v_fmac_f32_e32 v148, 0x3f317217, v131
	v_cmp_lt_f32_e64 s[12:13], |v131|, s4
	s_nop 1
	v_cndmask_b32_e64 v131, v131, v148, s[12:13]
	v_cndmask_b32_e32 v148, 0, v227, vcc
	v_sub_f32_e32 v131, v131, v148

; DEV u16 f2bf(float f) { return (u16)(pack2(f, 0.f) & 0xffffu); }
; DEV void phase_win(const Params& P, int l, const u16* __restrict__ xb, const u16* __restrict__ Wt, u16* __restrict__ h, char* smem) {
;     ...
;         for (int j = 0; j < 4; ++j) {
;           int row = m0 + wm * 128 + ms * 16 + quad * 4 + j;
;           int col = cb + ns * 16 + l15;
;           float v = acc[ms][ns][j];
;           if (mode == 1) { float lbv = lbp[col - C_HF]; v = __logf(lbv + (1.f - lbv) / (1.f + __expf(-v))); }
;           else if (mode == 2) v = v / (1.f + __expf(-v));
;           h[(size_t)row * HS + col] = f2bf(v);
.LBB0_1701:
	s_andn2_b64 vcc, exec, s[4:5]
	s_cbranch_vccnz .LBB0_1704
	s_cmp_eq_u32 s17, 1
	v_mov_b32_e32 v131, v87
	s_cbranch_scc0 .LBB0_1704
	v_lshl_add_u64 v[148:149], v[0:1], 2, s[14:15]
	v_add_co_u32_e32 v148, vcc, 0xfffff000, v148
	s_nop 1
	v_addc_co_u32_e32 v149, vcc, -1, v149, vcc
	v_mov_b32_e32 v131, v161
	v_mul_f32_e32 v148, 0xbfb8aa3b, v87
	v_exp_f32_e32 v148, v148
	v_sub_f32_e32 v149, 1.0, v131
	v_add_f32_e32 v148, 1.0, v148
	v_div_scale_f32 v150, s[4:5], v148, v148, v149
	v_rcp_f32_e32 v151, v150
	v_div_scale_f32 v152, vcc, v149, v148, v149
	s_mov_b32 s4, 0x800000
	v_fma_f32 v153, -v150, v151, 1.0
	v_fmac_f32_e32 v151, v153, v151
	v_mul_f32_e32 v153, v152, v151
	v_fma_f32 v154, -v150, v153, v152
	v_fmac_f32_e32 v153, v154, v151
	v_fma_f32 v150, -v150, v153, v152
	v_div_fmas_f32 v150, v150, v151, v153
	v_div_fixup_f32 v148, v150, v148, v149
	v_add_f32_e32 v131, v131, v148
	v_cmp_gt_f32_e32 vcc, s4, v131
	s_mov_b32 s4, 0x3f317217
	s_nop 0
	v_cndmask_b32_e64 v148, 0, 32, vcc
	v_ldexp_f32 v131, v131, v148
	v_log_f32_e32 v131, v131
	s_nop 0
	v_mul_f32_e32 v148, 0x3f317217, v131
	v_fma_f32 v148, v131, s4, -v148
	v_fmac_f32_e32 v148, 0x3377d1cf, v131
	s_mov_b32 s4, 0x7f800000
	v_fmac_f32_e32 v148, 0x3f317217, v131
	v_cmp_lt_f32_e64 s[12:13], |v131|, s4
	s_nop 1
	v_cndmask_b32_e64 v131, v131, v148, s[12:13]
	v_cndmask_b32_e32 v148, 0, v227, vcc
	v_sub_f32_e32 v131, v131, v148

; DEV u16 f2bf(float f) { return (u16)(pack2(f, 0.f) & 0xffffu); }
; DEV void phase_win(const Params& P, int l, const u16* __restrict__ xb, const u16* __restrict__ Wt, u16* __restrict__ h, char* smem) {
;     ...
;         for (int j = 0; j < 4; ++j) {
;           int row = m0 + wm * 128 + ms * 16 + quad * 4 + j;
;           int col = cb + ns * 16 + l15;
;           float v = acc[ms][ns][j];
;           if (mode == 1) { float lbv = lbp[col - C_HF]; v = __logf(lbv + (1.f - lbv) / (1.f + __expf(-v))); }
;           else if (mode == 2) v = v / (1.f + __expf(-v));
;           h[(size_t)row * HS + col] = f2bf(v);
.LBB0_1706:
	s_andn2_b64 vcc, exec, s[4:5]
	s_cbranch_vccnz .LBB0_1709
	s_cmp_eq_u32 s17, 1
	v_mov_b32_e32 v131, v88
	s_cbranch_scc0 .LBB0_1709
	v_lshl_add_u64 v[148:149], v[0:1], 2, s[14:15]
	v_add_co_u32_e32 v148, vcc, 0xfffff000, v148
	s_nop 1
	v_addc_co_u32_e32 v149, vcc, -1, v149, vcc
	v_mov_b32_e32 v131, v161
	v_mul_f32_e32 v148, 0xbfb8aa3b, v88
	v_exp_f32_e32 v148, v148
	v_sub_f32_e32 v149, 1.0, v131
	v_add_f32_e32 v148, 1.0, v148
	v_div_scale_f32 v150, s[4:5], v148, v148, v149
	v_rcp_f32_e32 v151, v150
	v_div_scale_f32 v152, vcc, v149, v148, v149
	s_mov_b32 s4, 0x800000
	v_fma_f32 v153, -v150, v151, 1.0
	v_fmac_f32_e32 v151, v153, v151
	v_mul_f32_e32 v153, v152, v151
	v_fma_f32 v154, -v150, v153, v152
	v_fmac_f32_e32 v153, v154, v151
	v_fma_f32 v150, -v150, v153, v152
	v_div_fmas_f32 v150, v150, v151, v153
	v_div_fixup_f32 v148, v150, v148, v149
	v_add_f32_e32 v131, v131, v148
	v_cmp_gt_f32_e32 vcc, s4, v131
	s_mov_b32 s4, 0x3f317217
	s_nop 0
	v_cndmask_b32_e64 v148, 0, 32, vcc
	v_ldexp_f32 v131, v131, v148
	v_log_f32_e32 v131, v131
	s_nop 0
	v_mul_f32_e32 v148, 0x3f317217, v131
	v_fma_f32 v148, v131, s4, -v148
	v_fmac_f32_e32 v148, 0x3377d1cf, v131
	s_mov_b32 s4, 0x7f800000
	v_fmac_f32_e32 v148, 0x3f317217, v131
	v_cmp_lt_f32_e64 s[12:13], |v131|, s4
	s_nop 1
	v_cndmask_b32_e64 v131, v131, v148, s[12:13]
	v_cndmask_b32_e32 v148, 0, v227, vcc
	v_sub_f32_e32 v131, v131, v148

; DEV u16 f2bf(float f) { return (u16)(pack2(f, 0.f) & 0xffffu); }
; DEV void phase_win(const Params& P, int l, const u16* __restrict__ xb, const u16* __restrict__ Wt, u16* __restrict__ h, char* smem) {
;     ...
;         for (int j = 0; j < 4; ++j) {
;           int row = m0 + wm * 128 + ms * 16 + quad * 4 + j;
;           int col = cb + ns * 16 + l15;
;           float v = acc[ms][ns][j];
;           if (mode == 1) { float lbv = lbp[col - C_HF]; v = __logf(lbv + (1.f - lbv) / (1.f + __expf(-v))); }
;           else if (mode == 2) v = v / (1.f + __expf(-v));
;           h[(size_t)row * HS + col] = f2bf(v);
.LBB0_1711:
	s_andn2_b64 vcc, exec, s[4:5]
	s_cbranch_vccnz .LBB0_1714
	s_cmp_eq_u32 s17, 1
	v_mov_b32_e32 v131, v89
	s_cbranch_scc0 .LBB0_1714
	v_lshl_add_u64 v[148:149], v[0:1], 2, s[14:15]
	v_add_co_u32_e32 v148, vcc, 0xfffff000, v148
	s_nop 1
	v_addc_co_u32_e32 v149, vcc, -1, v149, vcc
	v_mov_b32_e32 v131, v161
	v_mul_f32_e32 v148, 0xbfb8aa3b, v89
	v_exp_f32_e32 v148, v148
	v_sub_f32_e32 v149, 1.0, v131
	v_add_f32_e32 v148, 1.0, v148
	v_div_scale_f32 v150, s[4:5], v148, v148, v149
	v_rcp_f32_e32 v151, v150
	v_div_scale_f32 v152, vcc, v149, v148, v149
	s_mov_b32 s4, 0x800000
	v_fma_f32 v153, -v150, v151, 1.0
	v_fmac_f32_e32 v151, v153, v151
	v_mul_f32_e32 v153, v152, v151
	v_fma_f32 v154, -v150, v153, v152
	v_fmac_f32_e32 v153, v154, v151
	v_fma_f32 v150, -v150, v153, v152
	v_div_fmas_f32 v150, v150, v151, v153
	v_div_fixup_f32 v148, v150, v148, v149
	v_add_f32_e32 v131, v131, v148
	v_cmp_gt_f32_e32 vcc, s4, v131
	s_mov_b32 s4, 0x3f317217
	s_nop 0
	v_cndmask_b32_e64 v148, 0, 32, vcc
	v_ldexp_f32 v131, v131, v148
	v_log_f32_e32 v131, v131
	s_nop 0
	v_mul_f32_e32 v148, 0x3f317217, v131
	v_fma_f32 v148, v131, s4, -v148
	v_fmac_f32_e32 v148, 0x3377d1cf, v131
	s_mov_b32 s4, 0x7f800000
	v_fmac_f32_e32 v148, 0x3f317217, v131
	v_cmp_lt_f32_e64 s[12:13], |v131|, s4
	s_nop 1
	v_cndmask_b32_e64 v131, v131, v148, s[12:13]
	v_cndmask_b32_e32 v148, 0, v227, vcc
	v_sub_f32_e32 v131, v131, v148

; DEV u16 f2bf(float f) { return (u16)(pack2(f, 0.f) & 0xffffu); }
; DEV void phase_win(const Params& P, int l, const u16* __restrict__ xb, const u16* __restrict__ Wt, u16* __restrict__ h, char* smem) {
;     ...
;         for (int j = 0; j < 4; ++j) {
;           int row = m0 + wm * 128 + ms * 16 + quad * 4 + j;
;           int col = cb + ns * 16 + l15;
;           float v = acc[ms][ns][j];
;           if (mode == 1) { float lbv = lbp[col - C_HF]; v = __logf(lbv + (1.f - lbv) / (1.f + __expf(-v))); }
;           else if (mode == 2) v = v / (1.f + __expf(-v));
;           h[(size_t)row * HS + col] = f2bf(v);
.LBB0_1716:
	s_andn2_b64 vcc, exec, s[4:5]
	s_cbranch_vccnz .LBB0_1719
	s_cmp_eq_u32 s17, 1
	v_mov_b32_e32 v131, v90
	s_cbranch_scc0 .LBB0_1719
	v_lshl_add_u64 v[148:149], v[0:1], 2, s[14:15]
	v_add_co_u32_e32 v148, vcc, 0xfffff000, v148
	s_nop 1
	v_addc_co_u32_e32 v149, vcc, -1, v149, vcc
	v_mov_b32_e32 v131, v162
	v_mul_f32_e32 v148, 0xbfb8aa3b, v90
	v_exp_f32_e32 v148, v148
	v_sub_f32_e32 v149, 1.0, v131
	v_add_f32_e32 v148, 1.0, v148
	v_div_scale_f32 v150, s[4:5], v148, v148, v149
	v_rcp_f32_e32 v151, v150
	v_div_scale_f32 v152, vcc, v149, v148, v149
	s_mov_b32 s4, 0x800000
	v_fma_f32 v153, -v150, v151, 1.0
	v_fmac_f32_e32 v151, v153, v151
	v_mul_f32_e32 v153, v152, v151
	v_fma_f32 v154, -v150, v153, v152
	v_fmac_f32_e32 v153, v154, v151
	v_fma_f32 v150, -v150, v153, v152
	v_div_fmas_f32 v150, v150, v151, v153
	v_div_fixup_f32 v148, v150, v148, v149
	v_add_f32_e32 v131, v131, v148
	v_cmp_gt_f32_e32 vcc, s4, v131
	s_mov_b32 s4, 0x3f317217
	s_nop 0
	v_cndmask_b32_e64 v148, 0, 32, vcc
	v_ldexp_f32 v131, v131, v148
	v_log_f32_e32 v131, v131
	s_nop 0
	v_mul_f32_e32 v148, 0x3f317217, v131
	v_fma_f32 v148, v131, s4, -v148
	v_fmac_f32_e32 v148, 0x3377d1cf, v131
	s_mov_b32 s4, 0x7f800000
	v_fmac_f32_e32 v148, 0x3f317217, v131
	v_cmp_lt_f32_e64 s[12:13], |v131|, s4
	s_nop 1
	v_cndmask_b32_e64 v131, v131, v148, s[12:13]
	v_cndmask_b32_e32 v148, 0, v227, vcc
	v_sub_f32_e32 v131, v131, v148

; DEV u16 f2bf(float f) { return (u16)(pack2(f, 0.f) & 0xffffu); }
; DEV void phase_win(const Params& P, int l, const u16* __restrict__ xb, const u16* __restrict__ Wt, u16* __restrict__ h, char* smem) {
;     ...
;         for (int j = 0; j < 4; ++j) {
;           int row = m0 + wm * 128 + ms * 16 + quad * 4 + j;
;           int col = cb + ns * 16 + l15;
;           float v = acc[ms][ns][j];
;           if (mode == 1) { float lbv = lbp[col - C_HF]; v = __logf(lbv + (1.f - lbv) / (1.f + __expf(-v))); }
;           else if (mode == 2) v = v / (1.f + __expf(-v));
;           h[(size_t)row * HS + col] = f2bf(v);
.LBB0_1721:
	s_andn2_b64 vcc, exec, s[4:5]
	s_cbranch_vccnz .LBB0_1724
	s_cmp_eq_u32 s17, 1
	v_mov_b32_e32 v131, v91
	s_cbranch_scc0 .LBB0_1724
	v_lshl_add_u64 v[148:149], v[0:1], 2, s[14:15]
	v_add_co_u32_e32 v148, vcc, 0xfffff000, v148
	s_nop 1
	v_addc_co_u32_e32 v149, vcc, -1, v149, vcc
	v_mov_b32_e32 v131, v162
	v_mul_f32_e32 v148, 0xbfb8aa3b, v91
	v_exp_f32_e32 v148, v148
	v_sub_f32_e32 v149, 1.0, v131
	v_add_f32_e32 v148, 1.0, v148
	v_div_scale_f32 v150, s[4:5], v148, v148, v149
	v_rcp_f32_e32 v151, v150
	v_div_scale_f32 v152, vcc, v149, v148, v149
	s_mov_b32 s4, 0x800000
	v_fma_f32 v153, -v150, v151, 1.0
	v_fmac_f32_e32 v151, v153, v151
	v_mul_f32_e32 v153, v152, v151
	v_fma_f32 v154, -v150, v153, v152
	v_fmac_f32_e32 v153, v154, v151
	v_fma_f32 v150, -v150, v153, v152
	v_div_fmas_f32 v150, v150, v151, v153
	v_div_fixup_f32 v148, v150, v148, v149
	v_add_f32_e32 v131, v131, v148
	v_cmp_gt_f32_e32 vcc, s4, v131
	s_mov_b32 s4, 0x3f317217
	s_nop 0
	v_cndmask_b32_e64 v148, 0, 32, vcc
	v_ldexp_f32 v131, v131, v148
	v_log_f32_e32 v131, v131
	s_nop 0
	v_mul_f32_e32 v148, 0x3f317217, v131
	v_fma_f32 v148, v131, s4, -v148
	v_fmac_f32_e32 v148, 0x3377d1cf, v131
	s_mov_b32 s4, 0x7f800000
	v_fmac_f32_e32 v148, 0x3f317217, v131
	v_cmp_lt_f32_e64 s[12:13], |v131|, s4
	s_nop 1
	v_cndmask_b32_e64 v131, v131, v148, s[12:13]
	v_cndmask_b32_e32 v148, 0, v227, vcc
	v_sub_f32_e32 v131, v131, v148

; DEV u16 f2bf(float f) { return (u16)(pack2(f, 0.f) & 0xffffu); }
; DEV void phase_win(const Params& P, int l, const u16* __restrict__ xb, const u16* __restrict__ Wt, u16* __restrict__ h, char* smem) {
;     ...
;         for (int j = 0; j < 4; ++j) {
;           int row = m0 + wm * 128 + ms * 16 + quad * 4 + j;
;           int col = cb + ns * 16 + l15;
;           float v = acc[ms][ns][j];
;           if (mode == 1) { float lbv = lbp[col - C_HF]; v = __logf(lbv + (1.f - lbv) / (1.f + __expf(-v))); }
;           else if (mode == 2) v = v / (1.f + __expf(-v));
;           h[(size_t)row * HS + col] = f2bf(v);
.LBB0_1726:
	s_andn2_b64 vcc, exec, s[4:5]
	s_cbranch_vccnz .LBB0_1729
	s_cmp_eq_u32 s17, 1
	v_mov_b32_e32 v131, v92
	s_cbranch_scc0 .LBB0_1729
	v_lshl_add_u64 v[148:149], v[0:1], 2, s[14:15]
	v_add_co_u32_e32 v148, vcc, 0xfffff000, v148
	s_nop 1
	v_addc_co_u32_e32 v149, vcc, -1, v149, vcc
	v_mov_b32_e32 v131, v162
	v_mul_f32_e32 v148, 0xbfb8aa3b, v92
	v_exp_f32_e32 v148, v148
	v_sub_f32_e32 v149, 1.0, v131
	v_add_f32_e32 v148, 1.0, v148
	v_div_scale_f32 v150, s[4:5], v148, v148, v149
	v_rcp_f32_e32 v151, v150
	v_div_scale_f32 v152, vcc, v149, v148, v149
	s_mov_b32 s4, 0x800000
	v_fma_f32 v153, -v150, v151, 1.0
	v_fmac_f32_e32 v151, v153, v151
	v_mul_f32_e32 v153, v152, v151
	v_fma_f32 v154, -v150, v153, v152
	v_fmac_f32_e32 v153, v154, v151
	v_fma_f32 v150, -v150, v153, v152
	v_div_fmas_f32 v150, v150, v151, v153
	v_div_fixup_f32 v148, v150, v148, v149
	v_add_f32_e32 v131, v131, v148
	v_cmp_gt_f32_e32 vcc, s4, v131
	s_mov_b32 s4, 0x3f317217
	s_nop 0
	v_cndmask_b32_e64 v148, 0, 32, vcc
	v_ldexp_f32 v131, v131, v148
	v_log_f32_e32 v131, v131
	s_nop 0
	v_mul_f32_e32 v148, 0x3f317217, v131
	v_fma_f32 v148, v131, s4, -v148
	v_fmac_f32_e32 v148, 0x3377d1cf, v131
	s_mov_b32 s4, 0x7f800000
	v_fmac_f32_e32 v148, 0x3f317217, v131
	v_cmp_lt_f32_e64 s[12:13], |v131|, s4
	s_nop 1
	v_cndmask_b32_e64 v131, v131, v148, s[12:13]
	v_cndmask_b32_e32 v148, 0, v227, vcc
	v_sub_f32_e32 v131, v131, v148

; DEV u16 f2bf(float f) { return (u16)(pack2(f, 0.f) & 0xffffu); }
; DEV void phase_win(const Params& P, int l, const u16* __restrict__ xb, const u16* __restrict__ Wt, u16* __restrict__ h, char* smem) {
;     ...
;         for (int j = 0; j < 4; ++j) {
;           int row = m0 + wm * 128 + ms * 16 + quad * 4 + j;
;           int col = cb + ns * 16 + l15;
;           float v = acc[ms][ns][j];
;           if (mode == 1) { float lbv = lbp[col - C_HF]; v = __logf(lbv + (1.f - lbv) / (1.f + __expf(-v))); }
;           else if (mode == 2) v = v / (1.f + __expf(-v));
;           h[(size_t)row * HS + col] = f2bf(v);
.LBB0_1731:
	s_andn2_b64 vcc, exec, s[4:5]
	s_cbranch_vccnz .LBB0_1734
	s_cmp_eq_u32 s17, 1
	v_mov_b32_e32 v131, v93
	s_cbranch_scc0 .LBB0_1734
	v_lshl_add_u64 v[148:149], v[0:1], 2, s[14:15]
	v_add_co_u32_e32 v148, vcc, 0xfffff000, v148
	s_nop 1
	v_addc_co_u32_e32 v149, vcc, -1, v149, vcc
	v_mov_b32_e32 v131, v162
	v_mul_f32_e32 v148, 0xbfb8aa3b, v93
	v_exp_f32_e32 v148, v148
	v_sub_f32_e32 v149, 1.0, v131
	v_add_f32_e32 v148, 1.0, v148
	v_div_scale_f32 v150, s[4:5], v148, v148, v149
	v_rcp_f32_e32 v151, v150
	v_div_scale_f32 v152, vcc, v149, v148, v149
	s_mov_b32 s4, 0x800000
	v_fma_f32 v153, -v150, v151, 1.0
	v_fmac_f32_e32 v151, v153, v151
	v_mul_f32_e32 v153, v152, v151
	v_fma_f32 v154, -v150, v153, v152
	v_fmac_f32_e32 v153, v154, v151
	v_fma_f32 v150, -v150, v153, v152
	v_div_fmas_f32 v150, v150, v151, v153
	v_div_fixup_f32 v148, v150, v148, v149
	v_add_f32_e32 v131, v131, v148
	v_cmp_gt_f32_e32 vcc, s4, v131
	s_mov_b32 s4, 0x3f317217
	s_nop 0
	v_cndmask_b32_e64 v148, 0, 32, vcc
	v_ldexp_f32 v131, v131, v148
	v_log_f32_e32 v131, v131
	s_nop 0
	v_mul_f32_e32 v148, 0x3f317217, v131
	v_fma_f32 v148, v131, s4, -v148
	v_fmac_f32_e32 v148, 0x3377d1cf, v131
	s_mov_b32 s4, 0x7f800000
	v_fmac_f32_e32 v148, 0x3f317217, v131
	v_cmp_lt_f32_e64 s[12:13], |v131|, s4
	s_nop 1
	v_cndmask_b32_e64 v131, v131, v148, s[12:13]
	v_cndmask_b32_e32 v148, 0, v227, vcc
	v_sub_f32_e32 v131, v131, v148

; DEV u16 f2bf(float f) { return (u16)(pack2(f, 0.f) & 0xffffu); }
; DEV void phase_win(const Params& P, int l, const u16* __restrict__ xb, const u16* __restrict__ Wt, u16* __restrict__ h, char* smem) {
;     ...
;         for (int j = 0; j < 4; ++j) {
;           int row = m0 + wm * 128 + ms * 16 + quad * 4 + j;
;           int col = cb + ns * 16 + l15;
;           float v = acc[ms][ns][j];
;           if (mode == 1) { float lbv = lbp[col - C_HF]; v = __logf(lbv + (1.f - lbv) / (1.f + __expf(-v))); }
;           else if (mode == 2) v = v / (1.f + __expf(-v));
;           h[(size_t)row * HS + col] = f2bf(v);
.LBB0_1736:
	s_andn2_b64 vcc, exec, s[4:5]
	s_cbranch_vccnz .LBB0_1739
	s_cmp_eq_u32 s17, 1
	v_mov_b32_e32 v131, v82
	s_cbranch_scc0 .LBB0_1739
	v_lshl_add_u64 v[148:149], v[0:1], 2, s[14:15]
	v_add_co_u32_e32 v148, vcc, 0xfffff000, v148
	s_nop 1
	v_addc_co_u32_e32 v149, vcc, -1, v149, vcc
	v_mov_b32_e32 v131, v163
	v_mul_f32_e32 v148, 0xbfb8aa3b, v82
	v_exp_f32_e32 v148, v148
	v_sub_f32_e32 v149, 1.0, v131
	v_add_f32_e32 v148, 1.0, v148
	v_div_scale_f32 v150, s[4:5], v148, v148, v149
	v_rcp_f32_e32 v151, v150
	v_div_scale_f32 v152, vcc, v149, v148, v149
	s_mov_b32 s4, 0x800000
	v_fma_f32 v153, -v150, v151, 1.0
	v_fmac_f32_e32 v151, v153, v151
	v_mul_f32_e32 v153, v152, v151
	v_fma_f32 v154, -v150, v153, v152
	v_fmac_f32_e32 v153, v154, v151
	v_fma_f32 v150, -v150, v153, v152
	v_div_fmas_f32 v150, v150, v151, v153
	v_div_fixup_f32 v148, v150, v148, v149
	v_add_f32_e32 v131, v131, v148
	v_cmp_gt_f32_e32 vcc, s4, v131
	s_mov_b32 s4, 0x3f317217
	s_nop 0
	v_cndmask_b32_e64 v148, 0, 32, vcc
	v_ldexp_f32 v131, v131, v148
	v_log_f32_e32 v131, v131
	s_nop 0
	v_mul_f32_e32 v148, 0x3f317217, v131
	v_fma_f32 v148, v131, s4, -v148
	v_fmac_f32_e32 v148, 0x3377d1cf, v131
	s_mov_b32 s4, 0x7f800000
	v_fmac_f32_e32 v148, 0x3f317217, v131
	v_cmp_lt_f32_e64 s[12:13], |v131|, s4
	s_nop 1
	v_cndmask_b32_e64 v131, v131, v148, s[12:13]
	v_cndmask_b32_e32 v148, 0, v227, vcc
	v_sub_f32_e32 v131, v131, v148

; DEV u16 f2bf(float f) { return (u16)(pack2(f, 0.f) & 0xffffu); }
; DEV void phase_win(const Params& P, int l, const u16* __restrict__ xb, const u16* __restrict__ Wt, u16* __restrict__ h, char* smem) {
;     ...
;         for (int j = 0; j < 4; ++j) {
;           int row = m0 + wm * 128 + ms * 16 + quad * 4 + j;
;           int col = cb + ns * 16 + l15;
;           float v = acc[ms][ns][j];
;           if (mode == 1) { float lbv = lbp[col - C_HF]; v = __logf(lbv + (1.f - lbv) / (1.f + __expf(-v))); }
;           else if (mode == 2) v = v / (1.f + __expf(-v));
;           h[(size_t)row * HS + col] = f2bf(v);
.LBB0_1741:
	s_andn2_b64 vcc, exec, s[4:5]
	s_cbranch_vccnz .LBB0_1744
	s_cmp_eq_u32 s17, 1
	v_mov_b32_e32 v131, v83
	s_cbranch_scc0 .LBB0_1744
	v_lshl_add_u64 v[140:141], v[0:1], 2, s[14:15]
	v_add_co_u32_e32 v140, vcc, 0xfffff000, v140
	s_nop 1
	v_addc_co_u32_e32 v141, vcc, -1, v141, vcc
	v_mov_b32_e32 v131, v163
	v_mul_f32_e32 v140, 0xbfb8aa3b, v83
	v_exp_f32_e32 v140, v140
	v_sub_f32_e32 v141, 1.0, v131
	v_add_f32_e32 v140, 1.0, v140
	v_div_scale_f32 v148, s[4:5], v140, v140, v141
	v_rcp_f32_e32 v149, v148
	v_div_scale_f32 v150, vcc, v141, v140, v141
	s_mov_b32 s4, 0x800000
	v_fma_f32 v151, -v148, v149, 1.0
	v_fmac_f32_e32 v149, v151, v149
	v_mul_f32_e32 v151, v150, v149
	v_fma_f32 v152, -v148, v151, v150
	v_fmac_f32_e32 v151, v152, v149
	v_fma_f32 v148, -v148, v151, v150
	v_div_fmas_f32 v148, v148, v149, v151
	v_div_fixup_f32 v140, v148, v140, v141
	v_add_f32_e32 v131, v131, v140
	v_cmp_gt_f32_e32 vcc, s4, v131
	s_mov_b32 s4, 0x3f317217
	s_nop 0
	v_cndmask_b32_e64 v140, 0, 32, vcc
	v_ldexp_f32 v131, v131, v140
	v_log_f32_e32 v131, v131
	s_nop 0
	v_mul_f32_e32 v140, 0x3f317217, v131
	v_fma_f32 v140, v131, s4, -v140
	v_fmac_f32_e32 v140, 0x3377d1cf, v131
	s_mov_b32 s4, 0x7f800000
	v_fmac_f32_e32 v140, 0x3f317217, v131
	v_cmp_lt_f32_e64 s[12:13], |v131|, s4
	s_nop 1
	v_cndmask_b32_e64 v131, v131, v140, s[12:13]
	v_cndmask_b32_e32 v140, 0, v227, vcc
	v_sub_f32_e32 v131, v131, v140

; DEV u16 f2bf(float f) { return (u16)(pack2(f, 0.f) & 0xffffu); }
; DEV void phase_win(const Params& P, int l, const u16* __restrict__ xb, const u16* __restrict__ Wt, u16* __restrict__ h, char* smem) {
;     ...
;         for (int j = 0; j < 4; ++j) {
;           int row = m0 + wm * 128 + ms * 16 + quad * 4 + j;
;           int col = cb + ns * 16 + l15;
;           float v = acc[ms][ns][j];
;           if (mode == 1) { float lbv = lbp[col - C_HF]; v = __logf(lbv + (1.f - lbv) / (1.f + __expf(-v))); }
;           else if (mode == 2) v = v / (1.f + __expf(-v));
;           h[(size_t)row * HS + col] = f2bf(v);
.LBB0_1746:
	s_andn2_b64 vcc, exec, s[4:5]
	s_cbranch_vccnz .LBB0_1749
	s_cmp_eq_u32 s17, 1
	v_mov_b32_e32 v131, v84
	s_cbranch_scc0 .LBB0_1749
	v_lshl_add_u64 v[140:141], v[0:1], 2, s[14:15]
	v_add_co_u32_e32 v140, vcc, 0xfffff000, v140
	s_nop 1
	v_addc_co_u32_e32 v141, vcc, -1, v141, vcc
	v_mov_b32_e32 v131, v163
	v_mul_f32_e32 v140, 0xbfb8aa3b, v84
	v_exp_f32_e32 v140, v140
	v_sub_f32_e32 v141, 1.0, v131
	v_add_f32_e32 v140, 1.0, v140
	v_div_scale_f32 v142, s[4:5], v140, v140, v141
	v_rcp_f32_e32 v143, v142
	v_div_scale_f32 v148, vcc, v141, v140, v141
	s_mov_b32 s4, 0x800000
	v_fma_f32 v149, -v142, v143, 1.0
	v_fmac_f32_e32 v143, v149, v143
	v_mul_f32_e32 v149, v148, v143
	v_fma_f32 v150, -v142, v149, v148
	v_fmac_f32_e32 v149, v150, v143
	v_fma_f32 v142, -v142, v149, v148
	v_div_fmas_f32 v142, v142, v143, v149
	v_div_fixup_f32 v140, v142, v140, v141
	v_add_f32_e32 v131, v131, v140
	v_cmp_gt_f32_e32 vcc, s4, v131
	s_mov_b32 s4, 0x3f317217
	s_nop 0
	v_cndmask_b32_e64 v140, 0, 32, vcc
	v_ldexp_f32 v131, v131, v140
	v_log_f32_e32 v131, v131
	s_nop 0
	v_mul_f32_e32 v140, 0x3f317217, v131
	v_fma_f32 v140, v131, s4, -v140
	v_fmac_f32_e32 v140, 0x3377d1cf, v131
	s_mov_b32 s4, 0x7f800000
	v_fmac_f32_e32 v140, 0x3f317217, v131
	v_cmp_lt_f32_e64 s[12:13], |v131|, s4
	s_nop 1
	v_cndmask_b32_e64 v131, v131, v140, s[12:13]
	v_cndmask_b32_e32 v140, 0, v227, vcc
	v_sub_f32_e32 v131, v131, v140

; DEV u16 f2bf(float f) { return (u16)(pack2(f, 0.f) & 0xffffu); }
; DEV void phase_win(const Params& P, int l, const u16* __restrict__ xb, const u16* __restrict__ Wt, u16* __restrict__ h, char* smem) {
;     ...
;         for (int j = 0; j < 4; ++j) {
;           int row = m0 + wm * 128 + ms * 16 + quad * 4 + j;
;           int col = cb + ns * 16 + l15;
;           float v = acc[ms][ns][j];
;           if (mode == 1) { float lbv = lbp[col - C_HF]; v = __logf(lbv + (1.f - lbv) / (1.f + __expf(-v))); }
;           else if (mode == 2) v = v / (1.f + __expf(-v));
;           h[(size_t)row * HS + col] = f2bf(v);
.LBB0_1751:
	s_andn2_b64 vcc, exec, s[4:5]
	s_cbranch_vccnz .LBB0_1754
	s_cmp_eq_u32 s17, 1
	v_mov_b32_e32 v131, v85
	s_cbranch_scc0 .LBB0_1754
	v_lshl_add_u64 v[140:141], v[0:1], 2, s[14:15]
	v_add_co_u32_e32 v140, vcc, 0xfffff000, v140
	s_nop 1
	v_addc_co_u32_e32 v141, vcc, -1, v141, vcc
	v_mov_b32_e32 v131, v163
	v_mul_f32_e32 v140, 0xbfb8aa3b, v85
	v_exp_f32_e32 v140, v140
	v_sub_f32_e32 v141, 1.0, v131
	v_add_f32_e32 v140, 1.0, v140
	v_div_scale_f32 v142, s[4:5], v140, v140, v141
	v_rcp_f32_e32 v143, v142
	v_div_scale_f32 v144, vcc, v141, v140, v141
	s_mov_b32 s4, 0x800000
	v_fma_f32 v145, -v142, v143, 1.0
	v_fmac_f32_e32 v143, v145, v143
	v_mul_f32_e32 v145, v144, v143
	v_fma_f32 v148, -v142, v145, v144
	v_fmac_f32_e32 v145, v148, v143
	v_fma_f32 v142, -v142, v145, v144
	v_div_fmas_f32 v142, v142, v143, v145
	v_div_fixup_f32 v140, v142, v140, v141
	v_add_f32_e32 v131, v131, v140
	v_cmp_gt_f32_e32 vcc, s4, v131
	s_mov_b32 s4, 0x3f317217
	s_nop 0
	v_cndmask_b32_e64 v140, 0, 32, vcc
	v_ldexp_f32 v131, v131, v140
	v_log_f32_e32 v131, v131
	s_nop 0
	v_mul_f32_e32 v140, 0x3f317217, v131
	v_fma_f32 v140, v131, s4, -v140
	v_fmac_f32_e32 v140, 0x3377d1cf, v131
	s_mov_b32 s4, 0x7f800000
	v_fmac_f32_e32 v140, 0x3f317217, v131
	v_cmp_lt_f32_e64 s[12:13], |v131|, s4
	s_nop 1
	v_cndmask_b32_e64 v131, v131, v140, s[12:13]
	v_cndmask_b32_e32 v140, 0, v227, vcc
	v_sub_f32_e32 v131, v131, v140

; DEV u16 f2bf(float f) { return (u16)(pack2(f, 0.f) & 0xffffu); }
; DEV void phase_win(const Params& P, int l, const u16* __restrict__ xb, const u16* __restrict__ Wt, u16* __restrict__ h, char* smem) {
;     ...
;         for (int j = 0; j < 4; ++j) {
;           int row = m0 + wm * 128 + ms * 16 + quad * 4 + j;
;           int col = cb + ns * 16 + l15;
;           float v = acc[ms][ns][j];
;           if (mode == 1) { float lbv = lbp[col - C_HF]; v = __logf(lbv + (1.f - lbv) / (1.f + __expf(-v))); }
;           else if (mode == 2) v = v / (1.f + __expf(-v));
;           h[(size_t)row * HS + col] = f2bf(v);
.LBB0_1756:
	s_andn2_b64 vcc, exec, s[4:5]
	s_cbranch_vccnz .LBB0_1759
	s_cmp_eq_u32 s17, 1
	v_mov_b32_e32 v140, v14
	s_cbranch_scc0 .LBB0_1759
	v_lshl_add_u64 v[140:141], v[0:1], 2, s[14:15]
	v_add_co_u32_e32 v140, vcc, 0xfffff000, v140
	s_nop 1
	v_addc_co_u32_e32 v141, vcc, -1, v141, vcc
	v_mov_b32_e32 v131, v160
	v_mul_f32_e32 v140, 0xbfb8aa3b, v14
	v_exp_f32_e32 v140, v140
	v_sub_f32_e32 v141, 1.0, v131
	v_add_f32_e32 v140, 1.0, v140
	v_div_scale_f32 v142, s[4:5], v140, v140, v141
	v_rcp_f32_e32 v143, v142
	v_div_scale_f32 v144, vcc, v141, v140, v141
	s_mov_b32 s4, 0x800000
	v_fma_f32 v145, -v142, v143, 1.0
	v_fmac_f32_e32 v143, v145, v143
	v_mul_f32_e32 v145, v144, v143
	v_fma_f32 v146, -v142, v145, v144
	v_fmac_f32_e32 v145, v146, v143
	v_fma_f32 v142, -v142, v145, v144
	v_div_fmas_f32 v142, v142, v143, v145
	v_div_fixup_f32 v140, v142, v140, v141
	v_add_f32_e32 v131, v131, v140
	v_cmp_gt_f32_e32 vcc, s4, v131
	s_mov_b32 s4, 0x3f317217
	s_nop 0
	v_cndmask_b32_e64 v140, 0, 32, vcc
	v_ldexp_f32 v131, v131, v140
	v_log_f32_e32 v131, v131
	s_nop 0
	v_mul_f32_e32 v140, 0x3f317217, v131
	v_fma_f32 v140, v131, s4, -v140
	v_fmac_f32_e32 v140, 0x3377d1cf, v131
	s_mov_b32 s4, 0x7f800000
	v_fmac_f32_e32 v140, 0x3f317217, v131
	v_cmp_lt_f32_e64 s[12:13], |v131|, s4
	s_nop 1
	v_cndmask_b32_e64 v131, v131, v140, s[12:13]
	v_cndmask_b32_e32 v140, 0, v227, vcc
	v_sub_f32_e32 v140, v131, v140

; DEV u16 f2bf(float f) { return (u16)(pack2(f, 0.f) & 0xffffu); }
; DEV void phase_win(const Params& P, int l, const u16* __restrict__ xb, const u16* __restrict__ Wt, u16* __restrict__ h, char* smem) {
;     ...
;         for (int j = 0; j < 4; ++j) {
;           int row = m0 + wm * 128 + ms * 16 + quad * 4 + j;
;           int col = cb + ns * 16 + l15;
;           float v = acc[ms][ns][j];
;           if (mode == 1) { float lbv = lbp[col - C_HF]; v = __logf(lbv + (1.f - lbv) / (1.f + __expf(-v))); }
;           else if (mode == 2) v = v / (1.f + __expf(-v));
;           h[(size_t)row * HS + col] = f2bf(v);
.LBB0_1761:
	s_andn2_b64 vcc, exec, s[4:5]
	s_cbranch_vccnz .LBB0_1764
	s_cmp_eq_u32 s17, 1
	v_mov_b32_e32 v142, v15
	s_cbranch_scc0 .LBB0_1764
	v_lshl_add_u64 v[142:143], v[0:1], 2, s[14:15]
	v_add_co_u32_e32 v142, vcc, 0xfffff000, v142
	s_nop 1
	v_addc_co_u32_e32 v143, vcc, -1, v143, vcc
	v_mov_b32_e32 v142, v160
	v_mul_f32_e32 v143, 0xbfb8aa3b, v15
	v_exp_f32_e32 v143, v143
	v_sub_f32_e32 v144, 1.0, v142
	v_add_f32_e32 v143, 1.0, v143
	v_div_scale_f32 v145, s[4:5], v143, v143, v144
	v_rcp_f32_e32 v146, v145
	v_div_scale_f32 v147, vcc, v144, v143, v144
	s_mov_b32 s4, 0x800000
	v_fma_f32 v148, -v145, v146, 1.0
	v_fmac_f32_e32 v146, v148, v146
	v_mul_f32_e32 v148, v147, v146
	v_fma_f32 v149, -v145, v148, v147
	v_fmac_f32_e32 v148, v149, v146
	v_fma_f32 v145, -v145, v148, v147
	v_div_fmas_f32 v145, v145, v146, v148
	v_div_fixup_f32 v143, v145, v143, v144
	v_add_f32_e32 v142, v142, v143
	v_cmp_gt_f32_e32 vcc, s4, v142
	s_mov_b32 s4, 0x3f317217
	s_nop 0
	v_cndmask_b32_e64 v143, 0, 32, vcc
	v_ldexp_f32 v142, v142, v143
	v_log_f32_e32 v142, v142
	s_nop 0
	v_mul_f32_e32 v143, 0x3f317217, v142
	v_fma_f32 v143, v142, s4, -v143
	v_fmac_f32_e32 v143, 0x3377d1cf, v142
	s_mov_b32 s4, 0x7f800000
	v_fmac_f32_e32 v143, 0x3f317217, v142
	v_cmp_lt_f32_e64 s[12:13], |v142|, s4
	s_nop 1
	v_cndmask_b32_e64 v142, v142, v143, s[12:13]
	v_cndmask_b32_e32 v143, 0, v227, vcc
	v_sub_f32_e32 v142, v142, v143

; DEV u16 f2bf(float f) { return (u16)(pack2(f, 0.f) & 0xffffu); }
; DEV void phase_win(const Params& P, int l, const u16* __restrict__ xb, const u16* __restrict__ Wt, u16* __restrict__ h, char* smem) {
;     ...
;         for (int j = 0; j < 4; ++j) {
;           int row = m0 + wm * 128 + ms * 16 + quad * 4 + j;
;           int col = cb + ns * 16 + l15;
;           float v = acc[ms][ns][j];
;           if (mode == 1) { float lbv = lbp[col - C_HF]; v = __logf(lbv + (1.f - lbv) / (1.f + __expf(-v))); }
;           else if (mode == 2) v = v / (1.f + __expf(-v));
;           h[(size_t)row * HS + col] = f2bf(v);
.LBB0_1766:
	s_andn2_b64 vcc, exec, s[4:5]
	s_cbranch_vccnz .LBB0_1769
	s_cmp_eq_u32 s17, 1
	v_mov_b32_e32 v144, v16
	s_cbranch_scc0 .LBB0_1769
	v_lshl_add_u64 v[144:145], v[0:1], 2, s[14:15]
	v_add_co_u32_e32 v144, vcc, 0xfffff000, v144
	s_nop 1
	v_addc_co_u32_e32 v145, vcc, -1, v145, vcc
	v_mov_b32_e32 v144, v160
	v_mul_f32_e32 v145, 0xbfb8aa3b, v16
	v_exp_f32_e32 v145, v145
	v_sub_f32_e32 v146, 1.0, v144
	v_add_f32_e32 v145, 1.0, v145
	v_div_scale_f32 v147, s[4:5], v145, v145, v146
	v_rcp_f32_e32 v148, v147
	v_div_scale_f32 v149, vcc, v146, v145, v146
	s_mov_b32 s4, 0x800000
	v_fma_f32 v150, -v147, v148, 1.0
	v_fmac_f32_e32 v148, v150, v148
	v_mul_f32_e32 v150, v149, v148
	v_fma_f32 v151, -v147, v150, v149
	v_fmac_f32_e32 v150, v151, v148
	v_fma_f32 v147, -v147, v150, v149
	v_div_fmas_f32 v147, v147, v148, v150
	v_div_fixup_f32 v145, v147, v145, v146
	v_add_f32_e32 v144, v144, v145
	v_cmp_gt_f32_e32 vcc, s4, v144
	s_mov_b32 s4, 0x3f317217
	s_nop 0
	v_cndmask_b32_e64 v145, 0, 32, vcc
	v_ldexp_f32 v144, v144, v145
	v_log_f32_e32 v144, v144
	s_nop 0
	v_mul_f32_e32 v145, 0x3f317217, v144
	v_fma_f32 v145, v144, s4, -v145
	v_fmac_f32_e32 v145, 0x3377d1cf, v144
	s_mov_b32 s4, 0x7f800000
	v_fmac_f32_e32 v145, 0x3f317217, v144
	v_cmp_lt_f32_e64 s[12:13], |v144|, s4
	s_nop 1
	v_cndmask_b32_e64 v144, v144, v145, s[12:13]
	v_cndmask_b32_e32 v145, 0, v227, vcc
	v_sub_f32_e32 v144, v144, v145

; DEV u16 f2bf(float f) { return (u16)(pack2(f, 0.f) & 0xffffu); }
; DEV void phase_win(const Params& P, int l, const u16* __restrict__ xb, const u16* __restrict__ Wt, u16* __restrict__ h, char* smem) {
;     ...
;         for (int j = 0; j < 4; ++j) {
;           int row = m0 + wm * 128 + ms * 16 + quad * 4 + j;
;           int col = cb + ns * 16 + l15;
;           float v = acc[ms][ns][j];
;           if (mode == 1) { float lbv = lbp[col - C_HF]; v = __logf(lbv + (1.f - lbv) / (1.f + __expf(-v))); }
;           else if (mode == 2) v = v / (1.f + __expf(-v));
;           h[(size_t)row * HS + col] = f2bf(v);
.LBB0_1771:
	s_andn2_b64 vcc, exec, s[4:5]
	s_cbranch_vccnz .LBB0_1774
	s_cmp_eq_u32 s17, 1
	v_mov_b32_e32 v146, v17
	s_cbranch_scc0 .LBB0_1774
	v_lshl_add_u64 v[146:147], v[0:1], 2, s[14:15]
	v_add_co_u32_e32 v146, vcc, 0xfffff000, v146
	s_nop 1
	v_addc_co_u32_e32 v147, vcc, -1, v147, vcc
	v_mov_b32_e32 v146, v160
	v_mul_f32_e32 v147, 0xbfb8aa3b, v17
	v_exp_f32_e32 v147, v147
	v_sub_f32_e32 v148, 1.0, v146
	v_add_f32_e32 v147, 1.0, v147
	v_div_scale_f32 v149, s[4:5], v147, v147, v148
	v_rcp_f32_e32 v150, v149
	v_div_scale_f32 v151, vcc, v148, v147, v148
	s_mov_b32 s4, 0x800000
	v_fma_f32 v152, -v149, v150, 1.0
	v_fmac_f32_e32 v150, v152, v150
	v_mul_f32_e32 v152, v151, v150
	v_fma_f32 v153, -v149, v152, v151
	v_fmac_f32_e32 v152, v153, v150
	v_fma_f32 v149, -v149, v152, v151
	v_div_fmas_f32 v149, v149, v150, v152
	v_div_fixup_f32 v147, v149, v147, v148
	v_add_f32_e32 v146, v146, v147
	v_cmp_gt_f32_e32 vcc, s4, v146
	s_mov_b32 s4, 0x3f317217
	s_nop 0
	v_cndmask_b32_e64 v147, 0, 32, vcc
	v_ldexp_f32 v146, v146, v147
	v_log_f32_e32 v146, v146
	s_nop 0
	v_mul_f32_e32 v147, 0x3f317217, v146
	v_fma_f32 v147, v146, s4, -v147
	v_fmac_f32_e32 v147, 0x3377d1cf, v146
	s_mov_b32 s4, 0x7f800000
	v_fmac_f32_e32 v147, 0x3f317217, v146
	v_cmp_lt_f32_e64 s[12:13], |v146|, s4
	s_nop 1
	v_cndmask_b32_e64 v146, v146, v147, s[12:13]
	v_cndmask_b32_e32 v147, 0, v227, vcc
	v_sub_f32_e32 v146, v146, v147

; DEV u16 f2bf(float f) { return (u16)(pack2(f, 0.f) & 0xffffu); }
; DEV void phase_win(const Params& P, int l, const u16* __restrict__ xb, const u16* __restrict__ Wt, u16* __restrict__ h, char* smem) {
;     ...
;         for (int j = 0; j < 4; ++j) {
;           int row = m0 + wm * 128 + ms * 16 + quad * 4 + j;
;           int col = cb + ns * 16 + l15;
;           float v = acc[ms][ns][j];
;           if (mode == 1) { float lbv = lbp[col - C_HF]; v = __logf(lbv + (1.f - lbv) / (1.f + __expf(-v))); }
;           else if (mode == 2) v = v / (1.f + __expf(-v));
;           h[(size_t)row * HS + col] = f2bf(v);
.LBB0_1776:
	s_andn2_b64 vcc, exec, s[4:5]
	s_cbranch_vccnz .LBB0_1779
	s_cmp_eq_u32 s17, 1
	v_mov_b32_e32 v131, v74
	s_cbranch_scc0 .LBB0_1779
	v_lshl_add_u64 v[148:149], v[0:1], 2, s[14:15]
	v_add_co_u32_e32 v148, vcc, 0xfffff000, v148
	s_nop 1
	v_addc_co_u32_e32 v149, vcc, -1, v149, vcc
	v_mov_b32_e32 v131, v161
	v_mul_f32_e32 v148, 0xbfb8aa3b, v74
	v_exp_f32_e32 v148, v148
	v_sub_f32_e32 v149, 1.0, v131
	v_add_f32_e32 v148, 1.0, v148
	v_div_scale_f32 v150, s[4:5], v148, v148, v149
	v_rcp_f32_e32 v151, v150
	v_div_scale_f32 v152, vcc, v149, v148, v149
	s_mov_b32 s4, 0x800000
	v_fma_f32 v153, -v150, v151, 1.0
	v_fmac_f32_e32 v151, v153, v151
	v_mul_f32_e32 v153, v152, v151
	v_fma_f32 v154, -v150, v153, v152
	v_fmac_f32_e32 v153, v154, v151
	v_fma_f32 v150, -v150, v153, v152
	v_div_fmas_f32 v150, v150, v151, v153
	v_div_fixup_f32 v148, v150, v148, v149
	v_add_f32_e32 v131, v131, v148
	v_cmp_gt_f32_e32 vcc, s4, v131
	s_mov_b32 s4, 0x3f317217
	s_nop 0
	v_cndmask_b32_e64 v148, 0, 32, vcc
	v_ldexp_f32 v131, v131, v148
	v_log_f32_e32 v131, v131
	s_nop 0
	v_mul_f32_e32 v148, 0x3f317217, v131
	v_fma_f32 v148, v131, s4, -v148
	v_fmac_f32_e32 v148, 0x3377d1cf, v131
	s_mov_b32 s4, 0x7f800000
	v_fmac_f32_e32 v148, 0x3f317217, v131
	v_cmp_lt_f32_e64 s[12:13], |v131|, s4
	s_nop 1
	v_cndmask_b32_e64 v131, v131, v148, s[12:13]
	v_cndmask_b32_e32 v148, 0, v227, vcc
	v_sub_f32_e32 v131, v131, v148

; DEV u16 f2bf(float f) { return (u16)(pack2(f, 0.f) & 0xffffu); }
; DEV void phase_win(const Params& P, int l, const u16* __restrict__ xb, const u16* __restrict__ Wt, u16* __restrict__ h, char* smem) {
;     ...
;         for (int j = 0; j < 4; ++j) {
;           int row = m0 + wm * 128 + ms * 16 + quad * 4 + j;
;           int col = cb + ns * 16 + l15;
;           float v = acc[ms][ns][j];
;           if (mode == 1) { float lbv = lbp[col - C_HF]; v = __logf(lbv + (1.f - lbv) / (1.f + __expf(-v))); }
;           else if (mode == 2) v = v / (1.f + __expf(-v));
;           h[(size_t)row * HS + col] = f2bf(v);
.LBB0_1781:
	s_andn2_b64 vcc, exec, s[4:5]
	s_cbranch_vccnz .LBB0_1784
	s_cmp_eq_u32 s17, 1
	v_mov_b32_e32 v131, v75
	s_cbranch_scc0 .LBB0_1784
	v_lshl_add_u64 v[148:149], v[0:1], 2, s[14:15]
	v_add_co_u32_e32 v148, vcc, 0xfffff000, v148
	s_nop 1
	v_addc_co_u32_e32 v149, vcc, -1, v149, vcc
	v_mov_b32_e32 v131, v161
	v_mul_f32_e32 v148, 0xbfb8aa3b, v75
	v_exp_f32_e32 v148, v148
	v_sub_f32_e32 v149, 1.0, v131
	v_add_f32_e32 v148, 1.0, v148
	v_div_scale_f32 v150, s[4:5], v148, v148, v149
	v_rcp_f32_e32 v151, v150
	v_div_scale_f32 v152, vcc, v149, v148, v149
	s_mov_b32 s4, 0x800000
	v_fma_f32 v153, -v150, v151, 1.0
	v_fmac_f32_e32 v151, v153, v151
	v_mul_f32_e32 v153, v152, v151
	v_fma_f32 v154, -v150, v153, v152
	v_fmac_f32_e32 v153, v154, v151
	v_fma_f32 v150, -v150, v153, v152
	v_div_fmas_f32 v150, v150, v151, v153
	v_div_fixup_f32 v148, v150, v148, v149
	v_add_f32_e32 v131, v131, v148
	v_cmp_gt_f32_e32 vcc, s4, v131
	s_mov_b32 s4, 0x3f317217
	s_nop 0
	v_cndmask_b32_e64 v148, 0, 32, vcc
	v_ldexp_f32 v131, v131, v148
	v_log_f32_e32 v131, v131
	s_nop 0
	v_mul_f32_e32 v148, 0x3f317217, v131
	v_fma_f32 v148, v131, s4, -v148
	v_fmac_f32_e32 v148, 0x3377d1cf, v131
	s_mov_b32 s4, 0x7f800000
	v_fmac_f32_e32 v148, 0x3f317217, v131
	v_cmp_lt_f32_e64 s[12:13], |v131|, s4
	s_nop 1
	v_cndmask_b32_e64 v131, v131, v148, s[12:13]
	v_cndmask_b32_e32 v148, 0, v227, vcc
	v_sub_f32_e32 v131, v131, v148

; DEV u16 f2bf(float f) { return (u16)(pack2(f, 0.f) & 0xffffu); }
; DEV void phase_win(const Params& P, int l, const u16* __restrict__ xb, const u16* __restrict__ Wt, u16* __restrict__ h, char* smem) {
;     ...
;         for (int j = 0; j < 4; ++j) {
;           int row = m0 + wm * 128 + ms * 16 + quad * 4 + j;
;           int col = cb + ns * 16 + l15;
;           float v = acc[ms][ns][j];
;           if (mode == 1) { float lbv = lbp[col - C_HF]; v = __logf(lbv + (1.f - lbv) / (1.f + __expf(-v))); }
;           else if (mode == 2) v = v / (1.f + __expf(-v));
;           h[(size_t)row * HS + col] = f2bf(v);
.LBB0_1786:
	s_andn2_b64 vcc, exec, s[4:5]
	s_cbranch_vccnz .LBB0_1789
	s_cmp_eq_u32 s17, 1
	v_mov_b32_e32 v131, v76
	s_cbranch_scc0 .LBB0_1789
	v_lshl_add_u64 v[148:149], v[0:1], 2, s[14:15]
	v_add_co_u32_e32 v148, vcc, 0xfffff000, v148
	s_nop 1
	v_addc_co_u32_e32 v149, vcc, -1, v149, vcc
	v_mov_b32_e32 v131, v161
	v_mul_f32_e32 v148, 0xbfb8aa3b, v76
	v_exp_f32_e32 v148, v148
	v_sub_f32_e32 v149, 1.0, v131
	v_add_f32_e32 v148, 1.0, v148
	v_div_scale_f32 v150, s[4:5], v148, v148, v149
	v_rcp_f32_e32 v151, v150
	v_div_scale_f32 v152, vcc, v149, v148, v149
	s_mov_b32 s4, 0x800000
	v_fma_f32 v153, -v150, v151, 1.0
	v_fmac_f32_e32 v151, v153, v151
	v_mul_f32_e32 v153, v152, v151
	v_fma_f32 v154, -v150, v153, v152
	v_fmac_f32_e32 v153, v154, v151
	v_fma_f32 v150, -v150, v153, v152
	v_div_fmas_f32 v150, v150, v151, v153
	v_div_fixup_f32 v148, v150, v148, v149
	v_add_f32_e32 v131, v131, v148
	v_cmp_gt_f32_e32 vcc, s4, v131
	s_mov_b32 s4, 0x3f317217
	s_nop 0
	v_cndmask_b32_e64 v148, 0, 32, vcc
	v_ldexp_f32 v131, v131, v148
	v_log_f32_e32 v131, v131
	s_nop 0
	v_mul_f32_e32 v148, 0x3f317217, v131
	v_fma_f32 v148, v131, s4, -v148
	v_fmac_f32_e32 v148, 0x3377d1cf, v131
	s_mov_b32 s4, 0x7f800000
	v_fmac_f32_e32 v148, 0x3f317217, v131
	v_cmp_lt_f32_e64 s[12:13], |v131|, s4
	s_nop 1
	v_cndmask_b32_e64 v131, v131, v148, s[12:13]
	v_cndmask_b32_e32 v148, 0, v227, vcc
	v_sub_f32_e32 v131, v131, v148

; DEV u16 f2bf(float f) { return (u16)(pack2(f, 0.f) & 0xffffu); }
; DEV void phase_win(const Params& P, int l, const u16* __restrict__ xb, const u16* __restrict__ Wt, u16* __restrict__ h, char* smem) {
;     ...
;         for (int j = 0; j < 4; ++j) {
;           int row = m0 + wm * 128 + ms * 16 + quad * 4 + j;
;           int col = cb + ns * 16 + l15;
;           float v = acc[ms][ns][j];
;           if (mode == 1) { float lbv = lbp[col - C_HF]; v = __logf(lbv + (1.f - lbv) / (1.f + __expf(-v))); }
;           else if (mode == 2) v = v / (1.f + __expf(-v));
;           h[(size_t)row * HS + col] = f2bf(v);
.LBB0_1791:
	s_andn2_b64 vcc, exec, s[4:5]
	s_cbranch_vccnz .LBB0_1794
	s_cmp_eq_u32 s17, 1
	v_mov_b32_e32 v131, v77
	s_cbranch_scc0 .LBB0_1794
	v_lshl_add_u64 v[148:149], v[0:1], 2, s[14:15]
	v_add_co_u32_e32 v148, vcc, 0xfffff000, v148
	s_nop 1
	v_addc_co_u32_e32 v149, vcc, -1, v149, vcc
	v_mov_b32_e32 v131, v161
	v_mul_f32_e32 v148, 0xbfb8aa3b, v77
	v_exp_f32_e32 v148, v148
	v_sub_f32_e32 v149, 1.0, v131
	v_add_f32_e32 v148, 1.0, v148
	v_div_scale_f32 v150, s[4:5], v148, v148, v149
	v_rcp_f32_e32 v151, v150
	v_div_scale_f32 v152, vcc, v149, v148, v149
	s_mov_b32 s4, 0x800000
	v_fma_f32 v153, -v150, v151, 1.0
	v_fmac_f32_e32 v151, v153, v151
	v_mul_f32_e32 v153, v152, v151
	v_fma_f32 v154, -v150, v153, v152
	v_fmac_f32_e32 v153, v154, v151
	v_fma_f32 v150, -v150, v153, v152
	v_div_fmas_f32 v150, v150, v151, v153
	v_div_fixup_f32 v148, v150, v148, v149
	v_add_f32_e32 v131, v131, v148
	v_cmp_gt_f32_e32 vcc, s4, v131
	s_mov_b32 s4, 0x3f317217
	s_nop 0
	v_cndmask_b32_e64 v148, 0, 32, vcc
	v_ldexp_f32 v131, v131, v148
	v_log_f32_e32 v131, v131
	s_nop 0
	v_mul_f32_e32 v148, 0x3f317217, v131
	v_fma_f32 v148, v131, s4, -v148
	v_fmac_f32_e32 v148, 0x3377d1cf, v131
	s_mov_b32 s4, 0x7f800000
	v_fmac_f32_e32 v148, 0x3f317217, v131
	v_cmp_lt_f32_e64 s[12:13], |v131|, s4
	s_nop 1
	v_cndmask_b32_e64 v131, v131, v148, s[12:13]
	v_cndmask_b32_e32 v148, 0, v227, vcc
	v_sub_f32_e32 v131, v131, v148

; DEV u16 f2bf(float f) { return (u16)(pack2(f, 0.f) & 0xffffu); }
; DEV void phase_win(const Params& P, int l, const u16* __restrict__ xb, const u16* __restrict__ Wt, u16* __restrict__ h, char* smem) {
;     ...
;         for (int j = 0; j < 4; ++j) {
;           int row = m0 + wm * 128 + ms * 16 + quad * 4 + j;
;           int col = cb + ns * 16 + l15;
;           float v = acc[ms][ns][j];
;           if (mode == 1) { float lbv = lbp[col - C_HF]; v = __logf(lbv + (1.f - lbv) / (1.f + __expf(-v))); }
;           else if (mode == 2) v = v / (1.f + __expf(-v));
;           h[(size_t)row * HS + col] = f2bf(v);
.LBB0_1796:
	s_andn2_b64 vcc, exec, s[4:5]
	s_cbranch_vccnz .LBB0_1799
	s_cmp_eq_u32 s17, 1
	v_mov_b32_e32 v131, v78
	s_cbranch_scc0 .LBB0_1799
	v_lshl_add_u64 v[148:149], v[0:1], 2, s[14:15]
	v_add_co_u32_e32 v148, vcc, 0xfffff000, v148
	s_nop 1
	v_addc_co_u32_e32 v149, vcc, -1, v149, vcc
	v_mov_b32_e32 v131, v162
	v_mul_f32_e32 v148, 0xbfb8aa3b, v78
	v_exp_f32_e32 v148, v148
	v_sub_f32_e32 v149, 1.0, v131
	v_add_f32_e32 v148, 1.0, v148
	v_div_scale_f32 v150, s[4:5], v148, v148, v149
	v_rcp_f32_e32 v151, v150
	v_div_scale_f32 v152, vcc, v149, v148, v149
	s_mov_b32 s4, 0x800000
	v_fma_f32 v153, -v150, v151, 1.0
	v_fmac_f32_e32 v151, v153, v151
	v_mul_f32_e32 v153, v152, v151
	v_fma_f32 v154, -v150, v153, v152
	v_fmac_f32_e32 v153, v154, v151
	v_fma_f32 v150, -v150, v153, v152
	v_div_fmas_f32 v150, v150, v151, v153
	v_div_fixup_f32 v148, v150, v148, v149
	v_add_f32_e32 v131, v131, v148
	v_cmp_gt_f32_e32 vcc, s4, v131
	s_mov_b32 s4, 0x3f317217
	s_nop 0
	v_cndmask_b32_e64 v148, 0, 32, vcc
	v_ldexp_f32 v131, v131, v148
	v_log_f32_e32 v131, v131
	s_nop 0
	v_mul_f32_e32 v148, 0x3f317217, v131
	v_fma_f32 v148, v131, s4, -v148
	v_fmac_f32_e32 v148, 0x3377d1cf, v131
	s_mov_b32 s4, 0x7f800000
	v_fmac_f32_e32 v148, 0x3f317217, v131
	v_cmp_lt_f32_e64 s[12:13], |v131|, s4
	s_nop 1
	v_cndmask_b32_e64 v131, v131, v148, s[12:13]
	v_cndmask_b32_e32 v148, 0, v227, vcc
	v_sub_f32_e32 v131, v131, v148

; DEV u16 f2bf(float f) { return (u16)(pack2(f, 0.f) & 0xffffu); }
; DEV void phase_win(const Params& P, int l, const u16* __restrict__ xb, const u16* __restrict__ Wt, u16* __restrict__ h, char* smem) {
;     ...
;         for (int j = 0; j < 4; ++j) {
;           int row = m0 + wm * 128 + ms * 16 + quad * 4 + j;
;           int col = cb + ns * 16 + l15;
;           float v = acc[ms][ns][j];
;           if (mode == 1) { float lbv = lbp[col - C_HF]; v = __logf(lbv + (1.f - lbv) / (1.f + __expf(-v))); }
;           else if (mode == 2) v = v / (1.f + __expf(-v));
;           h[(size_t)row * HS + col] = f2bf(v);
.LBB0_1801:
	s_andn2_b64 vcc, exec, s[4:5]
	s_cbranch_vccnz .LBB0_1804
	s_cmp_eq_u32 s17, 1
	v_mov_b32_e32 v131, v79
	s_cbranch_scc0 .LBB0_1804
	v_lshl_add_u64 v[148:149], v[0:1], 2, s[14:15]
	v_add_co_u32_e32 v148, vcc, 0xfffff000, v148
	s_nop 1
	v_addc_co_u32_e32 v149, vcc, -1, v149, vcc
	v_mov_b32_e32 v131, v162
	v_mul_f32_e32 v148, 0xbfb8aa3b, v79
	v_exp_f32_e32 v148, v148
	v_sub_f32_e32 v149, 1.0, v131
	v_add_f32_e32 v148, 1.0, v148
	v_div_scale_f32 v150, s[4:5], v148, v148, v149
	v_rcp_f32_e32 v151, v150
	v_div_scale_f32 v152, vcc, v149, v148, v149
	s_mov_b32 s4, 0x800000
	v_fma_f32 v153, -v150, v151, 1.0
	v_fmac_f32_e32 v151, v153, v151
	v_mul_f32_e32 v153, v152, v151
	v_fma_f32 v154, -v150, v153, v152
	v_fmac_f32_e32 v153, v154, v151
	v_fma_f32 v150, -v150, v153, v152
	v_div_fmas_f32 v150, v150, v151, v153
	v_div_fixup_f32 v148, v150, v148, v149
	v_add_f32_e32 v131, v131, v148
	v_cmp_gt_f32_e32 vcc, s4, v131
	s_mov_b32 s4, 0x3f317217
	s_nop 0
	v_cndmask_b32_e64 v148, 0, 32, vcc
	v_ldexp_f32 v131, v131, v148
	v_log_f32_e32 v131, v131
	s_nop 0
	v_mul_f32_e32 v148, 0x3f317217, v131
	v_fma_f32 v148, v131, s4, -v148
	v_fmac_f32_e32 v148, 0x3377d1cf, v131
	s_mov_b32 s4, 0x7f800000
	v_fmac_f32_e32 v148, 0x3f317217, v131
	v_cmp_lt_f32_e64 s[12:13], |v131|, s4
	s_nop 1
	v_cndmask_b32_e64 v131, v131, v148, s[12:13]
	v_cndmask_b32_e32 v148, 0, v227, vcc
	v_sub_f32_e32 v131, v131, v148

; DEV u16 f2bf(float f) { return (u16)(pack2(f, 0.f) & 0xffffu); }
; DEV void phase_win(const Params& P, int l, const u16* __restrict__ xb, const u16* __restrict__ Wt, u16* __restrict__ h, char* smem) {
;     ...
;         for (int j = 0; j < 4; ++j) {
;           int row = m0 + wm * 128 + ms * 16 + quad * 4 + j;
;           int col = cb + ns * 16 + l15;
;           float v = acc[ms][ns][j];
;           if (mode == 1) { float lbv = lbp[col - C_HF]; v = __logf(lbv + (1.f - lbv) / (1.f + __expf(-v))); }
;           else if (mode == 2) v = v / (1.f + __expf(-v));
;           h[(size_t)row * HS + col] = f2bf(v);
.LBB0_1806:
	s_andn2_b64 vcc, exec, s[4:5]
	s_cbranch_vccnz .LBB0_1809
	s_cmp_eq_u32 s17, 1
	v_mov_b32_e32 v131, v80
	s_cbranch_scc0 .LBB0_1809
	v_lshl_add_u64 v[148:149], v[0:1], 2, s[14:15]
	v_add_co_u32_e32 v148, vcc, 0xfffff000, v148
	s_nop 1
	v_addc_co_u32_e32 v149, vcc, -1, v149, vcc
	v_mov_b32_e32 v131, v162
	v_mul_f32_e32 v148, 0xbfb8aa3b, v80
	v_exp_f32_e32 v148, v148
	v_sub_f32_e32 v149, 1.0, v131
	v_add_f32_e32 v148, 1.0, v148
	v_div_scale_f32 v150, s[4:5], v148, v148, v149
	v_rcp_f32_e32 v151, v150
	v_div_scale_f32 v152, vcc, v149, v148, v149
	s_mov_b32 s4, 0x800000
	v_fma_f32 v153, -v150, v151, 1.0
	v_fmac_f32_e32 v151, v153, v151
	v_mul_f32_e32 v153, v152, v151
	v_fma_f32 v154, -v150, v153, v152
	v_fmac_f32_e32 v153, v154, v151
	v_fma_f32 v150, -v150, v153, v152
	v_div_fmas_f32 v150, v150, v151, v153
	v_div_fixup_f32 v148, v150, v148, v149
	v_add_f32_e32 v131, v131, v148
	v_cmp_gt_f32_e32 vcc, s4, v131
	s_mov_b32 s4, 0x3f317217
	s_nop 0
	v_cndmask_b32_e64 v148, 0, 32, vcc
	v_ldexp_f32 v131, v131, v148
	v_log_f32_e32 v131, v131
	s_nop 0
	v_mul_f32_e32 v148, 0x3f317217, v131
	v_fma_f32 v148, v131, s4, -v148
	v_fmac_f32_e32 v148, 0x3377d1cf, v131
	s_mov_b32 s4, 0x7f800000
	v_fmac_f32_e32 v148, 0x3f317217, v131
	v_cmp_lt_f32_e64 s[12:13], |v131|, s4
	s_nop 1
	v_cndmask_b32_e64 v131, v131, v148, s[12:13]
	v_cndmask_b32_e32 v148, 0, v227, vcc
	v_sub_f32_e32 v131, v131, v148

; DEV u16 f2bf(float f) { return (u16)(pack2(f, 0.f) & 0xffffu); }
; DEV void phase_win(const Params& P, int l, const u16* __restrict__ xb, const u16* __restrict__ Wt, u16* __restrict__ h, char* smem) {
;     ...
;         for (int j = 0; j < 4; ++j) {
;           int row = m0 + wm * 128 + ms * 16 + quad * 4 + j;
;           int col = cb + ns * 16 + l15;
;           float v = acc[ms][ns][j];
;           if (mode == 1) { float lbv = lbp[col - C_HF]; v = __logf(lbv + (1.f - lbv) / (1.f + __expf(-v))); }
;           else if (mode == 2) v = v / (1.f + __expf(-v));
;           h[(size_t)row * HS + col] = f2bf(v);
.LBB0_1811:
	s_andn2_b64 vcc, exec, s[4:5]
	s_cbranch_vccnz .LBB0_1814
	s_cmp_eq_u32 s17, 1
	v_mov_b32_e32 v131, v81
	s_cbranch_scc0 .LBB0_1814
	v_lshl_add_u64 v[148:149], v[0:1], 2, s[14:15]
	v_add_co_u32_e32 v148, vcc, 0xfffff000, v148
	s_nop 1
	v_addc_co_u32_e32 v149, vcc, -1, v149, vcc
	v_mov_b32_e32 v131, v162
	v_mul_f32_e32 v148, 0xbfb8aa3b, v81
	v_exp_f32_e32 v148, v148
	v_sub_f32_e32 v149, 1.0, v131
	v_add_f32_e32 v148, 1.0, v148
	v_div_scale_f32 v150, s[4:5], v148, v148, v149
	v_rcp_f32_e32 v151, v150
	v_div_scale_f32 v152, vcc, v149, v148, v149
	s_mov_b32 s4, 0x800000
	v_fma_f32 v153, -v150, v151, 1.0
	v_fmac_f32_e32 v151, v153, v151
	v_mul_f32_e32 v153, v152, v151
	v_fma_f32 v154, -v150, v153, v152
	v_fmac_f32_e32 v153, v154, v151
	v_fma_f32 v150, -v150, v153, v152
	v_div_fmas_f32 v150, v150, v151, v153
	v_div_fixup_f32 v148, v150, v148, v149
	v_add_f32_e32 v131, v131, v148
	v_cmp_gt_f32_e32 vcc, s4, v131
	s_mov_b32 s4, 0x3f317217
	s_nop 0
	v_cndmask_b32_e64 v148, 0, 32, vcc
	v_ldexp_f32 v131, v131, v148
	v_log_f32_e32 v131, v131
	s_nop 0
	v_mul_f32_e32 v148, 0x3f317217, v131
	v_fma_f32 v148, v131, s4, -v148
	v_fmac_f32_e32 v148, 0x3377d1cf, v131
	s_mov_b32 s4, 0x7f800000
	v_fmac_f32_e32 v148, 0x3f317217, v131
	v_cmp_lt_f32_e64 s[12:13], |v131|, s4
	s_nop 1
	v_cndmask_b32_e64 v131, v131, v148, s[12:13]
	v_cndmask_b32_e32 v148, 0, v227, vcc
	v_sub_f32_e32 v131, v131, v148

; DEV u16 f2bf(float f) { return (u16)(pack2(f, 0.f) & 0xffffu); }
; DEV void phase_win(const Params& P, int l, const u16* __restrict__ xb, const u16* __restrict__ Wt, u16* __restrict__ h, char* smem) {
;     ...
;         for (int j = 0; j < 4; ++j) {
;           int row = m0 + wm * 128 + ms * 16 + quad * 4 + j;
;           int col = cb + ns * 16 + l15;
;           float v = acc[ms][ns][j];
;           if (mode == 1) { float lbv = lbp[col - C_HF]; v = __logf(lbv + (1.f - lbv) / (1.f + __expf(-v))); }
;           else if (mode == 2) v = v / (1.f + __expf(-v));
;           h[(size_t)row * HS + col] = f2bf(v);
.LBB0_1816:
	s_andn2_b64 vcc, exec, s[4:5]
	s_cbranch_vccnz .LBB0_1819
	s_cmp_eq_u32 s17, 1
	v_mov_b32_e32 v131, v70
	s_cbranch_scc0 .LBB0_1819
	v_lshl_add_u64 v[148:149], v[0:1], 2, s[14:15]
	v_add_co_u32_e32 v148, vcc, 0xfffff000, v148
	s_nop 1
	v_addc_co_u32_e32 v149, vcc, -1, v149, vcc
	v_mov_b32_e32 v131, v163
	v_mul_f32_e32 v148, 0xbfb8aa3b, v70
	v_exp_f32_e32 v148, v148
	v_sub_f32_e32 v149, 1.0, v131
	v_add_f32_e32 v148, 1.0, v148
	v_div_scale_f32 v150, s[4:5], v148, v148, v149
	v_rcp_f32_e32 v151, v150
	v_div_scale_f32 v152, vcc, v149, v148, v149
	s_mov_b32 s4, 0x800000
	v_fma_f32 v153, -v150, v151, 1.0
	v_fmac_f32_e32 v151, v153, v151
	v_mul_f32_e32 v153, v152, v151
	v_fma_f32 v154, -v150, v153, v152
	v_fmac_f32_e32 v153, v154, v151
	v_fma_f32 v150, -v150, v153, v152
	v_div_fmas_f32 v150, v150, v151, v153
	v_div_fixup_f32 v148, v150, v148, v149
	v_add_f32_e32 v131, v131, v148
	v_cmp_gt_f32_e32 vcc, s4, v131
	s_mov_b32 s4, 0x3f317217
	s_nop 0
	v_cndmask_b32_e64 v148, 0, 32, vcc
	v_ldexp_f32 v131, v131, v148
	v_log_f32_e32 v131, v131
	s_nop 0
	v_mul_f32_e32 v148, 0x3f317217, v131
	v_fma_f32 v148, v131, s4, -v148
	v_fmac_f32_e32 v148, 0x3377d1cf, v131
	s_mov_b32 s4, 0x7f800000
	v_fmac_f32_e32 v148, 0x3f317217, v131
	v_cmp_lt_f32_e64 s[12:13], |v131|, s4
	s_nop 1
	v_cndmask_b32_e64 v131, v131, v148, s[12:13]
	v_cndmask_b32_e32 v148, 0, v227, vcc
	v_sub_f32_e32 v131, v131, v148

; DEV u16 f2bf(float f) { return (u16)(pack2(f, 0.f) & 0xffffu); }
; DEV void phase_win(const Params& P, int l, const u16* __restrict__ xb, const u16* __restrict__ Wt, u16* __restrict__ h, char* smem) {
;     ...
;         for (int j = 0; j < 4; ++j) {
;           int row = m0 + wm * 128 + ms * 16 + quad * 4 + j;
;           int col = cb + ns * 16 + l15;
;           float v = acc[ms][ns][j];
;           if (mode == 1) { float lbv = lbp[col - C_HF]; v = __logf(lbv + (1.f - lbv) / (1.f + __expf(-v))); }
;           else if (mode == 2) v = v / (1.f + __expf(-v));
;           h[(size_t)row * HS + col] = f2bf(v);
.LBB0_1821:
	s_andn2_b64 vcc, exec, s[4:5]
	s_cbranch_vccnz .LBB0_1824
	s_cmp_eq_u32 s17, 1
	v_mov_b32_e32 v131, v71
	s_cbranch_scc0 .LBB0_1824
	v_lshl_add_u64 v[140:141], v[0:1], 2, s[14:15]
	v_add_co_u32_e32 v140, vcc, 0xfffff000, v140
	s_nop 1
	v_addc_co_u32_e32 v141, vcc, -1, v141, vcc
	v_mov_b32_e32 v131, v163
	v_mul_f32_e32 v140, 0xbfb8aa3b, v71
	v_exp_f32_e32 v140, v140
	v_sub_f32_e32 v141, 1.0, v131
	v_add_f32_e32 v140, 1.0, v140
	v_div_scale_f32 v148, s[4:5], v140, v140, v141
	v_rcp_f32_e32 v149, v148
	v_div_scale_f32 v150, vcc, v141, v140, v141
	s_mov_b32 s4, 0x800000
	v_fma_f32 v151, -v148, v149, 1.0
	v_fmac_f32_e32 v149, v151, v149
	v_mul_f32_e32 v151, v150, v149
	v_fma_f32 v152, -v148, v151, v150
	v_fmac_f32_e32 v151, v152, v149
	v_fma_f32 v148, -v148, v151, v150
	v_div_fmas_f32 v148, v148, v149, v151
	v_div_fixup_f32 v140, v148, v140, v141
	v_add_f32_e32 v131, v131, v140
	v_cmp_gt_f32_e32 vcc, s4, v131
	s_mov_b32 s4, 0x3f317217
	s_nop 0
	v_cndmask_b32_e64 v140, 0, 32, vcc
	v_ldexp_f32 v131, v131, v140
	v_log_f32_e32 v131, v131
	s_nop 0
	v_mul_f32_e32 v140, 0x3f317217, v131
	v_fma_f32 v140, v131, s4, -v140
	v_fmac_f32_e32 v140, 0x3377d1cf, v131
	s_mov_b32 s4, 0x7f800000
	v_fmac_f32_e32 v140, 0x3f317217, v131
	v_cmp_lt_f32_e64 s[12:13], |v131|, s4
	s_nop 1
	v_cndmask_b32_e64 v131, v131, v140, s[12:13]
	v_cndmask_b32_e32 v140, 0, v227, vcc
	v_sub_f32_e32 v131, v131, v140

; DEV u16 f2bf(float f) { return (u16)(pack2(f, 0.f) & 0xffffu); }
; DEV void phase_win(const Params& P, int l, const u16* __restrict__ xb, const u16* __restrict__ Wt, u16* __restrict__ h, char* smem) {
;     ...
;         for (int j = 0; j < 4; ++j) {
;           int row = m0 + wm * 128 + ms * 16 + quad * 4 + j;
;           int col = cb + ns * 16 + l15;
;           float v = acc[ms][ns][j];
;           if (mode == 1) { float lbv = lbp[col - C_HF]; v = __logf(lbv + (1.f - lbv) / (1.f + __expf(-v))); }
;           else if (mode == 2) v = v / (1.f + __expf(-v));
;           h[(size_t)row * HS + col] = f2bf(v);
.LBB0_1826:
	s_andn2_b64 vcc, exec, s[4:5]
	s_cbranch_vccnz .LBB0_1829
	s_cmp_eq_u32 s17, 1
	v_mov_b32_e32 v131, v72
	s_cbranch_scc0 .LBB0_1829
	v_lshl_add_u64 v[140:141], v[0:1], 2, s[14:15]
	v_add_co_u32_e32 v140, vcc, 0xfffff000, v140
	s_nop 1
	v_addc_co_u32_e32 v141, vcc, -1, v141, vcc
	v_mov_b32_e32 v131, v163
	v_mul_f32_e32 v140, 0xbfb8aa3b, v72
	v_exp_f32_e32 v140, v140
	v_sub_f32_e32 v141, 1.0, v131
	v_add_f32_e32 v140, 1.0, v140
	v_div_scale_f32 v142, s[4:5], v140, v140, v141
	v_rcp_f32_e32 v143, v142
	v_div_scale_f32 v148, vcc, v141, v140, v141
	s_mov_b32 s4, 0x800000
	v_fma_f32 v149, -v142, v143, 1.0
	v_fmac_f32_e32 v143, v149, v143
	v_mul_f32_e32 v149, v148, v143
	v_fma_f32 v150, -v142, v149, v148
	v_fmac_f32_e32 v149, v150, v143
	v_fma_f32 v142, -v142, v149, v148
	v_div_fmas_f32 v142, v142, v143, v149
	v_div_fixup_f32 v140, v142, v140, v141
	v_add_f32_e32 v131, v131, v140
	v_cmp_gt_f32_e32 vcc, s4, v131
	s_mov_b32 s4, 0x3f317217
	s_nop 0
	v_cndmask_b32_e64 v140, 0, 32, vcc
	v_ldexp_f32 v131, v131, v140
	v_log_f32_e32 v131, v131
	s_nop 0
	v_mul_f32_e32 v140, 0x3f317217, v131
	v_fma_f32 v140, v131, s4, -v140
	v_fmac_f32_e32 v140, 0x3377d1cf, v131
	s_mov_b32 s4, 0x7f800000
	v_fmac_f32_e32 v140, 0x3f317217, v131
	v_cmp_lt_f32_e64 s[12:13], |v131|, s4
	s_nop 1
	v_cndmask_b32_e64 v131, v131, v140, s[12:13]
	v_cndmask_b32_e32 v140, 0, v227, vcc
	v_sub_f32_e32 v131, v131, v140

; DEV u16 f2bf(float f) { return (u16)(pack2(f, 0.f) & 0xffffu); }
; DEV void phase_win(const Params& P, int l, const u16* __restrict__ xb, const u16* __restrict__ Wt, u16* __restrict__ h, char* smem) {
;     ...
;         for (int j = 0; j < 4; ++j) {
;           int row = m0 + wm * 128 + ms * 16 + quad * 4 + j;
;           int col = cb + ns * 16 + l15;
;           float v = acc[ms][ns][j];
;           if (mode == 1) { float lbv = lbp[col - C_HF]; v = __logf(lbv + (1.f - lbv) / (1.f + __expf(-v))); }
;           else if (mode == 2) v = v / (1.f + __expf(-v));
;           h[(size_t)row * HS + col] = f2bf(v);
.LBB0_1831:
	s_andn2_b64 vcc, exec, s[4:5]
	s_cbranch_vccnz .LBB0_1834
	s_cmp_eq_u32 s17, 1
	v_mov_b32_e32 v131, v73
	s_cbranch_scc0 .LBB0_1834
	v_lshl_add_u64 v[140:141], v[0:1], 2, s[14:15]
	v_add_co_u32_e32 v140, vcc, 0xfffff000, v140
	s_nop 1
	v_addc_co_u32_e32 v141, vcc, -1, v141, vcc
	v_mov_b32_e32 v131, v163
	v_mul_f32_e32 v140, 0xbfb8aa3b, v73
	v_exp_f32_e32 v140, v140
	v_sub_f32_e32 v141, 1.0, v131
	v_add_f32_e32 v140, 1.0, v140
	v_div_scale_f32 v142, s[4:5], v140, v140, v141
	v_rcp_f32_e32 v143, v142
	v_div_scale_f32 v144, vcc, v141, v140, v141
	s_mov_b32 s4, 0x800000
	v_fma_f32 v145, -v142, v143, 1.0
	v_fmac_f32_e32 v143, v145, v143
	v_mul_f32_e32 v145, v144, v143
	v_fma_f32 v148, -v142, v145, v144
	v_fmac_f32_e32 v145, v148, v143
	v_fma_f32 v142, -v142, v145, v144
	v_div_fmas_f32 v142, v142, v143, v145
	v_div_fixup_f32 v140, v142, v140, v141
	v_add_f32_e32 v131, v131, v140
	v_cmp_gt_f32_e32 vcc, s4, v131
	s_mov_b32 s4, 0x3f317217
	s_nop 0
	v_cndmask_b32_e64 v140, 0, 32, vcc
	v_ldexp_f32 v131, v131, v140
	v_log_f32_e32 v131, v131
	s_nop 0
	v_mul_f32_e32 v140, 0x3f317217, v131
	v_fma_f32 v140, v131, s4, -v140
	v_fmac_f32_e32 v140, 0x3377d1cf, v131
	s_mov_b32 s4, 0x7f800000
	v_fmac_f32_e32 v140, 0x3f317217, v131
	v_cmp_lt_f32_e64 s[12:13], |v131|, s4
	s_nop 1
	v_cndmask_b32_e64 v131, v131, v140, s[12:13]
	v_cndmask_b32_e32 v140, 0, v227, vcc
	v_sub_f32_e32 v131, v131, v140

; DEV u16 f2bf(float f) { return (u16)(pack2(f, 0.f) & 0xffffu); }
; DEV void phase_win(const Params& P, int l, const u16* __restrict__ xb, const u16* __restrict__ Wt, u16* __restrict__ h, char* smem) {
;     ...
;         for (int j = 0; j < 4; ++j) {
;           int row = m0 + wm * 128 + ms * 16 + quad * 4 + j;
;           int col = cb + ns * 16 + l15;
;           float v = acc[ms][ns][j];
;           if (mode == 1) { float lbv = lbp[col - C_HF]; v = __logf(lbv + (1.f - lbv) / (1.f + __expf(-v))); }
;           else if (mode == 2) v = v / (1.f + __expf(-v));
;           h[(size_t)row * HS + col] = f2bf(v);
.LBB0_1836:
	s_andn2_b64 vcc, exec, s[4:5]
	s_cbranch_vccnz .LBB0_1839
	s_cmp_eq_u32 s17, 1
	v_mov_b32_e32 v140, v10
	s_cbranch_scc0 .LBB0_1839
	v_lshl_add_u64 v[140:141], v[0:1], 2, s[14:15]
	v_add_co_u32_e32 v140, vcc, 0xfffff000, v140
	s_nop 1
	v_addc_co_u32_e32 v141, vcc, -1, v141, vcc
	v_mov_b32_e32 v131, v160
	v_mul_f32_e32 v140, 0xbfb8aa3b, v10
	v_exp_f32_e32 v140, v140
	v_sub_f32_e32 v141, 1.0, v131
	v_add_f32_e32 v140, 1.0, v140
	v_div_scale_f32 v142, s[4:5], v140, v140, v141
	v_rcp_f32_e32 v143, v142
	v_div_scale_f32 v144, vcc, v141, v140, v141
	s_mov_b32 s4, 0x800000
	v_fma_f32 v145, -v142, v143, 1.0
	v_fmac_f32_e32 v143, v145, v143
	v_mul_f32_e32 v145, v144, v143
	v_fma_f32 v146, -v142, v145, v144
	v_fmac_f32_e32 v145, v146, v143
	v_fma_f32 v142, -v142, v145, v144
	v_div_fmas_f32 v142, v142, v143, v145
	v_div_fixup_f32 v140, v142, v140, v141
	v_add_f32_e32 v131, v131, v140
	v_cmp_gt_f32_e32 vcc, s4, v131
	s_mov_b32 s4, 0x3f317217
	s_nop 0
	v_cndmask_b32_e64 v140, 0, 32, vcc
	v_ldexp_f32 v131, v131, v140
	v_log_f32_e32 v131, v131
	s_nop 0
	v_mul_f32_e32 v140, 0x3f317217, v131
	v_fma_f32 v140, v131, s4, -v140
	v_fmac_f32_e32 v140, 0x3377d1cf, v131
	s_mov_b32 s4, 0x7f800000
	v_fmac_f32_e32 v140, 0x3f317217, v131
	v_cmp_lt_f32_e64 s[12:13], |v131|, s4
	s_nop 1
	v_cndmask_b32_e64 v131, v131, v140, s[12:13]
	v_cndmask_b32_e32 v140, 0, v227, vcc
	v_sub_f32_e32 v140, v131, v140

; DEV u16 f2bf(float f) { return (u16)(pack2(f, 0.f) & 0xffffu); }
; DEV void phase_win(const Params& P, int l, const u16* __restrict__ xb, const u16* __restrict__ Wt, u16* __restrict__ h, char* smem) {
;     ...
;         for (int j = 0; j < 4; ++j) {
;           int row = m0 + wm * 128 + ms * 16 + quad * 4 + j;
;           int col = cb + ns * 16 + l15;
;           float v = acc[ms][ns][j];
;           if (mode == 1) { float lbv = lbp[col - C_HF]; v = __logf(lbv + (1.f - lbv) / (1.f + __expf(-v))); }
;           else if (mode == 2) v = v / (1.f + __expf(-v));
;           h[(size_t)row * HS + col] = f2bf(v);
.LBB0_1841:
	s_andn2_b64 vcc, exec, s[4:5]
	s_cbranch_vccnz .LBB0_1844
	s_cmp_eq_u32 s17, 1
	v_mov_b32_e32 v142, v11
	s_cbranch_scc0 .LBB0_1844
	v_lshl_add_u64 v[142:143], v[0:1], 2, s[14:15]
	v_add_co_u32_e32 v142, vcc, 0xfffff000, v142
	s_nop 1
	v_addc_co_u32_e32 v143, vcc, -1, v143, vcc
	v_mov_b32_e32 v142, v160
	v_mul_f32_e32 v143, 0xbfb8aa3b, v11
	v_exp_f32_e32 v143, v143
	v_sub_f32_e32 v144, 1.0, v142
	v_add_f32_e32 v143, 1.0, v143
	v_div_scale_f32 v145, s[4:5], v143, v143, v144
	v_rcp_f32_e32 v146, v145
	v_div_scale_f32 v147, vcc, v144, v143, v144
	s_mov_b32 s4, 0x800000
	v_fma_f32 v148, -v145, v146, 1.0
	v_fmac_f32_e32 v146, v148, v146
	v_mul_f32_e32 v148, v147, v146
	v_fma_f32 v149, -v145, v148, v147
	v_fmac_f32_e32 v148, v149, v146
	v_fma_f32 v145, -v145, v148, v147
	v_div_fmas_f32 v145, v145, v146, v148
	v_div_fixup_f32 v143, v145, v143, v144
	v_add_f32_e32 v142, v142, v143
	v_cmp_gt_f32_e32 vcc, s4, v142
	s_mov_b32 s4, 0x3f317217
	s_nop 0
	v_cndmask_b32_e64 v143, 0, 32, vcc
	v_ldexp_f32 v142, v142, v143
	v_log_f32_e32 v142, v142
	s_nop 0
	v_mul_f32_e32 v143, 0x3f317217, v142
	v_fma_f32 v143, v142, s4, -v143
	v_fmac_f32_e32 v143, 0x3377d1cf, v142
	s_mov_b32 s4, 0x7f800000
	v_fmac_f32_e32 v143, 0x3f317217, v142
	v_cmp_lt_f32_e64 s[12:13], |v142|, s4
	s_nop 1
	v_cndmask_b32_e64 v142, v142, v143, s[12:13]
	v_cndmask_b32_e32 v143, 0, v227, vcc
	v_sub_f32_e32 v142, v142, v143

; DEV u16 f2bf(float f) { return (u16)(pack2(f, 0.f) & 0xffffu); }
; DEV void phase_win(const Params& P, int l, const u16* __restrict__ xb, const u16* __restrict__ Wt, u16* __restrict__ h, char* smem) {
;     ...
;         for (int j = 0; j < 4; ++j) {
;           int row = m0 + wm * 128 + ms * 16 + quad * 4 + j;
;           int col = cb + ns * 16 + l15;
;           float v = acc[ms][ns][j];
;           if (mode == 1) { float lbv = lbp[col - C_HF]; v = __logf(lbv + (1.f - lbv) / (1.f + __expf(-v))); }
;           else if (mode == 2) v = v / (1.f + __expf(-v));
;           h[(size_t)row * HS + col] = f2bf(v);
.LBB0_1846:
	s_andn2_b64 vcc, exec, s[4:5]
	s_cbranch_vccnz .LBB0_1849
	s_cmp_eq_u32 s17, 1
	v_mov_b32_e32 v144, v12
	s_cbranch_scc0 .LBB0_1849
	v_lshl_add_u64 v[144:145], v[0:1], 2, s[14:15]
	v_add_co_u32_e32 v144, vcc, 0xfffff000, v144
	s_nop 1
	v_addc_co_u32_e32 v145, vcc, -1, v145, vcc
	v_mov_b32_e32 v144, v160
	v_mul_f32_e32 v145, 0xbfb8aa3b, v12
	v_exp_f32_e32 v145, v145
	v_sub_f32_e32 v146, 1.0, v144
	v_add_f32_e32 v145, 1.0, v145
	v_div_scale_f32 v147, s[4:5], v145, v145, v146
	v_rcp_f32_e32 v148, v147
	v_div_scale_f32 v149, vcc, v146, v145, v146
	s_mov_b32 s4, 0x800000
	v_fma_f32 v150, -v147, v148, 1.0
	v_fmac_f32_e32 v148, v150, v148
	v_mul_f32_e32 v150, v149, v148
	v_fma_f32 v151, -v147, v150, v149
	v_fmac_f32_e32 v150, v151, v148
	v_fma_f32 v147, -v147, v150, v149
	v_div_fmas_f32 v147, v147, v148, v150
	v_div_fixup_f32 v145, v147, v145, v146
	v_add_f32_e32 v144, v144, v145
	v_cmp_gt_f32_e32 vcc, s4, v144
	s_mov_b32 s4, 0x3f317217
	s_nop 0
	v_cndmask_b32_e64 v145, 0, 32, vcc
	v_ldexp_f32 v144, v144, v145
	v_log_f32_e32 v144, v144
	s_nop 0
	v_mul_f32_e32 v145, 0x3f317217, v144
	v_fma_f32 v145, v144, s4, -v145
	v_fmac_f32_e32 v145, 0x3377d1cf, v144
	s_mov_b32 s4, 0x7f800000
	v_fmac_f32_e32 v145, 0x3f317217, v144
	v_cmp_lt_f32_e64 s[12:13], |v144|, s4
	s_nop 1
	v_cndmask_b32_e64 v144, v144, v145, s[12:13]
	v_cndmask_b32_e32 v145, 0, v227, vcc
	v_sub_f32_e32 v144, v144, v145

; DEV u16 f2bf(float f) { return (u16)(pack2(f, 0.f) & 0xffffu); }
; DEV void phase_win(const Params& P, int l, const u16* __restrict__ xb, const u16* __restrict__ Wt, u16* __restrict__ h, char* smem) {
;     ...
;         for (int j = 0; j < 4; ++j) {
;           int row = m0 + wm * 128 + ms * 16 + quad * 4 + j;
;           int col = cb + ns * 16 + l15;
;           float v = acc[ms][ns][j];
;           if (mode == 1) { float lbv = lbp[col - C_HF]; v = __logf(lbv + (1.f - lbv) / (1.f + __expf(-v))); }
;           else if (mode == 2) v = v / (1.f + __expf(-v));
;           h[(size_t)row * HS + col] = f2bf(v);
.LBB0_1851:
	s_andn2_b64 vcc, exec, s[4:5]
	s_cbranch_vccnz .LBB0_1854
	s_cmp_eq_u32 s17, 1
	v_mov_b32_e32 v146, v13
	s_cbranch_scc0 .LBB0_1854
	v_lshl_add_u64 v[146:147], v[0:1], 2, s[14:15]
	v_add_co_u32_e32 v146, vcc, 0xfffff000, v146
	s_nop 1
	v_addc_co_u32_e32 v147, vcc, -1, v147, vcc
	v_mov_b32_e32 v146, v160
	v_mul_f32_e32 v147, 0xbfb8aa3b, v13
	v_exp_f32_e32 v147, v147
	v_sub_f32_e32 v148, 1.0, v146
	v_add_f32_e32 v147, 1.0, v147
	v_div_scale_f32 v149, s[4:5], v147, v147, v148
	v_rcp_f32_e32 v150, v149
	v_div_scale_f32 v151, vcc, v148, v147, v148
	s_mov_b32 s4, 0x800000
	v_fma_f32 v152, -v149, v150, 1.0
	v_fmac_f32_e32 v150, v152, v150
	v_mul_f32_e32 v152, v151, v150
	v_fma_f32 v153, -v149, v152, v151
	v_fmac_f32_e32 v152, v153, v150
	v_fma_f32 v149, -v149, v152, v151
	v_div_fmas_f32 v149, v149, v150, v152
	v_div_fixup_f32 v147, v149, v147, v148
	v_add_f32_e32 v146, v146, v147
	v_cmp_gt_f32_e32 vcc, s4, v146
	s_mov_b32 s4, 0x3f317217
	s_nop 0
	v_cndmask_b32_e64 v147, 0, 32, vcc
	v_ldexp_f32 v146, v146, v147
	v_log_f32_e32 v146, v146
	s_nop 0
	v_mul_f32_e32 v147, 0x3f317217, v146
	v_fma_f32 v147, v146, s4, -v147
	v_fmac_f32_e32 v147, 0x3377d1cf, v146
	s_mov_b32 s4, 0x7f800000
	v_fmac_f32_e32 v147, 0x3f317217, v146
	v_cmp_lt_f32_e64 s[12:13], |v146|, s4
	s_nop 1
	v_cndmask_b32_e64 v146, v146, v147, s[12:13]
	v_cndmask_b32_e32 v147, 0, v227, vcc
	v_sub_f32_e32 v146, v146, v147

; DEV u16 f2bf(float f) { return (u16)(pack2(f, 0.f) & 0xffffu); }
; DEV void phase_win(const Params& P, int l, const u16* __restrict__ xb, const u16* __restrict__ Wt, u16* __restrict__ h, char* smem) {
;     ...
;         for (int j = 0; j < 4; ++j) {
;           int row = m0 + wm * 128 + ms * 16 + quad * 4 + j;
;           int col = cb + ns * 16 + l15;
;           float v = acc[ms][ns][j];
;           if (mode == 1) { float lbv = lbp[col - C_HF]; v = __logf(lbv + (1.f - lbv) / (1.f + __expf(-v))); }
;           else if (mode == 2) v = v / (1.f + __expf(-v));
;           h[(size_t)row * HS + col] = f2bf(v);
.LBB0_1856:
	s_andn2_b64 vcc, exec, s[4:5]
	s_cbranch_vccnz .LBB0_1859
	s_cmp_eq_u32 s17, 1
	v_mov_b32_e32 v131, v62
	s_cbranch_scc0 .LBB0_1859
	v_lshl_add_u64 v[148:149], v[0:1], 2, s[14:15]
	v_add_co_u32_e32 v148, vcc, 0xfffff000, v148
	s_nop 1
	v_addc_co_u32_e32 v149, vcc, -1, v149, vcc
	v_mov_b32_e32 v131, v161
	v_mul_f32_e32 v148, 0xbfb8aa3b, v62
	v_exp_f32_e32 v148, v148
	v_sub_f32_e32 v149, 1.0, v131
	v_add_f32_e32 v148, 1.0, v148
	v_div_scale_f32 v150, s[4:5], v148, v148, v149
	v_rcp_f32_e32 v151, v150
	v_div_scale_f32 v152, vcc, v149, v148, v149
	s_mov_b32 s4, 0x800000
	v_fma_f32 v153, -v150, v151, 1.0
	v_fmac_f32_e32 v151, v153, v151
	v_mul_f32_e32 v153, v152, v151
	v_fma_f32 v154, -v150, v153, v152
	v_fmac_f32_e32 v153, v154, v151
	v_fma_f32 v150, -v150, v153, v152
	v_div_fmas_f32 v150, v150, v151, v153
	v_div_fixup_f32 v148, v150, v148, v149
	v_add_f32_e32 v131, v131, v148
	v_cmp_gt_f32_e32 vcc, s4, v131
	s_mov_b32 s4, 0x3f317217
	s_nop 0
	v_cndmask_b32_e64 v148, 0, 32, vcc
	v_ldexp_f32 v131, v131, v148
	v_log_f32_e32 v131, v131
	s_nop 0
	v_mul_f32_e32 v148, 0x3f317217, v131
	v_fma_f32 v148, v131, s4, -v148
	v_fmac_f32_e32 v148, 0x3377d1cf, v131
	s_mov_b32 s4, 0x7f800000
	v_fmac_f32_e32 v148, 0x3f317217, v131
	v_cmp_lt_f32_e64 s[12:13], |v131|, s4
	s_nop 1
	v_cndmask_b32_e64 v131, v131, v148, s[12:13]
	v_cndmask_b32_e32 v148, 0, v227, vcc
	v_sub_f32_e32 v131, v131, v148

; DEV u16 f2bf(float f) { return (u16)(pack2(f, 0.f) & 0xffffu); }
; DEV void phase_win(const Params& P, int l, const u16* __restrict__ xb, const u16* __restrict__ Wt, u16* __restrict__ h, char* smem) {
;     ...
;         for (int j = 0; j < 4; ++j) {
;           int row = m0 + wm * 128 + ms * 16 + quad * 4 + j;
;           int col = cb + ns * 16 + l15;
;           float v = acc[ms][ns][j];
;           if (mode == 1) { float lbv = lbp[col - C_HF]; v = __logf(lbv + (1.f - lbv) / (1.f + __expf(-v))); }
;           else if (mode == 2) v = v / (1.f + __expf(-v));
;           h[(size_t)row * HS + col] = f2bf(v);
.LBB0_1861:
	s_andn2_b64 vcc, exec, s[4:5]
	s_cbranch_vccnz .LBB0_1864
	s_cmp_eq_u32 s17, 1
	v_mov_b32_e32 v131, v63
	s_cbranch_scc0 .LBB0_1864
	v_lshl_add_u64 v[148:149], v[0:1], 2, s[14:15]
	v_add_co_u32_e32 v148, vcc, 0xfffff000, v148
	s_nop 1
	v_addc_co_u32_e32 v149, vcc, -1, v149, vcc
	v_mov_b32_e32 v131, v161
	v_mul_f32_e32 v148, 0xbfb8aa3b, v63
	v_exp_f32_e32 v148, v148
	v_sub_f32_e32 v149, 1.0, v131
	v_add_f32_e32 v148, 1.0, v148
	v_div_scale_f32 v150, s[4:5], v148, v148, v149
	v_rcp_f32_e32 v151, v150
	v_div_scale_f32 v152, vcc, v149, v148, v149
	s_mov_b32 s4, 0x800000
	v_fma_f32 v153, -v150, v151, 1.0
	v_fmac_f32_e32 v151, v153, v151
	v_mul_f32_e32 v153, v152, v151
	v_fma_f32 v154, -v150, v153, v152
	v_fmac_f32_e32 v153, v154, v151
	v_fma_f32 v150, -v150, v153, v152
	v_div_fmas_f32 v150, v150, v151, v153
	v_div_fixup_f32 v148, v150, v148, v149
	v_add_f32_e32 v131, v131, v148
	v_cmp_gt_f32_e32 vcc, s4, v131
	s_mov_b32 s4, 0x3f317217
	s_nop 0
	v_cndmask_b32_e64 v148, 0, 32, vcc
	v_ldexp_f32 v131, v131, v148
	v_log_f32_e32 v131, v131
	s_nop 0
	v_mul_f32_e32 v148, 0x3f317217, v131
	v_fma_f32 v148, v131, s4, -v148
	v_fmac_f32_e32 v148, 0x3377d1cf, v131
	s_mov_b32 s4, 0x7f800000
	v_fmac_f32_e32 v148, 0x3f317217, v131
	v_cmp_lt_f32_e64 s[12:13], |v131|, s4
	s_nop 1
	v_cndmask_b32_e64 v131, v131, v148, s[12:13]
	v_cndmask_b32_e32 v148, 0, v227, vcc
	v_sub_f32_e32 v131, v131, v148

; DEV u16 f2bf(float f) { return (u16)(pack2(f, 0.f) & 0xffffu); }
; DEV void phase_win(const Params& P, int l, const u16* __restrict__ xb, const u16* __restrict__ Wt, u16* __restrict__ h, char* smem) {
;     ...
;         for (int j = 0; j < 4; ++j) {
;           int row = m0 + wm * 128 + ms * 16 + quad * 4 + j;
;           int col = cb + ns * 16 + l15;
;           float v = acc[ms][ns][j];
;           if (mode == 1) { float lbv = lbp[col - C_HF]; v = __logf(lbv + (1.f - lbv) / (1.f + __expf(-v))); }
;           else if (mode == 2) v = v / (1.f + __expf(-v));
;           h[(size_t)row * HS + col] = f2bf(v);
.LBB0_1866:
	s_andn2_b64 vcc, exec, s[4:5]
	s_cbranch_vccnz .LBB0_1869
	s_cmp_eq_u32 s17, 1
	v_mov_b32_e32 v131, v64
	s_cbranch_scc0 .LBB0_1869
	v_lshl_add_u64 v[148:149], v[0:1], 2, s[14:15]
	v_add_co_u32_e32 v148, vcc, 0xfffff000, v148
	s_nop 1
	v_addc_co_u32_e32 v149, vcc, -1, v149, vcc
	v_mov_b32_e32 v131, v161
	v_mul_f32_e32 v148, 0xbfb8aa3b, v64
	v_exp_f32_e32 v148, v148
	v_sub_f32_e32 v149, 1.0, v131
	v_add_f32_e32 v148, 1.0, v148
	v_div_scale_f32 v150, s[4:5], v148, v148, v149
	v_rcp_f32_e32 v151, v150
	v_div_scale_f32 v152, vcc, v149, v148, v149
	s_mov_b32 s4, 0x800000
	v_fma_f32 v153, -v150, v151, 1.0
	v_fmac_f32_e32 v151, v153, v151
	v_mul_f32_e32 v153, v152, v151
	v_fma_f32 v154, -v150, v153, v152
	v_fmac_f32_e32 v153, v154, v151
	v_fma_f32 v150, -v150, v153, v152
	v_div_fmas_f32 v150, v150, v151, v153
	v_div_fixup_f32 v148, v150, v148, v149
	v_add_f32_e32 v131, v131, v148
	v_cmp_gt_f32_e32 vcc, s4, v131
	s_mov_b32 s4, 0x3f317217
	s_nop 0
	v_cndmask_b32_e64 v148, 0, 32, vcc
	v_ldexp_f32 v131, v131, v148
	v_log_f32_e32 v131, v131
	s_nop 0
	v_mul_f32_e32 v148, 0x3f317217, v131
	v_fma_f32 v148, v131, s4, -v148
	v_fmac_f32_e32 v148, 0x3377d1cf, v131
	s_mov_b32 s4, 0x7f800000
	v_fmac_f32_e32 v148, 0x3f317217, v131
	v_cmp_lt_f32_e64 s[12:13], |v131|, s4
	s_nop 1
	v_cndmask_b32_e64 v131, v131, v148, s[12:13]
	v_cndmask_b32_e32 v148, 0, v227, vcc
	v_sub_f32_e32 v131, v131, v148

; DEV u16 f2bf(float f) { return (u16)(pack2(f, 0.f) & 0xffffu); }
; DEV void phase_win(const Params& P, int l, const u16* __restrict__ xb, const u16* __restrict__ Wt, u16* __restrict__ h, char* smem) {
;     ...
;         for (int j = 0; j < 4; ++j) {
;           int row = m0 + wm * 128 + ms * 16 + quad * 4 + j;
;           int col = cb + ns * 16 + l15;
;           float v = acc[ms][ns][j];
;           if (mode == 1) { float lbv = lbp[col - C_HF]; v = __logf(lbv + (1.f - lbv) / (1.f + __expf(-v))); }
;           else if (mode == 2) v = v / (1.f + __expf(-v));
;           h[(size_t)row * HS + col] = f2bf(v);
.LBB0_1871:
	s_andn2_b64 vcc, exec, s[4:5]
	s_cbranch_vccnz .LBB0_1874
	s_cmp_eq_u32 s17, 1
	v_mov_b32_e32 v131, v65
	s_cbranch_scc0 .LBB0_1874
	v_lshl_add_u64 v[148:149], v[0:1], 2, s[14:15]
	v_add_co_u32_e32 v148, vcc, 0xfffff000, v148
	s_nop 1
	v_addc_co_u32_e32 v149, vcc, -1, v149, vcc
	v_mov_b32_e32 v131, v161
	v_mul_f32_e32 v148, 0xbfb8aa3b, v65
	v_exp_f32_e32 v148, v148
	v_sub_f32_e32 v149, 1.0, v131
	v_add_f32_e32 v148, 1.0, v148
	v_div_scale_f32 v150, s[4:5], v148, v148, v149
	v_rcp_f32_e32 v151, v150
	v_div_scale_f32 v152, vcc, v149, v148, v149
	s_mov_b32 s4, 0x800000
	v_fma_f32 v153, -v150, v151, 1.0
	v_fmac_f32_e32 v151, v153, v151
	v_mul_f32_e32 v153, v152, v151
	v_fma_f32 v154, -v150, v153, v152
	v_fmac_f32_e32 v153, v154, v151
	v_fma_f32 v150, -v150, v153, v152
	v_div_fmas_f32 v150, v150, v151, v153
	v_div_fixup_f32 v148, v150, v148, v149
	v_add_f32_e32 v131, v131, v148
	v_cmp_gt_f32_e32 vcc, s4, v131
	s_mov_b32 s4, 0x3f317217
	s_nop 0
	v_cndmask_b32_e64 v148, 0, 32, vcc
	v_ldexp_f32 v131, v131, v148
	v_log_f32_e32 v131, v131
	s_nop 0
	v_mul_f32_e32 v148, 0x3f317217, v131
	v_fma_f32 v148, v131, s4, -v148
	v_fmac_f32_e32 v148, 0x3377d1cf, v131
	s_mov_b32 s4, 0x7f800000
	v_fmac_f32_e32 v148, 0x3f317217, v131
	v_cmp_lt_f32_e64 s[12:13], |v131|, s4
	s_nop 1
	v_cndmask_b32_e64 v131, v131, v148, s[12:13]
	v_cndmask_b32_e32 v148, 0, v227, vcc
	v_sub_f32_e32 v131, v131, v148

; DEV u16 f2bf(float f) { return (u16)(pack2(f, 0.f) & 0xffffu); }
; DEV void phase_win(const Params& P, int l, const u16* __restrict__ xb, const u16* __restrict__ Wt, u16* __restrict__ h, char* smem) {
;     ...
;         for (int j = 0; j < 4; ++j) {
;           int row = m0 + wm * 128 + ms * 16 + quad * 4 + j;
;           int col = cb + ns * 16 + l15;
;           float v = acc[ms][ns][j];
;           if (mode == 1) { float lbv = lbp[col - C_HF]; v = __logf(lbv + (1.f - lbv) / (1.f + __expf(-v))); }
;           else if (mode == 2) v = v / (1.f + __expf(-v));
;           h[(size_t)row * HS + col] = f2bf(v);
.LBB0_1876:
	s_andn2_b64 vcc, exec, s[4:5]
	s_cbranch_vccnz .LBB0_1879
	s_cmp_eq_u32 s17, 1
	v_mov_b32_e32 v131, v66
	s_cbranch_scc0 .LBB0_1879
	v_lshl_add_u64 v[148:149], v[0:1], 2, s[14:15]
	v_add_co_u32_e32 v148, vcc, 0xfffff000, v148
	s_nop 1
	v_addc_co_u32_e32 v149, vcc, -1, v149, vcc
	v_mov_b32_e32 v131, v162
	v_mul_f32_e32 v148, 0xbfb8aa3b, v66
	v_exp_f32_e32 v148, v148
	v_sub_f32_e32 v149, 1.0, v131
	v_add_f32_e32 v148, 1.0, v148
	v_div_scale_f32 v150, s[4:5], v148, v148, v149
	v_rcp_f32_e32 v151, v150
	v_div_scale_f32 v152, vcc, v149, v148, v149
	s_mov_b32 s4, 0x800000
	v_fma_f32 v153, -v150, v151, 1.0
	v_fmac_f32_e32 v151, v153, v151
	v_mul_f32_e32 v153, v152, v151
	v_fma_f32 v154, -v150, v153, v152
	v_fmac_f32_e32 v153, v154, v151
	v_fma_f32 v150, -v150, v153, v152
	v_div_fmas_f32 v150, v150, v151, v153
	v_div_fixup_f32 v148, v150, v148, v149
	v_add_f32_e32 v131, v131, v148
	v_cmp_gt_f32_e32 vcc, s4, v131
	s_mov_b32 s4, 0x3f317217
	s_nop 0
	v_cndmask_b32_e64 v148, 0, 32, vcc
	v_ldexp_f32 v131, v131, v148
	v_log_f32_e32 v131, v131
	s_nop 0
	v_mul_f32_e32 v148, 0x3f317217, v131
	v_fma_f32 v148, v131, s4, -v148
	v_fmac_f32_e32 v148, 0x3377d1cf, v131
	s_mov_b32 s4, 0x7f800000
	v_fmac_f32_e32 v148, 0x3f317217, v131
	v_cmp_lt_f32_e64 s[12:13], |v131|, s4
	s_nop 1
	v_cndmask_b32_e64 v131, v131, v148, s[12:13]
	v_cndmask_b32_e32 v148, 0, v227, vcc
	v_sub_f32_e32 v131, v131, v148

; DEV u16 f2bf(float f) { return (u16)(pack2(f, 0.f) & 0xffffu); }
; DEV void phase_win(const Params& P, int l, const u16* __restrict__ xb, const u16* __restrict__ Wt, u16* __restrict__ h, char* smem) {
;     ...
;         for (int j = 0; j < 4; ++j) {
;           int row = m0 + wm * 128 + ms * 16 + quad * 4 + j;
;           int col = cb + ns * 16 + l15;
;           float v = acc[ms][ns][j];
;           if (mode == 1) { float lbv = lbp[col - C_HF]; v = __logf(lbv + (1.f - lbv) / (1.f + __expf(-v))); }
;           else if (mode == 2) v = v / (1.f + __expf(-v));
;           h[(size_t)row * HS + col] = f2bf(v);
.LBB0_1881:
	s_andn2_b64 vcc, exec, s[4:5]
	s_cbranch_vccnz .LBB0_1884
	s_cmp_eq_u32 s17, 1
	v_mov_b32_e32 v131, v67
	s_cbranch_scc0 .LBB0_1884
	v_lshl_add_u64 v[148:149], v[0:1], 2, s[14:15]
	v_add_co_u32_e32 v148, vcc, 0xfffff000, v148
	s_nop 1
	v_addc_co_u32_e32 v149, vcc, -1, v149, vcc
	v_mov_b32_e32 v131, v162
	v_mul_f32_e32 v148, 0xbfb8aa3b, v67
	v_exp_f32_e32 v148, v148
	v_sub_f32_e32 v149, 1.0, v131
	v_add_f32_e32 v148, 1.0, v148
	v_div_scale_f32 v150, s[4:5], v148, v148, v149
	v_rcp_f32_e32 v151, v150
	v_div_scale_f32 v152, vcc, v149, v148, v149
	s_mov_b32 s4, 0x800000
	v_fma_f32 v153, -v150, v151, 1.0
	v_fmac_f32_e32 v151, v153, v151
	v_mul_f32_e32 v153, v152, v151
	v_fma_f32 v154, -v150, v153, v152
	v_fmac_f32_e32 v153, v154, v151
	v_fma_f32 v150, -v150, v153, v152
	v_div_fmas_f32 v150, v150, v151, v153
	v_div_fixup_f32 v148, v150, v148, v149
	v_add_f32_e32 v131, v131, v148
	v_cmp_gt_f32_e32 vcc, s4, v131
	s_mov_b32 s4, 0x3f317217
	s_nop 0
	v_cndmask_b32_e64 v148, 0, 32, vcc
	v_ldexp_f32 v131, v131, v148
	v_log_f32_e32 v131, v131
	s_nop 0
	v_mul_f32_e32 v148, 0x3f317217, v131
	v_fma_f32 v148, v131, s4, -v148
	v_fmac_f32_e32 v148, 0x3377d1cf, v131
	s_mov_b32 s4, 0x7f800000
	v_fmac_f32_e32 v148, 0x3f317217, v131
	v_cmp_lt_f32_e64 s[12:13], |v131|, s4
	s_nop 1
	v_cndmask_b32_e64 v131, v131, v148, s[12:13]
	v_cndmask_b32_e32 v148, 0, v227, vcc
	v_sub_f32_e32 v131, v131, v148

; DEV u16 f2bf(float f) { return (u16)(pack2(f, 0.f) & 0xffffu); }
; DEV void phase_win(const Params& P, int l, const u16* __restrict__ xb, const u16* __restrict__ Wt, u16* __restrict__ h, char* smem) {
;     ...
;         for (int j = 0; j < 4; ++j) {
;           int row = m0 + wm * 128 + ms * 16 + quad * 4 + j;
;           int col = cb + ns * 16 + l15;
;           float v = acc[ms][ns][j];
;           if (mode == 1) { float lbv = lbp[col - C_HF]; v = __logf(lbv + (1.f - lbv) / (1.f + __expf(-v))); }
;           else if (mode == 2) v = v / (1.f + __expf(-v));
;           h[(size_t)row * HS + col] = f2bf(v);
.LBB0_1886:
	s_andn2_b64 vcc, exec, s[4:5]
	s_cbranch_vccnz .LBB0_1889
	s_cmp_eq_u32 s17, 1
	v_mov_b32_e32 v131, v68
	s_cbranch_scc0 .LBB0_1889
	v_lshl_add_u64 v[148:149], v[0:1], 2, s[14:15]
	v_add_co_u32_e32 v148, vcc, 0xfffff000, v148
	s_nop 1
	v_addc_co_u32_e32 v149, vcc, -1, v149, vcc
	v_mov_b32_e32 v131, v162
	v_mul_f32_e32 v148, 0xbfb8aa3b, v68
	v_exp_f32_e32 v148, v148
	v_sub_f32_e32 v149, 1.0, v131
	v_add_f32_e32 v148, 1.0, v148
	v_div_scale_f32 v150, s[4:5], v148, v148, v149
	v_rcp_f32_e32 v151, v150
	v_div_scale_f32 v152, vcc, v149, v148, v149
	s_mov_b32 s4, 0x800000
	v_fma_f32 v153, -v150, v151, 1.0
	v_fmac_f32_e32 v151, v153, v151
	v_mul_f32_e32 v153, v152, v151
	v_fma_f32 v154, -v150, v153, v152
	v_fmac_f32_e32 v153, v154, v151
	v_fma_f32 v150, -v150, v153, v152
	v_div_fmas_f32 v150, v150, v151, v153
	v_div_fixup_f32 v148, v150, v148, v149
	v_add_f32_e32 v131, v131, v148
	v_cmp_gt_f32_e32 vcc, s4, v131
	s_mov_b32 s4, 0x3f317217
	s_nop 0
	v_cndmask_b32_e64 v148, 0, 32, vcc
	v_ldexp_f32 v131, v131, v148
	v_log_f32_e32 v131, v131
	s_nop 0
	v_mul_f32_e32 v148, 0x3f317217, v131
	v_fma_f32 v148, v131, s4, -v148
	v_fmac_f32_e32 v148, 0x3377d1cf, v131
	s_mov_b32 s4, 0x7f800000
	v_fmac_f32_e32 v148, 0x3f317217, v131
	v_cmp_lt_f32_e64 s[12:13], |v131|, s4
	s_nop 1
	v_cndmask_b32_e64 v131, v131, v148, s[12:13]
	v_cndmask_b32_e32 v148, 0, v227, vcc
	v_sub_f32_e32 v131, v131, v148

; DEV u16 f2bf(float f) { return (u16)(pack2(f, 0.f) & 0xffffu); }
; DEV void phase_win(const Params& P, int l, const u16* __restrict__ xb, const u16* __restrict__ Wt, u16* __restrict__ h, char* smem) {
;     ...
;         for (int j = 0; j < 4; ++j) {
;           int row = m0 + wm * 128 + ms * 16 + quad * 4 + j;
;           int col = cb + ns * 16 + l15;
;           float v = acc[ms][ns][j];
;           if (mode == 1) { float lbv = lbp[col - C_HF]; v = __logf(lbv + (1.f - lbv) / (1.f + __expf(-v))); }
;           else if (mode == 2) v = v / (1.f + __expf(-v));
;           h[(size_t)row * HS + col] = f2bf(v);
.LBB0_1891:
	s_andn2_b64 vcc, exec, s[4:5]
	s_cbranch_vccnz .LBB0_1894
	s_cmp_eq_u32 s17, 1
	v_mov_b32_e32 v131, v69
	s_cbranch_scc0 .LBB0_1894
	v_lshl_add_u64 v[148:149], v[0:1], 2, s[14:15]
	v_add_co_u32_e32 v148, vcc, 0xfffff000, v148
	s_nop 1
	v_addc_co_u32_e32 v149, vcc, -1, v149, vcc
	v_mov_b32_e32 v131, v162
	v_mul_f32_e32 v148, 0xbfb8aa3b, v69
	v_exp_f32_e32 v148, v148
	v_sub_f32_e32 v149, 1.0, v131
	v_add_f32_e32 v148, 1.0, v148
	v_div_scale_f32 v150, s[4:5], v148, v148, v149
	v_rcp_f32_e32 v151, v150
	v_div_scale_f32 v152, vcc, v149, v148, v149
	s_mov_b32 s4, 0x800000
	v_fma_f32 v153, -v150, v151, 1.0
	v_fmac_f32_e32 v151, v153, v151
	v_mul_f32_e32 v153, v152, v151
	v_fma_f32 v154, -v150, v153, v152
	v_fmac_f32_e32 v153, v154, v151
	v_fma_f32 v150, -v150, v153, v152
	v_div_fmas_f32 v150, v150, v151, v153
	v_div_fixup_f32 v148, v150, v148, v149
	v_add_f32_e32 v131, v131, v148
	v_cmp_gt_f32_e32 vcc, s4, v131
	s_mov_b32 s4, 0x3f317217
	s_nop 0
	v_cndmask_b32_e64 v148, 0, 32, vcc
	v_ldexp_f32 v131, v131, v148
	v_log_f32_e32 v131, v131
	s_nop 0
	v_mul_f32_e32 v148, 0x3f317217, v131
	v_fma_f32 v148, v131, s4, -v148
	v_fmac_f32_e32 v148, 0x3377d1cf, v131
	s_mov_b32 s4, 0x7f800000
	v_fmac_f32_e32 v148, 0x3f317217, v131
	v_cmp_lt_f32_e64 s[12:13], |v131|, s4
	s_nop 1
	v_cndmask_b32_e64 v131, v131, v148, s[12:13]
	v_cndmask_b32_e32 v148, 0, v227, vcc
	v_sub_f32_e32 v131, v131, v148

; DEV u16 f2bf(float f) { return (u16)(pack2(f, 0.f) & 0xffffu); }
; DEV void phase_win(const Params& P, int l, const u16* __restrict__ xb, const u16* __restrict__ Wt, u16* __restrict__ h, char* smem) {
;     ...
;         for (int j = 0; j < 4; ++j) {
;           int row = m0 + wm * 128 + ms * 16 + quad * 4 + j;
;           int col = cb + ns * 16 + l15;
;           float v = acc[ms][ns][j];
;           if (mode == 1) { float lbv = lbp[col - C_HF]; v = __logf(lbv + (1.f - lbv) / (1.f + __expf(-v))); }
;           else if (mode == 2) v = v / (1.f + __expf(-v));
;           h[(size_t)row * HS + col] = f2bf(v);
.LBB0_1896:
	s_andn2_b64 vcc, exec, s[4:5]
	s_cbranch_vccnz .LBB0_1899
	s_cmp_eq_u32 s17, 1
	v_mov_b32_e32 v131, v58
	s_cbranch_scc0 .LBB0_1899
	v_lshl_add_u64 v[148:149], v[0:1], 2, s[14:15]
	v_add_co_u32_e32 v148, vcc, 0xfffff000, v148
	s_nop 1
	v_addc_co_u32_e32 v149, vcc, -1, v149, vcc
	v_mov_b32_e32 v131, v163
	v_mul_f32_e32 v148, 0xbfb8aa3b, v58
	v_exp_f32_e32 v148, v148
	v_sub_f32_e32 v149, 1.0, v131
	v_add_f32_e32 v148, 1.0, v148
	v_div_scale_f32 v150, s[4:5], v148, v148, v149
	v_rcp_f32_e32 v151, v150
	v_div_scale_f32 v152, vcc, v149, v148, v149
	s_mov_b32 s4, 0x800000
	v_fma_f32 v153, -v150, v151, 1.0
	v_fmac_f32_e32 v151, v153, v151
	v_mul_f32_e32 v153, v152, v151
	v_fma_f32 v154, -v150, v153, v152
	v_fmac_f32_e32 v153, v154, v151
	v_fma_f32 v150, -v150, v153, v152
	v_div_fmas_f32 v150, v150, v151, v153
	v_div_fixup_f32 v148, v150, v148, v149
	v_add_f32_e32 v131, v131, v148
	v_cmp_gt_f32_e32 vcc, s4, v131
	s_mov_b32 s4, 0x3f317217
	s_nop 0
	v_cndmask_b32_e64 v148, 0, 32, vcc
	v_ldexp_f32 v131, v131, v148
	v_log_f32_e32 v131, v131
	s_nop 0
	v_mul_f32_e32 v148, 0x3f317217, v131
	v_fma_f32 v148, v131, s4, -v148
	v_fmac_f32_e32 v148, 0x3377d1cf, v131
	s_mov_b32 s4, 0x7f800000
	v_fmac_f32_e32 v148, 0x3f317217, v131
	v_cmp_lt_f32_e64 s[12:13], |v131|, s4
	s_nop 1
	v_cndmask_b32_e64 v131, v131, v148, s[12:13]
	v_cndmask_b32_e32 v148, 0, v227, vcc
	v_sub_f32_e32 v131, v131, v148

; DEV u16 f2bf(float f) { return (u16)(pack2(f, 0.f) & 0xffffu); }
; DEV void phase_win(const Params& P, int l, const u16* __restrict__ xb, const u16* __restrict__ Wt, u16* __restrict__ h, char* smem) {
;     ...
;         for (int j = 0; j < 4; ++j) {
;           int row = m0 + wm * 128 + ms * 16 + quad * 4 + j;
;           int col = cb + ns * 16 + l15;
;           float v = acc[ms][ns][j];
;           if (mode == 1) { float lbv = lbp[col - C_HF]; v = __logf(lbv + (1.f - lbv) / (1.f + __expf(-v))); }
;           else if (mode == 2) v = v / (1.f + __expf(-v));
;           h[(size_t)row * HS + col] = f2bf(v);
.LBB0_1901:
	s_andn2_b64 vcc, exec, s[4:5]
	s_cbranch_vccnz .LBB0_1904
	s_cmp_eq_u32 s17, 1
	v_mov_b32_e32 v131, v59
	s_cbranch_scc0 .LBB0_1904
	v_lshl_add_u64 v[140:141], v[0:1], 2, s[14:15]
	v_add_co_u32_e32 v140, vcc, 0xfffff000, v140
	s_nop 1
	v_addc_co_u32_e32 v141, vcc, -1, v141, vcc
	v_mov_b32_e32 v131, v163
	v_mul_f32_e32 v140, 0xbfb8aa3b, v59
	v_exp_f32_e32 v140, v140
	v_sub_f32_e32 v141, 1.0, v131
	v_add_f32_e32 v140, 1.0, v140
	v_div_scale_f32 v148, s[4:5], v140, v140, v141
	v_rcp_f32_e32 v149, v148
	v_div_scale_f32 v150, vcc, v141, v140, v141
	s_mov_b32 s4, 0x800000
	v_fma_f32 v151, -v148, v149, 1.0
	v_fmac_f32_e32 v149, v151, v149
	v_mul_f32_e32 v151, v150, v149
	v_fma_f32 v152, -v148, v151, v150
	v_fmac_f32_e32 v151, v152, v149
	v_fma_f32 v148, -v148, v151, v150
	v_div_fmas_f32 v148, v148, v149, v151
	v_div_fixup_f32 v140, v148, v140, v141
	v_add_f32_e32 v131, v131, v140
	v_cmp_gt_f32_e32 vcc, s4, v131
	s_mov_b32 s4, 0x3f317217
	s_nop 0
	v_cndmask_b32_e64 v140, 0, 32, vcc
	v_ldexp_f32 v131, v131, v140
	v_log_f32_e32 v131, v131
	s_nop 0
	v_mul_f32_e32 v140, 0x3f317217, v131
	v_fma_f32 v140, v131, s4, -v140
	v_fmac_f32_e32 v140, 0x3377d1cf, v131
	s_mov_b32 s4, 0x7f800000
	v_fmac_f32_e32 v140, 0x3f317217, v131
	v_cmp_lt_f32_e64 s[12:13], |v131|, s4
	s_nop 1
	v_cndmask_b32_e64 v131, v131, v140, s[12:13]
	v_cndmask_b32_e32 v140, 0, v227, vcc
	v_sub_f32_e32 v131, v131, v140

; DEV u16 f2bf(float f) { return (u16)(pack2(f, 0.f) & 0xffffu); }
; DEV void phase_win(const Params& P, int l, const u16* __restrict__ xb, const u16* __restrict__ Wt, u16* __restrict__ h, char* smem) {
;     ...
;         for (int j = 0; j < 4; ++j) {
;           int row = m0 + wm * 128 + ms * 16 + quad * 4 + j;
;           int col = cb + ns * 16 + l15;
;           float v = acc[ms][ns][j];
;           if (mode == 1) { float lbv = lbp[col - C_HF]; v = __logf(lbv + (1.f - lbv) / (1.f + __expf(-v))); }
;           else if (mode == 2) v = v / (1.f + __expf(-v));
;           h[(size_t)row * HS + col] = f2bf(v);
.LBB0_1906:
	s_andn2_b64 vcc, exec, s[4:5]
	s_cbranch_vccnz .LBB0_1909
	s_cmp_eq_u32 s17, 1
	v_mov_b32_e32 v131, v60
	s_cbranch_scc0 .LBB0_1909
	v_lshl_add_u64 v[140:141], v[0:1], 2, s[14:15]
	v_add_co_u32_e32 v140, vcc, 0xfffff000, v140
	s_nop 1
	v_addc_co_u32_e32 v141, vcc, -1, v141, vcc
	v_mov_b32_e32 v131, v163
	v_mul_f32_e32 v140, 0xbfb8aa3b, v60
	v_exp_f32_e32 v140, v140
	v_sub_f32_e32 v141, 1.0, v131
	v_add_f32_e32 v140, 1.0, v140
	v_div_scale_f32 v142, s[4:5], v140, v140, v141
	v_rcp_f32_e32 v143, v142
	v_div_scale_f32 v148, vcc, v141, v140, v141
	s_mov_b32 s4, 0x800000
	v_fma_f32 v149, -v142, v143, 1.0
	v_fmac_f32_e32 v143, v149, v143
	v_mul_f32_e32 v149, v148, v143
	v_fma_f32 v150, -v142, v149, v148
	v_fmac_f32_e32 v149, v150, v143
	v_fma_f32 v142, -v142, v149, v148
	v_div_fmas_f32 v142, v142, v143, v149
	v_div_fixup_f32 v140, v142, v140, v141
	v_add_f32_e32 v131, v131, v140
	v_cmp_gt_f32_e32 vcc, s4, v131
	s_mov_b32 s4, 0x3f317217
	s_nop 0
	v_cndmask_b32_e64 v140, 0, 32, vcc
	v_ldexp_f32 v131, v131, v140
	v_log_f32_e32 v131, v131
	s_nop 0
	v_mul_f32_e32 v140, 0x3f317217, v131
	v_fma_f32 v140, v131, s4, -v140
	v_fmac_f32_e32 v140, 0x3377d1cf, v131
	s_mov_b32 s4, 0x7f800000
	v_fmac_f32_e32 v140, 0x3f317217, v131
	v_cmp_lt_f32_e64 s[12:13], |v131|, s4
	s_nop 1
	v_cndmask_b32_e64 v131, v131, v140, s[12:13]
	v_cndmask_b32_e32 v140, 0, v227, vcc
	v_sub_f32_e32 v131, v131, v140

; DEV u16 f2bf(float f) { return (u16)(pack2(f, 0.f) & 0xffffu); }
; DEV void phase_win(const Params& P, int l, const u16* __restrict__ xb, const u16* __restrict__ Wt, u16* __restrict__ h, char* smem) {
;     ...
;         for (int j = 0; j < 4; ++j) {
;           int row = m0 + wm * 128 + ms * 16 + quad * 4 + j;
;           int col = cb + ns * 16 + l15;
;           float v = acc[ms][ns][j];
;           if (mode == 1) { float lbv = lbp[col - C_HF]; v = __logf(lbv + (1.f - lbv) / (1.f + __expf(-v))); }
;           else if (mode == 2) v = v / (1.f + __expf(-v));
;           h[(size_t)row * HS + col] = f2bf(v);
.LBB0_1911:
	s_andn2_b64 vcc, exec, s[4:5]
	s_cbranch_vccnz .LBB0_1914
	s_cmp_eq_u32 s17, 1
	v_mov_b32_e32 v131, v61
	s_cbranch_scc0 .LBB0_1914
	v_lshl_add_u64 v[140:141], v[0:1], 2, s[14:15]
	v_add_co_u32_e32 v140, vcc, 0xfffff000, v140
	s_nop 1
	v_addc_co_u32_e32 v141, vcc, -1, v141, vcc
	v_mov_b32_e32 v131, v163
	v_mul_f32_e32 v140, 0xbfb8aa3b, v61
	v_exp_f32_e32 v140, v140
	v_sub_f32_e32 v141, 1.0, v131
	v_add_f32_e32 v140, 1.0, v140
	v_div_scale_f32 v142, s[4:5], v140, v140, v141
	v_rcp_f32_e32 v143, v142
	v_div_scale_f32 v144, vcc, v141, v140, v141
	s_mov_b32 s4, 0x800000
	v_fma_f32 v145, -v142, v143, 1.0
	v_fmac_f32_e32 v143, v145, v143
	v_mul_f32_e32 v145, v144, v143
	v_fma_f32 v148, -v142, v145, v144
	v_fmac_f32_e32 v145, v148, v143
	v_fma_f32 v142, -v142, v145, v144
	v_div_fmas_f32 v142, v142, v143, v145
	v_div_fixup_f32 v140, v142, v140, v141
	v_add_f32_e32 v131, v131, v140
	v_cmp_gt_f32_e32 vcc, s4, v131
	s_mov_b32 s4, 0x3f317217
	s_nop 0
	v_cndmask_b32_e64 v140, 0, 32, vcc
	v_ldexp_f32 v131, v131, v140
	v_log_f32_e32 v131, v131
	s_nop 0
	v_mul_f32_e32 v140, 0x3f317217, v131
	v_fma_f32 v140, v131, s4, -v140
	v_fmac_f32_e32 v140, 0x3377d1cf, v131
	s_mov_b32 s4, 0x7f800000
	v_fmac_f32_e32 v140, 0x3f317217, v131
	v_cmp_lt_f32_e64 s[12:13], |v131|, s4
	s_nop 1
	v_cndmask_b32_e64 v131, v131, v140, s[12:13]
	v_cndmask_b32_e32 v140, 0, v227, vcc
	v_sub_f32_e32 v131, v131, v140

; DEV u16 f2bf(float f) { return (u16)(pack2(f, 0.f) & 0xffffu); }
; DEV void phase_win(const Params& P, int l, const u16* __restrict__ xb, const u16* __restrict__ Wt, u16* __restrict__ h, char* smem) {
;     ...
;         for (int j = 0; j < 4; ++j) {
;           int row = m0 + wm * 128 + ms * 16 + quad * 4 + j;
;           int col = cb + ns * 16 + l15;
;           float v = acc[ms][ns][j];
;           if (mode == 1) { float lbv = lbp[col - C_HF]; v = __logf(lbv + (1.f - lbv) / (1.f + __expf(-v))); }
;           else if (mode == 2) v = v / (1.f + __expf(-v));
;           h[(size_t)row * HS + col] = f2bf(v);
.LBB0_1916:
	s_andn2_b64 vcc, exec, s[4:5]
	s_cbranch_vccnz .LBB0_1919
	s_cmp_eq_u32 s17, 1
	v_mov_b32_e32 v140, v6
	s_cbranch_scc0 .LBB0_1919
	v_lshl_add_u64 v[140:141], v[0:1], 2, s[14:15]
	v_add_co_u32_e32 v140, vcc, 0xfffff000, v140
	s_nop 1
	v_addc_co_u32_e32 v141, vcc, -1, v141, vcc
	v_mov_b32_e32 v131, v160
	v_mul_f32_e32 v140, 0xbfb8aa3b, v6
	v_exp_f32_e32 v140, v140
	v_sub_f32_e32 v141, 1.0, v131
	v_add_f32_e32 v140, 1.0, v140
	v_div_scale_f32 v142, s[4:5], v140, v140, v141
	v_rcp_f32_e32 v143, v142
	v_div_scale_f32 v144, vcc, v141, v140, v141
	s_mov_b32 s4, 0x800000
	v_fma_f32 v145, -v142, v143, 1.0
	v_fmac_f32_e32 v143, v145, v143
	v_mul_f32_e32 v145, v144, v143
	v_fma_f32 v146, -v142, v145, v144
	v_fmac_f32_e32 v145, v146, v143
	v_fma_f32 v142, -v142, v145, v144
	v_div_fmas_f32 v142, v142, v143, v145
	v_div_fixup_f32 v140, v142, v140, v141
	v_add_f32_e32 v131, v131, v140
	v_cmp_gt_f32_e32 vcc, s4, v131
	s_mov_b32 s4, 0x3f317217
	s_nop 0
	v_cndmask_b32_e64 v140, 0, 32, vcc
	v_ldexp_f32 v131, v131, v140
	v_log_f32_e32 v131, v131
	s_nop 0
	v_mul_f32_e32 v140, 0x3f317217, v131
	v_fma_f32 v140, v131, s4, -v140
	v_fmac_f32_e32 v140, 0x3377d1cf, v131
	s_mov_b32 s4, 0x7f800000
	v_fmac_f32_e32 v140, 0x3f317217, v131
	v_cmp_lt_f32_e64 s[12:13], |v131|, s4
	s_nop 1
	v_cndmask_b32_e64 v131, v131, v140, s[12:13]
	v_cndmask_b32_e32 v140, 0, v227, vcc
	v_sub_f32_e32 v140, v131, v140

; DEV u16 f2bf(float f) { return (u16)(pack2(f, 0.f) & 0xffffu); }
; DEV void phase_win(const Params& P, int l, const u16* __restrict__ xb, const u16* __restrict__ Wt, u16* __restrict__ h, char* smem) {
;     ...
;         for (int j = 0; j < 4; ++j) {
;           int row = m0 + wm * 128 + ms * 16 + quad * 4 + j;
;           int col = cb + ns * 16 + l15;
;           float v = acc[ms][ns][j];
;           if (mode == 1) { float lbv = lbp[col - C_HF]; v = __logf(lbv + (1.f - lbv) / (1.f + __expf(-v))); }
;           else if (mode == 2) v = v / (1.f + __expf(-v));
;           h[(size_t)row * HS + col] = f2bf(v);
.LBB0_1921:
	s_andn2_b64 vcc, exec, s[4:5]
	s_cbranch_vccnz .LBB0_1924
	s_cmp_eq_u32 s17, 1
	v_mov_b32_e32 v142, v7
	s_cbranch_scc0 .LBB0_1924
	v_lshl_add_u64 v[142:143], v[0:1], 2, s[14:15]
	v_add_co_u32_e32 v142, vcc, 0xfffff000, v142
	s_nop 1
	v_addc_co_u32_e32 v143, vcc, -1, v143, vcc
	v_mov_b32_e32 v142, v160
	v_mul_f32_e32 v143, 0xbfb8aa3b, v7
	v_exp_f32_e32 v143, v143
	v_sub_f32_e32 v144, 1.0, v142
	v_add_f32_e32 v143, 1.0, v143
	v_div_scale_f32 v145, s[4:5], v143, v143, v144
	v_rcp_f32_e32 v146, v145
	v_div_scale_f32 v147, vcc, v144, v143, v144
	s_mov_b32 s4, 0x800000
	v_fma_f32 v148, -v145, v146, 1.0
	v_fmac_f32_e32 v146, v148, v146
	v_mul_f32_e32 v148, v147, v146
	v_fma_f32 v149, -v145, v148, v147
	v_fmac_f32_e32 v148, v149, v146
	v_fma_f32 v145, -v145, v148, v147
	v_div_fmas_f32 v145, v145, v146, v148
	v_div_fixup_f32 v143, v145, v143, v144
	v_add_f32_e32 v142, v142, v143
	v_cmp_gt_f32_e32 vcc, s4, v142
	s_mov_b32 s4, 0x3f317217
	s_nop 0
	v_cndmask_b32_e64 v143, 0, 32, vcc
	v_ldexp_f32 v142, v142, v143
	v_log_f32_e32 v142, v142
	s_nop 0
	v_mul_f32_e32 v143, 0x3f317217, v142
	v_fma_f32 v143, v142, s4, -v143
	v_fmac_f32_e32 v143, 0x3377d1cf, v142
	s_mov_b32 s4, 0x7f800000
	v_fmac_f32_e32 v143, 0x3f317217, v142
	v_cmp_lt_f32_e64 s[12:13], |v142|, s4
	s_nop 1
	v_cndmask_b32_e64 v142, v142, v143, s[12:13]
	v_cndmask_b32_e32 v143, 0, v227, vcc
	v_sub_f32_e32 v142, v142, v143

; DEV u16 f2bf(float f) { return (u16)(pack2(f, 0.f) & 0xffffu); }
; DEV void phase_win(const Params& P, int l, const u16* __restrict__ xb, const u16* __restrict__ Wt, u16* __restrict__ h, char* smem) {
;     ...
;         for (int j = 0; j < 4; ++j) {
;           int row = m0 + wm * 128 + ms * 16 + quad * 4 + j;
;           int col = cb + ns * 16 + l15;
;           float v = acc[ms][ns][j];
;           if (mode == 1) { float lbv = lbp[col - C_HF]; v = __logf(lbv + (1.f - lbv) / (1.f + __expf(-v))); }
;           else if (mode == 2) v = v / (1.f + __expf(-v));
;           h[(size_t)row * HS + col] = f2bf(v);
.LBB0_1926:
	s_andn2_b64 vcc, exec, s[4:5]
	s_cbranch_vccnz .LBB0_1929
	s_cmp_eq_u32 s17, 1
	v_mov_b32_e32 v144, v8
	s_cbranch_scc0 .LBB0_1929
	v_lshl_add_u64 v[144:145], v[0:1], 2, s[14:15]
	v_add_co_u32_e32 v144, vcc, 0xfffff000, v144
	s_nop 1
	v_addc_co_u32_e32 v145, vcc, -1, v145, vcc
	v_mov_b32_e32 v144, v160
	v_mul_f32_e32 v145, 0xbfb8aa3b, v8
	v_exp_f32_e32 v145, v145
	v_sub_f32_e32 v146, 1.0, v144
	v_add_f32_e32 v145, 1.0, v145
	v_div_scale_f32 v147, s[4:5], v145, v145, v146
	v_rcp_f32_e32 v148, v147
	v_div_scale_f32 v149, vcc, v146, v145, v146
	s_mov_b32 s4, 0x800000
	v_fma_f32 v150, -v147, v148, 1.0
	v_fmac_f32_e32 v148, v150, v148
	v_mul_f32_e32 v150, v149, v148
	v_fma_f32 v151, -v147, v150, v149
	v_fmac_f32_e32 v150, v151, v148
	v_fma_f32 v147, -v147, v150, v149
	v_div_fmas_f32 v147, v147, v148, v150
	v_div_fixup_f32 v145, v147, v145, v146
	v_add_f32_e32 v144, v144, v145
	v_cmp_gt_f32_e32 vcc, s4, v144
	s_mov_b32 s4, 0x3f317217
	s_nop 0
	v_cndmask_b32_e64 v145, 0, 32, vcc
	v_ldexp_f32 v144, v144, v145
	v_log_f32_e32 v144, v144
	s_nop 0
	v_mul_f32_e32 v145, 0x3f317217, v144
	v_fma_f32 v145, v144, s4, -v145
	v_fmac_f32_e32 v145, 0x3377d1cf, v144
	s_mov_b32 s4, 0x7f800000
	v_fmac_f32_e32 v145, 0x3f317217, v144
	v_cmp_lt_f32_e64 s[12:13], |v144|, s4
	s_nop 1
	v_cndmask_b32_e64 v144, v144, v145, s[12:13]
	v_cndmask_b32_e32 v145, 0, v227, vcc
	v_sub_f32_e32 v144, v144, v145

; DEV u16 f2bf(float f) { return (u16)(pack2(f, 0.f) & 0xffffu); }
; DEV void phase_win(const Params& P, int l, const u16* __restrict__ xb, const u16* __restrict__ Wt, u16* __restrict__ h, char* smem) {
;     ...
;         for (int j = 0; j < 4; ++j) {
;           int row = m0 + wm * 128 + ms * 16 + quad * 4 + j;
;           int col = cb + ns * 16 + l15;
;           float v = acc[ms][ns][j];
;           if (mode == 1) { float lbv = lbp[col - C_HF]; v = __logf(lbv + (1.f - lbv) / (1.f + __expf(-v))); }
;           else if (mode == 2) v = v / (1.f + __expf(-v));
;           h[(size_t)row * HS + col] = f2bf(v);
.LBB0_1931:
	s_andn2_b64 vcc, exec, s[4:5]
	s_cbranch_vccnz .LBB0_1934
	s_cmp_eq_u32 s17, 1
	v_mov_b32_e32 v146, v9
	s_cbranch_scc0 .LBB0_1934
	v_lshl_add_u64 v[146:147], v[0:1], 2, s[14:15]
	v_add_co_u32_e32 v146, vcc, 0xfffff000, v146
	s_nop 1
	v_addc_co_u32_e32 v147, vcc, -1, v147, vcc
	v_mov_b32_e32 v146, v160
	v_mul_f32_e32 v147, 0xbfb8aa3b, v9
	v_exp_f32_e32 v147, v147
	v_sub_f32_e32 v148, 1.0, v146
	v_add_f32_e32 v147, 1.0, v147
	v_div_scale_f32 v149, s[4:5], v147, v147, v148
	v_rcp_f32_e32 v150, v149
	v_div_scale_f32 v151, vcc, v148, v147, v148
	s_mov_b32 s4, 0x800000
	v_fma_f32 v152, -v149, v150, 1.0
	v_fmac_f32_e32 v150, v152, v150
	v_mul_f32_e32 v152, v151, v150
	v_fma_f32 v153, -v149, v152, v151
	v_fmac_f32_e32 v152, v153, v150
	v_fma_f32 v149, -v149, v152, v151
	v_div_fmas_f32 v149, v149, v150, v152
	v_div_fixup_f32 v147, v149, v147, v148
	v_add_f32_e32 v146, v146, v147
	v_cmp_gt_f32_e32 vcc, s4, v146
	s_mov_b32 s4, 0x3f317217
	s_nop 0
	v_cndmask_b32_e64 v147, 0, 32, vcc
	v_ldexp_f32 v146, v146, v147
	v_log_f32_e32 v146, v146
	s_nop 0
	v_mul_f32_e32 v147, 0x3f317217, v146
	v_fma_f32 v147, v146, s4, -v147
	v_fmac_f32_e32 v147, 0x3377d1cf, v146
	s_mov_b32 s4, 0x7f800000
	v_fmac_f32_e32 v147, 0x3f317217, v146
	v_cmp_lt_f32_e64 s[12:13], |v146|, s4
	s_nop 1
	v_cndmask_b32_e64 v146, v146, v147, s[12:13]
	v_cndmask_b32_e32 v147, 0, v227, vcc
	v_sub_f32_e32 v146, v146, v147

; DEV u16 f2bf(float f) { return (u16)(pack2(f, 0.f) & 0xffffu); }
; DEV void phase_win(const Params& P, int l, const u16* __restrict__ xb, const u16* __restrict__ Wt, u16* __restrict__ h, char* smem) {
;     ...
;         for (int j = 0; j < 4; ++j) {
;           int row = m0 + wm * 128 + ms * 16 + quad * 4 + j;
;           int col = cb + ns * 16 + l15;
;           float v = acc[ms][ns][j];
;           if (mode == 1) { float lbv = lbp[col - C_HF]; v = __logf(lbv + (1.f - lbv) / (1.f + __expf(-v))); }
;           else if (mode == 2) v = v / (1.f + __expf(-v));
;           h[(size_t)row * HS + col] = f2bf(v);
.LBB0_1936:
	s_andn2_b64 vcc, exec, s[4:5]
	s_cbranch_vccnz .LBB0_1939
	s_cmp_eq_u32 s17, 1
	v_mov_b32_e32 v131, v50
	s_cbranch_scc0 .LBB0_1939
	v_lshl_add_u64 v[148:149], v[0:1], 2, s[14:15]
	v_add_co_u32_e32 v148, vcc, 0xfffff000, v148
	s_nop 1
	v_addc_co_u32_e32 v149, vcc, -1, v149, vcc
	v_mov_b32_e32 v131, v161
	v_mul_f32_e32 v148, 0xbfb8aa3b, v50
	v_exp_f32_e32 v148, v148
	v_sub_f32_e32 v149, 1.0, v131
	v_add_f32_e32 v148, 1.0, v148
	v_div_scale_f32 v150, s[4:5], v148, v148, v149
	v_rcp_f32_e32 v151, v150
	v_div_scale_f32 v152, vcc, v149, v148, v149
	s_mov_b32 s4, 0x800000
	v_fma_f32 v153, -v150, v151, 1.0
	v_fmac_f32_e32 v151, v153, v151
	v_mul_f32_e32 v153, v152, v151
	v_fma_f32 v154, -v150, v153, v152
	v_fmac_f32_e32 v153, v154, v151
	v_fma_f32 v150, -v150, v153, v152
	v_div_fmas_f32 v150, v150, v151, v153
	v_div_fixup_f32 v148, v150, v148, v149
	v_add_f32_e32 v131, v131, v148
	v_cmp_gt_f32_e32 vcc, s4, v131
	s_mov_b32 s4, 0x3f317217
	s_nop 0
	v_cndmask_b32_e64 v148, 0, 32, vcc
	v_ldexp_f32 v131, v131, v148
	v_log_f32_e32 v131, v131
	s_nop 0
	v_mul_f32_e32 v148, 0x3f317217, v131
	v_fma_f32 v148, v131, s4, -v148
	v_fmac_f32_e32 v148, 0x3377d1cf, v131
	s_mov_b32 s4, 0x7f800000
	v_fmac_f32_e32 v148, 0x3f317217, v131
	v_cmp_lt_f32_e64 s[12:13], |v131|, s4
	s_nop 1
	v_cndmask_b32_e64 v131, v131, v148, s[12:13]
	v_cndmask_b32_e32 v148, 0, v227, vcc
	v_sub_f32_e32 v131, v131, v148

; DEV u16 f2bf(float f) { return (u16)(pack2(f, 0.f) & 0xffffu); }
; DEV void phase_win(const Params& P, int l, const u16* __restrict__ xb, const u16* __restrict__ Wt, u16* __restrict__ h, char* smem) {
;     ...
;         for (int j = 0; j < 4; ++j) {
;           int row = m0 + wm * 128 + ms * 16 + quad * 4 + j;
;           int col = cb + ns * 16 + l15;
;           float v = acc[ms][ns][j];
;           if (mode == 1) { float lbv = lbp[col - C_HF]; v = __logf(lbv + (1.f - lbv) / (1.f + __expf(-v))); }
;           else if (mode == 2) v = v / (1.f + __expf(-v));
;           h[(size_t)row * HS + col] = f2bf(v);
.LBB0_1941:
	s_andn2_b64 vcc, exec, s[4:5]
	s_cbranch_vccnz .LBB0_1944
	s_cmp_eq_u32 s17, 1
	v_mov_b32_e32 v131, v51
	s_cbranch_scc0 .LBB0_1944
	v_lshl_add_u64 v[148:149], v[0:1], 2, s[14:15]
	v_add_co_u32_e32 v148, vcc, 0xfffff000, v148
	s_nop 1
	v_addc_co_u32_e32 v149, vcc, -1, v149, vcc
	v_mov_b32_e32 v131, v161
	v_mul_f32_e32 v148, 0xbfb8aa3b, v51
	v_exp_f32_e32 v148, v148
	v_sub_f32_e32 v149, 1.0, v131
	v_add_f32_e32 v148, 1.0, v148
	v_div_scale_f32 v150, s[4:5], v148, v148, v149
	v_rcp_f32_e32 v151, v150
	v_div_scale_f32 v152, vcc, v149, v148, v149
	s_mov_b32 s4, 0x800000
	v_fma_f32 v153, -v150, v151, 1.0
	v_fmac_f32_e32 v151, v153, v151
	v_mul_f32_e32 v153, v152, v151
	v_fma_f32 v154, -v150, v153, v152
	v_fmac_f32_e32 v153, v154, v151
	v_fma_f32 v150, -v150, v153, v152
	v_div_fmas_f32 v150, v150, v151, v153
	v_div_fixup_f32 v148, v150, v148, v149
	v_add_f32_e32 v131, v131, v148
	v_cmp_gt_f32_e32 vcc, s4, v131
	s_mov_b32 s4, 0x3f317217
	s_nop 0
	v_cndmask_b32_e64 v148, 0, 32, vcc
	v_ldexp_f32 v131, v131, v148
	v_log_f32_e32 v131, v131
	s_nop 0
	v_mul_f32_e32 v148, 0x3f317217, v131
	v_fma_f32 v148, v131, s4, -v148
	v_fmac_f32_e32 v148, 0x3377d1cf, v131
	s_mov_b32 s4, 0x7f800000
	v_fmac_f32_e32 v148, 0x3f317217, v131
	v_cmp_lt_f32_e64 s[12:13], |v131|, s4
	s_nop 1
	v_cndmask_b32_e64 v131, v131, v148, s[12:13]
	v_cndmask_b32_e32 v148, 0, v227, vcc
	v_sub_f32_e32 v131, v131, v148

; DEV u16 f2bf(float f) { return (u16)(pack2(f, 0.f) & 0xffffu); }
; DEV void phase_win(const Params& P, int l, const u16* __restrict__ xb, const u16* __restrict__ Wt, u16* __restrict__ h, char* smem) {
;     ...
;         for (int j = 0; j < 4; ++j) {
;           int row = m0 + wm * 128 + ms * 16 + quad * 4 + j;
;           int col = cb + ns * 16 + l15;
;           float v = acc[ms][ns][j];
;           if (mode == 1) { float lbv = lbp[col - C_HF]; v = __logf(lbv + (1.f - lbv) / (1.f + __expf(-v))); }
;           else if (mode == 2) v = v / (1.f + __expf(-v));
;           h[(size_t)row * HS + col] = f2bf(v);
.LBB0_1946:
	s_andn2_b64 vcc, exec, s[4:5]
	s_cbranch_vccnz .LBB0_1949
	s_cmp_eq_u32 s17, 1
	v_mov_b32_e32 v131, v52
	s_cbranch_scc0 .LBB0_1949
	v_lshl_add_u64 v[148:149], v[0:1], 2, s[14:15]
	v_add_co_u32_e32 v148, vcc, 0xfffff000, v148
	s_nop 1
	v_addc_co_u32_e32 v149, vcc, -1, v149, vcc
	v_mov_b32_e32 v131, v161
	v_mul_f32_e32 v148, 0xbfb8aa3b, v52
	v_exp_f32_e32 v148, v148
	v_sub_f32_e32 v149, 1.0, v131
	v_add_f32_e32 v148, 1.0, v148
	v_div_scale_f32 v150, s[4:5], v148, v148, v149
	v_rcp_f32_e32 v151, v150
	v_div_scale_f32 v152, vcc, v149, v148, v149
	s_mov_b32 s4, 0x800000
	v_fma_f32 v153, -v150, v151, 1.0
	v_fmac_f32_e32 v151, v153, v151
	v_mul_f32_e32 v153, v152, v151
	v_fma_f32 v154, -v150, v153, v152
	v_fmac_f32_e32 v153, v154, v151
	v_fma_f32 v150, -v150, v153, v152
	v_div_fmas_f32 v150, v150, v151, v153
	v_div_fixup_f32 v148, v150, v148, v149
	v_add_f32_e32 v131, v131, v148
	v_cmp_gt_f32_e32 vcc, s4, v131
	s_mov_b32 s4, 0x3f317217
	s_nop 0
	v_cndmask_b32_e64 v148, 0, 32, vcc
	v_ldexp_f32 v131, v131, v148
	v_log_f32_e32 v131, v131
	s_nop 0
	v_mul_f32_e32 v148, 0x3f317217, v131
	v_fma_f32 v148, v131, s4, -v148
	v_fmac_f32_e32 v148, 0x3377d1cf, v131
	s_mov_b32 s4, 0x7f800000
	v_fmac_f32_e32 v148, 0x3f317217, v131
	v_cmp_lt_f32_e64 s[12:13], |v131|, s4
	s_nop 1
	v_cndmask_b32_e64 v131, v131, v148, s[12:13]
	v_cndmask_b32_e32 v148, 0, v227, vcc
	v_sub_f32_e32 v131, v131, v148

; DEV u16 f2bf(float f) { return (u16)(pack2(f, 0.f) & 0xffffu); }
; DEV void phase_win(const Params& P, int l, const u16* __restrict__ xb, const u16* __restrict__ Wt, u16* __restrict__ h, char* smem) {
;     ...
;         for (int j = 0; j < 4; ++j) {
;           int row = m0 + wm * 128 + ms * 16 + quad * 4 + j;
;           int col = cb + ns * 16 + l15;
;           float v = acc[ms][ns][j];
;           if (mode == 1) { float lbv = lbp[col - C_HF]; v = __logf(lbv + (1.f - lbv) / (1.f + __expf(-v))); }
;           else if (mode == 2) v = v / (1.f + __expf(-v));
;           h[(size_t)row * HS + col] = f2bf(v);
.LBB0_1951:
	s_andn2_b64 vcc, exec, s[4:5]
	s_cbranch_vccnz .LBB0_1954
	s_cmp_eq_u32 s17, 1
	v_mov_b32_e32 v131, v53
	s_cbranch_scc0 .LBB0_1954
	v_lshl_add_u64 v[148:149], v[0:1], 2, s[14:15]
	v_add_co_u32_e32 v148, vcc, 0xfffff000, v148
	s_nop 1
	v_addc_co_u32_e32 v149, vcc, -1, v149, vcc
	v_mov_b32_e32 v131, v161
	v_mul_f32_e32 v148, 0xbfb8aa3b, v53
	v_exp_f32_e32 v148, v148
	v_sub_f32_e32 v149, 1.0, v131
	v_add_f32_e32 v148, 1.0, v148
	v_div_scale_f32 v150, s[4:5], v148, v148, v149
	v_rcp_f32_e32 v151, v150
	v_div_scale_f32 v152, vcc, v149, v148, v149
	s_mov_b32 s4, 0x800000
	v_fma_f32 v153, -v150, v151, 1.0
	v_fmac_f32_e32 v151, v153, v151
	v_mul_f32_e32 v153, v152, v151
	v_fma_f32 v154, -v150, v153, v152
	v_fmac_f32_e32 v153, v154, v151
	v_fma_f32 v150, -v150, v153, v152
	v_div_fmas_f32 v150, v150, v151, v153
	v_div_fixup_f32 v148, v150, v148, v149
	v_add_f32_e32 v131, v131, v148
	v_cmp_gt_f32_e32 vcc, s4, v131
	s_mov_b32 s4, 0x3f317217
	s_nop 0
	v_cndmask_b32_e64 v148, 0, 32, vcc
	v_ldexp_f32 v131, v131, v148
	v_log_f32_e32 v131, v131
	s_nop 0
	v_mul_f32_e32 v148, 0x3f317217, v131
	v_fma_f32 v148, v131, s4, -v148
	v_fmac_f32_e32 v148, 0x3377d1cf, v131
	s_mov_b32 s4, 0x7f800000
	v_fmac_f32_e32 v148, 0x3f317217, v131
	v_cmp_lt_f32_e64 s[12:13], |v131|, s4
	s_nop 1
	v_cndmask_b32_e64 v131, v131, v148, s[12:13]
	v_cndmask_b32_e32 v148, 0, v227, vcc
	v_sub_f32_e32 v131, v131, v148

; DEV u16 f2bf(float f) { return (u16)(pack2(f, 0.f) & 0xffffu); }
; DEV void phase_win(const Params& P, int l, const u16* __restrict__ xb, const u16* __restrict__ Wt, u16* __restrict__ h, char* smem) {
;     ...
;         for (int j = 0; j < 4; ++j) {
;           int row = m0 + wm * 128 + ms * 16 + quad * 4 + j;
;           int col = cb + ns * 16 + l15;
;           float v = acc[ms][ns][j];
;           if (mode == 1) { float lbv = lbp[col - C_HF]; v = __logf(lbv + (1.f - lbv) / (1.f + __expf(-v))); }
;           else if (mode == 2) v = v / (1.f + __expf(-v));
;           h[(size_t)row * HS + col] = f2bf(v);
.LBB0_1956:
	s_andn2_b64 vcc, exec, s[4:5]
	s_cbranch_vccnz .LBB0_1959
	s_cmp_eq_u32 s17, 1
	v_mov_b32_e32 v131, v54
	s_cbranch_scc0 .LBB0_1959
	v_lshl_add_u64 v[148:149], v[0:1], 2, s[14:15]
	v_add_co_u32_e32 v148, vcc, 0xfffff000, v148
	s_nop 1
	v_addc_co_u32_e32 v149, vcc, -1, v149, vcc
	v_mov_b32_e32 v131, v162
	v_mul_f32_e32 v148, 0xbfb8aa3b, v54
	v_exp_f32_e32 v148, v148
	v_sub_f32_e32 v149, 1.0, v131
	v_add_f32_e32 v148, 1.0, v148
	v_div_scale_f32 v150, s[4:5], v148, v148, v149
	v_rcp_f32_e32 v151, v150
	v_div_scale_f32 v152, vcc, v149, v148, v149
	s_mov_b32 s4, 0x800000
	v_fma_f32 v153, -v150, v151, 1.0
	v_fmac_f32_e32 v151, v153, v151
	v_mul_f32_e32 v153, v152, v151
	v_fma_f32 v154, -v150, v153, v152
	v_fmac_f32_e32 v153, v154, v151
	v_fma_f32 v150, -v150, v153, v152
	v_div_fmas_f32 v150, v150, v151, v153
	v_div_fixup_f32 v148, v150, v148, v149
	v_add_f32_e32 v131, v131, v148
	v_cmp_gt_f32_e32 vcc, s4, v131
	s_mov_b32 s4, 0x3f317217
	s_nop 0
	v_cndmask_b32_e64 v148, 0, 32, vcc
	v_ldexp_f32 v131, v131, v148
	v_log_f32_e32 v131, v131
	s_nop 0
	v_mul_f32_e32 v148, 0x3f317217, v131
	v_fma_f32 v148, v131, s4, -v148
	v_fmac_f32_e32 v148, 0x3377d1cf, v131
	s_mov_b32 s4, 0x7f800000
	v_fmac_f32_e32 v148, 0x3f317217, v131
	v_cmp_lt_f32_e64 s[12:13], |v131|, s4
	s_nop 1
	v_cndmask_b32_e64 v131, v131, v148, s[12:13]
	v_cndmask_b32_e32 v148, 0, v227, vcc
	v_sub_f32_e32 v131, v131, v148

; DEV u16 f2bf(float f) { return (u16)(pack2(f, 0.f) & 0xffffu); }
; DEV void phase_win(const Params& P, int l, const u16* __restrict__ xb, const u16* __restrict__ Wt, u16* __restrict__ h, char* smem) {
;     ...
;         for (int j = 0; j < 4; ++j) {
;           int row = m0 + wm * 128 + ms * 16 + quad * 4 + j;
;           int col = cb + ns * 16 + l15;
;           float v = acc[ms][ns][j];
;           if (mode == 1) { float lbv = lbp[col - C_HF]; v = __logf(lbv + (1.f - lbv) / (1.f + __expf(-v))); }
;           else if (mode == 2) v = v / (1.f + __expf(-v));
;           h[(size_t)row * HS + col] = f2bf(v);
.LBB0_1961:
	s_andn2_b64 vcc, exec, s[4:5]
	s_cbranch_vccnz .LBB0_1964
	s_cmp_eq_u32 s17, 1
	v_mov_b32_e32 v131, v55
	s_cbranch_scc0 .LBB0_1964
	v_lshl_add_u64 v[148:149], v[0:1], 2, s[14:15]
	v_add_co_u32_e32 v148, vcc, 0xfffff000, v148
	s_nop 1
	v_addc_co_u32_e32 v149, vcc, -1, v149, vcc
	v_mov_b32_e32 v131, v162
	v_mul_f32_e32 v148, 0xbfb8aa3b, v55
	v_exp_f32_e32 v148, v148
	v_sub_f32_e32 v149, 1.0, v131
	v_add_f32_e32 v148, 1.0, v148
	v_div_scale_f32 v150, s[4:5], v148, v148, v149
	v_rcp_f32_e32 v151, v150
	v_div_scale_f32 v152, vcc, v149, v148, v149
	s_mov_b32 s4, 0x800000
	v_fma_f32 v153, -v150, v151, 1.0
	v_fmac_f32_e32 v151, v153, v151
	v_mul_f32_e32 v153, v152, v151
	v_fma_f32 v154, -v150, v153, v152
	v_fmac_f32_e32 v153, v154, v151
	v_fma_f32 v150, -v150, v153, v152
	v_div_fmas_f32 v150, v150, v151, v153
	v_div_fixup_f32 v148, v150, v148, v149
	v_add_f32_e32 v131, v131, v148
	v_cmp_gt_f32_e32 vcc, s4, v131
	s_mov_b32 s4, 0x3f317217
	s_nop 0
	v_cndmask_b32_e64 v148, 0, 32, vcc
	v_ldexp_f32 v131, v131, v148
	v_log_f32_e32 v131, v131
	s_nop 0
	v_mul_f32_e32 v148, 0x3f317217, v131
	v_fma_f32 v148, v131, s4, -v148
	v_fmac_f32_e32 v148, 0x3377d1cf, v131
	s_mov_b32 s4, 0x7f800000
	v_fmac_f32_e32 v148, 0x3f317217, v131
	v_cmp_lt_f32_e64 s[12:13], |v131|, s4
	s_nop 1
	v_cndmask_b32_e64 v131, v131, v148, s[12:13]
	v_cndmask_b32_e32 v148, 0, v227, vcc
	v_sub_f32_e32 v131, v131, v148

; DEV u16 f2bf(float f) { return (u16)(pack2(f, 0.f) & 0xffffu); }
; DEV void phase_win(const Params& P, int l, const u16* __restrict__ xb, const u16* __restrict__ Wt, u16* __restrict__ h, char* smem) {
;     ...
;         for (int j = 0; j < 4; ++j) {
;           int row = m0 + wm * 128 + ms * 16 + quad * 4 + j;
;           int col = cb + ns * 16 + l15;
;           float v = acc[ms][ns][j];
;           if (mode == 1) { float lbv = lbp[col - C_HF]; v = __logf(lbv + (1.f - lbv) / (1.f + __expf(-v))); }
;           else if (mode == 2) v = v / (1.f + __expf(-v));
;           h[(size_t)row * HS + col] = f2bf(v);
.LBB0_1966:
	s_andn2_b64 vcc, exec, s[4:5]
	s_cbranch_vccnz .LBB0_1969
	s_cmp_eq_u32 s17, 1
	v_mov_b32_e32 v131, v56
	s_cbranch_scc0 .LBB0_1969
	v_lshl_add_u64 v[148:149], v[0:1], 2, s[14:15]
	v_add_co_u32_e32 v148, vcc, 0xfffff000, v148
	s_nop 1
	v_addc_co_u32_e32 v149, vcc, -1, v149, vcc
	v_mov_b32_e32 v131, v162
	v_mul_f32_e32 v148, 0xbfb8aa3b, v56
	v_exp_f32_e32 v148, v148
	v_sub_f32_e32 v149, 1.0, v131
	v_add_f32_e32 v148, 1.0, v148
	v_div_scale_f32 v150, s[4:5], v148, v148, v149
	v_rcp_f32_e32 v151, v150
	v_div_scale_f32 v152, vcc, v149, v148, v149
	s_mov_b32 s4, 0x800000
	v_fma_f32 v153, -v150, v151, 1.0
	v_fmac_f32_e32 v151, v153, v151
	v_mul_f32_e32 v153, v152, v151
	v_fma_f32 v154, -v150, v153, v152
	v_fmac_f32_e32 v153, v154, v151
	v_fma_f32 v150, -v150, v153, v152
	v_div_fmas_f32 v150, v150, v151, v153
	v_div_fixup_f32 v148, v150, v148, v149
	v_add_f32_e32 v131, v131, v148
	v_cmp_gt_f32_e32 vcc, s4, v131
	s_mov_b32 s4, 0x3f317217
	s_nop 0
	v_cndmask_b32_e64 v148, 0, 32, vcc
	v_ldexp_f32 v131, v131, v148
	v_log_f32_e32 v131, v131
	s_nop 0
	v_mul_f32_e32 v148, 0x3f317217, v131
	v_fma_f32 v148, v131, s4, -v148
	v_fmac_f32_e32 v148, 0x3377d1cf, v131
	s_mov_b32 s4, 0x7f800000
	v_fmac_f32_e32 v148, 0x3f317217, v131
	v_cmp_lt_f32_e64 s[12:13], |v131|, s4
	s_nop 1
	v_cndmask_b32_e64 v131, v131, v148, s[12:13]
	v_cndmask_b32_e32 v148, 0, v227, vcc
	v_sub_f32_e32 v131, v131, v148

; DEV u16 f2bf(float f) { return (u16)(pack2(f, 0.f) & 0xffffu); }
; DEV void phase_win(const Params& P, int l, const u16* __restrict__ xb, const u16* __restrict__ Wt, u16* __restrict__ h, char* smem) {
;     ...
;         for (int j = 0; j < 4; ++j) {
;           int row = m0 + wm * 128 + ms * 16 + quad * 4 + j;
;           int col = cb + ns * 16 + l15;
;           float v = acc[ms][ns][j];
;           if (mode == 1) { float lbv = lbp[col - C_HF]; v = __logf(lbv + (1.f - lbv) / (1.f + __expf(-v))); }
;           else if (mode == 2) v = v / (1.f + __expf(-v));
;           h[(size_t)row * HS + col] = f2bf(v);
.LBB0_1971:
	s_andn2_b64 vcc, exec, s[4:5]
	s_cbranch_vccnz .LBB0_1974
	s_cmp_eq_u32 s17, 1
	v_mov_b32_e32 v131, v57
	s_cbranch_scc0 .LBB0_1974
	v_lshl_add_u64 v[148:149], v[0:1], 2, s[14:15]
	v_add_co_u32_e32 v148, vcc, 0xfffff000, v148
	s_nop 1
	v_addc_co_u32_e32 v149, vcc, -1, v149, vcc
	v_mov_b32_e32 v131, v162
	v_mul_f32_e32 v148, 0xbfb8aa3b, v57
	v_exp_f32_e32 v148, v148
	v_sub_f32_e32 v149, 1.0, v131
	v_add_f32_e32 v148, 1.0, v148
	v_div_scale_f32 v150, s[4:5], v148, v148, v149
	v_rcp_f32_e32 v151, v150
	v_div_scale_f32 v152, vcc, v149, v148, v149
	s_mov_b32 s4, 0x800000
	v_fma_f32 v153, -v150, v151, 1.0
	v_fmac_f32_e32 v151, v153, v151
	v_mul_f32_e32 v153, v152, v151
	v_fma_f32 v154, -v150, v153, v152
	v_fmac_f32_e32 v153, v154, v151
	v_fma_f32 v150, -v150, v153, v152
	v_div_fmas_f32 v150, v150, v151, v153
	v_div_fixup_f32 v148, v150, v148, v149
	v_add_f32_e32 v131, v131, v148
	v_cmp_gt_f32_e32 vcc, s4, v131
	s_mov_b32 s4, 0x3f317217
	s_nop 0
	v_cndmask_b32_e64 v148, 0, 32, vcc
	v_ldexp_f32 v131, v131, v148
	v_log_f32_e32 v131, v131
	s_nop 0
	v_mul_f32_e32 v148, 0x3f317217, v131
	v_fma_f32 v148, v131, s4, -v148
	v_fmac_f32_e32 v148, 0x3377d1cf, v131
	s_mov_b32 s4, 0x7f800000
	v_fmac_f32_e32 v148, 0x3f317217, v131
	v_cmp_lt_f32_e64 s[12:13], |v131|, s4
	s_nop 1
	v_cndmask_b32_e64 v131, v131, v148, s[12:13]
	v_cndmask_b32_e32 v148, 0, v227, vcc
	v_sub_f32_e32 v131, v131, v148

; DEV u16 f2bf(float f) { return (u16)(pack2(f, 0.f) & 0xffffu); }
; DEV void phase_win(const Params& P, int l, const u16* __restrict__ xb, const u16* __restrict__ Wt, u16* __restrict__ h, char* smem) {
;     ...
;         for (int j = 0; j < 4; ++j) {
;           int row = m0 + wm * 128 + ms * 16 + quad * 4 + j;
;           int col = cb + ns * 16 + l15;
;           float v = acc[ms][ns][j];
;           if (mode == 1) { float lbv = lbp[col - C_HF]; v = __logf(lbv + (1.f - lbv) / (1.f + __expf(-v))); }
;           else if (mode == 2) v = v / (1.f + __expf(-v));
;           h[(size_t)row * HS + col] = f2bf(v);
.LBB0_1976:
	s_andn2_b64 vcc, exec, s[4:5]
	s_cbranch_vccnz .LBB0_1979
	s_cmp_eq_u32 s17, 1
	v_mov_b32_e32 v131, v46
	s_cbranch_scc0 .LBB0_1979
	v_lshl_add_u64 v[148:149], v[0:1], 2, s[14:15]
	v_add_co_u32_e32 v148, vcc, 0xfffff000, v148
	s_nop 1
	v_addc_co_u32_e32 v149, vcc, -1, v149, vcc
	v_mov_b32_e32 v131, v163
	v_mul_f32_e32 v148, 0xbfb8aa3b, v46
	v_exp_f32_e32 v148, v148
	v_sub_f32_e32 v149, 1.0, v131
	v_add_f32_e32 v148, 1.0, v148
	v_div_scale_f32 v150, s[4:5], v148, v148, v149
	v_rcp_f32_e32 v151, v150
	v_div_scale_f32 v152, vcc, v149, v148, v149
	s_mov_b32 s4, 0x800000
	v_fma_f32 v153, -v150, v151, 1.0
	v_fmac_f32_e32 v151, v153, v151
	v_mul_f32_e32 v153, v152, v151
	v_fma_f32 v154, -v150, v153, v152
	v_fmac_f32_e32 v153, v154, v151
	v_fma_f32 v150, -v150, v153, v152
	v_div_fmas_f32 v150, v150, v151, v153
	v_div_fixup_f32 v148, v150, v148, v149
	v_add_f32_e32 v131, v131, v148
	v_cmp_gt_f32_e32 vcc, s4, v131
	s_mov_b32 s4, 0x3f317217
	s_nop 0
	v_cndmask_b32_e64 v148, 0, 32, vcc
	v_ldexp_f32 v131, v131, v148
	v_log_f32_e32 v131, v131
	s_nop 0
	v_mul_f32_e32 v148, 0x3f317217, v131
	v_fma_f32 v148, v131, s4, -v148
	v_fmac_f32_e32 v148, 0x3377d1cf, v131
	s_mov_b32 s4, 0x7f800000
	v_fmac_f32_e32 v148, 0x3f317217, v131
	v_cmp_lt_f32_e64 s[12:13], |v131|, s4
	s_nop 1
	v_cndmask_b32_e64 v131, v131, v148, s[12:13]
	v_cndmask_b32_e32 v148, 0, v227, vcc
	v_sub_f32_e32 v131, v131, v148

; DEV u16 f2bf(float f) { return (u16)(pack2(f, 0.f) & 0xffffu); }
; DEV void phase_win(const Params& P, int l, const u16* __restrict__ xb, const u16* __restrict__ Wt, u16* __restrict__ h, char* smem) {
;     ...
;         for (int j = 0; j < 4; ++j) {
;           int row = m0 + wm * 128 + ms * 16 + quad * 4 + j;
;           int col = cb + ns * 16 + l15;
;           float v = acc[ms][ns][j];
;           if (mode == 1) { float lbv = lbp[col - C_HF]; v = __logf(lbv + (1.f - lbv) / (1.f + __expf(-v))); }
;           else if (mode == 2) v = v / (1.f + __expf(-v));
;           h[(size_t)row * HS + col] = f2bf(v);
.LBB0_1981:
	s_andn2_b64 vcc, exec, s[4:5]
	s_cbranch_vccnz .LBB0_1984
	s_cmp_eq_u32 s17, 1
	v_mov_b32_e32 v131, v47
	s_cbranch_scc0 .LBB0_1984
	v_lshl_add_u64 v[140:141], v[0:1], 2, s[14:15]
	v_add_co_u32_e32 v140, vcc, 0xfffff000, v140
	s_nop 1
	v_addc_co_u32_e32 v141, vcc, -1, v141, vcc
	v_mov_b32_e32 v131, v163
	v_mul_f32_e32 v140, 0xbfb8aa3b, v47
	v_exp_f32_e32 v140, v140
	v_sub_f32_e32 v141, 1.0, v131
	v_add_f32_e32 v140, 1.0, v140
	v_div_scale_f32 v148, s[4:5], v140, v140, v141
	v_rcp_f32_e32 v149, v148
	v_div_scale_f32 v150, vcc, v141, v140, v141
	s_mov_b32 s4, 0x800000
	v_fma_f32 v151, -v148, v149, 1.0
	v_fmac_f32_e32 v149, v151, v149
	v_mul_f32_e32 v151, v150, v149
	v_fma_f32 v152, -v148, v151, v150
	v_fmac_f32_e32 v151, v152, v149
	v_fma_f32 v148, -v148, v151, v150
	v_div_fmas_f32 v148, v148, v149, v151
	v_div_fixup_f32 v140, v148, v140, v141
	v_add_f32_e32 v131, v131, v140
	v_cmp_gt_f32_e32 vcc, s4, v131
	s_mov_b32 s4, 0x3f317217
	s_nop 0
	v_cndmask_b32_e64 v140, 0, 32, vcc
	v_ldexp_f32 v131, v131, v140
	v_log_f32_e32 v131, v131
	s_nop 0
	v_mul_f32_e32 v140, 0x3f317217, v131
	v_fma_f32 v140, v131, s4, -v140
	v_fmac_f32_e32 v140, 0x3377d1cf, v131
	s_mov_b32 s4, 0x7f800000
	v_fmac_f32_e32 v140, 0x3f317217, v131
	v_cmp_lt_f32_e64 s[12:13], |v131|, s4
	s_nop 1
	v_cndmask_b32_e64 v131, v131, v140, s[12:13]
	v_cndmask_b32_e32 v140, 0, v227, vcc
	v_sub_f32_e32 v131, v131, v140

; DEV u16 f2bf(float f) { return (u16)(pack2(f, 0.f) & 0xffffu); }
; DEV void phase_win(const Params& P, int l, const u16* __restrict__ xb, const u16* __restrict__ Wt, u16* __restrict__ h, char* smem) {
;     ...
;         for (int j = 0; j < 4; ++j) {
;           int row = m0 + wm * 128 + ms * 16 + quad * 4 + j;
;           int col = cb + ns * 16 + l15;
;           float v = acc[ms][ns][j];
;           if (mode == 1) { float lbv = lbp[col - C_HF]; v = __logf(lbv + (1.f - lbv) / (1.f + __expf(-v))); }
;           else if (mode == 2) v = v / (1.f + __expf(-v));
;           h[(size_t)row * HS + col] = f2bf(v);
.LBB0_1986:
	s_andn2_b64 vcc, exec, s[4:5]
	s_cbranch_vccnz .LBB0_1989
	s_cmp_eq_u32 s17, 1
	v_mov_b32_e32 v131, v48
	s_cbranch_scc0 .LBB0_1989
	v_lshl_add_u64 v[140:141], v[0:1], 2, s[14:15]
	v_add_co_u32_e32 v140, vcc, 0xfffff000, v140
	s_nop 1
	v_addc_co_u32_e32 v141, vcc, -1, v141, vcc
	v_mov_b32_e32 v131, v163
	v_mul_f32_e32 v140, 0xbfb8aa3b, v48
	v_exp_f32_e32 v140, v140
	v_sub_f32_e32 v141, 1.0, v131
	v_add_f32_e32 v140, 1.0, v140
	v_div_scale_f32 v142, s[4:5], v140, v140, v141
	v_rcp_f32_e32 v143, v142
	v_div_scale_f32 v148, vcc, v141, v140, v141
	s_mov_b32 s4, 0x800000
	v_fma_f32 v149, -v142, v143, 1.0
	v_fmac_f32_e32 v143, v149, v143
	v_mul_f32_e32 v149, v148, v143
	v_fma_f32 v150, -v142, v149, v148
	v_fmac_f32_e32 v149, v150, v143
	v_fma_f32 v142, -v142, v149, v148
	v_div_fmas_f32 v142, v142, v143, v149
	v_div_fixup_f32 v140, v142, v140, v141
	v_add_f32_e32 v131, v131, v140
	v_cmp_gt_f32_e32 vcc, s4, v131
	s_mov_b32 s4, 0x3f317217
	s_nop 0
	v_cndmask_b32_e64 v140, 0, 32, vcc
	v_ldexp_f32 v131, v131, v140
	v_log_f32_e32 v131, v131
	s_nop 0
	v_mul_f32_e32 v140, 0x3f317217, v131
	v_fma_f32 v140, v131, s4, -v140
	v_fmac_f32_e32 v140, 0x3377d1cf, v131
	s_mov_b32 s4, 0x7f800000
	v_fmac_f32_e32 v140, 0x3f317217, v131
	v_cmp_lt_f32_e64 s[12:13], |v131|, s4
	s_nop 1
	v_cndmask_b32_e64 v131, v131, v140, s[12:13]
	v_cndmask_b32_e32 v140, 0, v227, vcc
	v_sub_f32_e32 v131, v131, v140

; DEV u16 f2bf(float f) { return (u16)(pack2(f, 0.f) & 0xffffu); }
; DEV void phase_win(const Params& P, int l, const u16* __restrict__ xb, const u16* __restrict__ Wt, u16* __restrict__ h, char* smem) {
;     ...
;         for (int j = 0; j < 4; ++j) {
;           int row = m0 + wm * 128 + ms * 16 + quad * 4 + j;
;           int col = cb + ns * 16 + l15;
;           float v = acc[ms][ns][j];
;           if (mode == 1) { float lbv = lbp[col - C_HF]; v = __logf(lbv + (1.f - lbv) / (1.f + __expf(-v))); }
;           else if (mode == 2) v = v / (1.f + __expf(-v));
;           h[(size_t)row * HS + col] = f2bf(v);
.LBB0_1991:
	s_andn2_b64 vcc, exec, s[4:5]
	s_cbranch_vccnz .LBB0_1994
	s_cmp_eq_u32 s17, 1
	v_mov_b32_e32 v131, v49
	s_cbranch_scc0 .LBB0_1994
	v_lshl_add_u64 v[140:141], v[0:1], 2, s[14:15]
	v_add_co_u32_e32 v140, vcc, 0xfffff000, v140
	s_nop 1
	v_addc_co_u32_e32 v141, vcc, -1, v141, vcc
	v_mov_b32_e32 v131, v163
	v_mul_f32_e32 v140, 0xbfb8aa3b, v49
	v_exp_f32_e32 v140, v140
	v_sub_f32_e32 v141, 1.0, v131
	v_add_f32_e32 v140, 1.0, v140
	v_div_scale_f32 v142, s[4:5], v140, v140, v141
	v_rcp_f32_e32 v143, v142
	v_div_scale_f32 v144, vcc, v141, v140, v141
	s_mov_b32 s4, 0x800000
	v_fma_f32 v145, -v142, v143, 1.0
	v_fmac_f32_e32 v143, v145, v143
	v_mul_f32_e32 v145, v144, v143
	v_fma_f32 v148, -v142, v145, v144
	v_fmac_f32_e32 v145, v148, v143
	v_fma_f32 v142, -v142, v145, v144
	v_div_fmas_f32 v142, v142, v143, v145
	v_div_fixup_f32 v140, v142, v140, v141
	v_add_f32_e32 v131, v131, v140
	v_cmp_gt_f32_e32 vcc, s4, v131
	s_mov_b32 s4, 0x3f317217
	s_nop 0
	v_cndmask_b32_e64 v140, 0, 32, vcc
	v_ldexp_f32 v131, v131, v140
	v_log_f32_e32 v131, v131
	s_nop 0
	v_mul_f32_e32 v140, 0x3f317217, v131
	v_fma_f32 v140, v131, s4, -v140
	v_fmac_f32_e32 v140, 0x3377d1cf, v131
	s_mov_b32 s4, 0x7f800000
	v_fmac_f32_e32 v140, 0x3f317217, v131
	v_cmp_lt_f32_e64 s[12:13], |v131|, s4
	s_nop 1
	v_cndmask_b32_e64 v131, v131, v140, s[12:13]
	v_cndmask_b32_e32 v140, 0, v227, vcc
	v_sub_f32_e32 v131, v131, v140

; DEV u16 f2bf(float f) { return (u16)(pack2(f, 0.f) & 0xffffu); }
; DEV void phase_win(const Params& P, int l, const u16* __restrict__ xb, const u16* __restrict__ Wt, u16* __restrict__ h, char* smem) {
;     ...
;         for (int j = 0; j < 4; ++j) {
;           int row = m0 + wm * 128 + ms * 16 + quad * 4 + j;
;           int col = cb + ns * 16 + l15;
;           float v = acc[ms][ns][j];
;           if (mode == 1) { float lbv = lbp[col - C_HF]; v = __logf(lbv + (1.f - lbv) / (1.f + __expf(-v))); }
;           else if (mode == 2) v = v / (1.f + __expf(-v));
;           h[(size_t)row * HS + col] = f2bf(v);
.LBB0_1996:
	s_andn2_b64 vcc, exec, s[4:5]
	s_cbranch_vccnz .LBB0_1999
	s_cmp_eq_u32 s17, 1
	v_mov_b32_e32 v140, v2
	s_cbranch_scc0 .LBB0_1999
	v_lshl_add_u64 v[140:141], v[0:1], 2, s[14:15]
	v_add_co_u32_e32 v140, vcc, 0xfffff000, v140
	s_nop 1
	v_addc_co_u32_e32 v141, vcc, -1, v141, vcc
	v_mov_b32_e32 v131, v160
	v_mul_f32_e32 v140, 0xbfb8aa3b, v2
	v_exp_f32_e32 v140, v140
	v_sub_f32_e32 v141, 1.0, v131
	v_add_f32_e32 v140, 1.0, v140
	v_div_scale_f32 v142, s[4:5], v140, v140, v141
	v_rcp_f32_e32 v143, v142
	v_div_scale_f32 v144, vcc, v141, v140, v141
	s_mov_b32 s4, 0x800000
	v_fma_f32 v145, -v142, v143, 1.0
	v_fmac_f32_e32 v143, v145, v143
	v_mul_f32_e32 v145, v144, v143
	v_fma_f32 v146, -v142, v145, v144
	v_fmac_f32_e32 v145, v146, v143
	v_fma_f32 v142, -v142, v145, v144
	v_div_fmas_f32 v142, v142, v143, v145
	v_div_fixup_f32 v140, v142, v140, v141
	v_add_f32_e32 v131, v131, v140
	v_cmp_gt_f32_e32 vcc, s4, v131
	s_mov_b32 s4, 0x3f317217
	s_nop 0
	v_cndmask_b32_e64 v140, 0, 32, vcc
	v_ldexp_f32 v131, v131, v140
	v_log_f32_e32 v131, v131
	s_nop 0
	v_mul_f32_e32 v140, 0x3f317217, v131
	v_fma_f32 v140, v131, s4, -v140
	v_fmac_f32_e32 v140, 0x3377d1cf, v131
	s_mov_b32 s4, 0x7f800000
	v_fmac_f32_e32 v140, 0x3f317217, v131
	v_cmp_lt_f32_e64 s[12:13], |v131|, s4
	s_nop 1
	v_cndmask_b32_e64 v131, v131, v140, s[12:13]
	v_cndmask_b32_e32 v140, 0, v227, vcc
	v_sub_f32_e32 v140, v131, v140

; DEV u16 f2bf(float f) { return (u16)(pack2(f, 0.f) & 0xffffu); }
; DEV void phase_win(const Params& P, int l, const u16* __restrict__ xb, const u16* __restrict__ Wt, u16* __restrict__ h, char* smem) {
;     ...
;           int row = m0 + wm * 128 + ms * 16 + quad * 4 + j;
;           int col = cb + ns * 16 + l15;
;           float v = acc[ms][ns][j];
;           if (mode == 1) { float lbv = lbp[col - C_HF]; v = __logf(lbv + (1.f - lbv) / (1.f + __expf(-v))); }
;           else if (mode == 2) v = v / (1.f + __expf(-v));
;           h[(size_t)row * HS + col] = f2bf(v);
.LBB0_2001:
	s_andn2_b64 vcc, exec, s[4:5]
	s_cbranch_vccnz .LBB0_2004
	s_cmp_eq_u32 s17, 1
	v_mov_b32_e32 v142, v3
	s_cbranch_scc0 .LBB0_2004
	v_lshl_add_u64 v[142:143], v[0:1], 2, s[14:15]
	v_add_co_u32_e32 v142, vcc, 0xfffff000, v142
	s_nop 1
	v_addc_co_u32_e32 v143, vcc, -1, v143, vcc
	v_mov_b32_e32 v142, v160
	v_mul_f32_e32 v143, 0xbfb8aa3b, v3
	v_exp_f32_e32 v143, v143
	v_sub_f32_e32 v144, 1.0, v142
	v_add_f32_e32 v143, 1.0, v143
	v_div_scale_f32 v145, s[4:5], v143, v143, v144
	v_rcp_f32_e32 v146, v145
	v_div_scale_f32 v147, vcc, v144, v143, v144
	s_mov_b32 s4, 0x800000
	v_fma_f32 v148, -v145, v146, 1.0
	v_fmac_f32_e32 v146, v148, v146
	v_mul_f32_e32 v148, v147, v146
	v_fma_f32 v149, -v145, v148, v147
	v_fmac_f32_e32 v148, v149, v146
	v_fma_f32 v145, -v145, v148, v147
	v_div_fmas_f32 v145, v145, v146, v148
	v_div_fixup_f32 v143, v145, v143, v144
	v_add_f32_e32 v142, v142, v143
	v_cmp_gt_f32_e32 vcc, s4, v142
	s_mov_b32 s4, 0x3f317217
	s_nop 0
	v_cndmask_b32_e64 v143, 0, 32, vcc
	v_ldexp_f32 v142, v142, v143
	v_log_f32_e32 v142, v142
	s_nop 0
	v_mul_f32_e32 v143, 0x3f317217, v142
	v_fma_f32 v143, v142, s4, -v143
	v_fmac_f32_e32 v143, 0x3377d1cf, v142
	s_mov_b32 s4, 0x7f800000
	v_fmac_f32_e32 v143, 0x3f317217, v142
	v_cmp_lt_f32_e64 s[12:13], |v142|, s4
	s_nop 1
	v_cndmask_b32_e64 v142, v142, v143, s[12:13]
	v_cndmask_b32_e32 v143, 0, v227, vcc
	v_sub_f32_e32 v142, v142, v143

; DEV u16 f2bf(float f) { return (u16)(pack2(f, 0.f) & 0xffffu); }
; DEV void phase_win(const Params& P, int l, const u16* __restrict__ xb, const u16* __restrict__ Wt, u16* __restrict__ h, char* smem) {
;     ...
;           int row = m0 + wm * 128 + ms * 16 + quad * 4 + j;
;           int col = cb + ns * 16 + l15;
;           float v = acc[ms][ns][j];
;           if (mode == 1) { float lbv = lbp[col - C_HF]; v = __logf(lbv + (1.f - lbv) / (1.f + __expf(-v))); }
;           else if (mode == 2) v = v / (1.f + __expf(-v));
;           h[(size_t)row * HS + col] = f2bf(v);
.LBB0_2006:
	s_andn2_b64 vcc, exec, s[4:5]
	s_cbranch_vccnz .LBB0_2009
	s_cmp_eq_u32 s17, 1
	v_mov_b32_e32 v144, v4
	s_cbranch_scc0 .LBB0_2009
	v_lshl_add_u64 v[144:145], v[0:1], 2, s[14:15]
	v_add_co_u32_e32 v144, vcc, 0xfffff000, v144
	s_nop 1
	v_addc_co_u32_e32 v145, vcc, -1, v145, vcc
	v_mov_b32_e32 v144, v160
	v_mul_f32_e32 v145, 0xbfb8aa3b, v4
	v_exp_f32_e32 v145, v145
	v_sub_f32_e32 v146, 1.0, v144
	v_add_f32_e32 v145, 1.0, v145
	v_div_scale_f32 v147, s[4:5], v145, v145, v146
	v_rcp_f32_e32 v148, v147
	v_div_scale_f32 v149, vcc, v146, v145, v146
	s_mov_b32 s4, 0x800000
	v_fma_f32 v150, -v147, v148, 1.0
	v_fmac_f32_e32 v148, v150, v148
	v_mul_f32_e32 v150, v149, v148
	v_fma_f32 v151, -v147, v150, v149
	v_fmac_f32_e32 v150, v151, v148
	v_fma_f32 v147, -v147, v150, v149
	v_div_fmas_f32 v147, v147, v148, v150
	v_div_fixup_f32 v145, v147, v145, v146
	v_add_f32_e32 v144, v144, v145
	v_cmp_gt_f32_e32 vcc, s4, v144
	s_mov_b32 s4, 0x3f317217
	s_nop 0
	v_cndmask_b32_e64 v145, 0, 32, vcc
	v_ldexp_f32 v144, v144, v145
	v_log_f32_e32 v144, v144
	s_nop 0
	v_mul_f32_e32 v145, 0x3f317217, v144
	v_fma_f32 v145, v144, s4, -v145
	v_fmac_f32_e32 v145, 0x3377d1cf, v144
	s_mov_b32 s4, 0x7f800000
	v_fmac_f32_e32 v145, 0x3f317217, v144
	v_cmp_lt_f32_e64 s[12:13], |v144|, s4
	s_nop 1
	v_cndmask_b32_e64 v144, v144, v145, s[12:13]
	v_cndmask_b32_e32 v145, 0, v227, vcc
	v_sub_f32_e32 v144, v144, v145

; DEV u16 f2bf(float f) { return (u16)(pack2(f, 0.f) & 0xffffu); }
; DEV void phase_win(const Params& P, int l, const u16* __restrict__ xb, const u16* __restrict__ Wt, u16* __restrict__ h, char* smem) {
;     ...
;           int row = m0 + wm * 128 + ms * 16 + quad * 4 + j;
;           int col = cb + ns * 16 + l15;
;           float v = acc[ms][ns][j];
;           if (mode == 1) { float lbv = lbp[col - C_HF]; v = __logf(lbv + (1.f - lbv) / (1.f + __expf(-v))); }
;           else if (mode == 2) v = v / (1.f + __expf(-v));
;           h[(size_t)row * HS + col] = f2bf(v);
.LBB0_2011:
	s_andn2_b64 vcc, exec, s[4:5]
	s_cbranch_vccnz .LBB0_2014
	s_cmp_eq_u32 s17, 1
	v_mov_b32_e32 v146, v5
	s_cbranch_scc0 .LBB0_2014
	v_lshl_add_u64 v[146:147], v[0:1], 2, s[14:15]
	v_add_co_u32_e32 v146, vcc, 0xfffff000, v146
	s_nop 1
	v_addc_co_u32_e32 v147, vcc, -1, v147, vcc
	v_mov_b32_e32 v146, v160
	v_mul_f32_e32 v147, 0xbfb8aa3b, v5
	v_exp_f32_e32 v147, v147
	v_sub_f32_e32 v148, 1.0, v146
	v_add_f32_e32 v147, 1.0, v147
	v_div_scale_f32 v149, s[4:5], v147, v147, v148
	v_rcp_f32_e32 v150, v149
	v_div_scale_f32 v151, vcc, v148, v147, v148
	s_mov_b32 s4, 0x800000
	v_fma_f32 v152, -v149, v150, 1.0
	v_fmac_f32_e32 v150, v152, v150
	v_mul_f32_e32 v152, v151, v150
	v_fma_f32 v153, -v149, v152, v151
	v_fmac_f32_e32 v152, v153, v150
	v_fma_f32 v149, -v149, v152, v151
	v_div_fmas_f32 v149, v149, v150, v152
	v_div_fixup_f32 v147, v149, v147, v148
	v_add_f32_e32 v146, v146, v147
	v_cmp_gt_f32_e32 vcc, s4, v146
	s_mov_b32 s4, 0x3f317217
	s_nop 0
	v_cndmask_b32_e64 v147, 0, 32, vcc
	v_ldexp_f32 v146, v146, v147
	v_log_f32_e32 v146, v146
	s_nop 0
	v_mul_f32_e32 v147, 0x3f317217, v146
	v_fma_f32 v147, v146, s4, -v147
	v_fmac_f32_e32 v147, 0x3377d1cf, v146
	s_mov_b32 s4, 0x7f800000
	v_fmac_f32_e32 v147, 0x3f317217, v146
	v_cmp_lt_f32_e64 s[12:13], |v146|, s4
	s_nop 1
	v_cndmask_b32_e64 v146, v146, v147, s[12:13]
	v_cndmask_b32_e32 v147, 0, v227, vcc
	v_sub_f32_e32 v146, v146, v147

; DEV u16 f2bf(float f) { return (u16)(pack2(f, 0.f) & 0xffffu); }
; DEV void phase_win(const Params& P, int l, const u16* __restrict__ xb, const u16* __restrict__ Wt, u16* __restrict__ h, char* smem) {
;     ...
;           int row = m0 + wm * 128 + ms * 16 + quad * 4 + j;
;           int col = cb + ns * 16 + l15;
;           float v = acc[ms][ns][j];
;           if (mode == 1) { float lbv = lbp[col - C_HF]; v = __logf(lbv + (1.f - lbv) / (1.f + __expf(-v))); }
;           else if (mode == 2) v = v / (1.f + __expf(-v));
;           h[(size_t)row * HS + col] = f2bf(v);
.LBB0_2016:
	s_andn2_b64 vcc, exec, s[4:5]
	s_cbranch_vccnz .LBB0_2019
	s_cmp_eq_u32 s17, 1
	v_mov_b32_e32 v131, v34
	s_cbranch_scc0 .LBB0_2019
	v_lshl_add_u64 v[132:133], v[0:1], 2, s[14:15]
	v_add_co_u32_e32 v132, vcc, 0xfffff000, v132
	s_nop 1
	v_addc_co_u32_e32 v133, vcc, -1, v133, vcc
	v_mov_b32_e32 v131, v161
	v_mul_f32_e32 v132, 0xbfb8aa3b, v34
	v_exp_f32_e32 v132, v132
	v_sub_f32_e32 v133, 1.0, v131
	v_add_f32_e32 v132, 1.0, v132
	v_div_scale_f32 v148, s[4:5], v132, v132, v133
	v_rcp_f32_e32 v149, v148
	v_div_scale_f32 v150, vcc, v133, v132, v133
	s_mov_b32 s4, 0x800000
	v_fma_f32 v151, -v148, v149, 1.0
	v_fmac_f32_e32 v149, v151, v149
	v_mul_f32_e32 v151, v150, v149
	v_fma_f32 v152, -v148, v151, v150
	v_fmac_f32_e32 v151, v152, v149
	v_fma_f32 v148, -v148, v151, v150
	v_div_fmas_f32 v148, v148, v149, v151
	v_div_fixup_f32 v132, v148, v132, v133
	v_add_f32_e32 v131, v131, v132
	v_cmp_gt_f32_e32 vcc, s4, v131
	s_mov_b32 s4, 0x3f317217
	s_nop 0
	v_cndmask_b32_e64 v132, 0, 32, vcc
	v_ldexp_f32 v131, v131, v132
	v_log_f32_e32 v131, v131
	s_nop 0
	v_mul_f32_e32 v132, 0x3f317217, v131
	v_fma_f32 v132, v131, s4, -v132
	v_fmac_f32_e32 v132, 0x3377d1cf, v131
	s_mov_b32 s4, 0x7f800000
	v_fmac_f32_e32 v132, 0x3f317217, v131
	v_cmp_lt_f32_e64 s[12:13], |v131|, s4
	s_nop 1
	v_cndmask_b32_e64 v131, v131, v132, s[12:13]
	v_cndmask_b32_e32 v132, 0, v227, vcc
	v_sub_f32_e32 v131, v131, v132

; DEV u16 f2bf(float f) { return (u16)(pack2(f, 0.f) & 0xffffu); }
; DEV void phase_win(const Params& P, int l, const u16* __restrict__ xb, const u16* __restrict__ Wt, u16* __restrict__ h, char* smem) {
;     ...
;           int row = m0 + wm * 128 + ms * 16 + quad * 4 + j;
;           int col = cb + ns * 16 + l15;
;           float v = acc[ms][ns][j];
;           if (mode == 1) { float lbv = lbp[col - C_HF]; v = __logf(lbv + (1.f - lbv) / (1.f + __expf(-v))); }
;           else if (mode == 2) v = v / (1.f + __expf(-v));
;           h[(size_t)row * HS + col] = f2bf(v);
.LBB0_2021:
	s_andn2_b64 vcc, exec, s[4:5]
	s_cbranch_vccnz .LBB0_2024
	s_cmp_eq_u32 s17, 1
	v_mov_b32_e32 v131, v35
	s_cbranch_scc0 .LBB0_2024
	v_lshl_add_u64 v[140:141], v[0:1], 2, s[14:15]
	v_add_co_u32_e32 v140, vcc, 0xfffff000, v140
	s_nop 1
	v_addc_co_u32_e32 v141, vcc, -1, v141, vcc
	v_mov_b32_e32 v131, v161
	v_mul_f32_e32 v140, 0xbfb8aa3b, v35
	v_exp_f32_e32 v140, v140
	v_sub_f32_e32 v141, 1.0, v131
	v_add_f32_e32 v140, 1.0, v140
	v_div_scale_f32 v148, s[4:5], v140, v140, v141
	v_rcp_f32_e32 v149, v148
	v_div_scale_f32 v150, vcc, v141, v140, v141
	s_mov_b32 s4, 0x800000
	v_fma_f32 v151, -v148, v149, 1.0
	v_fmac_f32_e32 v149, v151, v149
	v_mul_f32_e32 v151, v150, v149
	v_fma_f32 v152, -v148, v151, v150
	v_fmac_f32_e32 v151, v152, v149
	v_fma_f32 v148, -v148, v151, v150
	v_div_fmas_f32 v148, v148, v149, v151
	v_div_fixup_f32 v140, v148, v140, v141
	v_add_f32_e32 v131, v131, v140
	v_cmp_gt_f32_e32 vcc, s4, v131
	s_mov_b32 s4, 0x3f317217
	s_nop 0
	v_cndmask_b32_e64 v140, 0, 32, vcc
	v_ldexp_f32 v131, v131, v140
	v_log_f32_e32 v131, v131
	s_nop 0
	v_mul_f32_e32 v140, 0x3f317217, v131
	v_fma_f32 v140, v131, s4, -v140
	v_fmac_f32_e32 v140, 0x3377d1cf, v131
	s_mov_b32 s4, 0x7f800000
	v_fmac_f32_e32 v140, 0x3f317217, v131
	v_cmp_lt_f32_e64 s[12:13], |v131|, s4
	s_nop 1
	v_cndmask_b32_e64 v131, v131, v140, s[12:13]
	v_cndmask_b32_e32 v140, 0, v227, vcc
	v_sub_f32_e32 v131, v131, v140

; DEV u16 f2bf(float f) { return (u16)(pack2(f, 0.f) & 0xffffu); }
; DEV void phase_win(const Params& P, int l, const u16* __restrict__ xb, const u16* __restrict__ Wt, u16* __restrict__ h, char* smem) {
;     ...
;           int row = m0 + wm * 128 + ms * 16 + quad * 4 + j;
;           int col = cb + ns * 16 + l15;
;           float v = acc[ms][ns][j];
;           if (mode == 1) { float lbv = lbp[col - C_HF]; v = __logf(lbv + (1.f - lbv) / (1.f + __expf(-v))); }
;           else if (mode == 2) v = v / (1.f + __expf(-v));
;           h[(size_t)row * HS + col] = f2bf(v);
.LBB0_2026:
	s_andn2_b64 vcc, exec, s[4:5]
	s_cbranch_vccnz .LBB0_2029
	s_cmp_eq_u32 s17, 1
	v_mov_b32_e32 v131, v36
	s_cbranch_scc0 .LBB0_2029
	v_lshl_add_u64 v[142:143], v[0:1], 2, s[14:15]
	v_add_co_u32_e32 v142, vcc, 0xfffff000, v142
	s_nop 1
	v_addc_co_u32_e32 v143, vcc, -1, v143, vcc
	v_mov_b32_e32 v131, v161
	v_mul_f32_e32 v142, 0xbfb8aa3b, v36
	v_exp_f32_e32 v142, v142
	v_sub_f32_e32 v143, 1.0, v131
	v_add_f32_e32 v142, 1.0, v142
	v_div_scale_f32 v148, s[4:5], v142, v142, v143
	v_rcp_f32_e32 v149, v148
	v_div_scale_f32 v150, vcc, v143, v142, v143
	s_mov_b32 s4, 0x800000
	v_fma_f32 v151, -v148, v149, 1.0
	v_fmac_f32_e32 v149, v151, v149
	v_mul_f32_e32 v151, v150, v149
	v_fma_f32 v152, -v148, v151, v150
	v_fmac_f32_e32 v151, v152, v149
	v_fma_f32 v148, -v148, v151, v150
	v_div_fmas_f32 v148, v148, v149, v151
	v_div_fixup_f32 v142, v148, v142, v143
	v_add_f32_e32 v131, v131, v142
	v_cmp_gt_f32_e32 vcc, s4, v131
	s_mov_b32 s4, 0x3f317217
	s_nop 0
	v_cndmask_b32_e64 v142, 0, 32, vcc
	v_ldexp_f32 v131, v131, v142
	v_log_f32_e32 v131, v131
	s_nop 0
	v_mul_f32_e32 v142, 0x3f317217, v131
	v_fma_f32 v142, v131, s4, -v142
	v_fmac_f32_e32 v142, 0x3377d1cf, v131
	s_mov_b32 s4, 0x7f800000
	v_fmac_f32_e32 v142, 0x3f317217, v131
	v_cmp_lt_f32_e64 s[12:13], |v131|, s4
	s_nop 1
	v_cndmask_b32_e64 v131, v131, v142, s[12:13]
	v_cndmask_b32_e32 v142, 0, v227, vcc
	v_sub_f32_e32 v131, v131, v142

; DEV u16 f2bf(float f) { return (u16)(pack2(f, 0.f) & 0xffffu); }
; DEV void phase_win(const Params& P, int l, const u16* __restrict__ xb, const u16* __restrict__ Wt, u16* __restrict__ h, char* smem) {
;     ...
;           int row = m0 + wm * 128 + ms * 16 + quad * 4 + j;
;           int col = cb + ns * 16 + l15;
;           float v = acc[ms][ns][j];
;           if (mode == 1) { float lbv = lbp[col - C_HF]; v = __logf(lbv + (1.f - lbv) / (1.f + __expf(-v))); }
;           else if (mode == 2) v = v / (1.f + __expf(-v));
;           h[(size_t)row * HS + col] = f2bf(v);
.LBB0_2031:
	s_andn2_b64 vcc, exec, s[4:5]
	s_cbranch_vccnz .LBB0_2034
	s_cmp_eq_u32 s17, 1
	v_mov_b32_e32 v131, v37
	s_cbranch_scc0 .LBB0_2034
	v_lshl_add_u64 v[144:145], v[0:1], 2, s[14:15]
	v_add_co_u32_e32 v144, vcc, 0xfffff000, v144
	s_nop 1
	v_addc_co_u32_e32 v145, vcc, -1, v145, vcc
	v_mov_b32_e32 v131, v161
	v_mul_f32_e32 v144, 0xbfb8aa3b, v37
	v_exp_f32_e32 v144, v144
	v_sub_f32_e32 v145, 1.0, v131
	v_add_f32_e32 v144, 1.0, v144
	v_div_scale_f32 v148, s[4:5], v144, v144, v145
	v_rcp_f32_e32 v149, v148
	v_div_scale_f32 v150, vcc, v145, v144, v145
	s_mov_b32 s4, 0x800000
	v_fma_f32 v151, -v148, v149, 1.0
	v_fmac_f32_e32 v149, v151, v149
	v_mul_f32_e32 v151, v150, v149
	v_fma_f32 v152, -v148, v151, v150
	v_fmac_f32_e32 v151, v152, v149
	v_fma_f32 v148, -v148, v151, v150
	v_div_fmas_f32 v148, v148, v149, v151
	v_div_fixup_f32 v144, v148, v144, v145
	v_add_f32_e32 v131, v131, v144
	v_cmp_gt_f32_e32 vcc, s4, v131
	s_mov_b32 s4, 0x3f317217
	s_nop 0
	v_cndmask_b32_e64 v144, 0, 32, vcc
	v_ldexp_f32 v131, v131, v144
	v_log_f32_e32 v131, v131
	s_nop 0
	v_mul_f32_e32 v144, 0x3f317217, v131
	v_fma_f32 v144, v131, s4, -v144
	v_fmac_f32_e32 v144, 0x3377d1cf, v131
	s_mov_b32 s4, 0x7f800000
	v_fmac_f32_e32 v144, 0x3f317217, v131
	v_cmp_lt_f32_e64 s[12:13], |v131|, s4
	s_nop 1
	v_cndmask_b32_e64 v131, v131, v144, s[12:13]
	v_cndmask_b32_e32 v144, 0, v227, vcc
	v_sub_f32_e32 v131, v131, v144

; DEV u16 f2bf(float f) { return (u16)(pack2(f, 0.f) & 0xffffu); }
; DEV void phase_win(const Params& P, int l, const u16* __restrict__ xb, const u16* __restrict__ Wt, u16* __restrict__ h, char* smem) {
;     ...
;           int row = m0 + wm * 128 + ms * 16 + quad * 4 + j;
;           int col = cb + ns * 16 + l15;
;           float v = acc[ms][ns][j];
;           if (mode == 1) { float lbv = lbp[col - C_HF]; v = __logf(lbv + (1.f - lbv) / (1.f + __expf(-v))); }
;           else if (mode == 2) v = v / (1.f + __expf(-v));
;           h[(size_t)row * HS + col] = f2bf(v);
.LBB0_2036:
	s_andn2_b64 vcc, exec, s[4:5]
	s_cbranch_vccnz .LBB0_2039
	s_cmp_eq_u32 s17, 1
	v_mov_b32_e32 v131, v42
	s_cbranch_scc0 .LBB0_2039
	v_lshl_add_u64 v[134:135], v[0:1], 2, s[14:15]
	v_add_co_u32_e32 v134, vcc, 0xfffff000, v134
	s_nop 1
	v_addc_co_u32_e32 v135, vcc, -1, v135, vcc
	v_mov_b32_e32 v131, v162
	v_mul_f32_e32 v134, 0xbfb8aa3b, v42
	v_exp_f32_e32 v134, v134
	v_sub_f32_e32 v135, 1.0, v131
	v_add_f32_e32 v134, 1.0, v134
	v_div_scale_f32 v146, s[4:5], v134, v134, v135
	v_rcp_f32_e32 v147, v146
	v_div_scale_f32 v148, vcc, v135, v134, v135
	s_mov_b32 s4, 0x800000
	v_fma_f32 v149, -v146, v147, 1.0
	v_fmac_f32_e32 v147, v149, v147
	v_mul_f32_e32 v149, v148, v147
	v_fma_f32 v150, -v146, v149, v148
	v_fmac_f32_e32 v149, v150, v147
	v_fma_f32 v146, -v146, v149, v148
	v_div_fmas_f32 v146, v146, v147, v149
	v_div_fixup_f32 v134, v146, v134, v135
	v_add_f32_e32 v131, v131, v134
	v_cmp_gt_f32_e32 vcc, s4, v131
	s_mov_b32 s4, 0x3f317217
	s_nop 0
	v_cndmask_b32_e64 v134, 0, 32, vcc
	v_ldexp_f32 v131, v131, v134
	v_log_f32_e32 v131, v131
	s_nop 0
	v_mul_f32_e32 v134, 0x3f317217, v131
	v_fma_f32 v134, v131, s4, -v134
	v_fmac_f32_e32 v134, 0x3377d1cf, v131
	s_mov_b32 s4, 0x7f800000
	v_fmac_f32_e32 v134, 0x3f317217, v131
	v_cmp_lt_f32_e64 s[12:13], |v131|, s4
	s_nop 1
	v_cndmask_b32_e64 v131, v131, v134, s[12:13]
	v_cndmask_b32_e32 v134, 0, v227, vcc
	v_sub_f32_e32 v131, v131, v134

; DEV u16 f2bf(float f) { return (u16)(pack2(f, 0.f) & 0xffffu); }
; DEV void phase_win(const Params& P, int l, const u16* __restrict__ xb, const u16* __restrict__ Wt, u16* __restrict__ h, char* smem) {
;     ...
;           int row = m0 + wm * 128 + ms * 16 + quad * 4 + j;
;           int col = cb + ns * 16 + l15;
;           float v = acc[ms][ns][j];
;           if (mode == 1) { float lbv = lbp[col - C_HF]; v = __logf(lbv + (1.f - lbv) / (1.f + __expf(-v))); }
;           else if (mode == 2) v = v / (1.f + __expf(-v));
;           h[(size_t)row * HS + col] = f2bf(v);
.LBB0_2041:
	s_andn2_b64 vcc, exec, s[4:5]
	s_cbranch_vccnz .LBB0_2044
	s_cmp_eq_u32 s17, 1
	v_mov_b32_e32 v131, v43
	s_cbranch_scc0 .LBB0_2044
	v_lshl_add_u64 v[134:135], v[0:1], 2, s[14:15]
	v_add_co_u32_e32 v134, vcc, 0xfffff000, v134
	s_nop 1
	v_addc_co_u32_e32 v135, vcc, -1, v135, vcc
	v_mov_b32_e32 v131, v162
	v_mul_f32_e32 v134, 0xbfb8aa3b, v43
	v_exp_f32_e32 v134, v134
	v_sub_f32_e32 v135, 1.0, v131
	v_add_f32_e32 v134, 1.0, v134
	v_div_scale_f32 v146, s[4:5], v134, v134, v135
	v_rcp_f32_e32 v147, v146
	v_div_scale_f32 v148, vcc, v135, v134, v135
	s_mov_b32 s4, 0x800000
	v_fma_f32 v149, -v146, v147, 1.0
	v_fmac_f32_e32 v147, v149, v147
	v_mul_f32_e32 v149, v148, v147
	v_fma_f32 v150, -v146, v149, v148
	v_fmac_f32_e32 v149, v150, v147
	v_fma_f32 v146, -v146, v149, v148
	v_div_fmas_f32 v146, v146, v147, v149
	v_div_fixup_f32 v134, v146, v134, v135
	v_add_f32_e32 v131, v131, v134
	v_cmp_gt_f32_e32 vcc, s4, v131
	s_mov_b32 s4, 0x3f317217
	s_nop 0
	v_cndmask_b32_e64 v134, 0, 32, vcc
	v_ldexp_f32 v131, v131, v134
	v_log_f32_e32 v131, v131
	s_nop 0
	v_mul_f32_e32 v134, 0x3f317217, v131
	v_fma_f32 v134, v131, s4, -v134
	v_fmac_f32_e32 v134, 0x3377d1cf, v131
	s_mov_b32 s4, 0x7f800000
	v_fmac_f32_e32 v134, 0x3f317217, v131
	v_cmp_lt_f32_e64 s[12:13], |v131|, s4
	s_nop 1
	v_cndmask_b32_e64 v131, v131, v134, s[12:13]
	v_cndmask_b32_e32 v134, 0, v227, vcc
	v_sub_f32_e32 v131, v131, v134

; DEV u16 f2bf(float f) { return (u16)(pack2(f, 0.f) & 0xffffu); }
; DEV void phase_win(const Params& P, int l, const u16* __restrict__ xb, const u16* __restrict__ Wt, u16* __restrict__ h, char* smem) {
;     ...
;           int row = m0 + wm * 128 + ms * 16 + quad * 4 + j;
;           int col = cb + ns * 16 + l15;
;           float v = acc[ms][ns][j];
;           if (mode == 1) { float lbv = lbp[col - C_HF]; v = __logf(lbv + (1.f - lbv) / (1.f + __expf(-v))); }
;           else if (mode == 2) v = v / (1.f + __expf(-v));
;           h[(size_t)row * HS + col] = f2bf(v);
.LBB0_2046:
	s_andn2_b64 vcc, exec, s[4:5]
	s_cbranch_vccnz .LBB0_2049
	s_cmp_eq_u32 s17, 1
	v_mov_b32_e32 v131, v44
	s_cbranch_scc0 .LBB0_2049
	v_lshl_add_u64 v[134:135], v[0:1], 2, s[14:15]
	v_add_co_u32_e32 v134, vcc, 0xfffff000, v134
	s_nop 1
	v_addc_co_u32_e32 v135, vcc, -1, v135, vcc
	v_mov_b32_e32 v131, v162
	v_mul_f32_e32 v134, 0xbfb8aa3b, v44
	v_exp_f32_e32 v134, v134
	v_sub_f32_e32 v135, 1.0, v131
	v_add_f32_e32 v134, 1.0, v134
	v_div_scale_f32 v146, s[4:5], v134, v134, v135
	v_rcp_f32_e32 v147, v146
	v_div_scale_f32 v148, vcc, v135, v134, v135
	s_mov_b32 s4, 0x800000
	v_fma_f32 v149, -v146, v147, 1.0
	v_fmac_f32_e32 v147, v149, v147
	v_mul_f32_e32 v149, v148, v147
	v_fma_f32 v150, -v146, v149, v148
	v_fmac_f32_e32 v149, v150, v147
	v_fma_f32 v146, -v146, v149, v148
	v_div_fmas_f32 v146, v146, v147, v149
	v_div_fixup_f32 v134, v146, v134, v135
	v_add_f32_e32 v131, v131, v134
	v_cmp_gt_f32_e32 vcc, s4, v131
	s_mov_b32 s4, 0x3f317217
	s_nop 0
	v_cndmask_b32_e64 v134, 0, 32, vcc
	v_ldexp_f32 v131, v131, v134
	v_log_f32_e32 v131, v131
	s_nop 0
	v_mul_f32_e32 v134, 0x3f317217, v131
	v_fma_f32 v134, v131, s4, -v134
	v_fmac_f32_e32 v134, 0x3377d1cf, v131
	s_mov_b32 s4, 0x7f800000
	v_fmac_f32_e32 v134, 0x3f317217, v131
	v_cmp_lt_f32_e64 s[12:13], |v131|, s4
	s_nop 1
	v_cndmask_b32_e64 v131, v131, v134, s[12:13]
	v_cndmask_b32_e32 v134, 0, v227, vcc
	v_sub_f32_e32 v131, v131, v134

; DEV u16 f2bf(float f) { return (u16)(pack2(f, 0.f) & 0xffffu); }
; DEV void phase_win(const Params& P, int l, const u16* __restrict__ xb, const u16* __restrict__ Wt, u16* __restrict__ h, char* smem) {
;     ...
;           int row = m0 + wm * 128 + ms * 16 + quad * 4 + j;
;           int col = cb + ns * 16 + l15;
;           float v = acc[ms][ns][j];
;           if (mode == 1) { float lbv = lbp[col - C_HF]; v = __logf(lbv + (1.f - lbv) / (1.f + __expf(-v))); }
;           else if (mode == 2) v = v / (1.f + __expf(-v));
;           h[(size_t)row * HS + col] = f2bf(v);
.LBB0_2051:
	s_andn2_b64 vcc, exec, s[4:5]
	s_cbranch_vccnz .LBB0_2054
	s_cmp_eq_u32 s17, 1
	v_mov_b32_e32 v131, v45
	s_cbranch_scc0 .LBB0_2054
	v_lshl_add_u64 v[134:135], v[0:1], 2, s[14:15]
	v_add_co_u32_e32 v134, vcc, 0xfffff000, v134
	s_nop 1
	v_addc_co_u32_e32 v135, vcc, -1, v135, vcc
	v_mov_b32_e32 v131, v162
	v_mul_f32_e32 v134, 0xbfb8aa3b, v45
	v_exp_f32_e32 v134, v134
	v_sub_f32_e32 v135, 1.0, v131
	v_add_f32_e32 v134, 1.0, v134
	v_div_scale_f32 v146, s[4:5], v134, v134, v135
	v_rcp_f32_e32 v147, v146
	v_div_scale_f32 v148, vcc, v135, v134, v135
	s_mov_b32 s4, 0x800000
	v_fma_f32 v149, -v146, v147, 1.0
	v_fmac_f32_e32 v147, v149, v147
	v_mul_f32_e32 v149, v148, v147
	v_fma_f32 v150, -v146, v149, v148
	v_fmac_f32_e32 v149, v150, v147
	v_fma_f32 v146, -v146, v149, v148
	v_div_fmas_f32 v146, v146, v147, v149
	v_div_fixup_f32 v134, v146, v134, v135
	v_add_f32_e32 v131, v131, v134
	v_cmp_gt_f32_e32 vcc, s4, v131
	s_mov_b32 s4, 0x3f317217
	s_nop 0
	v_cndmask_b32_e64 v134, 0, 32, vcc
	v_ldexp_f32 v131, v131, v134
	v_log_f32_e32 v131, v131
	s_nop 0
	v_mul_f32_e32 v134, 0x3f317217, v131
	v_fma_f32 v134, v131, s4, -v134
	v_fmac_f32_e32 v134, 0x3377d1cf, v131
	s_mov_b32 s4, 0x7f800000
	v_fmac_f32_e32 v134, 0x3f317217, v131
	v_cmp_lt_f32_e64 s[12:13], |v131|, s4
	s_nop 1
	v_cndmask_b32_e64 v131, v131, v134, s[12:13]
	v_cndmask_b32_e32 v134, 0, v227, vcc
	v_sub_f32_e32 v131, v131, v134

; DEV u16 f2bf(float f) { return (u16)(pack2(f, 0.f) & 0xffffu); }
; DEV void phase_win(const Params& P, int l, const u16* __restrict__ xb, const u16* __restrict__ Wt, u16* __restrict__ h, char* smem) {
;     ...
;           int row = m0 + wm * 128 + ms * 16 + quad * 4 + j;
;           int col = cb + ns * 16 + l15;
;           float v = acc[ms][ns][j];
;           if (mode == 1) { float lbv = lbp[col - C_HF]; v = __logf(lbv + (1.f - lbv) / (1.f + __expf(-v))); }
;           else if (mode == 2) v = v / (1.f + __expf(-v));
;           h[(size_t)row * HS + col] = f2bf(v);
.LBB0_2056:
	s_andn2_b64 vcc, exec, s[4:5]
	s_cbranch_vccnz .LBB0_2059
	s_cmp_eq_u32 s17, 1
	v_mov_b32_e32 v131, v30
	s_cbranch_scc0 .LBB0_2059
	v_lshl_add_u64 v[134:135], v[0:1], 2, s[14:15]
	v_add_co_u32_e32 v134, vcc, 0xfffff000, v134
	s_nop 1
	v_addc_co_u32_e32 v135, vcc, -1, v135, vcc
	v_mov_b32_e32 v131, v163
	v_mul_f32_e32 v134, 0xbfb8aa3b, v30
	v_exp_f32_e32 v134, v134
	v_sub_f32_e32 v135, 1.0, v131
	v_add_f32_e32 v134, 1.0, v134
	v_div_scale_f32 v136, s[4:5], v134, v134, v135
	v_rcp_f32_e32 v137, v136
	v_div_scale_f32 v146, vcc, v135, v134, v135
	s_mov_b32 s4, 0x800000
	v_fma_f32 v147, -v136, v137, 1.0
	v_fmac_f32_e32 v137, v147, v137
	v_mul_f32_e32 v147, v146, v137
	v_fma_f32 v148, -v136, v147, v146
	v_fmac_f32_e32 v147, v148, v137
	v_fma_f32 v136, -v136, v147, v146
	v_div_fmas_f32 v136, v136, v137, v147
	v_div_fixup_f32 v134, v136, v134, v135
	v_add_f32_e32 v131, v131, v134
	v_cmp_gt_f32_e32 vcc, s4, v131
	s_mov_b32 s4, 0x3f317217
	s_nop 0
	v_cndmask_b32_e64 v134, 0, 32, vcc
	v_ldexp_f32 v131, v131, v134
	v_log_f32_e32 v131, v131
	s_nop 0
	v_mul_f32_e32 v134, 0x3f317217, v131
	v_fma_f32 v134, v131, s4, -v134
	v_fmac_f32_e32 v134, 0x3377d1cf, v131
	s_mov_b32 s4, 0x7f800000
	v_fmac_f32_e32 v134, 0x3f317217, v131
	v_cmp_lt_f32_e64 s[12:13], |v131|, s4
	s_nop 1
	v_cndmask_b32_e64 v131, v131, v134, s[12:13]
	v_cndmask_b32_e32 v134, 0, v227, vcc
	v_sub_f32_e32 v131, v131, v134

; DEV u16 f2bf(float f) { return (u16)(pack2(f, 0.f) & 0xffffu); }
; DEV void phase_win(const Params& P, int l, const u16* __restrict__ xb, const u16* __restrict__ Wt, u16* __restrict__ h, char* smem) {
;     ...
;           int row = m0 + wm * 128 + ms * 16 + quad * 4 + j;
;           int col = cb + ns * 16 + l15;
;           float v = acc[ms][ns][j];
;           if (mode == 1) { float lbv = lbp[col - C_HF]; v = __logf(lbv + (1.f - lbv) / (1.f + __expf(-v))); }
;           else if (mode == 2) v = v / (1.f + __expf(-v));
;           h[(size_t)row * HS + col] = f2bf(v);
.LBB0_2061:
	s_andn2_b64 vcc, exec, s[4:5]
	s_cbranch_vccnz .LBB0_2064
	s_cmp_eq_u32 s17, 1
	v_mov_b32_e32 v131, v31
	s_cbranch_scc0 .LBB0_2064
	v_lshl_add_u64 v[132:133], v[0:1], 2, s[14:15]
	v_add_co_u32_e32 v132, vcc, 0xfffff000, v132
	s_nop 1
	v_addc_co_u32_e32 v133, vcc, -1, v133, vcc
	v_mov_b32_e32 v131, v163
	v_mul_f32_e32 v132, 0xbfb8aa3b, v31
	v_exp_f32_e32 v132, v132
	v_sub_f32_e32 v133, 1.0, v131
	v_add_f32_e32 v132, 1.0, v132
	v_div_scale_f32 v134, s[4:5], v132, v132, v133
	v_rcp_f32_e32 v135, v134
	v_div_scale_f32 v136, vcc, v133, v132, v133
	s_mov_b32 s4, 0x800000
	v_fma_f32 v137, -v134, v135, 1.0
	v_fmac_f32_e32 v135, v137, v135
	v_mul_f32_e32 v137, v136, v135
	v_fma_f32 v146, -v134, v137, v136
	v_fmac_f32_e32 v137, v146, v135
	v_fma_f32 v134, -v134, v137, v136
	v_div_fmas_f32 v134, v134, v135, v137
	v_div_fixup_f32 v132, v134, v132, v133
	v_add_f32_e32 v131, v131, v132
	v_cmp_gt_f32_e32 vcc, s4, v131
	s_mov_b32 s4, 0x3f317217
	s_nop 0
	v_cndmask_b32_e64 v132, 0, 32, vcc
	v_ldexp_f32 v131, v131, v132
	v_log_f32_e32 v131, v131
	s_nop 0
	v_mul_f32_e32 v132, 0x3f317217, v131
	v_fma_f32 v132, v131, s4, -v132
	v_fmac_f32_e32 v132, 0x3377d1cf, v131
	s_mov_b32 s4, 0x7f800000
	v_fmac_f32_e32 v132, 0x3f317217, v131
	v_cmp_lt_f32_e64 s[12:13], |v131|, s4
	s_nop 1
	v_cndmask_b32_e64 v131, v131, v132, s[12:13]
	v_cndmask_b32_e32 v132, 0, v227, vcc
	v_sub_f32_e32 v131, v131, v132

; DEV u16 f2bf(float f) { return (u16)(pack2(f, 0.f) & 0xffffu); }
; DEV void phase_win(const Params& P, int l, const u16* __restrict__ xb, const u16* __restrict__ Wt, u16* __restrict__ h, char* smem) {
;     ...
;           int row = m0 + wm * 128 + ms * 16 + quad * 4 + j;
;           int col = cb + ns * 16 + l15;
;           float v = acc[ms][ns][j];
;           if (mode == 1) { float lbv = lbp[col - C_HF]; v = __logf(lbv + (1.f - lbv) / (1.f + __expf(-v))); }
;           else if (mode == 2) v = v / (1.f + __expf(-v));
;           h[(size_t)row * HS + col] = f2bf(v);
.LBB0_2066:
	s_andn2_b64 vcc, exec, s[4:5]
	s_cbranch_vccnz .LBB0_2069
	s_cmp_eq_u32 s17, 1
	v_mov_b32_e32 v131, v32
	s_cbranch_scc0 .LBB0_2069
	v_lshl_add_u64 v[132:133], v[0:1], 2, s[14:15]
	v_add_co_u32_e32 v132, vcc, 0xfffff000, v132
	s_nop 1
	v_addc_co_u32_e32 v133, vcc, -1, v133, vcc
	v_mov_b32_e32 v131, v163
	v_mul_f32_e32 v132, 0xbfb8aa3b, v32
	v_exp_f32_e32 v132, v132
	v_sub_f32_e32 v133, 1.0, v131
	v_add_f32_e32 v132, 1.0, v132
	v_div_scale_f32 v134, s[4:5], v132, v132, v133
	v_rcp_f32_e32 v135, v134
	v_div_scale_f32 v136, vcc, v133, v132, v133
	s_mov_b32 s4, 0x800000
	v_fma_f32 v137, -v134, v135, 1.0
	v_fmac_f32_e32 v135, v137, v135
	v_mul_f32_e32 v137, v136, v135
	v_fma_f32 v140, -v134, v137, v136
	v_fmac_f32_e32 v137, v140, v135
	v_fma_f32 v134, -v134, v137, v136
	v_div_fmas_f32 v134, v134, v135, v137
	v_div_fixup_f32 v132, v134, v132, v133
	v_add_f32_e32 v131, v131, v132
	v_cmp_gt_f32_e32 vcc, s4, v131
	s_mov_b32 s4, 0x3f317217
	s_nop 0
	v_cndmask_b32_e64 v132, 0, 32, vcc
	v_ldexp_f32 v131, v131, v132
	v_log_f32_e32 v131, v131
	s_nop 0
	v_mul_f32_e32 v132, 0x3f317217, v131
	v_fma_f32 v132, v131, s4, -v132
	v_fmac_f32_e32 v132, 0x3377d1cf, v131
	s_mov_b32 s4, 0x7f800000
	v_fmac_f32_e32 v132, 0x3f317217, v131
	v_cmp_lt_f32_e64 s[12:13], |v131|, s4
	s_nop 1
	v_cndmask_b32_e64 v131, v131, v132, s[12:13]
	v_cndmask_b32_e32 v132, 0, v227, vcc
	v_sub_f32_e32 v131, v131, v132

; DEV u16 f2bf(float f) { return (u16)(pack2(f, 0.f) & 0xffffu); }
; DEV void phase_win(const Params& P, int l, const u16* __restrict__ xb, const u16* __restrict__ Wt, u16* __restrict__ h, char* smem) {
;     ...
;           int row = m0 + wm * 128 + ms * 16 + quad * 4 + j;
;           int col = cb + ns * 16 + l15;
;           float v = acc[ms][ns][j];
;           if (mode == 1) { float lbv = lbp[col - C_HF]; v = __logf(lbv + (1.f - lbv) / (1.f + __expf(-v))); }
;           else if (mode == 2) v = v / (1.f + __expf(-v));
;           h[(size_t)row * HS + col] = f2bf(v);
.LBB0_2071:
	s_andn2_b64 vcc, exec, s[4:5]
	s_cbranch_vccnz .LBB0_2074
	s_cmp_eq_u32 s17, 1
	v_mov_b32_e32 v131, v33
	s_cbranch_scc0 .LBB0_2074
	v_lshl_add_u64 v[132:133], v[0:1], 2, s[14:15]
	v_add_co_u32_e32 v132, vcc, 0xfffff000, v132
	v_mul_f32_e32 v131, 0xbfb8aa3b, v33
	s_nop 0
	v_addc_co_u32_e32 v133, vcc, -1, v133, vcc
	v_mov_b32_e32 v0, v163
	v_exp_f32_e32 v131, v131
	v_sub_f32_e32 v132, 1.0, v0
	v_add_f32_e32 v131, 1.0, v131
	v_div_scale_f32 v133, s[4:5], v131, v131, v132
	v_rcp_f32_e32 v134, v133
	v_div_scale_f32 v135, vcc, v132, v131, v132
	s_mov_b32 s4, 0x800000
	v_fma_f32 v136, -v133, v134, 1.0
	v_fmac_f32_e32 v134, v136, v134
	v_mul_f32_e32 v136, v135, v134
	v_fma_f32 v137, -v133, v136, v135
	v_fmac_f32_e32 v136, v137, v134
	v_fma_f32 v133, -v133, v136, v135
	v_div_fmas_f32 v133, v133, v134, v136
	v_div_fixup_f32 v131, v133, v131, v132
	v_add_f32_e32 v0, v0, v131
	v_cmp_gt_f32_e32 vcc, s4, v0
	s_mov_b32 s4, 0x3f317217
	s_nop 0
	v_cndmask_b32_e64 v131, 0, 32, vcc
	v_ldexp_f32 v0, v0, v131
	v_log_f32_e32 v0, v0
	s_nop 0
	v_mul_f32_e32 v131, 0x3f317217, v0
	v_fma_f32 v131, v0, s4, -v131
	v_fmac_f32_e32 v131, 0x3377d1cf, v0
	s_mov_b32 s4, 0x7f800000
	v_fmac_f32_e32 v131, 0x3f317217, v0
	v_cmp_lt_f32_e64 s[12:13], |v0|, s4
	s_nop 1
	v_cndmask_b32_e64 v0, v0, v131, s[12:13]
	v_cndmask_b32_e32 v131, 0, v227, vcc
	v_sub_f32_e32 v131, v0, v131

; DEV u16 f2bf(float f) { return (u16)(pack2(f, 0.f) & 0xffffu); }
; DEV void phase_win(const Params& P, int l, const u16* __restrict__ xb, const u16* __restrict__ Wt, u16* __restrict__ h, char* smem) {
;     ...
;       const int dst = (cb < 256) ? (C_NQR + cb) : cb;
; #pragma unroll
;       for (int ms = 0; ms < 8; ++ms) {
;       asm volatile("" ::: "memory");
; #pragma unroll
;         for (int j = 0; j < 4; ++j) {
;           int row = m0 + wm * 128 + ms * 16 + quad * 4 + j;
;           int pos = row & (S - 1);
;           u16* hr = h + (size_t)row * HS;
; #pragma unroll
;           for (int ns = 0; ns < 2; ++ns) {
;             int d1 = ns * 16 + l15;
;             float x1 = acc[ms][ns][j], x2 = acc[ms][ns + 2][j];
;             float cs = cosT[pos * 32 + d1], sn = sinT[pos * 32 + d1];
;             hr[dst + d1] = f2bf(x1 * cs - x2 * sn);
;             hr[dst + d1 + 32] = f2bf(x1 * sn + x2 * cs);
;             if (cb < 256) {
;               hr[cb + d1] = f2bf(x1);
;               hr[cb + d1 + 32] = f2bf(x2);
;             }
;           }
.LBB0_2077:
	s_or_b64 exec, exec, s[22:23]
	s_and_saveexec_b64 s[12:13], s[4:5]
	s_cbranch_execz .LBB0_2206
	v_add_u32_e32 v0, 0xc80, v130
	v_cndmask_b32_e64 v136, v130, v0, s[10:11]
	v_add_u32_e32 v0, s16, v178
	v_mov_b64_e32 v[132:133], s[72:73]
	s_movk_i32 s4, 0x1b00
	v_lshlrev_b32_e32 v131, 5, v0
	v_mad_i64_i32 v[138:139], s[4:5], v0, s4, v[132:133]
	v_and_b32_e32 v131, 0x1f180, v131
	v_or_b32_e32 v132, v131, v186
	v_add_u32_e32 v160, s16, v178
	v_lshlrev_b32_e32 v160, 5, v160
	v_and_b32_e32 v160, 0x1f180, v160
	v_or_b32_e32 v160, v160, v186
	v_lshlrev_b32_e32 v160, 2, v160
	v_mov_b32_e32 v161, v160
	v_readlane_b32 s4, v252, 58
	v_readlane_b32 s5, v252, 59
	s_nop 4
	global_load_dword v144, v161, s[4:5]
	global_load_dword v145, v161, s[4:5] offset:64
	global_load_dword v146, v161, s[4:5] offset:128
	global_load_dword v147, v161, s[4:5] offset:192
	global_load_dword v148, v161, s[4:5] offset:256
	global_load_dword v149, v161, s[4:5] offset:320
	global_load_dword v150, v161, s[4:5] offset:384
	global_load_dword v151, v161, s[4:5] offset:448
	v_readlane_b32 s4, v252, 60
	v_readlane_b32 s5, v252, 61
	s_nop 4
	global_load_dword v152, v161, s[4:5]
	global_load_dword v153, v161, s[4:5] offset:64
	global_load_dword v154, v161, s[4:5] offset:128
	global_load_dword v155, v161, s[4:5] offset:192
	global_load_dword v156, v161, s[4:5] offset:256
	global_load_dword v157, v161, s[4:5] offset:320
	global_load_dword v158, v161, s[4:5] offset:384
	global_load_dword v159, v161, s[4:5] offset:448
	s_waitcnt vmcnt(0)
	v_readlane_b32 s4, v252, 58
	v_lshlrev_b32_e32 v132, 2, v132
	v_readlane_b32 s5, v252, 59
	s_nop 4
	v_mov_b32_e32 v137, v144
	v_readlane_b32 s4, v252, 60
	v_readlane_b32 s5, v252, 61
	s_nop 4
	v_mov_b32_e32 v140, v152
	v_mul_f32_e32 v132, v126, v140
	v_fma_f32 v132, v38, v137, -v132
	v_cvt_pk_bf16_f32 v141, v132, s0
	v_or_b32_e32 v132, v136, v186
	v_mul_f32_e32 v140, v38, v140
	v_ashrrev_i32_e32 v133, 31, v132
	v_fmac_f32_e32 v140, v126, v137
	v_lshl_add_u64 v[134:135], v[132:133], 1, v[138:139]
	v_cvt_pk_bf16_f32 v137, v140, s0
	global_store_short v[134:135], v141, off
	global_store_short v[134:135], v137, off offset:64
	v_or_b32_e32 v134, v130, v186
	v_ashrrev_i32_e32 v135, 31, v134
	s_and_saveexec_b64 s[4:5], s[10:11]
	s_cbranch_execz .LBB0_2080
	v_cvt_pk_bf16_f32 v137, v38, s0
	v_lshl_add_u64 v[140:141], v[134:135], 1, v[138:139]
	v_cvt_pk_bf16_f32 v126, v126, s0
	global_store_short v[140:141], v137, off
	global_store_short v[140:141], v126, off offset:64
.LBB0_2080:
	s_or_b64 exec, exec, s[4:5]
	v_or_b32_e32 v126, v131, v240
	v_readlane_b32 s4, v252, 58
	v_lshlrev_b32_e32 v126, 2, v126
	v_readlane_b32 s5, v252, 59
	s_nop 4
	v_mov_b32_e32 v131, v145
	v_readlane_b32 s4, v252, 60
	v_readlane_b32 s5, v252, 61
	s_nop 4
	v_mov_b32_e32 v126, v153
	v_mul_f32_e32 v137, v118, v126
	v_fma_f32 v137, v122, v131, -v137
	v_cvt_pk_bf16_f32 v142, v137, s0
	v_ashrrev_i32_e32 v137, 31, v136
	v_mul_f32_e32 v126, v122, v126
	v_lshl_add_u64 v[136:137], v[136:137], 0, v[186:187]
	v_fmac_f32_e32 v126, v118, v131
	v_lshl_add_u64 v[140:141], v[136:137], 1, v[138:139]
	v_cvt_pk_bf16_f32 v126, v126, s0
	v_ashrrev_i32_e32 v131, 31, v130
	global_store_short v[140:141], v142, off offset:32
	global_store_short v[140:141], v126, off offset:96
	s_and_saveexec_b64 s[4:5], s[10:11]
	s_cbranch_execz .LBB0_2082
	v_lshl_add_u64 v[140:141], v[130:131], 0, v[186:187]
	v_cvt_pk_bf16_f32 v122, v122, s0
	v_lshl_add_u64 v[138:139], v[140:141], 1, v[138:139]
	v_cvt_pk_bf16_f32 v118, v118, s0
	global_store_short v[138:139], v122, off offset:32
	global_store_short v[138:139], v118, off offset:96
.LBB0_2082:
	s_or_b64 exec, exec, s[4:5]
	v_or_b32_e32 v118, 1, v0
	v_mov_b64_e32 v[138:139], s[72:73]
	s_movk_i32 s4, 0x1b00
	v_mad_i64_i32 v[138:139], s[4:5], v118, s4, v[138:139]
	v_lshlrev_b32_e32 v118, 5, v118
	v_and_b32_e32 v118, 0x1f1a0, v118
	v_or_b32_e32 v122, v118, v186
	v_readlane_b32 s4, v252, 58
	v_lshlrev_b32_e32 v122, 2, v122
	v_readlane_b32 s5, v252, 59
	s_nop 4
	v_mov_b32_e32 v126, v146
	v_readlane_b32 s4, v252, 60
	v_readlane_b32 s5, v252, 61
	s_nop 4
	v_mov_b32_e32 v122, v154
	v_mul_f32_e32 v140, v127, v122
	v_mul_f32_e32 v122, v39, v122
	v_fma_f32 v140, v39, v126, -v140
	v_fmac_f32_e32 v122, v127, v126
	v_cvt_pk_bf16_f32 v142, v140, s0
	v_lshl_add_u64 v[140:141], v[132:133], 1, v[138:139]
	v_cvt_pk_bf16_f32 v122, v122, s0
	global_store_short v[140:141], v142, off
	global_store_short v[140:141], v122, off offset:64
	s_and_saveexec_b64 s[4:5], s[10:11]
	s_cbranch_execz .LBB0_2084
	v_cvt_pk_bf16_f32 v122, v39, s0
	v_cvt_pk_bf16_f32 v140, v127, s0
	v_lshl_add_u64 v[126:127], v[134:135], 1, v[138:139]
	global_store_short v[126:127], v122, off
	global_store_short v[126:127], v140, off offset:64
.LBB0_2084:
	s_or_b64 exec, exec, s[4:5]
	v_or_b32_e32 v118, v118, v240
	v_readlane_b32 s4, v252, 58
	v_lshlrev_b32_e32 v118, 2, v118
	v_readlane_b32 s5, v252, 59
	s_nop 4
	v_mov_b32_e32 v122, v147
	v_readlane_b32 s4, v252, 60
	v_readlane_b32 s5, v252, 61
	s_nop 4
	v_mov_b32_e32 v118, v155
	v_mul_f32_e32 v126, v119, v118
	v_mul_f32_e32 v118, v123, v118
	v_fma_f32 v126, v123, v122, -v126
	v_fmac_f32_e32 v118, v119, v122
	v_cvt_pk_bf16_f32 v140, v126, s0
	v_lshl_add_u64 v[126:127], v[136:137], 1, v[138:139]
	v_cvt_pk_bf16_f32 v118, v118, s0
	global_store_short v[126:127], v140, off offset:32
	global_store_short v[126:127], v118, off offset:96
	s_and_saveexec_b64 s[4:5], s[10:11]
	s_cbranch_execz .LBB0_2086
	v_cvt_pk_bf16_f32 v122, v123, s0
	v_cvt_pk_bf16_f32 v123, v119, s0
	v_lshl_add_u64 v[118:119], v[130:131], 0, v[186:187]
	v_lshl_add_u64 v[118:119], v[118:119], 1, v[138:139]
	global_store_short v[118:119], v122, off offset:32
	global_store_short v[118:119], v123, off offset:96
; DEV u16 f2bf(float f) { return (u16)(pack2(f, 0.f) & 0xffffu); }
; DEV void phase_win(const Params& P, int l, const u16* __restrict__ xb, const u16* __restrict__ Wt, u16* __restrict__ h, char* smem) {
;     ...
;       const int dst = (cb < 256) ? (C_NQR + cb) : cb;
; #pragma unroll
;       for (int ms = 0; ms < 8; ++ms) {
;       asm volatile("" ::: "memory");
; #pragma unroll
;         for (int j = 0; j < 4; ++j) {
;           int row = m0 + wm * 128 + ms * 16 + quad * 4 + j;
;           int pos = row & (S - 1);
;           u16* hr = h + (size_t)row * HS;
; #pragma unroll
;           for (int ns = 0; ns < 2; ++ns) {
;             int d1 = ns * 16 + l15;
;             float x1 = acc[ms][ns][j], x2 = acc[ms][ns + 2][j];
;             float cs = cosT[pos * 32 + d1], sn = sinT[pos * 32 + d1];
;             hr[dst + d1] = f2bf(x1 * cs - x2 * sn);
;             hr[dst + d1 + 32] = f2bf(x1 * sn + x2 * cs);
;             if (cb < 256) {
;               hr[cb + d1] = f2bf(x1);
;               hr[cb + d1 + 32] = f2bf(x2);
;             }
;           }
.LBB0_2086:
	s_or_b64 exec, exec, s[4:5]
	v_or_b32_e32 v122, 2, v0
	v_mov_b64_e32 v[118:119], s[72:73]
	s_movk_i32 s4, 0x1b00
	v_mad_i64_i32 v[118:119], s[4:5], v122, s4, v[118:119]
	v_lshlrev_b32_e32 v122, 5, v122
	v_and_b32_e32 v122, 0x1f1c0, v122
	v_or_b32_e32 v123, v122, v186
	v_readlane_b32 s4, v252, 58
	v_lshlrev_b32_e32 v123, 2, v123
	v_readlane_b32 s5, v252, 59
	s_nop 4
	v_mov_b32_e32 v138, v148
	v_readlane_b32 s4, v252, 60
	v_readlane_b32 s5, v252, 61
	s_nop 4
	v_mov_b32_e32 v123, v156
	v_mul_f32_e32 v126, v128, v123
	v_mul_f32_e32 v123, v40, v123
	v_fma_f32 v126, v40, v138, -v126
	v_fmac_f32_e32 v123, v128, v138
	v_cvt_pk_bf16_f32 v139, v126, s0
	v_lshl_add_u64 v[126:127], v[132:133], 1, v[118:119]
	v_cvt_pk_bf16_f32 v123, v123, s0
	global_store_short v[126:127], v139, off
	global_store_short v[126:127], v123, off offset:64
	s_and_saveexec_b64 s[4:5], s[10:11]
	s_cbranch_execz .LBB0_2088
	v_cvt_pk_bf16_f32 v123, v40, s0
	v_lshl_add_u64 v[126:127], v[134:135], 1, v[118:119]
	v_cvt_pk_bf16_f32 v128, v128, s0
	global_store_short v[126:127], v123, off
	global_store_short v[126:127], v128, off offset:64
.LBB0_2088:
	s_or_b64 exec, exec, s[4:5]
	v_or_b32_e32 v122, v122, v240
	v_readlane_b32 s4, v252, 58
	v_lshlrev_b32_e32 v122, 2, v122
	v_readlane_b32 s5, v252, 59
	s_nop 4
	v_mov_b32_e32 v126, v149
	v_readlane_b32 s4, v252, 60
	v_readlane_b32 s5, v252, 61
	s_nop 4
	v_mov_b32_e32 v127, v157
	v_mul_f32_e32 v122, v120, v127
	v_mul_f32_e32 v127, v124, v127
	v_fma_f32 v122, v124, v126, -v122
	v_fmac_f32_e32 v127, v120, v126
	v_cvt_pk_bf16_f32 v128, v122, s0
	v_lshl_add_u64 v[122:123], v[136:137], 1, v[118:119]
	v_cvt_pk_bf16_f32 v126, v127, s0
	global_store_short v[122:123], v128, off offset:32
	global_store_short v[122:123], v126, off offset:96
	s_and_saveexec_b64 s[4:5], s[10:11]
	s_cbranch_execz .LBB0_2090
	v_lshl_add_u64 v[122:123], v[130:131], 0, v[186:187]
	v_cvt_pk_bf16_f32 v124, v124, s0
	v_lshl_add_u64 v[118:119], v[122:123], 1, v[118:119]
	v_cvt_pk_bf16_f32 v120, v120, s0
	global_store_short v[118:119], v124, off offset:32
	global_store_short v[118:119], v120, off offset:96
.LBB0_2090:
	s_or_b64 exec, exec, s[4:5]
	v_or_b32_e32 v0, 3, v0
	v_mov_b64_e32 v[118:119], s[72:73]
	s_movk_i32 s4, 0x1b00
	v_mad_i64_i32 v[118:119], s[4:5], v0, s4, v[118:119]
	v_lshlrev_b32_e32 v0, 5, v0
	v_and_b32_e32 v0, 0x1f1e0, v0
	v_or_b32_e32 v120, v0, v186
	v_readlane_b32 s4, v252, 58
	v_lshlrev_b32_e32 v120, 2, v120
	v_readlane_b32 s5, v252, 59
	s_nop 4
	v_mov_b32_e32 v124, v150
	v_readlane_b32 s4, v252, 60
	v_readlane_b32 s5, v252, 61
	s_nop 4
	v_mov_b32_e32 v120, v158
	v_mul_f32_e32 v122, v129, v120
	v_mul_f32_e32 v120, v41, v120
	v_fma_f32 v122, v41, v124, -v122
	v_fmac_f32_e32 v120, v129, v124
	v_cvt_pk_bf16_f32 v126, v122, s0
	v_lshl_add_u64 v[122:123], v[132:133], 1, v[118:119]
	v_cvt_pk_bf16_f32 v120, v120, s0
	global_store_short v[122:123], v126, off
	global_store_short v[122:123], v120, off offset:64
	s_and_saveexec_b64 s[4:5], s[10:11]
	s_cbranch_execz .LBB0_2092
	v_cvt_pk_bf16_f32 v120, v41, s0
	v_lshl_add_u64 v[122:123], v[134:135], 1, v[118:119]
	v_cvt_pk_bf16_f32 v124, v129, s0
	global_store_short v[122:123], v120, off
	global_store_short v[122:123], v124, off offset:64
.LBB0_2092:
	s_or_b64 exec, exec, s[4:5]
	v_or_b32_e32 v0, v0, v240
	v_readlane_b32 s4, v252, 58
	v_lshlrev_b32_e32 v0, 2, v0
	v_readlane_b32 s5, v252, 59
	s_nop 4
	v_mov_b32_e32 v120, v151
	v_readlane_b32 s4, v252, 60
	v_readlane_b32 s5, v252, 61
	s_nop 4
	v_mov_b32_e32 v0, v159
	v_mul_f32_e32 v122, v121, v0
	v_mul_f32_e32 v0, v125, v0
	v_fma_f32 v122, v125, v120, -v122
	v_fmac_f32_e32 v0, v121, v120
	v_cvt_pk_bf16_f32 v124, v122, s0
	v_lshl_add_u64 v[122:123], v[136:137], 1, v[118:119]
	v_cvt_pk_bf16_f32 v0, v0, s0
	global_store_short v[122:123], v124, off offset:32
	global_store_short v[122:123], v0, off offset:96
	s_and_saveexec_b64 s[4:5], s[10:11]
	s_cbranch_execz .LBB0_2094
	v_cvt_pk_bf16_f32 v122, v121, s0
	v_lshl_add_u64 v[120:121], v[130:131], 0, v[186:187]
	v_cvt_pk_bf16_f32 v0, v125, s0
	v_lshl_add_u64 v[118:119], v[120:121], 1, v[118:119]
	global_store_short v[118:119], v0, off offset:32
	global_store_short v[118:119], v122, off offset:96
.LBB0_2094:
	s_or_b64 exec, exec, s[4:5]
	v_add_u32_e32 v0, s16, v184
	v_mov_b64_e32 v[118:119], s[72:73]
	s_movk_i32 s4, 0x1b00
	v_lshlrev_b32_e32 v120, 5, v0
	v_mad_i64_i32 v[118:119], s[4:5], v0, s4, v[118:119]
	v_and_b32_e32 v120, 0x1f380, v120
	v_or_b32_e32 v121, v120, v186
	v_add_u32_e32 v161, 0x800, v160
	v_readlane_b32 s4, v252, 58
	v_readlane_b32 s5, v252, 59
	s_nop 4
	global_load_dword v144, v161, s[4:5]
	global_load_dword v145, v161, s[4:5] offset:64
	global_load_dword v146, v161, s[4:5] offset:128
	global_load_dword v147, v161, s[4:5] offset:192
	global_load_dword v148, v161, s[4:5] offset:256
	global_load_dword v149, v161, s[4:5] offset:320
	global_load_dword v150, v161, s[4:5] offset:384
	global_load_dword v151, v161, s[4:5] offset:448
	v_readlane_b32 s4, v252, 60
	v_readlane_b32 s5, v252, 61
	s_nop 4
	global_load_dword v152, v161, s[4:5]
	global_load_dword v153, v161, s[4:5] offset:64
	global_load_dword v154, v161, s[4:5] offset:128
	global_load_dword v155, v161, s[4:5] offset:192
	global_load_dword v156, v161, s[4:5] offset:256
	global_load_dword v157, v161, s[4:5] offset:320
	global_load_dword v158, v161, s[4:5] offset:384
	global_load_dword v159, v161, s[4:5] offset:448
	s_waitcnt vmcnt(0)
	v_readlane_b32 s4, v252, 58
	v_lshlrev_b32_e32 v121, 2, v121
	v_readlane_b32 s5, v252, 59
	s_nop 4
	v_mov_b32_e32 v124, v144
	v_readlane_b32 s4, v252, 60
	v_readlane_b32 s5, v252, 61
	s_nop 4
	v_mov_b32_e32 v121, v152
	v_mul_f32_e32 v122, v114, v121
	v_mul_f32_e32 v121, v26, v121
	v_fma_f32 v122, v26, v124, -v122
	v_fmac_f32_e32 v121, v114, v124
	v_cvt_pk_bf16_f32 v125, v122, s0
	v_lshl_add_u64 v[122:123], v[132:133], 1, v[118:119]
	v_cvt_pk_bf16_f32 v121, v121, s0
	global_store_short v[122:123], v125, off
	global_store_short v[122:123], v121, off offset:64
	s_and_saveexec_b64 s[4:5], s[10:11]
	s_cbranch_execz .LBB0_2096
	v_cvt_pk_bf16_f32 v121, v26, s0
	v_lshl_add_u64 v[122:123], v[134:135], 1, v[118:119]
	v_cvt_pk_bf16_f32 v114, v114, s0
	global_store_short v[122:123], v121, off
	global_store_short v[122:123], v114, off offset:64
; DEV u16 f2bf(float f) { return (u16)(pack2(f, 0.f) & 0xffffu); }
; DEV void phase_win(const Params& P, int l, const u16* __restrict__ xb, const u16* __restrict__ Wt, u16* __restrict__ h, char* smem) {
;     ...
;       const int dst = (cb < 256) ? (C_NQR + cb) : cb;
; #pragma unroll
;       for (int ms = 0; ms < 8; ++ms) {
;       asm volatile("" ::: "memory");
; #pragma unroll
;         for (int j = 0; j < 4; ++j) {
;           int row = m0 + wm * 128 + ms * 16 + quad * 4 + j;
;           int pos = row & (S - 1);
;           u16* hr = h + (size_t)row * HS;
; #pragma unroll
;           for (int ns = 0; ns < 2; ++ns) {
;             int d1 = ns * 16 + l15;
;             float x1 = acc[ms][ns][j], x2 = acc[ms][ns + 2][j];
;             float cs = cosT[pos * 32 + d1], sn = sinT[pos * 32 + d1];
;             hr[dst + d1] = f2bf(x1 * cs - x2 * sn);
;             hr[dst + d1 + 32] = f2bf(x1 * sn + x2 * cs);
;             if (cb < 256) {
;               hr[cb + d1] = f2bf(x1);
;               hr[cb + d1 + 32] = f2bf(x2);
;             }
;           }
.LBB0_2096:
	s_or_b64 exec, exec, s[4:5]
	v_or_b32_e32 v114, v120, v240
	v_readlane_b32 s4, v252, 58
	v_lshlrev_b32_e32 v114, 2, v114
	v_readlane_b32 s5, v252, 59
	s_nop 4
	v_mov_b32_e32 v122, v145
	v_readlane_b32 s4, v252, 60
	v_readlane_b32 s5, v252, 61
	s_nop 4
	v_mov_b32_e32 v114, v153
	v_mul_f32_e32 v120, v106, v114
	v_mul_f32_e32 v114, v110, v114
	v_fma_f32 v120, v110, v122, -v120
	v_fmac_f32_e32 v114, v106, v122
	v_cvt_pk_bf16_f32 v123, v120, s0
	v_lshl_add_u64 v[120:121], v[136:137], 1, v[118:119]
	v_cvt_pk_bf16_f32 v114, v114, s0
	global_store_short v[120:121], v123, off offset:32
	global_store_short v[120:121], v114, off offset:96
	s_and_saveexec_b64 s[4:5], s[10:11]
	s_cbranch_execz .LBB0_2098
	v_lshl_add_u64 v[120:121], v[130:131], 0, v[186:187]
	v_cvt_pk_bf16_f32 v110, v110, s0
	v_lshl_add_u64 v[118:119], v[120:121], 1, v[118:119]
	v_cvt_pk_bf16_f32 v106, v106, s0
	global_store_short v[118:119], v110, off offset:32
	global_store_short v[118:119], v106, off offset:96
.LBB0_2098:
	s_or_b64 exec, exec, s[4:5]
	v_or_b32_e32 v106, 1, v0
	v_mov_b64_e32 v[118:119], s[72:73]
	s_movk_i32 s4, 0x1b00
	v_mad_i64_i32 v[118:119], s[4:5], v106, s4, v[118:119]
	v_lshlrev_b32_e32 v106, 5, v106
	v_and_b32_e32 v106, 0x1ffe0, v106
	v_or_b32_e32 v110, v106, v186
	v_readlane_b32 s4, v252, 58
	v_lshlrev_b32_e32 v110, 2, v110
	v_readlane_b32 s5, v252, 59
	s_nop 4
	v_mov_b32_e32 v114, v146
	v_readlane_b32 s4, v252, 60
	v_readlane_b32 s5, v252, 61
	s_nop 4
	v_mov_b32_e32 v110, v154
	v_mul_f32_e32 v120, v115, v110
	v_mul_f32_e32 v110, v27, v110
	v_fma_f32 v120, v27, v114, -v120
	v_fmac_f32_e32 v110, v115, v114
	v_cvt_pk_bf16_f32 v122, v120, s0
	v_lshl_add_u64 v[120:121], v[132:133], 1, v[118:119]
	v_cvt_pk_bf16_f32 v110, v110, s0
	global_store_short v[120:121], v122, off
	global_store_short v[120:121], v110, off offset:64
	s_and_saveexec_b64 s[4:5], s[10:11]
	s_cbranch_execz .LBB0_2100
	v_cvt_pk_bf16_f32 v110, v27, s0
	v_cvt_pk_bf16_f32 v120, v115, s0
	v_lshl_add_u64 v[114:115], v[134:135], 1, v[118:119]
	global_store_short v[114:115], v110, off
	global_store_short v[114:115], v120, off offset:64
.LBB0_2100:
	s_or_b64 exec, exec, s[4:5]
	v_or_b32_e32 v106, v106, v240
	v_readlane_b32 s4, v252, 58
	v_lshlrev_b32_e32 v106, 2, v106
	v_readlane_b32 s5, v252, 59
	s_nop 4
	v_mov_b32_e32 v110, v147
	v_readlane_b32 s4, v252, 60
	v_readlane_b32 s5, v252, 61
	s_nop 4
	v_mov_b32_e32 v106, v155
	v_mul_f32_e32 v114, v107, v106
	v_mul_f32_e32 v106, v111, v106
	v_fma_f32 v114, v111, v110, -v114
	v_fmac_f32_e32 v106, v107, v110
	v_cvt_pk_bf16_f32 v120, v114, s0
	v_lshl_add_u64 v[114:115], v[136:137], 1, v[118:119]
	v_cvt_pk_bf16_f32 v106, v106, s0
	global_store_short v[114:115], v120, off offset:32
	global_store_short v[114:115], v106, off offset:96
	s_and_saveexec_b64 s[4:5], s[10:11]
	s_cbranch_execz .LBB0_2102
	v_cvt_pk_bf16_f32 v110, v111, s0
	v_cvt_pk_bf16_f32 v111, v107, s0
	v_lshl_add_u64 v[106:107], v[130:131], 0, v[186:187]
	v_lshl_add_u64 v[106:107], v[106:107], 1, v[118:119]
	global_store_short v[106:107], v110, off offset:32
	global_store_short v[106:107], v111, off offset:96
.LBB0_2102:
	s_or_b64 exec, exec, s[4:5]
	v_or_b32_e32 v110, 2, v0
	v_mov_b64_e32 v[106:107], s[72:73]
	s_movk_i32 s4, 0x1b00
	v_mad_i64_i32 v[106:107], s[4:5], v110, s4, v[106:107]
	v_lshlrev_b32_e32 v110, 5, v110
	v_and_b32_e32 v110, 0x1ffe0, v110
	v_or_b32_e32 v111, v110, v186
	v_readlane_b32 s4, v252, 58
	v_lshlrev_b32_e32 v111, 2, v111
	v_readlane_b32 s5, v252, 59
	s_nop 4
	v_mov_b32_e32 v118, v148
	v_readlane_b32 s4, v252, 60
	v_readlane_b32 s5, v252, 61
	s_nop 4
	v_mov_b32_e32 v111, v156
	v_mul_f32_e32 v114, v116, v111
	v_mul_f32_e32 v111, v28, v111
	v_fma_f32 v114, v28, v118, -v114
	v_fmac_f32_e32 v111, v116, v118
	v_cvt_pk_bf16_f32 v119, v114, s0
	v_lshl_add_u64 v[114:115], v[132:133], 1, v[106:107]
	v_cvt_pk_bf16_f32 v111, v111, s0
	global_store_short v[114:115], v119, off
	global_store_short v[114:115], v111, off offset:64
	s_and_saveexec_b64 s[4:5], s[10:11]
	s_cbranch_execz .LBB0_2104
	v_cvt_pk_bf16_f32 v111, v28, s0
	v_lshl_add_u64 v[114:115], v[134:135], 1, v[106:107]
	v_cvt_pk_bf16_f32 v116, v116, s0
	global_store_short v[114:115], v111, off
	global_store_short v[114:115], v116, off offset:64
.LBB0_2104:
	s_or_b64 exec, exec, s[4:5]
	v_or_b32_e32 v110, v110, v240
	v_readlane_b32 s4, v252, 58
	v_lshlrev_b32_e32 v110, 2, v110
	v_readlane_b32 s5, v252, 59
	s_nop 4
	v_mov_b32_e32 v114, v149
	v_readlane_b32 s4, v252, 60
	v_readlane_b32 s5, v252, 61
	s_nop 4
	v_mov_b32_e32 v115, v157
	v_mul_f32_e32 v110, v108, v115
	v_mul_f32_e32 v115, v112, v115
	v_fma_f32 v110, v112, v114, -v110
	v_fmac_f32_e32 v115, v108, v114
	v_cvt_pk_bf16_f32 v116, v110, s0
	v_lshl_add_u64 v[110:111], v[136:137], 1, v[106:107]
	v_cvt_pk_bf16_f32 v114, v115, s0
	global_store_short v[110:111], v116, off offset:32
	global_store_short v[110:111], v114, off offset:96
	s_and_saveexec_b64 s[4:5], s[10:11]
	s_cbranch_execz .LBB0_2106
	v_lshl_add_u64 v[110:111], v[130:131], 0, v[186:187]
	v_cvt_pk_bf16_f32 v112, v112, s0
	v_lshl_add_u64 v[106:107], v[110:111], 1, v[106:107]
	v_cvt_pk_bf16_f32 v108, v108, s0
	global_store_short v[106:107], v112, off offset:32
	global_store_short v[106:107], v108, off offset:96
; DEV u16 f2bf(float f) { return (u16)(pack2(f, 0.f) & 0xffffu); }
; DEV void phase_win(const Params& P, int l, const u16* __restrict__ xb, const u16* __restrict__ Wt, u16* __restrict__ h, char* smem) {
;     ...
;       const int dst = (cb < 256) ? (C_NQR + cb) : cb;
; #pragma unroll
;       for (int ms = 0; ms < 8; ++ms) {
;       asm volatile("" ::: "memory");
; #pragma unroll
;         for (int j = 0; j < 4; ++j) {
;           int row = m0 + wm * 128 + ms * 16 + quad * 4 + j;
;           int pos = row & (S - 1);
;           u16* hr = h + (size_t)row * HS;
; #pragma unroll
;           for (int ns = 0; ns < 2; ++ns) {
;             int d1 = ns * 16 + l15;
;             float x1 = acc[ms][ns][j], x2 = acc[ms][ns + 2][j];
;             float cs = cosT[pos * 32 + d1], sn = sinT[pos * 32 + d1];
;             hr[dst + d1] = f2bf(x1 * cs - x2 * sn);
;             hr[dst + d1 + 32] = f2bf(x1 * sn + x2 * cs);
;             if (cb < 256) {
;               hr[cb + d1] = f2bf(x1);
;               hr[cb + d1 + 32] = f2bf(x2);
;             }
;           }
.LBB0_2106:
	s_or_b64 exec, exec, s[4:5]
	v_or_b32_e32 v0, 3, v0
	v_mov_b64_e32 v[106:107], s[72:73]
	s_movk_i32 s4, 0x1b00
	v_mad_i64_i32 v[106:107], s[4:5], v0, s4, v[106:107]
	v_lshlrev_b32_e32 v0, 5, v0
	v_and_b32_e32 v0, 0x1ffe0, v0
	v_or_b32_e32 v108, v0, v186
	v_readlane_b32 s4, v252, 58
	v_lshlrev_b32_e32 v108, 2, v108
	v_readlane_b32 s5, v252, 59
	s_nop 4
	v_mov_b32_e32 v112, v150
	v_readlane_b32 s4, v252, 60
	v_readlane_b32 s5, v252, 61
	s_nop 4
	v_mov_b32_e32 v108, v158
	v_mul_f32_e32 v110, v117, v108
	v_mul_f32_e32 v108, v29, v108
	v_fma_f32 v110, v29, v112, -v110
	v_fmac_f32_e32 v108, v117, v112
	v_cvt_pk_bf16_f32 v114, v110, s0
	v_lshl_add_u64 v[110:111], v[132:133], 1, v[106:107]
	v_cvt_pk_bf16_f32 v108, v108, s0
	global_store_short v[110:111], v114, off
	global_store_short v[110:111], v108, off offset:64
	s_and_saveexec_b64 s[4:5], s[10:11]
	s_cbranch_execz .LBB0_2108
	v_cvt_pk_bf16_f32 v108, v29, s0
	v_lshl_add_u64 v[110:111], v[134:135], 1, v[106:107]
	v_cvt_pk_bf16_f32 v112, v117, s0
	global_store_short v[110:111], v108, off
	global_store_short v[110:111], v112, off offset:64
.LBB0_2108:
	s_or_b64 exec, exec, s[4:5]
	v_or_b32_e32 v0, v0, v240
	v_readlane_b32 s4, v252, 58
	v_lshlrev_b32_e32 v0, 2, v0
	v_readlane_b32 s5, v252, 59
	s_nop 4
	v_mov_b32_e32 v108, v151
	v_readlane_b32 s4, v252, 60
	v_readlane_b32 s5, v252, 61
	s_nop 4
	v_mov_b32_e32 v0, v159
	v_mul_f32_e32 v110, v109, v0
	v_mul_f32_e32 v0, v113, v0
	v_fma_f32 v110, v113, v108, -v110
	v_fmac_f32_e32 v0, v109, v108
	v_cvt_pk_bf16_f32 v112, v110, s0
	v_lshl_add_u64 v[110:111], v[136:137], 1, v[106:107]
	v_cvt_pk_bf16_f32 v0, v0, s0
	global_store_short v[110:111], v112, off offset:32
	global_store_short v[110:111], v0, off offset:96
	s_and_saveexec_b64 s[4:5], s[10:11]
	s_cbranch_execz .LBB0_2110
	v_cvt_pk_bf16_f32 v110, v109, s0
	v_lshl_add_u64 v[108:109], v[130:131], 0, v[186:187]
	v_cvt_pk_bf16_f32 v0, v113, s0
	v_lshl_add_u64 v[106:107], v[108:109], 1, v[106:107]
	global_store_short v[106:107], v0, off offset:32
	global_store_short v[106:107], v110, off offset:96
.LBB0_2110:
	s_or_b64 exec, exec, s[4:5]
	v_add_u32_e32 v0, s16, v234
	v_mov_b64_e32 v[106:107], s[72:73]
	s_movk_i32 s4, 0x1b00
	v_lshlrev_b32_e32 v108, 5, v0
	v_mad_i64_i32 v[106:107], s[4:5], v0, s4, v[106:107]
	v_and_b32_e32 v108, 0x1f580, v108
	v_or_b32_e32 v109, v108, v186
	v_add_u32_e32 v161, 0x1000, v160
	v_readlane_b32 s4, v252, 58
	v_readlane_b32 s5, v252, 59
	s_nop 4
	global_load_dword v144, v161, s[4:5]
	global_load_dword v145, v161, s[4:5] offset:64
	global_load_dword v146, v161, s[4:5] offset:128
	global_load_dword v147, v161, s[4:5] offset:192
	global_load_dword v148, v161, s[4:5] offset:256
	global_load_dword v149, v161, s[4:5] offset:320
	global_load_dword v150, v161, s[4:5] offset:384
	global_load_dword v151, v161, s[4:5] offset:448
	v_readlane_b32 s4, v252, 60
	v_readlane_b32 s5, v252, 61
	s_nop 4
	global_load_dword v152, v161, s[4:5]
	global_load_dword v153, v161, s[4:5] offset:64
	global_load_dword v154, v161, s[4:5] offset:128
	global_load_dword v155, v161, s[4:5] offset:192
	global_load_dword v156, v161, s[4:5] offset:256
	global_load_dword v157, v161, s[4:5] offset:320
	global_load_dword v158, v161, s[4:5] offset:384
	global_load_dword v159, v161, s[4:5] offset:448
	s_waitcnt vmcnt(0)
	v_readlane_b32 s4, v252, 58
	v_lshlrev_b32_e32 v109, 2, v109
	v_readlane_b32 s5, v252, 59
	s_nop 4
	v_mov_b32_e32 v112, v144
	v_readlane_b32 s4, v252, 60
	v_readlane_b32 s5, v252, 61
	s_nop 4
	v_mov_b32_e32 v109, v152
	v_mul_f32_e32 v110, v102, v109
	v_mul_f32_e32 v109, v22, v109
	v_fma_f32 v110, v22, v112, -v110
	v_fmac_f32_e32 v109, v102, v112
	v_cvt_pk_bf16_f32 v113, v110, s0
	v_lshl_add_u64 v[110:111], v[132:133], 1, v[106:107]
	v_cvt_pk_bf16_f32 v109, v109, s0
	global_store_short v[110:111], v113, off
	global_store_short v[110:111], v109, off offset:64
	s_and_saveexec_b64 s[4:5], s[10:11]
	s_cbranch_execz .LBB0_2112
	v_cvt_pk_bf16_f32 v109, v22, s0
	v_lshl_add_u64 v[110:111], v[134:135], 1, v[106:107]
	v_cvt_pk_bf16_f32 v102, v102, s0
	global_store_short v[110:111], v109, off
	global_store_short v[110:111], v102, off offset:64
.LBB0_2112:
	s_or_b64 exec, exec, s[4:5]
	v_or_b32_e32 v102, v108, v240
	v_readlane_b32 s4, v252, 58
	v_lshlrev_b32_e32 v102, 2, v102
	v_readlane_b32 s5, v252, 59
	s_nop 4
	v_mov_b32_e32 v110, v145
	v_readlane_b32 s4, v252, 60
	v_readlane_b32 s5, v252, 61
	s_nop 4
	v_mov_b32_e32 v102, v153
	v_mul_f32_e32 v108, v94, v102
	v_mul_f32_e32 v102, v98, v102
	v_fma_f32 v108, v98, v110, -v108
	v_fmac_f32_e32 v102, v94, v110
	v_cvt_pk_bf16_f32 v111, v108, s0
	v_lshl_add_u64 v[108:109], v[136:137], 1, v[106:107]
	v_cvt_pk_bf16_f32 v102, v102, s0
	global_store_short v[108:109], v111, off offset:32
	global_store_short v[108:109], v102, off offset:96
	s_and_saveexec_b64 s[4:5], s[10:11]
	s_cbranch_execz .LBB0_2114
	v_lshl_add_u64 v[108:109], v[130:131], 0, v[186:187]
	v_cvt_pk_bf16_f32 v98, v98, s0
	v_lshl_add_u64 v[106:107], v[108:109], 1, v[106:107]
	v_cvt_pk_bf16_f32 v94, v94, s0
	global_store_short v[106:107], v98, off offset:32
	global_store_short v[106:107], v94, off offset:96
; DEV u16 f2bf(float f) { return (u16)(pack2(f, 0.f) & 0xffffu); }
; DEV void phase_win(const Params& P, int l, const u16* __restrict__ xb, const u16* __restrict__ Wt, u16* __restrict__ h, char* smem) {
;     ...
;       const int dst = (cb < 256) ? (C_NQR + cb) : cb;
; #pragma unroll
;       for (int ms = 0; ms < 8; ++ms) {
;       asm volatile("" ::: "memory");
; #pragma unroll
;         for (int j = 0; j < 4; ++j) {
;           int row = m0 + wm * 128 + ms * 16 + quad * 4 + j;
;           int pos = row & (S - 1);
;           u16* hr = h + (size_t)row * HS;
; #pragma unroll
;           for (int ns = 0; ns < 2; ++ns) {
;             int d1 = ns * 16 + l15;
;             float x1 = acc[ms][ns][j], x2 = acc[ms][ns + 2][j];
;             float cs = cosT[pos * 32 + d1], sn = sinT[pos * 32 + d1];
;             hr[dst + d1] = f2bf(x1 * cs - x2 * sn);
;             hr[dst + d1 + 32] = f2bf(x1 * sn + x2 * cs);
;             if (cb < 256) {
;               hr[cb + d1] = f2bf(x1);
;               hr[cb + d1 + 32] = f2bf(x2);
;             }
;           }
.LBB0_2114:
	s_or_b64 exec, exec, s[4:5]
	v_or_b32_e32 v94, 1, v0
	v_mov_b64_e32 v[106:107], s[72:73]
	s_movk_i32 s4, 0x1b00
	v_mad_i64_i32 v[106:107], s[4:5], v94, s4, v[106:107]
	v_lshlrev_b32_e32 v94, 5, v94
	v_and_b32_e32 v94, 0x1ffe0, v94
	v_or_b32_e32 v98, v94, v186
	v_readlane_b32 s4, v252, 58
	v_lshlrev_b32_e32 v98, 2, v98
	v_readlane_b32 s5, v252, 59
	s_nop 4
	v_mov_b32_e32 v102, v146
	v_readlane_b32 s4, v252, 60
	v_readlane_b32 s5, v252, 61
	s_nop 4
	v_mov_b32_e32 v98, v154
	v_mul_f32_e32 v108, v103, v98
	v_mul_f32_e32 v98, v23, v98
	v_fma_f32 v108, v23, v102, -v108
	v_fmac_f32_e32 v98, v103, v102
	v_cvt_pk_bf16_f32 v110, v108, s0
	v_lshl_add_u64 v[108:109], v[132:133], 1, v[106:107]
	v_cvt_pk_bf16_f32 v98, v98, s0
	global_store_short v[108:109], v110, off
	global_store_short v[108:109], v98, off offset:64
	s_and_saveexec_b64 s[4:5], s[10:11]
	s_cbranch_execz .LBB0_2116
	v_cvt_pk_bf16_f32 v98, v23, s0
	v_cvt_pk_bf16_f32 v108, v103, s0
	v_lshl_add_u64 v[102:103], v[134:135], 1, v[106:107]
	global_store_short v[102:103], v98, off
	global_store_short v[102:103], v108, off offset:64
.LBB0_2116:
	s_or_b64 exec, exec, s[4:5]
	v_or_b32_e32 v94, v94, v240
	v_readlane_b32 s4, v252, 58
	v_lshlrev_b32_e32 v94, 2, v94
	v_readlane_b32 s5, v252, 59
	s_nop 4
	v_mov_b32_e32 v98, v147
	v_readlane_b32 s4, v252, 60
	v_readlane_b32 s5, v252, 61
	s_nop 4
	v_mov_b32_e32 v94, v155
	v_mul_f32_e32 v102, v95, v94
	v_mul_f32_e32 v94, v99, v94
	v_fma_f32 v102, v99, v98, -v102
	v_fmac_f32_e32 v94, v95, v98
	v_cvt_pk_bf16_f32 v108, v102, s0
	v_lshl_add_u64 v[102:103], v[136:137], 1, v[106:107]
	v_cvt_pk_bf16_f32 v94, v94, s0
	global_store_short v[102:103], v108, off offset:32
	global_store_short v[102:103], v94, off offset:96
	s_and_saveexec_b64 s[4:5], s[10:11]
	s_cbranch_execz .LBB0_2118
	v_cvt_pk_bf16_f32 v98, v99, s0
	v_cvt_pk_bf16_f32 v99, v95, s0
	v_lshl_add_u64 v[94:95], v[130:131], 0, v[186:187]
	v_lshl_add_u64 v[94:95], v[94:95], 1, v[106:107]
	global_store_short v[94:95], v98, off offset:32
	global_store_short v[94:95], v99, off offset:96
.LBB0_2118:
	s_or_b64 exec, exec, s[4:5]
	v_or_b32_e32 v98, 2, v0
	v_mov_b64_e32 v[94:95], s[72:73]
	s_movk_i32 s4, 0x1b00
	v_mad_i64_i32 v[94:95], s[4:5], v98, s4, v[94:95]
	v_lshlrev_b32_e32 v98, 5, v98
	v_and_b32_e32 v98, 0x1ffe0, v98
	v_or_b32_e32 v99, v98, v186
	v_readlane_b32 s4, v252, 58
	v_lshlrev_b32_e32 v99, 2, v99
	v_readlane_b32 s5, v252, 59
	s_nop 4
	v_mov_b32_e32 v106, v148
	v_readlane_b32 s4, v252, 60
	v_readlane_b32 s5, v252, 61
	s_nop 4
	v_mov_b32_e32 v99, v156
	v_mul_f32_e32 v102, v104, v99
	v_mul_f32_e32 v99, v24, v99
	v_fma_f32 v102, v24, v106, -v102
	v_fmac_f32_e32 v99, v104, v106
	v_cvt_pk_bf16_f32 v107, v102, s0
	v_lshl_add_u64 v[102:103], v[132:133], 1, v[94:95]
	v_cvt_pk_bf16_f32 v99, v99, s0
	global_store_short v[102:103], v107, off
	global_store_short v[102:103], v99, off offset:64
	s_and_saveexec_b64 s[4:5], s[10:11]
	s_cbranch_execz .LBB0_2120
	v_cvt_pk_bf16_f32 v99, v24, s0
	v_lshl_add_u64 v[102:103], v[134:135], 1, v[94:95]
	v_cvt_pk_bf16_f32 v104, v104, s0
	global_store_short v[102:103], v99, off
	global_store_short v[102:103], v104, off offset:64
.LBB0_2120:
	s_or_b64 exec, exec, s[4:5]
	v_or_b32_e32 v98, v98, v240
	v_readlane_b32 s4, v252, 58
	v_lshlrev_b32_e32 v98, 2, v98
	v_readlane_b32 s5, v252, 59
	s_nop 4
	v_mov_b32_e32 v102, v149
	v_readlane_b32 s4, v252, 60
	v_readlane_b32 s5, v252, 61
	s_nop 4
	v_mov_b32_e32 v103, v157
	v_mul_f32_e32 v98, v96, v103
	v_mul_f32_e32 v103, v100, v103
	v_fma_f32 v98, v100, v102, -v98
	v_fmac_f32_e32 v103, v96, v102
	v_cvt_pk_bf16_f32 v104, v98, s0
	v_lshl_add_u64 v[98:99], v[136:137], 1, v[94:95]
	v_cvt_pk_bf16_f32 v102, v103, s0
	global_store_short v[98:99], v104, off offset:32
	global_store_short v[98:99], v102, off offset:96
	s_and_saveexec_b64 s[4:5], s[10:11]
	s_cbranch_execz .LBB0_2122
	v_lshl_add_u64 v[98:99], v[130:131], 0, v[186:187]
	v_cvt_pk_bf16_f32 v100, v100, s0
	v_lshl_add_u64 v[94:95], v[98:99], 1, v[94:95]
	v_cvt_pk_bf16_f32 v96, v96, s0
	global_store_short v[94:95], v100, off offset:32
	global_store_short v[94:95], v96, off offset:96
.LBB0_2122:
	s_or_b64 exec, exec, s[4:5]
	v_or_b32_e32 v0, 3, v0
	v_mov_b64_e32 v[94:95], s[72:73]
	s_movk_i32 s4, 0x1b00
	v_mad_i64_i32 v[94:95], s[4:5], v0, s4, v[94:95]
	v_lshlrev_b32_e32 v0, 5, v0
	v_and_b32_e32 v0, 0x1ffe0, v0
	v_or_b32_e32 v96, v0, v186
	v_readlane_b32 s4, v252, 58
	v_lshlrev_b32_e32 v96, 2, v96
	v_readlane_b32 s5, v252, 59
	s_nop 4
	v_mov_b32_e32 v100, v150
	v_readlane_b32 s4, v252, 60
	v_readlane_b32 s5, v252, 61
	s_nop 4
	v_mov_b32_e32 v96, v158
	v_mul_f32_e32 v98, v105, v96
	v_mul_f32_e32 v96, v25, v96
	v_fma_f32 v98, v25, v100, -v98
	v_fmac_f32_e32 v96, v105, v100
	v_cvt_pk_bf16_f32 v102, v98, s0
	v_lshl_add_u64 v[98:99], v[132:133], 1, v[94:95]
	v_cvt_pk_bf16_f32 v96, v96, s0
	global_store_short v[98:99], v102, off
	global_store_short v[98:99], v96, off offset:64
	s_and_saveexec_b64 s[4:5], s[10:11]
	s_cbranch_execz .LBB0_2124
	v_cvt_pk_bf16_f32 v96, v25, s0
	v_lshl_add_u64 v[98:99], v[134:135], 1, v[94:95]
	v_cvt_pk_bf16_f32 v100, v105, s0
	global_store_short v[98:99], v96, off
	global_store_short v[98:99], v100, off offset:64
; DEV u16 f2bf(float f) { return (u16)(pack2(f, 0.f) & 0xffffu); }
; DEV void phase_win(const Params& P, int l, const u16* __restrict__ xb, const u16* __restrict__ Wt, u16* __restrict__ h, char* smem) {
;     ...
;       const int dst = (cb < 256) ? (C_NQR + cb) : cb;
; #pragma unroll
;       for (int ms = 0; ms < 8; ++ms) {
;       asm volatile("" ::: "memory");
; #pragma unroll
;         for (int j = 0; j < 4; ++j) {
;           int row = m0 + wm * 128 + ms * 16 + quad * 4 + j;
;           int pos = row & (S - 1);
;           u16* hr = h + (size_t)row * HS;
; #pragma unroll
;           for (int ns = 0; ns < 2; ++ns) {
;             int d1 = ns * 16 + l15;
;             float x1 = acc[ms][ns][j], x2 = acc[ms][ns + 2][j];
;             float cs = cosT[pos * 32 + d1], sn = sinT[pos * 32 + d1];
;             hr[dst + d1] = f2bf(x1 * cs - x2 * sn);
;             hr[dst + d1 + 32] = f2bf(x1 * sn + x2 * cs);
;             if (cb < 256) {
;               hr[cb + d1] = f2bf(x1);
;               hr[cb + d1 + 32] = f2bf(x2);
;             }
;           }
.LBB0_2124:
	s_or_b64 exec, exec, s[4:5]
	v_or_b32_e32 v0, v0, v240
	v_readlane_b32 s4, v252, 58
	v_lshlrev_b32_e32 v0, 2, v0
	v_readlane_b32 s5, v252, 59
	s_nop 4
	v_mov_b32_e32 v96, v151
	v_readlane_b32 s4, v252, 60
	v_readlane_b32 s5, v252, 61
	s_nop 4
	v_mov_b32_e32 v0, v159
	v_mul_f32_e32 v98, v97, v0
	v_mul_f32_e32 v0, v101, v0
	v_fma_f32 v98, v101, v96, -v98
	v_fmac_f32_e32 v0, v97, v96
	v_cvt_pk_bf16_f32 v100, v98, s0
	v_lshl_add_u64 v[98:99], v[136:137], 1, v[94:95]
	v_cvt_pk_bf16_f32 v0, v0, s0
	global_store_short v[98:99], v100, off offset:32
	global_store_short v[98:99], v0, off offset:96
	s_and_saveexec_b64 s[4:5], s[10:11]
	s_cbranch_execz .LBB0_2126
	v_cvt_pk_bf16_f32 v98, v97, s0
	v_lshl_add_u64 v[96:97], v[130:131], 0, v[186:187]
	v_cvt_pk_bf16_f32 v0, v101, s0
	v_lshl_add_u64 v[94:95], v[96:97], 1, v[94:95]
	global_store_short v[94:95], v0, off offset:32
	global_store_short v[94:95], v98, off offset:96
.LBB0_2126:
	s_or_b64 exec, exec, s[4:5]
	v_add_u32_e32 v0, s16, v235
	v_mov_b64_e32 v[94:95], s[72:73]
	s_movk_i32 s4, 0x1b00
	v_lshlrev_b32_e32 v96, 5, v0
	v_mad_i64_i32 v[94:95], s[4:5], v0, s4, v[94:95]
	v_and_b32_e32 v96, 0x1f780, v96
	v_or_b32_e32 v97, v96, v186
	v_add_u32_e32 v161, 0x1800, v160
	v_readlane_b32 s4, v252, 58
	v_readlane_b32 s5, v252, 59
	s_nop 4
	global_load_dword v144, v161, s[4:5]
	global_load_dword v145, v161, s[4:5] offset:64
	global_load_dword v146, v161, s[4:5] offset:128
	global_load_dword v147, v161, s[4:5] offset:192
	global_load_dword v148, v161, s[4:5] offset:256
	global_load_dword v149, v161, s[4:5] offset:320
	global_load_dword v150, v161, s[4:5] offset:384
	global_load_dword v151, v161, s[4:5] offset:448
	v_readlane_b32 s4, v252, 60
	v_readlane_b32 s5, v252, 61
	s_nop 4
	global_load_dword v152, v161, s[4:5]
	global_load_dword v153, v161, s[4:5] offset:64
	global_load_dword v154, v161, s[4:5] offset:128
	global_load_dword v155, v161, s[4:5] offset:192
	global_load_dword v156, v161, s[4:5] offset:256
	global_load_dword v157, v161, s[4:5] offset:320
	global_load_dword v158, v161, s[4:5] offset:384
	global_load_dword v159, v161, s[4:5] offset:448
	s_waitcnt vmcnt(0)
	v_readlane_b32 s4, v252, 58
	v_lshlrev_b32_e32 v97, 2, v97
	v_readlane_b32 s5, v252, 59
	s_nop 4
	v_mov_b32_e32 v100, v144
	v_readlane_b32 s4, v252, 60
	v_readlane_b32 s5, v252, 61
	s_nop 4
	v_mov_b32_e32 v97, v152
	v_mul_f32_e32 v98, v90, v97
	v_mul_f32_e32 v97, v18, v97
	v_fma_f32 v98, v18, v100, -v98
	v_fmac_f32_e32 v97, v90, v100
	v_cvt_pk_bf16_f32 v101, v98, s0
	v_lshl_add_u64 v[98:99], v[132:133], 1, v[94:95]
	v_cvt_pk_bf16_f32 v97, v97, s0
	global_store_short v[98:99], v101, off
	global_store_short v[98:99], v97, off offset:64
	s_and_saveexec_b64 s[4:5], s[10:11]
	s_cbranch_execz .LBB0_2128
	v_cvt_pk_bf16_f32 v97, v18, s0
	v_lshl_add_u64 v[98:99], v[134:135], 1, v[94:95]
	v_cvt_pk_bf16_f32 v90, v90, s0
	global_store_short v[98:99], v97, off
	global_store_short v[98:99], v90, off offset:64
.LBB0_2128:
	s_or_b64 exec, exec, s[4:5]
	v_or_b32_e32 v90, v96, v240
	v_readlane_b32 s4, v252, 58
	v_lshlrev_b32_e32 v90, 2, v90
	v_readlane_b32 s5, v252, 59
	s_nop 4
	v_mov_b32_e32 v98, v145
	v_readlane_b32 s4, v252, 60
	v_readlane_b32 s5, v252, 61
	s_nop 4
	v_mov_b32_e32 v90, v153
	v_mul_f32_e32 v96, v82, v90
	v_mul_f32_e32 v90, v86, v90
	v_fma_f32 v96, v86, v98, -v96
	v_fmac_f32_e32 v90, v82, v98
	v_cvt_pk_bf16_f32 v99, v96, s0
	v_lshl_add_u64 v[96:97], v[136:137], 1, v[94:95]
	v_cvt_pk_bf16_f32 v90, v90, s0
	global_store_short v[96:97], v99, off offset:32
	global_store_short v[96:97], v90, off offset:96
	s_and_saveexec_b64 s[4:5], s[10:11]
	s_cbranch_execz .LBB0_2130
	v_lshl_add_u64 v[96:97], v[130:131], 0, v[186:187]
	v_cvt_pk_bf16_f32 v86, v86, s0
	v_lshl_add_u64 v[94:95], v[96:97], 1, v[94:95]
	v_cvt_pk_bf16_f32 v82, v82, s0
	global_store_short v[94:95], v86, off offset:32
	global_store_short v[94:95], v82, off offset:96
.LBB0_2130:
	s_or_b64 exec, exec, s[4:5]
	v_or_b32_e32 v82, 1, v0
	v_mov_b64_e32 v[94:95], s[72:73]
	s_movk_i32 s4, 0x1b00
	v_mad_i64_i32 v[94:95], s[4:5], v82, s4, v[94:95]
	v_lshlrev_b32_e32 v82, 5, v82
	v_and_b32_e32 v82, 0x1ffe0, v82
	v_or_b32_e32 v86, v82, v186
	v_readlane_b32 s4, v252, 58
	v_lshlrev_b32_e32 v86, 2, v86
	v_readlane_b32 s5, v252, 59
	s_nop 4
	v_mov_b32_e32 v90, v146
	v_readlane_b32 s4, v252, 60
	v_readlane_b32 s5, v252, 61
	s_nop 4
	v_mov_b32_e32 v86, v154
	v_mul_f32_e32 v96, v91, v86
	v_mul_f32_e32 v86, v19, v86
	v_fma_f32 v96, v19, v90, -v96
	v_fmac_f32_e32 v86, v91, v90
	v_cvt_pk_bf16_f32 v98, v96, s0
	v_lshl_add_u64 v[96:97], v[132:133], 1, v[94:95]
	v_cvt_pk_bf16_f32 v86, v86, s0
	global_store_short v[96:97], v98, off
	global_store_short v[96:97], v86, off offset:64
	s_and_saveexec_b64 s[4:5], s[10:11]
	s_cbranch_execz .LBB0_2132
	v_cvt_pk_bf16_f32 v86, v19, s0
	v_cvt_pk_bf16_f32 v96, v91, s0
	v_lshl_add_u64 v[90:91], v[134:135], 1, v[94:95]
	global_store_short v[90:91], v86, off
	global_store_short v[90:91], v96, off offset:64
.LBB0_2132:
	s_or_b64 exec, exec, s[4:5]
	v_or_b32_e32 v82, v82, v240
	v_readlane_b32 s4, v252, 58
	v_lshlrev_b32_e32 v82, 2, v82
	v_readlane_b32 s5, v252, 59
	s_nop 4
	v_mov_b32_e32 v86, v147
	v_readlane_b32 s4, v252, 60
	v_readlane_b32 s5, v252, 61
	s_nop 4
	v_mov_b32_e32 v82, v155
	v_mul_f32_e32 v90, v83, v82
	v_mul_f32_e32 v82, v87, v82
	v_fma_f32 v90, v87, v86, -v90
	v_fmac_f32_e32 v82, v83, v86
	v_cvt_pk_bf16_f32 v96, v90, s0
	v_lshl_add_u64 v[90:91], v[136:137], 1, v[94:95]
	v_cvt_pk_bf16_f32 v82, v82, s0
	global_store_short v[90:91], v96, off offset:32
	global_store_short v[90:91], v82, off offset:96
	s_and_saveexec_b64 s[4:5], s[10:11]
	s_cbranch_execz .LBB0_2134
	v_cvt_pk_bf16_f32 v86, v87, s0
	v_cvt_pk_bf16_f32 v87, v83, s0
	v_lshl_add_u64 v[82:83], v[130:131], 0, v[186:187]
	v_lshl_add_u64 v[82:83], v[82:83], 1, v[94:95]
	global_store_short v[82:83], v86, off offset:32
	global_store_short v[82:83], v87, off offset:96
; DEV u16 f2bf(float f) { return (u16)(pack2(f, 0.f) & 0xffffu); }
; DEV void phase_win(const Params& P, int l, const u16* __restrict__ xb, const u16* __restrict__ Wt, u16* __restrict__ h, char* smem) {
;     ...
;       const int dst = (cb < 256) ? (C_NQR + cb) : cb;
; #pragma unroll
;       for (int ms = 0; ms < 8; ++ms) {
;       asm volatile("" ::: "memory");
; #pragma unroll
;         for (int j = 0; j < 4; ++j) {
;           int row = m0 + wm * 128 + ms * 16 + quad * 4 + j;
;           int pos = row & (S - 1);
;           u16* hr = h + (size_t)row * HS;
; #pragma unroll
;           for (int ns = 0; ns < 2; ++ns) {
;             int d1 = ns * 16 + l15;
;             float x1 = acc[ms][ns][j], x2 = acc[ms][ns + 2][j];
;             float cs = cosT[pos * 32 + d1], sn = sinT[pos * 32 + d1];
;             hr[dst + d1] = f2bf(x1 * cs - x2 * sn);
;             hr[dst + d1 + 32] = f2bf(x1 * sn + x2 * cs);
;             if (cb < 256) {
;               hr[cb + d1] = f2bf(x1);
;               hr[cb + d1 + 32] = f2bf(x2);
;             }
;           }
.LBB0_2134:
	s_or_b64 exec, exec, s[4:5]
	v_or_b32_e32 v86, 2, v0
	v_mov_b64_e32 v[82:83], s[72:73]
	s_movk_i32 s4, 0x1b00
	v_mad_i64_i32 v[82:83], s[4:5], v86, s4, v[82:83]
	v_lshlrev_b32_e32 v86, 5, v86
	v_and_b32_e32 v86, 0x1ffe0, v86
	v_or_b32_e32 v87, v86, v186
	v_readlane_b32 s4, v252, 58
	v_lshlrev_b32_e32 v87, 2, v87
	v_readlane_b32 s5, v252, 59
	s_nop 4
	v_mov_b32_e32 v94, v148
	v_readlane_b32 s4, v252, 60
	v_readlane_b32 s5, v252, 61
	s_nop 4
	v_mov_b32_e32 v87, v156
	v_mul_f32_e32 v90, v92, v87
	v_mul_f32_e32 v87, v20, v87
	v_fma_f32 v90, v20, v94, -v90
	v_fmac_f32_e32 v87, v92, v94
	v_cvt_pk_bf16_f32 v95, v90, s0
	v_lshl_add_u64 v[90:91], v[132:133], 1, v[82:83]
	v_cvt_pk_bf16_f32 v87, v87, s0
	global_store_short v[90:91], v95, off
	global_store_short v[90:91], v87, off offset:64
	s_and_saveexec_b64 s[4:5], s[10:11]
	s_cbranch_execz .LBB0_2136
	v_cvt_pk_bf16_f32 v87, v20, s0
	v_lshl_add_u64 v[90:91], v[134:135], 1, v[82:83]
	v_cvt_pk_bf16_f32 v92, v92, s0
	global_store_short v[90:91], v87, off
	global_store_short v[90:91], v92, off offset:64
.LBB0_2136:
	s_or_b64 exec, exec, s[4:5]
	v_or_b32_e32 v86, v86, v240
	v_readlane_b32 s4, v252, 58
	v_lshlrev_b32_e32 v86, 2, v86
	v_readlane_b32 s5, v252, 59
	s_nop 4
	v_mov_b32_e32 v90, v149
	v_readlane_b32 s4, v252, 60
	v_readlane_b32 s5, v252, 61
	s_nop 4
	v_mov_b32_e32 v91, v157
	v_mul_f32_e32 v86, v84, v91
	v_mul_f32_e32 v91, v88, v91
	v_fma_f32 v86, v88, v90, -v86
	v_fmac_f32_e32 v91, v84, v90
	v_cvt_pk_bf16_f32 v92, v86, s0
	v_lshl_add_u64 v[86:87], v[136:137], 1, v[82:83]
	v_cvt_pk_bf16_f32 v90, v91, s0
	global_store_short v[86:87], v92, off offset:32
	global_store_short v[86:87], v90, off offset:96
	s_and_saveexec_b64 s[4:5], s[10:11]
	s_cbranch_execz .LBB0_2138
	v_lshl_add_u64 v[86:87], v[130:131], 0, v[186:187]
	v_cvt_pk_bf16_f32 v88, v88, s0
	v_lshl_add_u64 v[82:83], v[86:87], 1, v[82:83]
	v_cvt_pk_bf16_f32 v84, v84, s0
	global_store_short v[82:83], v88, off offset:32
	global_store_short v[82:83], v84, off offset:96
.LBB0_2138:
	s_or_b64 exec, exec, s[4:5]
	v_or_b32_e32 v0, 3, v0
	v_mov_b64_e32 v[82:83], s[72:73]
	s_movk_i32 s4, 0x1b00
	v_mad_i64_i32 v[82:83], s[4:5], v0, s4, v[82:83]
	v_lshlrev_b32_e32 v0, 5, v0
	v_and_b32_e32 v0, 0x1ffe0, v0
	v_or_b32_e32 v84, v0, v186
	v_readlane_b32 s4, v252, 58
	v_lshlrev_b32_e32 v84, 2, v84
	v_readlane_b32 s5, v252, 59
	s_nop 4
	v_mov_b32_e32 v88, v150
	v_readlane_b32 s4, v252, 60
	v_readlane_b32 s5, v252, 61
	s_nop 4
	v_mov_b32_e32 v84, v158
	v_mul_f32_e32 v86, v93, v84
	v_mul_f32_e32 v84, v21, v84
	v_fma_f32 v86, v21, v88, -v86
	v_fmac_f32_e32 v84, v93, v88
	v_cvt_pk_bf16_f32 v90, v86, s0
	v_lshl_add_u64 v[86:87], v[132:133], 1, v[82:83]
	v_cvt_pk_bf16_f32 v84, v84, s0
	global_store_short v[86:87], v90, off
	global_store_short v[86:87], v84, off offset:64
	s_and_saveexec_b64 s[4:5], s[10:11]
	s_cbranch_execz .LBB0_2140
	v_cvt_pk_bf16_f32 v84, v21, s0
	v_lshl_add_u64 v[86:87], v[134:135], 1, v[82:83]
	v_cvt_pk_bf16_f32 v88, v93, s0
	global_store_short v[86:87], v84, off
	global_store_short v[86:87], v88, off offset:64
.LBB0_2140:
	s_or_b64 exec, exec, s[4:5]
	v_or_b32_e32 v0, v0, v240
	v_readlane_b32 s4, v252, 58
	v_lshlrev_b32_e32 v0, 2, v0
	v_readlane_b32 s5, v252, 59
	s_nop 4
	v_mov_b32_e32 v84, v151
	v_readlane_b32 s4, v252, 60
	v_readlane_b32 s5, v252, 61
	s_nop 4
	v_mov_b32_e32 v0, v159
	v_mul_f32_e32 v86, v85, v0
	v_mul_f32_e32 v0, v89, v0
	v_fma_f32 v86, v89, v84, -v86
	v_fmac_f32_e32 v0, v85, v84
	v_cvt_pk_bf16_f32 v88, v86, s0
	v_lshl_add_u64 v[86:87], v[136:137], 1, v[82:83]
	v_cvt_pk_bf16_f32 v0, v0, s0
	global_store_short v[86:87], v88, off offset:32
	global_store_short v[86:87], v0, off offset:96
	s_and_saveexec_b64 s[4:5], s[10:11]
	s_cbranch_execz .LBB0_2142
	v_cvt_pk_bf16_f32 v86, v85, s0
	v_lshl_add_u64 v[84:85], v[130:131], 0, v[186:187]
	v_cvt_pk_bf16_f32 v0, v89, s0
	v_lshl_add_u64 v[82:83], v[84:85], 1, v[82:83]
	global_store_short v[82:83], v0, off offset:32
	global_store_short v[82:83], v86, off offset:96
.LBB0_2142:
	s_or_b64 exec, exec, s[4:5]
	v_add_u32_e32 v0, s16, v236
	v_mov_b64_e32 v[82:83], s[72:73]
	s_movk_i32 s4, 0x1b00
	v_lshlrev_b32_e32 v84, 5, v0
	v_mad_i64_i32 v[82:83], s[4:5], v0, s4, v[82:83]
	v_and_b32_e32 v84, 0x1f980, v84
	v_or_b32_e32 v85, v84, v186
	v_add_u32_e32 v161, 0x2000, v160
	v_readlane_b32 s4, v252, 58
	v_readlane_b32 s5, v252, 59
	s_nop 4
	global_load_dword v144, v161, s[4:5]
	global_load_dword v145, v161, s[4:5] offset:64
	global_load_dword v146, v161, s[4:5] offset:128
	global_load_dword v147, v161, s[4:5] offset:192
	global_load_dword v148, v161, s[4:5] offset:256
	global_load_dword v149, v161, s[4:5] offset:320
	global_load_dword v150, v161, s[4:5] offset:384
	global_load_dword v151, v161, s[4:5] offset:448
	v_readlane_b32 s4, v252, 60
	v_readlane_b32 s5, v252, 61
	s_nop 4
	global_load_dword v152, v161, s[4:5]
	global_load_dword v153, v161, s[4:5] offset:64
	global_load_dword v154, v161, s[4:5] offset:128
	global_load_dword v155, v161, s[4:5] offset:192
	global_load_dword v156, v161, s[4:5] offset:256
	global_load_dword v157, v161, s[4:5] offset:320
	global_load_dword v158, v161, s[4:5] offset:384
	global_load_dword v159, v161, s[4:5] offset:448
	s_waitcnt vmcnt(0)
	v_readlane_b32 s4, v252, 58
	v_lshlrev_b32_e32 v85, 2, v85
	v_readlane_b32 s5, v252, 59
	s_nop 4
	v_mov_b32_e32 v88, v144
	v_readlane_b32 s4, v252, 60
	v_readlane_b32 s5, v252, 61
	s_nop 4
	v_mov_b32_e32 v85, v152
	v_mul_f32_e32 v86, v78, v85
	v_mul_f32_e32 v85, v14, v85
	v_fma_f32 v86, v14, v88, -v86
	v_fmac_f32_e32 v85, v78, v88
	v_cvt_pk_bf16_f32 v89, v86, s0
	v_lshl_add_u64 v[86:87], v[132:133], 1, v[82:83]
	v_cvt_pk_bf16_f32 v85, v85, s0
	global_store_short v[86:87], v89, off
	global_store_short v[86:87], v85, off offset:64
	s_and_saveexec_b64 s[4:5], s[10:11]
	s_cbranch_execz .LBB0_2144
	v_cvt_pk_bf16_f32 v85, v14, s0
	v_lshl_add_u64 v[86:87], v[134:135], 1, v[82:83]
	v_cvt_pk_bf16_f32 v78, v78, s0
	global_store_short v[86:87], v85, off
	global_store_short v[86:87], v78, off offset:64
; DEV u16 f2bf(float f) { return (u16)(pack2(f, 0.f) & 0xffffu); }
; DEV void phase_win(const Params& P, int l, const u16* __restrict__ xb, const u16* __restrict__ Wt, u16* __restrict__ h, char* smem) {
;     ...
;       const int dst = (cb < 256) ? (C_NQR + cb) : cb;
; #pragma unroll
;       for (int ms = 0; ms < 8; ++ms) {
;       asm volatile("" ::: "memory");
; #pragma unroll
;         for (int j = 0; j < 4; ++j) {
;           int row = m0 + wm * 128 + ms * 16 + quad * 4 + j;
;           int pos = row & (S - 1);
;           u16* hr = h + (size_t)row * HS;
; #pragma unroll
;           for (int ns = 0; ns < 2; ++ns) {
;             int d1 = ns * 16 + l15;
;             float x1 = acc[ms][ns][j], x2 = acc[ms][ns + 2][j];
;             float cs = cosT[pos * 32 + d1], sn = sinT[pos * 32 + d1];
;             hr[dst + d1] = f2bf(x1 * cs - x2 * sn);
;             hr[dst + d1 + 32] = f2bf(x1 * sn + x2 * cs);
;             if (cb < 256) {
;               hr[cb + d1] = f2bf(x1);
;               hr[cb + d1 + 32] = f2bf(x2);
;             }
;           }
.LBB0_2144:
	s_or_b64 exec, exec, s[4:5]
	v_or_b32_e32 v78, v84, v240
	v_readlane_b32 s4, v252, 58
	v_lshlrev_b32_e32 v78, 2, v78
	v_readlane_b32 s5, v252, 59
	s_nop 4
	v_mov_b32_e32 v86, v145
	v_readlane_b32 s4, v252, 60
	v_readlane_b32 s5, v252, 61
	s_nop 4
	v_mov_b32_e32 v78, v153
	v_mul_f32_e32 v84, v70, v78
	v_mul_f32_e32 v78, v74, v78
	v_fma_f32 v84, v74, v86, -v84
	v_fmac_f32_e32 v78, v70, v86
	v_cvt_pk_bf16_f32 v87, v84, s0
	v_lshl_add_u64 v[84:85], v[136:137], 1, v[82:83]
	v_cvt_pk_bf16_f32 v78, v78, s0
	global_store_short v[84:85], v87, off offset:32
	global_store_short v[84:85], v78, off offset:96
	s_and_saveexec_b64 s[4:5], s[10:11]
	s_cbranch_execz .LBB0_2146
	v_lshl_add_u64 v[84:85], v[130:131], 0, v[186:187]
	v_cvt_pk_bf16_f32 v74, v74, s0
	v_lshl_add_u64 v[82:83], v[84:85], 1, v[82:83]
	v_cvt_pk_bf16_f32 v70, v70, s0
	global_store_short v[82:83], v74, off offset:32
	global_store_short v[82:83], v70, off offset:96
.LBB0_2146:
	s_or_b64 exec, exec, s[4:5]
	v_or_b32_e32 v70, 1, v0
	v_mov_b64_e32 v[82:83], s[72:73]
	s_movk_i32 s4, 0x1b00
	v_mad_i64_i32 v[82:83], s[4:5], v70, s4, v[82:83]
	v_lshlrev_b32_e32 v70, 5, v70
	v_and_b32_e32 v70, 0x1ffe0, v70
	v_or_b32_e32 v74, v70, v186
	v_readlane_b32 s4, v252, 58
	v_lshlrev_b32_e32 v74, 2, v74
	v_readlane_b32 s5, v252, 59
	s_nop 4
	v_mov_b32_e32 v78, v146
	v_readlane_b32 s4, v252, 60
	v_readlane_b32 s5, v252, 61
	s_nop 4
	v_mov_b32_e32 v74, v154
	v_mul_f32_e32 v84, v79, v74
	v_mul_f32_e32 v74, v15, v74
	v_fma_f32 v84, v15, v78, -v84
	v_fmac_f32_e32 v74, v79, v78
	v_cvt_pk_bf16_f32 v86, v84, s0
	v_lshl_add_u64 v[84:85], v[132:133], 1, v[82:83]
	v_cvt_pk_bf16_f32 v74, v74, s0
	global_store_short v[84:85], v86, off
	global_store_short v[84:85], v74, off offset:64
	s_and_saveexec_b64 s[4:5], s[10:11]
	s_cbranch_execz .LBB0_2148
	v_cvt_pk_bf16_f32 v74, v15, s0
	v_cvt_pk_bf16_f32 v84, v79, s0
	v_lshl_add_u64 v[78:79], v[134:135], 1, v[82:83]
	global_store_short v[78:79], v74, off
	global_store_short v[78:79], v84, off offset:64
.LBB0_2148:
	s_or_b64 exec, exec, s[4:5]
	v_or_b32_e32 v70, v70, v240
	v_readlane_b32 s4, v252, 58
	v_lshlrev_b32_e32 v70, 2, v70
	v_readlane_b32 s5, v252, 59
	s_nop 4
	v_mov_b32_e32 v74, v147
	v_readlane_b32 s4, v252, 60
	v_readlane_b32 s5, v252, 61
	s_nop 4
	v_mov_b32_e32 v70, v155
	v_mul_f32_e32 v78, v71, v70
	v_mul_f32_e32 v70, v75, v70
	v_fma_f32 v78, v75, v74, -v78
	v_fmac_f32_e32 v70, v71, v74
	v_cvt_pk_bf16_f32 v84, v78, s0
	v_lshl_add_u64 v[78:79], v[136:137], 1, v[82:83]
	v_cvt_pk_bf16_f32 v70, v70, s0
	global_store_short v[78:79], v84, off offset:32
	global_store_short v[78:79], v70, off offset:96
	s_and_saveexec_b64 s[4:5], s[10:11]
	s_cbranch_execz .LBB0_2150
	v_cvt_pk_bf16_f32 v74, v75, s0
	v_cvt_pk_bf16_f32 v75, v71, s0
	v_lshl_add_u64 v[70:71], v[130:131], 0, v[186:187]
	v_lshl_add_u64 v[70:71], v[70:71], 1, v[82:83]
	global_store_short v[70:71], v74, off offset:32
	global_store_short v[70:71], v75, off offset:96
.LBB0_2150:
	s_or_b64 exec, exec, s[4:5]
	v_or_b32_e32 v74, 2, v0
	v_mov_b64_e32 v[70:71], s[72:73]
	s_movk_i32 s4, 0x1b00
	v_mad_i64_i32 v[70:71], s[4:5], v74, s4, v[70:71]
	v_lshlrev_b32_e32 v74, 5, v74
	v_and_b32_e32 v74, 0x1ffe0, v74
	v_or_b32_e32 v75, v74, v186
	v_readlane_b32 s4, v252, 58
	v_lshlrev_b32_e32 v75, 2, v75
	v_readlane_b32 s5, v252, 59
	s_nop 4
	v_mov_b32_e32 v82, v148
	v_readlane_b32 s4, v252, 60
	v_readlane_b32 s5, v252, 61
	s_nop 4
	v_mov_b32_e32 v75, v156
	v_mul_f32_e32 v78, v80, v75
	v_mul_f32_e32 v75, v16, v75
	v_fma_f32 v78, v16, v82, -v78
	v_fmac_f32_e32 v75, v80, v82
	v_cvt_pk_bf16_f32 v83, v78, s0
	v_lshl_add_u64 v[78:79], v[132:133], 1, v[70:71]
	v_cvt_pk_bf16_f32 v75, v75, s0
	global_store_short v[78:79], v83, off
	global_store_short v[78:79], v75, off offset:64
	s_and_saveexec_b64 s[4:5], s[10:11]
	s_cbranch_execz .LBB0_2152
	v_cvt_pk_bf16_f32 v75, v16, s0
	v_lshl_add_u64 v[78:79], v[134:135], 1, v[70:71]
	v_cvt_pk_bf16_f32 v80, v80, s0
	global_store_short v[78:79], v75, off
	global_store_short v[78:79], v80, off offset:64
.LBB0_2152:
	s_or_b64 exec, exec, s[4:5]
	v_or_b32_e32 v74, v74, v240
	v_readlane_b32 s4, v252, 58
	v_lshlrev_b32_e32 v74, 2, v74
	v_readlane_b32 s5, v252, 59
	s_nop 4
	v_mov_b32_e32 v78, v149
	v_readlane_b32 s4, v252, 60
	v_readlane_b32 s5, v252, 61
	s_nop 4
	v_mov_b32_e32 v79, v157
	v_mul_f32_e32 v74, v72, v79
	v_mul_f32_e32 v79, v76, v79
	v_fma_f32 v74, v76, v78, -v74
	v_fmac_f32_e32 v79, v72, v78
	v_cvt_pk_bf16_f32 v80, v74, s0
	v_lshl_add_u64 v[74:75], v[136:137], 1, v[70:71]
	v_cvt_pk_bf16_f32 v78, v79, s0
	global_store_short v[74:75], v80, off offset:32
	global_store_short v[74:75], v78, off offset:96
	s_and_saveexec_b64 s[4:5], s[10:11]
	s_cbranch_execz .LBB0_2154
	v_lshl_add_u64 v[74:75], v[130:131], 0, v[186:187]
	v_cvt_pk_bf16_f32 v76, v76, s0
	v_lshl_add_u64 v[70:71], v[74:75], 1, v[70:71]
	v_cvt_pk_bf16_f32 v72, v72, s0
	global_store_short v[70:71], v76, off offset:32
	global_store_short v[70:71], v72, off offset:96
.LBB0_2154:
	s_or_b64 exec, exec, s[4:5]
	v_or_b32_e32 v0, 3, v0
	v_mov_b64_e32 v[70:71], s[72:73]
	s_movk_i32 s4, 0x1b00
	v_mad_i64_i32 v[70:71], s[4:5], v0, s4, v[70:71]
	v_lshlrev_b32_e32 v0, 5, v0
	v_and_b32_e32 v0, 0x1ffe0, v0
	v_or_b32_e32 v72, v0, v186
	v_readlane_b32 s4, v252, 58
	v_lshlrev_b32_e32 v72, 2, v72
	v_readlane_b32 s5, v252, 59
	s_nop 4
	v_mov_b32_e32 v76, v150
	v_readlane_b32 s4, v252, 60
	v_readlane_b32 s5, v252, 61
	s_nop 4
	v_mov_b32_e32 v72, v158
	v_mul_f32_e32 v74, v81, v72
	v_mul_f32_e32 v72, v17, v72
	v_fma_f32 v74, v17, v76, -v74
	v_fmac_f32_e32 v72, v81, v76
	v_cvt_pk_bf16_f32 v78, v74, s0
	v_lshl_add_u64 v[74:75], v[132:133], 1, v[70:71]
	v_cvt_pk_bf16_f32 v72, v72, s0
	global_store_short v[74:75], v78, off
	global_store_short v[74:75], v72, off offset:64
	s_and_saveexec_b64 s[4:5], s[10:11]
	s_cbranch_execz .LBB0_2156
	v_cvt_pk_bf16_f32 v72, v17, s0
	v_lshl_add_u64 v[74:75], v[134:135], 1, v[70:71]
	v_cvt_pk_bf16_f32 v76, v81, s0
	global_store_short v[74:75], v72, off
	global_store_short v[74:75], v76, off offset:64
; DEV u16 f2bf(float f) { return (u16)(pack2(f, 0.f) & 0xffffu); }
; DEV void phase_win(const Params& P, int l, const u16* __restrict__ xb, const u16* __restrict__ Wt, u16* __restrict__ h, char* smem) {
;     ...
;       const int dst = (cb < 256) ? (C_NQR + cb) : cb;
; #pragma unroll
;       for (int ms = 0; ms < 8; ++ms) {
;       asm volatile("" ::: "memory");
; #pragma unroll
;         for (int j = 0; j < 4; ++j) {
;           int row = m0 + wm * 128 + ms * 16 + quad * 4 + j;
;           int pos = row & (S - 1);
;           u16* hr = h + (size_t)row * HS;
; #pragma unroll
;           for (int ns = 0; ns < 2; ++ns) {
;             int d1 = ns * 16 + l15;
;             float x1 = acc[ms][ns][j], x2 = acc[ms][ns + 2][j];
;             float cs = cosT[pos * 32 + d1], sn = sinT[pos * 32 + d1];
;             hr[dst + d1] = f2bf(x1 * cs - x2 * sn);
;             hr[dst + d1 + 32] = f2bf(x1 * sn + x2 * cs);
;             if (cb < 256) {
;               hr[cb + d1] = f2bf(x1);
;               hr[cb + d1 + 32] = f2bf(x2);
;             }
;           }
.LBB0_2156:
	s_or_b64 exec, exec, s[4:5]
	v_or_b32_e32 v0, v0, v240
	v_readlane_b32 s4, v252, 58
	v_lshlrev_b32_e32 v0, 2, v0
	v_readlane_b32 s5, v252, 59
	s_nop 4
	v_mov_b32_e32 v72, v151
	v_readlane_b32 s4, v252, 60
	v_readlane_b32 s5, v252, 61
	s_nop 4
	v_mov_b32_e32 v0, v159
	v_mul_f32_e32 v74, v73, v0
	v_mul_f32_e32 v0, v77, v0
	v_fma_f32 v74, v77, v72, -v74
	v_fmac_f32_e32 v0, v73, v72
	v_cvt_pk_bf16_f32 v76, v74, s0
	v_lshl_add_u64 v[74:75], v[136:137], 1, v[70:71]
	v_cvt_pk_bf16_f32 v0, v0, s0
	global_store_short v[74:75], v76, off offset:32
	global_store_short v[74:75], v0, off offset:96
	s_and_saveexec_b64 s[4:5], s[10:11]
	s_cbranch_execz .LBB0_2158
	v_cvt_pk_bf16_f32 v74, v73, s0
	v_lshl_add_u64 v[72:73], v[130:131], 0, v[186:187]
	v_cvt_pk_bf16_f32 v0, v77, s0
	v_lshl_add_u64 v[70:71], v[72:73], 1, v[70:71]
	global_store_short v[70:71], v0, off offset:32
	global_store_short v[70:71], v74, off offset:96
.LBB0_2158:
	s_or_b64 exec, exec, s[4:5]
	v_add_u32_e32 v0, s16, v237
	v_mov_b64_e32 v[70:71], s[72:73]
	s_movk_i32 s4, 0x1b00
	v_lshlrev_b32_e32 v72, 5, v0
	v_mad_i64_i32 v[70:71], s[4:5], v0, s4, v[70:71]
	v_and_b32_e32 v72, 0x1fb80, v72
	v_or_b32_e32 v73, v72, v186
	v_add_u32_e32 v161, 0x2800, v160
	v_readlane_b32 s4, v252, 58
	v_readlane_b32 s5, v252, 59
	s_nop 4
	global_load_dword v144, v161, s[4:5]
	global_load_dword v145, v161, s[4:5] offset:64
	global_load_dword v146, v161, s[4:5] offset:128
	global_load_dword v147, v161, s[4:5] offset:192
	global_load_dword v148, v161, s[4:5] offset:256
	global_load_dword v149, v161, s[4:5] offset:320
	global_load_dword v150, v161, s[4:5] offset:384
	global_load_dword v151, v161, s[4:5] offset:448
	v_readlane_b32 s4, v252, 60
	v_readlane_b32 s5, v252, 61
	s_nop 4
	global_load_dword v152, v161, s[4:5]
	global_load_dword v153, v161, s[4:5] offset:64
	global_load_dword v154, v161, s[4:5] offset:128
	global_load_dword v155, v161, s[4:5] offset:192
	global_load_dword v156, v161, s[4:5] offset:256
	global_load_dword v157, v161, s[4:5] offset:320
	global_load_dword v158, v161, s[4:5] offset:384
	global_load_dword v159, v161, s[4:5] offset:448
	s_waitcnt vmcnt(0)
	v_readlane_b32 s4, v252, 58
	v_lshlrev_b32_e32 v73, 2, v73
	v_readlane_b32 s5, v252, 59
	s_nop 4
	v_mov_b32_e32 v76, v144
	v_readlane_b32 s4, v252, 60
	v_readlane_b32 s5, v252, 61
	s_nop 4
	v_mov_b32_e32 v73, v152
	v_mul_f32_e32 v74, v66, v73
	v_mul_f32_e32 v73, v10, v73
	v_fma_f32 v74, v10, v76, -v74
	v_fmac_f32_e32 v73, v66, v76
	v_cvt_pk_bf16_f32 v77, v74, s0
	v_lshl_add_u64 v[74:75], v[132:133], 1, v[70:71]
	v_cvt_pk_bf16_f32 v73, v73, s0
	global_store_short v[74:75], v77, off
	global_store_short v[74:75], v73, off offset:64
	s_and_saveexec_b64 s[4:5], s[10:11]
	s_cbranch_execz .LBB0_2160
	v_cvt_pk_bf16_f32 v73, v10, s0
	v_lshl_add_u64 v[74:75], v[134:135], 1, v[70:71]
	v_cvt_pk_bf16_f32 v66, v66, s0
	global_store_short v[74:75], v73, off
	global_store_short v[74:75], v66, off offset:64
.LBB0_2160:
	s_or_b64 exec, exec, s[4:5]
	v_or_b32_e32 v66, v72, v240
	v_readlane_b32 s4, v252, 58
	v_lshlrev_b32_e32 v66, 2, v66
	v_readlane_b32 s5, v252, 59
	s_nop 4
	v_mov_b32_e32 v74, v145
	v_readlane_b32 s4, v252, 60
	v_readlane_b32 s5, v252, 61
	s_nop 4
	v_mov_b32_e32 v66, v153
	v_mul_f32_e32 v72, v58, v66
	v_mul_f32_e32 v66, v62, v66
	v_fma_f32 v72, v62, v74, -v72
	v_fmac_f32_e32 v66, v58, v74
	v_cvt_pk_bf16_f32 v75, v72, s0
	v_lshl_add_u64 v[72:73], v[136:137], 1, v[70:71]
	v_cvt_pk_bf16_f32 v66, v66, s0
	global_store_short v[72:73], v75, off offset:32
	global_store_short v[72:73], v66, off offset:96
	s_and_saveexec_b64 s[4:5], s[10:11]
	s_cbranch_execz .LBB0_2162
	v_lshl_add_u64 v[72:73], v[130:131], 0, v[186:187]
	v_cvt_pk_bf16_f32 v62, v62, s0
	v_lshl_add_u64 v[70:71], v[72:73], 1, v[70:71]
	v_cvt_pk_bf16_f32 v58, v58, s0
	global_store_short v[70:71], v62, off offset:32
	global_store_short v[70:71], v58, off offset:96
.LBB0_2162:
	s_or_b64 exec, exec, s[4:5]
	v_or_b32_e32 v58, 1, v0
	v_mov_b64_e32 v[70:71], s[72:73]
	s_movk_i32 s4, 0x1b00
	v_mad_i64_i32 v[70:71], s[4:5], v58, s4, v[70:71]
	v_lshlrev_b32_e32 v58, 5, v58
	v_and_b32_e32 v58, 0x1ffe0, v58
	v_or_b32_e32 v62, v58, v186
	v_readlane_b32 s4, v252, 58
	v_lshlrev_b32_e32 v62, 2, v62
	v_readlane_b32 s5, v252, 59
	s_nop 4
	v_mov_b32_e32 v66, v146
	v_readlane_b32 s4, v252, 60
	v_readlane_b32 s5, v252, 61
	s_nop 4
	v_mov_b32_e32 v62, v154
	v_mul_f32_e32 v72, v67, v62
	v_mul_f32_e32 v62, v11, v62
	v_fma_f32 v72, v11, v66, -v72
	v_fmac_f32_e32 v62, v67, v66
	v_cvt_pk_bf16_f32 v74, v72, s0
	v_lshl_add_u64 v[72:73], v[132:133], 1, v[70:71]
	v_cvt_pk_bf16_f32 v62, v62, s0
	global_store_short v[72:73], v74, off
	global_store_short v[72:73], v62, off offset:64
	s_and_saveexec_b64 s[4:5], s[10:11]
	s_cbranch_execz .LBB0_2164
	v_cvt_pk_bf16_f32 v62, v11, s0
	v_cvt_pk_bf16_f32 v72, v67, s0
	v_lshl_add_u64 v[66:67], v[134:135], 1, v[70:71]
	global_store_short v[66:67], v62, off
	global_store_short v[66:67], v72, off offset:64
.LBB0_2164:
	s_or_b64 exec, exec, s[4:5]
	v_or_b32_e32 v58, v58, v240
	v_readlane_b32 s4, v252, 58
	v_lshlrev_b32_e32 v58, 2, v58
	v_readlane_b32 s5, v252, 59
	s_nop 4
	v_mov_b32_e32 v62, v147
	v_readlane_b32 s4, v252, 60
	v_readlane_b32 s5, v252, 61
	s_nop 4
	v_mov_b32_e32 v58, v155
	v_mul_f32_e32 v66, v59, v58
	v_mul_f32_e32 v58, v63, v58
	v_fma_f32 v66, v63, v62, -v66
	v_fmac_f32_e32 v58, v59, v62
	v_cvt_pk_bf16_f32 v72, v66, s0
	v_lshl_add_u64 v[66:67], v[136:137], 1, v[70:71]
	v_cvt_pk_bf16_f32 v58, v58, s0
	global_store_short v[66:67], v72, off offset:32
	global_store_short v[66:67], v58, off offset:96
	s_and_saveexec_b64 s[4:5], s[10:11]
	s_cbranch_execz .LBB0_2166
	v_cvt_pk_bf16_f32 v62, v63, s0
	v_cvt_pk_bf16_f32 v63, v59, s0
	v_lshl_add_u64 v[58:59], v[130:131], 0, v[186:187]
	v_lshl_add_u64 v[58:59], v[58:59], 1, v[70:71]
	global_store_short v[58:59], v62, off offset:32
	global_store_short v[58:59], v63, off offset:96
; DEV u16 f2bf(float f) { return (u16)(pack2(f, 0.f) & 0xffffu); }
; DEV void phase_win(const Params& P, int l, const u16* __restrict__ xb, const u16* __restrict__ Wt, u16* __restrict__ h, char* smem) {
;     ...
;       const int dst = (cb < 256) ? (C_NQR + cb) : cb;
; #pragma unroll
;       for (int ms = 0; ms < 8; ++ms) {
;       asm volatile("" ::: "memory");
; #pragma unroll
;         for (int j = 0; j < 4; ++j) {
;           int row = m0 + wm * 128 + ms * 16 + quad * 4 + j;
;           int pos = row & (S - 1);
;           u16* hr = h + (size_t)row * HS;
; #pragma unroll
;           for (int ns = 0; ns < 2; ++ns) {
;             int d1 = ns * 16 + l15;
;             float x1 = acc[ms][ns][j], x2 = acc[ms][ns + 2][j];
;             float cs = cosT[pos * 32 + d1], sn = sinT[pos * 32 + d1];
;             hr[dst + d1] = f2bf(x1 * cs - x2 * sn);
;             hr[dst + d1 + 32] = f2bf(x1 * sn + x2 * cs);
;             if (cb < 256) {
;               hr[cb + d1] = f2bf(x1);
;               hr[cb + d1 + 32] = f2bf(x2);
;             }
;           }
.LBB0_2166:
	s_or_b64 exec, exec, s[4:5]
	v_or_b32_e32 v62, 2, v0
	v_mov_b64_e32 v[58:59], s[72:73]
	s_movk_i32 s4, 0x1b00
	v_mad_i64_i32 v[58:59], s[4:5], v62, s4, v[58:59]
	v_lshlrev_b32_e32 v62, 5, v62
	v_and_b32_e32 v62, 0x1ffe0, v62
	v_or_b32_e32 v63, v62, v186
	v_readlane_b32 s4, v252, 58
	v_lshlrev_b32_e32 v63, 2, v63
	v_readlane_b32 s5, v252, 59
	s_nop 4
	v_mov_b32_e32 v70, v148
	v_readlane_b32 s4, v252, 60
	v_readlane_b32 s5, v252, 61
	s_nop 4
	v_mov_b32_e32 v63, v156
	v_mul_f32_e32 v66, v68, v63
	v_mul_f32_e32 v63, v12, v63
	v_fma_f32 v66, v12, v70, -v66
	v_fmac_f32_e32 v63, v68, v70
	v_cvt_pk_bf16_f32 v71, v66, s0
	v_lshl_add_u64 v[66:67], v[132:133], 1, v[58:59]
	v_cvt_pk_bf16_f32 v63, v63, s0
	global_store_short v[66:67], v71, off
	global_store_short v[66:67], v63, off offset:64
	s_and_saveexec_b64 s[4:5], s[10:11]
	s_cbranch_execz .LBB0_2168
	v_cvt_pk_bf16_f32 v63, v12, s0
	v_lshl_add_u64 v[66:67], v[134:135], 1, v[58:59]
	v_cvt_pk_bf16_f32 v68, v68, s0
	global_store_short v[66:67], v63, off
	global_store_short v[66:67], v68, off offset:64
.LBB0_2168:
	s_or_b64 exec, exec, s[4:5]
	v_or_b32_e32 v62, v62, v240
	v_readlane_b32 s4, v252, 58
	v_lshlrev_b32_e32 v62, 2, v62
	v_readlane_b32 s5, v252, 59
	s_nop 4
	v_mov_b32_e32 v66, v149
	v_readlane_b32 s4, v252, 60
	v_readlane_b32 s5, v252, 61
	s_nop 4
	v_mov_b32_e32 v67, v157
	v_mul_f32_e32 v62, v60, v67
	v_mul_f32_e32 v67, v64, v67
	v_fma_f32 v62, v64, v66, -v62
	v_fmac_f32_e32 v67, v60, v66
	v_cvt_pk_bf16_f32 v68, v62, s0
	v_lshl_add_u64 v[62:63], v[136:137], 1, v[58:59]
	v_cvt_pk_bf16_f32 v66, v67, s0
	global_store_short v[62:63], v68, off offset:32
	global_store_short v[62:63], v66, off offset:96
	s_and_saveexec_b64 s[4:5], s[10:11]
	s_cbranch_execz .LBB0_2170
	v_lshl_add_u64 v[62:63], v[130:131], 0, v[186:187]
	v_cvt_pk_bf16_f32 v64, v64, s0
	v_lshl_add_u64 v[58:59], v[62:63], 1, v[58:59]
	v_cvt_pk_bf16_f32 v60, v60, s0
	global_store_short v[58:59], v64, off offset:32
	global_store_short v[58:59], v60, off offset:96
.LBB0_2170:
	s_or_b64 exec, exec, s[4:5]
	v_or_b32_e32 v0, 3, v0
	v_mov_b64_e32 v[58:59], s[72:73]
	s_movk_i32 s4, 0x1b00
	v_mad_i64_i32 v[58:59], s[4:5], v0, s4, v[58:59]
	v_lshlrev_b32_e32 v0, 5, v0
	v_and_b32_e32 v0, 0x1ffe0, v0
	v_or_b32_e32 v60, v0, v186
	v_readlane_b32 s4, v252, 58
	v_lshlrev_b32_e32 v60, 2, v60
	v_readlane_b32 s5, v252, 59
	s_nop 4
	v_mov_b32_e32 v64, v150
	v_readlane_b32 s4, v252, 60
	v_readlane_b32 s5, v252, 61
	s_nop 4
	v_mov_b32_e32 v60, v158
	v_mul_f32_e32 v62, v69, v60
	v_mul_f32_e32 v60, v13, v60
	v_fma_f32 v62, v13, v64, -v62
	v_fmac_f32_e32 v60, v69, v64
	v_cvt_pk_bf16_f32 v66, v62, s0
	v_lshl_add_u64 v[62:63], v[132:133], 1, v[58:59]
	v_cvt_pk_bf16_f32 v60, v60, s0
	global_store_short v[62:63], v66, off
	global_store_short v[62:63], v60, off offset:64
	s_and_saveexec_b64 s[4:5], s[10:11]
	s_cbranch_execz .LBB0_2172
	v_cvt_pk_bf16_f32 v60, v13, s0
	v_lshl_add_u64 v[62:63], v[134:135], 1, v[58:59]
	v_cvt_pk_bf16_f32 v64, v69, s0
	global_store_short v[62:63], v60, off
	global_store_short v[62:63], v64, off offset:64
.LBB0_2172:
	s_or_b64 exec, exec, s[4:5]
	v_or_b32_e32 v0, v0, v240
	v_readlane_b32 s4, v252, 58
	v_lshlrev_b32_e32 v0, 2, v0
	v_readlane_b32 s5, v252, 59
	s_nop 4
	v_mov_b32_e32 v60, v151
	v_readlane_b32 s4, v252, 60
	v_readlane_b32 s5, v252, 61
	s_nop 4
	v_mov_b32_e32 v0, v159
	v_mul_f32_e32 v62, v61, v0
	v_mul_f32_e32 v0, v65, v0
	v_fma_f32 v62, v65, v60, -v62
	v_fmac_f32_e32 v0, v61, v60
	v_cvt_pk_bf16_f32 v64, v62, s0
	v_lshl_add_u64 v[62:63], v[136:137], 1, v[58:59]
	v_cvt_pk_bf16_f32 v0, v0, s0
	global_store_short v[62:63], v64, off offset:32
	global_store_short v[62:63], v0, off offset:96
	s_and_saveexec_b64 s[4:5], s[10:11]
	s_cbranch_execz .LBB0_2174
	v_cvt_pk_bf16_f32 v62, v61, s0
	v_lshl_add_u64 v[60:61], v[130:131], 0, v[186:187]
	v_cvt_pk_bf16_f32 v0, v65, s0
	v_lshl_add_u64 v[58:59], v[60:61], 1, v[58:59]
	global_store_short v[58:59], v0, off offset:32
	global_store_short v[58:59], v62, off offset:96
.LBB0_2174:
	s_or_b64 exec, exec, s[4:5]
	v_add_u32_e32 v0, s16, v238
	v_mov_b64_e32 v[58:59], s[72:73]
	s_movk_i32 s4, 0x1b00
	v_lshlrev_b32_e32 v60, 5, v0
	v_mad_i64_i32 v[58:59], s[4:5], v0, s4, v[58:59]
	v_and_b32_e32 v60, 0x1fd80, v60
	v_or_b32_e32 v61, v60, v186
	v_add_u32_e32 v161, 0x3000, v160
	v_readlane_b32 s4, v252, 58
	v_readlane_b32 s5, v252, 59
	s_nop 4
	global_load_dword v144, v161, s[4:5]
	global_load_dword v145, v161, s[4:5] offset:64
	global_load_dword v146, v161, s[4:5] offset:128
	global_load_dword v147, v161, s[4:5] offset:192
	global_load_dword v148, v161, s[4:5] offset:256
	global_load_dword v149, v161, s[4:5] offset:320
	global_load_dword v150, v161, s[4:5] offset:384
	global_load_dword v151, v161, s[4:5] offset:448
	v_readlane_b32 s4, v252, 60
	v_readlane_b32 s5, v252, 61
	s_nop 4
	global_load_dword v152, v161, s[4:5]
	global_load_dword v153, v161, s[4:5] offset:64
	global_load_dword v154, v161, s[4:5] offset:128
	global_load_dword v155, v161, s[4:5] offset:192
	global_load_dword v156, v161, s[4:5] offset:256
	global_load_dword v157, v161, s[4:5] offset:320
	global_load_dword v158, v161, s[4:5] offset:384
	global_load_dword v159, v161, s[4:5] offset:448
	s_waitcnt vmcnt(0)
	v_readlane_b32 s4, v252, 58
	v_lshlrev_b32_e32 v61, 2, v61
	v_readlane_b32 s5, v252, 59
	s_nop 4
	v_mov_b32_e32 v64, v144
	v_readlane_b32 s4, v252, 60
	v_readlane_b32 s5, v252, 61
	s_nop 4
	v_mov_b32_e32 v61, v152
	v_mul_f32_e32 v62, v54, v61
	v_mul_f32_e32 v61, v6, v61
	v_fma_f32 v62, v6, v64, -v62
	v_fmac_f32_e32 v61, v54, v64
	v_cvt_pk_bf16_f32 v65, v62, s0
	v_lshl_add_u64 v[62:63], v[132:133], 1, v[58:59]
	v_cvt_pk_bf16_f32 v61, v61, s0
	global_store_short v[62:63], v65, off
	global_store_short v[62:63], v61, off offset:64
	s_and_saveexec_b64 s[4:5], s[10:11]
	s_cbranch_execz .LBB0_2176
	v_cvt_pk_bf16_f32 v61, v6, s0
	v_lshl_add_u64 v[62:63], v[134:135], 1, v[58:59]
	v_cvt_pk_bf16_f32 v54, v54, s0
	global_store_short v[62:63], v61, off
	global_store_short v[62:63], v54, off offset:64
; DEV u16 f2bf(float f) { return (u16)(pack2(f, 0.f) & 0xffffu); }
; DEV void phase_win(const Params& P, int l, const u16* __restrict__ xb, const u16* __restrict__ Wt, u16* __restrict__ h, char* smem) {
;     ...
;       const int dst = (cb < 256) ? (C_NQR + cb) : cb;
; #pragma unroll
;       for (int ms = 0; ms < 8; ++ms) {
;       asm volatile("" ::: "memory");
; #pragma unroll
;         for (int j = 0; j < 4; ++j) {
;           int row = m0 + wm * 128 + ms * 16 + quad * 4 + j;
;           int pos = row & (S - 1);
;           u16* hr = h + (size_t)row * HS;
; #pragma unroll
;           for (int ns = 0; ns < 2; ++ns) {
;             int d1 = ns * 16 + l15;
;             float x1 = acc[ms][ns][j], x2 = acc[ms][ns + 2][j];
;             float cs = cosT[pos * 32 + d1], sn = sinT[pos * 32 + d1];
;             hr[dst + d1] = f2bf(x1 * cs - x2 * sn);
;             hr[dst + d1 + 32] = f2bf(x1 * sn + x2 * cs);
;             if (cb < 256) {
;               hr[cb + d1] = f2bf(x1);
;               hr[cb + d1 + 32] = f2bf(x2);
;             }
;           }
.LBB0_2176:
	s_or_b64 exec, exec, s[4:5]
	v_or_b32_e32 v54, v60, v240
	v_readlane_b32 s4, v252, 58
	v_lshlrev_b32_e32 v54, 2, v54
	v_readlane_b32 s5, v252, 59
	s_nop 4
	v_mov_b32_e32 v62, v145
	v_readlane_b32 s4, v252, 60
	v_readlane_b32 s5, v252, 61
	s_nop 4
	v_mov_b32_e32 v54, v153
	v_mul_f32_e32 v60, v46, v54
	v_mul_f32_e32 v54, v50, v54
	v_fma_f32 v60, v50, v62, -v60
	v_fmac_f32_e32 v54, v46, v62
	v_cvt_pk_bf16_f32 v63, v60, s0
	v_lshl_add_u64 v[60:61], v[136:137], 1, v[58:59]
	v_cvt_pk_bf16_f32 v54, v54, s0
	global_store_short v[60:61], v63, off offset:32
	global_store_short v[60:61], v54, off offset:96
	s_and_saveexec_b64 s[4:5], s[10:11]
	s_cbranch_execz .LBB0_2178
	v_lshl_add_u64 v[60:61], v[130:131], 0, v[186:187]
	v_cvt_pk_bf16_f32 v50, v50, s0
	v_lshl_add_u64 v[58:59], v[60:61], 1, v[58:59]
	v_cvt_pk_bf16_f32 v46, v46, s0
	global_store_short v[58:59], v50, off offset:32
	global_store_short v[58:59], v46, off offset:96
.LBB0_2178:
	s_or_b64 exec, exec, s[4:5]
	v_or_b32_e32 v46, 1, v0
	v_mov_b64_e32 v[58:59], s[72:73]
	s_movk_i32 s4, 0x1b00
	v_mad_i64_i32 v[58:59], s[4:5], v46, s4, v[58:59]
	v_lshlrev_b32_e32 v46, 5, v46
	v_and_b32_e32 v46, 0x1ffe0, v46
	v_or_b32_e32 v50, v46, v186
	v_readlane_b32 s4, v252, 58
	v_lshlrev_b32_e32 v50, 2, v50
	v_readlane_b32 s5, v252, 59
	s_nop 4
	v_mov_b32_e32 v54, v146
	v_readlane_b32 s4, v252, 60
	v_readlane_b32 s5, v252, 61
	s_nop 4
	v_mov_b32_e32 v50, v154
	v_mul_f32_e32 v60, v55, v50
	v_mul_f32_e32 v50, v7, v50
	v_fma_f32 v60, v7, v54, -v60
	v_fmac_f32_e32 v50, v55, v54
	v_cvt_pk_bf16_f32 v62, v60, s0
	v_lshl_add_u64 v[60:61], v[132:133], 1, v[58:59]
	v_cvt_pk_bf16_f32 v50, v50, s0
	global_store_short v[60:61], v62, off
	global_store_short v[60:61], v50, off offset:64
	s_and_saveexec_b64 s[4:5], s[10:11]
	s_cbranch_execz .LBB0_2180
	v_cvt_pk_bf16_f32 v50, v7, s0
	v_cvt_pk_bf16_f32 v60, v55, s0
	v_lshl_add_u64 v[54:55], v[134:135], 1, v[58:59]
	global_store_short v[54:55], v50, off
	global_store_short v[54:55], v60, off offset:64
.LBB0_2180:
	s_or_b64 exec, exec, s[4:5]
	v_or_b32_e32 v46, v46, v240
	v_readlane_b32 s4, v252, 58
	v_lshlrev_b32_e32 v46, 2, v46
	v_readlane_b32 s5, v252, 59
	s_nop 4
	v_mov_b32_e32 v50, v147
	v_readlane_b32 s4, v252, 60
	v_readlane_b32 s5, v252, 61
	s_nop 4
	v_mov_b32_e32 v46, v155
	v_mul_f32_e32 v54, v47, v46
	v_mul_f32_e32 v46, v51, v46
	v_fma_f32 v54, v51, v50, -v54
	v_fmac_f32_e32 v46, v47, v50
	v_cvt_pk_bf16_f32 v60, v54, s0
	v_lshl_add_u64 v[54:55], v[136:137], 1, v[58:59]
	v_cvt_pk_bf16_f32 v46, v46, s0
	global_store_short v[54:55], v60, off offset:32
	global_store_short v[54:55], v46, off offset:96
	s_and_saveexec_b64 s[4:5], s[10:11]
	s_cbranch_execz .LBB0_2182
	v_cvt_pk_bf16_f32 v50, v51, s0
	v_cvt_pk_bf16_f32 v51, v47, s0
	v_lshl_add_u64 v[46:47], v[130:131], 0, v[186:187]
	v_lshl_add_u64 v[46:47], v[46:47], 1, v[58:59]
	global_store_short v[46:47], v50, off offset:32
	global_store_short v[46:47], v51, off offset:96
.LBB0_2182:
	s_or_b64 exec, exec, s[4:5]
	v_or_b32_e32 v50, 2, v0
	v_mov_b64_e32 v[46:47], s[72:73]
	s_movk_i32 s4, 0x1b00
	v_mad_i64_i32 v[46:47], s[4:5], v50, s4, v[46:47]
	v_lshlrev_b32_e32 v50, 5, v50
	v_and_b32_e32 v50, 0x1ffe0, v50
	v_or_b32_e32 v51, v50, v186
	v_readlane_b32 s4, v252, 58
	v_lshlrev_b32_e32 v51, 2, v51
	v_readlane_b32 s5, v252, 59
	s_nop 4
	v_mov_b32_e32 v58, v148
	v_readlane_b32 s4, v252, 60
	v_readlane_b32 s5, v252, 61
	s_nop 4
	v_mov_b32_e32 v51, v156
	v_mul_f32_e32 v54, v56, v51
	v_mul_f32_e32 v51, v8, v51
	v_fma_f32 v54, v8, v58, -v54
	v_fmac_f32_e32 v51, v56, v58
	v_cvt_pk_bf16_f32 v59, v54, s0
	v_lshl_add_u64 v[54:55], v[132:133], 1, v[46:47]
	v_cvt_pk_bf16_f32 v51, v51, s0
	global_store_short v[54:55], v59, off
	global_store_short v[54:55], v51, off offset:64
	s_and_saveexec_b64 s[4:5], s[10:11]
	s_cbranch_execz .LBB0_2184
	v_cvt_pk_bf16_f32 v51, v8, s0
	v_lshl_add_u64 v[54:55], v[134:135], 1, v[46:47]
	v_cvt_pk_bf16_f32 v56, v56, s0
	global_store_short v[54:55], v51, off
	global_store_short v[54:55], v56, off offset:64
.LBB0_2184:
	s_or_b64 exec, exec, s[4:5]
	v_or_b32_e32 v50, v50, v240
	v_readlane_b32 s4, v252, 58
	v_lshlrev_b32_e32 v50, 2, v50
	v_readlane_b32 s5, v252, 59
	s_nop 4
	v_mov_b32_e32 v54, v149
	v_readlane_b32 s4, v252, 60
	v_readlane_b32 s5, v252, 61
	s_nop 4
	v_mov_b32_e32 v55, v157
	v_mul_f32_e32 v50, v48, v55
	v_mul_f32_e32 v55, v52, v55
	v_fma_f32 v50, v52, v54, -v50
	v_fmac_f32_e32 v55, v48, v54
	v_cvt_pk_bf16_f32 v56, v50, s0
	v_lshl_add_u64 v[50:51], v[136:137], 1, v[46:47]
	v_cvt_pk_bf16_f32 v54, v55, s0
	global_store_short v[50:51], v56, off offset:32
	global_store_short v[50:51], v54, off offset:96
	s_and_saveexec_b64 s[4:5], s[10:11]
	s_cbranch_execz .LBB0_2186
	v_lshl_add_u64 v[50:51], v[130:131], 0, v[186:187]
	v_cvt_pk_bf16_f32 v52, v52, s0
	v_lshl_add_u64 v[46:47], v[50:51], 1, v[46:47]
	v_cvt_pk_bf16_f32 v48, v48, s0
	global_store_short v[46:47], v52, off offset:32
	global_store_short v[46:47], v48, off offset:96
.LBB0_2186:
	s_or_b64 exec, exec, s[4:5]
	v_or_b32_e32 v0, 3, v0
	v_mov_b64_e32 v[46:47], s[72:73]
	s_movk_i32 s4, 0x1b00
	v_mad_i64_i32 v[46:47], s[4:5], v0, s4, v[46:47]
	v_lshlrev_b32_e32 v0, 5, v0
	v_and_b32_e32 v0, 0x1ffe0, v0
	v_or_b32_e32 v48, v0, v186
	v_readlane_b32 s4, v252, 58
	v_lshlrev_b32_e32 v48, 2, v48
	v_readlane_b32 s5, v252, 59
	s_nop 4
	v_mov_b32_e32 v52, v150
	v_readlane_b32 s4, v252, 60
	v_readlane_b32 s5, v252, 61
	s_nop 4
	v_mov_b32_e32 v48, v158
	v_mul_f32_e32 v50, v57, v48
	v_mul_f32_e32 v48, v9, v48
	v_fma_f32 v50, v9, v52, -v50
	v_fmac_f32_e32 v48, v57, v52
	v_cvt_pk_bf16_f32 v54, v50, s0
	v_lshl_add_u64 v[50:51], v[132:133], 1, v[46:47]
	v_cvt_pk_bf16_f32 v48, v48, s0
	global_store_short v[50:51], v54, off
	global_store_short v[50:51], v48, off offset:64
	s_and_saveexec_b64 s[4:5], s[10:11]
	s_cbranch_execz .LBB0_2188
	v_cvt_pk_bf16_f32 v48, v9, s0
	v_lshl_add_u64 v[50:51], v[134:135], 1, v[46:47]
	v_cvt_pk_bf16_f32 v52, v57, s0
	global_store_short v[50:51], v48, off
	global_store_short v[50:51], v52, off offset:64
; DEV u16 f2bf(float f) { return (u16)(pack2(f, 0.f) & 0xffffu); }
; DEV void phase_win(const Params& P, int l, const u16* __restrict__ xb, const u16* __restrict__ Wt, u16* __restrict__ h, char* smem) {
;     ...
;       const int dst = (cb < 256) ? (C_NQR + cb) : cb;
; #pragma unroll
;       for (int ms = 0; ms < 8; ++ms) {
;       asm volatile("" ::: "memory");
; #pragma unroll
;         for (int j = 0; j < 4; ++j) {
;           int row = m0 + wm * 128 + ms * 16 + quad * 4 + j;
;           int pos = row & (S - 1);
;           u16* hr = h + (size_t)row * HS;
; #pragma unroll
;           for (int ns = 0; ns < 2; ++ns) {
;             int d1 = ns * 16 + l15;
;             float x1 = acc[ms][ns][j], x2 = acc[ms][ns + 2][j];
;             float cs = cosT[pos * 32 + d1], sn = sinT[pos * 32 + d1];
;             hr[dst + d1] = f2bf(x1 * cs - x2 * sn);
;             hr[dst + d1 + 32] = f2bf(x1 * sn + x2 * cs);
;             if (cb < 256) {
;               hr[cb + d1] = f2bf(x1);
;               hr[cb + d1 + 32] = f2bf(x2);
;             }
;           }
.LBB0_2188:
	s_or_b64 exec, exec, s[4:5]
	v_or_b32_e32 v0, v0, v240
	v_readlane_b32 s4, v252, 58
	v_lshlrev_b32_e32 v0, 2, v0
	v_readlane_b32 s5, v252, 59
	s_nop 4
	v_mov_b32_e32 v48, v151
	v_readlane_b32 s4, v252, 60
	v_readlane_b32 s5, v252, 61
	s_nop 4
	v_mov_b32_e32 v0, v159
	v_mul_f32_e32 v50, v49, v0
	v_mul_f32_e32 v0, v53, v0
	v_fma_f32 v50, v53, v48, -v50
	v_fmac_f32_e32 v0, v49, v48
	v_cvt_pk_bf16_f32 v52, v50, s0
	v_lshl_add_u64 v[50:51], v[136:137], 1, v[46:47]
	v_cvt_pk_bf16_f32 v0, v0, s0
	global_store_short v[50:51], v52, off offset:32
	global_store_short v[50:51], v0, off offset:96
	s_and_saveexec_b64 s[4:5], s[10:11]
	s_cbranch_execz .LBB0_2190
	v_cvt_pk_bf16_f32 v50, v49, s0
	v_lshl_add_u64 v[48:49], v[130:131], 0, v[186:187]
	v_cvt_pk_bf16_f32 v0, v53, s0
	v_lshl_add_u64 v[46:47], v[48:49], 1, v[46:47]
	global_store_short v[46:47], v0, off offset:32
	global_store_short v[46:47], v50, off offset:96
.LBB0_2190:
	s_or_b64 exec, exec, s[4:5]
	v_add_u32_e32 v0, s16, v239
	v_mov_b64_e32 v[46:47], s[72:73]
	s_movk_i32 s4, 0x1b00
	v_lshlrev_b32_e32 v48, 5, v0
	v_mad_i64_i32 v[46:47], s[4:5], v0, s4, v[46:47]
	v_and_b32_e32 v48, 0x1ff80, v48
	v_or_b32_e32 v49, v48, v186
	v_add_u32_e32 v161, 0x3800, v160
	v_readlane_b32 s4, v252, 58
	v_readlane_b32 s5, v252, 59
	s_nop 4
	global_load_dword v144, v161, s[4:5]
	global_load_dword v145, v161, s[4:5] offset:64
	global_load_dword v146, v161, s[4:5] offset:128
	global_load_dword v147, v161, s[4:5] offset:192
	global_load_dword v148, v161, s[4:5] offset:256
	global_load_dword v149, v161, s[4:5] offset:320
	global_load_dword v150, v161, s[4:5] offset:384
	global_load_dword v151, v161, s[4:5] offset:448
	v_readlane_b32 s4, v252, 60
	v_readlane_b32 s5, v252, 61
	s_nop 4
	global_load_dword v152, v161, s[4:5]
	global_load_dword v153, v161, s[4:5] offset:64
	global_load_dword v154, v161, s[4:5] offset:128
	global_load_dword v155, v161, s[4:5] offset:192
	global_load_dword v156, v161, s[4:5] offset:256
	global_load_dword v157, v161, s[4:5] offset:320
	global_load_dword v158, v161, s[4:5] offset:384
	global_load_dword v159, v161, s[4:5] offset:448
	s_waitcnt vmcnt(0)
	v_readlane_b32 s4, v252, 58
	v_lshlrev_b32_e32 v49, 2, v49
	v_readlane_b32 s5, v252, 59
	s_nop 4
	v_mov_b32_e32 v52, v144
	v_readlane_b32 s4, v252, 60
	v_readlane_b32 s5, v252, 61
	s_nop 4
	v_mov_b32_e32 v49, v152
	v_mul_f32_e32 v50, v42, v49
	v_mul_f32_e32 v49, v2, v49
	v_fma_f32 v50, v2, v52, -v50
	v_fmac_f32_e32 v49, v42, v52
	v_cvt_pk_bf16_f32 v53, v50, s0
	v_lshl_add_u64 v[50:51], v[132:133], 1, v[46:47]
	v_cvt_pk_bf16_f32 v49, v49, s0
	global_store_short v[50:51], v53, off
	global_store_short v[50:51], v49, off offset:64
	s_and_saveexec_b64 s[4:5], s[10:11]
	s_cbranch_execz .LBB0_2192
	v_cvt_pk_bf16_f32 v49, v2, s0
	v_lshl_add_u64 v[50:51], v[134:135], 1, v[46:47]
	v_cvt_pk_bf16_f32 v42, v42, s0
	global_store_short v[50:51], v49, off
	global_store_short v[50:51], v42, off offset:64
.LBB0_2192:
	s_or_b64 exec, exec, s[4:5]
	v_or_b32_e32 v42, v48, v240
	v_readlane_b32 s4, v252, 58
	v_lshlrev_b32_e32 v42, 2, v42
	v_readlane_b32 s5, v252, 59
	s_nop 4
	v_mov_b32_e32 v50, v145
	v_readlane_b32 s4, v252, 60
	v_readlane_b32 s5, v252, 61
	s_nop 4
	v_mov_b32_e32 v42, v153
	v_mul_f32_e32 v48, v30, v42
	v_mul_f32_e32 v42, v34, v42
	v_fma_f32 v48, v34, v50, -v48
	v_fmac_f32_e32 v42, v30, v50
	v_cvt_pk_bf16_f32 v51, v48, s0
	v_lshl_add_u64 v[48:49], v[136:137], 1, v[46:47]
	v_cvt_pk_bf16_f32 v42, v42, s0
	global_store_short v[48:49], v51, off offset:32
	global_store_short v[48:49], v42, off offset:96
	s_and_saveexec_b64 s[4:5], s[10:11]
	s_cbranch_execz .LBB0_2194
	v_lshl_add_u64 v[48:49], v[130:131], 0, v[186:187]
	v_cvt_pk_bf16_f32 v34, v34, s0
	v_lshl_add_u64 v[46:47], v[48:49], 1, v[46:47]
	v_cvt_pk_bf16_f32 v30, v30, s0
	global_store_short v[46:47], v34, off offset:32
	global_store_short v[46:47], v30, off offset:96
.LBB0_2194:
	s_or_b64 exec, exec, s[4:5]
	v_or_b32_e32 v30, 1, v0
	v_mov_b64_e32 v[46:47], s[72:73]
	s_movk_i32 s4, 0x1b00
	v_mad_i64_i32 v[46:47], s[4:5], v30, s4, v[46:47]
	v_lshlrev_b32_e32 v30, 5, v30
	v_and_b32_e32 v30, 0x1ffe0, v30
	v_or_b32_e32 v34, v30, v186
	v_readlane_b32 s4, v252, 58
	v_lshlrev_b32_e32 v34, 2, v34
	v_readlane_b32 s5, v252, 59
	s_nop 4
	v_mov_b32_e32 v42, v146
	v_readlane_b32 s4, v252, 60
	v_readlane_b32 s5, v252, 61
	s_nop 4
	v_mov_b32_e32 v34, v154
	v_mul_f32_e32 v48, v43, v34
	v_mul_f32_e32 v34, v3, v34
	v_fma_f32 v48, v3, v42, -v48
	v_fmac_f32_e32 v34, v43, v42
	v_cvt_pk_bf16_f32 v50, v48, s0
	v_lshl_add_u64 v[48:49], v[132:133], 1, v[46:47]
	v_cvt_pk_bf16_f32 v34, v34, s0
	global_store_short v[48:49], v50, off
	global_store_short v[48:49], v34, off offset:64
	s_and_saveexec_b64 s[4:5], s[10:11]
	s_cbranch_execz .LBB0_2196
	v_cvt_pk_bf16_f32 v34, v3, s0
	v_cvt_pk_bf16_f32 v48, v43, s0
	v_lshl_add_u64 v[42:43], v[134:135], 1, v[46:47]
	global_store_short v[42:43], v34, off
	global_store_short v[42:43], v48, off offset:64
; DEV u16 f2bf(float f) { return (u16)(pack2(f, 0.f) & 0xffffu); }
; DEV void phase_win(const Params& P, int l, const u16* __restrict__ xb, const u16* __restrict__ Wt, u16* __restrict__ h, char* smem) {
;     ...
;       const int dst = (cb < 256) ? (C_NQR + cb) : cb;
; #pragma unroll
;       for (int ms = 0; ms < 8; ++ms) {
;       asm volatile("" ::: "memory");
; #pragma unroll
;         for (int j = 0; j < 4; ++j) {
;           int row = m0 + wm * 128 + ms * 16 + quad * 4 + j;
;           int pos = row & (S - 1);
;           u16* hr = h + (size_t)row * HS;
; #pragma unroll
;           for (int ns = 0; ns < 2; ++ns) {
;             int d1 = ns * 16 + l15;
;             float x1 = acc[ms][ns][j], x2 = acc[ms][ns + 2][j];
;             float cs = cosT[pos * 32 + d1], sn = sinT[pos * 32 + d1];
;             hr[dst + d1] = f2bf(x1 * cs - x2 * sn);
;             hr[dst + d1 + 32] = f2bf(x1 * sn + x2 * cs);
;             if (cb < 256) {
;               hr[cb + d1] = f2bf(x1);
;               hr[cb + d1 + 32] = f2bf(x2);
;             }
;           }
.LBB0_2196:
	s_or_b64 exec, exec, s[4:5]
	v_or_b32_e32 v30, v30, v240
	v_readlane_b32 s4, v252, 58
	v_lshlrev_b32_e32 v30, 2, v30
	v_readlane_b32 s5, v252, 59
	s_nop 4
	v_mov_b32_e32 v34, v147
	v_readlane_b32 s4, v252, 60
	v_readlane_b32 s5, v252, 61
	s_nop 4
	v_mov_b32_e32 v30, v155
	v_mul_f32_e32 v42, v31, v30
	v_mul_f32_e32 v30, v35, v30
	v_fma_f32 v42, v35, v34, -v42
	v_fmac_f32_e32 v30, v31, v34
	v_cvt_pk_bf16_f32 v48, v42, s0
	v_lshl_add_u64 v[42:43], v[136:137], 1, v[46:47]
	v_cvt_pk_bf16_f32 v30, v30, s0
	global_store_short v[42:43], v48, off offset:32
	global_store_short v[42:43], v30, off offset:96
	s_and_saveexec_b64 s[4:5], s[10:11]
	s_cbranch_execz .LBB0_2198
	v_cvt_pk_bf16_f32 v34, v35, s0
	v_cvt_pk_bf16_f32 v35, v31, s0
	v_lshl_add_u64 v[30:31], v[130:131], 0, v[186:187]
	v_lshl_add_u64 v[30:31], v[30:31], 1, v[46:47]
	global_store_short v[30:31], v34, off offset:32
	global_store_short v[30:31], v35, off offset:96
.LBB0_2198:
	s_or_b64 exec, exec, s[4:5]
	v_or_b32_e32 v34, 2, v0
	v_mov_b64_e32 v[30:31], s[72:73]
	s_movk_i32 s4, 0x1b00
	v_mad_i64_i32 v[30:31], s[4:5], v34, s4, v[30:31]
	v_lshlrev_b32_e32 v34, 5, v34
	v_and_b32_e32 v34, 0x1ffe0, v34
	v_or_b32_e32 v35, v34, v186
	v_readlane_b32 s4, v252, 58
	v_lshlrev_b32_e32 v35, 2, v35
	v_readlane_b32 s5, v252, 59
	s_nop 4
	v_mov_b32_e32 v46, v148
	v_readlane_b32 s4, v252, 60
	v_readlane_b32 s5, v252, 61
	s_nop 4
	v_mov_b32_e32 v35, v156
	v_mul_f32_e32 v42, v44, v35
	v_mul_f32_e32 v35, v4, v35
	v_fma_f32 v42, v4, v46, -v42
	v_fmac_f32_e32 v35, v44, v46
	v_cvt_pk_bf16_f32 v47, v42, s0
	v_lshl_add_u64 v[42:43], v[132:133], 1, v[30:31]
	v_cvt_pk_bf16_f32 v35, v35, s0
	global_store_short v[42:43], v47, off
	global_store_short v[42:43], v35, off offset:64
	s_and_saveexec_b64 s[4:5], s[10:11]
	s_cbranch_execz .LBB0_2200
	v_cvt_pk_bf16_f32 v35, v4, s0
	v_lshl_add_u64 v[42:43], v[134:135], 1, v[30:31]
	v_cvt_pk_bf16_f32 v44, v44, s0
	global_store_short v[42:43], v35, off
	global_store_short v[42:43], v44, off offset:64
.LBB0_2200:
	s_or_b64 exec, exec, s[4:5]
	v_or_b32_e32 v34, v34, v240
	v_readlane_b32 s4, v252, 58
	v_lshlrev_b32_e32 v34, 2, v34
	v_readlane_b32 s5, v252, 59
	s_nop 4
	v_mov_b32_e32 v42, v149
	v_readlane_b32 s4, v252, 60
	v_readlane_b32 s5, v252, 61
	s_nop 4
	v_mov_b32_e32 v43, v157
	v_mul_f32_e32 v34, v32, v43
	v_mul_f32_e32 v43, v36, v43
	v_fma_f32 v34, v36, v42, -v34
	v_fmac_f32_e32 v43, v32, v42
	v_cvt_pk_bf16_f32 v44, v34, s0
	v_lshl_add_u64 v[34:35], v[136:137], 1, v[30:31]
	v_cvt_pk_bf16_f32 v42, v43, s0
	global_store_short v[34:35], v44, off offset:32
	global_store_short v[34:35], v42, off offset:96
	s_and_saveexec_b64 s[4:5], s[10:11]
	s_cbranch_execz .LBB0_2202
	v_lshl_add_u64 v[34:35], v[130:131], 0, v[186:187]
	v_cvt_pk_bf16_f32 v36, v36, s0
	v_lshl_add_u64 v[30:31], v[34:35], 1, v[30:31]
	v_cvt_pk_bf16_f32 v32, v32, s0
	global_store_short v[30:31], v36, off offset:32
	global_store_short v[30:31], v32, off offset:96
.LBB0_2202:
	s_or_b64 exec, exec, s[4:5]
	v_or_b32_e32 v32, 3, v0
	v_lshlrev_b32_e32 v0, 5, v32
	v_and_b32_e32 v0, 0x1ffe0, v0
	v_or_b32_e32 v30, v0, v186
	v_readlane_b32 s4, v252, 60
	v_lshlrev_b32_e32 v30, 2, v30
	v_readlane_b32 s5, v252, 61
	s_nop 4
	v_mov_b32_e32 v36, v158
	v_readlane_b32 s4, v252, 58
	v_readlane_b32 s5, v252, 59
	s_nop 4
	v_mov_b32_e32 v42, v150
	v_mov_b64_e32 v[30:31], s[72:73]
	s_movk_i32 s4, 0x1b00
	v_mad_i64_i32 v[30:31], s[4:5], v32, s4, v[30:31]
	v_lshl_add_u64 v[34:35], v[132:133], 1, v[30:31]
	v_mul_f32_e32 v32, v45, v36
	v_mul_f32_e32 v36, v5, v36
	v_fma_f32 v32, v5, v42, -v32
	v_fmac_f32_e32 v36, v45, v42
	v_cvt_pk_bf16_f32 v32, v32, s0
	v_cvt_pk_bf16_f32 v36, v36, s0
	global_store_short v[34:35], v32, off
	global_store_short v[34:35], v36, off offset:64
	s_and_saveexec_b64 s[4:5], s[10:11]
	s_cbranch_execz .LBB0_2204
	v_cvt_pk_bf16_f32 v32, v5, s0
	v_lshl_add_u64 v[34:35], v[134:135], 1, v[30:31]
	v_cvt_pk_bf16_f32 v36, v45, s0
	global_store_short v[34:35], v32, off
	global_store_short v[34:35], v36, off offset:64
.LBB0_2204:
	s_or_b64 exec, exec, s[4:5]
	v_or_b32_e32 v0, v0, v240
	v_readlane_b32 s4, v252, 60
	v_lshlrev_b32_e32 v0, 2, v0
	v_readlane_b32 s5, v252, 61
	v_lshl_add_u64 v[34:35], v[136:137], 1, v[30:31]
	s_nop 3
	v_mov_b32_e32 v32, v159
	v_readlane_b32 s4, v252, 58
	v_readlane_b32 s5, v252, 59
	v_mul_f32_e32 v36, v33, v32
	s_nop 2
	v_mov_b32_e32 v0, v151
	v_mul_f32_e32 v32, v37, v32
	v_fma_f32 v36, v37, v0, -v36
	v_fmac_f32_e32 v32, v33, v0
	v_cvt_pk_bf16_f32 v0, v36, s0
	v_cvt_pk_bf16_f32 v32, v32, s0
	global_store_short v[34:35], v0, off offset:32
	global_store_short v[34:35], v32, off offset:96
	s_and_b64 exec, exec, s[10:11]
	s_cbranch_execz .LBB0_2206
	v_cvt_pk_bf16_f32 v34, v33, s0
	v_lshl_add_u64 v[32:33], v[130:131], 0, v[186:187]
	v_cvt_pk_bf16_f32 v0, v37, s0
	v_lshl_add_u64 v[30:31], v[32:33], 1, v[30:31]
	global_store_short v[30:31], v0, off offset:32
	global_store_short v[30:31], v34, off offset:96

; DEV void phase_ln(const Params& P, const float* __restrict__ g, const float* __restrict__ bta, u16* __restrict__ xb, bool zero_kc) {
;     ...
;   for (int row = gw; row < T; row += 2 * nw) {
;     const bool hasB = (row + nw) < T;
;     const int rows[2] = {row, hasB ? row + nw : row};
;     float4 v[2][4];
; #pragma unroll
;     for (int r = 0; r < 2; ++r) {
;       const float* xr = P.out + (size_t)rows[r] * D + lane * 4;
; #pragma unroll
;       for (int i = 0; i < 4; ++i) v[r][i] = *(const float4*)(xr + i * 256);
;     }
;     float s[2] = {0.f, 0.f};
; #pragma unroll
;     for (int r = 0; r < 2; ++r)
; #pragma unroll
;       for (int i = 0; i < 4; ++i) s[r] += v[r][i].x + v[r][i].y + v[r][i].z + v[r][i].w;
; #pragma unroll
;     for (int o = 32; o >= 1; o >>= 1) {
;       s[0] += __shfl_xor(s[0], o);
;       s[1] += __shfl_xor(s[1], o);
;     }
.Lln_loop_3:
	s_add_i32 s8, s4, 0
	s_min_i32 s8, s8, 0x7fff
	s_lshl_b32 s8, s8, 12
	v_add_u32_e32 v72, s8, v35
	global_load_dwordx4 v[108:111], v72, s[86:87]
	global_load_dwordx4 v[112:115], v72, s[86:87] offset:1024
	global_load_dwordx4 v[116:119], v72, s[86:87] offset:2048
	global_load_dwordx4 v[120:123], v72, s[86:87] offset:3072
	s_add_i32 s8, s4, 1
	s_min_i32 s8, s8, 0x7fff
	s_lshl_b32 s8, s8, 12
	v_add_u32_e32 v73, s8, v35
	global_load_dwordx4 v[124:127], v73, s[86:87]
	global_load_dwordx4 v[128:131], v73, s[86:87] offset:1024
	global_load_dwordx4 v[132:135], v73, s[86:87] offset:2048
	global_load_dwordx4 v[136:139], v73, s[86:87] offset:3072
	s_add_i32 s8, s4, 2
	s_min_i32 s8, s8, 0x7fff
	s_lshl_b32 s8, s8, 12
	v_add_u32_e32 v74, s8, v35
	global_load_dwordx4 v[140:143], v74, s[86:87]
	global_load_dwordx4 v[144:147], v74, s[86:87] offset:1024
	global_load_dwordx4 v[148:151], v74, s[86:87] offset:2048
	global_load_dwordx4 v[152:155], v74, s[86:87] offset:3072
	s_add_i32 s8, s4, 3
	s_min_i32 s8, s8, 0x7fff
	s_lshl_b32 s8, s8, 12
	v_add_u32_e32 v75, s8, v35
	global_load_dwordx4 v[156:159], v75, s[86:87]
	global_load_dwordx4 v[160:163], v75, s[86:87] offset:1024
	global_load_dwordx4 v[164:167], v75, s[86:87] offset:2048
	global_load_dwordx4 v[168:171], v75, s[86:87] offset:3072
	s_waitcnt vmcnt(0)
	v_add_f32_e32 v42, v108, v109
	v_add_f32_e32 v42, v42, v110
	v_add_f32_e32 v42, v42, v111
	v_add_f32_e32 v60, v112, v113
	v_add_f32_e32 v60, v60, v114
	v_add_f32_e32 v60, v60, v115
	v_add_f32_e32 v42, v42, v60
	v_add_f32_e32 v60, v116, v117
	v_add_f32_e32 v60, v60, v118
	v_add_f32_e32 v60, v60, v119
	v_add_f32_e32 v42, v42, v60
	v_add_f32_e32 v60, v120, v121
	v_add_f32_e32 v60, v60, v122
	v_add_f32_e32 v60, v60, v123
	v_add_f32_e32 v42, v42, v60
	v_add_f32_e32 v43, v124, v125
	v_add_f32_e32 v43, v43, v126
	v_add_f32_e32 v43, v43, v127
	v_add_f32_e32 v61, v128, v129
	v_add_f32_e32 v61, v61, v130
	v_add_f32_e32 v61, v61, v131
	v_add_f32_e32 v43, v43, v61
	v_add_f32_e32 v61, v132, v133
	v_add_f32_e32 v61, v61, v134
	v_add_f32_e32 v61, v61, v135
	v_add_f32_e32 v43, v43, v61
	v_add_f32_e32 v61, v136, v137
	v_add_f32_e32 v61, v61, v138
	v_add_f32_e32 v61, v61, v139
	v_add_f32_e32 v43, v43, v61
	v_add_f32_e32 v44, v140, v141
	v_add_f32_e32 v44, v44, v142
	v_add_f32_e32 v44, v44, v143
	v_add_f32_e32 v62, v144, v145
	v_add_f32_e32 v62, v62, v146
	v_add_f32_e32 v62, v62, v147
	v_add_f32_e32 v44, v44, v62
	v_add_f32_e32 v62, v148, v149
	v_add_f32_e32 v62, v62, v150
	v_add_f32_e32 v62, v62, v151
	v_add_f32_e32 v44, v44, v62
	v_add_f32_e32 v62, v152, v153
	v_add_f32_e32 v62, v62, v154
	v_add_f32_e32 v62, v62, v155
	v_add_f32_e32 v44, v44, v62
	v_add_f32_e32 v45, v156, v157
	v_add_f32_e32 v45, v45, v158
	v_add_f32_e32 v45, v45, v159
	v_add_f32_e32 v63, v160, v161
	v_add_f32_e32 v63, v63, v162
	v_add_f32_e32 v63, v63, v163
	v_add_f32_e32 v45, v45, v63
	v_add_f32_e32 v63, v164, v165
	v_add_f32_e32 v63, v63, v166
	v_add_f32_e32 v63, v63, v167
	v_add_f32_e32 v45, v45, v63
	v_add_f32_e32 v63, v168, v169
	v_add_f32_e32 v63, v63, v170
	v_add_f32_e32 v63, v63, v171
	v_add_f32_e32 v45, v45, v63
	ds_bpermute_b32 v60, v96, v42
	ds_bpermute_b32 v61, v96, v43
	ds_bpermute_b32 v62, v96, v44
	ds_bpermute_b32 v63, v96, v45
	s_waitcnt lgkmcnt(3)
	v_add_f32_e32 v42, v42, v60
	s_waitcnt lgkmcnt(2)
	v_add_f32_e32 v43, v43, v61
	s_waitcnt lgkmcnt(1)
	v_add_f32_e32 v44, v44, v62
	s_waitcnt lgkmcnt(0)
	v_add_f32_e32 v45, v45, v63
	ds_bpermute_b32 v60, v97, v42
	ds_bpermute_b32 v61, v97, v43
	ds_bpermute_b32 v62, v97, v44
	ds_bpermute_b32 v63, v97, v45
	s_waitcnt lgkmcnt(3)
	v_add_f32_e32 v42, v42, v60
	s_waitcnt lgkmcnt(2)
	v_add_f32_e32 v43, v43, v61
	s_waitcnt lgkmcnt(1)
	v_add_f32_e32 v44, v44, v62
	s_waitcnt lgkmcnt(0)
	v_add_f32_e32 v45, v45, v63
	ds_bpermute_b32 v60, v98, v42
	ds_bpermute_b32 v61, v98, v43
	ds_bpermute_b32 v62, v98, v44
	ds_bpermute_b32 v63, v98, v45
	s_waitcnt lgkmcnt(3)
	v_add_f32_e32 v42, v42, v60
	s_waitcnt lgkmcnt(2)
	v_add_f32_e32 v43, v43, v61
	s_waitcnt lgkmcnt(1)
	v_add_f32_e32 v44, v44, v62
	s_waitcnt lgkmcnt(0)
	v_add_f32_e32 v45, v45, v63
	ds_bpermute_b32 v60, v99, v42
	ds_bpermute_b32 v61, v99, v43
	ds_bpermute_b32 v62, v99, v44
	ds_bpermute_b32 v63, v99, v45
	s_waitcnt lgkmcnt(3)
	v_add_f32_e32 v42, v42, v60
	s_waitcnt lgkmcnt(2)
	v_add_f32_e32 v43, v43, v61
	s_waitcnt lgkmcnt(1)
	v_add_f32_e32 v44, v44, v62
	s_waitcnt lgkmcnt(0)
	v_add_f32_e32 v45, v45, v63
	ds_bpermute_b32 v60, v100, v42
	ds_bpermute_b32 v61, v100, v43
	ds_bpermute_b32 v62, v100, v44
	ds_bpermute_b32 v63, v100, v45
	s_waitcnt lgkmcnt(3)
	v_add_f32_e32 v42, v42, v60
	s_waitcnt lgkmcnt(2)
	v_add_f32_e32 v43, v43, v61
	s_waitcnt lgkmcnt(1)
	v_add_f32_e32 v44, v44, v62
	s_waitcnt lgkmcnt(0)
	v_add_f32_e32 v45, v45, v63
	ds_bpermute_b32 v60, v101, v42
	ds_bpermute_b32 v61, v101, v43
	ds_bpermute_b32 v62, v101, v44
	ds_bpermute_b32 v63, v101, v45
	s_waitcnt lgkmcnt(3)
	v_add_f32_e32 v42, v42, v60
	s_waitcnt lgkmcnt(2)
	v_add_f32_e32 v43, v43, v61
	s_waitcnt lgkmcnt(1)
	v_add_f32_e32 v44, v44, v62
	s_waitcnt lgkmcnt(0)
; DEV void phase_ln(const Params& P, const float* __restrict__ g, const float* __restrict__ bta, u16* __restrict__ xb, bool zero_kc) {
;     ...
;     float q[2] = {0.f, 0.f};
; #pragma unroll
;     for (int r = 0; r < 2; ++r) {
;       const float mu = s[r] * (1.f / 1024.f);
; #pragma unroll
;       for (int i = 0; i < 4; ++i) {
;         v[r][i].x -= mu; v[r][i].y -= mu; v[r][i].z -= mu; v[r][i].w -= mu;
;         q[r] += v[r][i].x * v[r][i].x + v[r][i].y * v[r][i].y + v[r][i].z * v[r][i].z + v[r][i].w * v[r][i].w;
;       }
;     }
; #pragma unroll
;     for (int o = 32; o >= 1; o >>= 1) {
;       q[0] += __shfl_xor(q[0], o);
;       q[1] += __shfl_xor(q[1], o);
;     }
	v_add_f32_e32 v45, v45, v63
	v_mul_f32_e32 v42, 0x3a800000, v42
	v_mul_f32_e32 v43, 0x3a800000, v43
	v_mul_f32_e32 v44, 0x3a800000, v44
	v_mul_f32_e32 v45, 0x3a800000, v45
	v_sub_f32_e32 v108, v108, v42
	v_sub_f32_e32 v109, v109, v42
	v_sub_f32_e32 v110, v110, v42
	v_sub_f32_e32 v111, v111, v42
	v_mul_f32_e32 v46, v108, v108
	v_fmac_f32_e32 v46, v109, v109
	v_fmac_f32_e32 v46, v110, v110
	v_fmac_f32_e32 v46, v111, v111
	v_sub_f32_e32 v112, v112, v42
	v_sub_f32_e32 v113, v113, v42
	v_sub_f32_e32 v114, v114, v42
	v_sub_f32_e32 v115, v115, v42
	v_mul_f32_e32 v60, v112, v112
	v_fmac_f32_e32 v60, v113, v113
	v_fmac_f32_e32 v60, v114, v114
	v_fmac_f32_e32 v60, v115, v115
	v_add_f32_e32 v46, v46, v60
	v_sub_f32_e32 v116, v116, v42
	v_sub_f32_e32 v117, v117, v42
	v_sub_f32_e32 v118, v118, v42
	v_sub_f32_e32 v119, v119, v42
	v_mul_f32_e32 v60, v116, v116
	v_fmac_f32_e32 v60, v117, v117
	v_fmac_f32_e32 v60, v118, v118
	v_fmac_f32_e32 v60, v119, v119
	v_add_f32_e32 v46, v46, v60
	v_sub_f32_e32 v120, v120, v42
	v_sub_f32_e32 v121, v121, v42
	v_sub_f32_e32 v122, v122, v42
	v_sub_f32_e32 v123, v123, v42
	v_mul_f32_e32 v60, v120, v120
	v_fmac_f32_e32 v60, v121, v121
	v_fmac_f32_e32 v60, v122, v122
	v_fmac_f32_e32 v60, v123, v123
	v_add_f32_e32 v46, v46, v60
	v_sub_f32_e32 v124, v124, v43
	v_sub_f32_e32 v125, v125, v43
	v_sub_f32_e32 v126, v126, v43
	v_sub_f32_e32 v127, v127, v43
	v_mul_f32_e32 v48, v124, v124
	v_fmac_f32_e32 v48, v125, v125
	v_fmac_f32_e32 v48, v126, v126
	v_fmac_f32_e32 v48, v127, v127
	v_sub_f32_e32 v128, v128, v43
	v_sub_f32_e32 v129, v129, v43
	v_sub_f32_e32 v130, v130, v43
	v_sub_f32_e32 v131, v131, v43
	v_mul_f32_e32 v61, v128, v128
	v_fmac_f32_e32 v61, v129, v129
	v_fmac_f32_e32 v61, v130, v130
	v_fmac_f32_e32 v61, v131, v131
	v_add_f32_e32 v48, v48, v61
	v_sub_f32_e32 v132, v132, v43
	v_sub_f32_e32 v133, v133, v43
	v_sub_f32_e32 v134, v134, v43
	v_sub_f32_e32 v135, v135, v43
	v_mul_f32_e32 v61, v132, v132
	v_fmac_f32_e32 v61, v133, v133
	v_fmac_f32_e32 v61, v134, v134
	v_fmac_f32_e32 v61, v135, v135
	v_add_f32_e32 v48, v48, v61
	v_sub_f32_e32 v136, v136, v43
	v_sub_f32_e32 v137, v137, v43
	v_sub_f32_e32 v138, v138, v43
	v_sub_f32_e32 v139, v139, v43
	v_mul_f32_e32 v61, v136, v136
	v_fmac_f32_e32 v61, v137, v137
	v_fmac_f32_e32 v61, v138, v138
	v_fmac_f32_e32 v61, v139, v139
	v_add_f32_e32 v48, v48, v61
	v_sub_f32_e32 v140, v140, v44
	v_sub_f32_e32 v141, v141, v44
	v_sub_f32_e32 v142, v142, v44
	v_sub_f32_e32 v143, v143, v44
	v_mul_f32_e32 v50, v140, v140
	v_fmac_f32_e32 v50, v141, v141
	v_fmac_f32_e32 v50, v142, v142
	v_fmac_f32_e32 v50, v143, v143
	v_sub_f32_e32 v144, v144, v44
	v_sub_f32_e32 v145, v145, v44
	v_sub_f32_e32 v146, v146, v44
	v_sub_f32_e32 v147, v147, v44
	v_mul_f32_e32 v62, v144, v144
	v_fmac_f32_e32 v62, v145, v145
	v_fmac_f32_e32 v62, v146, v146
	v_fmac_f32_e32 v62, v147, v147
	v_add_f32_e32 v50, v50, v62
	v_sub_f32_e32 v148, v148, v44
	v_sub_f32_e32 v149, v149, v44
	v_sub_f32_e32 v150, v150, v44
	v_sub_f32_e32 v151, v151, v44
	v_mul_f32_e32 v62, v148, v148
	v_fmac_f32_e32 v62, v149, v149
	v_fmac_f32_e32 v62, v150, v150
	v_fmac_f32_e32 v62, v151, v151
	v_add_f32_e32 v50, v50, v62
	v_sub_f32_e32 v152, v152, v44
	v_sub_f32_e32 v153, v153, v44
	v_sub_f32_e32 v154, v154, v44
	v_sub_f32_e32 v155, v155, v44
	v_mul_f32_e32 v62, v152, v152
	v_fmac_f32_e32 v62, v153, v153
	v_fmac_f32_e32 v62, v154, v154
	v_fmac_f32_e32 v62, v155, v155
	v_add_f32_e32 v50, v50, v62
	v_sub_f32_e32 v156, v156, v45
	v_sub_f32_e32 v157, v157, v45
	v_sub_f32_e32 v158, v158, v45
	v_sub_f32_e32 v159, v159, v45
	v_mul_f32_e32 v52, v156, v156
	v_fmac_f32_e32 v52, v157, v157
	v_fmac_f32_e32 v52, v158, v158
	v_fmac_f32_e32 v52, v159, v159
	v_sub_f32_e32 v160, v160, v45
	v_sub_f32_e32 v161, v161, v45
	v_sub_f32_e32 v162, v162, v45
	v_sub_f32_e32 v163, v163, v45
	v_mul_f32_e32 v63, v160, v160
	v_fmac_f32_e32 v63, v161, v161
	v_fmac_f32_e32 v63, v162, v162
	v_fmac_f32_e32 v63, v163, v163
	v_add_f32_e32 v52, v52, v63
	v_sub_f32_e32 v164, v164, v45
	v_sub_f32_e32 v165, v165, v45
	v_sub_f32_e32 v166, v166, v45
	v_sub_f32_e32 v167, v167, v45
	v_mul_f32_e32 v63, v164, v164
	v_fmac_f32_e32 v63, v165, v165
	v_fmac_f32_e32 v63, v166, v166
	v_fmac_f32_e32 v63, v167, v167
	v_add_f32_e32 v52, v52, v63
	v_sub_f32_e32 v168, v168, v45
	v_sub_f32_e32 v169, v169, v45
	v_sub_f32_e32 v170, v170, v45
	v_sub_f32_e32 v171, v171, v45
	v_mul_f32_e32 v63, v168, v168
	v_fmac_f32_e32 v63, v169, v169
	v_fmac_f32_e32 v63, v170, v170
	v_fmac_f32_e32 v63, v171, v171
	v_add_f32_e32 v52, v52, v63
	ds_bpermute_b32 v60, v96, v46
	ds_bpermute_b32 v61, v96, v48
	ds_bpermute_b32 v62, v96, v50
	ds_bpermute_b32 v63, v96, v52
	s_waitcnt lgkmcnt(3)
	v_add_f32_e32 v46, v46, v60
	s_waitcnt lgkmcnt(2)
	v_add_f32_e32 v48, v48, v61
	s_waitcnt lgkmcnt(1)
	v_add_f32_e32 v50, v50, v62
	s_waitcnt lgkmcnt(0)
	v_add_f32_e32 v52, v52, v63
	ds_bpermute_b32 v60, v97, v46
	ds_bpermute_b32 v61, v97, v48
	ds_bpermute_b32 v62, v97, v50
	ds_bpermute_b32 v63, v97, v52
	s_waitcnt lgkmcnt(3)
	v_add_f32_e32 v46, v46, v60
	s_waitcnt lgkmcnt(2)
	v_add_f32_e32 v48, v48, v61
	s_waitcnt lgkmcnt(1)
	v_add_f32_e32 v50, v50, v62
	s_waitcnt lgkmcnt(0)
	v_add_f32_e32 v52, v52, v63
	ds_bpermute_b32 v60, v98, v46
	ds_bpermute_b32 v61, v98, v48
	ds_bpermute_b32 v62, v98, v50
	ds_bpermute_b32 v63, v98, v52
	s_waitcnt lgkmcnt(3)
	v_add_f32_e32 v46, v46, v60
	s_waitcnt lgkmcnt(2)
	v_add_f32_e32 v48, v48, v61
	s_waitcnt lgkmcnt(1)
	v_add_f32_e32 v50, v50, v62
	s_waitcnt lgkmcnt(0)
	v_add_f32_e32 v52, v52, v63
	ds_bpermute_b32 v60, v99, v46
	ds_bpermute_b32 v61, v99, v48
	ds_bpermute_b32 v62, v99, v50
	ds_bpermute_b32 v63, v99, v52
	s_waitcnt lgkmcnt(3)
; DEV void phase_ln(const Params& P, const float* __restrict__ g, const float* __restrict__ bta, u16* __restrict__ xb, bool zero_kc) {
;     ...
;     for (int r = 0; r < 2; ++r) {
;       if (r == 1 && !hasB) break;
;       const float rs = rsqrtf(q[r] * (1.f / 1024.f) + 1e-5f);
;       const int rw = rows[r];
;       float* xr = P.out + (size_t)rw * D;
; #pragma unroll
;       for (int i = 0; i < 4; ++i) {
;         float4 y;
;         y.x = v[r][i].x * rs * gv[i].x + bv[i].x;
;         y.y = v[r][i].y * rs * gv[i].y + bv[i].y;
;         y.z = v[r][i].z * rs * gv[i].z + bv[i].z;
;         y.w = v[r][i].w * rs * gv[i].w + bv[i].w;
;         *(float4*)(xr + i * 256 + lane * 4) = y;
;         const int col = i * 256 + lane * 4;
;         *(uint2*)(xb + (size_t)(rw >> 8) * (256 * D) + (size_t)(col >> 5) * 8192 + (rw & 255) * 32 + (col & 31)) = make_uint2(pack2(y.x, y.y), pack2(y.z, y.w));
;       }
	v_add_f32_e32 v46, v46, v60
	s_waitcnt lgkmcnt(2)
	v_add_f32_e32 v48, v48, v61
	s_waitcnt lgkmcnt(1)
	v_add_f32_e32 v50, v50, v62
	s_waitcnt lgkmcnt(0)
	v_add_f32_e32 v52, v52, v63
	ds_bpermute_b32 v60, v100, v46
	ds_bpermute_b32 v61, v100, v48
	ds_bpermute_b32 v62, v100, v50
	ds_bpermute_b32 v63, v100, v52
	s_waitcnt lgkmcnt(3)
	v_add_f32_e32 v46, v46, v60
	s_waitcnt lgkmcnt(2)
	v_add_f32_e32 v48, v48, v61
	s_waitcnt lgkmcnt(1)
	v_add_f32_e32 v50, v50, v62
	s_waitcnt lgkmcnt(0)
	v_add_f32_e32 v52, v52, v63
	ds_bpermute_b32 v60, v101, v46
	ds_bpermute_b32 v61, v101, v48
	ds_bpermute_b32 v62, v101, v50
	ds_bpermute_b32 v63, v101, v52
	s_waitcnt lgkmcnt(3)
	v_add_f32_e32 v46, v46, v60
	s_waitcnt lgkmcnt(2)
	v_add_f32_e32 v48, v48, v61
	s_waitcnt lgkmcnt(1)
	v_add_f32_e32 v50, v50, v62
	s_waitcnt lgkmcnt(0)
	v_add_f32_e32 v52, v52, v63
	s_mov_b32 s2, 0x800000
	v_fmamk_f32 v46, v46, 0x3a800000, v216
	v_cmp_gt_f32_e32 vcc, s2, v46
	v_mul_f32_e32 v60, 0x4b800000, v46
	s_nop 1
	v_cndmask_b32_e32 v46, v46, v60, vcc
	v_rsq_f32_e32 v46, v46
	s_nop 0
	v_mul_f32_e32 v60, 0x45800000, v46
	s_nop 0
	v_cndmask_b32_e32 v46, v46, v60, vcc
	v_fmamk_f32 v48, v48, 0x3a800000, v216
	v_cmp_gt_f32_e32 vcc, s2, v48
	v_mul_f32_e32 v61, 0x4b800000, v48
	s_nop 1
	v_cndmask_b32_e32 v48, v48, v61, vcc
	v_rsq_f32_e32 v48, v48
	s_nop 0
	v_mul_f32_e32 v61, 0x45800000, v48
	s_nop 0
	v_cndmask_b32_e32 v48, v48, v61, vcc
	v_fmamk_f32 v50, v50, 0x3a800000, v216
	v_cmp_gt_f32_e32 vcc, s2, v50
	v_mul_f32_e32 v62, 0x4b800000, v50
	s_nop 1
	v_cndmask_b32_e32 v50, v50, v62, vcc
	v_rsq_f32_e32 v50, v50
	s_nop 0
	v_mul_f32_e32 v62, 0x45800000, v50
	s_nop 0
	v_cndmask_b32_e32 v50, v50, v62, vcc
	v_fmamk_f32 v52, v52, 0x3a800000, v216
	v_cmp_gt_f32_e32 vcc, s2, v52
	v_mul_f32_e32 v63, 0x4b800000, v52
	s_nop 1
	v_cndmask_b32_e32 v52, v52, v63, vcc
	v_rsq_f32_e32 v52, v52
	s_nop 0
	v_mul_f32_e32 v63, 0x45800000, v52
	s_nop 0
	v_cndmask_b32_e32 v52, v52, v63, vcc
	s_add_i32 s9, s4, 0
	s_cmp_lt_i32 s9, 0x8000
	s_cbranch_scc0 .Lln_skip_3_0
	s_lshr_b32 s8, s9, 8
	s_lshl_b32 s8, s8, 19
	s_and_b32 s2, s9, 0xff
	s_lshl_b32 s2, s2, 6
	s_add_i32 s8, s8, s2
	v_pk_mul_f32 v[64:65], v[108:109], v[46:47] op_sel_hi:[1,0]
	v_pk_mul_f32 v[66:67], v[110:111], v[46:47] op_sel_hi:[1,0]
	v_pk_fma_f32 v[64:65], v[2:3], v[64:65], v[10:11]
	v_pk_fma_f32 v[66:67], v[4:5], v[66:67], v[12:13]
	global_store_dwordx4 v72, v[64:67], s[86:87]
	v_add_u32_e32 v70, s8, v36
	v_cvt_pk_bf16_f32 v68, v64, v65
	v_cvt_pk_bf16_f32 v69, v66, v67
	global_store_dwordx2 v70, v[68:69], s[42:43]
	v_pk_mul_f32 v[64:65], v[112:113], v[46:47] op_sel_hi:[1,0]
	v_pk_mul_f32 v[66:67], v[114:115], v[46:47] op_sel_hi:[1,0]
	v_pk_fma_f32 v[64:65], v[6:7], v[64:65], v[14:15]
	v_pk_fma_f32 v[66:67], v[8:9], v[66:67], v[16:17]
	global_store_dwordx4 v72, v[64:67], s[86:87] offset:1024
	v_add_u32_e32 v70, s8, v37
	v_cvt_pk_bf16_f32 v68, v64, v65
	v_cvt_pk_bf16_f32 v69, v66, v67
	global_store_dwordx2 v70, v[68:69], s[42:43]
	v_pk_mul_f32 v[64:65], v[116:117], v[46:47] op_sel_hi:[1,0]
	v_pk_mul_f32 v[66:67], v[118:119], v[46:47] op_sel_hi:[1,0]
	v_pk_fma_f32 v[64:65], v[18:19], v[64:65], v[26:27]
	v_pk_fma_f32 v[66:67], v[20:21], v[66:67], v[28:29]
	global_store_dwordx4 v72, v[64:67], s[86:87] offset:2048
	v_add_u32_e32 v70, s8, v38
	v_cvt_pk_bf16_f32 v68, v64, v65
	v_cvt_pk_bf16_f32 v69, v66, v67
	global_store_dwordx2 v70, v[68:69], s[42:43]
	v_pk_mul_f32 v[64:65], v[120:121], v[46:47] op_sel_hi:[1,0]
	v_pk_mul_f32 v[66:67], v[122:123], v[46:47] op_sel_hi:[1,0]
	v_pk_fma_f32 v[64:65], v[22:23], v[64:65], v[30:31]
	v_pk_fma_f32 v[66:67], v[24:25], v[66:67], v[32:33]
	global_store_dwordx4 v72, v[64:67], s[86:87] offset:3072
	v_add_u32_e32 v70, s8, v39
	v_cvt_pk_bf16_f32 v68, v64, v65
	v_cvt_pk_bf16_f32 v69, v66, v67
	global_store_dwordx2 v70, v[68:69], s[42:43]
; DEV void phase_ln(const Params& P, const float* __restrict__ g, const float* __restrict__ bta, u16* __restrict__ xb, bool zero_kc) {
;     ...
; #pragma unroll
;     for (int r = 0; r < 2; ++r) {
;       if (r == 1 && !hasB) break;
;       const float rs = rsqrtf(q[r] * (1.f / 1024.f) + 1e-5f);
;       const int rw = rows[r];
;       float* xr = P.out + (size_t)rw * D;
; #pragma unroll
;       for (int i = 0; i < 4; ++i) {
;         float4 y;
;         y.x = v[r][i].x * rs * gv[i].x + bv[i].x;
;         y.y = v[r][i].y * rs * gv[i].y + bv[i].y;
;         y.z = v[r][i].z * rs * gv[i].z + bv[i].z;
;         y.w = v[r][i].w * rs * gv[i].w + bv[i].w;
;         *(float4*)(xr + i * 256 + lane * 4) = y;
;         const int col = i * 256 + lane * 4;
;         *(uint2*)(xb + (size_t)(rw >> 8) * (256 * D) + (size_t)(col >> 5) * 8192 + (rw & 255) * 32 + (col & 31)) = make_uint2(pack2(y.x, y.y), pack2(y.z, y.w));
;       }
;     }
.Lln_skip_3_0:
	s_add_i32 s9, s4, 1
	s_cmp_lt_i32 s9, 0x8000
	s_cbranch_scc0 .Lln_skip_3_1
	s_lshr_b32 s8, s9, 8
	s_lshl_b32 s8, s8, 19
	s_and_b32 s2, s9, 0xff
	s_lshl_b32 s2, s2, 6
	s_add_i32 s8, s8, s2
	v_pk_mul_f32 v[64:65], v[124:125], v[48:49] op_sel_hi:[1,0]
	v_pk_mul_f32 v[66:67], v[126:127], v[48:49] op_sel_hi:[1,0]
	v_pk_fma_f32 v[64:65], v[2:3], v[64:65], v[10:11]
	v_pk_fma_f32 v[66:67], v[4:5], v[66:67], v[12:13]
	global_store_dwordx4 v73, v[64:67], s[86:87]
	v_add_u32_e32 v70, s8, v36
	v_cvt_pk_bf16_f32 v68, v64, v65
	v_cvt_pk_bf16_f32 v69, v66, v67
	global_store_dwordx2 v70, v[68:69], s[42:43]
	v_pk_mul_f32 v[64:65], v[128:129], v[48:49] op_sel_hi:[1,0]
	v_pk_mul_f32 v[66:67], v[130:131], v[48:49] op_sel_hi:[1,0]
	v_pk_fma_f32 v[64:65], v[6:7], v[64:65], v[14:15]
	v_pk_fma_f32 v[66:67], v[8:9], v[66:67], v[16:17]
	global_store_dwordx4 v73, v[64:67], s[86:87] offset:1024
	v_add_u32_e32 v70, s8, v37
	v_cvt_pk_bf16_f32 v68, v64, v65
	v_cvt_pk_bf16_f32 v69, v66, v67
	global_store_dwordx2 v70, v[68:69], s[42:43]
	v_pk_mul_f32 v[64:65], v[132:133], v[48:49] op_sel_hi:[1,0]
	v_pk_mul_f32 v[66:67], v[134:135], v[48:49] op_sel_hi:[1,0]
	v_pk_fma_f32 v[64:65], v[18:19], v[64:65], v[26:27]
	v_pk_fma_f32 v[66:67], v[20:21], v[66:67], v[28:29]
	global_store_dwordx4 v73, v[64:67], s[86:87] offset:2048
	v_add_u32_e32 v70, s8, v38
	v_cvt_pk_bf16_f32 v68, v64, v65
	v_cvt_pk_bf16_f32 v69, v66, v67
	global_store_dwordx2 v70, v[68:69], s[42:43]
	v_pk_mul_f32 v[64:65], v[136:137], v[48:49] op_sel_hi:[1,0]
	v_pk_mul_f32 v[66:67], v[138:139], v[48:49] op_sel_hi:[1,0]
	v_pk_fma_f32 v[64:65], v[22:23], v[64:65], v[30:31]
	v_pk_fma_f32 v[66:67], v[24:25], v[66:67], v[32:33]
	global_store_dwordx4 v73, v[64:67], s[86:87] offset:3072
	v_add_u32_e32 v70, s8, v39
	v_cvt_pk_bf16_f32 v68, v64, v65
	v_cvt_pk_bf16_f32 v69, v66, v67
	global_store_dwordx2 v70, v[68:69], s[42:43]
.Lln_skip_3_1:
	s_add_i32 s9, s4, 2
	s_cmp_lt_i32 s9, 0x8000
	s_cbranch_scc0 .Lln_skip_3_2
	s_lshr_b32 s8, s9, 8
	s_lshl_b32 s8, s8, 19
	s_and_b32 s2, s9, 0xff
	s_lshl_b32 s2, s2, 6
	s_add_i32 s8, s8, s2
	v_pk_mul_f32 v[64:65], v[140:141], v[50:51] op_sel_hi:[1,0]
	v_pk_mul_f32 v[66:67], v[142:143], v[50:51] op_sel_hi:[1,0]
	v_pk_fma_f32 v[64:65], v[2:3], v[64:65], v[10:11]
	v_pk_fma_f32 v[66:67], v[4:5], v[66:67], v[12:13]
	global_store_dwordx4 v74, v[64:67], s[86:87]
	v_add_u32_e32 v70, s8, v36
	v_cvt_pk_bf16_f32 v68, v64, v65
	v_cvt_pk_bf16_f32 v69, v66, v67
	global_store_dwordx2 v70, v[68:69], s[42:43]
	v_pk_mul_f32 v[64:65], v[144:145], v[50:51] op_sel_hi:[1,0]
	v_pk_mul_f32 v[66:67], v[146:147], v[50:51] op_sel_hi:[1,0]
	v_pk_fma_f32 v[64:65], v[6:7], v[64:65], v[14:15]
	v_pk_fma_f32 v[66:67], v[8:9], v[66:67], v[16:17]
	global_store_dwordx4 v74, v[64:67], s[86:87] offset:1024
	v_add_u32_e32 v70, s8, v37
	v_cvt_pk_bf16_f32 v68, v64, v65
	v_cvt_pk_bf16_f32 v69, v66, v67
	global_store_dwordx2 v70, v[68:69], s[42:43]
	v_pk_mul_f32 v[64:65], v[148:149], v[50:51] op_sel_hi:[1,0]
	v_pk_mul_f32 v[66:67], v[150:151], v[50:51] op_sel_hi:[1,0]
	v_pk_fma_f32 v[64:65], v[18:19], v[64:65], v[26:27]
	v_pk_fma_f32 v[66:67], v[20:21], v[66:67], v[28:29]
	global_store_dwordx4 v74, v[64:67], s[86:87] offset:2048
	v_add_u32_e32 v70, s8, v38
	v_cvt_pk_bf16_f32 v68, v64, v65
	v_cvt_pk_bf16_f32 v69, v66, v67
	global_store_dwordx2 v70, v[68:69], s[42:43]
	v_pk_mul_f32 v[64:65], v[152:153], v[50:51] op_sel_hi:[1,0]
	v_pk_mul_f32 v[66:67], v[154:155], v[50:51] op_sel_hi:[1,0]
	v_pk_fma_f32 v[64:65], v[22:23], v[64:65], v[30:31]
	v_pk_fma_f32 v[66:67], v[24:25], v[66:67], v[32:33]
	global_store_dwordx4 v74, v[64:67], s[86:87] offset:3072
	v_add_u32_e32 v70, s8, v39
	v_cvt_pk_bf16_f32 v68, v64, v65
	v_cvt_pk_bf16_f32 v69, v66, v67
	global_store_dwordx2 v70, v[68:69], s[42:43]
.Lln_skip_3_2:
	s_add_i32 s9, s4, 3
	s_cmp_lt_i32 s9, 0x8000
	s_cbranch_scc0 .Lln_skip_3_3
	s_lshr_b32 s8, s9, 8
	s_lshl_b32 s8, s8, 19
	s_and_b32 s2, s9, 0xff
	s_lshl_b32 s2, s2, 6
	s_add_i32 s8, s8, s2
	v_pk_mul_f32 v[64:65], v[156:157], v[52:53] op_sel_hi:[1,0]
	v_pk_mul_f32 v[66:67], v[158:159], v[52:53] op_sel_hi:[1,0]
	v_pk_fma_f32 v[64:65], v[2:3], v[64:65], v[10:11]
	v_pk_fma_f32 v[66:67], v[4:5], v[66:67], v[12:13]
	global_store_dwordx4 v75, v[64:67], s[86:87]
	v_add_u32_e32 v70, s8, v36
	v_cvt_pk_bf16_f32 v68, v64, v65
	v_cvt_pk_bf16_f32 v69, v66, v67
	global_store_dwordx2 v70, v[68:69], s[42:43]
	v_pk_mul_f32 v[64:65], v[160:161], v[52:53] op_sel_hi:[1,0]
	v_pk_mul_f32 v[66:67], v[162:163], v[52:53] op_sel_hi:[1,0]
	v_pk_fma_f32 v[64:65], v[6:7], v[64:65], v[14:15]
	v_pk_fma_f32 v[66:67], v[8:9], v[66:67], v[16:17]
	global_store_dwordx4 v75, v[64:67], s[86:87] offset:1024
	v_add_u32_e32 v70, s8, v37
	v_cvt_pk_bf16_f32 v68, v64, v65
	v_cvt_pk_bf16_f32 v69, v66, v67
	global_store_dwordx2 v70, v[68:69], s[42:43]
	v_pk_mul_f32 v[64:65], v[164:165], v[52:53] op_sel_hi:[1,0]
	v_pk_mul_f32 v[66:67], v[166:167], v[52:53] op_sel_hi:[1,0]
	v_pk_fma_f32 v[64:65], v[18:19], v[64:65], v[26:27]
	v_pk_fma_f32 v[66:67], v[20:21], v[66:67], v[28:29]
	global_store_dwordx4 v75, v[64:67], s[86:87] offset:2048
	v_add_u32_e32 v70, s8, v38
	v_cvt_pk_bf16_f32 v68, v64, v65
	v_cvt_pk_bf16_f32 v69, v66, v67
	global_store_dwordx2 v70, v[68:69], s[42:43]
	v_pk_mul_f32 v[64:65], v[168:169], v[52:53] op_sel_hi:[1,0]
	v_pk_mul_f32 v[66:67], v[170:171], v[52:53] op_sel_hi:[1,0]
	v_pk_fma_f32 v[64:65], v[22:23], v[64:65], v[30:31]
	v_pk_fma_f32 v[66:67], v[24:25], v[66:67], v[32:33]
	global_store_dwordx4 v75, v[64:67], s[86:87] offset:3072
	v_add_u32_e32 v70, s8, v39
	v_cvt_pk_bf16_f32 v68, v64, v65
	v_cvt_pk_bf16_f32 v69, v66, v67
	global_store_dwordx2 v70, v[68:69], s[42:43]

; DEV int otid() { int t = threadIdx.x; asm volatile("" : "+v"(t)); return t; }
;     ...
;   const int tid = otid(), lane = tid & 63, wid = tid >> 6;
;   const int wm = wid >> 1, wn = wid & 1, l15 = lane & 15, quad = lane >> 4;
;   const int lrow = tid >> 2, pc = tid & 3;
;   const int gtab = ((lrow >> 2) & 3);
;   const int gl = (gtab == 0) ? 0 : (gtab == 1) ? 2 : (gtab == 2) ? 3 : 1;
;   const int lc = (pc ^ gl) * 8;
;     ...
;           const size_t xi = (size_t)row * D + col;
;           const float xv = xin ? xin[xi] : P.out[xi];
;           P.out[xi] = alpha * xv + sc * acc[ms][ns][j];
.LBB0_2256:
.LBB0_2257:
	v_mov_b32_e32 v9, v210
	s_mov_b32 s18, s2
	v_bfe_u32 v0, v9, 4, 2
	v_cmp_lt_i32_e32 vcc, 0, v0
	s_and_saveexec_b64 s[4:5], vcc
	s_cbranch_execz .LBB0_2263
	v_cmp_ne_u32_e32 vcc, 1, v0
	s_and_saveexec_b64 s[12:13], vcc
	s_xor_b64 s[12:13], exec, s[12:13]
	v_cmp_eq_u32_e32 vcc, 2, v0
	s_nop 1
	v_cndmask_b32_e64 v0, 1, 3, vcc
	s_andn2_saveexec_b64 s[12:13], s[12:13]
	v_mov_b32_e32 v0, 2
	s_or_b64 exec, exec, s[12:13]

;     ...
;     for (int ms = 0; ms < 8; ++ms) {
;       asm volatile("" ::: "memory");
; #pragma unroll
;       for (int ns = 0; ns < 4; ++ns)
; #pragma unroll
;         for (int j = 0; j < 4; ++j) {
;           int row = m0 + wm * 128 + ms * 16 + quad * 4 + j;
;           int col = n0 + wn * 64 + ns * 16 + l15;
;           const size_t xi = (size_t)row * D + col;
;           const float xv = xin ? xin[xi] : P.out[xi];
;           P.out[xi] = alpha * xv + sc * acc[ms][ns][j];
;         }
.LBB0_2281:
	v_add_u32_e32 v132, s14, v178
	v_or_b32_e32 v130, s15, v183
	v_lshlrev_b32_e32 v132, 12, v132
	v_lshl_add_u32 v138, v130, 2, v132
	v_add_u32_e32 v138, 0x1000, v138
	v_mov_b32_e32 v130, v138
	v_add_u32_e32 v131, 0x2000, v130
	v_add_u32_e32 v132, 0x10000, v130
	v_add_u32_e32 v133, 0x2000, v132
	global_load_dword v140, v130, s[8:9] offset:-4096
	global_load_dword v141, v130, s[8:9] offset:-4032
	global_load_dword v142, v130, s[8:9] offset:-3968
	global_load_dword v143, v130, s[8:9] offset:-3904
	global_load_dword v144, v130, s[8:9]
	global_load_dword v145, v130, s[8:9] offset:64
	global_load_dword v146, v130, s[8:9] offset:128
	global_load_dword v147, v130, s[8:9] offset:192
	global_load_dword v148, v131, s[8:9] offset:-4096
	global_load_dword v149, v131, s[8:9] offset:-4032
	global_load_dword v150, v131, s[8:9] offset:-3968
	global_load_dword v151, v131, s[8:9] offset:-3904
	global_load_dword v152, v131, s[8:9]
	global_load_dword v153, v131, s[8:9] offset:64
	global_load_dword v154, v131, s[8:9] offset:128
	global_load_dword v155, v131, s[8:9] offset:192
	global_load_dword v156, v132, s[8:9] offset:-4096
	global_load_dword v157, v132, s[8:9] offset:-4032
	global_load_dword v158, v132, s[8:9] offset:-3968
	global_load_dword v159, v132, s[8:9] offset:-3904
	global_load_dword v160, v132, s[8:9]
	global_load_dword v161, v132, s[8:9] offset:64
	global_load_dword v162, v132, s[8:9] offset:128
	global_load_dword v163, v132, s[8:9] offset:192
	global_load_dword v164, v133, s[8:9] offset:-4096
	global_load_dword v165, v133, s[8:9] offset:-4032
	global_load_dword v166, v133, s[8:9] offset:-3968
	global_load_dword v167, v133, s[8:9] offset:-3904
	global_load_dword v168, v133, s[8:9]
	global_load_dword v169, v133, s[8:9] offset:64
	global_load_dword v170, v133, s[8:9] offset:128
	global_load_dword v171, v133, s[8:9] offset:192
	s_waitcnt vmcnt(0)
	v_mul_f32_e32 v140, v212, v140
	v_fmac_f32_e32 v140, v211, v126
	global_store_dword v130, v140, s[86:87] offset:-4096
	v_mul_f32_e32 v141, v212, v141
	v_fmac_f32_e32 v141, v211, v122
	global_store_dword v130, v141, s[86:87] offset:-4032
	v_mul_f32_e32 v142, v212, v142
	v_fmac_f32_e32 v142, v211, v118
	global_store_dword v130, v142, s[86:87] offset:-3968
	v_mul_f32_e32 v143, v212, v143
	v_fmac_f32_e32 v143, v211, v114
	global_store_dword v130, v143, s[86:87] offset:-3904
	v_mul_f32_e32 v144, v212, v144
	v_fmac_f32_e32 v144, v211, v127
	global_store_dword v130, v144, s[86:87]
	v_mul_f32_e32 v145, v212, v145
	v_fmac_f32_e32 v145, v211, v123
	global_store_dword v130, v145, s[86:87] offset:64
	v_mul_f32_e32 v146, v212, v146
	v_fmac_f32_e32 v146, v211, v119
	global_store_dword v130, v146, s[86:87] offset:128
	v_mul_f32_e32 v147, v212, v147
	v_fmac_f32_e32 v147, v211, v115
	global_store_dword v130, v147, s[86:87] offset:192
	v_mul_f32_e32 v148, v212, v148
	v_fmac_f32_e32 v148, v211, v128
	global_store_dword v131, v148, s[86:87] offset:-4096
	v_mul_f32_e32 v149, v212, v149
	v_fmac_f32_e32 v149, v211, v124
	global_store_dword v131, v149, s[86:87] offset:-4032
	v_mul_f32_e32 v150, v212, v150
	v_fmac_f32_e32 v150, v211, v120
	global_store_dword v131, v150, s[86:87] offset:-3968
	v_mul_f32_e32 v151, v212, v151
	v_fmac_f32_e32 v151, v211, v116
	global_store_dword v131, v151, s[86:87] offset:-3904
	v_mul_f32_e32 v152, v212, v152
	v_fmac_f32_e32 v152, v211, v129
	global_store_dword v131, v152, s[86:87]
	v_mul_f32_e32 v153, v212, v153
	v_fmac_f32_e32 v153, v211, v125
	global_store_dword v131, v153, s[86:87] offset:64
	v_mul_f32_e32 v154, v212, v154
	v_fmac_f32_e32 v154, v211, v121
	global_store_dword v131, v154, s[86:87] offset:128
	v_mul_f32_e32 v155, v212, v155
	v_fmac_f32_e32 v155, v211, v117
	global_store_dword v131, v155, s[86:87] offset:192
	v_mul_f32_e32 v156, v212, v156
	v_fmac_f32_e32 v156, v211, v110
	global_store_dword v132, v156, s[86:87] offset:-4096
	v_mul_f32_e32 v157, v212, v157
	v_fmac_f32_e32 v157, v211, v106
	global_store_dword v132, v157, s[86:87] offset:-4032
	v_mul_f32_e32 v158, v212, v158
	v_fmac_f32_e32 v158, v211, v102
	global_store_dword v132, v158, s[86:87] offset:-3968
	v_mul_f32_e32 v159, v212, v159
	v_fmac_f32_e32 v159, v211, v98
	global_store_dword v132, v159, s[86:87] offset:-3904
	v_mul_f32_e32 v160, v212, v160
	v_fmac_f32_e32 v160, v211, v111
	global_store_dword v132, v160, s[86:87]
	v_mul_f32_e32 v161, v212, v161
	v_fmac_f32_e32 v161, v211, v107
	global_store_dword v132, v161, s[86:87] offset:64
	v_mul_f32_e32 v162, v212, v162
	v_fmac_f32_e32 v162, v211, v103
	global_store_dword v132, v162, s[86:87] offset:128
	v_mul_f32_e32 v163, v212, v163
	v_fmac_f32_e32 v163, v211, v99
	global_store_dword v132, v163, s[86:87] offset:192
	v_mul_f32_e32 v164, v212, v164
	v_fmac_f32_e32 v164, v211, v112
	global_store_dword v133, v164, s[86:87] offset:-4096
	v_mul_f32_e32 v165, v212, v165
	v_fmac_f32_e32 v165, v211, v108
	global_store_dword v133, v165, s[86:87] offset:-4032
	v_mul_f32_e32 v166, v212, v166
	v_fmac_f32_e32 v166, v211, v104
	global_store_dword v133, v166, s[86:87] offset:-3968
	v_mul_f32_e32 v167, v212, v167
	v_fmac_f32_e32 v167, v211, v100
	global_store_dword v133, v167, s[86:87] offset:-3904
	v_mul_f32_e32 v168, v212, v168
	v_fmac_f32_e32 v168, v211, v113
	global_store_dword v133, v168, s[86:87]
	v_mul_f32_e32 v169, v212, v169
	v_fmac_f32_e32 v169, v211, v109
	global_store_dword v133, v169, s[86:87] offset:64
	v_mul_f32_e32 v170, v212, v170
	v_fmac_f32_e32 v170, v211, v105
	global_store_dword v133, v170, s[86:87] offset:128
	v_mul_f32_e32 v171, v212, v171
	v_fmac_f32_e32 v171, v211, v101
	global_store_dword v133, v171, s[86:87] offset:192
	v_add_u32_e32 v130, 0x20000, v138
;     ...
;     for (int ms = 0; ms < 8; ++ms) {
;       asm volatile("" ::: "memory");
; #pragma unroll
;       for (int ns = 0; ns < 4; ++ns)
; #pragma unroll
;         for (int j = 0; j < 4; ++j) {
;           int row = m0 + wm * 128 + ms * 16 + quad * 4 + j;
;           int col = n0 + wn * 64 + ns * 16 + l15;
;           const size_t xi = (size_t)row * D + col;
;           const float xv = xin ? xin[xi] : P.out[xi];
;           P.out[xi] = alpha * xv + sc * acc[ms][ns][j];
;         }
	v_add_u32_e32 v131, 0x2000, v130
	v_add_u32_e32 v132, 0x10000, v130
	v_add_u32_e32 v133, 0x2000, v132
	global_load_dword v140, v130, s[8:9] offset:-4096
	global_load_dword v141, v130, s[8:9] offset:-4032
	global_load_dword v142, v130, s[8:9] offset:-3968
	global_load_dword v143, v130, s[8:9] offset:-3904
	global_load_dword v144, v130, s[8:9]
	global_load_dword v145, v130, s[8:9] offset:64
	global_load_dword v146, v130, s[8:9] offset:128
	global_load_dword v147, v130, s[8:9] offset:192
	global_load_dword v148, v131, s[8:9] offset:-4096
	global_load_dword v149, v131, s[8:9] offset:-4032
	global_load_dword v150, v131, s[8:9] offset:-3968
	global_load_dword v151, v131, s[8:9] offset:-3904
	global_load_dword v152, v131, s[8:9]
	global_load_dword v153, v131, s[8:9] offset:64
	global_load_dword v154, v131, s[8:9] offset:128
	global_load_dword v155, v131, s[8:9] offset:192
	global_load_dword v156, v132, s[8:9] offset:-4096
	global_load_dword v157, v132, s[8:9] offset:-4032
	global_load_dword v158, v132, s[8:9] offset:-3968
	global_load_dword v159, v132, s[8:9] offset:-3904
	global_load_dword v160, v132, s[8:9]
	global_load_dword v161, v132, s[8:9] offset:64
	global_load_dword v162, v132, s[8:9] offset:128
	global_load_dword v163, v132, s[8:9] offset:192
	global_load_dword v164, v133, s[8:9] offset:-4096
	global_load_dword v165, v133, s[8:9] offset:-4032
	global_load_dword v166, v133, s[8:9] offset:-3968
	global_load_dword v167, v133, s[8:9] offset:-3904
	global_load_dword v168, v133, s[8:9]
	global_load_dword v169, v133, s[8:9] offset:64
	global_load_dword v170, v133, s[8:9] offset:128
	global_load_dword v171, v133, s[8:9] offset:192
	s_waitcnt vmcnt(0)
	v_mul_f32_e32 v140, v212, v140
	v_fmac_f32_e32 v140, v211, v94
	global_store_dword v130, v140, s[86:87] offset:-4096
	v_mul_f32_e32 v141, v212, v141
	v_fmac_f32_e32 v141, v211, v90
	global_store_dword v130, v141, s[86:87] offset:-4032
	v_mul_f32_e32 v142, v212, v142
	v_fmac_f32_e32 v142, v211, v86
	global_store_dword v130, v142, s[86:87] offset:-3968
	v_mul_f32_e32 v143, v212, v143
	v_fmac_f32_e32 v143, v211, v82
	global_store_dword v130, v143, s[86:87] offset:-3904
	v_mul_f32_e32 v144, v212, v144
	v_fmac_f32_e32 v144, v211, v95
	global_store_dword v130, v144, s[86:87]
	v_mul_f32_e32 v145, v212, v145
	v_fmac_f32_e32 v145, v211, v91
	global_store_dword v130, v145, s[86:87] offset:64
	v_mul_f32_e32 v146, v212, v146
	v_fmac_f32_e32 v146, v211, v87
	global_store_dword v130, v146, s[86:87] offset:128
	v_mul_f32_e32 v147, v212, v147
	v_fmac_f32_e32 v147, v211, v83
	global_store_dword v130, v147, s[86:87] offset:192
	v_mul_f32_e32 v148, v212, v148
	v_fmac_f32_e32 v148, v211, v96
	global_store_dword v131, v148, s[86:87] offset:-4096
	v_mul_f32_e32 v149, v212, v149
	v_fmac_f32_e32 v149, v211, v92
	global_store_dword v131, v149, s[86:87] offset:-4032
	v_mul_f32_e32 v150, v212, v150
	v_fmac_f32_e32 v150, v211, v88
	global_store_dword v131, v150, s[86:87] offset:-3968
	v_mul_f32_e32 v151, v212, v151
	v_fmac_f32_e32 v151, v211, v84
	global_store_dword v131, v151, s[86:87] offset:-3904
	v_mul_f32_e32 v152, v212, v152
	v_fmac_f32_e32 v152, v211, v97
	global_store_dword v131, v152, s[86:87]
	v_mul_f32_e32 v153, v212, v153
	v_fmac_f32_e32 v153, v211, v93
	global_store_dword v131, v153, s[86:87] offset:64
	v_mul_f32_e32 v154, v212, v154
	v_fmac_f32_e32 v154, v211, v89
	global_store_dword v131, v154, s[86:87] offset:128
	v_mul_f32_e32 v155, v212, v155
	v_fmac_f32_e32 v155, v211, v85
	global_store_dword v131, v155, s[86:87] offset:192
	v_mul_f32_e32 v156, v212, v156
	v_fmac_f32_e32 v156, v211, v78
	global_store_dword v132, v156, s[86:87] offset:-4096
	v_mul_f32_e32 v157, v212, v157
	v_fmac_f32_e32 v157, v211, v74
	global_store_dword v132, v157, s[86:87] offset:-4032
	v_mul_f32_e32 v158, v212, v158
	v_fmac_f32_e32 v158, v211, v70
	global_store_dword v132, v158, s[86:87] offset:-3968
	v_mul_f32_e32 v159, v212, v159
	v_fmac_f32_e32 v159, v211, v66
	global_store_dword v132, v159, s[86:87] offset:-3904
	v_mul_f32_e32 v160, v212, v160
	v_fmac_f32_e32 v160, v211, v79
	global_store_dword v132, v160, s[86:87]
	v_mul_f32_e32 v161, v212, v161
	v_fmac_f32_e32 v161, v211, v75
	global_store_dword v132, v161, s[86:87] offset:64
	v_mul_f32_e32 v162, v212, v162
	v_fmac_f32_e32 v162, v211, v71
	global_store_dword v132, v162, s[86:87] offset:128
	v_mul_f32_e32 v163, v212, v163
	v_fmac_f32_e32 v163, v211, v67
	global_store_dword v132, v163, s[86:87] offset:192
	v_mul_f32_e32 v164, v212, v164
	v_fmac_f32_e32 v164, v211, v80
	global_store_dword v133, v164, s[86:87] offset:-4096
	v_mul_f32_e32 v165, v212, v165
	v_fmac_f32_e32 v165, v211, v76
	global_store_dword v133, v165, s[86:87] offset:-4032
	v_mul_f32_e32 v166, v212, v166
	v_fmac_f32_e32 v166, v211, v72
	global_store_dword v133, v166, s[86:87] offset:-3968
	v_mul_f32_e32 v167, v212, v167
	v_fmac_f32_e32 v167, v211, v68
	global_store_dword v133, v167, s[86:87] offset:-3904
	v_mul_f32_e32 v168, v212, v168
	v_fmac_f32_e32 v168, v211, v81
	global_store_dword v133, v168, s[86:87]
	v_mul_f32_e32 v169, v212, v169
	v_fmac_f32_e32 v169, v211, v77
	global_store_dword v133, v169, s[86:87] offset:64
	v_mul_f32_e32 v170, v212, v170
	v_fmac_f32_e32 v170, v211, v73
	global_store_dword v133, v170, s[86:87] offset:128
	v_mul_f32_e32 v171, v212, v171
	v_fmac_f32_e32 v171, v211, v69
	global_store_dword v133, v171, s[86:87] offset:192
	v_add_u32_e32 v130, 0x40000, v138
	v_add_u32_e32 v131, 0x2000, v130
	v_add_u32_e32 v132, 0x10000, v130
	v_add_u32_e32 v133, 0x2000, v132
	global_load_dword v140, v130, s[8:9] offset:-4096
	global_load_dword v141, v130, s[8:9] offset:-4032
	global_load_dword v142, v130, s[8:9] offset:-3968
;     ...
;     for (int ms = 0; ms < 8; ++ms) {
;       asm volatile("" ::: "memory");
; #pragma unroll
;       for (int ns = 0; ns < 4; ++ns)
; #pragma unroll
;         for (int j = 0; j < 4; ++j) {
;           int row = m0 + wm * 128 + ms * 16 + quad * 4 + j;
;           int col = n0 + wn * 64 + ns * 16 + l15;
;           const size_t xi = (size_t)row * D + col;
;           const float xv = xin ? xin[xi] : P.out[xi];
;           P.out[xi] = alpha * xv + sc * acc[ms][ns][j];
;         }
	global_load_dword v143, v130, s[8:9] offset:-3904
	global_load_dword v144, v130, s[8:9]
	global_load_dword v145, v130, s[8:9] offset:64
	global_load_dword v146, v130, s[8:9] offset:128
	global_load_dword v147, v130, s[8:9] offset:192
	global_load_dword v148, v131, s[8:9] offset:-4096
	global_load_dword v149, v131, s[8:9] offset:-4032
	global_load_dword v150, v131, s[8:9] offset:-3968
	global_load_dword v151, v131, s[8:9] offset:-3904
	global_load_dword v152, v131, s[8:9]
	global_load_dword v153, v131, s[8:9] offset:64
	global_load_dword v154, v131, s[8:9] offset:128
	global_load_dword v155, v131, s[8:9] offset:192
	global_load_dword v156, v132, s[8:9] offset:-4096
	global_load_dword v157, v132, s[8:9] offset:-4032
	global_load_dword v158, v132, s[8:9] offset:-3968
	global_load_dword v159, v132, s[8:9] offset:-3904
	global_load_dword v160, v132, s[8:9]
	global_load_dword v161, v132, s[8:9] offset:64
	global_load_dword v162, v132, s[8:9] offset:128
	global_load_dword v163, v132, s[8:9] offset:192
	global_load_dword v164, v133, s[8:9] offset:-4096
	global_load_dword v165, v133, s[8:9] offset:-4032
	global_load_dword v166, v133, s[8:9] offset:-3968
	global_load_dword v167, v133, s[8:9] offset:-3904
	global_load_dword v168, v133, s[8:9]
	global_load_dword v169, v133, s[8:9] offset:64
	global_load_dword v170, v133, s[8:9] offset:128
	global_load_dword v171, v133, s[8:9] offset:192
	s_waitcnt vmcnt(0)
	v_mul_f32_e32 v140, v212, v140
	v_fmac_f32_e32 v140, v211, v62
	global_store_dword v130, v140, s[86:87] offset:-4096
	v_mul_f32_e32 v141, v212, v141
	v_fmac_f32_e32 v141, v211, v58
	global_store_dword v130, v141, s[86:87] offset:-4032
	v_mul_f32_e32 v142, v212, v142
	v_fmac_f32_e32 v142, v211, v54
	global_store_dword v130, v142, s[86:87] offset:-3968
	v_mul_f32_e32 v143, v212, v143
	v_fmac_f32_e32 v143, v211, v50
	global_store_dword v130, v143, s[86:87] offset:-3904
	v_mul_f32_e32 v144, v212, v144
	v_fmac_f32_e32 v144, v211, v63
	global_store_dword v130, v144, s[86:87]
	v_mul_f32_e32 v145, v212, v145
	v_fmac_f32_e32 v145, v211, v59
	global_store_dword v130, v145, s[86:87] offset:64
	v_mul_f32_e32 v146, v212, v146
	v_fmac_f32_e32 v146, v211, v55
	global_store_dword v130, v146, s[86:87] offset:128
	v_mul_f32_e32 v147, v212, v147
	v_fmac_f32_e32 v147, v211, v51
	global_store_dword v130, v147, s[86:87] offset:192
	v_mul_f32_e32 v148, v212, v148
	v_fmac_f32_e32 v148, v211, v64
	global_store_dword v131, v148, s[86:87] offset:-4096
	v_mul_f32_e32 v149, v212, v149
	v_fmac_f32_e32 v149, v211, v60
	global_store_dword v131, v149, s[86:87] offset:-4032
	v_mul_f32_e32 v150, v212, v150
	v_fmac_f32_e32 v150, v211, v56
	global_store_dword v131, v150, s[86:87] offset:-3968
	v_mul_f32_e32 v151, v212, v151
	v_fmac_f32_e32 v151, v211, v52
	global_store_dword v131, v151, s[86:87] offset:-3904
	v_mul_f32_e32 v152, v212, v152
	v_fmac_f32_e32 v152, v211, v65
	global_store_dword v131, v152, s[86:87]
	v_mul_f32_e32 v153, v212, v153
	v_fmac_f32_e32 v153, v211, v61
	global_store_dword v131, v153, s[86:87] offset:64
	v_mul_f32_e32 v154, v212, v154
	v_fmac_f32_e32 v154, v211, v57
	global_store_dword v131, v154, s[86:87] offset:128
	v_mul_f32_e32 v155, v212, v155
	v_fmac_f32_e32 v155, v211, v53
	global_store_dword v131, v155, s[86:87] offset:192
	v_mul_f32_e32 v156, v212, v156
	v_fmac_f32_e32 v156, v211, v46
	global_store_dword v132, v156, s[86:87] offset:-4096
	v_mul_f32_e32 v157, v212, v157
	v_fmac_f32_e32 v157, v211, v42
	global_store_dword v132, v157, s[86:87] offset:-4032
	v_mul_f32_e32 v158, v212, v158
	v_fmac_f32_e32 v158, v211, v38
	global_store_dword v132, v158, s[86:87] offset:-3968
	v_mul_f32_e32 v159, v212, v159
	v_fmac_f32_e32 v159, v211, v34
	global_store_dword v132, v159, s[86:87] offset:-3904
	v_mul_f32_e32 v160, v212, v160
	v_fmac_f32_e32 v160, v211, v47
	global_store_dword v132, v160, s[86:87]
	v_mul_f32_e32 v161, v212, v161
	v_fmac_f32_e32 v161, v211, v43
	global_store_dword v132, v161, s[86:87] offset:64
	v_mul_f32_e32 v162, v212, v162
	v_fmac_f32_e32 v162, v211, v39
	global_store_dword v132, v162, s[86:87] offset:128
	v_mul_f32_e32 v163, v212, v163
	v_fmac_f32_e32 v163, v211, v35
	global_store_dword v132, v163, s[86:87] offset:192
	v_mul_f32_e32 v164, v212, v164
	v_fmac_f32_e32 v164, v211, v48
	global_store_dword v133, v164, s[86:87] offset:-4096
	v_mul_f32_e32 v165, v212, v165
	v_fmac_f32_e32 v165, v211, v44
	global_store_dword v133, v165, s[86:87] offset:-4032
	v_mul_f32_e32 v166, v212, v166
	v_fmac_f32_e32 v166, v211, v40
	global_store_dword v133, v166, s[86:87] offset:-3968
	v_mul_f32_e32 v167, v212, v167
	v_fmac_f32_e32 v167, v211, v36
	global_store_dword v133, v167, s[86:87] offset:-3904
	v_mul_f32_e32 v168, v212, v168
	v_fmac_f32_e32 v168, v211, v49
	global_store_dword v133, v168, s[86:87]
	v_mul_f32_e32 v169, v212, v169
	v_fmac_f32_e32 v169, v211, v45
	global_store_dword v133, v169, s[86:87] offset:64
	v_mul_f32_e32 v170, v212, v170
	v_fmac_f32_e32 v170, v211, v41
	global_store_dword v133, v170, s[86:87] offset:128
	v_mul_f32_e32 v171, v212, v171
	v_fmac_f32_e32 v171, v211, v37
	global_store_dword v133, v171, s[86:87] offset:192
	v_add_u32_e32 v130, 0x60000, v138
	v_add_u32_e32 v131, 0x2000, v130
	v_add_u32_e32 v132, 0x10000, v130
	v_add_u32_e32 v133, 0x2000, v132
	global_load_dword v140, v130, s[8:9] offset:-4096
	global_load_dword v141, v130, s[8:9] offset:-4032
	global_load_dword v142, v130, s[8:9] offset:-3968
	global_load_dword v143, v130, s[8:9] offset:-3904
	global_load_dword v144, v130, s[8:9]
	global_load_dword v145, v130, s[8:9] offset:64
	global_load_dword v146, v130, s[8:9] offset:128
	global_load_dword v147, v130, s[8:9] offset:192
	global_load_dword v148, v131, s[8:9] offset:-4096
	global_load_dword v149, v131, s[8:9] offset:-4032
	global_load_dword v150, v131, s[8:9] offset:-3968
	global_load_dword v151, v131, s[8:9] offset:-3904
	global_load_dword v152, v131, s[8:9]
	global_load_dword v153, v131, s[8:9] offset:64
	global_load_dword v154, v131, s[8:9] offset:128
	global_load_dword v155, v131, s[8:9] offset:192
	global_load_dword v156, v132, s[8:9] offset:-4096
	global_load_dword v157, v132, s[8:9] offset:-4032
	global_load_dword v158, v132, s[8:9] offset:-3968
	global_load_dword v159, v132, s[8:9] offset:-3904
	global_load_dword v160, v132, s[8:9]
	global_load_dword v161, v132, s[8:9] offset:64
	global_load_dword v162, v132, s[8:9] offset:128
	global_load_dword v163, v132, s[8:9] offset:192
	global_load_dword v164, v133, s[8:9] offset:-4096
	global_load_dword v165, v133, s[8:9] offset:-4032
	global_load_dword v166, v133, s[8:9] offset:-3968
	global_load_dword v167, v133, s[8:9] offset:-3904
	global_load_dword v168, v133, s[8:9]
	global_load_dword v169, v133, s[8:9] offset:64
	global_load_dword v170, v133, s[8:9] offset:128
	global_load_dword v171, v133, s[8:9] offset:192
	s_waitcnt vmcnt(0)
;     ...
;     for (int ms = 0; ms < 8; ++ms) {
;       asm volatile("" ::: "memory");
; #pragma unroll
;       for (int ns = 0; ns < 4; ++ns)
; #pragma unroll
;         for (int j = 0; j < 4; ++j) {
;           int row = m0 + wm * 128 + ms * 16 + quad * 4 + j;
;           int col = n0 + wn * 64 + ns * 16 + l15;
;           const size_t xi = (size_t)row * D + col;
;           const float xv = xin ? xin[xi] : P.out[xi];
;           P.out[xi] = alpha * xv + sc * acc[ms][ns][j];
;         }
	v_mul_f32_e32 v140, v212, v140
	v_fmac_f32_e32 v140, v211, v30
	global_store_dword v130, v140, s[86:87] offset:-4096
	v_mul_f32_e32 v141, v212, v141
	v_fmac_f32_e32 v141, v211, v26
	global_store_dword v130, v141, s[86:87] offset:-4032
	v_mul_f32_e32 v142, v212, v142
	v_fmac_f32_e32 v142, v211, v22
	global_store_dword v130, v142, s[86:87] offset:-3968
	v_mul_f32_e32 v143, v212, v143
	v_fmac_f32_e32 v143, v211, v18
	global_store_dword v130, v143, s[86:87] offset:-3904
	v_mul_f32_e32 v144, v212, v144
	v_fmac_f32_e32 v144, v211, v31
	global_store_dword v130, v144, s[86:87]
	v_mul_f32_e32 v145, v212, v145
	v_fmac_f32_e32 v145, v211, v27
	global_store_dword v130, v145, s[86:87] offset:64
	v_mul_f32_e32 v146, v212, v146
	v_fmac_f32_e32 v146, v211, v23
	global_store_dword v130, v146, s[86:87] offset:128
	v_mul_f32_e32 v147, v212, v147
	v_fmac_f32_e32 v147, v211, v19
	global_store_dword v130, v147, s[86:87] offset:192
	v_mul_f32_e32 v148, v212, v148
	v_fmac_f32_e32 v148, v211, v32
	global_store_dword v131, v148, s[86:87] offset:-4096
	v_mul_f32_e32 v149, v212, v149
	v_fmac_f32_e32 v149, v211, v28
	global_store_dword v131, v149, s[86:87] offset:-4032
	v_mul_f32_e32 v150, v212, v150
	v_fmac_f32_e32 v150, v211, v24
	global_store_dword v131, v150, s[86:87] offset:-3968
	v_mul_f32_e32 v151, v212, v151
	v_fmac_f32_e32 v151, v211, v20
	global_store_dword v131, v151, s[86:87] offset:-3904
	v_mul_f32_e32 v152, v212, v152
	v_fmac_f32_e32 v152, v211, v33
	global_store_dword v131, v152, s[86:87]
	v_mul_f32_e32 v153, v212, v153
	v_fmac_f32_e32 v153, v211, v29
	global_store_dword v131, v153, s[86:87] offset:64
	v_mul_f32_e32 v154, v212, v154
	v_fmac_f32_e32 v154, v211, v25
	global_store_dword v131, v154, s[86:87] offset:128
	v_mul_f32_e32 v155, v212, v155
	v_fmac_f32_e32 v155, v211, v21
	global_store_dword v131, v155, s[86:87] offset:192
	v_mul_f32_e32 v156, v212, v156
	v_fmac_f32_e32 v156, v211, v14
	global_store_dword v132, v156, s[86:87] offset:-4096
	v_mul_f32_e32 v157, v212, v157
	v_fmac_f32_e32 v157, v211, v10
	global_store_dword v132, v157, s[86:87] offset:-4032
	v_mul_f32_e32 v158, v212, v158
	v_fmac_f32_e32 v158, v211, v6
	global_store_dword v132, v158, s[86:87] offset:-3968
	v_mul_f32_e32 v159, v212, v159
	v_fmac_f32_e32 v159, v211, v2
	global_store_dword v132, v159, s[86:87] offset:-3904
	v_mul_f32_e32 v160, v212, v160
	v_fmac_f32_e32 v160, v211, v15
	global_store_dword v132, v160, s[86:87]
	v_mul_f32_e32 v161, v212, v161
	v_fmac_f32_e32 v161, v211, v11
	global_store_dword v132, v161, s[86:87] offset:64
	v_mul_f32_e32 v162, v212, v162
	v_fmac_f32_e32 v162, v211, v7
	global_store_dword v132, v162, s[86:87] offset:128
	v_mul_f32_e32 v163, v212, v163
	v_fmac_f32_e32 v163, v211, v3
	global_store_dword v132, v163, s[86:87] offset:192
	v_mul_f32_e32 v164, v212, v164
	v_fmac_f32_e32 v164, v211, v16
	global_store_dword v133, v164, s[86:87] offset:-4096
	v_mul_f32_e32 v165, v212, v165
	v_fmac_f32_e32 v165, v211, v12
	global_store_dword v133, v165, s[86:87] offset:-4032
	v_mul_f32_e32 v166, v212, v166
	v_fmac_f32_e32 v166, v211, v8
	global_store_dword v133, v166, s[86:87] offset:-3968
	v_mul_f32_e32 v167, v212, v167
	v_fmac_f32_e32 v167, v211, v4
	global_store_dword v133, v167, s[86:87] offset:-3904
	v_mul_f32_e32 v168, v212, v168
	v_fmac_f32_e32 v168, v211, v17
	global_store_dword v133, v168, s[86:87]
	v_mul_f32_e32 v169, v212, v169
	v_fmac_f32_e32 v169, v211, v13
	global_store_dword v133, v169, s[86:87] offset:64
	v_mul_f32_e32 v170, v212, v170
	v_fmac_f32_e32 v170, v211, v9
	global_store_dword v133, v170, s[86:87] offset:128
	v_mul_f32_e32 v171, v212, v171
	v_fmac_f32_e32 v171, v211, v5
	global_store_dword v133, v171, s[86:87] offset:192
	s_and_b64 vcc, exec, s[12:13]
	s_cbranch_vccnz .LBB0_2285
	s_branch .LBB0_2257
